# all plain dwordx4/x2 global stores made write-through (sc1) to shrink the L2 write-back at each grid barrier
# speedup vs baseline: 1.0168x; 1.0168x over previous
.LBB0_10:
	s_ashr_i32 s13, s12, 31
	s_lshl_b64 s[16:17], s[12:13], 21
	s_add_u32 s16, s2, s16
	s_addc_u32 s17, s3, s17
	v_add_u32_e32 v37, 4, v68
	ds_read2st64_b32 v[108:109], v68 offset1:1
	ds_read2st64_b32 v[110:111], v37 offset0:4 offset1:5
	s_lshl_b32 s13, s22, 10
	s_lshl_b32 s12, s12, 14
	s_add_i32 s13, s13, s12
	s_sub_i32 s12, s21, s13
	v_add_u32_e32 v132, s12, v67
	s_waitcnt lgkmcnt(0)
	v_cvt_pk_bf16_f32 v104, v108, v110
	v_add_u32_e32 v126, 8, v68
	v_add_u32_e32 v127, 12, v68
	v_add_u32_e32 v128, 16, v68
	v_add_u32_e32 v129, 20, v68
	v_add_u32_e32 v130, 24, v68
	v_add_u32_e32 v131, 28, v68
	v_cmp_gt_i32_e32 vcc, 0, v132
	v_and_or_b32 v108, v132, s19, v103
	ds_read2st64_b32 v[112:113], v126 offset0:8 offset1:9
	ds_read2st64_b32 v[114:115], v127 offset0:12 offset1:13
	ds_read2st64_b32 v[116:117], v128 offset0:16 offset1:17
	ds_read2st64_b32 v[118:119], v129 offset0:20 offset1:21
	ds_read2st64_b32 v[120:121], v130 offset0:24 offset1:25
	ds_read2st64_b32 v[122:123], v131 offset0:28 offset1:29
	v_cndmask_b32_e32 v124, v132, v108, vcc
	v_ashrrev_i32_e32 v125, 31, v124
	s_ashr_i32 s15, s14, 31
	v_lshlrev_b64 v[124:125], 11, v[124:125]
	v_lshl_add_u64 v[124:125], s[16:17], 0, v[124:125]
	s_lshl_b64 s[12:13], s[14:15], 1
	v_lshl_add_u64 v[124:125], v[124:125], 0, s[12:13]
	s_waitcnt lgkmcnt(4)
	v_cvt_pk_bf16_f32 v105, v112, v114
	s_waitcnt lgkmcnt(2)
	v_cvt_pk_bf16_f32 v106, v116, v118
	s_waitcnt lgkmcnt(0)
	v_cvt_pk_bf16_f32 v107, v120, v122
	v_lshl_add_u64 v[124:125], v[124:125], 0, v[34:35]
	v_add_u32_e32 v108, 64, v132
	global_store_dwordx4 v[124:125], v[104:107], off sc1
	v_cmp_gt_i32_e32 vcc, 0, v108
	s_mov_b32 s21, s23
	v_cvt_pk_bf16_f32 v104, v109, v111
	v_and_or_b32 v109, v108, s19, v103
	v_cndmask_b32_e32 v108, v108, v109, vcc
	v_ashrrev_i32_e32 v109, 31, v108
	v_lshlrev_b64 v[108:109], 11, v[108:109]
	v_lshl_add_u64 v[108:109], s[16:17], 0, v[108:109]
	v_lshl_add_u64 v[108:109], v[108:109], 0, s[12:13]
	v_cvt_pk_bf16_f32 v105, v113, v115
	v_cvt_pk_bf16_f32 v106, v117, v119
	v_cvt_pk_bf16_f32 v107, v121, v123
	v_lshl_add_u64 v[108:109], v[108:109], 0, v[34:35]
	global_store_dwordx4 v[108:109], v[104:107], off sc1
	ds_read2st64_b32 v[108:109], v68 offset0:2 offset1:3
	ds_read2st64_b32 v[110:111], v37 offset0:6 offset1:7
	v_add_u32_e32 v37, 0x80, v132
	v_cmp_gt_i32_e32 vcc, 0, v37
	ds_read2st64_b32 v[112:113], v126 offset0:10 offset1:11
	ds_read2st64_b32 v[114:115], v127 offset0:14 offset1:15
	ds_read2st64_b32 v[116:117], v128 offset0:18 offset1:19
	ds_read2st64_b32 v[118:119], v129 offset0:22 offset1:23
	s_waitcnt lgkmcnt(4)
	v_cvt_pk_bf16_f32 v104, v108, v110
	v_and_or_b32 v108, v37, s19, v103
	ds_read2st64_b32 v[120:121], v130 offset0:26 offset1:27
	ds_read2st64_b32 v[122:123], v131 offset0:30 offset1:31
	v_cndmask_b32_e32 v124, v37, v108, vcc
	v_ashrrev_i32_e32 v125, 31, v124
	v_lshlrev_b64 v[124:125], 11, v[124:125]
	v_lshl_add_u64 v[124:125], s[16:17], 0, v[124:125]
	v_add_u32_e32 v37, 0xc0, v132
	v_lshl_add_u64 v[124:125], v[124:125], 0, s[12:13]
	v_cmp_gt_i32_e32 vcc, 0, v37
	v_and_or_b32 v108, v37, s19, v103
	s_waitcnt lgkmcnt(4)
	v_cvt_pk_bf16_f32 v105, v112, v114
	s_waitcnt lgkmcnt(2)
	v_cvt_pk_bf16_f32 v106, v116, v118
	s_waitcnt lgkmcnt(0)
	v_cvt_pk_bf16_f32 v107, v120, v122
	v_lshl_add_u64 v[124:125], v[124:125], 0, v[34:35]
	v_cndmask_b32_e32 v108, v37, v108, vcc
	global_store_dwordx4 v[124:125], v[104:107], off sc1
	s_andn2_b64 vcc, exec, s[4:5]
	s_nop 0
	v_cvt_pk_bf16_f32 v104, v109, v111
	v_ashrrev_i32_e32 v109, 31, v108
	v_lshlrev_b64 v[108:109], 11, v[108:109]
	v_lshl_add_u64 v[108:109], s[16:17], 0, v[108:109]
	v_lshl_add_u64 v[108:109], v[108:109], 0, s[12:13]
	v_cvt_pk_bf16_f32 v105, v113, v115
	v_cvt_pk_bf16_f32 v106, v117, v119
	v_cvt_pk_bf16_f32 v107, v121, v123
	v_lshl_add_u64 v[108:109], v[108:109], 0, v[34:35]
	global_store_dwordx4 v[108:109], v[104:107], off sc1
	s_barrier
	s_cbranch_vccz .LBB0_79

.LBB0_196:
	s_cmp_eq_u64 s[16:17], 0
	v_lshlrev_b32_e32 v83, 3, v82
	s_cbranch_scc1 .LBB0_200
	v_mul_f32_e32 v86, v7, v7
	v_mul_f32_e32 v87, v9, v9
	v_fmac_f32_e32 v86, v6, v6
	v_fmac_f32_e32 v87, v8, v8
	v_add_f32_e32 v86, v86, v87
	v_mul_f32_e32 v87, v3, v3
	v_mul_f32_e32 v88, v5, v5
	v_fmac_f32_e32 v87, v2, v2
	v_fmac_f32_e32 v88, v4, v4
	v_add_f32_e32 v87, v87, v88
	v_add_f32_e32 v86, v86, v87
	v_mul_f32_e32 v87, v15, v15
	v_mul_f32_e32 v88, v17, v17
	v_fmac_f32_e32 v87, v14, v14
	v_fmac_f32_e32 v88, v16, v16
	v_add_f32_e32 v87, v87, v88
	v_add_f32_e32 v86, v86, v87
	v_mul_f32_e32 v87, v11, v11
	v_mul_f32_e32 v88, v13, v13
	v_fmac_f32_e32 v87, v10, v10
	v_fmac_f32_e32 v88, v12, v12
	v_add_f32_e32 v87, v87, v88
	v_add_f32_e32 v86, v86, v87
	v_and_b32_e32 v87, 64, v1
	v_add_u32_e32 v87, 64, v87
	v_xor_b32_e32 v88, 1, v1
	v_cmp_lt_i32_e32 vcc, v88, v87
	v_cvt_pk_bf16_f32 v2, v2, v3
	v_cvt_pk_bf16_f32 v3, v4, v5
	v_cndmask_b32_e32 v88, v1, v88, vcc
	v_lshlrev_b32_e32 v88, 2, v88
	ds_bpermute_b32 v88, v88, v86
	global_store_dwordx2 v83, v[2:3], s[16:17] offset:512 sc1
	v_cvt_pk_bf16_f32 v2, v14, v15
	v_cvt_pk_bf16_f32 v3, v16, v17
	v_cvt_pk_bf16_f32 v6, v6, v7
	s_waitcnt lgkmcnt(0)
	v_add_f32_e32 v86, v86, v88
	v_xor_b32_e32 v88, 2, v1
	v_cmp_lt_i32_e32 vcc, v88, v87
	v_cvt_pk_bf16_f32 v7, v8, v9
	global_store_dwordx2 v83, v[2:3], s[16:17] offset:1024 sc1
	v_cndmask_b32_e32 v88, v1, v88, vcc
	v_lshlrev_b32_e32 v88, 2, v88
	ds_bpermute_b32 v88, v88, v86
	v_cvt_pk_bf16_f32 v2, v10, v11
	v_cvt_pk_bf16_f32 v3, v12, v13
	global_store_dwordx2 v83, v[6:7], s[16:17] sc1
	global_store_dwordx2 v83, v[2:3], s[16:17] offset:1536 sc1
	s_waitcnt lgkmcnt(0)
	v_add_f32_e32 v86, v86, v88
	v_xor_b32_e32 v88, 4, v1
	v_cmp_lt_i32_e32 vcc, v88, v87
	s_nop 1
	v_cndmask_b32_e32 v88, v1, v88, vcc
	v_lshlrev_b32_e32 v88, 2, v88
	ds_bpermute_b32 v88, v88, v86
	s_waitcnt lgkmcnt(0)
	v_add_f32_e32 v86, v86, v88
	v_xor_b32_e32 v88, 8, v1
	v_cmp_lt_i32_e32 vcc, v88, v87
	s_nop 1
	v_cndmask_b32_e32 v88, v1, v88, vcc
	v_lshlrev_b32_e32 v88, 2, v88
	ds_bpermute_b32 v88, v88, v86
	s_waitcnt lgkmcnt(0)
	v_add_f32_e32 v86, v86, v88
	v_xor_b32_e32 v88, 16, v1
	v_cmp_lt_i32_e32 vcc, v88, v87
	s_nop 1
	v_cndmask_b32_e32 v88, v1, v88, vcc
	v_lshlrev_b32_e32 v88, 2, v88
	ds_bpermute_b32 v88, v88, v86
	s_waitcnt lgkmcnt(0)
	v_add_f32_e32 v86, v86, v88
	v_xor_b32_e32 v88, 32, v1
	v_cmp_lt_i32_e32 vcc, v88, v87
	s_nop 1
	v_cndmask_b32_e32 v87, v1, v88, vcc
	v_lshlrev_b32_e32 v87, 2, v87
	ds_bpermute_b32 v87, v87, v86
	s_and_saveexec_b64 s[6:7], s[4:5]
	s_cbranch_execz .LBB0_199
	s_waitcnt lgkmcnt(0)
	v_add_f32_e32 v2, v86, v87
	global_store_dword v85, v2, s[18:19]

.LBB0_200:
	s_cmp_eq_u64 s[20:21], 0
	s_cbranch_scc1 .LBB0_204
	v_mul_f32_e32 v2, v23, v23
	v_mul_f32_e32 v3, v25, v25
	v_fmac_f32_e32 v2, v22, v22
	v_fmac_f32_e32 v3, v24, v24
	v_add_f32_e32 v2, v2, v3
	v_mul_f32_e32 v3, v19, v19
	v_mul_f32_e32 v4, v21, v21
	v_fmac_f32_e32 v3, v18, v18
	v_fmac_f32_e32 v4, v20, v20
	v_add_f32_e32 v3, v3, v4
	v_add_f32_e32 v2, v2, v3
	s_waitcnt vmcnt(0)
	v_mul_f32_e32 v3, v31, v31
	v_mul_f32_e32 v4, v33, v33
	v_fmac_f32_e32 v3, v30, v30
	v_fmac_f32_e32 v4, v32, v32
	v_add_f32_e32 v3, v3, v4
	v_add_f32_e32 v2, v2, v3
	v_mul_f32_e32 v3, v27, v27
	v_mul_f32_e32 v4, v29, v29
	v_fmac_f32_e32 v3, v26, v26
	v_fmac_f32_e32 v4, v28, v28
	v_add_f32_e32 v3, v3, v4
	v_add_f32_e32 v2, v2, v3
	v_and_b32_e32 v3, 64, v1
	v_add_u32_e32 v3, 64, v3
	v_xor_b32_e32 v4, 1, v1
	v_cmp_lt_i32_e32 vcc, v4, v3
	v_cvt_pk_bf16_f32 v5, v24, v25
	s_nop 0
	v_cndmask_b32_e32 v4, v1, v4, vcc
	v_lshlrev_b32_e32 v4, 2, v4
	ds_bpermute_b32 v4, v4, v2
	s_waitcnt lgkmcnt(0)
	v_add_f32_e32 v2, v2, v4
	v_xor_b32_e32 v4, 2, v1
	v_cmp_lt_i32_e32 vcc, v4, v3
	s_nop 1
	v_cndmask_b32_e32 v4, v1, v4, vcc
	v_lshlrev_b32_e32 v4, 2, v4
	ds_bpermute_b32 v4, v4, v2
	s_waitcnt lgkmcnt(0)
	v_add_f32_e32 v2, v2, v4
	v_xor_b32_e32 v4, 4, v1
	v_cmp_lt_i32_e32 vcc, v4, v3
	s_nop 1
	v_cndmask_b32_e32 v4, v1, v4, vcc
	v_lshlrev_b32_e32 v4, 2, v4
	ds_bpermute_b32 v4, v4, v2
	s_waitcnt lgkmcnt(0)
	v_add_f32_e32 v2, v2, v4
	v_xor_b32_e32 v4, 8, v1
	v_cmp_lt_i32_e32 vcc, v4, v3
	s_nop 1
	v_cndmask_b32_e32 v4, v1, v4, vcc
	v_lshlrev_b32_e32 v4, 2, v4
	ds_bpermute_b32 v4, v4, v2
	s_waitcnt lgkmcnt(0)
	v_add_f32_e32 v2, v2, v4
	v_xor_b32_e32 v4, 16, v1
	v_cmp_lt_i32_e32 vcc, v4, v3
	s_nop 1
	v_cndmask_b32_e32 v4, v1, v4, vcc
	v_lshlrev_b32_e32 v4, 2, v4
	ds_bpermute_b32 v4, v4, v2
	s_waitcnt lgkmcnt(0)
	v_add_f32_e32 v2, v2, v4
	v_xor_b32_e32 v4, 32, v1
	v_cmp_lt_i32_e32 vcc, v4, v3
	s_nop 1
	v_cndmask_b32_e32 v3, v1, v4, vcc
	v_lshlrev_b32_e32 v3, 2, v3
	ds_bpermute_b32 v3, v3, v2
	v_cvt_pk_bf16_f32 v4, v22, v23
	global_store_dwordx2 v83, v[4:5], s[20:21] sc1
	v_cvt_pk_bf16_f32 v4, v18, v19
	v_cvt_pk_bf16_f32 v5, v20, v21
	global_store_dwordx2 v83, v[4:5], s[20:21] offset:512 sc1
	v_cvt_pk_bf16_f32 v4, v30, v31
	v_cvt_pk_bf16_f32 v5, v32, v33
	global_store_dwordx2 v83, v[4:5], s[20:21] offset:1024 sc1
	v_cvt_pk_bf16_f32 v4, v26, v27
	v_cvt_pk_bf16_f32 v5, v28, v29
	global_store_dwordx2 v83, v[4:5], s[20:21] offset:1536 sc1
	s_and_saveexec_b64 s[6:7], s[4:5]
	s_cbranch_execz .LBB0_203
	s_waitcnt lgkmcnt(0)
	v_add_f32_e32 v2, v2, v3
	global_store_dword v85, v2, s[22:23]

.LBB0_204:
	s_cmp_eq_u64 s[24:25], 0
	s_cbranch_scc1 .LBB0_208
	s_waitcnt vmcnt(0)
	v_mul_f32_e32 v2, v39, v39
	s_waitcnt lgkmcnt(0)
	v_mul_f32_e32 v3, v41, v41
	v_fmac_f32_e32 v2, v38, v38
	v_fmac_f32_e32 v3, v40, v40
	v_add_f32_e32 v2, v2, v3
	v_mul_f32_e32 v3, v35, v35
	v_mul_f32_e32 v4, v37, v37
	v_fmac_f32_e32 v3, v34, v34
	v_fmac_f32_e32 v4, v36, v36
	v_add_f32_e32 v3, v3, v4
	v_add_f32_e32 v2, v2, v3
	v_mul_f32_e32 v3, v47, v47
	v_mul_f32_e32 v4, v49, v49
	v_fmac_f32_e32 v3, v46, v46
	v_fmac_f32_e32 v4, v48, v48
	v_add_f32_e32 v3, v3, v4
	v_add_f32_e32 v2, v2, v3
	v_mul_f32_e32 v3, v43, v43
	v_mul_f32_e32 v4, v45, v45
	v_fmac_f32_e32 v3, v42, v42
	v_fmac_f32_e32 v4, v44, v44
	v_add_f32_e32 v3, v3, v4
	v_add_f32_e32 v2, v2, v3
	v_and_b32_e32 v3, 64, v1
	v_add_u32_e32 v3, 64, v3
	v_xor_b32_e32 v4, 1, v1
	v_cmp_lt_i32_e32 vcc, v4, v3
	v_cvt_pk_bf16_f32 v5, v40, v41
	s_nop 0
	v_cndmask_b32_e32 v4, v1, v4, vcc
	v_lshlrev_b32_e32 v4, 2, v4
	ds_bpermute_b32 v4, v4, v2
	s_waitcnt lgkmcnt(0)
	v_add_f32_e32 v2, v2, v4
	v_xor_b32_e32 v4, 2, v1
	v_cmp_lt_i32_e32 vcc, v4, v3
	s_nop 1
	v_cndmask_b32_e32 v4, v1, v4, vcc
	v_lshlrev_b32_e32 v4, 2, v4
	ds_bpermute_b32 v4, v4, v2
	s_waitcnt lgkmcnt(0)
	v_add_f32_e32 v2, v2, v4
	v_xor_b32_e32 v4, 4, v1
	v_cmp_lt_i32_e32 vcc, v4, v3
	s_nop 1
	v_cndmask_b32_e32 v4, v1, v4, vcc
	v_lshlrev_b32_e32 v4, 2, v4
	ds_bpermute_b32 v4, v4, v2
	s_waitcnt lgkmcnt(0)
	v_add_f32_e32 v2, v2, v4
	v_xor_b32_e32 v4, 8, v1
	v_cmp_lt_i32_e32 vcc, v4, v3
	s_nop 1
	v_cndmask_b32_e32 v4, v1, v4, vcc
	v_lshlrev_b32_e32 v4, 2, v4
	ds_bpermute_b32 v4, v4, v2
	s_waitcnt lgkmcnt(0)
	v_add_f32_e32 v2, v2, v4
	v_xor_b32_e32 v4, 16, v1
	v_cmp_lt_i32_e32 vcc, v4, v3
	s_nop 1
	v_cndmask_b32_e32 v4, v1, v4, vcc
	v_lshlrev_b32_e32 v4, 2, v4
	ds_bpermute_b32 v4, v4, v2
	s_waitcnt lgkmcnt(0)
	v_add_f32_e32 v2, v2, v4
	v_xor_b32_e32 v4, 32, v1
	v_cmp_lt_i32_e32 vcc, v4, v3
	s_nop 1
	v_cndmask_b32_e32 v3, v1, v4, vcc
	v_lshlrev_b32_e32 v3, 2, v3
	ds_bpermute_b32 v3, v3, v2
	v_cvt_pk_bf16_f32 v4, v38, v39
	global_store_dwordx2 v83, v[4:5], s[24:25] sc1
	v_cvt_pk_bf16_f32 v4, v34, v35
	v_cvt_pk_bf16_f32 v5, v36, v37
	global_store_dwordx2 v83, v[4:5], s[24:25] offset:512 sc1
	v_cvt_pk_bf16_f32 v4, v46, v47
	v_cvt_pk_bf16_f32 v5, v48, v49
	global_store_dwordx2 v83, v[4:5], s[24:25] offset:1024 sc1
	v_cvt_pk_bf16_f32 v4, v42, v43
	v_cvt_pk_bf16_f32 v5, v44, v45
	global_store_dwordx2 v83, v[4:5], s[24:25] offset:1536 sc1
	s_and_saveexec_b64 s[6:7], s[4:5]
	s_cbranch_execz .LBB0_207
	s_waitcnt lgkmcnt(0)
	v_add_f32_e32 v2, v2, v3
	global_store_dword v85, v2, s[26:27]

.LBB0_208:
	s_cmp_eq_u64 s[28:29], 0
	s_cbranch_scc1 .LBB0_212
	s_waitcnt vmcnt(0)
	v_mul_f32_e32 v2, v55, v55
	s_waitcnt lgkmcnt(0)
	v_mul_f32_e32 v3, v57, v57
	v_fmac_f32_e32 v2, v54, v54
	v_fmac_f32_e32 v3, v56, v56
	v_add_f32_e32 v2, v2, v3
	v_mul_f32_e32 v3, v51, v51
	v_mul_f32_e32 v4, v53, v53
	v_fmac_f32_e32 v3, v50, v50
	v_fmac_f32_e32 v4, v52, v52
	v_add_f32_e32 v3, v3, v4
	v_add_f32_e32 v2, v2, v3
	v_mul_f32_e32 v3, v63, v63
	v_mul_f32_e32 v4, v65, v65
	v_fmac_f32_e32 v3, v62, v62
	v_fmac_f32_e32 v4, v64, v64
	v_add_f32_e32 v3, v3, v4
	v_add_f32_e32 v2, v2, v3
	v_mul_f32_e32 v3, v59, v59
	v_mul_f32_e32 v4, v61, v61
	v_fmac_f32_e32 v3, v58, v58
	v_fmac_f32_e32 v4, v60, v60
	v_add_f32_e32 v3, v3, v4
	v_add_f32_e32 v2, v2, v3
	v_and_b32_e32 v3, 64, v1
	v_add_u32_e32 v3, 64, v3
	v_xor_b32_e32 v4, 1, v1
	v_cmp_lt_i32_e32 vcc, v4, v3
	v_cvt_pk_bf16_f32 v5, v56, v57
	s_nop 0
	v_cndmask_b32_e32 v4, v1, v4, vcc
	v_lshlrev_b32_e32 v4, 2, v4
	ds_bpermute_b32 v4, v4, v2
	s_waitcnt lgkmcnt(0)
	v_add_f32_e32 v2, v2, v4
	v_xor_b32_e32 v4, 2, v1
	v_cmp_lt_i32_e32 vcc, v4, v3
	s_nop 1
	v_cndmask_b32_e32 v4, v1, v4, vcc
	v_lshlrev_b32_e32 v4, 2, v4
	ds_bpermute_b32 v4, v4, v2
	s_waitcnt lgkmcnt(0)
	v_add_f32_e32 v2, v2, v4
	v_xor_b32_e32 v4, 4, v1
	v_cmp_lt_i32_e32 vcc, v4, v3
	s_nop 1
	v_cndmask_b32_e32 v4, v1, v4, vcc
	v_lshlrev_b32_e32 v4, 2, v4
	ds_bpermute_b32 v4, v4, v2
	s_waitcnt lgkmcnt(0)
	v_add_f32_e32 v2, v2, v4
	v_xor_b32_e32 v4, 8, v1
	v_cmp_lt_i32_e32 vcc, v4, v3
	s_nop 1
	v_cndmask_b32_e32 v4, v1, v4, vcc
	v_lshlrev_b32_e32 v4, 2, v4
	ds_bpermute_b32 v4, v4, v2
	s_waitcnt lgkmcnt(0)
	v_add_f32_e32 v2, v2, v4
	v_xor_b32_e32 v4, 16, v1
	v_cmp_lt_i32_e32 vcc, v4, v3
	s_nop 1
	v_cndmask_b32_e32 v4, v1, v4, vcc
	v_lshlrev_b32_e32 v4, 2, v4
	ds_bpermute_b32 v4, v4, v2
	s_waitcnt lgkmcnt(0)
	v_add_f32_e32 v2, v2, v4
	v_xor_b32_e32 v4, 32, v1
	v_cmp_lt_i32_e32 vcc, v4, v3
	s_nop 1
	v_cndmask_b32_e32 v3, v1, v4, vcc
	v_lshlrev_b32_e32 v3, 2, v3
	ds_bpermute_b32 v3, v3, v2
	v_cvt_pk_bf16_f32 v4, v54, v55
	global_store_dwordx2 v83, v[4:5], s[28:29] sc1
	v_cvt_pk_bf16_f32 v4, v50, v51
	v_cvt_pk_bf16_f32 v5, v52, v53
	global_store_dwordx2 v83, v[4:5], s[28:29] offset:512 sc1
	v_cvt_pk_bf16_f32 v4, v62, v63
	v_cvt_pk_bf16_f32 v5, v64, v65
	global_store_dwordx2 v83, v[4:5], s[28:29] offset:1024 sc1
	v_cvt_pk_bf16_f32 v4, v58, v59
	v_cvt_pk_bf16_f32 v5, v60, v61
	global_store_dwordx2 v83, v[4:5], s[28:29] offset:1536 sc1
	s_and_saveexec_b64 s[6:7], s[4:5]
	s_cbranch_execz .LBB0_211
	s_waitcnt lgkmcnt(0)
	v_add_f32_e32 v2, v2, v3
	global_store_dword v85, v2, s[30:31]

.LBB0_212:
	s_cmp_eq_u64 s[68:69], 0
	s_cbranch_scc1 .LBB0_83
	s_waitcnt vmcnt(0)
	v_mul_f32_e32 v2, v71, v71
	s_waitcnt lgkmcnt(0)
	v_mul_f32_e32 v3, v73, v73
	v_fmac_f32_e32 v2, v70, v70
	v_fmac_f32_e32 v3, v72, v72
	v_add_f32_e32 v2, v2, v3
	v_mul_f32_e32 v3, v67, v67
	v_mul_f32_e32 v4, v69, v69
	v_fmac_f32_e32 v3, v66, v66
	v_fmac_f32_e32 v4, v68, v68
	v_add_f32_e32 v3, v3, v4
	v_add_f32_e32 v2, v2, v3
	v_mul_f32_e32 v3, v79, v79
	v_mul_f32_e32 v4, v81, v81
	v_fmac_f32_e32 v3, v78, v78
	v_fmac_f32_e32 v4, v80, v80
	v_add_f32_e32 v3, v3, v4
	v_add_f32_e32 v2, v2, v3
	v_mul_f32_e32 v3, v75, v75
	v_mul_f32_e32 v4, v77, v77
	v_fmac_f32_e32 v3, v74, v74
	v_fmac_f32_e32 v4, v76, v76
	v_add_f32_e32 v3, v3, v4
	v_add_f32_e32 v2, v2, v3
	v_and_b32_e32 v3, 64, v1
	v_add_u32_e32 v3, 64, v3
	v_xor_b32_e32 v4, 1, v1
	v_cmp_lt_i32_e32 vcc, v4, v3
	v_cvt_pk_bf16_f32 v5, v72, v73
	s_nop 0
	v_cndmask_b32_e32 v4, v1, v4, vcc
	v_lshlrev_b32_e32 v4, 2, v4
	ds_bpermute_b32 v4, v4, v2
	s_waitcnt lgkmcnt(0)
	v_add_f32_e32 v2, v2, v4
	v_xor_b32_e32 v4, 2, v1
	v_cmp_lt_i32_e32 vcc, v4, v3
	s_nop 1
	v_cndmask_b32_e32 v4, v1, v4, vcc
	v_lshlrev_b32_e32 v4, 2, v4
	ds_bpermute_b32 v4, v4, v2
	s_waitcnt lgkmcnt(0)
	v_add_f32_e32 v2, v2, v4
	v_xor_b32_e32 v4, 4, v1
	v_cmp_lt_i32_e32 vcc, v4, v3
	s_nop 1
	v_cndmask_b32_e32 v4, v1, v4, vcc
	v_lshlrev_b32_e32 v4, 2, v4
	ds_bpermute_b32 v4, v4, v2
	s_waitcnt lgkmcnt(0)
	v_add_f32_e32 v2, v2, v4
	v_xor_b32_e32 v4, 8, v1
	v_cmp_lt_i32_e32 vcc, v4, v3
	s_nop 1
	v_cndmask_b32_e32 v4, v1, v4, vcc
	v_lshlrev_b32_e32 v4, 2, v4
	ds_bpermute_b32 v4, v4, v2
	s_waitcnt lgkmcnt(0)
	v_add_f32_e32 v2, v2, v4
	v_xor_b32_e32 v4, 16, v1
	v_cmp_lt_i32_e32 vcc, v4, v3
	s_nop 1
	v_cndmask_b32_e32 v4, v1, v4, vcc
	v_lshlrev_b32_e32 v4, 2, v4
	ds_bpermute_b32 v4, v4, v2
	s_waitcnt lgkmcnt(0)
	v_add_f32_e32 v2, v2, v4
	v_xor_b32_e32 v4, 32, v1
	v_cmp_lt_i32_e32 vcc, v4, v3
	s_nop 1
	v_cndmask_b32_e32 v3, v1, v4, vcc
	v_lshlrev_b32_e32 v3, 2, v3
	ds_bpermute_b32 v3, v3, v2
	v_cvt_pk_bf16_f32 v4, v70, v71
	global_store_dwordx2 v83, v[4:5], s[68:69] sc1
	v_cvt_pk_bf16_f32 v4, v66, v67
	v_cvt_pk_bf16_f32 v5, v68, v69
	global_store_dwordx2 v83, v[4:5], s[68:69] offset:512 sc1
	v_cvt_pk_bf16_f32 v4, v78, v79
	v_cvt_pk_bf16_f32 v5, v80, v81
	global_store_dwordx2 v83, v[4:5], s[68:69] offset:1024 sc1
	v_cvt_pk_bf16_f32 v4, v74, v75
	v_cvt_pk_bf16_f32 v5, v76, v77
	global_store_dwordx2 v83, v[4:5], s[68:69] offset:1536 sc1
	s_and_saveexec_b64 s[6:7], s[4:5]
	s_cbranch_execz .LBB0_82
	s_waitcnt lgkmcnt(0)
	v_add_f32_e32 v2, v2, v3
	global_store_dword v85, v2, s[36:37]
	s_branch .LBB0_82

.LBB0_253:
	s_lshl_b32 s2, s6, 8
	v_mov_b32_e32 v134, v1
	v_mov_b32_e32 v181, v168
	s_add_i32 s2, s2, s59
	s_lshl_b32 s6, s4, 8
	v_add_u32_e32 v140, s2, v134
	v_ashrrev_i32_e32 v141, 31, v140
	v_lshl_add_u64 v[142:143], v[140:141], 2, s[12:13]
	v_add_u32_e32 v154, 16, v140
	global_load_dword v134, v[142:143], off
	v_ashrrev_i32_e32 v155, 31, v154
	v_add_u32_e32 v152, 32, v140
	v_add_u32_e32 v150, 48, v140
	v_add_u32_e32 v148, 0x80, v140
	v_add_u32_e32 v146, 0x90, v140
	v_add_u32_e32 v144, 0xa0, v140
	v_add_u32_e32 v142, 0xb0, v140
	v_lshl_add_u64 v[156:157], v[154:155], 2, s[12:13]
	v_ashrrev_i32_e32 v153, 31, v152
	v_ashrrev_i32_e32 v151, 31, v150
	v_ashrrev_i32_e32 v149, 31, v148
	v_ashrrev_i32_e32 v147, 31, v146
	v_ashrrev_i32_e32 v145, 31, v144
	v_ashrrev_i32_e32 v143, 31, v142
	v_lshl_add_u64 v[158:159], v[152:153], 2, s[12:13]
	v_lshl_add_u64 v[160:161], v[150:151], 2, s[12:13]
	v_lshl_add_u64 v[162:163], v[148:149], 2, s[12:13]
	v_lshl_add_u64 v[164:165], v[146:147], 2, s[12:13]
	v_lshl_add_u64 v[166:167], v[144:145], 2, s[12:13]
	v_lshl_add_u64 v[182:183], v[142:143], 2, s[12:13]
	global_load_dword v180, v[156:157], off
	global_load_dword v179, v[158:159], off
	global_load_dword v178, v[160:161], off
	global_load_dword v177, v[162:163], off
	global_load_dword v176, v[164:165], off
	global_load_dword v175, v[166:167], off
	global_load_dword v174, v[182:183], off
	s_ashr_i32 s2, s4, 2
	s_ashr_i32 s3, s2, 31
	s_lshl_b64 s[4:5], s[2:3], 20
	s_add_u32 s28, s51, s4
	s_addc_u32 s29, s52, s5
	s_add_u32 s34, s53, s4
	s_addc_u32 s35, s54, s5
	s_lshl_b64 s[2:3], s[2:3], 19
	s_add_u32 s30, s55, s2
	s_addc_u32 s31, s56, s3
	s_add_u32 s36, s57, s2
	s_addc_u32 s37, s58, s3
	s_and_b32 s2, s6, 0x300
	s_or_b32 s2, s2, s60
	v_lshlrev_b64 v[162:163], 11, v[140:141]
	v_lshlrev_b64 v[164:165], 10, v[140:141]
	v_lshl_add_u32 v140, v181, 2, s2
	v_lshl_add_u64 v[156:157], s[34:35], 0, v[162:163]
	v_lshl_add_u64 v[158:159], s[36:37], 0, v[164:165]
	v_cmp_lt_i32_e32 vcc, s66, v140
	s_waitcnt vmcnt(0)
	v_fmamk_f32 v134, v134, 0x3a800000, v173
	v_rsq_f32_e32 v160, v134
	s_nop 0
	v_pk_mul_f32 v[128:129], v[128:129], v[160:161] op_sel_hi:[1,0]
	v_pk_mul_f32 v[126:127], v[126:127], v[160:161] op_sel_hi:[1,0]
	s_nop 0
	v_cvt_pk_bf16_f32 v166, v126, v127
	v_cvt_pk_bf16_f32 v167, v128, v129
	s_and_saveexec_b64 s[2:3], vcc
	s_xor_b64 s[4:5], exec, s[2:3]
	s_cbranch_execz .LBB0_255
	v_mov_b32_e32 v141, v135
	v_lshl_add_u64 v[182:183], v[140:141], 2, v[156:157]
	global_store_dwordx4 v[182:183], v[126:129], off offset:-2048 nt
	s_nop 1
	v_lshl_add_u64 v[126:127], v[140:141], 1, v[158:159]
	global_store_dwordx2 v[126:127], v[166:167], off offset:-1024 sc1
.LBB0_255:
	s_or_saveexec_b64 s[4:5], s[4:5]
	v_lshl_add_u64 v[162:163], s[28:29], 0, v[162:163]
	v_lshl_add_u64 v[164:165], s[30:31], 0, v[164:165]
	v_ashrrev_i32_e32 v141, 31, v140
	s_xor_b64 exec, exec, s[4:5]
	s_cbranch_execz .LBB0_257
	v_lshl_add_u64 v[182:183], v[140:141], 2, v[162:163]
	global_store_dwordx4 v[182:183], v[126:129], off nt
	s_nop 1
	v_lshl_add_u64 v[126:127], v[140:141], 1, v[164:165]
	global_store_dwordx2 v[126:127], v[166:167], off sc1
.LBB0_257:
	s_or_b64 exec, exec, s[4:5]
	v_mov_b32_e32 v161, v160
	v_mov_b32_e32 v126, v160
	v_mov_b32_e32 v127, v160
	v_add_u32_e32 v134, 16, v140
	v_pk_mul_f32 v[124:125], v[124:125], v[126:127]
	v_pk_mul_f32 v[122:123], v[122:123], v[160:161]
	v_cmp_lt_i32_e64 s[4:5], s67, v140
	v_cvt_pk_bf16_f32 v126, v122, v123
	v_cvt_pk_bf16_f32 v127, v124, v125
	s_and_saveexec_b64 s[2:3], s[4:5]
	s_xor_b64 s[6:7], exec, s[2:3]
	s_cbranch_execz .LBB0_259
	v_lshl_add_u64 v[128:129], v[134:135], 2, v[156:157]
	global_store_dwordx4 v[128:129], v[122:125], off offset:-2048 nt
	s_nop 1
	v_lshl_add_u64 v[122:123], v[134:135], 1, v[158:159]
	global_store_dwordx2 v[122:123], v[126:127], off offset:-1024 sc1
.LBB0_259:
	s_andn2_saveexec_b64 s[6:7], s[6:7]
	s_cbranch_execz .LBB0_261
	v_lshl_add_u64 v[128:129], v[140:141], 2, v[162:163]
	global_store_dwordx4 v[128:129], v[122:125], off offset:64 nt
	s_nop 1
	v_lshl_add_u64 v[122:123], v[140:141], 1, v[164:165]
	global_store_dwordx2 v[122:123], v[126:127], off offset:32 sc1
.LBB0_261:
	s_or_b64 exec, exec, s[6:7]
	v_mov_b32_e32 v124, v160
	v_mov_b32_e32 v125, v160
	v_add_u32_e32 v122, 0x80, v140
	v_pk_mul_f32 v[120:121], v[120:121], v[124:125]
	v_pk_mul_f32 v[118:119], v[118:119], v[160:161]
	v_cmp_lt_i32_e64 s[8:9], s68, v140
	v_cvt_pk_bf16_f32 v124, v118, v119
	v_cvt_pk_bf16_f32 v125, v120, v121
	s_and_saveexec_b64 s[2:3], s[8:9]
	s_xor_b64 s[6:7], exec, s[2:3]
	s_cbranch_execz .LBB0_263
	v_mov_b32_e32 v123, v135
	v_lshl_add_u64 v[126:127], v[122:123], 2, v[156:157]
	global_store_dwordx4 v[126:127], v[118:121], off offset:-2048 nt
	s_nop 1
	v_lshl_add_u64 v[118:119], v[122:123], 1, v[158:159]
	global_store_dwordx2 v[118:119], v[124:125], off offset:-1024 sc1
.LBB0_263:
	s_andn2_saveexec_b64 s[6:7], s[6:7]
	s_cbranch_execz .LBB0_265
	v_lshl_add_u64 v[126:127], v[140:141], 2, v[162:163]
	global_store_dwordx4 v[126:127], v[118:121], off offset:512 nt
	s_nop 1
	v_lshl_add_u64 v[118:119], v[140:141], 1, v[164:165]
	global_store_dwordx2 v[118:119], v[124:125], off offset:256 sc1
.LBB0_265:
	s_or_b64 exec, exec, s[6:7]
	v_mov_b32_e32 v120, v160
	v_mov_b32_e32 v121, v160
	v_add_u32_e32 v118, 0x90, v140
	v_pk_mul_f32 v[116:117], v[116:117], v[120:121]
	v_pk_mul_f32 v[114:115], v[114:115], v[160:161]
	v_cmp_lt_i32_e64 s[6:7], s69, v140
	v_cvt_pk_bf16_f32 v120, v114, v115
	v_cvt_pk_bf16_f32 v121, v116, v117
	s_and_saveexec_b64 s[2:3], s[6:7]
	s_xor_b64 s[38:39], exec, s[2:3]
	s_cbranch_execz .LBB0_267
	v_mov_b32_e32 v119, v135
	v_lshl_add_u64 v[124:125], v[118:119], 2, v[156:157]
	global_store_dwordx4 v[124:125], v[114:117], off offset:-2048 nt
	s_nop 1
	v_lshl_add_u64 v[114:115], v[118:119], 1, v[158:159]
	global_store_dwordx2 v[114:115], v[120:121], off offset:-1024 sc1
.LBB0_267:
	s_andn2_saveexec_b64 s[38:39], s[38:39]
	s_cbranch_execz .LBB0_269
	v_lshl_add_u64 v[124:125], v[140:141], 2, v[162:163]
	global_store_dwordx4 v[124:125], v[114:117], off offset:576 nt
	s_nop 1
	v_lshl_add_u64 v[114:115], v[140:141], 1, v[164:165]
	global_store_dwordx2 v[114:115], v[120:121], off offset:288 sc1
.LBB0_269:
	s_or_b64 exec, exec, s[38:39]
	v_fmamk_f32 v114, v180, 0x3a800000, v173
	v_rsq_f32_e32 v120, v114
	v_lshlrev_b64 v[124:125], 11, v[154:155]
	v_lshlrev_b64 v[126:127], 10, v[154:155]
	v_lshl_add_u64 v[114:115], s[34:35], 0, v[124:125]
	v_lshl_add_u64 v[116:117], s[36:37], 0, v[126:127]
	v_pk_mul_f32 v[112:113], v[112:113], v[120:121] op_sel_hi:[1,0]
	v_pk_mul_f32 v[110:111], v[110:111], v[120:121] op_sel_hi:[1,0]
	s_nop 0
	v_cvt_pk_bf16_f32 v128, v110, v111
	v_cvt_pk_bf16_f32 v129, v112, v113
	s_and_saveexec_b64 s[2:3], vcc
	s_xor_b64 s[38:39], exec, s[2:3]
	s_cbranch_execz .LBB0_271
	v_mov_b32_e32 v154, v140
	v_mov_b32_e32 v155, v135
	v_lshl_add_u64 v[156:157], v[154:155], 2, v[114:115]
	global_store_dwordx4 v[156:157], v[110:113], off offset:-2048 nt
	s_nop 1
	v_lshl_add_u64 v[110:111], v[154:155], 1, v[116:117]
	global_store_dwordx2 v[110:111], v[128:129], off offset:-1024 sc1
.LBB0_271:
	s_or_saveexec_b64 s[38:39], s[38:39]
	v_lshl_add_u64 v[124:125], s[28:29], 0, v[124:125]
	v_lshl_add_u64 v[126:127], s[30:31], 0, v[126:127]
	s_xor_b64 exec, exec, s[38:39]
	s_cbranch_execz .LBB0_273
	v_lshl_add_u64 v[154:155], v[140:141], 2, v[124:125]
	global_store_dwordx4 v[154:155], v[110:113], off nt
	s_nop 1
	v_lshl_add_u64 v[110:111], v[140:141], 1, v[126:127]
	global_store_dwordx2 v[110:111], v[128:129], off sc1
.LBB0_273:
	s_or_b64 exec, exec, s[38:39]
	v_mov_b32_e32 v121, v120
	v_mov_b32_e32 v110, v120
	v_mov_b32_e32 v111, v120
	v_pk_mul_f32 v[108:109], v[108:109], v[110:111]
	v_pk_mul_f32 v[106:107], v[106:107], v[120:121]
	s_nop 0
	v_cvt_pk_bf16_f32 v110, v106, v107
	v_cvt_pk_bf16_f32 v111, v108, v109
	s_and_saveexec_b64 s[2:3], s[4:5]
	s_xor_b64 s[38:39], exec, s[2:3]
	s_cbranch_execz .LBB0_275
	v_lshl_add_u64 v[112:113], v[134:135], 2, v[114:115]
	global_store_dwordx4 v[112:113], v[106:109], off offset:-2048 nt
	s_nop 1
	v_lshl_add_u64 v[106:107], v[134:135], 1, v[116:117]
	global_store_dwordx2 v[106:107], v[110:111], off offset:-1024 sc1
.LBB0_275:
	s_andn2_saveexec_b64 s[38:39], s[38:39]
	s_cbranch_execz .LBB0_277
	v_lshl_add_u64 v[112:113], v[140:141], 2, v[124:125]
	global_store_dwordx4 v[112:113], v[106:109], off offset:64 nt
	s_nop 1
	v_lshl_add_u64 v[106:107], v[140:141], 1, v[126:127]
	global_store_dwordx2 v[106:107], v[110:111], off offset:32 sc1
.LBB0_277:
	s_or_b64 exec, exec, s[38:39]
	v_mov_b32_e32 v106, v120
	v_mov_b32_e32 v107, v120
	v_pk_mul_f32 v[104:105], v[104:105], v[106:107]
	v_pk_mul_f32 v[102:103], v[102:103], v[120:121]
	s_nop 0
	v_cvt_pk_bf16_f32 v106, v102, v103
	v_cvt_pk_bf16_f32 v107, v104, v105
	s_and_saveexec_b64 s[2:3], s[8:9]
	s_xor_b64 s[38:39], exec, s[2:3]
	s_cbranch_execz .LBB0_279
	v_mov_b32_e32 v123, v135
	v_lshl_add_u64 v[108:109], v[122:123], 2, v[114:115]
	global_store_dwordx4 v[108:109], v[102:105], off offset:-2048 nt
	s_nop 1
	v_lshl_add_u64 v[102:103], v[122:123], 1, v[116:117]
	global_store_dwordx2 v[102:103], v[106:107], off offset:-1024 sc1
.LBB0_279:
	s_andn2_saveexec_b64 s[38:39], s[38:39]
	s_cbranch_execz .LBB0_281
	v_lshl_add_u64 v[108:109], v[140:141], 2, v[124:125]
	global_store_dwordx4 v[108:109], v[102:105], off offset:512 nt
	s_nop 1
	v_lshl_add_u64 v[102:103], v[140:141], 1, v[126:127]
	global_store_dwordx2 v[102:103], v[106:107], off offset:256 sc1
.LBB0_281:
	s_or_b64 exec, exec, s[38:39]
	v_mov_b32_e32 v102, v120
	v_mov_b32_e32 v103, v120
	v_pk_mul_f32 v[100:101], v[100:101], v[102:103]
	v_pk_mul_f32 v[98:99], v[98:99], v[120:121]
	s_nop 0
	v_cvt_pk_bf16_f32 v102, v98, v99
	v_cvt_pk_bf16_f32 v103, v100, v101
	s_and_saveexec_b64 s[2:3], s[6:7]
	s_xor_b64 s[38:39], exec, s[2:3]
	s_cbranch_execz .LBB0_283
	v_mov_b32_e32 v119, v135
	v_lshl_add_u64 v[104:105], v[118:119], 2, v[114:115]
	global_store_dwordx4 v[104:105], v[98:101], off offset:-2048 nt
	s_nop 1
	v_lshl_add_u64 v[98:99], v[118:119], 1, v[116:117]
	global_store_dwordx2 v[98:99], v[102:103], off offset:-1024 sc1
.LBB0_283:
	s_andn2_saveexec_b64 s[38:39], s[38:39]
	s_cbranch_execz .LBB0_285
	v_lshl_add_u64 v[104:105], v[140:141], 2, v[124:125]
	global_store_dwordx4 v[104:105], v[98:101], off offset:576 nt
	s_nop 1
	v_lshl_add_u64 v[98:99], v[140:141], 1, v[126:127]
	global_store_dwordx2 v[98:99], v[102:103], off offset:288 sc1
.LBB0_285:
	s_or_b64 exec, exec, s[38:39]
	v_fmamk_f32 v98, v179, 0x3a800000, v173
	v_rsq_f32_e32 v102, v98
	v_lshlrev_b64 v[104:105], 11, v[152:153]
	v_lshlrev_b64 v[106:107], 10, v[152:153]
	v_lshl_add_u64 v[98:99], s[34:35], 0, v[104:105]
	v_lshl_add_u64 v[100:101], s[36:37], 0, v[106:107]
	v_pk_mul_f32 v[96:97], v[96:97], v[102:103] op_sel_hi:[1,0]
	v_pk_mul_f32 v[94:95], v[94:95], v[102:103] op_sel_hi:[1,0]
	s_nop 0
	v_cvt_pk_bf16_f32 v108, v94, v95
	v_cvt_pk_bf16_f32 v109, v96, v97
	s_and_saveexec_b64 s[2:3], vcc
	s_xor_b64 s[38:39], exec, s[2:3]
	s_cbranch_execz .LBB0_287
	v_mov_b32_e32 v110, v140
	v_mov_b32_e32 v111, v135
	v_lshl_add_u64 v[112:113], v[110:111], 2, v[98:99]
	global_store_dwordx4 v[112:113], v[94:97], off offset:-2048 nt
	s_nop 1
	v_lshl_add_u64 v[94:95], v[110:111], 1, v[100:101]
	global_store_dwordx2 v[94:95], v[108:109], off offset:-1024 sc1
.LBB0_287:
	s_or_saveexec_b64 s[38:39], s[38:39]
	v_lshl_add_u64 v[104:105], s[28:29], 0, v[104:105]
	v_lshl_add_u64 v[106:107], s[30:31], 0, v[106:107]
	s_xor_b64 exec, exec, s[38:39]
	s_cbranch_execz .LBB0_289
	v_lshl_add_u64 v[110:111], v[140:141], 2, v[104:105]
	global_store_dwordx4 v[110:111], v[94:97], off nt
	s_nop 1
	v_lshl_add_u64 v[94:95], v[140:141], 1, v[106:107]
	global_store_dwordx2 v[94:95], v[108:109], off sc1
.LBB0_289:
	s_or_b64 exec, exec, s[38:39]
	v_mov_b32_e32 v103, v102
	v_mov_b32_e32 v94, v102
	v_mov_b32_e32 v95, v102
	v_pk_mul_f32 v[92:93], v[92:93], v[94:95]
	v_pk_mul_f32 v[90:91], v[90:91], v[102:103]
	s_nop 0
	v_cvt_pk_bf16_f32 v94, v90, v91
	v_cvt_pk_bf16_f32 v95, v92, v93
	s_and_saveexec_b64 s[2:3], s[4:5]
	s_xor_b64 s[38:39], exec, s[2:3]
	s_cbranch_execz .LBB0_291
	v_lshl_add_u64 v[96:97], v[134:135], 2, v[98:99]
	global_store_dwordx4 v[96:97], v[90:93], off offset:-2048 nt
	s_nop 1
	v_lshl_add_u64 v[90:91], v[134:135], 1, v[100:101]
	global_store_dwordx2 v[90:91], v[94:95], off offset:-1024 sc1
.LBB0_291:
	s_andn2_saveexec_b64 s[38:39], s[38:39]
	s_cbranch_execz .LBB0_293
	v_lshl_add_u64 v[96:97], v[140:141], 2, v[104:105]
	global_store_dwordx4 v[96:97], v[90:93], off offset:64 nt
	s_nop 1
	v_lshl_add_u64 v[90:91], v[140:141], 1, v[106:107]
	global_store_dwordx2 v[90:91], v[94:95], off offset:32 sc1
.LBB0_293:
	s_or_b64 exec, exec, s[38:39]
	v_mov_b32_e32 v90, v102
	v_mov_b32_e32 v91, v102
	v_pk_mul_f32 v[88:89], v[88:89], v[90:91]
	v_pk_mul_f32 v[86:87], v[86:87], v[102:103]
	s_nop 0
	v_cvt_pk_bf16_f32 v90, v86, v87
	v_cvt_pk_bf16_f32 v91, v88, v89
	s_and_saveexec_b64 s[2:3], s[8:9]
	s_xor_b64 s[38:39], exec, s[2:3]
	s_cbranch_execz .LBB0_295
	v_mov_b32_e32 v123, v135
	v_lshl_add_u64 v[92:93], v[122:123], 2, v[98:99]
	global_store_dwordx4 v[92:93], v[86:89], off offset:-2048 nt
	s_nop 1
	v_lshl_add_u64 v[86:87], v[122:123], 1, v[100:101]
	global_store_dwordx2 v[86:87], v[90:91], off offset:-1024 sc1
.LBB0_295:
	s_andn2_saveexec_b64 s[38:39], s[38:39]
	s_cbranch_execz .LBB0_297
	v_lshl_add_u64 v[92:93], v[140:141], 2, v[104:105]
	global_store_dwordx4 v[92:93], v[86:89], off offset:512 nt
	s_nop 1
	v_lshl_add_u64 v[86:87], v[140:141], 1, v[106:107]
	global_store_dwordx2 v[86:87], v[90:91], off offset:256 sc1
.LBB0_297:
	s_or_b64 exec, exec, s[38:39]
	v_mov_b32_e32 v86, v102
	v_mov_b32_e32 v87, v102
	v_pk_mul_f32 v[84:85], v[84:85], v[86:87]
	v_pk_mul_f32 v[82:83], v[82:83], v[102:103]
	s_nop 0
	v_cvt_pk_bf16_f32 v86, v82, v83
	v_cvt_pk_bf16_f32 v87, v84, v85
	s_and_saveexec_b64 s[2:3], s[6:7]
	s_xor_b64 s[38:39], exec, s[2:3]
	s_cbranch_execz .LBB0_299
	v_mov_b32_e32 v119, v135
	v_lshl_add_u64 v[88:89], v[118:119], 2, v[98:99]
	global_store_dwordx4 v[88:89], v[82:85], off offset:-2048 nt
	s_nop 1
	v_lshl_add_u64 v[82:83], v[118:119], 1, v[100:101]
	global_store_dwordx2 v[82:83], v[86:87], off offset:-1024 sc1
.LBB0_299:
	s_andn2_saveexec_b64 s[38:39], s[38:39]
	s_cbranch_execz .LBB0_301
	v_lshl_add_u64 v[88:89], v[140:141], 2, v[104:105]
	global_store_dwordx4 v[88:89], v[82:85], off offset:576 nt
	s_nop 1
	v_lshl_add_u64 v[82:83], v[140:141], 1, v[106:107]
	global_store_dwordx2 v[82:83], v[86:87], off offset:288 sc1
.LBB0_301:
	s_or_b64 exec, exec, s[38:39]
	v_fmamk_f32 v82, v178, 0x3a800000, v173
	v_rsq_f32_e32 v86, v82
	v_lshlrev_b64 v[88:89], 11, v[150:151]
	v_lshlrev_b64 v[90:91], 10, v[150:151]
	v_lshl_add_u64 v[82:83], s[34:35], 0, v[88:89]
	v_lshl_add_u64 v[84:85], s[36:37], 0, v[90:91]
	v_pk_mul_f32 v[80:81], v[80:81], v[86:87] op_sel_hi:[1,0]
	v_pk_mul_f32 v[78:79], v[78:79], v[86:87] op_sel_hi:[1,0]
	s_nop 0
	v_cvt_pk_bf16_f32 v92, v78, v79
	v_cvt_pk_bf16_f32 v93, v80, v81
	s_and_saveexec_b64 s[2:3], vcc
	s_xor_b64 s[38:39], exec, s[2:3]
	s_cbranch_execz .LBB0_303
	v_mov_b32_e32 v94, v140
	v_mov_b32_e32 v95, v135
	v_lshl_add_u64 v[96:97], v[94:95], 2, v[82:83]
	global_store_dwordx4 v[96:97], v[78:81], off offset:-2048 nt
	s_nop 1
	v_lshl_add_u64 v[78:79], v[94:95], 1, v[84:85]
	global_store_dwordx2 v[78:79], v[92:93], off offset:-1024 sc1
.LBB0_303:
	s_or_saveexec_b64 s[38:39], s[38:39]
	v_lshl_add_u64 v[88:89], s[28:29], 0, v[88:89]
	v_lshl_add_u64 v[90:91], s[30:31], 0, v[90:91]
	s_xor_b64 exec, exec, s[38:39]
	s_cbranch_execz .LBB0_305
	v_lshl_add_u64 v[94:95], v[140:141], 2, v[88:89]
	global_store_dwordx4 v[94:95], v[78:81], off nt
	s_nop 1
	v_lshl_add_u64 v[78:79], v[140:141], 1, v[90:91]
	global_store_dwordx2 v[78:79], v[92:93], off sc1
.LBB0_305:
	s_or_b64 exec, exec, s[38:39]
	v_mov_b32_e32 v87, v86
	v_mov_b32_e32 v78, v86
	v_mov_b32_e32 v79, v86
	v_pk_mul_f32 v[76:77], v[76:77], v[78:79]
	v_pk_mul_f32 v[74:75], v[74:75], v[86:87]
	s_nop 0
	v_cvt_pk_bf16_f32 v78, v74, v75
	v_cvt_pk_bf16_f32 v79, v76, v77
	s_and_saveexec_b64 s[2:3], s[4:5]
	s_xor_b64 s[38:39], exec, s[2:3]
	s_cbranch_execz .LBB0_307
	v_lshl_add_u64 v[80:81], v[134:135], 2, v[82:83]
	global_store_dwordx4 v[80:81], v[74:77], off offset:-2048 nt
	s_nop 1
	v_lshl_add_u64 v[74:75], v[134:135], 1, v[84:85]
	global_store_dwordx2 v[74:75], v[78:79], off offset:-1024 sc1
.LBB0_307:
	s_andn2_saveexec_b64 s[38:39], s[38:39]
	s_cbranch_execz .LBB0_309
	v_lshl_add_u64 v[80:81], v[140:141], 2, v[88:89]
	global_store_dwordx4 v[80:81], v[74:77], off offset:64 nt
	s_nop 1
	v_lshl_add_u64 v[74:75], v[140:141], 1, v[90:91]
	global_store_dwordx2 v[74:75], v[78:79], off offset:32 sc1
.LBB0_309:
	s_or_b64 exec, exec, s[38:39]
	v_mov_b32_e32 v74, v86
	v_mov_b32_e32 v75, v86
	v_pk_mul_f32 v[72:73], v[72:73], v[74:75]
	v_pk_mul_f32 v[70:71], v[70:71], v[86:87]
	s_nop 0
	v_cvt_pk_bf16_f32 v74, v70, v71
	v_cvt_pk_bf16_f32 v75, v72, v73
	s_and_saveexec_b64 s[2:3], s[8:9]
	s_xor_b64 s[38:39], exec, s[2:3]
	s_cbranch_execz .LBB0_311
	v_mov_b32_e32 v123, v135
	v_lshl_add_u64 v[76:77], v[122:123], 2, v[82:83]
	global_store_dwordx4 v[76:77], v[70:73], off offset:-2048 nt
	s_nop 1
	v_lshl_add_u64 v[70:71], v[122:123], 1, v[84:85]
	global_store_dwordx2 v[70:71], v[74:75], off offset:-1024 sc1
.LBB0_311:
	s_andn2_saveexec_b64 s[38:39], s[38:39]
	s_cbranch_execz .LBB0_313
	v_lshl_add_u64 v[76:77], v[140:141], 2, v[88:89]
	global_store_dwordx4 v[76:77], v[70:73], off offset:512 nt
	s_nop 1
	v_lshl_add_u64 v[70:71], v[140:141], 1, v[90:91]
	global_store_dwordx2 v[70:71], v[74:75], off offset:256 sc1
.LBB0_313:
	s_or_b64 exec, exec, s[38:39]
	v_mov_b32_e32 v70, v86
	v_mov_b32_e32 v71, v86
	v_pk_mul_f32 v[68:69], v[68:69], v[70:71]
	v_pk_mul_f32 v[66:67], v[66:67], v[86:87]
	s_nop 0
	v_cvt_pk_bf16_f32 v70, v66, v67
	v_cvt_pk_bf16_f32 v71, v68, v69
	s_and_saveexec_b64 s[2:3], s[6:7]
	s_xor_b64 s[38:39], exec, s[2:3]
	s_cbranch_execz .LBB0_315
	v_mov_b32_e32 v119, v135
	v_lshl_add_u64 v[72:73], v[118:119], 2, v[82:83]
	global_store_dwordx4 v[72:73], v[66:69], off offset:-2048 nt
	s_nop 1
	v_lshl_add_u64 v[66:67], v[118:119], 1, v[84:85]
	global_store_dwordx2 v[66:67], v[70:71], off offset:-1024 sc1
.LBB0_315:
	s_andn2_saveexec_b64 s[38:39], s[38:39]
	s_cbranch_execz .LBB0_317
	v_lshl_add_u64 v[72:73], v[140:141], 2, v[88:89]
	global_store_dwordx4 v[72:73], v[66:69], off offset:576 nt
	s_nop 1
	v_lshl_add_u64 v[66:67], v[140:141], 1, v[90:91]
	global_store_dwordx2 v[66:67], v[70:71], off offset:288 sc1
.LBB0_317:
	s_or_b64 exec, exec, s[38:39]
	v_fmamk_f32 v66, v177, 0x3a800000, v173
	v_rsq_f32_e32 v70, v66
	v_lshlrev_b64 v[72:73], 11, v[148:149]
	v_lshlrev_b64 v[74:75], 10, v[148:149]
	v_lshl_add_u64 v[66:67], s[34:35], 0, v[72:73]
	v_lshl_add_u64 v[68:69], s[36:37], 0, v[74:75]
	v_pk_mul_f32 v[64:65], v[64:65], v[70:71] op_sel_hi:[1,0]
	v_pk_mul_f32 v[62:63], v[62:63], v[70:71] op_sel_hi:[1,0]
	s_nop 0
	v_cvt_pk_bf16_f32 v76, v62, v63
	v_cvt_pk_bf16_f32 v77, v64, v65
	s_and_saveexec_b64 s[2:3], vcc
	s_xor_b64 s[38:39], exec, s[2:3]
	s_cbranch_execz .LBB0_319
	v_mov_b32_e32 v78, v140
	v_mov_b32_e32 v79, v135
	v_lshl_add_u64 v[80:81], v[78:79], 2, v[66:67]
	global_store_dwordx4 v[80:81], v[62:65], off offset:-2048 nt
	s_nop 1
	v_lshl_add_u64 v[62:63], v[78:79], 1, v[68:69]
	global_store_dwordx2 v[62:63], v[76:77], off offset:-1024 sc1
.LBB0_319:
	s_or_saveexec_b64 s[38:39], s[38:39]
	v_lshl_add_u64 v[72:73], s[28:29], 0, v[72:73]
	v_lshl_add_u64 v[74:75], s[30:31], 0, v[74:75]
	s_xor_b64 exec, exec, s[38:39]
	s_cbranch_execz .LBB0_321
	v_lshl_add_u64 v[78:79], v[140:141], 2, v[72:73]
	global_store_dwordx4 v[78:79], v[62:65], off nt
	s_nop 1
	v_lshl_add_u64 v[62:63], v[140:141], 1, v[74:75]
	global_store_dwordx2 v[62:63], v[76:77], off sc1
.LBB0_321:
	s_or_b64 exec, exec, s[38:39]
	v_mov_b32_e32 v71, v70
	v_mov_b32_e32 v62, v70
	v_mov_b32_e32 v63, v70
	v_pk_mul_f32 v[60:61], v[60:61], v[62:63]
	v_pk_mul_f32 v[58:59], v[58:59], v[70:71]
	s_nop 0
	v_cvt_pk_bf16_f32 v62, v58, v59
	v_cvt_pk_bf16_f32 v63, v60, v61
	s_and_saveexec_b64 s[2:3], s[4:5]
	s_xor_b64 s[38:39], exec, s[2:3]
	s_cbranch_execz .LBB0_323
	v_lshl_add_u64 v[64:65], v[134:135], 2, v[66:67]
	global_store_dwordx4 v[64:65], v[58:61], off offset:-2048 nt
	s_nop 1
	v_lshl_add_u64 v[58:59], v[134:135], 1, v[68:69]
	global_store_dwordx2 v[58:59], v[62:63], off offset:-1024 sc1
.LBB0_323:
	s_andn2_saveexec_b64 s[38:39], s[38:39]
	s_cbranch_execz .LBB0_325
	v_lshl_add_u64 v[64:65], v[140:141], 2, v[72:73]
	global_store_dwordx4 v[64:65], v[58:61], off offset:64 nt
	s_nop 1
	v_lshl_add_u64 v[58:59], v[140:141], 1, v[74:75]
	global_store_dwordx2 v[58:59], v[62:63], off offset:32 sc1
.LBB0_325:
	s_or_b64 exec, exec, s[38:39]
	v_mov_b32_e32 v58, v70
	v_mov_b32_e32 v59, v70
	v_pk_mul_f32 v[56:57], v[56:57], v[58:59]
	v_pk_mul_f32 v[54:55], v[54:55], v[70:71]
	s_nop 0
	v_cvt_pk_bf16_f32 v58, v54, v55
	v_cvt_pk_bf16_f32 v59, v56, v57
	s_and_saveexec_b64 s[2:3], s[8:9]
	s_xor_b64 s[38:39], exec, s[2:3]
	s_cbranch_execz .LBB0_327
	v_mov_b32_e32 v123, v135
	v_lshl_add_u64 v[60:61], v[122:123], 2, v[66:67]
	global_store_dwordx4 v[60:61], v[54:57], off offset:-2048 nt
	s_nop 1
	v_lshl_add_u64 v[54:55], v[122:123], 1, v[68:69]
	global_store_dwordx2 v[54:55], v[58:59], off offset:-1024 sc1
.LBB0_327:
	s_andn2_saveexec_b64 s[38:39], s[38:39]
	s_cbranch_execz .LBB0_329
	v_lshl_add_u64 v[60:61], v[140:141], 2, v[72:73]
	global_store_dwordx4 v[60:61], v[54:57], off offset:512 nt
	s_nop 1
	v_lshl_add_u64 v[54:55], v[140:141], 1, v[74:75]
	global_store_dwordx2 v[54:55], v[58:59], off offset:256 sc1
.LBB0_329:
	s_or_b64 exec, exec, s[38:39]
	v_mov_b32_e32 v54, v70
	v_mov_b32_e32 v55, v70
	v_pk_mul_f32 v[52:53], v[52:53], v[54:55]
	v_pk_mul_f32 v[50:51], v[50:51], v[70:71]
	s_nop 0
	v_cvt_pk_bf16_f32 v54, v50, v51
	v_cvt_pk_bf16_f32 v55, v52, v53
	s_and_saveexec_b64 s[2:3], s[6:7]
	s_xor_b64 s[38:39], exec, s[2:3]
	s_cbranch_execz .LBB0_331
	v_mov_b32_e32 v119, v135
	v_lshl_add_u64 v[56:57], v[118:119], 2, v[66:67]
	global_store_dwordx4 v[56:57], v[50:53], off offset:-2048 nt
	s_nop 1
	v_lshl_add_u64 v[50:51], v[118:119], 1, v[68:69]
	global_store_dwordx2 v[50:51], v[54:55], off offset:-1024 sc1
.LBB0_331:
	s_andn2_saveexec_b64 s[38:39], s[38:39]
	s_cbranch_execz .LBB0_333
	v_lshl_add_u64 v[56:57], v[140:141], 2, v[72:73]
	global_store_dwordx4 v[56:57], v[50:53], off offset:576 nt
	s_nop 1
	v_lshl_add_u64 v[50:51], v[140:141], 1, v[74:75]
	global_store_dwordx2 v[50:51], v[54:55], off offset:288 sc1
.LBB0_333:
	s_or_b64 exec, exec, s[38:39]
	v_fmamk_f32 v50, v176, 0x3a800000, v173
	v_rsq_f32_e32 v54, v50
	v_lshlrev_b64 v[56:57], 11, v[146:147]
	v_lshlrev_b64 v[58:59], 10, v[146:147]
	v_lshl_add_u64 v[50:51], s[34:35], 0, v[56:57]
	v_lshl_add_u64 v[52:53], s[36:37], 0, v[58:59]
	v_pk_mul_f32 v[48:49], v[48:49], v[54:55] op_sel_hi:[1,0]
	v_pk_mul_f32 v[46:47], v[46:47], v[54:55] op_sel_hi:[1,0]
	s_nop 0
	v_cvt_pk_bf16_f32 v60, v46, v47
	v_cvt_pk_bf16_f32 v61, v48, v49
	s_and_saveexec_b64 s[2:3], vcc
	s_xor_b64 s[38:39], exec, s[2:3]
	s_cbranch_execz .LBB0_335
	v_mov_b32_e32 v62, v140
	v_mov_b32_e32 v63, v135
	v_lshl_add_u64 v[64:65], v[62:63], 2, v[50:51]
	global_store_dwordx4 v[64:65], v[46:49], off offset:-2048 nt
	s_nop 1
	v_lshl_add_u64 v[46:47], v[62:63], 1, v[52:53]
	global_store_dwordx2 v[46:47], v[60:61], off offset:-1024 sc1
.LBB0_335:
	s_or_saveexec_b64 s[38:39], s[38:39]
	v_lshl_add_u64 v[56:57], s[28:29], 0, v[56:57]
	v_lshl_add_u64 v[58:59], s[30:31], 0, v[58:59]
	s_xor_b64 exec, exec, s[38:39]
	s_cbranch_execz .LBB0_337
	v_lshl_add_u64 v[62:63], v[140:141], 2, v[56:57]
	global_store_dwordx4 v[62:63], v[46:49], off nt
	s_nop 1
	v_lshl_add_u64 v[46:47], v[140:141], 1, v[58:59]
	global_store_dwordx2 v[46:47], v[60:61], off sc1
.LBB0_337:
	s_or_b64 exec, exec, s[38:39]
	v_mov_b32_e32 v55, v54
	v_mov_b32_e32 v46, v54
	v_mov_b32_e32 v47, v54
	v_pk_mul_f32 v[44:45], v[44:45], v[46:47]
	v_pk_mul_f32 v[42:43], v[42:43], v[54:55]
	s_nop 0
	v_cvt_pk_bf16_f32 v46, v42, v43
	v_cvt_pk_bf16_f32 v47, v44, v45
	s_and_saveexec_b64 s[2:3], s[4:5]
	s_xor_b64 s[38:39], exec, s[2:3]
	s_cbranch_execz .LBB0_339
	v_lshl_add_u64 v[48:49], v[134:135], 2, v[50:51]
	global_store_dwordx4 v[48:49], v[42:45], off offset:-2048 nt
	s_nop 1
	v_lshl_add_u64 v[42:43], v[134:135], 1, v[52:53]
	global_store_dwordx2 v[42:43], v[46:47], off offset:-1024 sc1
.LBB0_339:
	s_andn2_saveexec_b64 s[38:39], s[38:39]
	s_cbranch_execz .LBB0_341
	v_lshl_add_u64 v[48:49], v[140:141], 2, v[56:57]
	global_store_dwordx4 v[48:49], v[42:45], off offset:64 nt
	s_nop 1
	v_lshl_add_u64 v[42:43], v[140:141], 1, v[58:59]
	global_store_dwordx2 v[42:43], v[46:47], off offset:32 sc1
.LBB0_341:
	s_or_b64 exec, exec, s[38:39]
	v_mov_b32_e32 v42, v54
	v_mov_b32_e32 v43, v54
	v_pk_mul_f32 v[40:41], v[40:41], v[42:43]
	v_pk_mul_f32 v[38:39], v[38:39], v[54:55]
	s_nop 0
	v_cvt_pk_bf16_f32 v42, v38, v39
	v_cvt_pk_bf16_f32 v43, v40, v41
	s_and_saveexec_b64 s[2:3], s[8:9]
	s_xor_b64 s[38:39], exec, s[2:3]
	s_cbranch_execz .LBB0_343
	v_mov_b32_e32 v123, v135
	v_lshl_add_u64 v[44:45], v[122:123], 2, v[50:51]
	global_store_dwordx4 v[44:45], v[38:41], off offset:-2048 nt
	s_nop 1
	v_lshl_add_u64 v[38:39], v[122:123], 1, v[52:53]
	global_store_dwordx2 v[38:39], v[42:43], off offset:-1024 sc1
.LBB0_343:
	s_andn2_saveexec_b64 s[38:39], s[38:39]
	s_cbranch_execz .LBB0_345
	v_lshl_add_u64 v[44:45], v[140:141], 2, v[56:57]
	global_store_dwordx4 v[44:45], v[38:41], off offset:512 nt
	s_nop 1
	v_lshl_add_u64 v[38:39], v[140:141], 1, v[58:59]
	global_store_dwordx2 v[38:39], v[42:43], off offset:256 sc1
.LBB0_345:
	s_or_b64 exec, exec, s[38:39]
	v_mov_b32_e32 v38, v54
	v_mov_b32_e32 v39, v54
	v_pk_mul_f32 v[36:37], v[36:37], v[38:39]
	v_pk_mul_f32 v[34:35], v[34:35], v[54:55]
	s_nop 0
	v_cvt_pk_bf16_f32 v38, v34, v35
	v_cvt_pk_bf16_f32 v39, v36, v37
	s_and_saveexec_b64 s[2:3], s[6:7]
	s_xor_b64 s[38:39], exec, s[2:3]
	s_cbranch_execz .LBB0_347
	v_mov_b32_e32 v119, v135
	v_lshl_add_u64 v[40:41], v[118:119], 2, v[50:51]
	global_store_dwordx4 v[40:41], v[34:37], off offset:-2048 nt
	s_nop 1
	v_lshl_add_u64 v[34:35], v[118:119], 1, v[52:53]
	global_store_dwordx2 v[34:35], v[38:39], off offset:-1024 sc1
.LBB0_347:
	s_andn2_saveexec_b64 s[38:39], s[38:39]
	s_cbranch_execz .LBB0_349
	v_lshl_add_u64 v[40:41], v[140:141], 2, v[56:57]
	global_store_dwordx4 v[40:41], v[34:37], off offset:576 nt
	s_nop 1
	v_lshl_add_u64 v[34:35], v[140:141], 1, v[58:59]
	global_store_dwordx2 v[34:35], v[38:39], off offset:288 sc1
.LBB0_349:
	s_or_b64 exec, exec, s[38:39]
	v_fmamk_f32 v34, v175, 0x3a800000, v173
	v_rsq_f32_e32 v38, v34
	v_lshlrev_b64 v[40:41], 11, v[144:145]
	v_lshlrev_b64 v[42:43], 10, v[144:145]
	v_lshl_add_u64 v[34:35], s[34:35], 0, v[40:41]
	v_lshl_add_u64 v[36:37], s[36:37], 0, v[42:43]
	v_pk_mul_f32 v[32:33], v[32:33], v[38:39] op_sel_hi:[1,0]
	v_pk_mul_f32 v[30:31], v[30:31], v[38:39] op_sel_hi:[1,0]
	s_nop 0
	v_cvt_pk_bf16_f32 v44, v30, v31
	v_cvt_pk_bf16_f32 v45, v32, v33
	s_and_saveexec_b64 s[2:3], vcc
	s_xor_b64 s[38:39], exec, s[2:3]
	s_cbranch_execz .LBB0_351
	v_mov_b32_e32 v46, v140
	v_mov_b32_e32 v47, v135
	v_lshl_add_u64 v[48:49], v[46:47], 2, v[34:35]
	global_store_dwordx4 v[48:49], v[30:33], off offset:-2048 nt
	s_nop 1
	v_lshl_add_u64 v[30:31], v[46:47], 1, v[36:37]
	global_store_dwordx2 v[30:31], v[44:45], off offset:-1024 sc1
.LBB0_351:
	s_or_saveexec_b64 s[38:39], s[38:39]
	v_lshl_add_u64 v[40:41], s[28:29], 0, v[40:41]
	v_lshl_add_u64 v[42:43], s[30:31], 0, v[42:43]
	s_xor_b64 exec, exec, s[38:39]
	s_cbranch_execz .LBB0_353
	v_lshl_add_u64 v[46:47], v[140:141], 2, v[40:41]
	global_store_dwordx4 v[46:47], v[30:33], off nt
	s_nop 1
	v_lshl_add_u64 v[30:31], v[140:141], 1, v[42:43]
	global_store_dwordx2 v[30:31], v[44:45], off sc1
.LBB0_353:
	s_or_b64 exec, exec, s[38:39]
	v_mov_b32_e32 v39, v38
	v_mov_b32_e32 v30, v38
	v_mov_b32_e32 v31, v38
	v_pk_mul_f32 v[28:29], v[28:29], v[30:31]
	v_pk_mul_f32 v[26:27], v[26:27], v[38:39]
	s_nop 0
	v_cvt_pk_bf16_f32 v30, v26, v27
	v_cvt_pk_bf16_f32 v31, v28, v29
	s_and_saveexec_b64 s[2:3], s[4:5]
	s_xor_b64 s[38:39], exec, s[2:3]
	s_cbranch_execz .LBB0_355
	v_lshl_add_u64 v[32:33], v[134:135], 2, v[34:35]
	global_store_dwordx4 v[32:33], v[26:29], off offset:-2048 nt
	s_nop 1
	v_lshl_add_u64 v[26:27], v[134:135], 1, v[36:37]
	global_store_dwordx2 v[26:27], v[30:31], off offset:-1024 sc1
.LBB0_355:
	s_andn2_saveexec_b64 s[38:39], s[38:39]
	s_cbranch_execz .LBB0_357
	v_lshl_add_u64 v[32:33], v[140:141], 2, v[40:41]
	global_store_dwordx4 v[32:33], v[26:29], off offset:64 nt
	s_nop 1
	v_lshl_add_u64 v[26:27], v[140:141], 1, v[42:43]
	global_store_dwordx2 v[26:27], v[30:31], off offset:32 sc1
.LBB0_357:
	s_or_b64 exec, exec, s[38:39]
	v_mov_b32_e32 v26, v38
	v_mov_b32_e32 v27, v38
	v_pk_mul_f32 v[24:25], v[24:25], v[26:27]
	v_pk_mul_f32 v[22:23], v[22:23], v[38:39]
	s_nop 0
	v_cvt_pk_bf16_f32 v26, v22, v23
	v_cvt_pk_bf16_f32 v27, v24, v25
	s_and_saveexec_b64 s[2:3], s[8:9]
	s_xor_b64 s[38:39], exec, s[2:3]
	s_cbranch_execz .LBB0_359
	v_mov_b32_e32 v123, v135
	v_lshl_add_u64 v[28:29], v[122:123], 2, v[34:35]
	global_store_dwordx4 v[28:29], v[22:25], off offset:-2048 nt
	s_nop 1
	v_lshl_add_u64 v[22:23], v[122:123], 1, v[36:37]
	global_store_dwordx2 v[22:23], v[26:27], off offset:-1024 sc1
.LBB0_359:
	s_andn2_saveexec_b64 s[38:39], s[38:39]
	s_cbranch_execz .LBB0_361
	v_lshl_add_u64 v[28:29], v[140:141], 2, v[40:41]
	global_store_dwordx4 v[28:29], v[22:25], off offset:512 nt
	s_nop 1
	v_lshl_add_u64 v[22:23], v[140:141], 1, v[42:43]
	global_store_dwordx2 v[22:23], v[26:27], off offset:256 sc1
.LBB0_361:
	s_or_b64 exec, exec, s[38:39]
	v_mov_b32_e32 v22, v38
	v_mov_b32_e32 v23, v38
	v_pk_mul_f32 v[20:21], v[20:21], v[22:23]
	v_pk_mul_f32 v[18:19], v[18:19], v[38:39]
	s_nop 0
	v_cvt_pk_bf16_f32 v22, v18, v19
	v_cvt_pk_bf16_f32 v23, v20, v21
	s_and_saveexec_b64 s[2:3], s[6:7]
	s_xor_b64 s[38:39], exec, s[2:3]
	s_cbranch_execz .LBB0_363
	v_mov_b32_e32 v119, v135
	v_lshl_add_u64 v[24:25], v[118:119], 2, v[34:35]
	global_store_dwordx4 v[24:25], v[18:21], off offset:-2048 nt
	s_nop 1
	v_lshl_add_u64 v[18:19], v[118:119], 1, v[36:37]
	global_store_dwordx2 v[18:19], v[22:23], off offset:-1024 sc1
.LBB0_363:
	s_andn2_saveexec_b64 s[38:39], s[38:39]
	s_cbranch_execz .LBB0_365
	v_lshl_add_u64 v[24:25], v[140:141], 2, v[40:41]
	global_store_dwordx4 v[24:25], v[18:21], off offset:576 nt
	s_nop 1
	v_lshl_add_u64 v[18:19], v[140:141], 1, v[42:43]
	global_store_dwordx2 v[18:19], v[22:23], off offset:288 sc1
.LBB0_365:
	s_or_b64 exec, exec, s[38:39]
	v_fmamk_f32 v18, v174, 0x3a800000, v173
	v_rsq_f32_e32 v24, v18
	v_lshlrev_b64 v[22:23], 11, v[142:143]
	v_lshlrev_b64 v[26:27], 10, v[142:143]
	v_lshl_add_u64 v[18:19], s[34:35], 0, v[22:23]
	v_lshl_add_u64 v[20:21], s[36:37], 0, v[26:27]
	v_pk_mul_f32 v[16:17], v[16:17], v[24:25] op_sel_hi:[1,0]
	v_pk_mul_f32 v[14:15], v[14:15], v[24:25] op_sel_hi:[1,0]
	s_nop 0
	v_cvt_pk_bf16_f32 v28, v14, v15
	v_cvt_pk_bf16_f32 v29, v16, v17
	s_and_saveexec_b64 s[2:3], vcc
	s_xor_b64 s[34:35], exec, s[2:3]
	s_cbranch_execz .LBB0_367
	v_mov_b32_e32 v30, v140
	v_mov_b32_e32 v31, v135
	v_lshl_add_u64 v[32:33], v[30:31], 2, v[18:19]
	global_store_dwordx4 v[32:33], v[14:17], off offset:-2048 nt
	s_nop 1
	v_lshl_add_u64 v[14:15], v[30:31], 1, v[20:21]
	global_store_dwordx2 v[14:15], v[28:29], off offset:-1024 sc1
.LBB0_367:
	s_or_saveexec_b64 s[34:35], s[34:35]
	v_lshl_add_u64 v[22:23], s[28:29], 0, v[22:23]
	v_lshl_add_u64 v[26:27], s[30:31], 0, v[26:27]
	s_xor_b64 exec, exec, s[34:35]
	s_cbranch_execz .LBB0_369
	v_lshl_add_u64 v[30:31], v[140:141], 2, v[22:23]
	global_store_dwordx4 v[30:31], v[14:17], off nt
	s_nop 1
	v_lshl_add_u64 v[14:15], v[140:141], 1, v[26:27]
	global_store_dwordx2 v[14:15], v[28:29], off sc1
.LBB0_369:
	s_or_b64 exec, exec, s[34:35]
	v_mov_b32_e32 v25, v24
	v_mov_b32_e32 v14, v24
	v_mov_b32_e32 v15, v24
	v_pk_mul_f32 v[12:13], v[12:13], v[14:15]
	v_pk_mul_f32 v[10:11], v[10:11], v[24:25]
	s_nop 0
	v_cvt_pk_bf16_f32 v14, v10, v11
	v_cvt_pk_bf16_f32 v15, v12, v13
	s_and_saveexec_b64 s[2:3], s[4:5]
	s_xor_b64 s[4:5], exec, s[2:3]
	s_cbranch_execz .LBB0_371
	v_lshl_add_u64 v[16:17], v[134:135], 2, v[18:19]
	global_store_dwordx4 v[16:17], v[10:13], off offset:-2048 nt
	s_nop 1
	v_lshl_add_u64 v[10:11], v[134:135], 1, v[20:21]
	global_store_dwordx2 v[10:11], v[14:15], off offset:-1024 sc1
.LBB0_371:
	s_andn2_saveexec_b64 s[4:5], s[4:5]
	s_cbranch_execz .LBB0_373
	v_lshl_add_u64 v[16:17], v[140:141], 2, v[22:23]
	global_store_dwordx4 v[16:17], v[10:13], off offset:64 nt
	s_nop 1
	v_lshl_add_u64 v[10:11], v[140:141], 1, v[26:27]
	global_store_dwordx2 v[10:11], v[14:15], off offset:32 sc1
.LBB0_373:
	s_or_b64 exec, exec, s[4:5]
	v_mov_b32_e32 v10, v24
	v_mov_b32_e32 v11, v24
	v_pk_mul_f32 v[8:9], v[8:9], v[10:11]
	v_pk_mul_f32 v[6:7], v[6:7], v[24:25]
	s_nop 0
	v_cvt_pk_bf16_f32 v10, v6, v7
	v_cvt_pk_bf16_f32 v11, v8, v9
	s_and_saveexec_b64 s[2:3], s[8:9]
	s_xor_b64 s[4:5], exec, s[2:3]
	s_cbranch_execz .LBB0_375
	v_mov_b32_e32 v123, v135
	v_lshl_add_u64 v[12:13], v[122:123], 2, v[18:19]
	global_store_dwordx4 v[12:13], v[6:9], off offset:-2048 nt
	s_nop 1
	v_lshl_add_u64 v[6:7], v[122:123], 1, v[20:21]
	global_store_dwordx2 v[6:7], v[10:11], off offset:-1024 sc1
.LBB0_375:
	s_andn2_saveexec_b64 s[4:5], s[4:5]
	s_cbranch_execz .LBB0_377
	v_lshl_add_u64 v[12:13], v[140:141], 2, v[22:23]
	global_store_dwordx4 v[12:13], v[6:9], off offset:512 nt
	s_nop 1
	v_lshl_add_u64 v[6:7], v[140:141], 1, v[26:27]
	global_store_dwordx2 v[6:7], v[10:11], off offset:256 sc1
.LBB0_377:
	s_or_b64 exec, exec, s[4:5]
	v_mov_b32_e32 v6, v24
	v_mov_b32_e32 v7, v24
	v_pk_mul_f32 v[4:5], v[4:5], v[6:7]
	v_pk_mul_f32 v[2:3], v[2:3], v[24:25]
	s_nop 0
	v_cvt_pk_bf16_f32 v6, v2, v3
	v_cvt_pk_bf16_f32 v7, v4, v5
	s_and_saveexec_b64 s[2:3], s[6:7]
	s_xor_b64 s[4:5], exec, s[2:3]
	s_cbranch_execz .LBB0_380
	v_mov_b32_e32 v119, v135
	v_lshl_add_u64 v[8:9], v[118:119], 2, v[18:19]
	global_store_dwordx4 v[8:9], v[2:5], off offset:-2048 nt
	s_nop 1
	v_lshl_add_u64 v[2:3], v[118:119], 1, v[20:21]
	global_store_dwordx2 v[2:3], v[6:7], off offset:-1024 sc1
	s_andn2_saveexec_b64 s[4:5], s[4:5]
	s_cbranch_execnz .LBB0_381

.LBB0_381:
	v_lshl_add_u64 v[8:9], v[140:141], 2, v[22:23]
	global_store_dwordx4 v[8:9], v[2:5], off offset:576 nt
	s_nop 1
	v_lshl_add_u64 v[2:3], v[140:141], 1, v[26:27]
	global_store_dwordx2 v[2:3], v[6:7], off offset:288 sc1
	s_or_b64 exec, exec, s[4:5]
	s_andn2_b64 vcc, exec, s[18:19]
	s_mov_b64 s[4:5], -1
	s_cbranch_vccnz .LBB0_242

.LBB0_403:
	s_ashr_i32 s14, s28, 6
	s_lshl_b32 s24, s2, 3
	s_add_i32 s24, s24, s14
	s_ashr_i32 s2, s24, 3
	s_cmp_gt_i32 s2, 63
	s_cbranch_scc1 .LBB0_410
	s_lshl_b32 s3, s2, 4
	s_lshl_b32 s2, s2, 6
	s_and_b32 s20, s3, 0xffffffe0
	s_and_b32 s2, s2, 64
	s_lshl_b32 s3, s14, 3
	v_mov_b32_e32 v2, v197
	s_bitset1_b32 s2, 14
	s_and_b32 s3, s3, -16
	s_add_i32 s3, s2, s3
	s_waitcnt vmcnt(0)
	v_and_b32_e32 v10, 15, v2
	v_lshrrev_b32_e32 v5, 2, v2
	v_or_b32_e32 v4, s3, v10
	s_lshl_b32 s3, s14, 4
	v_and_b32_e32 v5, 12, v5
	v_and_or_b32 v5, s3, 16, v5
	v_or_b32_e32 v6, s20, v5
	v_ashrrev_i32_e32 v5, 31, v4
	s_waitcnt vmcnt(22)
	v_lshlrev_b64 v[8:9], 11, v[4:5]
	v_lshl_add_u64 v[8:9], s[36:37], 0, v[8:9]
	v_ashrrev_i32_e32 v7, 31, v6
	s_mulk_i32 s2, 0xc00
	v_and_b32_e32 v158, 63, v2
	v_lshl_add_u64 v[6:7], v[6:7], 1, v[8:9]
	s_mov_b32 s3, 0x3600000
	s_add_u32 s2, s0, s2
	s_mul_i32 s22, s14, 0xc0
	v_lshrrev_b32_e32 v2, 1, v2
	v_add_co_u32_e32 v6, vcc, s3, v6
	s_addc_u32 s3, s1, 0
	s_mul_hi_i32 s21, s20, 0xc00
	s_mulk_i32 s20, 0xc00
	v_and_or_b32 v8, v2, 24, s22
	s_add_u32 s20, s4, s20
	v_ashrrev_i32_e32 v9, 31, v8
	s_addc_u32 s21, s9, s21
	s_waitcnt vmcnt(0)
	v_lshlrev_b64 v[52:53], 1, v[8:9]
	v_mul_u32_u24_e32 v2, 0x600, v10
	v_lshl_add_u64 v[8:9], s[20:21], 0, v[52:53]
	v_lshlrev_b32_e32 v2, 1, v2
	v_addc_co_u32_e32 v7, vcc, 0, v7, vcc
	v_lshl_add_u64 v[28:29], v[8:9], 0, v[2:3]
	v_add_co_u32_e32 v54, vcc, s6, v28
	v_lshl_add_u64 v[124:125], s[2:3], 0, v[52:53]
	s_nop 0
	v_addc_co_u32_e32 v55, vcc, 0, v29, vcc
	v_lshl_add_u64 v[100:101], v[124:125], 0, v[2:3]
	v_add_co_u32_e32 v102, vcc, s6, v100
	v_or_b32_e32 v2, 48, v158
	s_nop 0
	v_addc_co_u32_e32 v103, vcc, 0, v101, vcc
	v_mul_u32_u24_e32 v2, 0x600, v2
	s_mov_b64 s[20:21], 0xc000
	v_add_co_u32_e32 v126, vcc, s7, v100
	v_lshlrev_b32_e32 v2, 1, v2
	v_lshl_add_u64 v[48:49], v[28:29], 0, s[20:21]
	v_lshl_add_u64 v[96:97], v[100:101], 0, s[20:21]
	v_addc_co_u32_e32 v127, vcc, 0, v101, vcc
	v_lshl_add_u64 v[148:149], v[124:125], 0, v[2:3]
	global_load_dwordx2 v[156:157], v[6:7], off
	global_load_dwordx4 v[8:11], v[28:29], off
	global_load_dwordx4 v[12:15], v[28:29], off offset:64
	global_load_dwordx4 v[16:19], v[28:29], off offset:128
	global_load_dwordx4 v[20:23], v[28:29], off offset:192
	global_load_dwordx4 v[24:27], v[28:29], off offset:256
	s_nop 0
	global_load_dwordx4 v[28:31], v[28:29], off offset:320
	s_nop 0
	global_load_dwordx4 v[32:35], v[48:49], off offset:64
	global_load_dwordx4 v[36:39], v[48:49], off offset:128
	global_load_dwordx4 v[40:43], v[48:49], off offset:192
	global_load_dwordx4 v[44:47], v[48:49], off offset:256
	s_nop 0
	global_load_dwordx4 v[48:51], v[48:49], off offset:320
	s_nop 0
	global_load_dwordx4 v[52:55], v[54:55], off
	s_nop 0
	global_load_dwordx4 v[56:59], v[100:101], off
	global_load_dwordx4 v[60:63], v[100:101], off offset:64
	global_load_dwordx4 v[64:67], v[100:101], off offset:128
	global_load_dwordx4 v[68:71], v[100:101], off offset:192
	global_load_dwordx4 v[72:75], v[100:101], off offset:256
	global_load_dwordx4 v[76:79], v[100:101], off offset:320
	global_load_dwordx4 v[80:83], v[96:97], off offset:64
	global_load_dwordx4 v[84:87], v[96:97], off offset:128
	global_load_dwordx4 v[88:91], v[96:97], off offset:192
	global_load_dwordx4 v[92:95], v[96:97], off offset:256
	s_nop 0
	global_load_dwordx4 v[96:99], v[96:97], off offset:320
	s_nop 0
	global_load_dwordx4 v[100:103], v[102:103], off
	s_nop 0
	global_load_dwordx4 v[104:107], v[126:127], off
	global_load_dwordx4 v[108:111], v[126:127], off offset:64
	global_load_dwordx4 v[112:115], v[126:127], off offset:128
	global_load_dwordx4 v[116:119], v[126:127], off offset:192
	global_load_dwordx4 v[120:123], v[126:127], off offset:256
	s_nop 0
	global_load_dwordx4 v[124:127], v[126:127], off offset:320
	s_nop 0
	global_load_dwordx4 v[128:131], v[148:149], off
	global_load_dwordx4 v[132:135], v[148:149], off offset:64
	global_load_dwordx4 v[136:139], v[148:149], off offset:128
	global_load_dwordx4 v[140:143], v[148:149], off offset:192
	global_load_dwordx4 v[144:147], v[148:149], off offset:256
	s_nop 0
	global_load_dwordx4 v[148:151], v[148:149], off offset:320
	s_waitcnt vmcnt(23)
	v_mfma_f32_16x16x32_bf16 v[152:155], v[8:11], v[56:59], 0
	s_lshl_b32 s2, s14, 13
	v_lshlrev_b32_e32 v2, 4, v158
	s_add_i32 s2, s2, 0
	v_mfma_f32_16x16x32_bf16 v[56:59], v[52:55], v[56:59], 0
	v_cmp_lt_i32_e32 vcc, v234, v235
	s_waitcnt vmcnt(22)
	v_mfma_f32_16x16x32_bf16 v[152:155], v[12:15], v[60:63], v[152:155]
	v_mfma_f32_16x16x32_bf16 v[56:59], v[32:35], v[60:63], v[56:59]
	s_waitcnt vmcnt(21)
	v_mfma_f32_16x16x32_bf16 v[152:155], v[16:19], v[64:67], v[152:155]
	v_mfma_f32_16x16x32_bf16 v[56:59], v[36:39], v[64:67], v[56:59]
	s_waitcnt vmcnt(20)
	v_mfma_f32_16x16x32_bf16 v[152:155], v[20:23], v[68:71], v[152:155]
	v_mfma_f32_16x16x32_bf16 v[56:59], v[40:43], v[68:71], v[56:59]
	s_waitcnt vmcnt(12)
	v_mfma_f32_16x16x32_bf16 v[60:63], v[8:11], v[100:103], 0
	s_waitcnt vmcnt(11)
	v_mfma_f32_16x16x32_bf16 v[68:71], v[8:11], v[104:107], 0
	s_waitcnt vmcnt(5)
	v_mfma_f32_16x16x32_bf16 v[8:11], v[8:11], v[128:131], 0
	v_mfma_f32_16x16x32_bf16 v[152:155], v[24:27], v[72:75], v[152:155]
	v_mfma_f32_16x16x32_bf16 v[56:59], v[44:47], v[72:75], v[56:59]
	v_mfma_f32_16x16x32_bf16 v[72:75], v[52:55], v[104:107], 0
	v_mfma_f32_16x16x32_bf16 v[64:67], v[52:55], v[100:103], 0
	v_mfma_f32_16x16x32_bf16 v[60:63], v[12:15], v[80:83], v[60:63]
	v_mfma_f32_16x16x32_bf16 v[68:71], v[12:15], v[108:111], v[68:71]
	s_waitcnt vmcnt(4)
	v_mfma_f32_16x16x32_bf16 v[8:11], v[12:15], v[132:135], v[8:11]
	v_mfma_f32_16x16x32_bf16 v[12:15], v[52:55], v[128:131], 0
	v_mfma_f32_16x16x32_bf16 v[72:75], v[32:35], v[108:111], v[72:75]
	v_mfma_f32_16x16x32_bf16 v[64:67], v[32:35], v[80:83], v[64:67]
	v_mfma_f32_16x16x32_bf16 v[68:71], v[16:19], v[112:115], v[68:71]
	v_mfma_f32_16x16x32_bf16 v[12:15], v[32:35], v[132:135], v[12:15]
	v_mfma_f32_16x16x32_bf16 v[60:63], v[16:19], v[84:87], v[60:63]
	v_mfma_f32_16x16x32_bf16 v[72:75], v[36:39], v[112:115], v[72:75]
	v_mfma_f32_16x16x32_bf16 v[64:67], v[36:39], v[84:87], v[64:67]
	s_waitcnt vmcnt(3)
	v_mfma_f32_16x16x32_bf16 v[8:11], v[16:19], v[136:139], v[8:11]
	v_add_u32_e32 v16, s2, v2
	s_lshl_b32 s2, s14, 10
	s_add_i32 s2, s2, 0
	v_mfma_f32_16x16x32_bf16 v[68:71], v[20:23], v[116:119], v[68:71]
	v_add_u32_e32 v2, s2, v2
	v_mfma_f32_16x16x32_bf16 v[12:15], v[36:39], v[136:139], v[12:15]
	v_mfma_f32_16x16x32_bf16 v[60:63], v[20:23], v[88:91], v[60:63]
	v_mfma_f32_16x16x32_bf16 v[72:75], v[40:43], v[116:119], v[72:75]
	v_mfma_f32_16x16x32_bf16 v[64:67], v[40:43], v[88:91], v[64:67]
	s_waitcnt vmcnt(2)
	v_mfma_f32_16x16x32_bf16 v[8:11], v[20:23], v[140:143], v[8:11]
	v_mfma_f32_16x16x32_bf16 v[68:71], v[24:27], v[120:123], v[68:71]
	v_mfma_f32_16x16x32_bf16 v[12:15], v[40:43], v[140:143], v[12:15]
	v_mfma_f32_16x16x32_bf16 v[60:63], v[24:27], v[92:95], v[60:63]
	v_mfma_f32_16x16x32_bf16 v[72:75], v[44:47], v[120:123], v[72:75]
	v_mfma_f32_16x16x32_bf16 v[64:67], v[44:47], v[92:95], v[64:67]
	s_waitcnt vmcnt(1)
	v_mfma_f32_16x16x32_bf16 v[8:11], v[24:27], v[144:147], v[8:11]
	v_mfma_f32_16x16x32_bf16 v[152:155], v[28:31], v[76:79], v[152:155]
	v_mfma_f32_16x16x32_bf16 v[56:59], v[48:51], v[76:79], v[56:59]
	v_mfma_f32_16x16x32_bf16 v[68:71], v[28:31], v[124:127], v[68:71]
	s_nop 5
	ds_write_b128 v16, v[152:155]
	v_mfma_f32_16x16x32_bf16 v[12:15], v[44:47], v[144:147], v[12:15]
	v_mfma_f32_16x16x32_bf16 v[60:63], v[28:31], v[96:99], v[60:63]
	v_mfma_f32_16x16x32_bf16 v[72:75], v[48:51], v[124:127], v[72:75]
	v_mfma_f32_16x16x32_bf16 v[64:67], v[48:51], v[96:99], v[64:67]
	ds_write_b128 v16, v[56:59] offset:1024
	s_nop 4
	ds_write_b128 v16, v[60:63] offset:2048
	s_nop 0
	ds_write_b128 v16, v[64:67] offset:3072
	s_waitcnt vmcnt(0)
	v_mfma_f32_16x16x32_bf16 v[8:11], v[28:31], v[148:151], v[8:11]
	ds_write_b128 v16, v[68:71] offset:4096
	ds_write_b128 v16, v[72:75] offset:5120
	s_nop 5
	ds_write_b128 v16, v[8:11] offset:6144
	v_mfma_f32_16x16x32_bf16 v[8:11], v[48:51], v[148:151], v[12:15]
	s_nop 7
	ds_write_b128 v16, v[8:11] offset:7168
	s_waitcnt lgkmcnt(0)
	s_barrier
	ds_read_b128 v[8:11], v2
	ds_read_b128 v[12:15], v2 offset:8192
	ds_read_b128 v[16:19], v2 offset:16384
	ds_read_b128 v[20:23], v2 offset:24576
	s_waitcnt lgkmcnt(2)
	v_pk_add_f32 v[10:11], v[10:11], v[14:15]
	v_pk_add_f32 v[12:13], v[8:9], v[12:13]
	s_waitcnt lgkmcnt(1)
	v_pk_add_f32 v[14:15], v[10:11], v[18:19]
	ds_read_b128 v[8:11], v2 offset:32768
	v_pk_add_f32 v[12:13], v[12:13], v[16:17]
	s_waitcnt lgkmcnt(1)
	v_pk_add_f32 v[16:17], v[14:15], v[22:23]
	v_pk_add_f32 v[20:21], v[12:13], v[20:21]
	ds_read_b128 v[12:15], v2 offset:40960
	s_waitcnt lgkmcnt(1)
	v_pk_add_f32 v[22:23], v[16:17], v[10:11]
	ds_read_b128 v[16:19], v2 offset:49152
	v_pk_add_f32 v[20:21], v[20:21], v[8:9]
	ds_read_b128 v[8:11], v2 offset:57344
	s_waitcnt lgkmcnt(2)
	v_pk_add_f32 v[14:15], v[22:23], v[14:15]
	v_pk_add_f32 v[12:13], v[20:21], v[12:13]
	s_waitcnt lgkmcnt(1)
	v_pk_add_f32 v[14:15], v[14:15], v[18:19]
	v_pk_add_f32 v[12:13], v[12:13], v[16:17]
	s_waitcnt lgkmcnt(0)
	v_pk_add_f32 v[10:11], v[14:15], v[10:11]
	v_pk_add_f32 v[8:9], v[12:13], v[8:9]
	v_lshlrev_b32_e32 v12, 16, v156
	v_and_b32_e32 v13, 0xffff0000, v156
	v_lshlrev_b32_e32 v14, 16, v157
	v_and_b32_e32 v15, 0xffff0000, v157
	v_pk_add_f32 v[10:11], v[10:11], v[14:15]
	v_pk_add_f32 v[12:13], v[8:9], v[12:13]
	v_mul_f32_e32 v8, v11, v11
	v_mul_f32_e32 v2, v13, v13
	v_fmac_f32_e32 v2, v12, v12
	v_fmac_f32_e32 v8, v10, v10
	v_add_f32_e32 v2, v2, v8
	v_cndmask_b32_e32 v8, v231, v234, vcc
	v_lshlrev_b32_e32 v8, 2, v8
	ds_bpermute_b32 v8, v8, v2
	v_cmp_lt_i32_e32 vcc, v236, v235
	v_cvt_pk_bf16_f32 v12, v12, v13
	v_cvt_pk_bf16_f32 v13, v10, v11
	s_waitcnt lgkmcnt(0)
	v_add_f32_e32 v2, v2, v8
	v_cndmask_b32_e32 v8, v231, v236, vcc
	v_lshlrev_b32_e32 v8, 2, v8
	ds_bpermute_b32 v8, v8, v2
	v_cmp_gt_u32_e32 vcc, 16, v158
	s_barrier
	s_waitcnt lgkmcnt(0)
	global_store_dwordx2 v[6:7], v[12:13], off sc1
	s_and_saveexec_b64 s[2:3], vcc
	s_cbranch_execz .LBB0_406
	v_lshl_add_u64 v[4:5], v[4:5], 2, s[36:37]
	v_add_co_u32_e32 v4, vcc, 0x141000, v4
	v_add_f32_e32 v2, v2, v8
	s_nop 0
	v_addc_co_u32_e32 v5, vcc, 0, v5, vcc
	global_atomic_add_f32 v[4:5], v2, off

.LBB0_472:
	s_and_b32 s20, s24, 0x278
	s_add_i32 s14, s14, s20
	s_add_i32 s20, s14, 0x3e00
	s_ashr_i32 s21, s20, 31
	s_lshl_b64 s[22:23], s[20:21], 11
	s_waitcnt vmcnt(0)
	v_and_b32_e32 v12, 63, v197
	s_add_u32 s2, s2, s22
	s_addc_u32 s3, s3, s23
	v_lshlrev_b32_e32 v2, 3, v12
	s_waitcnt lgkmcnt(0)
	s_barrier
	global_load_dwordx2 v[10:11], v2, s[2:3]
	global_load_dwordx2 v[8:9], v2, s[2:3] offset:512
	global_load_dwordx2 v[6:7], v2, s[2:3] offset:1024
	global_load_dwordx2 v[4:5], v2, s[2:3] offset:1536
	s_lshl_b64 s[2:3], s[20:21], 2
	s_add_u32 s2, s36, s2
	s_addc_u32 s3, s37, s3
	v_mov_b32_e32 v2, 0x141000
	global_load_dword v2, v2, s[2:3]
	s_mov_b32 s2, 0xf800000
	s_waitcnt vmcnt(20)
	v_lshlrev_b32_e32 v18, 4, v12
	s_waitcnt vmcnt(4)
	v_lshlrev_b32_e32 v12, 16, v10
	s_waitcnt vmcnt(0)
	v_fmamk_f32 v2, v2, 0x3a800000, v1
	v_cmp_gt_f32_e32 vcc, s2, v2
	v_mul_f32_e32 v13, 0x4f800000, v2
	s_nop 0
	v_cndmask_b32_e32 v2, v2, v13, vcc
	v_sqrt_f32_e32 v13, v2
	s_nop 0
	v_add_u32_e32 v14, -1, v13
	v_fma_f32 v15, -v14, v13, v2
	v_cmp_ge_f32_e64 s[38:39], 0, v15
	v_add_u32_e32 v15, 1, v13
	s_nop 0
	v_cndmask_b32_e64 v14, v13, v14, s[38:39]
	v_fma_f32 v13, -v15, v13, v2
	v_cmp_lt_f32_e64 s[38:39], 0, v13
	s_nop 1
	v_cndmask_b32_e64 v13, v14, v15, s[38:39]
	v_mul_f32_e32 v14, 0x37800000, v13
	v_cndmask_b32_e32 v13, v13, v14, vcc
	v_cmp_class_f32_e32 vcc, v2, v228
	s_nop 1
	v_cndmask_b32_e32 v2, v13, v2, vcc
	v_div_scale_f32 v13, s[2:3], v2, v2, 1.0
	v_rcp_f32_e32 v14, v13
	s_lshl_b64 s[2:3], s[20:21], 12
	s_add_u32 s2, s46, s2
	s_addc_u32 s3, s47, s3
	v_fma_f32 v15, -v13, v14, 1.0
	v_fmac_f32_e32 v14, v15, v14
	v_div_scale_f32 v15, vcc, 1.0, v2, 1.0
	v_mul_f32_e32 v16, v15, v14
	v_fma_f32 v17, -v13, v16, v15
	v_fmac_f32_e32 v16, v17, v14
	v_fma_f32 v13, -v13, v16, v15
	v_div_fmas_f32 v13, v13, v14, v16
	v_div_fixup_f32 v2, v13, v2, 1.0
	v_and_b32_e32 v13, 0xffff0000, v10
	v_lshlrev_b32_e32 v10, 16, v11
	v_and_b32_e32 v11, 0xffff0000, v11
	v_pk_mul_f32 v[14:15], v[2:3], v[12:13] op_sel_hi:[0,1]
	v_pk_mul_f32 v[16:17], v[2:3], v[10:11] op_sel_hi:[0,1]
	global_load_dwordx4 v[10:13], v18, s[44:45]
	s_waitcnt vmcnt(0)
	v_pk_mul_f32 v[12:13], v[12:13], v[16:17]
	v_pk_mul_f32 v[10:11], v[10:11], v[14:15]
	global_store_dwordx4 v18, v[10:13], s[2:3] sc1
	s_nop 1
	v_lshlrev_b32_e32 v10, 16, v8
	v_and_b32_e32 v11, 0xffff0000, v8
	v_lshlrev_b32_e32 v8, 16, v9
	v_and_b32_e32 v9, 0xffff0000, v9
	v_pk_mul_f32 v[12:13], v[2:3], v[8:9] op_sel_hi:[0,1]
	v_pk_mul_f32 v[14:15], v[2:3], v[10:11] op_sel_hi:[0,1]
	global_load_dwordx4 v[8:11], v18, s[44:45] offset:1024
	s_waitcnt vmcnt(0)
	v_pk_mul_f32 v[8:9], v[8:9], v[14:15]
	v_pk_mul_f32 v[10:11], v[10:11], v[12:13]
	global_store_dwordx4 v18, v[8:11], s[2:3] offset:1024 sc1
	s_nop 1
	v_lshlrev_b32_e32 v8, 16, v6
	v_and_b32_e32 v9, 0xffff0000, v6
	v_lshlrev_b32_e32 v6, 16, v7
	v_and_b32_e32 v7, 0xffff0000, v7
	v_pk_mul_f32 v[10:11], v[2:3], v[6:7] op_sel_hi:[0,1]
	v_pk_mul_f32 v[12:13], v[2:3], v[8:9] op_sel_hi:[0,1]
	global_load_dwordx4 v[6:9], v18, s[44:45] offset:2048
	s_waitcnt vmcnt(0)
	v_pk_mul_f32 v[6:7], v[6:7], v[12:13]
	v_pk_mul_f32 v[8:9], v[8:9], v[10:11]
	global_store_dwordx4 v18, v[6:9], s[2:3] offset:2048 sc1
	s_nop 1
	v_lshlrev_b32_e32 v6, 16, v4
	v_and_b32_e32 v7, 0xffff0000, v4
	v_lshlrev_b32_e32 v4, 16, v5
	v_and_b32_e32 v5, 0xffff0000, v5
	v_pk_mul_f32 v[8:9], v[2:3], v[4:5] op_sel_hi:[0,1]
	v_pk_mul_f32 v[10:11], v[2:3], v[6:7] op_sel_hi:[0,1]
	global_load_dwordx4 v[4:7], v18, s[44:45] offset:3072
	s_waitcnt vmcnt(0)
	v_pk_mul_f32 v[4:5], v[10:11], v[4:5]
	v_pk_mul_f32 v[6:7], v[8:9], v[6:7]
	global_store_dwordx4 v18, v[4:7], s[2:3] offset:3072 sc1

.LBB0_474:
	s_and_b64 vcc, exec, s[2:3]
	s_cbranch_vccz .LBB0_525
	v_readlane_b32 s20, v254, 26
	s_add_u32 s2, s36, 0x3600000
	s_mul_i32 s14, s20, 0x10400
	s_addc_u32 s3, s37, 0
	s_add_i32 s14, s14, 0x10400
	v_readlane_b32 s21, v254, 27
	s_add_u32 s14, s36, s14
	s_addc_u32 s21, s37, 0
	s_add_u32 s20, s14, 0x100000
	s_addc_u32 s21, s21, 0
	v_mov_b32_e32 v2, v0
	v_readlane_b32 s22, v254, 28
	v_readlane_b32 s23, v253, 0
	s_bitcmp0_b32 s75, 0
	s_cselect_b64 s[22:23], -1, 0
	s_cmpk_gt_i32 s75, 0x7f
	s_cselect_b64 s[28:29], -1, 0
	s_or_b64 s[22:23], s[28:29], s[22:23]
	v_readfirstlane_b32 s14, v2
	s_and_b64 vcc, exec, s[22:23]
	s_cbranch_vccnz .LBB0_479
	s_ashr_i32 s22, s75, 1
	s_ashr_i32 s14, s14, 6
	s_lshl_b32 s23, s22, 4
	s_lshl_b32 s22, s22, 6
	s_and_b32 s24, s23, 0xffffffe0
	s_and_b32 s22, s22, 64
	s_lshl_b32 s23, s14, 3
	s_bitset1_b32 s22, 14
	s_and_b32 s23, s23, -16
	s_add_i32 s23, s23, s22
	s_waitcnt vmcnt(0)
	v_and_b32_e32 v10, 15, v2
	v_lshrrev_b32_e32 v5, 2, v2
	v_or_b32_e32 v4, s23, v10
	s_lshl_b32 s23, s14, 4
	v_and_b32_e32 v5, 12, v5
	v_and_or_b32 v5, s23, 16, v5
	s_mulk_i32 s22, 0xc00
	v_or_b32_e32 v6, s24, v5
	v_ashrrev_i32_e32 v5, 31, v4
	s_add_u32 s22, s0, s22
	s_waitcnt vmcnt(22)
	v_lshlrev_b64 v[8:9], 11, v[4:5]
	s_addc_u32 s23, s1, 0
	s_mul_hi_i32 s29, s24, 0xc00
	s_mulk_i32 s24, 0xc00
	v_and_b32_e32 v158, 63, v2
	v_lshl_add_u64 v[8:9], s[2:3], 0, v[8:9]
	v_ashrrev_i32_e32 v7, 31, v6
	s_add_u32 s28, s4, s24
	s_mul_i32 s24, s14, 0xc0
	v_lshrrev_b32_e32 v2, 1, v2
	v_lshl_add_u64 v[6:7], v[6:7], 1, v[8:9]
	v_and_or_b32 v8, v2, 24, s24
	v_ashrrev_i32_e32 v9, 31, v8
	s_addc_u32 s29, s9, s29
	s_waitcnt vmcnt(0)
	v_lshlrev_b64 v[52:53], 1, v[8:9]
	v_mul_u32_u24_e32 v2, 0x600, v10
	v_lshl_add_u64 v[8:9], s[28:29], 0, v[52:53]
	v_lshlrev_b32_e32 v2, 1, v2
	v_lshl_add_u64 v[28:29], v[8:9], 0, v[2:3]
	v_add_co_u32_e32 v54, vcc, s6, v28
	v_lshl_add_u64 v[124:125], s[22:23], 0, v[52:53]
	s_nop 0
	v_addc_co_u32_e32 v55, vcc, 0, v29, vcc
	v_lshl_add_u64 v[100:101], v[124:125], 0, v[2:3]
	v_add_co_u32_e32 v102, vcc, s6, v100
	v_or_b32_e32 v2, 48, v158
	s_nop 0
	v_addc_co_u32_e32 v103, vcc, 0, v101, vcc
	v_mul_u32_u24_e32 v2, 0x600, v2
	s_mov_b64 s[28:29], 0xc000
	v_add_co_u32_e32 v126, vcc, s7, v100
	v_lshlrev_b32_e32 v2, 1, v2
	v_lshl_add_u64 v[48:49], v[28:29], 0, s[28:29]
	v_lshl_add_u64 v[96:97], v[100:101], 0, s[28:29]
	v_addc_co_u32_e32 v127, vcc, 0, v101, vcc
	v_lshl_add_u64 v[148:149], v[124:125], 0, v[2:3]
	global_load_dwordx2 v[156:157], v[6:7], off
	global_load_dwordx4 v[8:11], v[28:29], off
	global_load_dwordx4 v[12:15], v[28:29], off offset:64
	global_load_dwordx4 v[16:19], v[28:29], off offset:128
	global_load_dwordx4 v[20:23], v[28:29], off offset:192
	global_load_dwordx4 v[24:27], v[28:29], off offset:256
	s_nop 0
	global_load_dwordx4 v[28:31], v[28:29], off offset:320
	s_nop 0
	global_load_dwordx4 v[32:35], v[48:49], off offset:64
	global_load_dwordx4 v[36:39], v[48:49], off offset:128
	global_load_dwordx4 v[40:43], v[48:49], off offset:192
	global_load_dwordx4 v[44:47], v[48:49], off offset:256
	s_nop 0
	global_load_dwordx4 v[48:51], v[48:49], off offset:320
	s_nop 0
	global_load_dwordx4 v[52:55], v[54:55], off
	s_nop 0
	global_load_dwordx4 v[56:59], v[100:101], off
	global_load_dwordx4 v[60:63], v[100:101], off offset:64
	global_load_dwordx4 v[64:67], v[100:101], off offset:128
	global_load_dwordx4 v[68:71], v[100:101], off offset:192
	global_load_dwordx4 v[72:75], v[100:101], off offset:256
	global_load_dwordx4 v[76:79], v[100:101], off offset:320
	global_load_dwordx4 v[80:83], v[96:97], off offset:64
	global_load_dwordx4 v[84:87], v[96:97], off offset:128
	global_load_dwordx4 v[88:91], v[96:97], off offset:192
	global_load_dwordx4 v[92:95], v[96:97], off offset:256
	s_nop 0
	global_load_dwordx4 v[96:99], v[96:97], off offset:320
	s_nop 0
	global_load_dwordx4 v[100:103], v[102:103], off
	s_nop 0
	global_load_dwordx4 v[104:107], v[126:127], off
	global_load_dwordx4 v[108:111], v[126:127], off offset:64
	global_load_dwordx4 v[112:115], v[126:127], off offset:128
	global_load_dwordx4 v[116:119], v[126:127], off offset:192
	global_load_dwordx4 v[120:123], v[126:127], off offset:256
	s_nop 0
	global_load_dwordx4 v[124:127], v[126:127], off offset:320
	s_nop 0
	global_load_dwordx4 v[128:131], v[148:149], off
	global_load_dwordx4 v[132:135], v[148:149], off offset:64
	global_load_dwordx4 v[136:139], v[148:149], off offset:128
	global_load_dwordx4 v[140:143], v[148:149], off offset:192
	global_load_dwordx4 v[144:147], v[148:149], off offset:256
	s_nop 0
	global_load_dwordx4 v[148:151], v[148:149], off offset:320
	s_waitcnt vmcnt(23)
	v_mfma_f32_16x16x32_bf16 v[152:155], v[8:11], v[56:59], 0
	s_lshl_b32 s22, s14, 13
	v_lshlrev_b32_e32 v2, 4, v158
	s_add_i32 s22, s22, 0
	v_mfma_f32_16x16x32_bf16 v[56:59], v[52:55], v[56:59], 0
	s_lshl_b32 s14, s14, 10
	s_add_i32 s14, s14, 0
	v_cmp_lt_i32_e32 vcc, v234, v235
	s_waitcnt vmcnt(22)
	v_mfma_f32_16x16x32_bf16 v[152:155], v[12:15], v[60:63], v[152:155]
	v_mfma_f32_16x16x32_bf16 v[56:59], v[32:35], v[60:63], v[56:59]
	s_waitcnt vmcnt(21)
	v_mfma_f32_16x16x32_bf16 v[152:155], v[16:19], v[64:67], v[152:155]
	v_mfma_f32_16x16x32_bf16 v[56:59], v[36:39], v[64:67], v[56:59]
	s_waitcnt vmcnt(20)
	v_mfma_f32_16x16x32_bf16 v[152:155], v[20:23], v[68:71], v[152:155]
	v_mfma_f32_16x16x32_bf16 v[56:59], v[40:43], v[68:71], v[56:59]
	s_waitcnt vmcnt(12)
	v_mfma_f32_16x16x32_bf16 v[60:63], v[8:11], v[100:103], 0
	s_waitcnt vmcnt(11)
	v_mfma_f32_16x16x32_bf16 v[68:71], v[8:11], v[104:107], 0
	s_waitcnt vmcnt(5)
	v_mfma_f32_16x16x32_bf16 v[8:11], v[8:11], v[128:131], 0
	v_mfma_f32_16x16x32_bf16 v[152:155], v[24:27], v[72:75], v[152:155]
	v_mfma_f32_16x16x32_bf16 v[56:59], v[44:47], v[72:75], v[56:59]
	v_mfma_f32_16x16x32_bf16 v[72:75], v[52:55], v[104:107], 0
	v_mfma_f32_16x16x32_bf16 v[64:67], v[52:55], v[100:103], 0
	v_mfma_f32_16x16x32_bf16 v[60:63], v[12:15], v[80:83], v[60:63]
	v_mfma_f32_16x16x32_bf16 v[68:71], v[12:15], v[108:111], v[68:71]
	s_waitcnt vmcnt(4)
	v_mfma_f32_16x16x32_bf16 v[8:11], v[12:15], v[132:135], v[8:11]
	v_mfma_f32_16x16x32_bf16 v[12:15], v[52:55], v[128:131], 0
	v_mfma_f32_16x16x32_bf16 v[72:75], v[32:35], v[108:111], v[72:75]
	v_mfma_f32_16x16x32_bf16 v[64:67], v[32:35], v[80:83], v[64:67]
	v_mfma_f32_16x16x32_bf16 v[68:71], v[16:19], v[112:115], v[68:71]
	v_mfma_f32_16x16x32_bf16 v[12:15], v[32:35], v[132:135], v[12:15]
	v_mfma_f32_16x16x32_bf16 v[60:63], v[16:19], v[84:87], v[60:63]
	v_mfma_f32_16x16x32_bf16 v[72:75], v[36:39], v[112:115], v[72:75]
	v_mfma_f32_16x16x32_bf16 v[64:67], v[36:39], v[84:87], v[64:67]
	s_waitcnt vmcnt(3)
	v_mfma_f32_16x16x32_bf16 v[8:11], v[16:19], v[136:139], v[8:11]
	v_add_u32_e32 v16, s22, v2
	v_add_u32_e32 v2, s14, v2
	v_mfma_f32_16x16x32_bf16 v[68:71], v[20:23], v[116:119], v[68:71]
	v_mfma_f32_16x16x32_bf16 v[12:15], v[36:39], v[136:139], v[12:15]
	v_mfma_f32_16x16x32_bf16 v[60:63], v[20:23], v[88:91], v[60:63]
	v_mfma_f32_16x16x32_bf16 v[72:75], v[40:43], v[116:119], v[72:75]
	v_mfma_f32_16x16x32_bf16 v[64:67], v[40:43], v[88:91], v[64:67]
	s_waitcnt vmcnt(2)
	v_mfma_f32_16x16x32_bf16 v[8:11], v[20:23], v[140:143], v[8:11]
	v_mfma_f32_16x16x32_bf16 v[68:71], v[24:27], v[120:123], v[68:71]
	v_mfma_f32_16x16x32_bf16 v[12:15], v[40:43], v[140:143], v[12:15]
	v_mfma_f32_16x16x32_bf16 v[60:63], v[24:27], v[92:95], v[60:63]
	v_mfma_f32_16x16x32_bf16 v[72:75], v[44:47], v[120:123], v[72:75]
	v_mfma_f32_16x16x32_bf16 v[64:67], v[44:47], v[92:95], v[64:67]
	s_waitcnt vmcnt(1)
	v_mfma_f32_16x16x32_bf16 v[8:11], v[24:27], v[144:147], v[8:11]
	v_mfma_f32_16x16x32_bf16 v[152:155], v[28:31], v[76:79], v[152:155]
	v_mfma_f32_16x16x32_bf16 v[56:59], v[48:51], v[76:79], v[56:59]
	v_mfma_f32_16x16x32_bf16 v[68:71], v[28:31], v[124:127], v[68:71]
	s_nop 5
	ds_write_b128 v16, v[152:155]
	v_mfma_f32_16x16x32_bf16 v[12:15], v[44:47], v[144:147], v[12:15]
	v_mfma_f32_16x16x32_bf16 v[60:63], v[28:31], v[96:99], v[60:63]
	v_mfma_f32_16x16x32_bf16 v[72:75], v[48:51], v[124:127], v[72:75]
	v_mfma_f32_16x16x32_bf16 v[64:67], v[48:51], v[96:99], v[64:67]
	ds_write_b128 v16, v[56:59] offset:1024
	s_nop 4
	ds_write_b128 v16, v[60:63] offset:2048
	s_nop 0
	ds_write_b128 v16, v[64:67] offset:3072
	s_waitcnt vmcnt(0)
	v_mfma_f32_16x16x32_bf16 v[8:11], v[28:31], v[148:151], v[8:11]
	ds_write_b128 v16, v[68:71] offset:4096
	ds_write_b128 v16, v[72:75] offset:5120
	s_nop 5
	ds_write_b128 v16, v[8:11] offset:6144
	v_mfma_f32_16x16x32_bf16 v[8:11], v[48:51], v[148:151], v[12:15]
	s_nop 7
	ds_write_b128 v16, v[8:11] offset:7168
	s_waitcnt lgkmcnt(0)
	s_barrier
	ds_read_b128 v[8:11], v2
	ds_read_b128 v[12:15], v2 offset:8192
	ds_read_b128 v[16:19], v2 offset:16384
	ds_read_b128 v[20:23], v2 offset:24576
	s_waitcnt lgkmcnt(2)
	v_pk_add_f32 v[10:11], v[10:11], v[14:15]
	v_pk_add_f32 v[12:13], v[8:9], v[12:13]
	s_waitcnt lgkmcnt(1)
	v_pk_add_f32 v[14:15], v[10:11], v[18:19]
	ds_read_b128 v[8:11], v2 offset:32768
	v_pk_add_f32 v[12:13], v[12:13], v[16:17]
	s_waitcnt lgkmcnt(1)
	v_pk_add_f32 v[16:17], v[14:15], v[22:23]
	v_pk_add_f32 v[20:21], v[12:13], v[20:21]
	ds_read_b128 v[12:15], v2 offset:40960
	s_waitcnt lgkmcnt(1)
	v_pk_add_f32 v[22:23], v[16:17], v[10:11]
	ds_read_b128 v[16:19], v2 offset:49152
	v_pk_add_f32 v[20:21], v[20:21], v[8:9]
	ds_read_b128 v[8:11], v2 offset:57344
	s_waitcnt lgkmcnt(2)
	v_pk_add_f32 v[14:15], v[22:23], v[14:15]
	v_pk_add_f32 v[12:13], v[20:21], v[12:13]
	s_waitcnt lgkmcnt(1)
	v_pk_add_f32 v[14:15], v[14:15], v[18:19]
	v_pk_add_f32 v[12:13], v[12:13], v[16:17]
	s_waitcnt lgkmcnt(0)
	v_pk_add_f32 v[10:11], v[14:15], v[10:11]
	v_pk_add_f32 v[8:9], v[12:13], v[8:9]
	v_lshlrev_b32_e32 v12, 16, v156
	v_and_b32_e32 v13, 0xffff0000, v156
	v_lshlrev_b32_e32 v14, 16, v157
	v_and_b32_e32 v15, 0xffff0000, v157
	v_pk_add_f32 v[10:11], v[10:11], v[14:15]
	v_pk_add_f32 v[12:13], v[8:9], v[12:13]
	v_mul_f32_e32 v8, v11, v11
	v_mul_f32_e32 v2, v13, v13
	v_fmac_f32_e32 v2, v12, v12
	v_fmac_f32_e32 v8, v10, v10
	v_add_f32_e32 v2, v2, v8
	v_cndmask_b32_e32 v8, v231, v234, vcc
	v_lshlrev_b32_e32 v8, 2, v8
	ds_bpermute_b32 v8, v8, v2
	v_cmp_lt_i32_e32 vcc, v236, v235
	v_cvt_pk_bf16_f32 v12, v12, v13
	v_cvt_pk_bf16_f32 v13, v10, v11
	s_waitcnt lgkmcnt(0)
	v_add_f32_e32 v2, v2, v8
	v_cndmask_b32_e32 v8, v231, v236, vcc
	v_lshlrev_b32_e32 v8, 2, v8
	ds_bpermute_b32 v8, v8, v2
	v_cmp_gt_u32_e32 vcc, 16, v158
	s_barrier
	s_waitcnt lgkmcnt(0)
	global_store_dwordx2 v[6:7], v[12:13], off sc1
	s_and_saveexec_b64 s[22:23], vcc
	s_cbranch_execz .LBB0_478
	v_lshl_add_u64 v[4:5], v[4:5], 2, s[20:21]
	v_add_f32_e32 v2, v2, v8
	global_atomic_add_f32 v[4:5], v2, off

.LBB0_505:
	s_lshl_b32 s40, s61, 8
	v_mov_b32_e32 v116, v197
	v_mov_b32_e32 v240, v245
	s_or_b32 s40, s40, s52
	s_nop 0
	v_lshl_add_u32 v208, v240, 3, s40
	s_lshl_b32 s40, s60, 8
	s_add_i32 s40, s40, s51
	v_add_u32_e32 v224, s40, v116
	v_ashrrev_i32_e32 v209, 31, v208
	v_lshlrev_b64 v[226:227], 1, v[208:209]
	v_ashrrev_i32_e32 v225, 31, v224
	v_lshl_add_u64 v[116:117], s[2:3], 0, v[226:227]
	v_lshlrev_b64 v[228:229], 11, v[224:225]
	v_lshl_add_u64 v[118:119], v[116:117], 0, v[228:229]
	global_load_dwordx4 v[248:251], v[118:119], off
	global_load_dwordx4 v[188:191], v[118:119], off offset:256
	s_mov_b64 s[40:41], 0x8000
	v_lshl_add_u64 v[222:223], v[228:229], 0, s[40:41]
	s_mov_b64 s[40:41], 0x10000
	v_lshl_add_u64 v[220:221], v[228:229], 0, s[40:41]
	s_mov_b64 s[40:41], 0x18000
	v_lshl_add_u64 v[118:119], v[116:117], 0, v[222:223]
	v_lshl_add_u64 v[218:219], v[228:229], 0, s[40:41]
	s_mov_b64 s[40:41], 0x40000
	global_load_dwordx4 v[184:187], v[118:119], off
	global_load_dwordx4 v[180:183], v[118:119], off offset:256
	v_lshl_add_u64 v[118:119], v[116:117], 0, v[220:221]
	v_lshl_add_u64 v[216:217], v[228:229], 0, s[40:41]
	s_mov_b64 s[40:41], 0x48000
	global_load_dwordx4 v[176:179], v[118:119], off
	global_load_dwordx4 v[172:175], v[118:119], off offset:256
	v_lshl_add_u64 v[118:119], v[116:117], 0, v[218:219]
	v_lshl_add_u64 v[214:215], v[228:229], 0, s[40:41]
	s_mov_b64 s[40:41], 0x50000
	global_load_dwordx4 v[168:171], v[118:119], off
	global_load_dwordx4 v[156:159], v[118:119], off offset:256
	v_lshl_add_u64 v[118:119], v[116:117], 0, v[216:217]
	v_lshl_add_u64 v[212:213], v[228:229], 0, s[40:41]
	s_mov_b64 s[40:41], 0x58000
	global_load_dwordx4 v[152:155], v[118:119], off
	global_load_dwordx4 v[148:151], v[118:119], off offset:256
	v_lshl_add_u64 v[118:119], v[116:117], 0, v[214:215]
	v_lshl_add_u64 v[210:211], v[228:229], 0, s[40:41]
	global_load_dwordx4 v[144:147], v[118:119], off
	global_load_dwordx4 v[136:139], v[118:119], off offset:256
	v_lshl_add_u64 v[118:119], v[116:117], 0, v[212:213]
	v_lshl_add_u64 v[116:117], v[116:117], 0, v[210:211]
	global_load_dwordx4 v[128:131], v[118:119], off
	global_load_dwordx4 v[120:123], v[118:119], off offset:256
	global_load_dwordx4 v[124:127], v[116:117], off
	s_nop 0
	global_load_dwordx4 v[116:119], v[116:117], off offset:256
	v_cmp_eq_u32_e32 vcc, 0, v240
	v_lshl_add_u64 v[228:229], s[2:3], 0, v[228:229]
	v_lshl_add_u64 v[226:227], v[228:229], 0, v[226:227]
	v_cmp_lt_i32_e64 s[40:41], v234, v235
	s_waitcnt vmcnt(0)
	v_lshlrev_b32_e32 v240, 16, v248
	v_and_b32_e32 v241, 0xffff0000, v248
	v_lshlrev_b32_e32 v248, 16, v249
	v_and_b32_e32 v249, 0xffff0000, v249
	v_pk_add_f32 v[164:165], v[164:165], v[240:241]
	v_lshlrev_b32_e32 v240, 16, v250
	v_and_b32_e32 v241, 0xffff0000, v250
	v_pk_add_f32 v[166:167], v[166:167], v[248:249]
	v_lshlrev_b32_e32 v248, 16, v251
	v_and_b32_e32 v249, 0xffff0000, v251
	v_pk_add_f32 v[240:241], v[160:161], v[240:241]
	v_cvt_pk_bf16_f32 v160, v164, v165
	v_cvt_pk_bf16_f32 v161, v166, v167
	v_pk_add_f32 v[248:249], v[162:163], v[248:249]
	v_cvt_pk_bf16_f32 v162, v240, v241
	s_nop 0
	v_cvt_pk_bf16_f32 v163, v248, v249
	global_store_dwordx4 v[226:227], v[160:163], off sc1
	s_nop 1
	v_mul_f32_e32 v160, v165, v165
	v_mul_f32_e32 v161, v167, v167
	v_fmac_f32_e32 v160, v164, v164
	v_fmac_f32_e32 v161, v166, v166
	v_add_f32_e32 v160, v160, v161
	v_mul_f32_e32 v161, v241, v241
	v_mul_f32_e32 v162, v249, v249
	v_fmac_f32_e32 v161, v240, v240
	v_fmac_f32_e32 v162, v248, v248
	v_add_f32_e32 v161, v161, v162
	v_add_f32_e32 v164, v160, v161
	v_lshlrev_b32_e32 v160, 16, v188
	v_and_b32_e32 v161, 0xffff0000, v188
	v_lshlrev_b32_e32 v162, 16, v189
	v_and_b32_e32 v163, 0xffff0000, v189
	v_pk_add_f32 v[140:141], v[140:141], v[160:161]
	v_lshlrev_b32_e32 v160, 16, v190
	v_and_b32_e32 v161, 0xffff0000, v190
	v_pk_add_f32 v[142:143], v[142:143], v[162:163]
	v_lshlrev_b32_e32 v162, 16, v191
	v_and_b32_e32 v163, 0xffff0000, v191
	v_pk_add_f32 v[160:161], v[132:133], v[160:161]
	v_cvt_pk_bf16_f32 v132, v140, v141
	v_cvt_pk_bf16_f32 v133, v142, v143
	v_pk_add_f32 v[162:163], v[134:135], v[162:163]
	v_cvt_pk_bf16_f32 v134, v160, v161
	s_nop 0
	v_cvt_pk_bf16_f32 v135, v162, v163
	global_store_dwordx4 v[226:227], v[132:135], off offset:256 sc1
	s_nop 1
	v_mul_f32_e32 v132, v141, v141
	v_mul_f32_e32 v133, v143, v143
	v_fmac_f32_e32 v132, v140, v140
	v_fmac_f32_e32 v133, v142, v142
	v_add_f32_e32 v132, v132, v133
	v_mul_f32_e32 v133, v161, v161
	v_mul_f32_e32 v134, v163, v163
	v_fmac_f32_e32 v133, v160, v160
	v_fmac_f32_e32 v134, v162, v162
	v_add_f32_e32 v133, v133, v134
	v_add_f32_e32 v132, v132, v133
	v_cndmask_b32_e64 v133, v231, v234, s[40:41]
	v_add_f32_e32 v132, v164, v132
	v_lshlrev_b32_e32 v134, 2, v133
	ds_bpermute_b32 v133, v134, v132
	v_cmp_lt_i32_e64 s[40:41], v236, v235
	s_waitcnt lgkmcnt(0)
	v_add_f32_e32 v140, v132, v133
	v_cndmask_b32_e64 v132, v231, v236, s[40:41]
	v_lshlrev_b32_e32 v135, 2, v132
	ds_bpermute_b32 v141, v135, v140
	v_lshl_add_u64 v[132:133], v[224:225], 2, s[20:21]
	s_and_saveexec_b64 s[40:41], vcc
	s_mov_b32 s63, 0x25000
	s_cbranch_execz .LBB0_507
	s_waitcnt lgkmcnt(0)
	v_add_f32_e32 v140, v140, v141
	global_atomic_add_f32 v[132:133], v140, off
.LBB0_507:
	s_or_b64 exec, exec, s[40:41]
	v_lshlrev_b32_e32 v140, 16, v184
	s_waitcnt lgkmcnt(0)
	v_and_b32_e32 v141, 0xffff0000, v184
	v_lshlrev_b32_e32 v142, 16, v185
	v_and_b32_e32 v143, 0xffff0000, v185
	v_pk_add_f32 v[112:113], v[112:113], v[140:141]
	v_lshlrev_b32_e32 v140, 16, v186
	v_and_b32_e32 v141, 0xffff0000, v186
	v_pk_add_f32 v[114:115], v[114:115], v[142:143]
	v_pk_add_f32 v[140:141], v[108:109], v[140:141]
	v_cvt_pk_bf16_f32 v108, v112, v113
	v_mul_f32_e32 v113, v113, v113
	v_lshlrev_b32_e32 v142, 16, v187
	v_and_b32_e32 v143, 0xffff0000, v187
	v_fmac_f32_e32 v113, v112, v112
	v_mul_f32_e32 v112, v115, v115
	v_pk_add_f32 v[142:143], v[110:111], v[142:143]
	v_fmac_f32_e32 v112, v114, v114
	v_cvt_pk_bf16_f32 v109, v114, v115
	v_add_f32_e32 v112, v113, v112
	v_mul_f32_e32 v113, v141, v141
	v_mul_f32_e32 v114, v143, v143
	v_fmac_f32_e32 v113, v140, v140
	v_fmac_f32_e32 v114, v142, v142
	v_add_f32_e32 v113, v113, v114
	v_cvt_pk_bf16_f32 v110, v140, v141
	v_add_f32_e32 v140, v112, v113
	v_lshlrev_b32_e32 v112, 16, v180
	v_and_b32_e32 v113, 0xffff0000, v180
	v_lshlrev_b32_e32 v114, 16, v181
	v_and_b32_e32 v115, 0xffff0000, v181
	v_pk_add_f32 v[106:107], v[106:107], v[114:115]
	v_pk_add_f32 v[104:105], v[104:105], v[112:113]
	v_lshlrev_b32_e32 v112, 16, v182
	v_and_b32_e32 v113, 0xffff0000, v182
	v_lshlrev_b32_e32 v114, 16, v183
	v_and_b32_e32 v115, 0xffff0000, v183
	v_pk_add_f32 v[112:113], v[100:101], v[112:113]
	v_mul_f32_e32 v100, v105, v105
	v_mul_f32_e32 v101, v107, v107
	v_pk_add_f32 v[114:115], v[102:103], v[114:115]
	v_fmac_f32_e32 v100, v104, v104
	v_fmac_f32_e32 v101, v106, v106
	v_add_f32_e32 v100, v100, v101
	v_mul_f32_e32 v101, v113, v113
	v_mul_f32_e32 v102, v115, v115
	v_fmac_f32_e32 v101, v112, v112
	v_fmac_f32_e32 v102, v114, v114
	v_add_f32_e32 v101, v101, v102
	v_add_f32_e32 v100, v100, v101
	v_add_f32_e32 v103, v140, v100
	v_cvt_pk_bf16_f32 v111, v142, v143
	ds_bpermute_b32 v142, v134, v103
	v_lshl_add_u64 v[100:101], s[2:3], 0, v[222:223]
	v_lshl_add_u64 v[140:141], v[208:209], 1, v[100:101]
	global_store_dwordx4 v[140:141], v[108:111], off sc1
	v_cvt_pk_bf16_f32 v102, v104, v105
	s_waitcnt lgkmcnt(0)
	v_add_f32_e32 v100, v103, v142
	ds_bpermute_b32 v101, v135, v100
	v_cvt_pk_bf16_f32 v103, v106, v107
	v_cvt_pk_bf16_f32 v104, v112, v113
	v_cvt_pk_bf16_f32 v105, v114, v115
	global_store_dwordx4 v[140:141], v[102:105], off offset:256 sc1
	s_and_saveexec_b64 s[40:41], vcc
	s_cbranch_execz .LBB0_509
	s_waitcnt lgkmcnt(0)
	v_add_f32_e32 v100, v100, v101
	global_atomic_add_f32 v[132:133], v100, off offset:64
.LBB0_509:
	s_or_b64 exec, exec, s[40:41]
	v_lshlrev_b32_e32 v100, 16, v176
	s_waitcnt lgkmcnt(0)
	v_and_b32_e32 v101, 0xffff0000, v176
	v_lshlrev_b32_e32 v102, 16, v177
	v_and_b32_e32 v103, 0xffff0000, v177
	v_pk_add_f32 v[96:97], v[96:97], v[100:101]
	v_lshlrev_b32_e32 v100, 16, v178
	v_and_b32_e32 v101, 0xffff0000, v178
	v_pk_add_f32 v[98:99], v[98:99], v[102:103]
	v_pk_add_f32 v[100:101], v[92:93], v[100:101]
	v_cvt_pk_bf16_f32 v92, v96, v97
	v_mul_f32_e32 v97, v97, v97
	v_lshlrev_b32_e32 v102, 16, v179
	v_and_b32_e32 v103, 0xffff0000, v179
	v_fmac_f32_e32 v97, v96, v96
	v_mul_f32_e32 v96, v99, v99
	v_pk_add_f32 v[102:103], v[94:95], v[102:103]
	v_fmac_f32_e32 v96, v98, v98
	v_cvt_pk_bf16_f32 v93, v98, v99
	v_add_f32_e32 v96, v97, v96
	v_mul_f32_e32 v97, v101, v101
	v_mul_f32_e32 v98, v103, v103
	v_fmac_f32_e32 v97, v100, v100
	v_fmac_f32_e32 v98, v102, v102
	v_add_f32_e32 v97, v97, v98
	v_cvt_pk_bf16_f32 v94, v100, v101
	v_add_f32_e32 v100, v96, v97
	v_lshlrev_b32_e32 v96, 16, v172
	v_and_b32_e32 v97, 0xffff0000, v172
	v_lshlrev_b32_e32 v98, 16, v173
	v_and_b32_e32 v99, 0xffff0000, v173
	v_pk_add_f32 v[90:91], v[90:91], v[98:99]
	v_pk_add_f32 v[88:89], v[88:89], v[96:97]
	v_lshlrev_b32_e32 v96, 16, v174
	v_and_b32_e32 v97, 0xffff0000, v174
	v_lshlrev_b32_e32 v98, 16, v175
	v_and_b32_e32 v99, 0xffff0000, v175
	v_pk_add_f32 v[96:97], v[84:85], v[96:97]
	v_mul_f32_e32 v84, v89, v89
	v_mul_f32_e32 v85, v91, v91
	v_pk_add_f32 v[98:99], v[86:87], v[98:99]
	v_fmac_f32_e32 v84, v88, v88
	v_fmac_f32_e32 v85, v90, v90
	v_add_f32_e32 v84, v84, v85
	v_mul_f32_e32 v85, v97, v97
	v_mul_f32_e32 v86, v99, v99
	v_fmac_f32_e32 v85, v96, v96
	v_fmac_f32_e32 v86, v98, v98
	v_add_f32_e32 v85, v85, v86
	v_add_f32_e32 v84, v84, v85
	v_add_f32_e32 v87, v100, v84
	v_cvt_pk_bf16_f32 v95, v102, v103
	ds_bpermute_b32 v102, v134, v87
	v_lshl_add_u64 v[84:85], s[2:3], 0, v[220:221]
	v_lshl_add_u64 v[100:101], v[208:209], 1, v[84:85]
	global_store_dwordx4 v[100:101], v[92:95], off sc1
	v_cvt_pk_bf16_f32 v86, v88, v89
	s_waitcnt lgkmcnt(0)
	v_add_f32_e32 v84, v87, v102
	ds_bpermute_b32 v85, v135, v84
	v_cvt_pk_bf16_f32 v87, v90, v91
	v_cvt_pk_bf16_f32 v88, v96, v97
	v_cvt_pk_bf16_f32 v89, v98, v99
	global_store_dwordx4 v[100:101], v[86:89], off offset:256 sc1
	s_and_saveexec_b64 s[40:41], vcc
	s_cbranch_execz .LBB0_511
	s_waitcnt lgkmcnt(0)
	v_add_f32_e32 v84, v84, v85
	global_atomic_add_f32 v[132:133], v84, off offset:128
.LBB0_511:
	s_or_b64 exec, exec, s[40:41]
	v_lshlrev_b32_e32 v84, 16, v168
	s_waitcnt lgkmcnt(0)
	v_and_b32_e32 v85, 0xffff0000, v168
	v_lshlrev_b32_e32 v86, 16, v169
	v_and_b32_e32 v87, 0xffff0000, v169
	v_pk_add_f32 v[80:81], v[80:81], v[84:85]
	v_lshlrev_b32_e32 v84, 16, v170
	v_and_b32_e32 v85, 0xffff0000, v170
	v_pk_add_f32 v[82:83], v[82:83], v[86:87]
	v_pk_add_f32 v[84:85], v[76:77], v[84:85]
	v_cvt_pk_bf16_f32 v76, v80, v81
	v_mul_f32_e32 v81, v81, v81
	v_lshlrev_b32_e32 v86, 16, v171
	v_and_b32_e32 v87, 0xffff0000, v171
	v_fmac_f32_e32 v81, v80, v80
	v_mul_f32_e32 v80, v83, v83
	v_pk_add_f32 v[86:87], v[78:79], v[86:87]
	v_fmac_f32_e32 v80, v82, v82
	v_cvt_pk_bf16_f32 v77, v82, v83
	v_add_f32_e32 v80, v81, v80
	v_mul_f32_e32 v81, v85, v85
	v_mul_f32_e32 v82, v87, v87
	v_fmac_f32_e32 v81, v84, v84
	v_fmac_f32_e32 v82, v86, v86
	v_add_f32_e32 v81, v81, v82
	v_cvt_pk_bf16_f32 v78, v84, v85
	v_add_f32_e32 v84, v80, v81
	v_lshlrev_b32_e32 v80, 16, v156
	v_and_b32_e32 v81, 0xffff0000, v156
	v_lshlrev_b32_e32 v82, 16, v157
	v_and_b32_e32 v83, 0xffff0000, v157
	v_pk_add_f32 v[74:75], v[74:75], v[82:83]
	v_pk_add_f32 v[72:73], v[72:73], v[80:81]
	v_lshlrev_b32_e32 v80, 16, v158
	v_and_b32_e32 v81, 0xffff0000, v158
	v_lshlrev_b32_e32 v82, 16, v159
	v_and_b32_e32 v83, 0xffff0000, v159
	v_pk_add_f32 v[80:81], v[68:69], v[80:81]
	v_mul_f32_e32 v68, v73, v73
	v_mul_f32_e32 v69, v75, v75
	v_pk_add_f32 v[82:83], v[70:71], v[82:83]
	v_fmac_f32_e32 v68, v72, v72
	v_fmac_f32_e32 v69, v74, v74
	v_add_f32_e32 v68, v68, v69
	v_mul_f32_e32 v69, v81, v81
	v_mul_f32_e32 v70, v83, v83
	v_fmac_f32_e32 v69, v80, v80
	v_fmac_f32_e32 v70, v82, v82
	v_add_f32_e32 v69, v69, v70
	v_add_f32_e32 v68, v68, v69
	v_add_f32_e32 v71, v84, v68
	v_cvt_pk_bf16_f32 v79, v86, v87
	ds_bpermute_b32 v86, v134, v71
	v_lshl_add_u64 v[68:69], s[2:3], 0, v[218:219]
	v_lshl_add_u64 v[84:85], v[208:209], 1, v[68:69]
	global_store_dwordx4 v[84:85], v[76:79], off sc1
	v_cvt_pk_bf16_f32 v70, v72, v73
	s_waitcnt lgkmcnt(0)
	v_add_f32_e32 v68, v71, v86
	ds_bpermute_b32 v69, v135, v68
	v_cvt_pk_bf16_f32 v71, v74, v75
	v_cvt_pk_bf16_f32 v72, v80, v81
	v_cvt_pk_bf16_f32 v73, v82, v83
	global_store_dwordx4 v[84:85], v[70:73], off offset:256 sc1
	s_and_saveexec_b64 s[40:41], vcc
	s_cbranch_execz .LBB0_513
	s_waitcnt lgkmcnt(0)
	v_add_f32_e32 v68, v68, v69
	global_atomic_add_f32 v[132:133], v68, off offset:192
.LBB0_513:
	s_or_b64 exec, exec, s[40:41]
	v_lshlrev_b32_e32 v68, 16, v152
	s_waitcnt lgkmcnt(0)
	v_and_b32_e32 v69, 0xffff0000, v152
	v_lshlrev_b32_e32 v70, 16, v153
	v_and_b32_e32 v71, 0xffff0000, v153
	v_pk_add_f32 v[64:65], v[64:65], v[68:69]
	v_lshlrev_b32_e32 v68, 16, v154
	v_and_b32_e32 v69, 0xffff0000, v154
	v_pk_add_f32 v[66:67], v[66:67], v[70:71]
	v_pk_add_f32 v[68:69], v[60:61], v[68:69]
	v_cvt_pk_bf16_f32 v60, v64, v65
	v_mul_f32_e32 v65, v65, v65
	v_lshlrev_b32_e32 v70, 16, v155
	v_and_b32_e32 v71, 0xffff0000, v155
	v_fmac_f32_e32 v65, v64, v64
	v_mul_f32_e32 v64, v67, v67
	v_pk_add_f32 v[70:71], v[62:63], v[70:71]
	v_fmac_f32_e32 v64, v66, v66
	v_cvt_pk_bf16_f32 v61, v66, v67
	v_add_f32_e32 v64, v65, v64
	v_mul_f32_e32 v65, v69, v69
	v_mul_f32_e32 v66, v71, v71
	v_fmac_f32_e32 v65, v68, v68
	v_fmac_f32_e32 v66, v70, v70
	v_add_f32_e32 v65, v65, v66
	v_cvt_pk_bf16_f32 v62, v68, v69
	v_add_f32_e32 v68, v64, v65
	v_lshlrev_b32_e32 v64, 16, v148
	v_and_b32_e32 v65, 0xffff0000, v148
	v_lshlrev_b32_e32 v66, 16, v149
	v_and_b32_e32 v67, 0xffff0000, v149
	v_pk_add_f32 v[58:59], v[58:59], v[66:67]
	v_pk_add_f32 v[56:57], v[56:57], v[64:65]
	v_lshlrev_b32_e32 v64, 16, v150
	v_and_b32_e32 v65, 0xffff0000, v150
	v_lshlrev_b32_e32 v66, 16, v151
	v_and_b32_e32 v67, 0xffff0000, v151
	v_pk_add_f32 v[64:65], v[52:53], v[64:65]
	v_mul_f32_e32 v52, v57, v57
	v_mul_f32_e32 v53, v59, v59
	v_pk_add_f32 v[66:67], v[54:55], v[66:67]
	v_fmac_f32_e32 v52, v56, v56
	v_fmac_f32_e32 v53, v58, v58
	v_add_f32_e32 v52, v52, v53
	v_mul_f32_e32 v53, v65, v65
	v_mul_f32_e32 v54, v67, v67
	v_fmac_f32_e32 v53, v64, v64
	v_fmac_f32_e32 v54, v66, v66
	v_add_f32_e32 v53, v53, v54
	v_add_f32_e32 v52, v52, v53
	v_add_f32_e32 v55, v68, v52
	v_cvt_pk_bf16_f32 v63, v70, v71
	ds_bpermute_b32 v70, v134, v55
	v_lshl_add_u64 v[52:53], s[2:3], 0, v[216:217]
	v_lshl_add_u64 v[68:69], v[208:209], 1, v[52:53]
	global_store_dwordx4 v[68:69], v[60:63], off sc1
	v_cvt_pk_bf16_f32 v54, v56, v57
	s_waitcnt lgkmcnt(0)
	v_add_f32_e32 v52, v55, v70
	ds_bpermute_b32 v53, v135, v52
	v_cvt_pk_bf16_f32 v55, v58, v59
	v_cvt_pk_bf16_f32 v56, v64, v65
	v_cvt_pk_bf16_f32 v57, v66, v67
	global_store_dwordx4 v[68:69], v[54:57], off offset:256 sc1
	s_and_saveexec_b64 s[40:41], vcc
	s_cbranch_execz .LBB0_515
	s_waitcnt lgkmcnt(0)
	v_add_f32_e32 v52, v52, v53
	global_atomic_add_f32 v[132:133], v52, off offset:512
.LBB0_515:
	s_or_b64 exec, exec, s[40:41]
	v_lshlrev_b32_e32 v52, 16, v144
	s_waitcnt lgkmcnt(0)
	v_and_b32_e32 v53, 0xffff0000, v144
	v_lshlrev_b32_e32 v54, 16, v145
	v_and_b32_e32 v55, 0xffff0000, v145
	v_pk_add_f32 v[48:49], v[48:49], v[52:53]
	v_lshlrev_b32_e32 v52, 16, v146
	v_and_b32_e32 v53, 0xffff0000, v146
	v_pk_add_f32 v[50:51], v[50:51], v[54:55]
	v_pk_add_f32 v[52:53], v[44:45], v[52:53]
	v_cvt_pk_bf16_f32 v44, v48, v49
	v_mul_f32_e32 v49, v49, v49
	v_lshlrev_b32_e32 v54, 16, v147
	v_and_b32_e32 v55, 0xffff0000, v147
	v_fmac_f32_e32 v49, v48, v48
	v_mul_f32_e32 v48, v51, v51
	v_pk_add_f32 v[54:55], v[46:47], v[54:55]
	v_fmac_f32_e32 v48, v50, v50
	v_cvt_pk_bf16_f32 v45, v50, v51
	v_add_f32_e32 v48, v49, v48
	v_mul_f32_e32 v49, v53, v53
	v_mul_f32_e32 v50, v55, v55
	v_fmac_f32_e32 v49, v52, v52
	v_fmac_f32_e32 v50, v54, v54
	v_add_f32_e32 v49, v49, v50
	v_cvt_pk_bf16_f32 v46, v52, v53
	v_add_f32_e32 v52, v48, v49
	v_lshlrev_b32_e32 v48, 16, v136
	v_and_b32_e32 v49, 0xffff0000, v136
	v_lshlrev_b32_e32 v50, 16, v137
	v_and_b32_e32 v51, 0xffff0000, v137
	v_pk_add_f32 v[42:43], v[42:43], v[50:51]
	v_pk_add_f32 v[40:41], v[40:41], v[48:49]
	v_lshlrev_b32_e32 v48, 16, v138
	v_and_b32_e32 v49, 0xffff0000, v138
	v_lshlrev_b32_e32 v50, 16, v139
	v_and_b32_e32 v51, 0xffff0000, v139
	v_pk_add_f32 v[48:49], v[36:37], v[48:49]
	v_mul_f32_e32 v36, v41, v41
	v_mul_f32_e32 v37, v43, v43
	v_pk_add_f32 v[50:51], v[38:39], v[50:51]
	v_fmac_f32_e32 v36, v40, v40
	v_fmac_f32_e32 v37, v42, v42
	v_add_f32_e32 v36, v36, v37
	v_mul_f32_e32 v37, v49, v49
	v_mul_f32_e32 v38, v51, v51
	v_fmac_f32_e32 v37, v48, v48
	v_fmac_f32_e32 v38, v50, v50
	v_add_f32_e32 v37, v37, v38
	v_add_f32_e32 v36, v36, v37
	v_add_f32_e32 v39, v52, v36
	v_cvt_pk_bf16_f32 v47, v54, v55
	ds_bpermute_b32 v54, v134, v39
	v_lshl_add_u64 v[36:37], s[2:3], 0, v[214:215]
	v_lshl_add_u64 v[52:53], v[208:209], 1, v[36:37]
	global_store_dwordx4 v[52:53], v[44:47], off sc1
	v_cvt_pk_bf16_f32 v38, v40, v41
	s_waitcnt lgkmcnt(0)
	v_add_f32_e32 v36, v39, v54
	ds_bpermute_b32 v37, v135, v36
	v_cvt_pk_bf16_f32 v39, v42, v43
	v_cvt_pk_bf16_f32 v40, v48, v49
	v_cvt_pk_bf16_f32 v41, v50, v51
	global_store_dwordx4 v[52:53], v[38:41], off offset:256 sc1
	s_and_saveexec_b64 s[40:41], vcc
	s_cbranch_execz .LBB0_517
	s_waitcnt lgkmcnt(0)
	v_add_f32_e32 v36, v36, v37
	global_atomic_add_f32 v[132:133], v36, off offset:576
.LBB0_517:
	s_or_b64 exec, exec, s[40:41]
	v_lshlrev_b32_e32 v36, 16, v128
	s_waitcnt lgkmcnt(0)
	v_and_b32_e32 v37, 0xffff0000, v128
	v_lshlrev_b32_e32 v38, 16, v129
	v_and_b32_e32 v39, 0xffff0000, v129
	v_pk_add_f32 v[32:33], v[32:33], v[36:37]
	v_lshlrev_b32_e32 v36, 16, v130
	v_and_b32_e32 v37, 0xffff0000, v130
	v_pk_add_f32 v[34:35], v[34:35], v[38:39]
	v_pk_add_f32 v[36:37], v[28:29], v[36:37]
	v_cvt_pk_bf16_f32 v28, v32, v33
	v_mul_f32_e32 v33, v33, v33
	v_lshlrev_b32_e32 v38, 16, v131
	v_and_b32_e32 v39, 0xffff0000, v131
	v_fmac_f32_e32 v33, v32, v32
	v_mul_f32_e32 v32, v35, v35
	v_pk_add_f32 v[38:39], v[30:31], v[38:39]
	v_fmac_f32_e32 v32, v34, v34
	v_cvt_pk_bf16_f32 v29, v34, v35
	v_add_f32_e32 v32, v33, v32
	v_mul_f32_e32 v33, v37, v37
	v_mul_f32_e32 v34, v39, v39
	v_fmac_f32_e32 v33, v36, v36
	v_fmac_f32_e32 v34, v38, v38
	v_add_f32_e32 v33, v33, v34
	v_cvt_pk_bf16_f32 v30, v36, v37
	v_add_f32_e32 v36, v32, v33
	v_lshlrev_b32_e32 v32, 16, v120
	v_and_b32_e32 v33, 0xffff0000, v120
	v_lshlrev_b32_e32 v34, 16, v121
	v_and_b32_e32 v35, 0xffff0000, v121
	v_pk_add_f32 v[26:27], v[26:27], v[34:35]
	v_pk_add_f32 v[24:25], v[24:25], v[32:33]
	v_lshlrev_b32_e32 v32, 16, v122
	v_and_b32_e32 v33, 0xffff0000, v122
	v_lshlrev_b32_e32 v34, 16, v123
	v_and_b32_e32 v35, 0xffff0000, v123
	v_pk_add_f32 v[32:33], v[20:21], v[32:33]
	v_mul_f32_e32 v20, v25, v25
	v_mul_f32_e32 v21, v27, v27
	v_pk_add_f32 v[34:35], v[22:23], v[34:35]
	v_fmac_f32_e32 v20, v24, v24
	v_fmac_f32_e32 v21, v26, v26
	v_add_f32_e32 v20, v20, v21
	v_mul_f32_e32 v21, v33, v33
	v_mul_f32_e32 v22, v35, v35
	v_fmac_f32_e32 v21, v32, v32
	v_fmac_f32_e32 v22, v34, v34
	v_add_f32_e32 v21, v21, v22
	v_add_f32_e32 v20, v20, v21
	v_add_f32_e32 v23, v36, v20
	v_cvt_pk_bf16_f32 v31, v38, v39
	ds_bpermute_b32 v38, v134, v23
	v_lshl_add_u64 v[20:21], s[2:3], 0, v[212:213]
	v_lshl_add_u64 v[36:37], v[208:209], 1, v[20:21]
	global_store_dwordx4 v[36:37], v[28:31], off sc1
	v_cvt_pk_bf16_f32 v22, v24, v25
	s_waitcnt lgkmcnt(0)
	v_add_f32_e32 v20, v23, v38
	ds_bpermute_b32 v21, v135, v20
	v_cvt_pk_bf16_f32 v23, v26, v27
	v_cvt_pk_bf16_f32 v24, v32, v33
	v_cvt_pk_bf16_f32 v25, v34, v35
	global_store_dwordx4 v[36:37], v[22:25], off offset:256 sc1
	s_and_saveexec_b64 s[40:41], vcc
	s_cbranch_execz .LBB0_519
	s_waitcnt lgkmcnt(0)
	v_add_f32_e32 v20, v20, v21
	global_atomic_add_f32 v[132:133], v20, off offset:640
.LBB0_519:
	s_or_b64 exec, exec, s[40:41]
	v_lshlrev_b32_e32 v20, 16, v124
	s_waitcnt lgkmcnt(0)
	v_and_b32_e32 v21, 0xffff0000, v124
	v_lshlrev_b32_e32 v22, 16, v125
	v_and_b32_e32 v23, 0xffff0000, v125
	v_pk_add_f32 v[16:17], v[16:17], v[20:21]
	v_lshlrev_b32_e32 v20, 16, v126
	v_and_b32_e32 v21, 0xffff0000, v126
	v_pk_add_f32 v[18:19], v[18:19], v[22:23]
	v_pk_add_f32 v[20:21], v[12:13], v[20:21]
	v_cvt_pk_bf16_f32 v12, v16, v17
	v_mul_f32_e32 v17, v17, v17
	v_lshlrev_b32_e32 v22, 16, v127
	v_and_b32_e32 v23, 0xffff0000, v127
	v_fmac_f32_e32 v17, v16, v16
	v_mul_f32_e32 v16, v19, v19
	v_pk_add_f32 v[22:23], v[14:15], v[22:23]
	v_fmac_f32_e32 v16, v18, v18
	v_cvt_pk_bf16_f32 v13, v18, v19
	v_add_f32_e32 v16, v17, v16
	v_mul_f32_e32 v17, v21, v21
	v_mul_f32_e32 v18, v23, v23
	v_fmac_f32_e32 v17, v20, v20
	v_fmac_f32_e32 v18, v22, v22
	v_add_f32_e32 v17, v17, v18
	v_cvt_pk_bf16_f32 v14, v20, v21
	v_add_f32_e32 v20, v16, v17
	v_lshlrev_b32_e32 v16, 16, v116
	v_and_b32_e32 v17, 0xffff0000, v116
	v_lshlrev_b32_e32 v18, 16, v117
	v_and_b32_e32 v19, 0xffff0000, v117
	v_pk_add_f32 v[10:11], v[10:11], v[18:19]
	v_pk_add_f32 v[8:9], v[8:9], v[16:17]
	v_lshlrev_b32_e32 v16, 16, v118
	v_and_b32_e32 v17, 0xffff0000, v118
	v_lshlrev_b32_e32 v18, 16, v119
	v_and_b32_e32 v19, 0xffff0000, v119
	v_pk_add_f32 v[16:17], v[4:5], v[16:17]
	v_mul_f32_e32 v4, v9, v9
	v_mul_f32_e32 v5, v11, v11
	v_pk_add_f32 v[18:19], v[6:7], v[18:19]
	v_fmac_f32_e32 v4, v8, v8
	v_fmac_f32_e32 v5, v10, v10
	v_add_f32_e32 v4, v4, v5
	v_mul_f32_e32 v5, v17, v17
	v_mul_f32_e32 v6, v19, v19
	v_fmac_f32_e32 v5, v16, v16
	v_fmac_f32_e32 v6, v18, v18
	v_add_f32_e32 v5, v5, v6
	v_add_f32_e32 v4, v4, v5
	v_add_f32_e32 v7, v20, v4
	v_cvt_pk_bf16_f32 v15, v22, v23
	ds_bpermute_b32 v22, v134, v7
	v_lshl_add_u64 v[4:5], s[2:3], 0, v[210:211]
	v_lshl_add_u64 v[20:21], v[208:209], 1, v[4:5]
	global_store_dwordx4 v[20:21], v[12:15], off sc1
	v_cvt_pk_bf16_f32 v6, v8, v9
	s_waitcnt lgkmcnt(0)
	v_add_f32_e32 v4, v7, v22
	ds_bpermute_b32 v5, v135, v4
	v_cvt_pk_bf16_f32 v7, v10, v11
	v_cvt_pk_bf16_f32 v8, v16, v17
	v_cvt_pk_bf16_f32 v9, v18, v19
	global_store_dwordx4 v[20:21], v[6:9], off offset:256 sc1
	s_and_saveexec_b64 s[40:41], vcc
	s_cbranch_execz .LBB0_521
	s_waitcnt lgkmcnt(0)
	v_add_f32_e32 v4, v4, v5
	global_atomic_add_f32 v[132:133], v4, off offset:704

.LBB0_532:
	s_ashr_i32 s44, s40, 4
	s_add_i32 s20, s44, 0x4000
	s_and_b32 s41, s40, 15
	s_ashr_i32 s21, s20, 31
	s_mul_i32 s23, s20, 0x1800
	s_mul_hi_i32 s22, s20, 0x1800
	s_add_u32 s23, s0, s23
	s_addc_u32 s24, s1, s22
	s_lshl_b32 s22, s41, 7
	s_add_u32 s22, s23, s22
	s_addc_u32 s23, s24, 0
	s_lshl_b64 s[30:31], s[20:21], 8
	s_add_u32 s21, s4, s30
	s_addc_u32 s24, s9, s31
	s_lshl_b32 s42, s40, 3
	s_and_b32 s45, s42, 64
	s_lshl_b32 s46, s45, 1
	s_add_u32 s42, s21, s46
	s_addc_u32 s43, s24, 0
	s_add_u32 s21, s14, s30
	s_addc_u32 s24, s28, s31
	s_add_u32 s30, s21, s46
	s_waitcnt vmcnt(24) lgkmcnt(2)
	v_lshl_add_u64 v[6:7], s[42:43], 0, v[104:105]
	s_addc_u32 s31, s24, 0
	s_add_i32 s24, s41, s29
	v_lshl_add_u64 v[4:5], s[22:23], 0, v[104:105]
	global_load_dwordx2 v[6:7], v[6:7], off
	s_nop 0
	global_load_dwordx2 v[106:107], v2, s[30:31]
	global_load_dwordx2 v[112:113], v[4:5], off
	s_lshl_b64 s[30:31], s[24:25], 2
	s_add_u32 s30, s2, s30
	s_addc_u32 s31, s3, s31
	global_load_dword v120, v3, s[30:31] offset:-128
	v_lshl_or_b32 v4, s44, 7, v197
	v_ashrrev_i32_e32 v5, 31, v4
	v_lshlrev_b64 v[110:111], 9, v[4:5]
	v_lshl_or_b32 v110, s45, 2, v110
	v_lshl_add_u64 v[4:5], v[100:101], 0, v[110:111]
	s_waitcnt vmcnt(3)
	v_lshlrev_b32_e32 v121, 16, v6
	v_and_b32_e32 v123, 0xffff0000, v6
	v_lshlrev_b32_e32 v122, 16, v7
	v_and_b32_e32 v124, 0xffff0000, v7
	v_add_co_u32_e32 v6, vcc, s17, v4
	global_load_dwordx4 v[126:129], v[4:5], off nt
	global_load_dwordx4 v[130:133], v[4:5], off offset:2048 nt
	v_addc_co_u32_e32 v7, vcc, 0, v5, vcc
	v_add_co_u32_e32 v108, vcc, s91, v4
	s_movk_i32 s21, 0x6000
	s_nop 0
	v_addc_co_u32_e32 v109, vcc, 0, v5, vcc
	v_add_co_u32_e32 v8, vcc, s50, v4
	global_load_dwordx4 v[134:137], v[108:109], off nt
	global_load_dwordx4 v[138:141], v[108:109], off offset:2048 nt
	v_addc_co_u32_e32 v9, vcc, 0, v5, vcc
	s_waitcnt lgkmcnt(1)
	v_add_co_u32_e32 v10, vcc, s90, v4
	s_waitcnt vmcnt(4)
	v_mul_f32_e32 v120, 0x3fb8aa3b, v120
	s_waitcnt lgkmcnt(0)
	v_addc_co_u32_e32 v11, vcc, 0, v5, vcc
	global_load_dwordx4 v[142:145], v[6:7], off offset:2048 nt
	global_load_dwordx4 v[146:149], v[8:9], off offset:2048 nt
	global_load_dwordx4 v[150:153], v[10:11], off offset:-4096 nt
	global_load_dwordx4 v[96:99], v[10:11], off nt
	v_add_co_u32_e32 v6, vcc, s96, v4
	s_nop 1
	v_addc_co_u32_e32 v7, vcc, 0, v5, vcc
	v_add_co_u32_e32 v8, vcc, s21, v4
	s_nop 1
	v_addc_co_u32_e32 v9, vcc, 0, v5, vcc
	global_load_dwordx4 v[92:95], v[10:11], off offset:2048 nt
	global_load_dwordx4 v[88:91], v[8:9], off offset:-4096 nt
	global_load_dwordx4 v[80:83], v[8:9], off nt
	global_load_dwordx4 v[76:79], v[8:9], off offset:2048 nt
	v_add_co_u32_e32 v8, vcc, s51, v4
	s_nop 1
	v_addc_co_u32_e32 v9, vcc, 0, v5, vcc
	v_add_co_u32_e32 v10, vcc, s92, v4
	s_nop 1
	v_addc_co_u32_e32 v11, vcc, 0, v5, vcc
	global_load_dwordx4 v[84:87], v[6:7], off offset:2048 nt
	global_load_dwordx4 v[68:71], v[8:9], off offset:2048 nt
	global_load_dwordx4 v[72:75], v[10:11], off offset:-4096 nt
	global_load_dwordx4 v[64:67], v[10:11], off nt
	v_add_co_u32_e32 v6, vcc, s56, v4
	s_nop 1
	v_addc_co_u32_e32 v7, vcc, 0, v5, vcc
	v_add_co_u32_e32 v8, vcc, s93, v4
	s_nop 1
	v_addc_co_u32_e32 v9, vcc, 0, v5, vcc
	global_load_dwordx4 v[60:63], v[10:11], off offset:2048 nt
	global_load_dwordx4 v[56:59], v[8:9], off offset:-4096 nt
	global_load_dwordx4 v[48:51], v[8:9], off nt
	global_load_dwordx4 v[44:47], v[8:9], off offset:2048 nt
	v_add_co_u32_e32 v8, vcc, s57, v4
	s_nop 1
	v_addc_co_u32_e32 v9, vcc, 0, v5, vcc
	v_add_co_u32_e32 v10, vcc, s6, v4
	s_nop 1
	v_addc_co_u32_e32 v11, vcc, 0, v5, vcc
	global_load_dwordx4 v[52:55], v[6:7], off offset:2048 nt
	global_load_dwordx4 v[36:39], v[8:9], off offset:2048 nt
	global_load_dwordx4 v[40:43], v[10:11], off offset:-4096 nt
	global_load_dwordx4 v[32:35], v[10:11], off nt
	v_add_co_u32_e32 v6, vcc, s58, v4
	s_nop 1
	v_addc_co_u32_e32 v7, vcc, 0, v5, vcc
	v_add_co_u32_e32 v8, vcc, s95, v4
	s_nop 1
	v_addc_co_u32_e32 v9, vcc, 0, v5, vcc
	v_add_co_u32_e32 v4, vcc, s52, v4
	global_load_dwordx4 v[28:31], v[10:11], off offset:2048 nt
	global_load_dwordx4 v[24:27], v[8:9], off offset:-4096 nt
	global_load_dwordx4 v[16:19], v[8:9], off nt
	global_load_dwordx4 v[12:15], v[8:9], off offset:2048 nt
	v_addc_co_u32_e32 v5, vcc, 0, v5, vcc
	global_load_dwordx4 v[20:23], v[6:7], off offset:2048 nt
	global_load_dwordx4 v[8:11], v[4:5], off nt
	global_load_dwordx4 v[154:157], v[108:109], off offset:-4096 nt
	s_nop 0
	global_load_dwordx4 v[4:7], v[4:5], off offset:2048 nt
	v_and_b32_e32 v108, 0xffff0000, v112
	v_lshlrev_b32_e32 v109, 16, v113
	v_lshlrev_b32_e32 v112, 16, v112
	v_and_b32_e32 v113, 0xffff0000, v113
	s_waitcnt vmcnt(31)
	v_mov_b32_e32 v158, v127
	v_mov_b32_e32 v127, v129
	v_mov_b32_e32 v159, v128
	v_pk_mul_f32 v[126:127], v[126:127], v[112:113]
	s_movk_i32 s33, 0x6000
	v_pk_fma_f32 v[126:127], v[158:159], v[108:109], v[126:127]
	s_nop 0
	v_add_f32_e32 v125, v126, v127
	s_waitcnt vmcnt(30)
	v_mov_b32_e32 v126, v131
	v_mov_b32_e32 v131, v133
	v_mov_b32_e32 v127, v132
	v_pk_mul_f32 v[128:129], v[130:131], v[112:113]
	ds_bpermute_b32 v158, v114, v125
	v_pk_fma_f32 v[126:127], v[126:127], v[108:109], v[128:129]
	s_waitcnt lgkmcnt(0)
	v_add_f32_e32 v125, v125, v158
	v_add_f32_e32 v126, v126, v127
	ds_bpermute_b32 v127, v114, v126
	ds_bpermute_b32 v128, v115, v125
	s_waitcnt lgkmcnt(1)
	v_add_f32_e32 v126, v126, v127
	ds_bpermute_b32 v127, v115, v126
	s_waitcnt lgkmcnt(1)
	v_add_f32_e32 v125, v125, v128
	ds_bpermute_b32 v128, v116, v125
	s_waitcnt lgkmcnt(1)
	v_add_f32_e32 v126, v126, v127
	ds_bpermute_b32 v127, v116, v126
	s_waitcnt lgkmcnt(1)
	v_add_f32_e32 v125, v125, v128
	ds_bpermute_b32 v130, v117, v125
	s_waitcnt lgkmcnt(1)
	v_add_f32_e32 v131, v126, v127
	s_waitcnt vmcnt(1)
	v_mov_b32_e32 v126, v155
	v_mov_b32_e32 v155, v157
	v_mov_b32_e32 v127, v156
	v_pk_mul_f32 v[128:129], v[154:155], v[112:113]
	ds_bpermute_b32 v132, v117, v131
	v_pk_fma_f32 v[126:127], v[126:127], v[108:109], v[128:129]
	s_waitcnt lgkmcnt(1)
	v_add_f32_e32 v130, v125, v130
	v_add_f32_e32 v133, v126, v127
	v_mov_b32_e32 v126, v143
	v_mov_b32_e32 v143, v145
	v_mov_b32_e32 v127, v144
	v_pk_mul_f32 v[128:129], v[142:143], v[112:113]
	ds_bpermute_b32 v154, v114, v133
	v_pk_fma_f32 v[126:127], v[126:127], v[108:109], v[128:129]
	v_mov_b32_e32 v129, v136
	v_add_f32_e32 v127, v126, v127
	ds_bpermute_b32 v128, v114, v127
	s_waitcnt lgkmcnt(2)
	v_add_f32_e32 v126, v131, v132
	s_waitcnt lgkmcnt(1)
	v_add_f32_e32 v125, v133, v154
	ds_bpermute_b32 v131, v115, v125
	s_waitcnt lgkmcnt(1)
	v_add_f32_e32 v127, v127, v128
	v_mov_b32_e32 v128, v135
	v_mov_b32_e32 v135, v137
	v_pk_mul_f32 v[132:133], v[134:135], v[112:113]
	ds_bpermute_b32 v142, v115, v127
	v_pk_fma_f32 v[128:129], v[128:129], v[108:109], v[132:133]
	s_waitcnt lgkmcnt(1)
	v_add_f32_e32 v125, v125, v131
	v_add_f32_e32 v128, v128, v129
	ds_bpermute_b32 v129, v114, v128
	s_waitcnt lgkmcnt(1)
	v_add_f32_e32 v127, v127, v142
	ds_bpermute_b32 v132, v116, v127
	ds_bpermute_b32 v131, v116, v125
	s_waitcnt lgkmcnt(2)
	v_add_f32_e32 v128, v128, v129
	ds_bpermute_b32 v129, v115, v128
	s_waitcnt lgkmcnt(2)
	v_add_f32_e32 v127, v127, v132
	s_waitcnt lgkmcnt(1)
	v_add_f32_e32 v125, v125, v131
	ds_bpermute_b32 v131, v117, v125
	ds_bpermute_b32 v134, v117, v127
	s_waitcnt lgkmcnt(2)
	v_add_f32_e32 v135, v128, v129
	v_mov_b32_e32 v128, v139
	v_mov_b32_e32 v139, v141
	v_mov_b32_e32 v129, v140
	v_pk_mul_f32 v[132:133], v[138:139], v[112:113]
	ds_bpermute_b32 v136, v116, v135
	v_pk_fma_f32 v[128:129], v[128:129], v[108:109], v[132:133]
	v_mov_b32_e32 v133, v152
	v_add_f32_e32 v129, v128, v129
	ds_bpermute_b32 v132, v114, v129
	s_waitcnt lgkmcnt(3)
	v_add_f32_e32 v128, v125, v131
	s_waitcnt lgkmcnt(2)
	v_add_f32_e32 v125, v127, v134
	s_waitcnt lgkmcnt(1)
	v_add_f32_e32 v127, v135, v136
	ds_bpermute_b32 v131, v117, v127
	s_waitcnt lgkmcnt(1)
	v_add_f32_e32 v129, v129, v132
	v_mov_b32_e32 v132, v151
	v_mov_b32_e32 v151, v153
	v_pk_mul_f32 v[134:135], v[150:151], v[112:113]
	ds_bpermute_b32 v136, v115, v129
	v_pk_fma_f32 v[132:133], v[132:133], v[108:109], v[134:135]
	s_waitcnt lgkmcnt(0)
	v_add_f32_e32 v129, v129, v136
	v_add_f32_e32 v137, v132, v133
	v_mov_b32_e32 v132, v147
	v_mov_b32_e32 v147, v149
	v_mov_b32_e32 v133, v148
	v_pk_mul_f32 v[134:135], v[146:147], v[112:113]
	ds_bpermute_b32 v138, v114, v137
	v_pk_fma_f32 v[132:133], v[132:133], v[108:109], v[134:135]
	ds_bpermute_b32 v134, v116, v129
	v_add_f32_e32 v132, v132, v133
	ds_bpermute_b32 v133, v114, v132
	s_waitcnt lgkmcnt(2)
	v_add_f32_e32 v135, v137, v138
	ds_bpermute_b32 v136, v115, v135
	s_waitcnt lgkmcnt(2)
	v_add_f32_e32 v134, v129, v134
	v_add_f32_e32 v129, v127, v131
	s_waitcnt lgkmcnt(1)
	v_add_f32_e32 v132, v132, v133
	ds_bpermute_b32 v133, v115, v132
	s_waitcnt lgkmcnt(1)
	v_add_f32_e32 v135, v135, v136
	ds_bpermute_b32 v136, v116, v135
	ds_bpermute_b32 v137, v117, v134
	s_waitcnt lgkmcnt(2)
	v_add_f32_e32 v132, v132, v133
	ds_bpermute_b32 v133, v116, v132
	s_waitcnt lgkmcnt(2)
	v_add_f32_e32 v131, v135, v136
	s_waitcnt lgkmcnt(1)
	v_add_f32_e32 v127, v134, v137
	ds_bpermute_b32 v134, v117, v131
	s_waitcnt lgkmcnt(1)
	v_add_f32_e32 v135, v132, v133
	v_mov_b32_e32 v132, v97
	v_mov_b32_e32 v97, v99
	v_mov_b32_e32 v133, v98
	v_pk_mul_f32 v[96:97], v[96:97], v[112:113]
	ds_bpermute_b32 v136, v117, v135
	v_pk_fma_f32 v[96:97], v[132:133], v[108:109], v[96:97]
	s_nop 0
	v_add_f32_e32 v98, v96, v97
	v_mov_b32_e32 v96, v93
	v_mov_b32_e32 v93, v95
	v_mov_b32_e32 v97, v94
	v_pk_mul_f32 v[92:93], v[92:93], v[112:113]
	ds_bpermute_b32 v99, v114, v98
	v_pk_fma_f32 v[92:93], v[96:97], v[108:109], v[92:93]
	s_waitcnt lgkmcnt(0)
	v_add_f32_e32 v96, v98, v99
	v_add_f32_e32 v94, v92, v93
	ds_bpermute_b32 v95, v114, v94
	ds_bpermute_b32 v97, v115, v96
	v_add_f32_e32 v93, v131, v134
	v_add_f32_e32 v92, v135, v136
	s_waitcnt lgkmcnt(1)
	v_add_f32_e32 v98, v94, v95
	v_mov_b32_e32 v94, v89
	v_mov_b32_e32 v89, v91
	v_mov_b32_e32 v95, v90
	v_pk_mul_f32 v[88:89], v[88:89], v[112:113]
	s_waitcnt lgkmcnt(0)
	v_add_f32_e32 v90, v96, v97
	v_pk_fma_f32 v[88:89], v[94:95], v[108:109], v[88:89]
	ds_bpermute_b32 v91, v116, v90
	v_add_f32_e32 v88, v88, v89
	ds_bpermute_b32 v89, v114, v88
	ds_bpermute_b32 v99, v115, v98
	s_waitcnt lgkmcnt(2)
	v_add_f32_e32 v90, v90, v91
	ds_bpermute_b32 v91, v117, v90
	s_waitcnt lgkmcnt(2)
	v_add_f32_e32 v88, v88, v89
	ds_bpermute_b32 v89, v115, v88
	s_waitcnt lgkmcnt(2)
	v_add_f32_e32 v94, v98, v99
	ds_bpermute_b32 v95, v116, v94
	s_waitcnt lgkmcnt(1)
	v_add_f32_e32 v96, v88, v89
	v_mov_b32_e32 v88, v85
	v_mov_b32_e32 v85, v87
	v_mov_b32_e32 v89, v86
	v_pk_mul_f32 v[84:85], v[84:85], v[112:113]
	ds_bpermute_b32 v97, v116, v96
	v_pk_fma_f32 v[84:85], v[88:89], v[108:109], v[84:85]
	s_waitcnt lgkmcnt(1)
	v_add_f32_e32 v94, v94, v95
	v_add_f32_e32 v86, v84, v85
	ds_bpermute_b32 v87, v114, v86
	v_add_f32_e32 v85, v90, v91
	s_waitcnt lgkmcnt(1)
	v_add_f32_e32 v88, v96, v97
	ds_bpermute_b32 v95, v117, v94
	ds_bpermute_b32 v89, v117, v88
	s_waitcnt lgkmcnt(2)
	v_add_f32_e32 v90, v86, v87
	v_mov_b32_e32 v86, v81
	v_mov_b32_e32 v81, v83
	ds_bpermute_b32 v91, v115, v90
	v_mov_b32_e32 v87, v82
	v_pk_mul_f32 v[80:81], v[80:81], v[112:113]
	s_waitcnt lgkmcnt(2)
	v_add_f32_e32 v84, v94, v95
	v_pk_fma_f32 v[80:81], v[86:87], v[108:109], v[80:81]
	s_nop 0
	v_add_f32_e32 v82, v80, v81
	v_mov_b32_e32 v80, v77
	v_mov_b32_e32 v77, v79
	v_mov_b32_e32 v81, v78
	v_pk_mul_f32 v[76:77], v[76:77], v[112:113]
	s_waitcnt lgkmcnt(0)
	v_add_f32_e32 v78, v90, v91
	v_pk_fma_f32 v[76:77], v[80:81], v[108:109], v[76:77]
	ds_bpermute_b32 v79, v116, v78
	v_add_f32_e32 v76, v76, v77
	ds_bpermute_b32 v77, v114, v76
	ds_bpermute_b32 v83, v114, v82
	s_waitcnt lgkmcnt(2)
	v_add_f32_e32 v78, v78, v79
	ds_bpermute_b32 v79, v117, v78
	s_waitcnt lgkmcnt(2)
	v_add_f32_e32 v76, v76, v77
	ds_bpermute_b32 v77, v115, v76
	s_waitcnt lgkmcnt(2)
	v_add_f32_e32 v80, v82, v83
	ds_bpermute_b32 v81, v115, v80
	s_waitcnt lgkmcnt(1)
	v_add_f32_e32 v82, v76, v77
	v_add_f32_e32 v76, v78, v79
	v_mov_b32_e32 v78, v73
	v_mov_b32_e32 v73, v75
	v_mov_b32_e32 v79, v74
	v_pk_mul_f32 v[72:73], v[72:73], v[112:113]
	ds_bpermute_b32 v83, v116, v82
	v_pk_fma_f32 v[72:73], v[78:79], v[108:109], v[72:73]
	s_waitcnt lgkmcnt(1)
	v_add_f32_e32 v80, v80, v81
	v_add_f32_e32 v74, v72, v73
	v_mov_b32_e32 v72, v69
	v_mov_b32_e32 v69, v71
	v_mov_b32_e32 v73, v70
	v_pk_mul_f32 v[68:69], v[68:69], v[112:113]
	ds_bpermute_b32 v75, v114, v74
	v_pk_fma_f32 v[68:69], v[72:73], v[108:109], v[68:69]
	s_waitcnt lgkmcnt(1)
	v_add_f32_e32 v82, v82, v83
	v_add_f32_e32 v70, v68, v69
	ds_bpermute_b32 v71, v114, v70
	s_waitcnt lgkmcnt(1)
	v_add_f32_e32 v72, v74, v75
	ds_bpermute_b32 v73, v115, v72
	ds_bpermute_b32 v83, v117, v82
	ds_bpermute_b32 v81, v116, v80
	s_waitcnt lgkmcnt(3)
	v_add_f32_e32 v74, v70, v71
	v_mov_b32_e32 v70, v65
	v_mov_b32_e32 v65, v67
	v_mov_b32_e32 v71, v66
	v_pk_mul_f32 v[64:65], v[64:65], v[112:113]
	s_waitcnt lgkmcnt(2)
	v_add_f32_e32 v66, v72, v73
	v_pk_fma_f32 v[64:65], v[70:71], v[108:109], v[64:65]
	ds_bpermute_b32 v67, v116, v66
	v_add_f32_e32 v64, v64, v65
	ds_bpermute_b32 v65, v114, v64
	ds_bpermute_b32 v75, v115, v74
	s_waitcnt lgkmcnt(4)
	v_add_f32_e32 v68, v82, v83
	s_waitcnt lgkmcnt(2)
	v_add_f32_e32 v66, v66, v67
	ds_bpermute_b32 v67, v117, v66
	s_waitcnt lgkmcnt(2)
	v_add_f32_e32 v64, v64, v65
	ds_bpermute_b32 v65, v115, v64
	s_waitcnt lgkmcnt(2)
	v_add_f32_e32 v70, v74, v75
	ds_bpermute_b32 v71, v116, v70
	s_waitcnt lgkmcnt(2)
	v_add_f32_e32 v66, v66, v67
	v_add_f32_e32 v80, v80, v81
	s_waitcnt lgkmcnt(1)
	v_add_f32_e32 v72, v64, v65
	v_mov_b32_e32 v64, v61
	v_mov_b32_e32 v61, v63
	v_mov_b32_e32 v65, v62
	v_pk_mul_f32 v[60:61], v[60:61], v[112:113]
	ds_bpermute_b32 v81, v117, v80
	v_pk_fma_f32 v[60:61], v[64:65], v[108:109], v[60:61]
	ds_bpermute_b32 v73, v116, v72
	v_add_f32_e32 v60, v60, v61
	ds_bpermute_b32 v61, v114, v60
	s_waitcnt lgkmcnt(3)
	v_add_f32_e32 v70, v70, v71
	ds_bpermute_b32 v71, v117, v70
	v_add_f32_e32 v77, v88, v89
	s_waitcnt lgkmcnt(3)
	v_add_f32_e32 v69, v80, v81
	s_waitcnt lgkmcnt(1)
	v_add_f32_e32 v65, v60, v61
	v_mov_b32_e32 v60, v57
	v_mov_b32_e32 v57, v59
	v_mov_b32_e32 v61, v58
	v_pk_mul_f32 v[56:57], v[56:57], v[112:113]
	ds_bpermute_b32 v67, v115, v65
	v_pk_fma_f32 v[56:57], v[60:61], v[108:109], v[56:57]
	v_add_f32_e32 v62, v72, v73
	v_add_f32_e32 v58, v56, v57
	v_mov_b32_e32 v56, v53
	v_mov_b32_e32 v53, v55
	v_mov_b32_e32 v57, v54
	v_pk_mul_f32 v[52:53], v[52:53], v[112:113]
	ds_bpermute_b32 v59, v114, v58
	v_pk_fma_f32 v[52:53], v[56:57], v[108:109], v[52:53]
	s_waitcnt lgkmcnt(1)
	v_add_f32_e32 v54, v65, v67
	v_add_f32_e32 v52, v52, v53
	ds_bpermute_b32 v53, v114, v52
	s_waitcnt lgkmcnt(1)
	v_add_f32_e32 v56, v58, v59
	ds_bpermute_b32 v55, v116, v54
	ds_bpermute_b32 v57, v115, v56
	ds_bpermute_b32 v63, v117, v62
	s_waitcnt lgkmcnt(3)
	v_add_f32_e32 v52, v52, v53
	ds_bpermute_b32 v53, v115, v52
	s_waitcnt lgkmcnt(3)
	v_add_f32_e32 v54, v54, v55
	s_waitcnt lgkmcnt(2)
	v_add_f32_e32 v56, v56, v57
	ds_bpermute_b32 v55, v117, v54
	ds_bpermute_b32 v57, v116, v56
	s_waitcnt lgkmcnt(2)
	v_add_f32_e32 v52, v52, v53
	ds_bpermute_b32 v53, v116, v52
	v_add_f32_e32 v64, v70, v71
	s_waitcnt lgkmcnt(2)
	v_add_f32_e32 v58, v54, v55
	s_waitcnt lgkmcnt(1)
	v_add_f32_e32 v54, v56, v57
	ds_bpermute_b32 v55, v117, v54
	s_waitcnt lgkmcnt(1)
	v_add_f32_e32 v56, v52, v53
	v_mov_b32_e32 v52, v49
	v_mov_b32_e32 v49, v51
	v_mov_b32_e32 v53, v50
	v_pk_mul_f32 v[48:49], v[48:49], v[112:113]
	s_waitcnt lgkmcnt(0)
	v_add_f32_e32 v61, v54, v55
	v_pk_fma_f32 v[48:49], v[52:53], v[108:109], v[48:49]
	ds_bpermute_b32 v57, v117, v56
	v_add_f32_e32 v50, v48, v49
	v_mov_b32_e32 v48, v45
	v_mov_b32_e32 v45, v47
	v_mov_b32_e32 v49, v46
	v_pk_mul_f32 v[44:45], v[44:45], v[112:113]
	ds_bpermute_b32 v51, v114, v50
	v_pk_fma_f32 v[44:45], v[48:49], v[108:109], v[44:45]
	s_waitcnt lgkmcnt(1)
	v_add_f32_e32 v57, v56, v57
	v_add_f32_e32 v44, v44, v45
	ds_bpermute_b32 v45, v114, v44
	s_waitcnt lgkmcnt(1)
	v_add_f32_e32 v46, v50, v51
	ds_bpermute_b32 v47, v115, v46
	v_add_f32_e32 v62, v62, v63
	s_waitcnt lgkmcnt(1)
	v_add_f32_e32 v48, v44, v45
	v_mov_b32_e32 v44, v41
	v_mov_b32_e32 v41, v43
	v_mov_b32_e32 v45, v42
	v_pk_mul_f32 v[40:41], v[40:41], v[112:113]
	s_waitcnt lgkmcnt(0)
	v_add_f32_e32 v42, v46, v47
	v_pk_fma_f32 v[40:41], v[44:45], v[108:109], v[40:41]
	ds_bpermute_b32 v49, v115, v48
	v_add_f32_e32 v40, v40, v41
	ds_bpermute_b32 v41, v114, v40
	ds_bpermute_b32 v43, v116, v42
	s_waitcnt lgkmcnt(2)
	v_add_f32_e32 v44, v48, v49
	ds_bpermute_b32 v45, v116, v44
	s_waitcnt lgkmcnt(2)
	v_add_f32_e32 v40, v40, v41
	ds_bpermute_b32 v41, v115, v40
	v_lshl_add_u64 v[48:49], v[102:103], 0, v[110:111]
	s_waitcnt lgkmcnt(2)
	v_add_f32_e32 v42, v42, v43
	s_waitcnt lgkmcnt(1)
	v_add_f32_e32 v44, v44, v45
	ds_bpermute_b32 v43, v117, v42
	s_waitcnt lgkmcnt(1)
	v_add_f32_e32 v46, v40, v41
	v_mov_b32_e32 v40, v37
	v_mov_b32_e32 v37, v39
	v_mov_b32_e32 v41, v38
	v_pk_mul_f32 v[36:37], v[36:37], v[112:113]
	ds_bpermute_b32 v45, v117, v44
	v_pk_fma_f32 v[36:37], v[40:41], v[108:109], v[36:37]
	ds_bpermute_b32 v47, v116, v46
	v_add_f32_e32 v36, v36, v37
	ds_bpermute_b32 v37, v114, v36
	s_waitcnt lgkmcnt(3)
	v_add_f32_e32 v60, v42, v43
	s_waitcnt lgkmcnt(2)
	v_add_f32_e32 v56, v44, v45
	s_waitcnt lgkmcnt(1)
	v_add_f32_e32 v38, v46, v47
	global_load_dwordx4 v[78:81], v[48:49], off nt
	global_load_dwordx4 v[86:89], v[48:49], off offset:2048 nt
	s_waitcnt lgkmcnt(0)
	v_add_f32_e32 v40, v36, v37
	v_mov_b32_e32 v36, v33
	v_mov_b32_e32 v33, v35
	v_mov_b32_e32 v37, v34
	v_pk_mul_f32 v[32:33], v[32:33], v[112:113]
	ds_bpermute_b32 v41, v115, v40
	v_pk_fma_f32 v[32:33], v[36:37], v[108:109], v[32:33]
	ds_bpermute_b32 v39, v117, v38
	v_add_f32_e32 v34, v32, v33
	v_mov_b32_e32 v32, v29
	v_mov_b32_e32 v29, v31
	v_mov_b32_e32 v33, v30
	v_pk_mul_f32 v[28:29], v[28:29], v[112:113]
	ds_bpermute_b32 v35, v114, v34
	v_pk_fma_f32 v[28:29], v[32:33], v[108:109], v[28:29]
	s_waitcnt lgkmcnt(2)
	v_add_f32_e32 v30, v40, v41
	v_add_f32_e32 v28, v28, v29
	ds_bpermute_b32 v29, v114, v28
	s_waitcnt lgkmcnt(1)
	v_add_f32_e32 v32, v34, v35
	ds_bpermute_b32 v33, v115, v32
	ds_bpermute_b32 v31, v116, v30
	v_add_f32_e32 v63, v38, v39
	s_waitcnt lgkmcnt(2)
	v_add_f32_e32 v28, v28, v29
	ds_bpermute_b32 v29, v115, v28
	s_waitcnt lgkmcnt(2)
	v_add_f32_e32 v32, v32, v33
	ds_bpermute_b32 v33, v116, v32
	s_waitcnt lgkmcnt(2)
	v_add_f32_e32 v30, v30, v31
	ds_bpermute_b32 v31, v117, v30
	s_waitcnt lgkmcnt(2)
	v_add_f32_e32 v34, v28, v29
	v_mov_b32_e32 v28, v25
	v_mov_b32_e32 v25, v27
	v_mov_b32_e32 v29, v26
	v_pk_mul_f32 v[24:25], v[24:25], v[112:113]
	s_waitcnt lgkmcnt(1)
	v_add_f32_e32 v26, v32, v33
	v_pk_fma_f32 v[24:25], v[28:29], v[108:109], v[24:25]
	ds_bpermute_b32 v27, v117, v26
	v_add_f32_e32 v24, v24, v25
	ds_bpermute_b32 v25, v114, v24
	ds_bpermute_b32 v35, v116, v34
	s_waitcnt lgkmcnt(3)
	v_add_f32_e32 v59, v30, v31
	s_waitcnt lgkmcnt(2)
	v_add_f32_e32 v54, v26, v27
	s_waitcnt lgkmcnt(1)
	v_add_f32_e32 v24, v24, v25
	ds_bpermute_b32 v25, v115, v24
	s_waitcnt lgkmcnt(1)
	v_add_f32_e32 v28, v34, v35
	ds_bpermute_b32 v29, v117, v28
	s_waitcnt lgkmcnt(1)
	v_add_f32_e32 v26, v24, v25
	v_mov_b32_e32 v24, v21
	v_mov_b32_e32 v21, v23
	v_mov_b32_e32 v25, v22
	v_pk_mul_f32 v[20:21], v[20:21], v[112:113]
	ds_bpermute_b32 v27, v116, v26
	v_pk_fma_f32 v[20:21], v[24:25], v[108:109], v[20:21]
	s_waitcnt lgkmcnt(1)
	v_add_f32_e32 v52, v28, v29
	v_add_f32_e32 v22, v20, v21
	v_mov_b32_e32 v20, v17
	v_mov_b32_e32 v17, v19
	v_mov_b32_e32 v21, v18
	v_pk_mul_f32 v[16:17], v[16:17], v[112:113]
	ds_bpermute_b32 v23, v114, v22
	v_pk_fma_f32 v[16:17], v[20:21], v[108:109], v[16:17]
	s_waitcnt lgkmcnt(1)
	v_add_f32_e32 v53, v26, v27
	v_add_f32_e32 v16, v16, v17
	ds_bpermute_b32 v17, v114, v16
	s_waitcnt lgkmcnt(1)
	v_add_f32_e32 v18, v22, v23
	ds_bpermute_b32 v19, v115, v18
	ds_bpermute_b32 v55, v117, v53
	s_waitcnt lgkmcnt(2)
	v_add_f32_e32 v20, v16, v17
	v_mov_b32_e32 v16, v13
	v_mov_b32_e32 v13, v15
	v_mov_b32_e32 v17, v14
	v_pk_mul_f32 v[12:13], v[12:13], v[112:113]
	ds_bpermute_b32 v21, v115, v20
	v_pk_fma_f32 v[12:13], v[16:17], v[108:109], v[12:13]
	s_waitcnt lgkmcnt(2)
	v_add_f32_e32 v14, v18, v19
	v_add_f32_e32 v12, v12, v13
	ds_bpermute_b32 v13, v114, v12
	ds_bpermute_b32 v15, v116, v14
	s_waitcnt lgkmcnt(2)
	v_add_f32_e32 v16, v20, v21
	ds_bpermute_b32 v17, v116, v16
	v_add_f32_e32 v73, v53, v55
	s_waitcnt lgkmcnt(2)
	v_add_f32_e32 v12, v12, v13
	ds_bpermute_b32 v13, v115, v12
	s_waitcnt lgkmcnt(2)
	v_add_f32_e32 v65, v14, v15
	s_waitcnt lgkmcnt(1)
	v_add_f32_e32 v74, v16, v17
	ds_bpermute_b32 v75, v117, v74
	ds_bpermute_b32 v67, v117, v65
	s_waitcnt lgkmcnt(2)
	v_add_f32_e32 v82, v12, v13
	v_add_co_u32_e32 v12, vcc, s17, v48
	ds_bpermute_b32 v83, v116, v82
	s_nop 0
	v_addc_co_u32_e32 v13, vcc, 0, v49, vcc
	v_add_co_u32_e32 v14, vcc, s91, v48
	s_waitcnt lgkmcnt(0)
	v_add_f32_e32 v53, v82, v83
	v_addc_co_u32_e32 v15, vcc, 0, v49, vcc
	v_add_co_u32_e32 v16, vcc, s50, v48
	global_load_dwordx4 v[94:97], v[14:15], off offset:-4096 nt
	global_load_dwordx4 v[132:135], v[14:15], off nt
	v_addc_co_u32_e32 v17, vcc, 0, v49, vcc
	v_add_co_u32_e32 v18, vcc, s90, v48
	ds_bpermute_b32 v55, v117, v53
	s_nop 0
	v_addc_co_u32_e32 v19, vcc, 0, v49, vcc
	global_load_dwordx4 v[136:139], v[14:15], off offset:2048 nt
	global_load_dwordx4 v[140:143], v[18:19], off offset:-4096 nt
	global_load_dwordx4 v[144:147], v[12:13], off offset:2048 nt
	global_load_dwordx4 v[44:47], v[16:17], off offset:2048 nt
	global_load_dwordx4 v[40:43], v[18:19], off nt
	global_load_dwordx4 v[32:35], v[18:19], off offset:2048 nt
	v_add_co_u32_e32 v12, vcc, s96, v48
	v_add_f32_e32 v72, v65, v67
	s_nop 0
	v_addc_co_u32_e32 v13, vcc, 0, v49, vcc
	v_add_co_u32_e32 v14, vcc, s21, v48
	s_nop 1
	v_addc_co_u32_e32 v15, vcc, 0, v49, vcc
	v_add_co_u32_e32 v70, vcc, s51, v48
	global_load_dwordx4 v[36:39], v[14:15], off offset:-4096 nt
	global_load_dwordx4 v[24:27], v[14:15], off nt
	v_addc_co_u32_e32 v71, vcc, 0, v49, vcc
	v_add_co_u32_e32 v50, vcc, s92, v48
	s_nop 1
	v_addc_co_u32_e32 v51, vcc, 0, v49, vcc
	global_load_dwordx4 v[20:23], v[14:15], off offset:2048 nt
	global_load_dwordx4 v[16:19], v[50:51], off offset:-4096 nt
	global_load_dwordx4 v[28:31], v[12:13], off offset:2048 nt
	s_nop 0
	global_load_dwordx4 v[12:15], v[70:71], off offset:2048 nt
	v_add_f32_e32 v70, v74, v75
	v_mov_b32_e32 v74, v9
	v_mov_b32_e32 v9, v11
	v_mov_b32_e32 v75, v10
	v_pk_mul_f32 v[8:9], v[8:9], v[112:113]
	s_waitcnt lgkmcnt(0)
	v_add_f32_e32 v71, v53, v55
	v_pk_fma_f32 v[8:9], v[74:75], v[108:109], v[8:9]
	s_nop 0
	v_add_f32_e32 v10, v8, v9
	s_waitcnt vmcnt(16)
	v_mov_b32_e32 v8, v5
	v_mov_b32_e32 v9, v6
	v_mov_b32_e32 v5, v7
	v_mul_f32_e32 v6, v108, v123
	v_mul_f32_e32 v7, v113, v124
	v_pk_mul_f32 v[4:5], v[4:5], v[112:113]
	v_fmac_f32_e32 v6, v112, v121
	v_fmac_f32_e32 v7, v109, v122
	v_pk_fma_f32 v[4:5], v[8:9], v[108:109], v[4:5]
	v_add_f32_e32 v6, v6, v7
	v_add_f32_e32 v4, v4, v5
	ds_bpermute_b32 v7, v114, v6
	ds_bpermute_b32 v5, v114, v4
	ds_bpermute_b32 v11, v114, v10
	s_waitcnt lgkmcnt(2)
	v_add_f32_e32 v6, v6, v7
	s_waitcnt lgkmcnt(1)
	v_add_f32_e32 v4, v4, v5
	ds_bpermute_b32 v7, v115, v6
	ds_bpermute_b32 v5, v115, v4
	s_waitcnt lgkmcnt(2)
	v_add_f32_e32 v8, v10, v11
	ds_bpermute_b32 v9, v115, v8
	s_waitcnt lgkmcnt(2)
	v_add_f32_e32 v6, v6, v7
	s_waitcnt lgkmcnt(1)
	v_add_f32_e32 v4, v4, v5
	ds_bpermute_b32 v7, v116, v6
	ds_bpermute_b32 v5, v116, v4
	s_waitcnt lgkmcnt(2)
	v_add_f32_e32 v8, v8, v9
	ds_bpermute_b32 v9, v116, v8
	s_waitcnt lgkmcnt(2)
	v_add_f32_e32 v6, v6, v7
	s_waitcnt lgkmcnt(1)
	v_add_f32_e32 v4, v4, v5
	ds_bpermute_b32 v7, v117, v6
	ds_bpermute_b32 v5, v117, v4
	s_waitcnt lgkmcnt(2)
	v_add_f32_e32 v8, v8, v9
	ds_bpermute_b32 v9, v117, v8
	s_waitcnt lgkmcnt(2)
	v_add_f32_e32 v53, v6, v7
	s_waitcnt lgkmcnt(1)
	v_add_f32_e32 v65, v4, v5
	v_cndmask_b32_e64 v4, v130, v237, s[38:39]
	v_max_f32_e32 v5, v53, v120
	v_max3_f32 v5, v5, v4, v126
	v_max3_f32 v5, v5, v128, v125
	v_max3_f32 v5, v5, v129, v127
	v_max3_f32 v5, v5, v93, v92
	v_max3_f32 v5, v5, v85, v84
	v_max3_f32 v5, v5, v77, v76
	v_max3_f32 v5, v5, v69, v68
	v_max3_f32 v5, v5, v66, v64
	v_max3_f32 v5, v5, v62, v58
	v_max3_f32 v5, v5, v61, v57
	v_max3_f32 v5, v5, v60, v56
	v_max3_f32 v5, v5, v63, v59
	v_max3_f32 v5, v5, v54, v52
	v_max3_f32 v5, v5, v73, v72
	s_waitcnt lgkmcnt(0)
	v_add_f32_e32 v67, v8, v9
	v_max3_f32 v5, v5, v70, v71
	v_max3_f32 v5, v5, v67, v65
	ds_bpermute_b32 v6, v118, v5
	s_waitcnt lgkmcnt(0)
	v_max_f32_e32 v6, v6, v6
	v_max_f32_e32 v5, v5, v6
	ds_bpermute_b32 v6, v119, v5
	s_waitcnt lgkmcnt(0)
	v_max_f32_e32 v6, v6, v6
	v_max_f32_e32 v55, v5, v6
	v_sub_f32_e32 v4, v4, v55
	v_exp_f32_e32 v4, v4
	v_sub_f32_e32 v8, v126, v55
	v_exp_f32_e32 v8, v8
	v_add_f32_e32 v9, 0, v4
	s_waitcnt vmcnt(15)
	v_pk_fma_f32 v[6:7], v[78:79], v[4:5], 0 op_sel_hi:[1,0,0]
	v_pk_fma_f32 v[4:5], v[80:81], v[4:5], 0 op_sel_hi:[1,0,0]
	v_add_f32_e32 v9, v8, v9
	s_waitcnt vmcnt(14)
	v_pk_fma_f32 v[4:5], v[88:89], v[8:9], v[4:5] op_sel_hi:[1,0,1]
	v_pk_fma_f32 v[6:7], v[86:87], v[8:9], v[6:7] op_sel_hi:[1,0,1]
	v_sub_f32_e32 v8, v128, v55
	v_exp_f32_e32 v8, v8
	s_nop 0
	v_add_f32_e32 v9, v8, v9
	s_waitcnt vmcnt(13)
	v_pk_fma_f32 v[6:7], v[94:95], v[8:9], v[6:7] op_sel_hi:[1,0,1]
	v_pk_fma_f32 v[4:5], v[96:97], v[8:9], v[4:5] op_sel_hi:[1,0,1]
	v_sub_f32_e32 v8, v125, v55
	v_exp_f32_e32 v8, v8
	s_nop 0
	v_add_f32_e32 v9, v8, v9
	s_waitcnt vmcnt(9)
	v_pk_fma_f32 v[4:5], v[146:147], v[8:9], v[4:5] op_sel_hi:[1,0,1]
	v_pk_fma_f32 v[6:7], v[144:145], v[8:9], v[6:7] op_sel_hi:[1,0,1]
	v_sub_f32_e32 v8, v129, v55
	v_exp_f32_e32 v8, v8
	s_nop 0
	v_add_f32_e32 v9, v8, v9
	v_pk_fma_f32 v[6:7], v[132:133], v[8:9], v[6:7] op_sel_hi:[1,0,1]
	v_pk_fma_f32 v[4:5], v[134:135], v[8:9], v[4:5] op_sel_hi:[1,0,1]
	v_sub_f32_e32 v8, v127, v55
	v_exp_f32_e32 v8, v8
	s_nop 0
	v_add_f32_e32 v9, v8, v9
	v_pk_fma_f32 v[4:5], v[138:139], v[8:9], v[4:5] op_sel_hi:[1,0,1]
	v_pk_fma_f32 v[6:7], v[136:137], v[8:9], v[6:7] op_sel_hi:[1,0,1]
	v_sub_f32_e32 v8, v93, v55
	v_exp_f32_e32 v8, v8
	s_nop 0
	v_add_f32_e32 v9, v8, v9
	v_pk_fma_f32 v[6:7], v[140:141], v[8:9], v[6:7] op_sel_hi:[1,0,1]
	v_pk_fma_f32 v[4:5], v[142:143], v[8:9], v[4:5] op_sel_hi:[1,0,1]
	v_sub_f32_e32 v8, v92, v55
	v_exp_f32_e32 v8, v8
	s_nop 0
	v_add_f32_e32 v9, v8, v9
	s_waitcnt vmcnt(8)
	v_pk_fma_f32 v[4:5], v[46:47], v[8:9], v[4:5] op_sel_hi:[1,0,1]
	v_pk_fma_f32 v[6:7], v[44:45], v[8:9], v[6:7] op_sel_hi:[1,0,1]
	v_sub_f32_e32 v8, v85, v55
	v_exp_f32_e32 v8, v8
	s_nop 0
	v_add_f32_e32 v9, v8, v9
	s_waitcnt vmcnt(7)
	v_pk_fma_f32 v[6:7], v[40:41], v[8:9], v[6:7] op_sel_hi:[1,0,1]
	v_pk_fma_f32 v[4:5], v[42:43], v[8:9], v[4:5] op_sel_hi:[1,0,1]
	v_sub_f32_e32 v8, v84, v55
	v_exp_f32_e32 v8, v8
	s_nop 0
	v_add_f32_e32 v9, v8, v9
	s_waitcnt vmcnt(6)
	v_pk_fma_f32 v[4:5], v[34:35], v[8:9], v[4:5] op_sel_hi:[1,0,1]
	v_pk_fma_f32 v[6:7], v[32:33], v[8:9], v[6:7] op_sel_hi:[1,0,1]
	v_sub_f32_e32 v8, v77, v55
	v_exp_f32_e32 v8, v8
	s_nop 0
	v_add_f32_e32 v9, v8, v9
	s_waitcnt vmcnt(5)
	v_pk_fma_f32 v[6:7], v[36:37], v[8:9], v[6:7] op_sel_hi:[1,0,1]
	v_pk_fma_f32 v[4:5], v[38:39], v[8:9], v[4:5] op_sel_hi:[1,0,1]
	v_sub_f32_e32 v8, v76, v55
	v_exp_f32_e32 v8, v8
	s_nop 0
	v_add_f32_e32 v9, v8, v9
	s_waitcnt vmcnt(1)
	v_pk_fma_f32 v[4:5], v[30:31], v[8:9], v[4:5] op_sel_hi:[1,0,1]
	v_pk_fma_f32 v[6:7], v[28:29], v[8:9], v[6:7] op_sel_hi:[1,0,1]
	v_sub_f32_e32 v8, v69, v55
	v_exp_f32_e32 v8, v8
	s_nop 0
	v_add_f32_e32 v9, v8, v9
	v_pk_fma_f32 v[6:7], v[24:25], v[8:9], v[6:7] op_sel_hi:[1,0,1]
	v_pk_fma_f32 v[4:5], v[26:27], v[8:9], v[4:5] op_sel_hi:[1,0,1]
	v_sub_f32_e32 v8, v68, v55
	v_exp_f32_e32 v8, v8
	s_nop 0
	v_add_f32_e32 v9, v8, v9
	v_pk_fma_f32 v[4:5], v[22:23], v[8:9], v[4:5] op_sel_hi:[1,0,1]
	v_pk_fma_f32 v[6:7], v[20:21], v[8:9], v[6:7] op_sel_hi:[1,0,1]
	v_sub_f32_e32 v8, v66, v55
	v_exp_f32_e32 v8, v8
	s_nop 0
	v_add_f32_e32 v9, v8, v9
	v_pk_fma_f32 v[6:7], v[16:17], v[8:9], v[6:7] op_sel_hi:[1,0,1]
	v_pk_fma_f32 v[4:5], v[18:19], v[8:9], v[4:5] op_sel_hi:[1,0,1]
	v_sub_f32_e32 v8, v64, v55
	v_exp_f32_e32 v8, v8
	s_nop 0
	v_add_f32_e32 v64, v8, v9
	s_waitcnt vmcnt(0)
	v_pk_fma_f32 v[68:69], v[14:15], v[8:9], v[4:5] op_sel_hi:[1,0,1]
	v_pk_fma_f32 v[90:91], v[12:13], v[8:9], v[6:7] op_sel_hi:[1,0,1]
	v_add_co_u32_e32 v4, vcc, s56, v48
	s_nop 1
	v_addc_co_u32_e32 v5, vcc, 0, v49, vcc
	v_add_co_u32_e32 v6, vcc, s93, v48
	s_nop 1
	v_addc_co_u32_e32 v7, vcc, 0, v49, vcc
	global_load_dwordx4 v[28:31], v[50:51], off offset:2048 nt
	global_load_dwordx4 v[32:35], v[6:7], off offset:-4096 nt
	global_load_dwordx4 v[36:39], v[6:7], off nt
	global_load_dwordx4 v[40:43], v[6:7], off offset:2048 nt
	v_add_co_u32_e32 v6, vcc, s57, v48
	s_nop 1
	v_addc_co_u32_e32 v7, vcc, 0, v49, vcc
	v_add_co_u32_e32 v8, vcc, s6, v48
	s_nop 1
	v_addc_co_u32_e32 v9, vcc, 0, v49, vcc
	global_load_dwordx4 v[44:47], v[4:5], off offset:2048 nt
	global_load_dwordx4 v[74:77], v[6:7], off offset:2048 nt
	global_load_dwordx4 v[78:81], v[8:9], off offset:-4096 nt
	global_load_dwordx4 v[82:85], v[8:9], off nt
	v_add_co_u32_e32 v4, vcc, s58, v48
	s_nop 1
	v_addc_co_u32_e32 v5, vcc, 0, v49, vcc
	v_add_co_u32_e32 v6, vcc, s95, v48
	s_nop 1
	v_addc_co_u32_e32 v7, vcc, 0, v49, vcc
	global_load_dwordx4 v[86:89], v[8:9], off offset:2048 nt
	global_load_dwordx4 v[24:27], v[6:7], off offset:-4096 nt
	global_load_dwordx4 v[16:19], v[6:7], off nt
	global_load_dwordx4 v[12:15], v[6:7], off offset:2048 nt
	v_add_co_u32_e32 v6, vcc, s52, v48
	s_nop 1
	v_addc_co_u32_e32 v7, vcc, 0, v49, vcc
	global_load_dwordx4 v[20:23], v[4:5], off offset:2048 nt
	global_load_dwordx4 v[8:11], v[6:7], off nt
	s_nop 0
	global_load_dwordx4 v[48:51], v[50:51], off nt
	s_nop 0
	global_load_dwordx4 v[4:7], v[6:7], off offset:2048 nt
	v_sub_f32_e32 v62, v62, v55
	v_exp_f32_e32 v62, v62
	v_sub_f32_e32 v58, v58, v55
	v_exp_f32_e32 v58, v58
	s_waitcnt vmcnt(1)
	v_pk_fma_f32 v[48:49], v[48:49], v[62:63], v[90:91] op_sel_hi:[1,0,1]
	v_add_f32_e32 v64, v62, v64
	v_pk_fma_f32 v[28:29], v[28:29], v[58:59], v[48:49] op_sel_hi:[1,0,1]
	v_sub_f32_e32 v48, v61, v55
	v_exp_f32_e32 v48, v48
	v_pk_fma_f32 v[50:51], v[50:51], v[62:63], v[68:69] op_sel_hi:[1,0,1]
	v_add_f32_e32 v62, v58, v64
	v_pk_fma_f32 v[30:31], v[30:31], v[58:59], v[50:51] op_sel_hi:[1,0,1]
	v_add_f32_e32 v49, v48, v62
	v_pk_fma_f32 v[28:29], v[32:33], v[48:49], v[28:29] op_sel_hi:[1,0,1]
	v_sub_f32_e32 v32, v57, v55
	v_exp_f32_e32 v32, v32
	v_pk_fma_f32 v[30:31], v[34:35], v[48:49], v[30:31] op_sel_hi:[1,0,1]
	v_add_f32_e32 v33, v32, v49
	v_pk_fma_f32 v[30:31], v[46:47], v[32:33], v[30:31] op_sel_hi:[1,0,1]
	v_pk_fma_f32 v[28:29], v[44:45], v[32:33], v[28:29] op_sel_hi:[1,0,1]
	v_sub_f32_e32 v32, v60, v55
	v_exp_f32_e32 v32, v32
	s_nop 0
	v_add_f32_e32 v33, v32, v33
	v_pk_fma_f32 v[28:29], v[36:37], v[32:33], v[28:29] op_sel_hi:[1,0,1]
	v_pk_fma_f32 v[30:31], v[38:39], v[32:33], v[30:31] op_sel_hi:[1,0,1]
	v_sub_f32_e32 v32, v56, v55
	v_exp_f32_e32 v32, v32
	s_nop 0
	v_add_f32_e32 v33, v32, v33
	v_pk_fma_f32 v[30:31], v[42:43], v[32:33], v[30:31] op_sel_hi:[1,0,1]
	v_pk_fma_f32 v[28:29], v[40:41], v[32:33], v[28:29] op_sel_hi:[1,0,1]
	v_sub_f32_e32 v32, v63, v55
	v_exp_f32_e32 v32, v32
	s_nop 0
	v_add_f32_e32 v33, v32, v33
	v_pk_fma_f32 v[28:29], v[78:79], v[32:33], v[28:29] op_sel_hi:[1,0,1]
	v_pk_fma_f32 v[30:31], v[80:81], v[32:33], v[30:31] op_sel_hi:[1,0,1]
	v_sub_f32_e32 v32, v59, v55
	v_exp_f32_e32 v32, v32
	s_nop 0
	v_add_f32_e32 v33, v32, v33
	v_pk_fma_f32 v[30:31], v[76:77], v[32:33], v[30:31] op_sel_hi:[1,0,1]
	v_pk_fma_f32 v[28:29], v[74:75], v[32:33], v[28:29] op_sel_hi:[1,0,1]
	v_sub_f32_e32 v32, v54, v55
	v_exp_f32_e32 v32, v32
	s_nop 0
	v_add_f32_e32 v33, v32, v33
	v_pk_fma_f32 v[28:29], v[82:83], v[32:33], v[28:29] op_sel_hi:[1,0,1]
	v_pk_fma_f32 v[30:31], v[84:85], v[32:33], v[30:31] op_sel_hi:[1,0,1]
	v_sub_f32_e32 v32, v52, v55
	v_exp_f32_e32 v32, v32
	s_nop 0
	v_add_f32_e32 v33, v32, v33
	v_pk_fma_f32 v[30:31], v[88:89], v[32:33], v[30:31] op_sel_hi:[1,0,1]
	v_pk_fma_f32 v[28:29], v[86:87], v[32:33], v[28:29] op_sel_hi:[1,0,1]
	v_sub_f32_e32 v32, v73, v55
	v_exp_f32_e32 v32, v32
	s_nop 0
	v_add_f32_e32 v33, v32, v33
	v_pk_fma_f32 v[24:25], v[24:25], v[32:33], v[28:29] op_sel_hi:[1,0,1]
	v_sub_f32_e32 v28, v72, v55
	v_exp_f32_e32 v28, v28
	v_pk_fma_f32 v[26:27], v[26:27], v[32:33], v[30:31] op_sel_hi:[1,0,1]
	v_add_f32_e32 v29, v28, v33
	v_pk_fma_f32 v[20:21], v[20:21], v[28:29], v[24:25] op_sel_hi:[1,0,1]
	v_sub_f32_e32 v24, v70, v55
	v_exp_f32_e32 v24, v24
	v_pk_fma_f32 v[22:23], v[22:23], v[28:29], v[26:27] op_sel_hi:[1,0,1]
	v_add_f32_e32 v25, v24, v29
	v_pk_fma_f32 v[16:17], v[16:17], v[24:25], v[20:21] op_sel_hi:[1,0,1]
	v_sub_f32_e32 v20, v71, v55
	v_exp_f32_e32 v20, v20
	v_pk_fma_f32 v[18:19], v[18:19], v[24:25], v[22:23] op_sel_hi:[1,0,1]
	v_add_f32_e32 v21, v20, v25
	v_pk_fma_f32 v[12:13], v[12:13], v[20:21], v[16:17] op_sel_hi:[1,0,1]
	v_sub_f32_e32 v16, v67, v55
	v_exp_f32_e32 v16, v16
	v_pk_fma_f32 v[14:15], v[14:15], v[20:21], v[18:19] op_sel_hi:[1,0,1]
	v_add_f32_e32 v17, v16, v21
	v_pk_fma_f32 v[8:9], v[8:9], v[16:17], v[12:13] op_sel_hi:[1,0,1]
	v_sub_f32_e32 v12, v65, v55
	v_exp_f32_e32 v12, v12
	v_pk_fma_f32 v[10:11], v[10:11], v[16:17], v[14:15] op_sel_hi:[1,0,1]
	v_add_f32_e32 v13, v12, v17
	s_waitcnt vmcnt(0)
	v_pk_fma_f32 v[10:11], v[6:7], v[12:13], v[10:11] op_sel_hi:[1,0,1]
	v_pk_fma_f32 v[4:5], v[4:5], v[12:13], v[8:9] op_sel_hi:[1,0,1]
	ds_bpermute_b32 v12, v118, v13
	ds_bpermute_b32 v6, v118, v4
	ds_bpermute_b32 v7, v118, v5
	ds_bpermute_b32 v8, v118, v10
	ds_bpermute_b32 v9, v118, v11
	s_waitcnt lgkmcnt(4)
	v_add_f32_e32 v12, v13, v12
	ds_bpermute_b32 v13, v119, v12
	s_waitcnt lgkmcnt(3)
	v_pk_add_f32 v[4:5], v[4:5], v[6:7]
	ds_bpermute_b32 v6, v119, v4
	s_waitcnt lgkmcnt(2)
	v_pk_add_f32 v[8:9], v[10:11], v[8:9]
	ds_bpermute_b32 v7, v119, v5
	ds_bpermute_b32 v10, v119, v8
	ds_bpermute_b32 v11, v119, v9
	s_and_saveexec_b64 s[30:31], s[38:39]
	s_cbranch_execz .LBB0_531
	global_load_dwordx2 v[14:15], v2, s[22:23] offset:2048
	s_waitcnt lgkmcnt(2)
	v_pk_add_f32 v[4:5], v[4:5], v[6:7]
	s_waitcnt lgkmcnt(0)
	v_pk_add_f32 v[6:7], v[8:9], v[10:11]
	v_sub_f32_e32 v8, v53, v55
	v_sub_f32_e32 v9, v120, v55
	v_exp_f32_e32 v8, v8
	v_exp_f32_e32 v9, v9
	v_add_f32_e32 v12, v12, v13
	s_lshl_b32 s21, s41, 6
	v_lshlrev_b32_e32 v18, 16, v107
	v_and_b32_e32 v19, 0xffff0000, v107
	s_mul_hi_i32 s22, s20, 0xc00
	s_mulk_i32 s20, 0xc00
	v_add_f32_e32 v10, v8, v12
	s_add_u32 s20, s34, s20
	v_pk_fma_f32 v[6:7], v[8:9], v[18:19], v[6:7] op_sel_hi:[0,1,1]
	v_add_f32_e32 v9, v9, v10
	s_addc_u32 s24, s35, s22
	v_div_scale_f32 v10, s[22:23], v9, v9, 1.0
	v_rcp_f32_e32 v11, v10
	v_lshlrev_b32_e32 v16, 16, v106
	v_and_b32_e32 v17, 0xffff0000, v106
	v_pk_fma_f32 v[4:5], v[8:9], v[16:17], v[4:5] op_sel_hi:[0,1,1]
	v_fma_f32 v12, -v10, v11, 1.0
	v_div_scale_f32 v8, vcc, 1.0, v9, 1.0
	v_fmac_f32_e32 v11, v12, v11
	v_mul_f32_e32 v12, v8, v11
	v_fma_f32 v13, -v10, v12, v8
	v_fmac_f32_e32 v12, v13, v11
	v_fma_f32 v8, -v10, v12, v8
	v_div_fmas_f32 v8, v8, v11, v12
	v_div_fixup_f32 v8, v8, v9, 1.0
	s_lshl_b32 s21, s21, 1
	v_mul_f32_e32 v4, v8, v4
	v_mul_f32_e32 v5, v8, v5
	v_mul_f32_e32 v6, v8, v6
	v_mul_f32_e32 v7, v8, v7
	s_add_u32 s20, s20, s21
	s_addc_u32 s21, s24, 0
	s_waitcnt vmcnt(0)
	v_lshlrev_b32_e32 v8, 16, v14
	v_and_b32_e32 v9, 0xffff0000, v14
	v_lshlrev_b32_e32 v10, 16, v15
	v_and_b32_e32 v11, 0xffff0000, v15
	v_mul_f32_e32 v4, v4, v8
	v_mul_f32_e32 v5, v5, v9
	v_mul_f32_e32 v6, v6, v10
	v_mul_f32_e32 v7, v7, v11
	v_cvt_pk_bf16_f32 v4, v4, v5
	v_cvt_pk_bf16_f32 v5, v6, v7
	global_store_dwordx2 v2, v[4:5], s[20:21] sc1
	s_branch .LBB0_531

.LBB0_547:
	s_ashr_i32 s38, s40, 7
	s_lshl_b32 s24, s38, 8
	s_add_i32 s42, s24, s30
	s_ashr_i32 s43, s42, 31
	s_lshl_b64 s[42:43], s[42:43], 10
	s_add_u32 s39, s22, s42
	s_addc_u32 s41, s23, s43
	s_and_b32 s24, s14, 0x180
	s_lshl_b32 s24, s24, 1
	s_add_u32 s44, s39, s24
	s_addc_u32 s45, s41, 0
	v_mov_b32_e32 v211, v208
	s_add_u32 s39, s31, s42
	s_addc_u32 s41, s21, s43
	s_waitcnt vmcnt(0)
	v_ashrrev_i32_e32 v62, 5, v211
	v_and_b32_e32 v69, -8, v62
	s_add_u32 s42, s39, s24
	v_and_b32_e32 v68, 0xff, v211
	v_lshlrev_b32_e32 v4, 3, v69
	s_addc_u32 s43, s41, 0
	v_lshlrev_b32_e32 v2, 10, v68
	v_ashrrev_i32_e32 v5, 31, v4
	v_or_b32_e32 v70, 1, v69
	v_lshl_add_u64 v[60:61], s[44:45], 0, v[2:3]
	v_lshl_add_u64 v[64:65], s[42:43], 0, v[2:3]
	v_lshlrev_b64 v[8:9], 1, v[4:5]
	v_lshlrev_b32_e32 v16, 3, v70
	v_or_b32_e32 v71, 2, v69
	v_or_b32_e32 v73, 4, v69
	v_lshl_add_u64 v[28:29], v[60:61], 0, v[8:9]
	v_lshl_add_u64 v[8:9], v[64:65], 0, v[8:9]
	v_ashrrev_i32_e32 v17, 31, v16
	v_lshlrev_b32_e32 v24, 3, v71
	v_or_b32_e32 v72, 3, v69
	v_lshlrev_b32_e32 v36, 3, v73
	global_load_dwordx4 v[4:7], v[28:29], off
	s_nop 0
	global_load_dwordx4 v[8:11], v[8:9], off
	s_nop 0
	global_load_dwordx4 v[12:15], v[28:29], off offset:16
	v_lshl_add_u64 v[16:17], v[16:17], 1, v[64:65]
	v_ashrrev_i32_e32 v25, 31, v24
	v_lshlrev_b32_e32 v32, 3, v72
	v_ashrrev_i32_e32 v37, 31, v36
	global_load_dwordx4 v[16:19], v[16:17], off
	s_nop 0
	global_load_dwordx4 v[20:23], v[28:29], off offset:32
	v_lshl_add_u64 v[24:25], v[24:25], 1, v[64:65]
	v_ashrrev_i32_e32 v33, 31, v32
	v_lshlrev_b64 v[40:41], 1, v[36:37]
	v_or_b32_e32 v74, 5, v69
	v_or_b32_e32 v75, 6, v69
	v_or_b32_e32 v76, 7, v62
	global_load_dwordx4 v[24:27], v[24:25], off
	s_nop 0
	global_load_dwordx4 v[28:31], v[28:29], off offset:48
	v_lshl_add_u64 v[32:33], v[32:33], 1, v[64:65]
	v_lshl_add_u64 v[52:53], v[60:61], 0, v[40:41]
	v_lshlrev_b32_e32 v48, 3, v74
	v_lshlrev_b32_e32 v56, 3, v75
	v_lshlrev_b32_e32 v62, 3, v76
	global_load_dwordx4 v[32:35], v[32:33], off
	v_lshl_add_u64 v[40:41], v[64:65], 0, v[40:41]
	global_load_dwordx4 v[36:39], v[52:53], off
	v_ashrrev_i32_e32 v49, 31, v48
	v_ashrrev_i32_e32 v57, 31, v56
	v_ashrrev_i32_e32 v63, 31, v62
	global_load_dwordx4 v[40:43], v[40:41], off
	v_lshl_add_u64 v[48:49], v[48:49], 1, v[64:65]
	global_load_dwordx4 v[44:47], v[52:53], off offset:16
	v_lshl_add_u64 v[56:57], v[56:57], 1, v[64:65]
	v_lshlrev_b64 v[66:67], 1, v[62:63]
	global_load_dwordx4 v[48:51], v[48:49], off
	v_lshl_add_u64 v[60:61], v[60:61], 0, v[66:67]
	global_load_dwordx4 v[56:59], v[56:57], off
	v_lshl_add_u64 v[64:65], v[64:65], 0, v[66:67]
	global_load_dwordx4 v[52:55], v[52:53], off offset:32
	v_mad_u32_u24 v77, v68, s53, 0
	global_load_dwordx4 v[60:63], v[60:61], off
	v_lshl_add_u32 v2, v68, 1, s11
	global_load_dwordx4 v[64:67], v[64:65], off
	v_lshl_add_u32 v78, v69, 4, v77
	v_mad_u64_u32 v[68:69], s[42:43], v69, s77, v[2:3]
	v_lshl_add_u32 v69, v70, 4, v77
	s_ashr_i32 s39, s38, 31
	s_lshl_b64 s[38:39], s[38:39], 13
	s_and_b32 s41, s1, 0x1f00
	s_add_u32 s41, s41, s3
	v_and_b32_e32 v213, 31, v211
	v_bfe_u32 v201, v211, 4, 2
	s_waitcnt vmcnt(15)
	ds_write_b128 v78, v[4:7]
	s_waitcnt vmcnt(14)
	ds_write_b16 v68, v8
	ds_write_b16_d16_hi v68, v8 offset:520
	ds_write_b16 v68, v9 offset:1040
	ds_write_b16_d16_hi v68, v9 offset:1560
	ds_write_b16 v68, v10 offset:2080
	ds_write_b16_d16_hi v68, v10 offset:2600
	ds_write_b16 v68, v11 offset:3120
	ds_write_b16_d16_hi v68, v11 offset:3640
	s_waitcnt vmcnt(13)
	ds_write_b128 v69, v[12:15]
	s_waitcnt vmcnt(12)
	ds_write_b16 v68, v16 offset:4160
	ds_write_b16_d16_hi v68, v16 offset:4680
	ds_write_b16 v68, v17 offset:5200
	ds_write_b16_d16_hi v68, v17 offset:5720
	ds_write_b16 v68, v18 offset:6240
	ds_write_b16_d16_hi v68, v18 offset:6760
	ds_write_b16 v68, v19 offset:7280
	ds_write_b16_d16_hi v68, v19 offset:7800
	v_lshl_add_u32 v4, v71, 4, v77
	s_waitcnt vmcnt(11)
	ds_write_b128 v4, v[20:23]
	s_waitcnt vmcnt(10)
	ds_write_b16 v68, v24 offset:8320
	ds_write_b16_d16_hi v68, v24 offset:8840
	ds_write_b16 v68, v25 offset:9360
	ds_write_b16_d16_hi v68, v25 offset:9880
	ds_write_b16 v68, v26 offset:10400
	ds_write_b16_d16_hi v68, v26 offset:10920
	ds_write_b16 v68, v27 offset:11440
	ds_write_b16_d16_hi v68, v27 offset:11960
	v_lshl_add_u32 v4, v72, 4, v77
	s_waitcnt vmcnt(9)
	ds_write_b128 v4, v[28:31]
	s_waitcnt vmcnt(8)
	ds_write_b16 v68, v32 offset:12480
	ds_write_b16_d16_hi v68, v32 offset:13000
	ds_write_b16 v68, v33 offset:13520
	ds_write_b16_d16_hi v68, v33 offset:14040
	ds_write_b16 v68, v34 offset:14560
	ds_write_b16_d16_hi v68, v34 offset:15080
	ds_write_b16 v68, v35 offset:15600
	ds_write_b16_d16_hi v68, v35 offset:16120
	v_lshl_add_u32 v4, v73, 4, v77
	s_waitcnt vmcnt(7)
	ds_write_b128 v4, v[36:39]
	s_waitcnt vmcnt(6)
	ds_write_b16 v68, v40 offset:16640
	ds_write_b16_d16_hi v68, v40 offset:17160
	ds_write_b16 v68, v41 offset:17680
	ds_write_b16_d16_hi v68, v41 offset:18200
	ds_write_b16 v68, v42 offset:18720
	ds_write_b16_d16_hi v68, v42 offset:19240
	ds_write_b16 v68, v43 offset:19760
	ds_write_b16_d16_hi v68, v43 offset:20280
	v_lshl_add_u32 v4, v74, 4, v77
	s_waitcnt vmcnt(5)
	ds_write_b128 v4, v[44:47]
	s_waitcnt vmcnt(4)
	ds_write_b16 v68, v48 offset:20800
	ds_write_b16_d16_hi v68, v48 offset:21320
	ds_write_b16 v68, v49 offset:21840
	ds_write_b16_d16_hi v68, v49 offset:22360
	ds_write_b16 v68, v50 offset:22880
	ds_write_b16_d16_hi v68, v50 offset:23400
	ds_write_b16 v68, v51 offset:23920
	ds_write_b16_d16_hi v68, v51 offset:24440
	v_lshl_add_u32 v4, v75, 4, v77
	s_waitcnt vmcnt(2)
	ds_write_b128 v4, v[52:55]
	ds_write_b16 v68, v56 offset:24960
	ds_write_b16_d16_hi v68, v56 offset:25480
	ds_write_b16 v68, v57 offset:26000
	ds_write_b16_d16_hi v68, v57 offset:26520
	ds_write_b16 v68, v58 offset:27040
	ds_write_b16_d16_hi v68, v58 offset:27560
	ds_write_b16 v68, v59 offset:28080
	ds_write_b16_d16_hi v68, v59 offset:28600
	v_lshl_add_u32 v4, v76, 4, v77
	s_waitcnt vmcnt(1)
	ds_write_b128 v4, v[60:63]
	v_mad_u64_u32 v[4:5], s[42:43], v76, s77, v[2:3]
	s_addc_u32 s42, 0, s20
	s_add_u32 s38, s41, s38
	s_waitcnt vmcnt(0)
	ds_write_b16 v4, v64
	ds_write_b16_d16_hi v4, v64 offset:520
	ds_write_b16 v4, v65 offset:1040
	ds_write_b16_d16_hi v4, v65 offset:1560
	ds_write_b16 v4, v66 offset:2080
	ds_write_b16_d16_hi v4, v66 offset:2600
	ds_write_b16 v4, v67 offset:3120
	ds_write_b16_d16_hi v4, v67 offset:3640
	v_or_b32_e32 v2, s38, v213
	v_mov_b64_e32 v[4:5], s[72:73]
	s_addc_u32 s39, s42, s39
	v_mad_u64_u32 v[4:5], s[42:43], v2, s16, v[4:5]
	v_lshrrev_b32_e32 v2, 2, v211
	v_mad_i32_i24 v5, s39, v238, v5
	v_and_b32_e32 v215, 8, v2
	v_lshl_add_u64 v[4:5], v[4:5], 0, s[24:25]
	v_lshlrev_b32_e32 v6, 1, v215
	v_mov_b32_e32 v7, v3
	v_lshl_add_u64 v[4:5], v[4:5], 0, v[6:7]
	v_add_co_u32_e32 v6, vcc, s17, v4
	s_waitcnt lgkmcnt(0)
	s_nop 0
	v_addc_co_u32_e32 v7, vcc, 0, v5, vcc
	s_barrier
	global_load_dwordx4 v[116:119], v[6:7], off
	v_lshl_add_u64 v[8:9], v[4:5], 0, s[64:65]
	global_load_dwordx4 v[188:191], v[8:9], off offset:32
	global_load_dwordx4 v[184:187], v[8:9], off offset:64
	global_load_dwordx4 v[180:183], v[8:9], off offset:96
	global_load_dwordx4 v[176:179], v[8:9], off offset:128
	global_load_dwordx4 v[168:171], v[8:9], off offset:160
	global_load_dwordx4 v[164:167], v[8:9], off offset:192
	s_mul_i32 s41, s39, 0x1800
	s_mul_hi_u32 s42, s38, 0x1800
	s_add_i32 s42, s42, s41
	s_mul_i32 s41, s38, 0x1800
	v_lshrrev_b32_e32 v2, 1, v211
	s_add_u32 s41, s72, s41
	v_and_b32_e32 v2, 16, v2
	v_mul_u32_u24_e32 v4, 0x110, v213
	s_addc_u32 s43, s73, s42
	v_add3_u32 v202, 0, v2, v4
	s_add_u32 s42, s41, s24
	v_mul_u32_u24_e32 v2, 0xc00, v201
	s_addc_u32 s43, s43, 0
	v_lshlrev_b32_e32 v2, 1, v2
	global_load_dwordx4 v[172:175], v[8:9], off offset:224
	v_lshl_add_u64 v[8:9], s[42:43], 0, v[2:3]
	v_lshlrev_b32_e32 v2, 4, v211
	v_and_b32_e32 v2, 0xf0, v2
	v_lshl_add_u64 v[8:9], v[8:9], 0, v[2:3]
	v_add_co_u32_e32 v10, vcc, s17, v8
	ds_read_b128 v[4:7], v202
	s_nop 0
	v_addc_co_u32_e32 v11, vcc, 0, v9, vcc
	v_add_co_u32_e32 v12, vcc, s51, v8
	s_nop 1
	v_addc_co_u32_e32 v13, vcc, 0, v9, vcc
	global_load_dwordx4 v[160:163], v[10:11], off offset:1024
	global_load_dwordx4 v[156:159], v[12:13], off offset:1024
	v_add_co_u32_e32 v10, vcc, s58, v8
	s_nop 1
	v_addc_co_u32_e32 v11, vcc, 0, v9, vcc
	v_add_co_u32_e32 v12, vcc, s59, v8
	s_nop 1
	v_addc_co_u32_e32 v13, vcc, 0, v9, vcc
	global_load_dwordx4 v[152:155], v[10:11], off offset:1024
	global_load_dwordx4 v[148:151], v[12:13], off offset:1024
	v_add_co_u32_e32 v10, vcc, s60, v8
	s_nop 1
	v_addc_co_u32_e32 v11, vcc, 0, v9, vcc
	v_add_co_u32_e32 v12, vcc, s61, v8
	s_nop 1
	v_addc_co_u32_e32 v13, vcc, 0, v9, vcc
	global_load_dwordx4 v[144:147], v[10:11], off offset:1024
	global_load_dwordx4 v[140:143], v[12:13], off offset:1024
	v_add_co_u32_e32 v10, vcc, s63, v8
	s_nop 1
	v_addc_co_u32_e32 v11, vcc, 0, v9, vcc
	v_add_co_u32_e32 v8, vcc, s46, v8
	s_nop 1
	v_addc_co_u32_e32 v9, vcc, 0, v9, vcc
	global_load_dwordx4 v[136:139], v[10:11], off offset:1024
	global_load_dwordx4 v[132:135], v[8:9], off offset:1024
	ds_read_b128 v[20:23], v202 offset:32
	s_waitcnt vmcnt(15) lgkmcnt(1)
	v_mfma_f32_32x32x16_bf16 v[4:19], v[4:7], v[116:119], 0
	s_waitcnt vmcnt(14) lgkmcnt(0)
	v_mfma_f32_32x32x16_bf16 v[4:19], v[20:23], v[188:191], v[4:19]
	ds_read_b128 v[20:23], v202 offset:64
	s_waitcnt vmcnt(13) lgkmcnt(0)
	v_mfma_f32_32x32x16_bf16 v[4:19], v[20:23], v[184:187], v[4:19]
	ds_read_b128 v[20:23], v202 offset:96
	s_waitcnt vmcnt(12) lgkmcnt(0)
	v_mfma_f32_32x32x16_bf16 v[4:19], v[20:23], v[180:183], v[4:19]
	ds_read_b128 v[20:23], v202 offset:128
	s_waitcnt vmcnt(11) lgkmcnt(0)
	v_mfma_f32_32x32x16_bf16 v[4:19], v[20:23], v[176:179], v[4:19]
	ds_read_b128 v[20:23], v202 offset:160
	s_waitcnt vmcnt(10) lgkmcnt(0)
	v_mfma_f32_32x32x16_bf16 v[4:19], v[20:23], v[168:171], v[4:19]
	ds_read_b128 v[20:23], v202 offset:192
	s_waitcnt vmcnt(9) lgkmcnt(0)
	v_mfma_f32_32x32x16_bf16 v[4:19], v[20:23], v[164:167], v[4:19]
	ds_read_b128 v[20:23], v202 offset:224
	s_waitcnt vmcnt(8) lgkmcnt(0)
	v_mfma_f32_32x32x16_bf16 v[4:19], v[20:23], v[172:175], v[4:19]
	ds_read_b128 v[20:23], v202 offset:8704
	ds_read_b128 v[36:39], v202 offset:8736
	s_waitcnt lgkmcnt(1)
	v_mfma_f32_32x32x16_bf16 v[20:35], v[20:23], v[116:119], 0
	s_waitcnt lgkmcnt(0)
	v_mfma_f32_32x32x16_bf16 v[20:35], v[36:39], v[188:191], v[20:35]
	ds_read_b128 v[36:39], v202 offset:8768
	s_waitcnt lgkmcnt(0)
	v_mfma_f32_32x32x16_bf16 v[20:35], v[36:39], v[184:187], v[20:35]
	ds_read_b128 v[36:39], v202 offset:8800
	s_waitcnt lgkmcnt(0)
	v_mfma_f32_32x32x16_bf16 v[20:35], v[36:39], v[180:183], v[20:35]
	ds_read_b128 v[36:39], v202 offset:8832
	s_waitcnt lgkmcnt(0)
	v_mfma_f32_32x32x16_bf16 v[20:35], v[36:39], v[176:179], v[20:35]
	ds_read_b128 v[36:39], v202 offset:8864
	s_waitcnt lgkmcnt(0)
	v_mfma_f32_32x32x16_bf16 v[20:35], v[36:39], v[168:171], v[20:35]
	ds_read_b128 v[36:39], v202 offset:8896
	s_waitcnt lgkmcnt(0)
	v_mfma_f32_32x32x16_bf16 v[20:35], v[36:39], v[164:167], v[20:35]
	ds_read_b128 v[36:39], v202 offset:8928
	s_waitcnt lgkmcnt(0)
	v_mfma_f32_32x32x16_bf16 v[20:35], v[36:39], v[172:175], v[20:35]
	ds_read_b128 v[36:39], v202 offset:17408
	ds_read_b128 v[52:55], v202 offset:17440
	v_or_b32_e32 v214, 64, v213
	s_waitcnt lgkmcnt(1)
	v_mfma_f32_32x32x16_bf16 v[36:51], v[36:39], v[116:119], 0
	s_waitcnt lgkmcnt(0)
	v_mfma_f32_32x32x16_bf16 v[36:51], v[52:55], v[188:191], v[36:51]
	ds_read_b128 v[52:55], v202 offset:17472
	s_waitcnt lgkmcnt(0)
	v_mfma_f32_32x32x16_bf16 v[36:51], v[52:55], v[184:187], v[36:51]
	ds_read_b128 v[52:55], v202 offset:17504
	s_waitcnt lgkmcnt(0)
	v_mfma_f32_32x32x16_bf16 v[36:51], v[52:55], v[180:183], v[36:51]
	ds_read_b128 v[52:55], v202 offset:17536
	s_waitcnt lgkmcnt(0)
	v_mfma_f32_32x32x16_bf16 v[36:51], v[52:55], v[176:179], v[36:51]
	ds_read_b128 v[52:55], v202 offset:17568
	s_waitcnt lgkmcnt(0)
	v_mfma_f32_32x32x16_bf16 v[36:51], v[52:55], v[168:171], v[36:51]
	ds_read_b128 v[52:55], v202 offset:17600
	s_waitcnt lgkmcnt(0)
	v_mfma_f32_32x32x16_bf16 v[36:51], v[52:55], v[164:167], v[36:51]
	ds_read_b128 v[52:55], v202 offset:17632
	s_waitcnt lgkmcnt(0)
	v_mfma_f32_32x32x16_bf16 v[36:51], v[52:55], v[172:175], v[36:51]
	ds_read_b128 v[52:55], v202 offset:26112
	ds_read_b128 v[68:71], v202 offset:26144
	v_or_b32_e32 v212, 0x60, v213
	s_waitcnt lgkmcnt(1)
	v_mfma_f32_32x32x16_bf16 v[52:67], v[52:55], v[116:119], 0
	s_waitcnt lgkmcnt(0)
	v_mfma_f32_32x32x16_bf16 v[52:67], v[68:71], v[188:191], v[52:67]
	ds_read_b128 v[68:71], v202 offset:26176
	s_waitcnt lgkmcnt(0)
	v_mfma_f32_32x32x16_bf16 v[52:67], v[68:71], v[184:187], v[52:67]
	ds_read_b128 v[68:71], v202 offset:26208
	s_waitcnt lgkmcnt(0)
	v_mfma_f32_32x32x16_bf16 v[52:67], v[68:71], v[180:183], v[52:67]
	ds_read_b128 v[68:71], v202 offset:26240
	s_waitcnt lgkmcnt(0)
	v_mfma_f32_32x32x16_bf16 v[52:67], v[68:71], v[176:179], v[52:67]
	ds_read_b128 v[68:71], v202 offset:26272
	s_waitcnt lgkmcnt(0)
	v_mfma_f32_32x32x16_bf16 v[52:67], v[68:71], v[168:171], v[52:67]
	ds_read_b128 v[68:71], v202 offset:26304
	s_waitcnt lgkmcnt(0)
	v_mfma_f32_32x32x16_bf16 v[52:67], v[68:71], v[164:167], v[52:67]
	ds_read_b128 v[68:71], v202 offset:26336
	s_waitcnt lgkmcnt(0)
	v_mfma_f32_32x32x16_bf16 v[52:67], v[68:71], v[172:175], v[52:67]
	ds_read_b128 v[68:71], v202 offset:34816
	ds_read_b128 v[84:87], v202 offset:34848
	s_waitcnt lgkmcnt(1)
	v_mfma_f32_32x32x16_bf16 v[68:83], v[68:71], v[116:119], 0
	s_waitcnt lgkmcnt(0)
	v_mfma_f32_32x32x16_bf16 v[68:83], v[84:87], v[188:191], v[68:83]
	ds_read_b128 v[84:87], v202 offset:34880
	s_waitcnt lgkmcnt(0)
	v_mfma_f32_32x32x16_bf16 v[68:83], v[84:87], v[184:187], v[68:83]
	ds_read_b128 v[84:87], v202 offset:34912
	s_waitcnt lgkmcnt(0)
	v_mfma_f32_32x32x16_bf16 v[68:83], v[84:87], v[180:183], v[68:83]
	ds_read_b128 v[84:87], v202 offset:34944
	s_waitcnt lgkmcnt(0)
	v_mfma_f32_32x32x16_bf16 v[68:83], v[84:87], v[176:179], v[68:83]
	ds_read_b128 v[84:87], v202 offset:34976
	s_waitcnt lgkmcnt(0)
	v_mfma_f32_32x32x16_bf16 v[68:83], v[84:87], v[168:171], v[68:83]
	ds_read_b128 v[84:87], v202 offset:35008
	s_waitcnt lgkmcnt(0)
	v_mfma_f32_32x32x16_bf16 v[68:83], v[84:87], v[164:167], v[68:83]
	ds_read_b128 v[84:87], v202 offset:35040
	s_waitcnt lgkmcnt(0)
	v_mfma_f32_32x32x16_bf16 v[68:83], v[84:87], v[172:175], v[68:83]
	ds_read_b128 v[84:87], v202 offset:43520
	ds_read_b128 v[100:103], v202 offset:43552
	s_waitcnt lgkmcnt(1)
	v_mfma_f32_32x32x16_bf16 v[84:99], v[84:87], v[116:119], 0
	s_waitcnt lgkmcnt(0)
	v_mfma_f32_32x32x16_bf16 v[84:99], v[100:103], v[188:191], v[84:99]
	ds_read_b128 v[100:103], v202 offset:43584
	s_waitcnt lgkmcnt(0)
	v_mfma_f32_32x32x16_bf16 v[84:99], v[100:103], v[184:187], v[84:99]
	ds_read_b128 v[100:103], v202 offset:43616
	s_waitcnt lgkmcnt(0)
	v_mfma_f32_32x32x16_bf16 v[84:99], v[100:103], v[180:183], v[84:99]
	ds_read_b128 v[100:103], v202 offset:43648
	s_waitcnt lgkmcnt(0)
	v_mfma_f32_32x32x16_bf16 v[84:99], v[100:103], v[176:179], v[84:99]
	ds_read_b128 v[100:103], v202 offset:43680
	s_waitcnt lgkmcnt(0)
	v_mfma_f32_32x32x16_bf16 v[84:99], v[100:103], v[168:171], v[84:99]
	ds_read_b128 v[100:103], v202 offset:43712
	s_waitcnt lgkmcnt(0)
	v_mfma_f32_32x32x16_bf16 v[84:99], v[100:103], v[164:167], v[84:99]
	ds_read_b128 v[100:103], v202 offset:43744
	s_waitcnt lgkmcnt(0)
	v_mfma_f32_32x32x16_bf16 v[84:99], v[100:103], v[172:175], v[84:99]
	ds_read_b128 v[100:103], v202 offset:52224
	ds_read_b128 v[120:123], v202 offset:52256
	s_waitcnt lgkmcnt(1)
	v_mfma_f32_32x32x16_bf16 v[100:115], v[100:103], v[116:119], 0
	s_waitcnt lgkmcnt(0)
	v_mfma_f32_32x32x16_bf16 v[100:115], v[120:123], v[188:191], v[100:115]
	ds_read_b128 v[120:123], v202 offset:52288
	s_waitcnt lgkmcnt(0)
	v_mfma_f32_32x32x16_bf16 v[100:115], v[120:123], v[184:187], v[100:115]
	ds_read_b128 v[120:123], v202 offset:52320
	s_waitcnt lgkmcnt(0)
	v_mfma_f32_32x32x16_bf16 v[100:115], v[120:123], v[180:183], v[100:115]
	ds_read_b128 v[120:123], v202 offset:52352
	s_waitcnt lgkmcnt(0)
	v_mfma_f32_32x32x16_bf16 v[100:115], v[120:123], v[176:179], v[100:115]
	ds_read_b128 v[120:123], v202 offset:52384
	s_waitcnt lgkmcnt(0)
	v_mfma_f32_32x32x16_bf16 v[100:115], v[120:123], v[168:171], v[100:115]
	ds_read_b128 v[120:123], v202 offset:52416
	s_waitcnt lgkmcnt(0)
	v_mfma_f32_32x32x16_bf16 v[100:115], v[120:123], v[164:167], v[100:115]
	ds_read_b128 v[120:123], v202 offset:52448
	s_waitcnt lgkmcnt(0)
	v_mfma_f32_32x32x16_bf16 v[100:115], v[120:123], v[172:175], v[100:115]
	ds_read_b128 v[120:123], v202 offset:60928
	ds_read_b128 v[204:207], v202 offset:60960
	s_waitcnt lgkmcnt(1)
	v_mfma_f32_32x32x16_bf16 v[116:131], v[120:123], v[116:119], 0
	s_waitcnt lgkmcnt(0)
	v_mfma_f32_32x32x16_bf16 v[116:131], v[204:207], v[188:191], v[116:131]
	ds_read_b128 v[188:191], v202 offset:60992
	s_waitcnt lgkmcnt(0)
	v_mfma_f32_32x32x16_bf16 v[116:131], v[188:191], v[184:187], v[116:131]
	ds_read_b128 v[184:187], v202 offset:61024
	s_waitcnt lgkmcnt(0)
	v_mfma_f32_32x32x16_bf16 v[116:131], v[184:187], v[180:183], v[116:131]
	ds_read_b128 v[180:183], v202 offset:61056
	s_waitcnt lgkmcnt(0)
	v_mfma_f32_32x32x16_bf16 v[116:131], v[180:183], v[176:179], v[116:131]
	ds_read_b128 v[176:179], v202 offset:61088
	s_waitcnt lgkmcnt(0)
	v_mfma_f32_32x32x16_bf16 v[116:131], v[176:179], v[168:171], v[116:131]
	ds_read_b128 v[168:171], v202 offset:61120
	s_waitcnt lgkmcnt(0)
	v_mfma_f32_32x32x16_bf16 v[116:131], v[168:171], v[164:167], v[116:131]
	ds_read_b128 v[164:167], v202 offset:61152
	s_waitcnt lgkmcnt(0)
	v_mfma_f32_32x32x16_bf16 v[116:131], v[164:167], v[172:175], v[116:131]
	v_max3_f32 v164, v4, s76, v5
	v_max3_f32 v164, v164, v6, v7
	v_max3_f32 v164, v164, v8, v9
	v_max3_f32 v164, v164, v10, v11
	v_max3_f32 v164, v164, v12, v13
	v_max3_f32 v164, v164, v14, v15
	v_max3_f32 v164, v164, v16, v17
	v_max3_f32 v164, v164, v18, v19
	v_max3_f32 v164, v164, v20, v21
	v_max3_f32 v164, v164, v22, v23
	v_max3_f32 v164, v164, v24, v25
	v_max3_f32 v164, v164, v26, v27
	v_max3_f32 v164, v164, v28, v29
	v_max3_f32 v164, v164, v30, v31
	v_max3_f32 v164, v164, v32, v33
	v_max3_f32 v164, v164, v34, v35
	v_max3_f32 v164, v164, v36, v37
	v_max3_f32 v164, v164, v38, v39
	v_max3_f32 v164, v164, v40, v41
	v_max3_f32 v164, v164, v42, v43
	v_max3_f32 v164, v164, v44, v45
	v_max3_f32 v164, v164, v46, v47
	v_max3_f32 v164, v164, v48, v49
	v_max3_f32 v164, v164, v50, v51
	v_max3_f32 v164, v164, v52, v53
	v_max3_f32 v164, v164, v54, v55
	v_max3_f32 v164, v164, v56, v57
	v_max3_f32 v164, v164, v58, v59
	v_max3_f32 v164, v164, v60, v61
	v_max3_f32 v164, v164, v62, v63
	v_max3_f32 v164, v164, v64, v65
	v_max3_f32 v164, v164, v66, v67
	v_max3_f32 v164, v164, v68, v69
	v_max3_f32 v164, v164, v70, v71
	v_max3_f32 v164, v164, v72, v73
	v_max3_f32 v164, v164, v74, v75
	v_max3_f32 v164, v164, v76, v77
	v_max3_f32 v164, v164, v78, v79
	v_max3_f32 v164, v164, v80, v81
	v_max3_f32 v164, v164, v82, v83
	v_max3_f32 v164, v164, v84, v85
	v_max3_f32 v164, v164, v86, v87
	v_max3_f32 v164, v164, v88, v89
	v_max3_f32 v164, v164, v90, v91
	v_max3_f32 v164, v164, v92, v93
	v_max3_f32 v164, v164, v94, v95
	v_max3_f32 v164, v164, v96, v97
	v_max3_f32 v164, v164, v98, v99
	v_max3_f32 v164, v164, v100, v101
	v_max3_f32 v164, v164, v102, v103
	v_max3_f32 v164, v164, v104, v105
	v_max3_f32 v164, v164, v106, v107
	v_max3_f32 v164, v164, v108, v109
	v_max3_f32 v164, v164, v110, v111
	v_max3_f32 v164, v164, v112, v113
	v_max3_f32 v164, v164, v114, v115
	v_max3_f32 v164, v164, v116, v117
	v_max3_f32 v164, v164, v118, v119
	v_max3_f32 v164, v164, v120, v121
	v_max3_f32 v164, v164, v122, v123
	v_max3_f32 v164, v164, v124, v125
	v_max3_f32 v164, v164, v126, v127
	v_cmp_lt_i32_e32 vcc, v236, v235
	v_max3_f32 v164, v164, v128, v129
	v_max3_f32 v164, v164, v130, v131
	v_cndmask_b32_e32 v165, v231, v236, vcc
	v_lshlrev_b32_e32 v216, 2, v165
	ds_bpermute_b32 v165, v216, v164
	s_waitcnt lgkmcnt(0)
	s_barrier
	v_max_f32_e32 v165, v165, v165
	v_max_f32_e32 v217, v164, v165
	v_sub_f32_e32 v10, v10, v217
	v_exp_f32_e32 v164, v10
	v_sub_f32_e32 v10, v11, v217
	v_exp_f32_e32 v165, v10
	v_sub_f32_e32 v10, v12, v217
	v_exp_f32_e32 v166, v10
	v_sub_f32_e32 v10, v13, v217
	v_exp_f32_e32 v167, v10
	v_sub_f32_e32 v10, v14, v217
	v_exp_f32_e32 v168, v10
	v_sub_f32_e32 v10, v15, v217
	v_exp_f32_e32 v169, v10
	v_sub_f32_e32 v10, v16, v217
	v_exp_f32_e32 v170, v10
	v_sub_f32_e32 v10, v17, v217
	v_sub_f32_e32 v16, v26, v217
	v_exp_f32_e32 v171, v10
	v_sub_f32_e32 v10, v18, v217
	v_exp_f32_e32 v18, v16
	v_sub_f32_e32 v16, v27, v217
	v_exp_f32_e32 v172, v10
	v_sub_f32_e32 v10, v19, v217
	v_exp_f32_e32 v19, v16
	v_sub_f32_e32 v16, v28, v217
	v_exp_f32_e32 v28, v16
	v_sub_f32_e32 v16, v29, v217
	v_exp_f32_e32 v29, v16
	v_sub_f32_e32 v16, v30, v217
	v_exp_f32_e32 v30, v16
	v_sub_f32_e32 v16, v31, v217
	v_exp_f32_e32 v31, v16
	v_sub_f32_e32 v16, v32, v217
	v_exp_f32_e32 v32, v16
	v_sub_f32_e32 v16, v33, v217
	v_exp_f32_e32 v33, v16
	v_sub_f32_e32 v16, v34, v217
	v_exp_f32_e32 v173, v10
	v_sub_f32_e32 v10, v20, v217
	v_exp_f32_e32 v34, v16
	v_sub_f32_e32 v16, v35, v217
	v_sub_f32_e32 v20, v38, v217
	v_exp_f32_e32 v35, v16
	v_sub_f32_e32 v16, v36, v217
	v_exp_f32_e32 v36, v20
	v_sub_f32_e32 v20, v39, v217
	v_sub_f32_e32 v17, v37, v217
	v_exp_f32_e32 v37, v20
	v_sub_f32_e32 v20, v40, v217
	v_exp_f32_e32 v38, v20
	v_sub_f32_e32 v20, v41, v217
	v_exp_f32_e32 v39, v20
	v_sub_f32_e32 v20, v42, v217
	v_exp_f32_e32 v40, v20
	v_sub_f32_e32 v20, v43, v217
	v_exp_f32_e32 v41, v20
	v_sub_f32_e32 v20, v44, v217
	v_exp_f32_e32 v42, v20
	v_sub_f32_e32 v20, v45, v217
	v_exp_f32_e32 v43, v20
	v_sub_f32_e32 v20, v46, v217
	v_exp_f32_e32 v174, v20
	v_sub_f32_e32 v20, v47, v217
	v_exp_f32_e32 v175, v20
	v_sub_f32_e32 v20, v48, v217
	v_exp_f32_e32 v176, v20
	v_sub_f32_e32 v20, v49, v217
	v_exp_f32_e32 v177, v20
	v_sub_f32_e32 v20, v50, v217
	v_exp_f32_e32 v178, v20
	v_sub_f32_e32 v20, v51, v217
	v_exp_f32_e32 v179, v20
	v_sub_f32_e32 v20, v52, v217
	v_exp_f32_e32 v44, v20
	v_sub_f32_e32 v20, v53, v217
	v_exp_f32_e32 v45, v20
	v_sub_f32_e32 v20, v54, v217
	v_exp_f32_e32 v46, v20
	v_sub_f32_e32 v20, v55, v217
	v_exp_f32_e32 v47, v20
	v_sub_f32_e32 v20, v56, v217
	v_exp_f32_e32 v48, v20
	v_sub_f32_e32 v20, v57, v217
	v_exp_f32_e32 v49, v20
	v_sub_f32_e32 v20, v58, v217
	v_exp_f32_e32 v50, v20
	v_sub_f32_e32 v20, v59, v217
	v_exp_f32_e32 v51, v20
	v_sub_f32_e32 v20, v60, v217
	v_exp_f32_e32 v56, v20
	v_sub_f32_e32 v20, v61, v217
	v_exp_f32_e32 v57, v20
	v_sub_f32_e32 v20, v62, v217
	v_exp_f32_e32 v60, v20
	v_sub_f32_e32 v20, v63, v217
	v_exp_f32_e32 v61, v20
	v_sub_f32_e32 v20, v64, v217
	v_exp_f32_e32 v180, v20
	v_sub_f32_e32 v20, v65, v217
	v_exp_f32_e32 v181, v20
	v_sub_f32_e32 v20, v66, v217
	v_exp_f32_e32 v182, v20
	v_sub_f32_e32 v20, v67, v217
	v_exp_f32_e32 v183, v20
	v_sub_f32_e32 v20, v68, v217
	v_exp_f32_e32 v52, v20
	v_sub_f32_e32 v20, v69, v217
	v_exp_f32_e32 v53, v20
	v_sub_f32_e32 v20, v70, v217
	v_exp_f32_e32 v54, v20
	v_sub_f32_e32 v20, v71, v217
	v_exp_f32_e32 v55, v20
	v_sub_f32_e32 v20, v72, v217
	v_exp_f32_e32 v58, v20
	v_sub_f32_e32 v20, v73, v217
	v_exp_f32_e32 v59, v20
	v_sub_f32_e32 v20, v74, v217
	v_exp_f32_e32 v64, v20
	v_sub_f32_e32 v20, v75, v217
	v_exp_f32_e32 v65, v20
	v_sub_f32_e32 v20, v76, v217
	v_exp_f32_e32 v68, v20
	v_sub_f32_e32 v20, v77, v217
	v_exp_f32_e32 v69, v20
	v_sub_f32_e32 v20, v78, v217
	v_exp_f32_e32 v72, v20
	v_sub_f32_e32 v20, v79, v217
	v_exp_f32_e32 v73, v20
	v_sub_f32_e32 v20, v80, v217
	v_exp_f32_e32 v186, v20
	v_sub_f32_e32 v20, v81, v217
	v_exp_f32_e32 v187, v20
	v_sub_f32_e32 v20, v82, v217
	v_exp_f32_e32 v190, v20
	v_sub_f32_e32 v20, v83, v217
	v_exp_f32_e32 v191, v20
	v_sub_f32_e32 v20, v84, v217
	v_exp_f32_e32 v62, v20
	v_sub_f32_e32 v20, v85, v217
	v_exp_f32_e32 v63, v20
	v_sub_f32_e32 v20, v86, v217
	v_exp_f32_e32 v66, v20
	v_sub_f32_e32 v20, v87, v217
	v_exp_f32_e32 v67, v20
	v_sub_f32_e32 v20, v88, v217
	v_exp_f32_e32 v70, v20
	v_sub_f32_e32 v20, v89, v217
	v_exp_f32_e32 v71, v20
	v_sub_f32_e32 v20, v90, v217
	v_exp_f32_e32 v184, v20
	v_sub_f32_e32 v20, v91, v217
	v_exp_f32_e32 v185, v20
	v_sub_f32_e32 v20, v92, v217
	v_exp_f32_e32 v188, v20
	v_sub_f32_e32 v20, v93, v217
	v_exp_f32_e32 v189, v20
	v_sub_f32_e32 v20, v94, v217
	v_exp_f32_e32 v202, v20
	v_sub_f32_e32 v20, v95, v217
	v_exp_f32_e32 v203, v20
	v_sub_f32_e32 v20, v96, v217
	v_exp_f32_e32 v204, v20
	v_sub_f32_e32 v20, v97, v217
	v_exp_f32_e32 v205, v20
	v_sub_f32_e32 v20, v98, v217
	v_exp_f32_e32 v206, v20
	v_sub_f32_e32 v20, v99, v217
	v_exp_f32_e32 v207, v20
	v_sub_f32_e32 v20, v100, v217
	v_exp_f32_e32 v74, v20
	v_sub_f32_e32 v20, v101, v217
	v_exp_f32_e32 v75, v20
	v_sub_f32_e32 v20, v102, v217
	v_exp_f32_e32 v92, v20
	v_sub_f32_e32 v20, v103, v217
	v_exp_f32_e32 v93, v20
	v_sub_f32_e32 v20, v104, v217
	v_exp_f32_e32 v94, v20
	v_sub_f32_e32 v20, v105, v217
	v_exp_f32_e32 v95, v20
	v_sub_f32_e32 v20, v106, v217
	v_exp_f32_e32 v96, v20
	v_sub_f32_e32 v20, v107, v217
	v_exp_f32_e32 v97, v20
	v_sub_f32_e32 v20, v108, v217
	v_exp_f32_e32 v98, v20
	v_sub_f32_e32 v20, v109, v217
	v_exp_f32_e32 v99, v20
	v_sub_f32_e32 v20, v110, v217
	v_exp_f32_e32 v100, v20
	v_sub_f32_e32 v20, v111, v217
	v_exp_f32_e32 v101, v20
	v_sub_f32_e32 v20, v112, v217
	v_exp_f32_e32 v102, v20
	v_sub_f32_e32 v20, v113, v217
	v_exp_f32_e32 v103, v20
	v_sub_f32_e32 v20, v114, v217
	v_exp_f32_e32 v104, v20
	v_sub_f32_e32 v20, v115, v217
	v_exp_f32_e32 v105, v20
	v_sub_f32_e32 v20, v116, v217
	v_exp_f32_e32 v76, v20
	v_sub_f32_e32 v20, v117, v217
	v_exp_f32_e32 v77, v20
	v_sub_f32_e32 v20, v118, v217
	v_exp_f32_e32 v80, v20
	v_sub_f32_e32 v20, v119, v217
	v_exp_f32_e32 v81, v20
	v_sub_f32_e32 v20, v120, v217
	v_exp_f32_e32 v84, v20
	v_sub_f32_e32 v20, v121, v217
	v_exp_f32_e32 v85, v20
	v_sub_f32_e32 v20, v122, v217
	v_exp_f32_e32 v88, v20
	v_sub_f32_e32 v20, v123, v217
	v_exp_f32_e32 v89, v20
	v_sub_f32_e32 v20, v124, v217
	v_exp_f32_e32 v78, v20
	v_sub_f32_e32 v20, v125, v217
	v_exp_f32_e32 v79, v20
	v_sub_f32_e32 v20, v126, v217
	v_sub_f32_e32 v4, v4, v217
	v_exp_f32_e32 v82, v20
	v_sub_f32_e32 v20, v127, v217
	v_sub_f32_e32 v5, v5, v217
	v_exp_f32_e32 v4, v4
	v_exp_f32_e32 v83, v20
	v_sub_f32_e32 v20, v128, v217
	v_exp_f32_e32 v5, v5
	v_sub_f32_e32 v6, v6, v217
	v_exp_f32_e32 v86, v20
	v_sub_f32_e32 v20, v129, v217
	v_exp_f32_e32 v6, v6
	v_sub_f32_e32 v7, v7, v217
	v_exp_f32_e32 v87, v20
	v_sub_f32_e32 v20, v130, v217
	v_exp_f32_e32 v7, v7
	v_sub_f32_e32 v8, v8, v217
	v_exp_f32_e32 v90, v20
	v_sub_f32_e32 v20, v131, v217
	v_exp_f32_e32 v8, v8
	v_sub_f32_e32 v9, v9, v217
	v_exp_f32_e32 v91, v20
	v_add_f32_e32 v20, 0, v4
	v_exp_f32_e32 v9, v9
	v_add_f32_e32 v20, v5, v20
	v_add_f32_e32 v20, v6, v20
	v_add_f32_e32 v20, v7, v20
	v_add_f32_e32 v20, v8, v20
	v_add_f32_e32 v20, v9, v20
	v_add_f32_e32 v20, v164, v20
	v_add_f32_e32 v20, v165, v20
	v_add_f32_e32 v20, v166, v20
	v_add_f32_e32 v20, v167, v20
	v_add_f32_e32 v20, v168, v20
	v_add_f32_e32 v20, v169, v20
	v_exp_f32_e32 v10, v10
	v_sub_f32_e32 v11, v21, v217
	v_add_f32_e32 v20, v170, v20
	v_exp_f32_e32 v11, v11
	v_sub_f32_e32 v12, v22, v217
	v_add_f32_e32 v20, v171, v20
	v_exp_f32_e32 v12, v12
	v_sub_f32_e32 v13, v23, v217
	v_add_f32_e32 v20, v172, v20
	v_exp_f32_e32 v13, v13
	v_sub_f32_e32 v14, v24, v217
	v_add_f32_e32 v20, v173, v20
	v_exp_f32_e32 v14, v14
	v_sub_f32_e32 v15, v25, v217
	v_add_f32_e32 v20, v10, v20
	v_exp_f32_e32 v15, v15
	v_add_f32_e32 v20, v11, v20
	v_add_f32_e32 v20, v12, v20
	v_add_f32_e32 v20, v13, v20
	v_add_f32_e32 v20, v14, v20
	v_add_f32_e32 v20, v15, v20
	v_add_f32_e32 v20, v18, v20
	v_add_f32_e32 v20, v19, v20
	v_add_f32_e32 v20, v28, v20
	v_add_f32_e32 v20, v29, v20
	v_add_f32_e32 v20, v30, v20
	v_add_f32_e32 v20, v31, v20
	v_exp_f32_e32 v16, v16
	v_add_f32_e32 v20, v32, v20
	v_exp_f32_e32 v17, v17
	v_add_f32_e32 v20, v33, v20
	v_add_f32_e32 v20, v34, v20
	v_add_f32_e32 v20, v35, v20
	v_add_f32_e32 v20, v16, v20
	v_add_f32_e32 v20, v17, v20
	v_add_f32_e32 v20, v36, v20
	v_add_f32_e32 v20, v37, v20
	v_add_f32_e32 v20, v38, v20
	v_add_f32_e32 v20, v39, v20
	v_add_f32_e32 v20, v40, v20
	v_add_f32_e32 v20, v41, v20
	v_add_f32_e32 v20, v42, v20
	v_add_f32_e32 v20, v43, v20
	v_add_f32_e32 v20, v174, v20
	v_add_f32_e32 v20, v175, v20
	v_add_f32_e32 v20, v176, v20
	v_add_f32_e32 v20, v177, v20
	v_add_f32_e32 v20, v178, v20
	v_add_f32_e32 v20, v179, v20
	v_add_f32_e32 v20, v44, v20
	v_add_f32_e32 v20, v45, v20
	v_add_f32_e32 v20, v46, v20
	v_add_f32_e32 v20, v47, v20
	v_add_f32_e32 v20, v48, v20
	v_add_f32_e32 v20, v49, v20
	v_add_f32_e32 v20, v50, v20
	v_add_f32_e32 v20, v51, v20
	v_add_f32_e32 v20, v56, v20
	v_add_f32_e32 v20, v57, v20
	v_add_f32_e32 v20, v60, v20
	v_add_f32_e32 v20, v61, v20
	v_add_f32_e32 v20, v180, v20
	v_add_f32_e32 v20, v181, v20
	v_add_f32_e32 v20, v182, v20
	v_add_f32_e32 v20, v183, v20
	v_add_f32_e32 v20, v52, v20
	v_add_f32_e32 v20, v53, v20
	v_add_f32_e32 v20, v54, v20
	v_add_f32_e32 v20, v55, v20
	v_add_f32_e32 v20, v58, v20
	v_add_f32_e32 v20, v59, v20
	v_add_f32_e32 v20, v64, v20
	v_add_f32_e32 v20, v65, v20
	v_add_f32_e32 v20, v68, v20
	v_add_f32_e32 v20, v69, v20
	v_add_f32_e32 v20, v72, v20
	v_add_f32_e32 v20, v73, v20
	v_add_f32_e32 v20, v186, v20
	v_add_f32_e32 v20, v187, v20
	v_add_f32_e32 v20, v190, v20
	v_add_f32_e32 v20, v191, v20
	v_add_f32_e32 v20, v62, v20
	v_add_f32_e32 v20, v63, v20
	v_add_f32_e32 v20, v66, v20
	v_add_f32_e32 v20, v67, v20
	v_add_f32_e32 v20, v70, v20
	v_add_f32_e32 v20, v71, v20
	v_add_f32_e32 v20, v184, v20
	v_add_f32_e32 v20, v185, v20
	v_add_f32_e32 v20, v188, v20
	v_add_f32_e32 v20, v189, v20
	v_add_f32_e32 v20, v202, v20
	v_add_f32_e32 v20, v203, v20
	v_add_f32_e32 v20, v204, v20
	v_add_f32_e32 v20, v205, v20
	v_add_f32_e32 v20, v206, v20
	v_add_f32_e32 v20, v207, v20
	v_add_f32_e32 v20, v74, v20
	v_add_f32_e32 v20, v75, v20
	v_add_f32_e32 v20, v92, v20
	v_add_f32_e32 v20, v93, v20
	v_add_f32_e32 v20, v94, v20
	v_add_f32_e32 v20, v95, v20
	v_add_f32_e32 v20, v96, v20
	v_add_f32_e32 v20, v97, v20
	v_add_f32_e32 v20, v98, v20
	v_add_f32_e32 v20, v99, v20
	v_add_f32_e32 v20, v100, v20
	v_add_f32_e32 v20, v101, v20
	v_add_f32_e32 v20, v102, v20
	v_add_f32_e32 v20, v103, v20
	v_add_f32_e32 v20, v104, v20
	v_add_f32_e32 v20, v105, v20
	v_add_f32_e32 v20, v76, v20
	v_add_f32_e32 v20, v77, v20
	v_add_f32_e32 v20, v80, v20
	v_add_f32_e32 v20, v81, v20
	v_add_f32_e32 v20, v84, v20
	v_add_f32_e32 v20, v85, v20
	v_add_f32_e32 v20, v88, v20
	v_add_f32_e32 v20, v89, v20
	v_add_f32_e32 v20, v78, v20
	v_add_f32_e32 v20, v79, v20
	v_add_f32_e32 v20, v82, v20
	v_add_f32_e32 v20, v83, v20
	v_add_f32_e32 v20, v86, v20
	v_add_f32_e32 v20, v87, v20
	v_add_f32_e32 v20, v90, v20
	v_add_f32_e32 v20, v91, v20
	ds_bpermute_b32 v21, v216, v20
	s_waitcnt lgkmcnt(0)
	v_add_f32_e32 v20, v20, v21
	v_div_scale_f32 v21, s[42:43], v20, v20, 1.0
	v_rcp_f32_e32 v22, v21
	s_nop 0
	v_fma_f32 v23, -v21, v22, 1.0
	v_fmac_f32_e32 v22, v23, v22
	v_div_scale_f32 v23, vcc, 1.0, v20, 1.0
	v_mul_f32_e32 v24, v23, v22
	v_fma_f32 v25, -v21, v24, v23
	v_fmac_f32_e32 v24, v25, v22
	v_fma_f32 v21, -v21, v24, v23
	v_div_fmas_f32 v21, v21, v22, v24
	v_div_fixup_f32 v106, v21, v20, 1.0
	v_pk_mul_f32 v[6:7], v[6:7], v[106:107] op_sel_hi:[1,0]
	v_pk_mul_f32 v[4:5], v[4:5], v[106:107] op_sel_hi:[1,0]
	v_pk_mul_f32 v[8:9], v[8:9], v[106:107] op_sel_hi:[1,0]
	v_cvt_pk_bf16_f32 v21, v6, v7
	v_pk_mul_f32 v[6:7], v[12:13], v[106:107] op_sel_hi:[1,0]
	v_pk_mul_f32 v[24:25], v[164:165], v[106:107] op_sel_hi:[1,0]
	v_pk_mul_f32 v[108:109], v[168:169], v[106:107] op_sel_hi:[1,0]
	v_cvt_pk_bf16_f32 v20, v4, v5
	v_cvt_pk_bf16_f32 v22, v8, v9
	v_pk_mul_f32 v[4:5], v[10:11], v[106:107] op_sel_hi:[1,0]
	v_pk_mul_f32 v[8:9], v[14:15], v[106:107] op_sel_hi:[1,0]
	v_pk_mul_f32 v[10:11], v[18:19], v[106:107] op_sel_hi:[1,0]
	v_pk_mul_f32 v[18:19], v[32:33], v[106:107] op_sel_hi:[1,0]
	v_cvt_pk_bf16_f32 v33, v6, v7
	v_pk_mul_f32 v[6:7], v[36:37], v[106:107] op_sel_hi:[1,0]
	v_cvt_pk_bf16_f32 v23, v24, v25
	v_cvt_pk_bf16_f32 v25, v108, v109
	v_pk_mul_f32 v[108:109], v[34:35], v[106:107] op_sel_hi:[1,0]
	v_cvt_pk_bf16_f32 v32, v4, v5
	v_cvt_pk_bf16_f32 v34, v8, v9
	v_pk_mul_f32 v[4:5], v[16:17], v[106:107] op_sel_hi:[1,0]
	v_pk_mul_f32 v[8:9], v[38:39], v[106:107] op_sel_hi:[1,0]
	v_cvt_pk_bf16_f32 v37, v6, v7
	v_pk_mul_f32 v[6:7], v[46:47], v[106:107] op_sel_hi:[1,0]
	v_cvt_pk_bf16_f32 v35, v10, v11
	v_pk_mul_f32 v[10:11], v[40:41], v[106:107] op_sel_hi:[1,0]
	v_cvt_pk_bf16_f32 v36, v4, v5
	v_cvt_pk_bf16_f32 v38, v8, v9
	v_pk_mul_f32 v[4:5], v[44:45], v[106:107] op_sel_hi:[1,0]
	v_pk_mul_f32 v[8:9], v[48:49], v[106:107] op_sel_hi:[1,0]
	v_cvt_pk_bf16_f32 v49, v6, v7
	v_pk_mul_f32 v[6:7], v[54:55], v[106:107] op_sel_hi:[1,0]
	v_pk_mul_f32 v[12:13], v[28:29], v[106:107] op_sel_hi:[1,0]
	v_cvt_pk_bf16_f32 v39, v10, v11
	v_pk_mul_f32 v[10:11], v[50:51], v[106:107] op_sel_hi:[1,0]
	v_cvt_pk_bf16_f32 v48, v4, v5
	v_pk_mul_f32 v[4:5], v[52:53], v[106:107] op_sel_hi:[1,0]
	v_cvt_pk_bf16_f32 v53, v6, v7
	v_pk_mul_f32 v[6:7], v[66:67], v[106:107] op_sel_hi:[1,0]
	v_cvt_pk_bf16_f32 v28, v12, v13
	v_pk_mul_f32 v[12:13], v[42:43], v[106:107] op_sel_hi:[1,0]
	v_cvt_pk_bf16_f32 v51, v10, v11
	v_pk_mul_f32 v[10:11], v[64:65], v[106:107] op_sel_hi:[1,0]
	v_cvt_pk_bf16_f32 v52, v4, v5
	v_pk_mul_f32 v[4:5], v[62:63], v[106:107] op_sel_hi:[1,0]
	v_cvt_pk_bf16_f32 v65, v6, v7
	v_pk_mul_f32 v[6:7], v[92:93], v[106:107] op_sel_hi:[1,0]
	v_add_u32_e32 v92, s11, v215
	v_pk_mul_f32 v[14:15], v[30:31], v[106:107] op_sel_hi:[1,0]
	v_cvt_pk_bf16_f32 v40, v12, v13
	v_pk_mul_f32 v[12:13], v[56:57], v[106:107] op_sel_hi:[1,0]
	v_cvt_pk_bf16_f32 v64, v4, v5
	v_pk_mul_f32 v[4:5], v[74:75], v[106:107] op_sel_hi:[1,0]
	v_mad_u32_u24 v93, v213, s8, v92
	v_cvt_pk_bf16_f32 v29, v14, v15
	v_cvt_pk_bf16_f32 v30, v18, v19
	v_pk_mul_f32 v[14:15], v[174:175], v[106:107] op_sel_hi:[1,0]
	v_pk_mul_f32 v[16:17], v[176:177], v[106:107] op_sel_hi:[1,0]
	v_pk_mul_f32 v[18:19], v[178:179], v[106:107] op_sel_hi:[1,0]
	v_cvt_pk_bf16_f32 v44, v12, v13
	v_pk_mul_f32 v[12:13], v[68:69], v[106:107] op_sel_hi:[1,0]
	v_cvt_pk_bf16_f32 v68, v4, v5
	v_cvt_pk_bf16_f32 v69, v6, v7
	ds_read2_b64 v[4:7], v93 offset1:2
	v_cvt_pk_bf16_f32 v41, v14, v15
	v_cvt_pk_bf16_f32 v42, v16, v17
	v_cvt_pk_bf16_f32 v43, v18, v19
	v_pk_mul_f32 v[14:15], v[60:61], v[106:107] op_sel_hi:[1,0]
	v_pk_mul_f32 v[16:17], v[180:181], v[106:107] op_sel_hi:[1,0]
	v_pk_mul_f32 v[18:19], v[182:183], v[106:107] op_sel_hi:[1,0]
	v_cvt_pk_bf16_f32 v50, v8, v9
	v_cvt_pk_bf16_f32 v45, v14, v15
	v_cvt_pk_bf16_f32 v46, v16, v17
	v_cvt_pk_bf16_f32 v47, v18, v19
	v_pk_mul_f32 v[8:9], v[58:59], v[106:107] op_sel_hi:[1,0]
	v_pk_mul_f32 v[14:15], v[72:73], v[106:107] op_sel_hi:[1,0]
	v_pk_mul_f32 v[16:17], v[186:187], v[106:107] op_sel_hi:[1,0]
	v_pk_mul_f32 v[18:19], v[190:191], v[106:107] op_sel_hi:[1,0]
	v_cvt_pk_bf16_f32 v54, v8, v9
	v_cvt_pk_bf16_f32 v55, v10, v11
	v_cvt_pk_bf16_f32 v56, v12, v13
	v_cvt_pk_bf16_f32 v57, v14, v15
	v_cvt_pk_bf16_f32 v58, v16, v17
	v_cvt_pk_bf16_f32 v59, v18, v19
	v_pk_mul_f32 v[8:9], v[70:71], v[106:107] op_sel_hi:[1,0]
	v_pk_mul_f32 v[10:11], v[184:185], v[106:107] op_sel_hi:[1,0]
	v_pk_mul_f32 v[12:13], v[188:189], v[106:107] op_sel_hi:[1,0]
	v_pk_mul_f32 v[14:15], v[202:203], v[106:107] op_sel_hi:[1,0]
	v_pk_mul_f32 v[16:17], v[204:205], v[106:107] op_sel_hi:[1,0]
	v_pk_mul_f32 v[18:19], v[206:207], v[106:107] op_sel_hi:[1,0]
	v_cvt_pk_bf16_f32 v66, v8, v9
	v_cvt_pk_bf16_f32 v67, v10, v11
	v_cvt_pk_bf16_f32 v60, v12, v13
	v_cvt_pk_bf16_f32 v61, v14, v15
	v_cvt_pk_bf16_f32 v62, v16, v17
	v_cvt_pk_bf16_f32 v63, v18, v19
	v_pk_mul_f32 v[8:9], v[94:95], v[106:107] op_sel_hi:[1,0]
	v_pk_mul_f32 v[10:11], v[96:97], v[106:107] op_sel_hi:[1,0]
	v_pk_mul_f32 v[12:13], v[98:99], v[106:107] op_sel_hi:[1,0]
	v_pk_mul_f32 v[14:15], v[100:101], v[106:107] op_sel_hi:[1,0]
	v_pk_mul_f32 v[16:17], v[102:103], v[106:107] op_sel_hi:[1,0]
	v_pk_mul_f32 v[18:19], v[104:105], v[106:107] op_sel_hi:[1,0]
	v_cvt_pk_bf16_f32 v70, v8, v9
	v_cvt_pk_bf16_f32 v71, v10, v11
	v_cvt_pk_bf16_f32 v72, v12, v13
	v_cvt_pk_bf16_f32 v73, v14, v15
	v_cvt_pk_bf16_f32 v74, v16, v17
	v_cvt_pk_bf16_f32 v75, v18, v19
	s_waitcnt lgkmcnt(0)
	v_mfma_f32_32x32x16_bf16 v[4:19], v[20:23], v[4:7], 0
	v_mul_f32_e64 v26, v166, v106
	v_mul_f32_e64 v27, v167, v106
	v_mul_f32_e64 v110, v170, v106
	v_mul_f32_e64 v111, v171, v106
	v_mul_f32_e64 v112, v172, v106
	v_mul_f32_e64 v113, v173, v106
	v_cvt_pk_bf16_f32 v24, v26, v27
	v_cvt_pk_bf16_f32 v26, v110, v111
	v_cvt_pk_bf16_f32 v27, v112, v113
	v_pk_mul_f32 v[94:95], v[80:81], v[106:107] op_sel_hi:[1,0]
	v_pk_mul_f32 v[96:97], v[78:79], v[106:107] op_sel_hi:[1,0]
	ds_read2_b64 v[78:81], v93 offset0:4 offset1:6
	s_waitcnt lgkmcnt(0)
	v_mfma_f32_32x32x16_bf16 v[4:19], v[24:27], v[78:81], v[4:19]
	v_mul_f32_e64 v84, v84, v106
	v_mul_f32_e64 v85, v85, v106
	v_mul_f32_e64 v98, v86, v106
	v_mul_f32_e64 v99, v87, v106
	v_cvt_pk_bf16_f32 v78, v84, v85
	ds_read2_b64 v[84:87], v93 offset0:8 offset1:10
	v_pk_mul_f32 v[88:89], v[88:89], v[106:107] op_sel_hi:[1,0]
	v_cvt_pk_bf16_f32 v31, v108, v109
	v_cvt_pk_bf16_f32 v79, v88, v89
	s_waitcnt lgkmcnt(0)
	v_mfma_f32_32x32x16_bf16 v[4:19], v[32:35], v[84:87], v[4:19]
	ds_read2_b64 v[86:89], v93 offset0:12 offset1:14
	v_lshrrev_b32_e32 v84, 3, v211
	v_and_b32_e32 v84, 4, v84
	v_lshlrev_b32_e32 v85, 1, v211
	v_mul_f32_e64 v76, v76, v106
	v_mul_f32_e64 v77, v77, v106
	v_pk_mul_f32 v[82:83], v[82:83], v[106:107] op_sel_hi:[1,0]
	v_pk_mul_f32 v[90:91], v[90:91], v[106:107] op_sel_hi:[1,0]
	v_mul_u32_u24_e32 v84, 0x110, v84
	v_and_b32_e32 v85, 62, v85
	v_cvt_pk_bf16_f32 v76, v76, v77
	v_cvt_pk_bf16_f32 v77, v94, v95
	v_cvt_pk_bf16_f32 v80, v96, v97
	v_cvt_pk_bf16_f32 v81, v82, v83
	v_cvt_pk_bf16_f32 v82, v98, v99
	v_cvt_pk_bf16_f32 v83, v90, v91
	v_add3_u32 v84, s4, v84, v85
	s_waitcnt lgkmcnt(0)
	v_mfma_f32_32x32x16_bf16 v[4:19], v[28:31], v[86:89], v[4:19]
	ds_read2_b64 v[86:89], v93 offset0:16 offset1:18
	s_waitcnt lgkmcnt(0)
	v_mfma_f32_32x32x16_bf16 v[4:19], v[36:39], v[86:89], v[4:19]
	ds_read2_b64 v[86:89], v93 offset0:20 offset1:22
	s_waitcnt lgkmcnt(0)
	v_mfma_f32_32x32x16_bf16 v[4:19], v[40:43], v[86:89], v[4:19]
	ds_read2_b64 v[86:89], v93 offset0:24 offset1:26
	s_waitcnt lgkmcnt(0)
	v_mfma_f32_32x32x16_bf16 v[4:19], v[48:51], v[86:89], v[4:19]
	ds_read2_b64 v[86:89], v93 offset0:28 offset1:30
	s_waitcnt lgkmcnt(0)
	v_mfma_f32_32x32x16_bf16 v[4:19], v[44:47], v[86:89], v[4:19]
	ds_read2_b64 v[86:89], v93 offset0:32 offset1:34
	s_waitcnt lgkmcnt(0)
	v_mfma_f32_32x32x16_bf16 v[4:19], v[52:55], v[86:89], v[4:19]
	ds_read2_b64 v[86:89], v93 offset0:36 offset1:38
	s_waitcnt lgkmcnt(0)
	v_mfma_f32_32x32x16_bf16 v[4:19], v[56:59], v[86:89], v[4:19]
	ds_read2_b64 v[86:89], v93 offset0:40 offset1:42
	s_waitcnt lgkmcnt(0)
	v_mfma_f32_32x32x16_bf16 v[4:19], v[64:67], v[86:89], v[4:19]
	ds_read2_b64 v[86:89], v93 offset0:44 offset1:46
	s_waitcnt lgkmcnt(0)
	v_mfma_f32_32x32x16_bf16 v[4:19], v[60:63], v[86:89], v[4:19]
	ds_read2_b64 v[86:89], v93 offset0:48 offset1:50
	s_waitcnt lgkmcnt(0)
	v_mfma_f32_32x32x16_bf16 v[4:19], v[68:71], v[86:89], v[4:19]
	ds_read2_b64 v[86:89], v93 offset0:52 offset1:54
	s_waitcnt lgkmcnt(0)
	v_mfma_f32_32x32x16_bf16 v[4:19], v[72:75], v[86:89], v[4:19]
	ds_read2_b64 v[86:89], v93 offset0:56 offset1:58
	s_waitcnt lgkmcnt(0)
	v_mfma_f32_32x32x16_bf16 v[4:19], v[76:79], v[86:89], v[4:19]
	ds_read2_b64 v[86:89], v93 offset0:60 offset1:62
	s_waitcnt lgkmcnt(0)
	v_mfma_f32_32x32x16_bf16 v[4:19], v[80:83], v[86:89], v[4:19]
	s_nop 11
	v_cvt_pk_bf16_f32 v4, v4, v5
	ds_write_b16 v84, v4
	ds_write_b16_d16_hi v84, v4 offset:272
	v_cvt_pk_bf16_f32 v4, v6, v7
	ds_write_b16 v84, v4 offset:544
	ds_write_b16_d16_hi v84, v4 offset:816
	v_cvt_pk_bf16_f32 v4, v8, v9
	ds_write_b16 v84, v4 offset:2176
	ds_write_b16_d16_hi v84, v4 offset:2448
	v_cvt_pk_bf16_f32 v4, v10, v11
	ds_write_b16 v84, v4 offset:2720
	ds_write_b16_d16_hi v84, v4 offset:2992
	v_cvt_pk_bf16_f32 v4, v12, v13
	ds_write_b16 v84, v4 offset:4352
	ds_write_b16_d16_hi v84, v4 offset:4624
	v_cvt_pk_bf16_f32 v4, v14, v15
	ds_write_b16 v84, v4 offset:4896
	ds_write_b16_d16_hi v84, v4 offset:5168
	v_cvt_pk_bf16_f32 v4, v16, v17
	ds_write_b16 v84, v4 offset:6528
	ds_write_b16_d16_hi v84, v4 offset:6800
	v_cvt_pk_bf16_f32 v4, v18, v19
	ds_write_b16 v84, v4 offset:7072
	ds_write_b16_d16_hi v84, v4 offset:7344
	v_add_u32_e32 v85, 0x4000, v93
	ds_read2_b64 v[4:7], v85 offset0:32 offset1:34
	s_waitcnt lgkmcnt(0)
	v_mfma_f32_32x32x16_bf16 v[4:19], v[20:23], v[4:7], 0
	ds_read2_b64 v[86:89], v85 offset0:36 offset1:38
	s_waitcnt lgkmcnt(0)
	v_mfma_f32_32x32x16_bf16 v[4:19], v[24:27], v[86:89], v[4:19]
	ds_read2_b64 v[86:89], v85 offset0:40 offset1:42
	s_waitcnt lgkmcnt(0)
	v_mfma_f32_32x32x16_bf16 v[4:19], v[32:35], v[86:89], v[4:19]
	ds_read2_b64 v[86:89], v85 offset0:44 offset1:46
	s_waitcnt lgkmcnt(0)
	v_mfma_f32_32x32x16_bf16 v[4:19], v[28:31], v[86:89], v[4:19]
	ds_read2_b64 v[86:89], v85 offset0:48 offset1:50
	s_waitcnt lgkmcnt(0)
	v_mfma_f32_32x32x16_bf16 v[4:19], v[36:39], v[86:89], v[4:19]
	ds_read2_b64 v[86:89], v85 offset0:52 offset1:54
	s_waitcnt lgkmcnt(0)
	v_mfma_f32_32x32x16_bf16 v[4:19], v[40:43], v[86:89], v[4:19]
	ds_read2_b64 v[86:89], v85 offset0:56 offset1:58
	s_waitcnt lgkmcnt(0)
	v_mfma_f32_32x32x16_bf16 v[4:19], v[48:51], v[86:89], v[4:19]
	ds_read2_b64 v[86:89], v85 offset0:60 offset1:62
	s_waitcnt lgkmcnt(0)
	v_mfma_f32_32x32x16_bf16 v[4:19], v[44:47], v[86:89], v[4:19]
	ds_read2_b64 v[86:89], v85 offset0:64 offset1:66
	s_waitcnt lgkmcnt(0)
	v_mfma_f32_32x32x16_bf16 v[4:19], v[52:55], v[86:89], v[4:19]
	ds_read2_b64 v[86:89], v85 offset0:68 offset1:70
	s_waitcnt lgkmcnt(0)
	v_mfma_f32_32x32x16_bf16 v[4:19], v[56:59], v[86:89], v[4:19]
	ds_read2_b64 v[86:89], v85 offset0:72 offset1:74
	s_waitcnt lgkmcnt(0)
	v_mfma_f32_32x32x16_bf16 v[4:19], v[64:67], v[86:89], v[4:19]
	ds_read2_b64 v[86:89], v85 offset0:76 offset1:78
	s_waitcnt lgkmcnt(0)
	v_mfma_f32_32x32x16_bf16 v[4:19], v[60:63], v[86:89], v[4:19]
	ds_read2_b64 v[86:89], v85 offset0:80 offset1:82
	s_waitcnt lgkmcnt(0)
	v_mfma_f32_32x32x16_bf16 v[4:19], v[68:71], v[86:89], v[4:19]
	ds_read2_b64 v[86:89], v85 offset0:84 offset1:86
	s_waitcnt lgkmcnt(0)
	v_mfma_f32_32x32x16_bf16 v[4:19], v[72:75], v[86:89], v[4:19]
	ds_read2_b64 v[86:89], v85 offset0:88 offset1:90
	s_waitcnt lgkmcnt(0)
	v_mfma_f32_32x32x16_bf16 v[4:19], v[76:79], v[86:89], v[4:19]
	ds_read2_b64 v[86:89], v85 offset0:92 offset1:94
	s_waitcnt lgkmcnt(0)
	v_mfma_f32_32x32x16_bf16 v[4:19], v[80:83], v[86:89], v[4:19]
	s_nop 11
	v_cvt_pk_bf16_f32 v4, v4, v5
	ds_write_b16 v84, v4 offset:64
	ds_write_b16_d16_hi v84, v4 offset:336
	v_cvt_pk_bf16_f32 v4, v6, v7
	ds_write_b16 v84, v4 offset:608
	ds_write_b16_d16_hi v84, v4 offset:880
	v_cvt_pk_bf16_f32 v4, v8, v9
	ds_write_b16 v84, v4 offset:2240
	ds_write_b16_d16_hi v84, v4 offset:2512
	v_cvt_pk_bf16_f32 v4, v10, v11
	ds_write_b16 v84, v4 offset:2784
	ds_write_b16_d16_hi v84, v4 offset:3056
	v_cvt_pk_bf16_f32 v4, v12, v13
	ds_write_b16 v84, v4 offset:4416
	ds_write_b16_d16_hi v84, v4 offset:4688
	v_cvt_pk_bf16_f32 v4, v14, v15
	ds_write_b16 v84, v4 offset:4960
	ds_write_b16_d16_hi v84, v4 offset:5232
	v_cvt_pk_bf16_f32 v4, v16, v17
	ds_write_b16 v84, v4 offset:6592
	ds_write_b16_d16_hi v84, v4 offset:6864
	v_cvt_pk_bf16_f32 v4, v18, v19
	ds_write_b16 v84, v4 offset:7136
	ds_write_b16_d16_hi v84, v4 offset:7408
	v_mad_u32_u24 v85, v214, s8, v92
	ds_read2_b64 v[4:7], v85 offset1:2
	s_waitcnt lgkmcnt(0)
	v_mfma_f32_32x32x16_bf16 v[4:19], v[20:23], v[4:7], 0
	ds_read2_b64 v[86:89], v85 offset0:4 offset1:6
	s_waitcnt lgkmcnt(0)
	v_mfma_f32_32x32x16_bf16 v[4:19], v[24:27], v[86:89], v[4:19]
	ds_read2_b64 v[86:89], v85 offset0:8 offset1:10
	s_waitcnt lgkmcnt(0)
	v_mfma_f32_32x32x16_bf16 v[4:19], v[32:35], v[86:89], v[4:19]
	ds_read2_b64 v[86:89], v85 offset0:12 offset1:14
	s_waitcnt lgkmcnt(0)
	v_mfma_f32_32x32x16_bf16 v[4:19], v[28:31], v[86:89], v[4:19]
	ds_read2_b64 v[86:89], v85 offset0:16 offset1:18
	s_waitcnt lgkmcnt(0)
	v_mfma_f32_32x32x16_bf16 v[4:19], v[36:39], v[86:89], v[4:19]
	ds_read2_b64 v[86:89], v85 offset0:20 offset1:22
	s_waitcnt lgkmcnt(0)
	v_mfma_f32_32x32x16_bf16 v[4:19], v[40:43], v[86:89], v[4:19]
	ds_read2_b64 v[86:89], v85 offset0:24 offset1:26
	s_waitcnt lgkmcnt(0)
	v_mfma_f32_32x32x16_bf16 v[4:19], v[48:51], v[86:89], v[4:19]
	ds_read2_b64 v[86:89], v85 offset0:28 offset1:30
	s_waitcnt lgkmcnt(0)
	v_mfma_f32_32x32x16_bf16 v[4:19], v[44:47], v[86:89], v[4:19]
	ds_read2_b64 v[86:89], v85 offset0:32 offset1:34
	s_waitcnt lgkmcnt(0)
	v_mfma_f32_32x32x16_bf16 v[4:19], v[52:55], v[86:89], v[4:19]
	ds_read2_b64 v[86:89], v85 offset0:36 offset1:38
	s_waitcnt lgkmcnt(0)
	v_mfma_f32_32x32x16_bf16 v[4:19], v[56:59], v[86:89], v[4:19]
	ds_read2_b64 v[86:89], v85 offset0:40 offset1:42
	s_waitcnt lgkmcnt(0)
	v_mfma_f32_32x32x16_bf16 v[4:19], v[64:67], v[86:89], v[4:19]
	ds_read2_b64 v[86:89], v85 offset0:44 offset1:46
	s_waitcnt lgkmcnt(0)
	v_mfma_f32_32x32x16_bf16 v[4:19], v[60:63], v[86:89], v[4:19]
	ds_read2_b64 v[86:89], v85 offset0:48 offset1:50
	s_waitcnt lgkmcnt(0)
	v_mfma_f32_32x32x16_bf16 v[4:19], v[68:71], v[86:89], v[4:19]
	ds_read2_b64 v[86:89], v85 offset0:52 offset1:54
	s_waitcnt lgkmcnt(0)
	v_mfma_f32_32x32x16_bf16 v[4:19], v[72:75], v[86:89], v[4:19]
	ds_read2_b64 v[86:89], v85 offset0:56 offset1:58
	s_waitcnt lgkmcnt(0)
	v_mfma_f32_32x32x16_bf16 v[4:19], v[76:79], v[86:89], v[4:19]
	ds_read2_b64 v[86:89], v85 offset0:60 offset1:62
	s_waitcnt lgkmcnt(0)
	v_mfma_f32_32x32x16_bf16 v[4:19], v[80:83], v[86:89], v[4:19]
	s_nop 11
	v_cvt_pk_bf16_f32 v4, v4, v5
	ds_write_b16 v84, v4 offset:128
	ds_write_b16_d16_hi v84, v4 offset:400
	v_cvt_pk_bf16_f32 v4, v6, v7
	ds_write_b16 v84, v4 offset:672
	ds_write_b16_d16_hi v84, v4 offset:944
	v_cvt_pk_bf16_f32 v4, v8, v9
	ds_write_b16 v84, v4 offset:2304
	ds_write_b16_d16_hi v84, v4 offset:2576
	v_cvt_pk_bf16_f32 v4, v10, v11
	ds_write_b16 v84, v4 offset:2848
	ds_write_b16_d16_hi v84, v4 offset:3120
	v_cvt_pk_bf16_f32 v4, v12, v13
	ds_write_b16 v84, v4 offset:4480
	ds_write_b16_d16_hi v84, v4 offset:4752
	v_cvt_pk_bf16_f32 v4, v14, v15
	ds_write_b16 v84, v4 offset:5024
	ds_write_b16_d16_hi v84, v4 offset:5296
	v_cvt_pk_bf16_f32 v4, v16, v17
	ds_write_b16 v84, v4 offset:6656
	ds_write_b16_d16_hi v84, v4 offset:6928
	v_cvt_pk_bf16_f32 v4, v18, v19
	ds_write_b16 v84, v4 offset:7200
	ds_write_b16_d16_hi v84, v4 offset:7472
	v_mad_u32_u24 v85, v212, s8, v92
	ds_read2_b64 v[4:7], v85 offset1:2
	s_waitcnt lgkmcnt(0)
	v_mfma_f32_32x32x16_bf16 v[4:19], v[20:23], v[4:7], 0
	ds_read2_b64 v[20:23], v85 offset0:4 offset1:6
	s_waitcnt lgkmcnt(0)
	v_mfma_f32_32x32x16_bf16 v[4:19], v[24:27], v[20:23], v[4:19]
	ds_read2_b64 v[20:23], v85 offset0:8 offset1:10
	s_waitcnt lgkmcnt(0)
	v_mfma_f32_32x32x16_bf16 v[4:19], v[32:35], v[20:23], v[4:19]
	ds_read2_b64 v[20:23], v85 offset0:12 offset1:14
	s_waitcnt lgkmcnt(0)
	v_mfma_f32_32x32x16_bf16 v[4:19], v[28:31], v[20:23], v[4:19]
	ds_read2_b64 v[20:23], v85 offset0:16 offset1:18
	s_waitcnt lgkmcnt(0)
	v_mfma_f32_32x32x16_bf16 v[4:19], v[36:39], v[20:23], v[4:19]
	ds_read2_b64 v[20:23], v85 offset0:20 offset1:22
	s_waitcnt lgkmcnt(0)
	v_mfma_f32_32x32x16_bf16 v[4:19], v[40:43], v[20:23], v[4:19]
	ds_read2_b64 v[20:23], v85 offset0:24 offset1:26
	s_waitcnt lgkmcnt(0)
	v_mfma_f32_32x32x16_bf16 v[4:19], v[48:51], v[20:23], v[4:19]
	ds_read2_b64 v[20:23], v85 offset0:28 offset1:30
	s_waitcnt lgkmcnt(0)
	v_mfma_f32_32x32x16_bf16 v[4:19], v[44:47], v[20:23], v[4:19]
	ds_read2_b64 v[20:23], v85 offset0:32 offset1:34
	s_waitcnt lgkmcnt(0)
	v_mfma_f32_32x32x16_bf16 v[4:19], v[52:55], v[20:23], v[4:19]
	ds_read2_b64 v[20:23], v85 offset0:36 offset1:38
	s_waitcnt lgkmcnt(0)
	v_mfma_f32_32x32x16_bf16 v[4:19], v[56:59], v[20:23], v[4:19]
	ds_read2_b64 v[20:23], v85 offset0:40 offset1:42
	s_waitcnt lgkmcnt(0)
	v_mfma_f32_32x32x16_bf16 v[4:19], v[64:67], v[20:23], v[4:19]
	ds_read2_b64 v[20:23], v85 offset0:44 offset1:46
	s_waitcnt lgkmcnt(0)
	v_mfma_f32_32x32x16_bf16 v[4:19], v[60:63], v[20:23], v[4:19]
	ds_read2_b64 v[20:23], v85 offset0:48 offset1:50
	s_waitcnt lgkmcnt(0)
	v_mfma_f32_32x32x16_bf16 v[4:19], v[68:71], v[20:23], v[4:19]
	ds_read2_b64 v[20:23], v85 offset0:52 offset1:54
	s_waitcnt lgkmcnt(0)
	v_mfma_f32_32x32x16_bf16 v[4:19], v[72:75], v[20:23], v[4:19]
	ds_read2_b64 v[20:23], v85 offset0:56 offset1:58
	s_waitcnt lgkmcnt(0)
	v_mfma_f32_32x32x16_bf16 v[4:19], v[76:79], v[20:23], v[4:19]
	ds_read2_b64 v[20:23], v85 offset0:60 offset1:62
	s_waitcnt lgkmcnt(0)
	v_mfma_f32_32x32x16_bf16 v[4:19], v[80:83], v[20:23], v[4:19]
	s_nop 11
	v_cvt_pk_bf16_f32 v4, v4, v5
	ds_write_b16 v84, v4 offset:192
	ds_write_b16_d16_hi v84, v4 offset:464
	v_cvt_pk_bf16_f32 v4, v6, v7
	ds_write_b16 v84, v4 offset:736
	ds_write_b16_d16_hi v84, v4 offset:1008
	v_cvt_pk_bf16_f32 v4, v8, v9
	ds_write_b16 v84, v4 offset:2368
	ds_write_b16_d16_hi v84, v4 offset:2640
	v_cvt_pk_bf16_f32 v4, v10, v11
	ds_write_b16 v84, v4 offset:2912
	ds_write_b16_d16_hi v84, v4 offset:3184
	v_cvt_pk_bf16_f32 v4, v12, v13
	ds_write_b16 v84, v4 offset:4544
	ds_write_b16_d16_hi v84, v4 offset:4816
	v_cvt_pk_bf16_f32 v4, v14, v15
	ds_write_b16 v84, v4 offset:5088
	ds_write_b16_d16_hi v84, v4 offset:5360
	v_cvt_pk_bf16_f32 v4, v16, v17
	ds_write_b16 v84, v4 offset:6720
	ds_write_b16_d16_hi v84, v4 offset:6992
	v_cvt_pk_bf16_f32 v4, v18, v19
	ds_write_b16 v84, v4 offset:7264
	ds_write_b16_d16_hi v84, v4 offset:7536
	v_mul_u32_u24_e32 v4, 0x110, v201
	v_add3_u32 v6, s4, v4, v2
	ds_read_b128 v[8:11], v6
	s_mulk_i32 s39, 0xc00
	s_mul_hi_u32 s41, s38, 0xc00
	s_waitcnt vmcnt(7)
	v_lshlrev_b32_e32 v14, 16, v160
	v_and_b32_e32 v15, 0xffff0000, v160
	s_waitcnt lgkmcnt(0)
	v_lshlrev_b32_e32 v12, 16, v8
	v_and_b32_e32 v13, 0xffff0000, v8
	s_add_i32 s41, s41, s39
	s_mulk_i32 s38, 0xc00
	v_pk_mul_f32 v[12:13], v[14:15], v[12:13]
	s_add_u32 s38, s36, s38
	v_cvt_pk_bf16_f32 v8, v12, v13
	v_lshlrev_b32_e32 v12, 16, v9
	v_and_b32_e32 v13, 0xffff0000, v9
	v_lshlrev_b32_e32 v14, 16, v161
	v_and_b32_e32 v15, 0xffff0000, v161
	s_addc_u32 s39, s37, s41
	v_pk_mul_f32 v[12:13], v[14:15], v[12:13]
	s_add_u32 s38, s38, s24
	v_mul_u32_u24_e32 v4, 0x600, v201
	v_cvt_pk_bf16_f32 v9, v12, v13
	v_lshlrev_b32_e32 v12, 16, v10
	v_and_b32_e32 v13, 0xffff0000, v10
	v_lshlrev_b32_e32 v14, 16, v162
	v_and_b32_e32 v15, 0xffff0000, v162
	s_addc_u32 s39, s39, 0
	v_lshlrev_b32_e32 v4, 1, v4
	v_mov_b32_e32 v5, v3
	v_pk_mul_f32 v[12:13], v[14:15], v[12:13]
	v_lshl_add_u64 v[4:5], s[38:39], 0, v[4:5]
	v_cvt_pk_bf16_f32 v10, v12, v13
	v_lshlrev_b32_e32 v12, 16, v11
	v_and_b32_e32 v13, 0xffff0000, v11
	v_lshlrev_b32_e32 v14, 16, v163
	v_and_b32_e32 v15, 0xffff0000, v163
	v_lshl_add_u64 v[4:5], v[4:5], 0, v[2:3]
	v_pk_mul_f32 v[12:13], v[14:15], v[12:13]
	s_waitcnt vmcnt(6)
	v_lshlrev_b32_e32 v14, 16, v156
	v_cvt_pk_bf16_f32 v11, v12, v13
	v_add_co_u32_e32 v12, vcc, s47, v4
	v_and_b32_e32 v15, 0xffff0000, v156
	s_nop 0
	v_addc_co_u32_e32 v13, vcc, 0, v5, vcc
	global_store_dwordx4 v[12:13], v[8:11], off offset:2048 sc1
	ds_read_b128 v[8:11], v6 offset:1088
	s_add_i32 s40, s40, s10
	s_add_i32 s14, s14, s28
	s_add_i32 s1, s1, s29
	s_cmpk_gt_i32 s40, 0xff
	s_waitcnt lgkmcnt(0)
	v_lshlrev_b32_e32 v12, 16, v8
	v_and_b32_e32 v13, 0xffff0000, v8
	v_pk_mul_f32 v[12:13], v[14:15], v[12:13]
	v_lshlrev_b32_e32 v14, 16, v157
	v_cvt_pk_bf16_f32 v8, v12, v13
	v_lshlrev_b32_e32 v12, 16, v9
	v_and_b32_e32 v13, 0xffff0000, v9
	v_and_b32_e32 v15, 0xffff0000, v157
	v_pk_mul_f32 v[12:13], v[14:15], v[12:13]
	v_lshlrev_b32_e32 v14, 16, v158
	v_cvt_pk_bf16_f32 v9, v12, v13
	v_lshlrev_b32_e32 v12, 16, v10
	v_and_b32_e32 v13, 0xffff0000, v10
	v_and_b32_e32 v15, 0xffff0000, v158
	v_pk_mul_f32 v[12:13], v[14:15], v[12:13]
	v_lshlrev_b32_e32 v14, 16, v159
	v_cvt_pk_bf16_f32 v10, v12, v13
	v_lshlrev_b32_e32 v12, 16, v11
	v_and_b32_e32 v13, 0xffff0000, v11
	v_and_b32_e32 v15, 0xffff0000, v159
	v_pk_mul_f32 v[12:13], v[14:15], v[12:13]
	s_waitcnt vmcnt(6)
	v_lshlrev_b32_e32 v14, 16, v152
	v_cvt_pk_bf16_f32 v11, v12, v13
	v_add_co_u32_e32 v12, vcc, s48, v4
	v_and_b32_e32 v15, 0xffff0000, v152
	s_nop 0
	v_addc_co_u32_e32 v13, vcc, 0, v5, vcc
	global_store_dwordx4 v[12:13], v[8:11], off offset:2048 sc1
	ds_read_b128 v[8:11], v6 offset:2176
	s_waitcnt lgkmcnt(0)
	v_lshlrev_b32_e32 v12, 16, v8
	v_and_b32_e32 v13, 0xffff0000, v8
	v_pk_mul_f32 v[12:13], v[14:15], v[12:13]
	v_lshlrev_b32_e32 v14, 16, v153
	v_cvt_pk_bf16_f32 v8, v12, v13
	v_lshlrev_b32_e32 v12, 16, v9
	v_and_b32_e32 v13, 0xffff0000, v9
	v_and_b32_e32 v15, 0xffff0000, v153
	v_pk_mul_f32 v[12:13], v[14:15], v[12:13]
	v_lshlrev_b32_e32 v14, 16, v154
	v_cvt_pk_bf16_f32 v9, v12, v13
	v_lshlrev_b32_e32 v12, 16, v10
	v_and_b32_e32 v13, 0xffff0000, v10
	v_and_b32_e32 v15, 0xffff0000, v154
	v_pk_mul_f32 v[12:13], v[14:15], v[12:13]
	v_lshlrev_b32_e32 v14, 16, v155
	v_cvt_pk_bf16_f32 v10, v12, v13
	v_lshlrev_b32_e32 v12, 16, v11
	v_and_b32_e32 v13, 0xffff0000, v11
	v_and_b32_e32 v15, 0xffff0000, v155
	v_pk_mul_f32 v[12:13], v[14:15], v[12:13]
	s_waitcnt vmcnt(6)
	v_lshlrev_b32_e32 v14, 16, v148
	v_cvt_pk_bf16_f32 v11, v12, v13
	v_add_co_u32_e32 v12, vcc, s49, v4
	v_and_b32_e32 v15, 0xffff0000, v148
	s_nop 0
	v_addc_co_u32_e32 v13, vcc, 0, v5, vcc
	global_store_dwordx4 v[12:13], v[8:11], off offset:2048 sc1
	ds_read_b128 v[8:11], v6 offset:3264
	s_waitcnt lgkmcnt(0)
	v_lshlrev_b32_e32 v12, 16, v8
	v_and_b32_e32 v13, 0xffff0000, v8
	v_pk_mul_f32 v[12:13], v[14:15], v[12:13]
	v_lshlrev_b32_e32 v14, 16, v149
	v_cvt_pk_bf16_f32 v8, v12, v13
	v_lshlrev_b32_e32 v12, 16, v9
	v_and_b32_e32 v13, 0xffff0000, v9
	v_and_b32_e32 v15, 0xffff0000, v149
	v_pk_mul_f32 v[12:13], v[14:15], v[12:13]
	v_lshlrev_b32_e32 v14, 16, v150
	v_cvt_pk_bf16_f32 v9, v12, v13
	v_lshlrev_b32_e32 v12, 16, v10
	v_and_b32_e32 v13, 0xffff0000, v10
	v_and_b32_e32 v15, 0xffff0000, v150
	v_pk_mul_f32 v[12:13], v[14:15], v[12:13]
	v_lshlrev_b32_e32 v14, 16, v151
	v_cvt_pk_bf16_f32 v10, v12, v13
	v_lshlrev_b32_e32 v12, 16, v11
	v_and_b32_e32 v13, 0xffff0000, v11
	v_and_b32_e32 v15, 0xffff0000, v151
	v_pk_mul_f32 v[12:13], v[14:15], v[12:13]
	s_waitcnt vmcnt(6)
	v_lshlrev_b32_e32 v14, 16, v144
	v_cvt_pk_bf16_f32 v11, v12, v13
	v_add_co_u32_e32 v12, vcc, s54, v4
	v_and_b32_e32 v15, 0xffff0000, v144
	s_nop 0
	v_addc_co_u32_e32 v13, vcc, 0, v5, vcc
	global_store_dwordx4 v[12:13], v[8:11], off offset:2048 sc1
	ds_read_b128 v[8:11], v6 offset:4352
	s_waitcnt lgkmcnt(0)
	v_lshlrev_b32_e32 v12, 16, v8
	v_and_b32_e32 v13, 0xffff0000, v8
	v_pk_mul_f32 v[12:13], v[14:15], v[12:13]
	v_lshlrev_b32_e32 v14, 16, v145
	v_cvt_pk_bf16_f32 v8, v12, v13
	v_lshlrev_b32_e32 v12, 16, v9
	v_and_b32_e32 v13, 0xffff0000, v9
	v_and_b32_e32 v15, 0xffff0000, v145
	v_pk_mul_f32 v[12:13], v[14:15], v[12:13]
	v_lshlrev_b32_e32 v14, 16, v146
	v_cvt_pk_bf16_f32 v9, v12, v13
	v_lshlrev_b32_e32 v12, 16, v10
	v_and_b32_e32 v13, 0xffff0000, v10
	v_and_b32_e32 v15, 0xffff0000, v146
	v_pk_mul_f32 v[12:13], v[14:15], v[12:13]
	v_lshlrev_b32_e32 v14, 16, v147
	v_cvt_pk_bf16_f32 v10, v12, v13
	v_lshlrev_b32_e32 v12, 16, v11
	v_and_b32_e32 v13, 0xffff0000, v11
	v_and_b32_e32 v15, 0xffff0000, v147
	v_pk_mul_f32 v[12:13], v[14:15], v[12:13]
	s_waitcnt vmcnt(6)
	v_lshlrev_b32_e32 v14, 16, v140
	v_cvt_pk_bf16_f32 v11, v12, v13
	v_add_co_u32_e32 v12, vcc, s94, v4
	v_and_b32_e32 v15, 0xffff0000, v140
	s_nop 0
	v_addc_co_u32_e32 v13, vcc, 0, v5, vcc
	global_store_dwordx4 v[12:13], v[8:11], off offset:2048 sc1
	ds_read_b128 v[8:11], v6 offset:5440
	s_waitcnt lgkmcnt(0)
	v_lshlrev_b32_e32 v12, 16, v8
	v_and_b32_e32 v13, 0xffff0000, v8
	v_pk_mul_f32 v[12:13], v[14:15], v[12:13]
	v_lshlrev_b32_e32 v14, 16, v141
	v_cvt_pk_bf16_f32 v8, v12, v13
	v_lshlrev_b32_e32 v12, 16, v9
	v_and_b32_e32 v13, 0xffff0000, v9
	v_and_b32_e32 v15, 0xffff0000, v141
	v_pk_mul_f32 v[12:13], v[14:15], v[12:13]
	v_lshlrev_b32_e32 v14, 16, v142
	v_cvt_pk_bf16_f32 v9, v12, v13
	v_lshlrev_b32_e32 v12, 16, v10
	v_and_b32_e32 v13, 0xffff0000, v10
	v_and_b32_e32 v15, 0xffff0000, v142
	v_pk_mul_f32 v[12:13], v[14:15], v[12:13]
	v_lshlrev_b32_e32 v14, 16, v143
	v_cvt_pk_bf16_f32 v10, v12, v13
	v_lshlrev_b32_e32 v12, 16, v11
	v_and_b32_e32 v13, 0xffff0000, v11
	v_and_b32_e32 v15, 0xffff0000, v143
	v_pk_mul_f32 v[12:13], v[14:15], v[12:13]
	s_waitcnt vmcnt(6)
	v_lshlrev_b32_e32 v14, 16, v136
	v_cvt_pk_bf16_f32 v11, v12, v13
	v_add_co_u32_e32 v12, vcc, s97, v4
	v_and_b32_e32 v15, 0xffff0000, v136
	s_nop 0
	v_addc_co_u32_e32 v13, vcc, 0, v5, vcc
	global_store_dwordx4 v[12:13], v[8:11], off offset:2048 sc1
	ds_read_b128 v[8:11], v6 offset:6528
	s_waitcnt lgkmcnt(0)
	v_lshlrev_b32_e32 v12, 16, v8
	v_and_b32_e32 v13, 0xffff0000, v8
	v_pk_mul_f32 v[12:13], v[14:15], v[12:13]
	v_lshlrev_b32_e32 v14, 16, v137
	v_cvt_pk_bf16_f32 v8, v12, v13
	v_lshlrev_b32_e32 v12, 16, v9
	v_and_b32_e32 v13, 0xffff0000, v9
	v_and_b32_e32 v15, 0xffff0000, v137
	v_pk_mul_f32 v[12:13], v[14:15], v[12:13]
	v_lshlrev_b32_e32 v14, 16, v138
	v_cvt_pk_bf16_f32 v9, v12, v13
	v_lshlrev_b32_e32 v12, 16, v10
	v_and_b32_e32 v13, 0xffff0000, v10
	v_and_b32_e32 v15, 0xffff0000, v138
	v_pk_mul_f32 v[12:13], v[14:15], v[12:13]
	v_lshlrev_b32_e32 v14, 16, v139
	v_cvt_pk_bf16_f32 v10, v12, v13
	v_lshlrev_b32_e32 v12, 16, v11
	v_and_b32_e32 v13, 0xffff0000, v11
	v_and_b32_e32 v15, 0xffff0000, v139
	v_pk_mul_f32 v[12:13], v[14:15], v[12:13]
	s_nop 0
	v_cvt_pk_bf16_f32 v11, v12, v13
	v_add_co_u32_e32 v12, vcc, s55, v4
	s_nop 1
	v_addc_co_u32_e32 v13, vcc, 0, v5, vcc
	global_store_dwordx4 v[12:13], v[8:11], off offset:2048 sc1
	ds_read_b128 v[6:9], v6 offset:7616
	s_waitcnt vmcnt(7)
	v_lshlrev_b32_e32 v12, 16, v132
	v_and_b32_e32 v13, 0xffff0000, v132
	v_add_co_u32_e32 v4, vcc, 0xc615000, v4
	s_waitcnt lgkmcnt(0)
	v_lshlrev_b32_e32 v10, 16, v6
	v_and_b32_e32 v11, 0xffff0000, v6
	v_pk_mul_f32 v[10:11], v[12:13], v[10:11]
	v_lshlrev_b32_e32 v12, 16, v133
	v_cvt_pk_bf16_f32 v6, v10, v11
	v_lshlrev_b32_e32 v10, 16, v7
	v_and_b32_e32 v11, 0xffff0000, v7
	v_and_b32_e32 v13, 0xffff0000, v133
	v_pk_mul_f32 v[10:11], v[12:13], v[10:11]
	v_lshlrev_b32_e32 v12, 16, v134
	v_cvt_pk_bf16_f32 v7, v10, v11
	v_lshlrev_b32_e32 v10, 16, v8
	v_and_b32_e32 v11, 0xffff0000, v8
	v_and_b32_e32 v13, 0xffff0000, v134
	v_pk_mul_f32 v[10:11], v[12:13], v[10:11]
	v_lshlrev_b32_e32 v12, 16, v135
	v_cvt_pk_bf16_f32 v8, v10, v11
	v_lshlrev_b32_e32 v10, 16, v9
	v_and_b32_e32 v11, 0xffff0000, v9
	v_and_b32_e32 v13, 0xffff0000, v135
	v_pk_mul_f32 v[10:11], v[12:13], v[10:11]
	v_addc_co_u32_e32 v5, vcc, 0, v5, vcc
	v_cvt_pk_bf16_f32 v9, v10, v11
	global_store_dwordx4 v[4:5], v[6:9], off offset:2048 sc1
	s_barrier
	s_cbranch_scc0 .LBB0_547

.LBB0_550:
	v_cndmask_b32_e64 v118, v239, v237, s[70:71]
	v_max_f32_e32 v118, v118, v118
	v_max_f32_e32 v67, v67, v67
	v_min_f32_e32 v157, v67, v118
	v_cndmask_b32_e64 v67, v239, v237, s[68:69]
	v_max_f32_e32 v67, v67, v67
	v_max_f32_e32 v66, v66, v66
	v_min_f32_e32 v158, v66, v67
	v_cndmask_b32_e64 v66, v239, v237, s[66:67]
	v_max_f32_e32 v66, v66, v66
	v_max_f32_e32 v65, v65, v65
	v_min_f32_e32 v65, v65, v66
	v_cndmask_b32_e64 v66, v239, v237, s[64:65]
	v_max_f32_e32 v66, v66, v66
	v_max_f32_e32 v64, v64, v64
	v_min_f32_e32 v64, v64, v66
	v_cndmask_b32_e64 v66, v239, v237, s[62:63]
	v_max_f32_e32 v66, v66, v66
	v_max_f32_e32 v63, v63, v63
	v_min_f32_e32 v159, v63, v66
	v_cndmask_b32_e64 v63, v239, v237, s[60:61]
	v_max_f32_e32 v63, v63, v63
	v_max_f32_e32 v62, v62, v62
	v_min_f32_e32 v160, v62, v63
	v_cndmask_b32_e64 v62, v239, v237, s[58:59]
	v_max_f32_e32 v62, v62, v62
	v_max_f32_e32 v61, v61, v61
	v_min_f32_e32 v61, v61, v62
	v_cndmask_b32_e64 v62, v239, v237, s[56:57]
	v_max_f32_e32 v62, v62, v62
	v_max_f32_e32 v60, v60, v60
	v_min_f32_e32 v60, v60, v62
	v_cndmask_b32_e64 v62, v239, v237, s[54:55]
	v_max_f32_e32 v62, v62, v62
	v_max_f32_e32 v59, v59, v59
	v_min_f32_e32 v161, v59, v62
	v_cndmask_b32_e64 v59, v239, v237, s[52:53]
	v_max_f32_e32 v59, v59, v59
	v_max_f32_e32 v58, v58, v58
	v_min_f32_e32 v162, v58, v59
	v_cndmask_b32_e64 v58, v239, v237, s[50:51]
	v_max_f32_e32 v58, v58, v58
	v_max_f32_e32 v57, v57, v57
	v_min_f32_e32 v57, v57, v58
	v_cndmask_b32_e64 v58, v239, v237, s[48:49]
	v_max_f32_e32 v58, v58, v58
	v_max_f32_e32 v56, v56, v56
	v_min_f32_e32 v56, v56, v58
	v_cndmask_b32_e64 v58, v239, v237, s[46:47]
	v_max_f32_e32 v58, v58, v58
	v_max_f32_e32 v55, v55, v55
	v_min_f32_e32 v163, v55, v58
	v_cndmask_b32_e64 v55, v239, v237, s[44:45]
	v_max_f32_e32 v55, v55, v55
	v_max_f32_e32 v54, v54, v54
	v_min_f32_e32 v164, v54, v55
	v_cndmask_b32_e64 v54, v239, v237, s[42:43]
	v_max_f32_e32 v54, v54, v54
	v_max_f32_e32 v53, v53, v53
	v_min_f32_e32 v53, v53, v54
	v_cndmask_b32_e64 v54, v239, v237, s[40:41]
	v_max_f32_e32 v54, v54, v54
	v_max_f32_e32 v52, v52, v52
	v_min_f32_e32 v52, v52, v54
	v_max3_f32 v54, v68, s76, v69
	v_max3_f32 v54, v54, v70, v71
	v_max3_f32 v54, v54, v72, v73
	v_max3_f32 v54, v54, v74, v75
	v_max3_f32 v54, v54, v76, v77
	v_max3_f32 v54, v54, v78, v79
	v_max3_f32 v54, v54, v80, v81
	v_max3_f32 v54, v54, v82, v83
	v_max3_f32 v54, v54, v36, v37
	v_max3_f32 v54, v54, v38, v39
	v_max3_f32 v54, v54, v40, v41
	v_max3_f32 v54, v54, v42, v43
	v_max3_f32 v54, v54, v44, v45
	v_max3_f32 v54, v54, v46, v47
	v_max3_f32 v54, v54, v48, v49
	v_max3_f32 v54, v54, v50, v51
	v_max3_f32 v54, v54, v20, v21
	v_max3_f32 v54, v54, v22, v23
	v_max3_f32 v54, v54, v24, v25
	v_max3_f32 v54, v54, v26, v27
	v_max3_f32 v54, v54, v28, v29
	v_max3_f32 v54, v54, v30, v31
	v_max3_f32 v54, v54, v32, v33
	v_max3_f32 v54, v54, v34, v35
	v_max3_f32 v54, v54, v4, v5
	v_max3_f32 v54, v54, v6, v7
	v_max3_f32 v54, v54, v8, v9
	v_max3_f32 v54, v54, v10, v11
	v_max3_f32 v54, v54, v12, v13
	v_max3_f32 v54, v54, v14, v15
	v_max3_f32 v54, v54, v16, v17
	v_max3_f32 v54, v54, v18, v19
	v_max3_f32 v54, v54, v52, v53
	v_max3_f32 v54, v54, v164, v163
	v_max3_f32 v54, v54, v56, v57
	v_max3_f32 v54, v54, v162, v161
	v_max3_f32 v54, v54, v60, v61
	v_max3_f32 v54, v54, v160, v159
	v_cmp_lt_i32_e32 vcc, v236, v235
	v_max3_f32 v54, v54, v64, v65
	v_max3_f32 v54, v54, v158, v157
	v_cndmask_b32_e32 v55, v231, v236, vcc
	v_lshlrev_b32_e32 v155, 2, v55
	ds_bpermute_b32 v55, v155, v54
	v_mul_f32_e32 v156, 0x3fb8aa3b, v154
	s_waitcnt lgkmcnt(0)
	v_max3_f32 v165, v54, v55, v156
	v_sub_f32_e32 v62, v72, v165
	v_sub_f32_e32 v72, v80, v165
	v_sub_f32_e32 v66, v74, v165
	v_exp_f32_e32 v74, v72
	v_sub_f32_e32 v72, v81, v165
	v_sub_f32_e32 v67, v75, v165
	v_exp_f32_e32 v75, v72
	v_sub_f32_e32 v72, v82, v165
	v_sub_f32_e32 v58, v70, v165
	v_sub_f32_e32 v70, v78, v165
	v_exp_f32_e32 v78, v72
	v_sub_f32_e32 v72, v83, v165
	v_sub_f32_e32 v42, v42, v165
	v_sub_f32_e32 v59, v71, v165
	v_sub_f32_e32 v71, v79, v165
	v_exp_f32_e32 v79, v72
	v_exp_f32_e32 v72, v42
	v_sub_f32_e32 v42, v43, v165
	v_sub_f32_e32 v63, v73, v165
	v_exp_f32_e32 v73, v42
	v_sub_f32_e32 v42, v44, v165
	v_sub_f32_e32 v54, v68, v165
	v_sub_f32_e32 v68, v76, v165
	v_exp_f32_e32 v76, v42
	v_sub_f32_e32 v42, v45, v165
	v_sub_f32_e32 v55, v69, v165
	v_sub_f32_e32 v69, v77, v165
	v_exp_f32_e32 v77, v42
	v_sub_f32_e32 v42, v46, v165
	v_exp_f32_e32 v80, v42
	v_sub_f32_e32 v42, v47, v165
	v_exp_f32_e32 v81, v42
	v_sub_f32_e32 v42, v48, v165
	v_exp_f32_e32 v82, v42
	v_sub_f32_e32 v42, v49, v165
	v_exp_f32_e32 v83, v42
	v_sub_f32_e32 v42, v50, v165
	v_exp_f32_e32 v122, v42
	v_sub_f32_e32 v42, v51, v165
	v_sub_f32_e32 v20, v20, v165
	v_exp_f32_e32 v123, v42
	v_exp_f32_e32 v42, v20
	v_sub_f32_e32 v20, v21, v165
	v_sub_f32_e32 v4, v4, v165
	v_exp_f32_e32 v43, v20
	v_sub_f32_e32 v20, v22, v165
	v_exp_f32_e32 v48, v4
	v_sub_f32_e32 v4, v5, v165
	v_exp_f32_e32 v44, v20
	v_sub_f32_e32 v20, v23, v165
	v_exp_f32_e32 v49, v4
	v_sub_f32_e32 v4, v6, v165
	v_exp_f32_e32 v45, v20
	v_sub_f32_e32 v20, v24, v165
	v_exp_f32_e32 v118, v4
	v_sub_f32_e32 v4, v7, v165
	v_exp_f32_e32 v46, v20
	v_sub_f32_e32 v20, v25, v165
	v_exp_f32_e32 v119, v4
	v_sub_f32_e32 v4, v8, v165
	v_exp_f32_e32 v47, v20
	v_sub_f32_e32 v20, v26, v165
	v_exp_f32_e32 v124, v4
	v_sub_f32_e32 v4, v9, v165
	v_exp_f32_e32 v50, v20
	v_sub_f32_e32 v20, v27, v165
	v_exp_f32_e32 v125, v4
	v_sub_f32_e32 v4, v10, v165
	v_exp_f32_e32 v51, v20
	v_sub_f32_e32 v20, v28, v165
	v_exp_f32_e32 v128, v4
	v_sub_f32_e32 v4, v11, v165
	v_exp_f32_e32 v120, v20
	v_sub_f32_e32 v20, v29, v165
	v_exp_f32_e32 v129, v4
	v_sub_f32_e32 v4, v12, v165
	v_exp_f32_e32 v121, v20
	v_sub_f32_e32 v20, v30, v165
	v_exp_f32_e32 v12, v4
	v_sub_f32_e32 v4, v13, v165
	v_exp_f32_e32 v126, v20
	v_sub_f32_e32 v20, v31, v165
	v_exp_f32_e32 v13, v4
	v_sub_f32_e32 v4, v14, v165
	v_exp_f32_e32 v127, v20
	v_sub_f32_e32 v20, v32, v165
	v_exp_f32_e32 v14, v4
	v_sub_f32_e32 v4, v15, v165
	v_exp_f32_e32 v130, v20
	v_sub_f32_e32 v20, v33, v165
	v_exp_f32_e32 v15, v4
	v_sub_f32_e32 v4, v16, v165
	v_exp_f32_e32 v131, v20
	v_sub_f32_e32 v20, v34, v165
	v_exp_f32_e32 v16, v4
	v_sub_f32_e32 v4, v17, v165
	v_exp_f32_e32 v148, v20
	v_sub_f32_e32 v20, v35, v165
	v_exp_f32_e32 v17, v4
	v_sub_f32_e32 v4, v18, v165
	v_exp_f32_e32 v149, v20
	v_exp_f32_e32 v18, v4
	v_sub_f32_e32 v4, v19, v165
	v_sub_f32_e32 v20, v60, v165
	v_exp_f32_e32 v19, v4
	v_sub_f32_e32 v4, v52, v165
	v_exp_f32_e32 v52, v20
	v_sub_f32_e32 v20, v61, v165
	v_sub_f32_e32 v5, v53, v165
	v_exp_f32_e32 v53, v20
	v_sub_f32_e32 v20, v160, v165
	v_sub_f32_e32 v8, v56, v165
	v_exp_f32_e32 v56, v20
	v_sub_f32_e32 v20, v159, v165
	v_exp_f32_e32 v54, v54
	v_sub_f32_e32 v9, v57, v165
	v_exp_f32_e32 v57, v20
	v_sub_f32_e32 v20, v64, v165
	v_exp_f32_e32 v55, v55
	v_exp_f32_e32 v60, v20
	v_sub_f32_e32 v20, v65, v165
	v_exp_f32_e32 v58, v58
	v_exp_f32_e32 v61, v20
	v_sub_f32_e32 v20, v158, v165
	v_exp_f32_e32 v59, v59
	v_exp_f32_e32 v64, v20
	v_sub_f32_e32 v20, v157, v165
	v_exp_f32_e32 v62, v62
	v_exp_f32_e32 v65, v20
	v_add_f32_e32 v20, 0, v54
	v_exp_f32_e32 v63, v63
	v_add_f32_e32 v20, v55, v20
	v_exp_f32_e32 v66, v66
	v_add_f32_e32 v20, v58, v20
	v_exp_f32_e32 v67, v67
	v_add_f32_e32 v20, v59, v20
	v_exp_f32_e32 v68, v68
	v_add_f32_e32 v20, v62, v20
	v_exp_f32_e32 v69, v69
	v_add_f32_e32 v20, v63, v20
	v_exp_f32_e32 v70, v70
	v_add_f32_e32 v20, v66, v20
	v_exp_f32_e32 v71, v71
	v_add_f32_e32 v20, v67, v20
	v_add_f32_e32 v20, v68, v20
	v_add_f32_e32 v20, v69, v20
	v_add_f32_e32 v20, v70, v20
	v_sub_f32_e32 v36, v36, v165
	v_add_f32_e32 v20, v71, v20
	v_exp_f32_e32 v36, v36
	v_sub_f32_e32 v37, v37, v165
	v_add_f32_e32 v20, v74, v20
	v_exp_f32_e32 v37, v37
	v_sub_f32_e32 v38, v38, v165
	v_add_f32_e32 v20, v75, v20
	v_exp_f32_e32 v38, v38
	v_sub_f32_e32 v39, v39, v165
	v_add_f32_e32 v20, v78, v20
	v_exp_f32_e32 v39, v39
	v_sub_f32_e32 v40, v40, v165
	v_add_f32_e32 v20, v79, v20
	v_exp_f32_e32 v40, v40
	v_sub_f32_e32 v41, v41, v165
	v_add_f32_e32 v20, v36, v20
	v_exp_f32_e32 v41, v41
	v_add_f32_e32 v20, v37, v20
	v_add_f32_e32 v20, v38, v20
	v_add_f32_e32 v20, v39, v20
	v_add_f32_e32 v20, v40, v20
	v_add_f32_e32 v20, v41, v20
	v_add_f32_e32 v20, v72, v20
	v_add_f32_e32 v20, v73, v20
	v_add_f32_e32 v20, v76, v20
	v_add_f32_e32 v20, v77, v20
	v_add_f32_e32 v20, v80, v20
	v_add_f32_e32 v20, v81, v20
	v_add_f32_e32 v20, v82, v20
	v_add_f32_e32 v20, v83, v20
	v_add_f32_e32 v20, v122, v20
	v_add_f32_e32 v20, v123, v20
	v_add_f32_e32 v20, v42, v20
	v_add_f32_e32 v20, v43, v20
	v_add_f32_e32 v20, v44, v20
	v_add_f32_e32 v20, v45, v20
	v_add_f32_e32 v20, v46, v20
	v_add_f32_e32 v20, v47, v20
	v_add_f32_e32 v20, v50, v20
	v_add_f32_e32 v20, v51, v20
	v_add_f32_e32 v20, v120, v20
	v_add_f32_e32 v20, v121, v20
	v_add_f32_e32 v20, v126, v20
	v_add_f32_e32 v20, v127, v20
	v_add_f32_e32 v20, v130, v20
	v_add_f32_e32 v20, v131, v20
	v_add_f32_e32 v20, v148, v20
	v_add_f32_e32 v20, v149, v20
	v_add_f32_e32 v20, v48, v20
	v_add_f32_e32 v20, v49, v20
	v_add_f32_e32 v20, v118, v20
	v_add_f32_e32 v20, v119, v20
	v_add_f32_e32 v20, v124, v20
	v_add_f32_e32 v20, v125, v20
	v_add_f32_e32 v20, v128, v20
	v_add_f32_e32 v20, v129, v20
	v_add_f32_e32 v20, v12, v20
	v_add_f32_e32 v20, v13, v20
	v_add_f32_e32 v20, v14, v20
	v_add_f32_e32 v20, v15, v20
	v_exp_f32_e32 v4, v4
	v_add_f32_e32 v20, v16, v20
	v_exp_f32_e32 v5, v5
	v_sub_f32_e32 v6, v164, v165
	v_add_f32_e32 v20, v17, v20
	v_exp_f32_e32 v6, v6
	v_sub_f32_e32 v7, v163, v165
	v_add_f32_e32 v20, v18, v20
	v_exp_f32_e32 v7, v7
	v_add_f32_e32 v20, v19, v20
	v_exp_f32_e32 v8, v8
	v_add_f32_e32 v20, v4, v20
	v_exp_f32_e32 v9, v9
	v_sub_f32_e32 v10, v162, v165
	v_add_f32_e32 v20, v5, v20
	v_exp_f32_e32 v10, v10
	v_sub_f32_e32 v11, v161, v165
	v_add_f32_e32 v20, v6, v20
	v_exp_f32_e32 v11, v11
	v_add_f32_e32 v20, v7, v20
	v_add_f32_e32 v20, v8, v20
	v_add_f32_e32 v20, v9, v20
	v_add_f32_e32 v20, v10, v20
	v_add_f32_e32 v20, v11, v20
	v_add_f32_e32 v20, v52, v20
	v_add_f32_e32 v20, v53, v20
	v_add_f32_e32 v20, v56, v20
	v_add_f32_e32 v20, v57, v20
	v_add_f32_e32 v20, v60, v20
	v_add_f32_e32 v20, v61, v20
	v_add_f32_e32 v20, v64, v20
	v_add_f32_e32 v20, v65, v20
	ds_bpermute_b32 v21, v155, v20
	v_fma_f32 v22, v154, s18, -v165
	v_exp_f32_e32 v22, v22
	v_or_b32_e32 v157, 32, v153
	s_waitcnt lgkmcnt(0)
	v_add_f32_e32 v20, v20, v21
	v_add_f32_e32 v20, v22, v20
	v_div_scale_f32 v21, s[40:41], v20, v20, 1.0
	v_rcp_f32_e32 v22, v21
	s_add_u32 s40, s81, s90
	s_addc_u32 s41, s9, s91
	v_fma_f32 v23, -v21, v22, 1.0
	v_fmac_f32_e32 v22, v23, v22
	v_div_scale_f32 v23, vcc, 1.0, v20, 1.0
	v_mul_f32_e32 v24, v23, v22
	v_fma_f32 v25, -v21, v24, v23
	v_fmac_f32_e32 v24, v25, v22
	v_fma_f32 v21, -v21, v24, v23
	v_div_fmas_f32 v21, v21, v22, v24
	v_div_fixup_f32 v158, v21, v20, 1.0
	v_pk_mul_f32 v[20:21], v[54:55], v[158:159] op_sel_hi:[1,0]
	v_pk_mul_f32 v[22:23], v[58:59], v[158:159] op_sel_hi:[1,0]
	v_pk_mul_f32 v[24:25], v[62:63], v[158:159] op_sel_hi:[1,0]
	v_pk_mul_f32 v[26:27], v[66:67], v[158:159] op_sel_hi:[1,0]
	v_pk_mul_f32 v[28:29], v[68:69], v[158:159] op_sel_hi:[1,0]
	v_pk_mul_f32 v[30:31], v[70:71], v[158:159] op_sel_hi:[1,0]
	v_pk_mul_f32 v[34:35], v[78:79], v[158:159] op_sel_hi:[1,0]
	v_pk_mul_f32 v[32:33], v[74:75], v[158:159] op_sel_hi:[1,0]
	v_cvt_pk_bf16_f32 v20, v20, v21
	v_cvt_pk_bf16_f32 v21, v22, v23
	v_cvt_pk_bf16_f32 v22, v24, v25
	v_cvt_pk_bf16_f32 v23, v26, v27
	v_cvt_pk_bf16_f32 v24, v28, v29
	v_cvt_pk_bf16_f32 v25, v30, v31
	v_cvt_pk_bf16_f32 v27, v34, v35
	v_pk_mul_f32 v[28:29], v[36:37], v[158:159] op_sel_hi:[1,0]
	v_pk_mul_f32 v[30:31], v[38:39], v[158:159] op_sel_hi:[1,0]
	v_pk_mul_f32 v[34:35], v[40:41], v[158:159] op_sel_hi:[1,0]
	v_pk_mul_f32 v[36:37], v[72:73], v[158:159] op_sel_hi:[1,0]
	v_pk_mul_f32 v[38:39], v[76:77], v[158:159] op_sel_hi:[1,0]
	v_pk_mul_f32 v[40:41], v[80:81], v[158:159] op_sel_hi:[1,0]
	v_cvt_pk_bf16_f32 v26, v32, v33
	v_cvt_pk_bf16_f32 v32, v28, v29
	v_cvt_pk_bf16_f32 v34, v34, v35
	v_cvt_pk_bf16_f32 v35, v36, v37
	v_cvt_pk_bf16_f32 v28, v38, v39
	v_cvt_pk_bf16_f32 v29, v40, v41
	v_pk_mul_f32 v[36:37], v[42:43], v[158:159] op_sel_hi:[1,0]
	v_pk_mul_f32 v[38:39], v[44:45], v[158:159] op_sel_hi:[1,0]
	v_pk_mul_f32 v[40:41], v[46:47], v[158:159] op_sel_hi:[1,0]
	v_pk_mul_f32 v[44:45], v[120:121], v[158:159] op_sel_hi:[1,0]
	v_cvt_pk_bf16_f32 v36, v36, v37
	v_cvt_pk_bf16_f32 v37, v38, v39
	v_cvt_pk_bf16_f32 v38, v40, v41
	v_cvt_pk_bf16_f32 v40, v44, v45
	v_pk_mul_f32 v[44:45], v[48:49], v[158:159] op_sel_hi:[1,0]
	v_pk_mul_f32 v[12:13], v[12:13], v[158:159] op_sel_hi:[1,0]
	v_cvt_pk_bf16_f32 v48, v44, v45
	v_cvt_pk_bf16_f32 v44, v12, v13
	v_ashrrev_i32_e32 v12, 2, v152
	v_and_b32_e32 v12, -8, v12
	v_add_u32_e32 v76, 0, v12
	v_mad_u32_u24 v12, v153, s8, v76
	v_pk_mul_f32 v[14:15], v[14:15], v[158:159] op_sel_hi:[1,0]
	v_add_u32_e32 v77, 0x9000, v12
	v_cvt_pk_bf16_f32 v45, v14, v15
	ds_read2_b64 v[12:15], v77 offset1:2
	v_pk_mul_f32 v[46:47], v[126:127], v[158:159] op_sel_hi:[1,0]
	v_pk_mul_f32 v[58:59], v[122:123], v[158:159] op_sel_hi:[1,0]
	v_cvt_pk_bf16_f32 v41, v46, v47
	v_pk_mul_f32 v[46:47], v[118:119], v[158:159] op_sel_hi:[1,0]
	v_pk_mul_f32 v[16:17], v[16:17], v[158:159] op_sel_hi:[1,0]
	v_pk_mul_f32 v[18:19], v[18:19], v[158:159] op_sel_hi:[1,0]
	v_pk_mul_f32 v[54:55], v[82:83], v[158:159] op_sel_hi:[1,0]
	v_cvt_pk_bf16_f32 v33, v30, v31
	v_cvt_pk_bf16_f32 v31, v58, v59
	v_cvt_pk_bf16_f32 v49, v46, v47
	v_cvt_pk_bf16_f32 v46, v16, v17
	v_cvt_pk_bf16_f32 v47, v18, v19
	v_pk_mul_f32 v[58:59], v[4:5], v[158:159] op_sel_hi:[1,0]
	v_pk_mul_f32 v[62:63], v[6:7], v[158:159] op_sel_hi:[1,0]
	v_pk_mul_f32 v[66:67], v[8:9], v[158:159] op_sel_hi:[1,0]
	v_pk_mul_f32 v[68:69], v[10:11], v[158:159] op_sel_hi:[1,0]
	s_waitcnt lgkmcnt(0)
	v_mfma_f32_32x32x16_bf16 v[4:19], v[20:23], v[12:15], 0
	v_cvt_pk_bf16_f32 v30, v54, v55
	v_mul_f32_e64 v42, v50, v158
	v_mul_f32_e64 v43, v51, v158
	v_mul_f32_e64 v50, v130, v158
	v_mul_f32_e64 v51, v131, v158
	v_pk_mul_f32 v[54:55], v[148:149], v[158:159] op_sel_hi:[1,0]
	v_cvt_pk_bf16_f32 v39, v42, v43
	v_cvt_pk_bf16_f32 v42, v50, v51
	v_cvt_pk_bf16_f32 v43, v54, v55
	v_pk_mul_f32 v[50:51], v[124:125], v[158:159] op_sel_hi:[1,0]
	v_pk_mul_f32 v[54:55], v[128:129], v[158:159] op_sel_hi:[1,0]
	v_cvt_pk_bf16_f32 v50, v50, v51
	v_cvt_pk_bf16_f32 v51, v54, v55
	v_pk_mul_f32 v[70:71], v[52:53], v[158:159] op_sel_hi:[1,0]
	ds_read2_b64 v[52:55], v77 offset0:4 offset1:6
	s_waitcnt lgkmcnt(0)
	v_mfma_f32_32x32x16_bf16 v[4:19], v[24:27], v[52:55], v[4:19]
	ds_read2_b64 v[52:55], v77 offset0:8 offset1:10
	v_mul_f32_e64 v64, v64, v158
	v_mul_f32_e64 v65, v65, v158
	v_mul_f32_e64 v72, v56, v158
	v_mul_f32_e64 v73, v57, v158
	v_cvt_pk_bf16_f32 v57, v62, v63
	v_cvt_pk_bf16_f32 v63, v64, v65
	v_lshlrev_b32_e32 v65, 1, v152
	v_pk_mul_f32 v[74:75], v[60:61], v[158:159] op_sel_hi:[1,0]
	s_waitcnt lgkmcnt(0)
	v_mfma_f32_32x32x16_bf16 v[4:19], v[32:35], v[52:55], v[4:19]
	v_lshrrev_b32_e32 v52, 3, v152
	v_and_b32_e32 v64, 0xffffffc, v52
	ds_read2_b64 v[52:55], v77 offset0:12 offset1:14
	v_mul_lo_u32 v64, v64, s13
	v_and_b32_e32 v65, 62, v65
	v_cvt_pk_bf16_f32 v56, v58, v59
	v_cvt_pk_bf16_f32 v58, v66, v67
	v_cvt_pk_bf16_f32 v59, v68, v69
	v_cvt_pk_bf16_f32 v60, v70, v71
	v_cvt_pk_bf16_f32 v61, v72, v73
	v_cvt_pk_bf16_f32 v62, v74, v75
	v_add3_u32 v64, s2, v64, v65
	s_waitcnt lgkmcnt(0)
	v_mfma_f32_32x32x16_bf16 v[4:19], v[28:31], v[52:55], v[4:19]
	ds_read2_b64 v[52:55], v77 offset0:16 offset1:18
	s_waitcnt lgkmcnt(0)
	v_mfma_f32_32x32x16_bf16 v[4:19], v[36:39], v[52:55], v[4:19]
	ds_read2_b64 v[52:55], v77 offset0:20 offset1:22
	s_waitcnt lgkmcnt(0)
	v_mfma_f32_32x32x16_bf16 v[4:19], v[40:43], v[52:55], v[4:19]
	ds_read2_b64 v[52:55], v77 offset0:24 offset1:26
	s_waitcnt lgkmcnt(0)
	v_mfma_f32_32x32x16_bf16 v[4:19], v[48:51], v[52:55], v[4:19]
	ds_read2_b64 v[52:55], v77 offset0:28 offset1:30
	s_waitcnt lgkmcnt(0)
	v_mfma_f32_32x32x16_bf16 v[4:19], v[44:47], v[52:55], v[4:19]
	ds_read2_b64 v[52:55], v77 offset0:32 offset1:34
	s_waitcnt lgkmcnt(0)
	v_mfma_f32_32x32x16_bf16 v[4:19], v[56:59], v[52:55], v[4:19]
	ds_read2_b64 v[52:55], v77 offset0:36 offset1:38
	s_waitcnt lgkmcnt(0)
	v_mfma_f32_32x32x16_bf16 v[4:19], v[60:63], v[52:55], v[4:19]
	s_nop 11
	v_cvt_pk_bf16_f32 v4, v4, v5
	ds_write_b16 v64, v4
	ds_write_b16_d16_hi v64, v4 offset:144
	v_cvt_pk_bf16_f32 v4, v6, v7
	ds_write_b16 v64, v4 offset:288
	ds_write_b16_d16_hi v64, v4 offset:432
	v_cvt_pk_bf16_f32 v4, v8, v9
	ds_write_b16 v64, v4 offset:1152
	ds_write_b16_d16_hi v64, v4 offset:1296
	v_cvt_pk_bf16_f32 v4, v10, v11
	ds_write_b16 v64, v4 offset:1440
	ds_write_b16_d16_hi v64, v4 offset:1584
	v_cvt_pk_bf16_f32 v4, v12, v13
	ds_write_b16 v64, v4 offset:2304
	ds_write_b16_d16_hi v64, v4 offset:2448
	v_cvt_pk_bf16_f32 v4, v14, v15
	ds_write_b16 v64, v4 offset:2592
	ds_write_b16_d16_hi v64, v4 offset:2736
	v_cvt_pk_bf16_f32 v4, v16, v17
	ds_write_b16 v64, v4 offset:3456
	ds_write_b16_d16_hi v64, v4 offset:3600
	v_cvt_pk_bf16_f32 v4, v18, v19
	ds_write_b16 v64, v4 offset:3744
	ds_write_b16_d16_hi v64, v4 offset:3888
	v_mad_u32_u24 v4, v157, s8, v76
	v_add_u32_e32 v52, 0x9000, v4
	ds_read2_b64 v[4:7], v52 offset1:2
	s_waitcnt lgkmcnt(0)
	v_mfma_f32_32x32x16_bf16 v[4:19], v[20:23], v[4:7], 0
	ds_read2_b64 v[20:23], v52 offset0:4 offset1:6
	s_waitcnt lgkmcnt(0)
	v_mfma_f32_32x32x16_bf16 v[4:19], v[24:27], v[20:23], v[4:19]
	ds_read2_b64 v[20:23], v52 offset0:8 offset1:10
	s_waitcnt lgkmcnt(0)
	v_mfma_f32_32x32x16_bf16 v[4:19], v[32:35], v[20:23], v[4:19]
	ds_read2_b64 v[20:23], v52 offset0:12 offset1:14
	s_waitcnt lgkmcnt(0)
	v_mfma_f32_32x32x16_bf16 v[4:19], v[28:31], v[20:23], v[4:19]
	ds_read2_b64 v[20:23], v52 offset0:16 offset1:18
	s_waitcnt lgkmcnt(0)
	v_mfma_f32_32x32x16_bf16 v[4:19], v[36:39], v[20:23], v[4:19]
	ds_read2_b64 v[20:23], v52 offset0:20 offset1:22
	s_waitcnt lgkmcnt(0)
	v_mfma_f32_32x32x16_bf16 v[4:19], v[40:43], v[20:23], v[4:19]
	ds_read2_b64 v[20:23], v52 offset0:24 offset1:26
	s_waitcnt lgkmcnt(0)
	v_mfma_f32_32x32x16_bf16 v[4:19], v[48:51], v[20:23], v[4:19]
	ds_read2_b64 v[20:23], v52 offset0:28 offset1:30
	s_waitcnt lgkmcnt(0)
	v_mfma_f32_32x32x16_bf16 v[4:19], v[44:47], v[20:23], v[4:19]
	ds_read2_b64 v[20:23], v52 offset0:32 offset1:34
	s_waitcnt lgkmcnt(0)
	v_mfma_f32_32x32x16_bf16 v[4:19], v[56:59], v[20:23], v[4:19]
	ds_read2_b64 v[20:23], v52 offset0:36 offset1:38
	s_waitcnt lgkmcnt(0)
	v_mfma_f32_32x32x16_bf16 v[4:19], v[60:63], v[20:23], v[4:19]
	s_nop 11
	v_cvt_pk_bf16_f32 v4, v4, v5
	ds_write_b16 v64, v4 offset:64
	ds_write_b16_d16_hi v64, v4 offset:208
	v_cvt_pk_bf16_f32 v4, v6, v7
	ds_write_b16 v64, v4 offset:352
	ds_write_b16_d16_hi v64, v4 offset:496
	v_cvt_pk_bf16_f32 v4, v8, v9
	ds_write_b16 v64, v4 offset:1216
	ds_write_b16_d16_hi v64, v4 offset:1360
	v_cvt_pk_bf16_f32 v4, v10, v11
	ds_write_b16 v64, v4 offset:1504
	ds_write_b16_d16_hi v64, v4 offset:1648
	v_cvt_pk_bf16_f32 v4, v12, v13
	ds_write_b16 v64, v4 offset:2368
	ds_write_b16_d16_hi v64, v4 offset:2512
	v_cvt_pk_bf16_f32 v4, v14, v15
	ds_write_b16 v64, v4 offset:2656
	ds_write_b16_d16_hi v64, v4 offset:2800
	v_cvt_pk_bf16_f32 v4, v16, v17
	ds_write_b16 v64, v4 offset:3520
	ds_write_b16_d16_hi v64, v4 offset:3664
	v_cvt_pk_bf16_f32 v4, v18, v19
	ds_write_b16 v64, v4 offset:3808
	ds_write_b16_d16_hi v64, v4 offset:3952
	v_mul_lo_u32 v4, v150, s13
	v_lshlrev_b32_e32 v5, 4, v151
	s_mul_i32 s42, s95, 0xc00
	s_mul_hi_u32 s43, s24, 0xc00
	v_add3_u32 v18, s2, v4, v5
	s_add_i32 s43, s43, s42
	s_mul_i32 s42, s24, 0xc00
	ds_read_b128 v[4:7], v18
	s_add_u32 s40, s40, s42
	s_addc_u32 s41, s41, s43
	v_mov_b64_e32 v[148:149], s[40:41]
	v_mad_i64_i32 v[8:9], s[40:41], v150, s5, v[148:149]
	v_lshl_add_u64 v[12:13], v[116:117], 1, v[8:9]
	ds_read_b128 v[8:11], v18 offset:1152
	s_waitcnt lgkmcnt(1)
	v_lshlrev_b32_e32 v14, 16, v4
	v_and_b32_e32 v15, 0xffff0000, v4
	s_waitcnt vmcnt(11)
	v_lshlrev_b32_e32 v16, 16, v108
	v_and_b32_e32 v17, 0xffff0000, v108
	v_pk_mul_f32 v[14:15], v[16:17], v[14:15]
	v_lshlrev_b32_e32 v16, 16, v109
	v_cvt_pk_bf16_f32 v4, v14, v15
	v_lshlrev_b32_e32 v14, 16, v5
	v_and_b32_e32 v15, 0xffff0000, v5
	v_and_b32_e32 v17, 0xffff0000, v109
	v_pk_mul_f32 v[14:15], v[16:17], v[14:15]
	v_lshlrev_b32_e32 v16, 16, v110
	v_cvt_pk_bf16_f32 v5, v14, v15
	v_lshlrev_b32_e32 v14, 16, v6
	v_and_b32_e32 v15, 0xffff0000, v6
	v_and_b32_e32 v17, 0xffff0000, v110
	v_pk_mul_f32 v[14:15], v[16:17], v[14:15]
	v_lshlrev_b32_e32 v16, 16, v111
	v_cvt_pk_bf16_f32 v6, v14, v15
	v_lshlrev_b32_e32 v14, 16, v7
	v_and_b32_e32 v15, 0xffff0000, v7
	v_and_b32_e32 v17, 0xffff0000, v111
	v_pk_mul_f32 v[14:15], v[16:17], v[14:15]
	s_waitcnt vmcnt(9)
	v_lshlrev_b32_e32 v16, 16, v92
	v_cvt_pk_bf16_f32 v7, v14, v15
	global_store_dwordx4 v[12:13], v[4:7], off sc1
	v_add_co_u32_e32 v14, vcc, s33, v12
	s_waitcnt lgkmcnt(0)
	v_lshlrev_b32_e32 v4, 16, v8
	v_and_b32_e32 v5, 0xffff0000, v8
	v_lshlrev_b32_e32 v6, 16, v96
	v_and_b32_e32 v7, 0xffff0000, v96
	v_pk_mul_f32 v[4:5], v[6:7], v[4:5]
	v_lshlrev_b32_e32 v6, 16, v9
	v_and_b32_e32 v7, 0xffff0000, v9
	v_lshlrev_b32_e32 v8, 16, v97
	v_and_b32_e32 v9, 0xffff0000, v97
	v_pk_mul_f32 v[6:7], v[8:9], v[6:7]
	v_cvt_pk_bf16_f32 v4, v4, v5
	v_cvt_pk_bf16_f32 v5, v6, v7
	v_lshlrev_b32_e32 v6, 16, v10
	v_and_b32_e32 v7, 0xffff0000, v10
	v_lshlrev_b32_e32 v8, 16, v98
	v_and_b32_e32 v9, 0xffff0000, v98
	v_pk_mul_f32 v[6:7], v[8:9], v[6:7]
	v_lshlrev_b32_e32 v8, 16, v11
	v_and_b32_e32 v9, 0xffff0000, v11
	v_lshlrev_b32_e32 v10, 16, v99
	v_and_b32_e32 v11, 0xffff0000, v99
	v_pk_mul_f32 v[8:9], v[10:11], v[8:9]
	v_cvt_pk_bf16_f32 v6, v6, v7
	v_cvt_pk_bf16_f32 v7, v8, v9
	ds_read_b128 v[8:11], v18 offset:2304
	v_addc_co_u32_e32 v15, vcc, 0, v13, vcc
	global_store_dwordx4 v[14:15], v[4:7], off sc1
	ds_read_b128 v[4:7], v18 offset:3456
	s_waitcnt lgkmcnt(1)
	v_lshlrev_b32_e32 v14, 16, v8
	v_and_b32_e32 v15, 0xffff0000, v8
	v_and_b32_e32 v17, 0xffff0000, v92
	v_pk_mul_f32 v[14:15], v[16:17], v[14:15]
	v_lshlrev_b32_e32 v16, 16, v93
	v_cvt_pk_bf16_f32 v8, v14, v15
	v_lshlrev_b32_e32 v14, 16, v9
	v_and_b32_e32 v15, 0xffff0000, v9
	v_and_b32_e32 v17, 0xffff0000, v93
	v_pk_mul_f32 v[14:15], v[16:17], v[14:15]
	v_lshlrev_b32_e32 v16, 16, v94
	v_cvt_pk_bf16_f32 v9, v14, v15
	v_lshlrev_b32_e32 v14, 16, v10
	v_and_b32_e32 v15, 0xffff0000, v10
	v_and_b32_e32 v17, 0xffff0000, v94
	v_pk_mul_f32 v[14:15], v[16:17], v[14:15]
	v_lshlrev_b32_e32 v16, 16, v95
	v_cvt_pk_bf16_f32 v10, v14, v15
	v_lshlrev_b32_e32 v14, 16, v11
	v_and_b32_e32 v15, 0xffff0000, v11
	v_and_b32_e32 v17, 0xffff0000, v95
	v_pk_mul_f32 v[14:15], v[16:17], v[14:15]
	s_mov_b32 s40, 0x12000
	v_cvt_pk_bf16_f32 v11, v14, v15
	v_add_co_u32_e32 v14, vcc, s6, v12
	v_mov_b32_e32 v160, v2
	s_nop 0
	v_addc_co_u32_e32 v15, vcc, 0, v13, vcc
	global_store_dwordx4 v[14:15], v[8:11], off sc1
	s_or_b32 s42, s24, 64
	v_mov_b64_e32 v[150:151], s[92:93]
	s_waitcnt lgkmcnt(0)
	v_lshlrev_b32_e32 v8, 16, v4
	v_and_b32_e32 v9, 0xffff0000, v4
	s_waitcnt vmcnt(11)
	v_lshlrev_b32_e32 v10, 16, v84
	v_and_b32_e32 v11, 0xffff0000, v84
	v_pk_mul_f32 v[8:9], v[10:11], v[8:9]
	v_lshlrev_b32_e32 v10, 16, v85
	v_cvt_pk_bf16_f32 v4, v8, v9
	v_lshlrev_b32_e32 v8, 16, v5
	v_and_b32_e32 v9, 0xffff0000, v5
	v_and_b32_e32 v11, 0xffff0000, v85
	v_pk_mul_f32 v[8:9], v[10:11], v[8:9]
	v_lshlrev_b32_e32 v10, 16, v86
	v_cvt_pk_bf16_f32 v5, v8, v9
	v_lshlrev_b32_e32 v8, 16, v6
	v_and_b32_e32 v9, 0xffff0000, v6
	v_and_b32_e32 v11, 0xffff0000, v86
	v_pk_mul_f32 v[8:9], v[10:11], v[8:9]
	v_lshlrev_b32_e32 v10, 16, v87
	v_cvt_pk_bf16_f32 v6, v8, v9
	v_lshlrev_b32_e32 v8, 16, v7
	v_and_b32_e32 v9, 0xffff0000, v7
	v_and_b32_e32 v11, 0xffff0000, v87
	v_pk_mul_f32 v[8:9], v[10:11], v[8:9]
	s_nop 0
	v_cvt_pk_bf16_f32 v7, v8, v9
	v_add_co_u32_e32 v8, vcc, s40, v12
	s_nop 1
	v_addc_co_u32_e32 v9, vcc, 0, v13, vcc
	global_store_dwordx4 v[8:9], v[4:7], off sc1
	s_nop 0
	v_and_b32_e32 v161, 31, v160
	v_ashrrev_i32_e32 v162, 5, v160
	v_or_b32_e32 v4, s42, v161
	v_mad_u64_u32 v[4:5], s[40:41], v4, s16, v[150:151]
	v_lshlrev_b32_e32 v6, 3, v162
	v_add_u32_e32 v5, s94, v5
	v_ashrrev_i32_e32 v7, 31, v6
	v_lshl_add_u64 v[4:5], v[6:7], 1, v[4:5]
	global_load_dwordx4 v[128:131], v[4:5], off
	global_load_dwordx4 v[124:127], v[4:5], off offset:32
	global_load_dwordx4 v[120:123], v[4:5], off offset:64
	global_load_dwordx4 v[116:119], v[4:5], off offset:96
	s_mul_hi_u32 s40, s42, 0x1800
	v_ashrrev_i32_e32 v4, 31, v160
	s_add_i32 s40, s40, s94
	s_mulk_i32 s42, 0x1800
	v_lshrrev_b32_e32 v4, 29, v4
	s_add_u32 s41, s72, s42
	v_add_u32_e32 v6, v160, v4
	s_addc_u32 s42, s73, s40
	v_ashrrev_i32_e32 v157, 3, v6
	v_and_b32_e32 v6, -8, v6
	s_add_u32 s40, s41, s90
	v_sub_u32_e32 v158, v160, v6
	s_addc_u32 s41, s42, s91
	v_lshlrev_b32_e32 v6, 3, v158
	v_mov_b64_e32 v[4:5], s[40:41]
	v_ashrrev_i32_e32 v7, 31, v6
	v_mad_i64_i32 v[4:5], s[40:41], v157, s16, v[4:5]
	v_lshlrev_b64 v[152:153], 1, v[6:7]
	v_lshl_add_u64 v[4:5], v[4:5], 0, v[152:153]
	v_add_co_u32_e32 v6, vcc, s6, v4
	s_nop 1
	v_addc_co_u32_e32 v7, vcc, 0, v5, vcc
	global_load_dwordx4 v[108:111], v[4:5], off offset:2048
	global_load_dwordx4 v[96:99], v[6:7], off offset:2048
	v_add_co_u32_e32 v6, vcc, s7, v4
	s_nop 1
	v_addc_co_u32_e32 v7, vcc, 0, v5, vcc
	v_add_co_u32_e32 v4, vcc, s82, v4
	s_nop 1
	v_addc_co_u32_e32 v5, vcc, 0, v5, vcc
	global_load_dwordx4 v[92:95], v[6:7], off offset:2048
	global_load_dwordx4 v[84:87], v[4:5], off offset:2048
	v_ashrrev_i32_e32 v4, 1, v160
	v_and_b32_e32 v4, -16, v4
	v_add_u32_e32 v8, 0, v4
	v_or_b32_e32 v159, 32, v161
	v_mad_u32_u24 v9, v159, s13, v8
	ds_read_b128 v[4:7], v9
	s_waitcnt vmcnt(19) lgkmcnt(0)
	v_mfma_f32_32x32x16_bf16 v[36:51], v[4:7], v[144:147], 0
	ds_read_b128 v[4:7], v9 offset:32
	s_waitcnt vmcnt(18) lgkmcnt(0)
	v_mfma_f32_32x32x16_bf16 v[36:51], v[4:7], v[140:143], v[36:51]
	ds_read_b128 v[4:7], v9 offset:64
	s_waitcnt vmcnt(17) lgkmcnt(0)
	v_mfma_f32_32x32x16_bf16 v[36:51], v[4:7], v[136:139], v[36:51]
	ds_read_b128 v[4:7], v9 offset:96
	s_waitcnt vmcnt(16) lgkmcnt(0)
	v_mfma_f32_32x32x16_bf16 v[36:51], v[4:7], v[132:135], v[36:51]
	v_mad_u32_u24 v163, v161, s13, v8
	ds_read_b128 v[4:7], v163 offset:9216
	s_waitcnt lgkmcnt(0)
	v_mfma_f32_32x32x16_bf16 v[20:35], v[4:7], v[144:147], 0
	ds_read_b128 v[4:7], v163 offset:9248
	s_waitcnt lgkmcnt(0)
	v_mfma_f32_32x32x16_bf16 v[20:35], v[4:7], v[140:143], v[20:35]
	ds_read_b128 v[4:7], v163 offset:9280
	s_waitcnt lgkmcnt(0)
	v_mfma_f32_32x32x16_bf16 v[20:35], v[4:7], v[136:139], v[20:35]
	ds_read_b128 v[4:7], v163 offset:9312
	s_waitcnt lgkmcnt(0)
	v_mfma_f32_32x32x16_bf16 v[20:35], v[4:7], v[132:135], v[20:35]
	ds_read_b128 v[4:7], v163 offset:13824
	s_waitcnt lgkmcnt(0)
	v_mfma_f32_32x32x16_bf16 v[52:67], v[4:7], v[144:147], 0
	ds_read_b128 v[4:7], v163 offset:13856
	s_waitcnt lgkmcnt(0)
	v_mfma_f32_32x32x16_bf16 v[52:67], v[4:7], v[140:143], v[52:67]
	ds_read_b128 v[4:7], v163 offset:13888
	s_waitcnt lgkmcnt(0)
	v_mfma_f32_32x32x16_bf16 v[52:67], v[4:7], v[136:139], v[52:67]
	ds_read_b128 v[4:7], v163 offset:13920
	s_waitcnt lgkmcnt(0)
	v_mfma_f32_32x32x16_bf16 v[52:67], v[4:7], v[132:135], v[52:67]
	ds_read_b128 v[4:7], v163 offset:18432
	ds_read_b128 v[68:71], v163 offset:18464
	s_waitcnt lgkmcnt(1)
	v_mfma_f32_32x32x16_bf16 v[4:19], v[4:7], v[144:147], 0
	s_waitcnt lgkmcnt(0)
	v_mfma_f32_32x32x16_bf16 v[4:19], v[68:71], v[140:143], v[4:19]
	ds_read_b128 v[68:71], v163 offset:18496
	s_waitcnt lgkmcnt(0)
	v_mfma_f32_32x32x16_bf16 v[4:19], v[68:71], v[136:139], v[4:19]
	ds_read_b128 v[68:71], v163 offset:18528
	s_waitcnt lgkmcnt(0)
	v_mfma_f32_32x32x16_bf16 v[4:19], v[68:71], v[132:135], v[4:19]
	ds_read_b128 v[68:71], v163 offset:23040
	s_waitcnt lgkmcnt(0)
	v_mfma_f32_32x32x16_bf16 v[68:83], v[68:71], v[144:147], 0
	ds_read_b128 v[144:147], v163 offset:23072
	s_waitcnt lgkmcnt(0)
	v_mfma_f32_32x32x16_bf16 v[68:83], v[144:147], v[140:143], v[68:83]
	ds_read_b128 v[140:143], v163 offset:23104
	s_waitcnt lgkmcnt(0)
	v_mfma_f32_32x32x16_bf16 v[68:83], v[140:143], v[136:139], v[68:83]
	ds_read_b128 v[136:139], v163 offset:23136
	s_waitcnt lgkmcnt(0)
	v_mfma_f32_32x32x16_bf16 v[68:83], v[136:139], v[132:135], v[68:83]
	v_lshlrev_b32_e32 v132, 2, v162
	v_sub_u32_e32 v132, v132, v161
	v_cmp_lt_i32_e32 vcc, 0, v132
	v_max_f32_e32 v36, v36, v36
	s_nop 7
	v_max_f32_e32 v68, v68, v68
	v_cndmask_b32_e32 v133, v237, v239, vcc
	v_cndmask_b32_e32 v134, v239, v237, vcc
	v_max_f32_e32 v133, v133, v133
	v_min_f32_e32 v36, v36, v133
	v_max_f32_e32 v133, v134, v134
	v_cmp_gt_u32_e32 vcc, s83, v132
	v_min_f32_e32 v133, v68, v133
	v_max_f32_e32 v37, v37, v37
	v_cndmask_b32_e32 v68, v237, v239, vcc
	v_cndmask_b32_e32 v134, v239, v237, vcc
	v_max_f32_e32 v68, v68, v68
	v_min_f32_e32 v37, v37, v68
	v_max_f32_e32 v68, v69, v69
	v_max_f32_e32 v69, v134, v134
	v_cmp_lt_i32_e32 vcc, -2, v132
	v_min_f32_e32 v134, v68, v69
	v_max_f32_e32 v38, v38, v38
	v_cndmask_b32_e32 v68, v237, v239, vcc
	v_cndmask_b32_e32 v69, v239, v237, vcc
	v_max_f32_e32 v68, v68, v68
	v_min_f32_e32 v38, v38, v68
	v_max_f32_e32 v68, v70, v70
	v_max_f32_e32 v69, v69, v69
	v_cmp_lt_i32_e32 vcc, -3, v132
	v_min_f32_e32 v135, v68, v69
	v_max_f32_e32 v39, v39, v39
	v_cndmask_b32_e32 v68, v237, v239, vcc
	v_cndmask_b32_e32 v69, v239, v237, vcc
	v_max_f32_e32 v68, v68, v68
	v_min_f32_e32 v39, v39, v68
	v_max_f32_e32 v68, v71, v71
	v_max_f32_e32 v69, v69, v69
	v_cmp_lt_i32_e32 vcc, -8, v132
	v_min_f32_e32 v136, v68, v69
	v_max_f32_e32 v40, v40, v40
	v_cndmask_b32_e32 v68, v237, v239, vcc
	v_cndmask_b32_e32 v69, v239, v237, vcc
	v_max_f32_e32 v68, v68, v68
	v_min_f32_e32 v40, v40, v68
	v_max_f32_e32 v68, v72, v72
	v_max_f32_e32 v69, v69, v69
	v_cmp_lt_i32_e32 vcc, -9, v132
	v_min_f32_e32 v137, v68, v69
	v_max_f32_e32 v41, v41, v41
	v_cndmask_b32_e32 v68, v237, v239, vcc
	v_cndmask_b32_e32 v69, v239, v237, vcc
	v_max_f32_e32 v68, v68, v68
	v_min_f32_e32 v41, v41, v68
	v_max_f32_e32 v68, v73, v73
	v_max_f32_e32 v69, v69, v69
	v_cmp_lt_i32_e32 vcc, -10, v132
	v_min_f32_e32 v138, v68, v69
	v_max_f32_e32 v42, v42, v42
	v_cndmask_b32_e32 v68, v237, v239, vcc
	v_cndmask_b32_e32 v69, v239, v237, vcc
	v_max_f32_e32 v68, v68, v68
	v_min_f32_e32 v42, v42, v68
	v_max_f32_e32 v68, v74, v74
	v_max_f32_e32 v69, v69, v69
	v_cmp_lt_i32_e32 vcc, -11, v132
	v_min_f32_e32 v139, v68, v69
	v_max_f32_e32 v43, v43, v43
	v_cndmask_b32_e32 v68, v237, v239, vcc
	v_cndmask_b32_e32 v69, v239, v237, vcc
	v_max_f32_e32 v68, v68, v68
	v_min_f32_e32 v43, v43, v68
	v_max_f32_e32 v68, v75, v75
	v_max_f32_e32 v69, v69, v69
	v_cmp_lt_i32_e32 vcc, -16, v132
	v_min_f32_e32 v140, v68, v69
	v_max_f32_e32 v44, v44, v44
	v_cndmask_b32_e32 v68, v237, v239, vcc
	v_cndmask_b32_e32 v69, v239, v237, vcc
	v_max_f32_e32 v68, v68, v68
	v_min_f32_e32 v44, v44, v68
	v_max_f32_e32 v68, v76, v76
	v_max_f32_e32 v69, v69, v69
	v_cmp_lt_i32_e32 vcc, s84, v132
	v_min_f32_e32 v141, v68, v69
	v_max_f32_e32 v45, v45, v45
	v_cndmask_b32_e32 v68, v237, v239, vcc
	v_cndmask_b32_e32 v69, v239, v237, vcc
	v_max_f32_e32 v68, v68, v68
	v_min_f32_e32 v45, v45, v68
	v_max_f32_e32 v68, v77, v77
	v_max_f32_e32 v69, v69, v69
	v_cmp_lt_i32_e32 vcc, s85, v132
	v_min_f32_e32 v142, v68, v69
	v_max_f32_e32 v46, v46, v46
	v_cndmask_b32_e32 v68, v237, v239, vcc
	v_cndmask_b32_e32 v69, v239, v237, vcc
	v_max_f32_e32 v68, v68, v68
	v_min_f32_e32 v46, v46, v68
	v_max_f32_e32 v68, v78, v78
	v_max_f32_e32 v69, v69, v69
	v_cmp_lt_i32_e32 vcc, s86, v132
	v_min_f32_e32 v143, v68, v69
	v_max_f32_e32 v47, v47, v47
	v_cndmask_b32_e32 v68, v237, v239, vcc
	v_cndmask_b32_e32 v69, v239, v237, vcc
	v_max_f32_e32 v68, v68, v68
	v_min_f32_e32 v47, v47, v68
	v_max_f32_e32 v68, v79, v79
	v_max_f32_e32 v69, v69, v69
	v_cmp_lt_i32_e32 vcc, s87, v132
	v_min_f32_e32 v144, v68, v69
	v_max_f32_e32 v48, v48, v48
	v_cndmask_b32_e32 v68, v237, v239, vcc
	v_cndmask_b32_e32 v69, v239, v237, vcc
	v_max_f32_e32 v68, v68, v68
	v_min_f32_e32 v48, v48, v68
	v_max_f32_e32 v68, v80, v80
	v_max_f32_e32 v69, v69, v69
	v_cmp_lt_i32_e32 vcc, s19, v132
	v_min_f32_e32 v145, v68, v69
	v_max_f32_e32 v49, v49, v49
	v_cndmask_b32_e32 v68, v237, v239, vcc
	v_cndmask_b32_e32 v69, v239, v237, vcc
	v_max_f32_e32 v68, v68, v68
	v_min_f32_e32 v49, v49, v68
	v_max_f32_e32 v68, v81, v81
	v_max_f32_e32 v69, v69, v69
	v_cmp_lt_i32_e32 vcc, s15, v132
	v_min_f32_e32 v146, v68, v69
	v_max_f32_e32 v50, v50, v50
	v_cndmask_b32_e32 v68, v237, v239, vcc
	v_cndmask_b32_e32 v69, v239, v237, vcc
	v_max_f32_e32 v68, v68, v68
	v_min_f32_e32 v50, v50, v68
	v_max_f32_e32 v68, v82, v82
	v_max_f32_e32 v69, v69, v69
	v_cmp_lt_i32_e32 vcc, s12, v132
	v_cndmask_b32_e64 v72, v29, v237, s[38:39]
	v_cndmask_b32_e64 v73, v28, v237, s[38:39]
	v_cndmask_b32_e64 v29, v21, v237, s[38:39]
	v_cndmask_b32_e64 v28, v20, v237, s[38:39]
	v_cndmask_b32_e64 v21, v37, v237, s[38:39]
	v_cndmask_b32_e64 v20, v36, v237, s[38:39]
	v_min_f32_e32 v147, v68, v69
	v_cndmask_b32_e32 v68, v237, v239, vcc
	v_cndmask_b32_e64 v71, v61, v237, s[38:39]
	v_cndmask_b32_e64 v70, v60, v237, s[38:39]
	v_cndmask_b32_e64 v61, v31, v237, s[38:39]
	v_cndmask_b32_e64 v60, v30, v237, s[38:39]
	v_cndmask_b32_e64 v31, v23, v237, s[38:39]
	v_cndmask_b32_e64 v30, v22, v237, s[38:39]
	v_cndmask_b32_e64 v23, v39, v237, s[38:39]
	v_cndmask_b32_e64 v22, v38, v237, s[38:39]
	v_max3_f32 v36, v20, s76, v21
	v_cndmask_b32_e32 v69, v239, v237, vcc
	v_max_f32_e32 v51, v51, v51
	v_max_f32_e32 v68, v68, v68
	v_cndmask_b32_e64 v74, v65, v237, s[38:39]
	v_cndmask_b32_e64 v75, v64, v237, s[38:39]
	v_cndmask_b32_e64 v64, v35, v237, s[38:39]
	v_cndmask_b32_e64 v65, v34, v237, s[38:39]
	v_cndmask_b32_e64 v35, v25, v237, s[38:39]
	v_cndmask_b32_e64 v34, v24, v237, s[38:39]
	v_cndmask_b32_e64 v25, v41, v237, s[38:39]
	v_cndmask_b32_e64 v24, v40, v237, s[38:39]
	v_max3_f32 v36, v36, v22, v23
	v_min_f32_e32 v51, v51, v68
	v_max_f32_e32 v68, v83, v83
	v_max_f32_e32 v69, v69, v69
	v_cndmask_b32_e64 v76, v27, v237, s[38:39]
	v_cndmask_b32_e64 v77, v26, v237, s[38:39]
	v_cndmask_b32_e64 v27, v43, v237, s[38:39]
	v_cndmask_b32_e64 v26, v42, v237, s[38:39]
	v_max3_f32 v36, v36, v24, v25
	v_min_f32_e32 v132, v68, v69
	v_cndmask_b32_e64 v68, v67, v237, s[38:39]
	v_cndmask_b32_e64 v69, v66, v237, s[38:39]
	v_cndmask_b32_e64 v67, v33, v237, s[38:39]
	v_cndmask_b32_e64 v66, v32, v237, s[38:39]
	v_cndmask_b32_e64 v33, v45, v237, s[38:39]
	v_cndmask_b32_e64 v32, v44, v237, s[38:39]
	v_max3_f32 v36, v36, v26, v27
	v_cndmask_b32_e64 v47, v47, v237, s[38:39]
	v_cndmask_b32_e64 v46, v46, v237, s[38:39]
	v_max3_f32 v36, v36, v32, v33
	v_cndmask_b32_e64 v49, v49, v237, s[38:39]
	v_cndmask_b32_e64 v48, v48, v237, s[38:39]
	v_max3_f32 v36, v36, v46, v47
	v_cndmask_b32_e64 v51, v51, v237, s[38:39]
	v_cndmask_b32_e64 v50, v50, v237, s[38:39]
	v_max3_f32 v36, v36, v48, v49
	v_max3_f32 v36, v36, v50, v51
	v_max3_f32 v36, v36, v28, v29
	v_max3_f32 v36, v36, v30, v31
	v_max3_f32 v36, v36, v34, v35
	v_max3_f32 v36, v36, v77, v76
	v_max3_f32 v36, v36, v73, v72
	v_max3_f32 v36, v36, v60, v61
	v_max3_f32 v36, v36, v66, v67
	v_cndmask_b32_e64 v53, v53, v237, s[38:39]
	v_cndmask_b32_e64 v52, v52, v237, s[38:39]
	v_max3_f32 v36, v36, v65, v64
	v_cndmask_b32_e64 v55, v55, v237, s[38:39]
	v_cndmask_b32_e64 v54, v54, v237, s[38:39]
	v_max3_f32 v36, v36, v52, v53
	v_cndmask_b32_e64 v57, v57, v237, s[38:39]
	v_cndmask_b32_e64 v56, v56, v237, s[38:39]
	v_max3_f32 v36, v36, v54, v55
	v_cndmask_b32_e64 v59, v59, v237, s[38:39]
	v_cndmask_b32_e64 v58, v58, v237, s[38:39]
	v_max3_f32 v36, v36, v56, v57
	v_max3_f32 v36, v36, v58, v59
	v_cndmask_b32_e64 v63, v63, v237, s[38:39]
	v_cndmask_b32_e64 v62, v62, v237, s[38:39]
	v_max3_f32 v36, v36, v70, v71
	v_max3_f32 v36, v36, v62, v63
	v_max3_f32 v36, v36, v75, v74
	v_max3_f32 v36, v36, v69, v68
	v_max3_f32 v36, v36, v4, v5
	v_max3_f32 v36, v36, v6, v7
	v_max3_f32 v36, v36, v8, v9
	v_max3_f32 v36, v36, v10, v11
	v_max3_f32 v36, v36, v12, v13
	v_max3_f32 v36, v36, v14, v15
	v_max3_f32 v36, v36, v16, v17
	v_max3_f32 v36, v36, v18, v19
	v_max3_f32 v36, v36, v133, v134
	v_max3_f32 v36, v36, v135, v136
	v_max3_f32 v36, v36, v137, v138
	v_max3_f32 v36, v36, v139, v140
	v_max3_f32 v36, v36, v141, v142
	v_max3_f32 v36, v36, v143, v144
	v_max3_f32 v36, v36, v145, v146
	v_max3_f32 v36, v36, v147, v132
	ds_bpermute_b32 v37, v155, v36
	s_waitcnt lgkmcnt(0)
	v_max3_f32 v162, v36, v37, v156
	v_sub_f32_e32 v38, v48, v162
	v_exp_f32_e32 v42, v38
	v_sub_f32_e32 v38, v49, v162
	v_exp_f32_e32 v43, v38
	v_sub_f32_e32 v38, v50, v162
	v_exp_f32_e32 v48, v38
	v_sub_f32_e32 v38, v51, v162
	v_exp_f32_e32 v49, v38
	v_sub_f32_e32 v38, v77, v162
	v_exp_f32_e32 v40, v38
	v_sub_f32_e32 v38, v76, v162
	v_exp_f32_e32 v41, v38
	v_sub_f32_e32 v38, v73, v162
	v_sub_f32_e32 v36, v46, v162
	v_exp_f32_e32 v46, v38
	v_sub_f32_e32 v38, v72, v162
	v_sub_f32_e32 v37, v47, v162
	v_exp_f32_e32 v47, v38
	v_sub_f32_e32 v38, v60, v162
	v_exp_f32_e32 v60, v38
	v_sub_f32_e32 v38, v61, v162
	v_sub_f32_e32 v20, v20, v162
	v_exp_f32_e32 v61, v38
	v_sub_f32_e32 v38, v66, v162
	v_exp_f32_e32 v20, v20
	v_sub_f32_e32 v21, v21, v162
	v_exp_f32_e32 v66, v38
	v_sub_f32_e32 v38, v67, v162
	v_exp_f32_e32 v21, v21
	v_sub_f32_e32 v22, v22, v162
	v_exp_f32_e32 v67, v38
	v_sub_f32_e32 v38, v65, v162
	v_exp_f32_e32 v22, v22
	v_sub_f32_e32 v23, v23, v162
	v_exp_f32_e32 v72, v38
	v_sub_f32_e32 v38, v64, v162
	v_exp_f32_e32 v23, v23
	v_sub_f32_e32 v24, v24, v162
	v_exp_f32_e32 v73, v38
	v_sub_f32_e32 v38, v52, v162
	v_sub_f32_e32 v52, v58, v162
	v_exp_f32_e32 v24, v24
	v_sub_f32_e32 v25, v25, v162
	v_exp_f32_e32 v64, v52
	v_sub_f32_e32 v52, v59, v162
	v_sub_f32_e32 v59, v132, v162
	v_add_f32_e32 v132, 0, v20
	v_exp_f32_e32 v25, v25
	v_sub_f32_e32 v26, v26, v162
	v_add_f32_e32 v132, v21, v132
	v_exp_f32_e32 v26, v26
	v_sub_f32_e32 v27, v27, v162
	v_add_f32_e32 v132, v22, v132
	v_exp_f32_e32 v27, v27
	v_sub_f32_e32 v32, v32, v162
	v_add_f32_e32 v132, v23, v132
	v_exp_f32_e32 v32, v32
	v_sub_f32_e32 v33, v33, v162
	v_add_f32_e32 v132, v24, v132
	v_exp_f32_e32 v33, v33
	v_add_f32_e32 v132, v25, v132
	v_exp_f32_e32 v36, v36
	v_add_f32_e32 v132, v26, v132
	v_exp_f32_e32 v37, v37
	v_add_f32_e32 v132, v27, v132
	v_add_f32_e32 v132, v32, v132
	v_add_f32_e32 v132, v33, v132
	v_add_f32_e32 v132, v36, v132
	v_sub_f32_e32 v28, v28, v162
	v_add_f32_e32 v132, v37, v132
	v_exp_f32_e32 v28, v28
	v_sub_f32_e32 v29, v29, v162
	v_add_f32_e32 v132, v42, v132
	v_exp_f32_e32 v29, v29
	v_sub_f32_e32 v30, v30, v162
	v_add_f32_e32 v132, v43, v132
	v_exp_f32_e32 v30, v30
	v_sub_f32_e32 v31, v31, v162
	v_add_f32_e32 v132, v48, v132
	v_exp_f32_e32 v31, v31
	v_sub_f32_e32 v34, v34, v162
	v_add_f32_e32 v132, v49, v132
	v_exp_f32_e32 v34, v34
	v_sub_f32_e32 v35, v35, v162
	v_add_f32_e32 v132, v28, v132
	v_exp_f32_e32 v35, v35
	v_add_f32_e32 v132, v29, v132
	v_add_f32_e32 v132, v30, v132
	v_add_f32_e32 v132, v31, v132
	v_add_f32_e32 v132, v34, v132
	v_add_f32_e32 v132, v35, v132
	v_add_f32_e32 v132, v40, v132
	v_add_f32_e32 v132, v41, v132
	v_add_f32_e32 v132, v46, v132
	v_add_f32_e32 v132, v47, v132
	v_add_f32_e32 v132, v60, v132
	v_add_f32_e32 v132, v61, v132
	v_exp_f32_e32 v38, v38
	v_sub_f32_e32 v39, v53, v162
	v_add_f32_e32 v132, v66, v132
	v_exp_f32_e32 v39, v39
	v_sub_f32_e32 v44, v54, v162
	v_add_f32_e32 v132, v67, v132
	v_exp_f32_e32 v44, v44
	v_sub_f32_e32 v45, v55, v162
	v_add_f32_e32 v132, v72, v132
	v_exp_f32_e32 v45, v45
	v_sub_f32_e32 v50, v56, v162
	v_add_f32_e32 v132, v73, v132
	v_exp_f32_e32 v50, v50
	v_sub_f32_e32 v51, v57, v162
	v_add_f32_e32 v132, v38, v132
	v_exp_f32_e32 v51, v51
	v_add_f32_e32 v132, v39, v132
	v_add_f32_e32 v132, v44, v132
	v_exp_f32_e32 v65, v52
	v_sub_f32_e32 v52, v70, v162
	v_add_f32_e32 v132, v45, v132
	v_exp_f32_e32 v70, v52
	v_sub_f32_e32 v52, v71, v162
	v_add_f32_e32 v132, v50, v132
	v_exp_f32_e32 v71, v52
	v_sub_f32_e32 v52, v62, v162
	v_add_f32_e32 v132, v51, v132
	v_exp_f32_e32 v76, v52
	v_sub_f32_e32 v52, v63, v162
	v_add_f32_e32 v132, v64, v132
	v_exp_f32_e32 v77, v52
	v_sub_f32_e32 v52, v75, v162
	v_add_f32_e32 v132, v65, v132
	v_exp_f32_e32 v80, v52
	v_sub_f32_e32 v52, v74, v162
	v_add_f32_e32 v132, v70, v132
	v_exp_f32_e32 v81, v52
	v_sub_f32_e32 v52, v69, v162
	v_add_f32_e32 v132, v71, v132
	v_exp_f32_e32 v82, v52
	v_sub_f32_e32 v52, v68, v162
	v_add_f32_e32 v132, v76, v132
	v_exp_f32_e32 v83, v52
	v_sub_f32_e32 v4, v4, v162
	v_add_f32_e32 v132, v77, v132
	v_exp_f32_e32 v62, v4
	v_sub_f32_e32 v4, v5, v162
	v_add_f32_e32 v132, v80, v132
	v_exp_f32_e32 v63, v4
	v_sub_f32_e32 v4, v6, v162
	v_add_f32_e32 v132, v81, v132
	v_exp_f32_e32 v68, v4
	v_sub_f32_e32 v4, v7, v162
	v_add_f32_e32 v132, v82, v132
	v_exp_f32_e32 v69, v4
	v_sub_f32_e32 v4, v8, v162
	v_add_f32_e32 v132, v83, v132
	v_exp_f32_e32 v74, v4
	v_sub_f32_e32 v4, v9, v162
	v_add_f32_e32 v132, v62, v132
	v_exp_f32_e32 v75, v4
	v_sub_f32_e32 v4, v10, v162
	v_add_f32_e32 v132, v63, v132
	v_exp_f32_e32 v78, v4
	v_sub_f32_e32 v4, v11, v162
	v_add_f32_e32 v132, v68, v132
	v_exp_f32_e32 v79, v4
	v_sub_f32_e32 v4, v12, v162
	v_add_f32_e32 v132, v69, v132
	v_exp_f32_e32 v12, v4
	v_sub_f32_e32 v4, v13, v162
	v_add_f32_e32 v132, v74, v132
	v_exp_f32_e32 v13, v4
	v_sub_f32_e32 v4, v14, v162
	v_add_f32_e32 v132, v75, v132
	v_exp_f32_e32 v14, v4
	v_sub_f32_e32 v4, v15, v162
	v_add_f32_e32 v132, v78, v132
	v_exp_f32_e32 v15, v4
	v_sub_f32_e32 v4, v16, v162
	v_add_f32_e32 v132, v79, v132
	v_exp_f32_e32 v16, v4
	v_sub_f32_e32 v4, v17, v162
	v_add_f32_e32 v132, v12, v132
	v_exp_f32_e32 v17, v4
	v_sub_f32_e32 v4, v18, v162
	v_add_f32_e32 v132, v13, v132
	v_exp_f32_e32 v18, v4
	v_sub_f32_e32 v4, v19, v162
	v_add_f32_e32 v132, v14, v132
	v_exp_f32_e32 v19, v4
	v_sub_f32_e32 v4, v133, v162
	v_add_f32_e32 v132, v15, v132
	v_exp_f32_e32 v4, v4
	v_sub_f32_e32 v5, v134, v162
	v_add_f32_e32 v132, v16, v132
	v_exp_f32_e32 v5, v5
	v_sub_f32_e32 v6, v135, v162
	v_add_f32_e32 v132, v17, v132
	v_exp_f32_e32 v6, v6
	v_sub_f32_e32 v7, v136, v162
	v_add_f32_e32 v132, v18, v132
	v_exp_f32_e32 v7, v7
	v_sub_f32_e32 v8, v137, v162
	v_add_f32_e32 v132, v19, v132
	v_exp_f32_e32 v8, v8
	v_sub_f32_e32 v9, v138, v162
	v_add_f32_e32 v132, v4, v132
	v_exp_f32_e32 v9, v9
	v_sub_f32_e32 v10, v139, v162
	v_add_f32_e32 v132, v5, v132
	v_exp_f32_e32 v10, v10
	v_sub_f32_e32 v11, v140, v162
	v_add_f32_e32 v132, v6, v132
	v_exp_f32_e32 v11, v11
	v_sub_f32_e32 v52, v141, v162
	v_add_f32_e32 v132, v7, v132
	v_exp_f32_e32 v52, v52
	v_sub_f32_e32 v53, v142, v162
	v_add_f32_e32 v132, v8, v132
	v_exp_f32_e32 v53, v53
	v_sub_f32_e32 v54, v143, v162
	v_add_f32_e32 v132, v9, v132
	v_exp_f32_e32 v54, v54
	v_sub_f32_e32 v55, v144, v162
	v_add_f32_e32 v132, v10, v132
	v_exp_f32_e32 v55, v55
	v_sub_f32_e32 v56, v145, v162
	v_add_f32_e32 v132, v11, v132
	v_exp_f32_e32 v56, v56
	v_sub_f32_e32 v57, v146, v162
	v_add_f32_e32 v132, v52, v132
	v_exp_f32_e32 v57, v57
	v_sub_f32_e32 v58, v147, v162
	v_add_f32_e32 v132, v53, v132
	v_exp_f32_e32 v58, v58
	v_add_f32_e32 v132, v54, v132
	v_exp_f32_e32 v59, v59
	v_add_f32_e32 v132, v55, v132
	v_add_f32_e32 v132, v56, v132
	v_add_f32_e32 v132, v57, v132
	v_add_f32_e32 v132, v58, v132
	v_add_f32_e32 v132, v59, v132
	ds_bpermute_b32 v133, v155, v132
	v_fma_f32 v134, v154, s18, -v162
	v_exp_f32_e32 v134, v134
	s_waitcnt lgkmcnt(0)
	v_add_f32_e32 v132, v132, v133
	v_add_f32_e32 v132, v134, v132
	v_div_scale_f32 v133, s[40:41], v132, v132, 1.0
	v_rcp_f32_e32 v134, v133
	s_nop 0
	v_fma_f32 v135, -v133, v134, 1.0
	v_fmac_f32_e32 v134, v135, v134
	v_div_scale_f32 v135, vcc, 1.0, v132, 1.0
	v_mul_f32_e32 v136, v135, v134
	v_fma_f32 v137, -v133, v136, v135
	v_fmac_f32_e32 v136, v137, v134
	v_fma_f32 v133, -v133, v136, v135
	v_div_fmas_f32 v133, v133, v134, v136
	v_div_fixup_f32 v132, v133, v132, 1.0
	v_pk_mul_f32 v[20:21], v[20:21], v[132:133] op_sel_hi:[1,0]
	v_pk_mul_f32 v[22:23], v[22:23], v[132:133] op_sel_hi:[1,0]
	v_pk_mul_f32 v[24:25], v[24:25], v[132:133] op_sel_hi:[1,0]
	v_pk_mul_f32 v[36:37], v[36:37], v[132:133] op_sel_hi:[1,0]
	v_pk_mul_f32 v[26:27], v[26:27], v[132:133] op_sel_hi:[1,0]
	v_pk_mul_f32 v[32:33], v[32:33], v[132:133] op_sel_hi:[1,0]
	v_pk_mul_f32 v[42:43], v[42:43], v[132:133] op_sel_hi:[1,0]
	v_pk_mul_f32 v[48:49], v[48:49], v[132:133] op_sel_hi:[1,0]
	v_cvt_pk_bf16_f32 v20, v20, v21
	v_cvt_pk_bf16_f32 v21, v22, v23
	v_cvt_pk_bf16_f32 v22, v24, v25
	v_cvt_pk_bf16_f32 v25, v36, v37
	v_pk_mul_f32 v[28:29], v[28:29], v[132:133] op_sel_hi:[1,0]
	v_pk_mul_f32 v[34:35], v[34:35], v[132:133] op_sel_hi:[1,0]
	v_pk_mul_f32 v[36:37], v[40:41], v[132:133] op_sel_hi:[1,0]
	v_pk_mul_f32 v[40:41], v[46:47], v[132:133] op_sel_hi:[1,0]
	v_cvt_pk_bf16_f32 v23, v26, v27
	v_cvt_pk_bf16_f32 v24, v32, v33
	v_cvt_pk_bf16_f32 v26, v42, v43
	v_cvt_pk_bf16_f32 v27, v48, v49
	v_pk_mul_f32 v[30:31], v[30:31], v[132:133] op_sel_hi:[1,0]
	v_pk_mul_f32 v[42:43], v[60:61], v[132:133] op_sel_hi:[1,0]
	v_pk_mul_f32 v[48:49], v[72:73], v[132:133] op_sel_hi:[1,0]
	v_cvt_pk_bf16_f32 v32, v28, v29
	v_cvt_pk_bf16_f32 v34, v34, v35
	v_cvt_pk_bf16_f32 v35, v36, v37
	v_cvt_pk_bf16_f32 v28, v40, v41
	v_pk_mul_f32 v[36:37], v[38:39], v[132:133] op_sel_hi:[1,0]
	v_pk_mul_f32 v[38:39], v[44:45], v[132:133] op_sel_hi:[1,0]
	v_pk_mul_f32 v[40:41], v[50:51], v[132:133] op_sel_hi:[1,0]
	v_pk_mul_f32 v[44:45], v[70:71], v[132:133] op_sel_hi:[1,0]
	v_cvt_pk_bf16_f32 v33, v30, v31
	v_cvt_pk_bf16_f32 v29, v42, v43
	v_cvt_pk_bf16_f32 v31, v48, v49
	v_pk_mul_f32 v[42:43], v[64:65], v[132:133] op_sel_hi:[1,0]
	v_pk_mul_f32 v[48:49], v[80:81], v[132:133] op_sel_hi:[1,0]
	v_cvt_pk_bf16_f32 v36, v36, v37
	v_cvt_pk_bf16_f32 v37, v38, v39
	v_cvt_pk_bf16_f32 v38, v40, v41
	v_cvt_pk_bf16_f32 v40, v44, v45
	v_pk_mul_f32 v[44:45], v[62:63], v[132:133] op_sel_hi:[1,0]
	v_pk_mul_f32 v[12:13], v[12:13], v[132:133] op_sel_hi:[1,0]
	v_cvt_pk_bf16_f32 v39, v42, v43
	v_cvt_pk_bf16_f32 v42, v48, v49
	v_cvt_pk_bf16_f32 v48, v44, v45
	v_cvt_pk_bf16_f32 v44, v12, v13
	v_ashrrev_i32_e32 v12, 2, v160
	v_pk_mul_f32 v[46:47], v[66:67], v[132:133] op_sel_hi:[1,0]
	v_and_b32_e32 v12, -8, v12
	v_cvt_pk_bf16_f32 v30, v46, v47
	v_pk_mul_f32 v[46:47], v[76:77], v[132:133] op_sel_hi:[1,0]
	v_add_u32_e32 v76, 0, v12
	v_mad_u32_u24 v12, v161, s8, v76
	v_pk_mul_f32 v[14:15], v[14:15], v[132:133] op_sel_hi:[1,0]
	v_add_u32_e32 v77, 0x9000, v12
	v_cvt_pk_bf16_f32 v45, v14, v15
	ds_read2_b64 v[12:15], v77 offset0:8 offset1:10
	v_pk_mul_f32 v[50:51], v[82:83], v[132:133] op_sel_hi:[1,0]
	v_cvt_pk_bf16_f32 v41, v46, v47
	v_cvt_pk_bf16_f32 v43, v50, v51
	v_pk_mul_f32 v[46:47], v[68:69], v[132:133] op_sel_hi:[1,0]
	v_pk_mul_f32 v[50:51], v[74:75], v[132:133] op_sel_hi:[1,0]
	v_pk_mul_f32 v[60:61], v[78:79], v[132:133] op_sel_hi:[1,0]
	v_pk_mul_f32 v[16:17], v[16:17], v[132:133] op_sel_hi:[1,0]
	v_pk_mul_f32 v[18:19], v[18:19], v[132:133] op_sel_hi:[1,0]
	v_cvt_pk_bf16_f32 v49, v46, v47
	v_cvt_pk_bf16_f32 v50, v50, v51
	v_cvt_pk_bf16_f32 v51, v60, v61
	v_cvt_pk_bf16_f32 v46, v16, v17
	v_cvt_pk_bf16_f32 v47, v18, v19
	v_pk_mul_f32 v[60:61], v[4:5], v[132:133] op_sel_hi:[1,0]
	v_pk_mul_f32 v[62:63], v[6:7], v[132:133] op_sel_hi:[1,0]
	v_pk_mul_f32 v[64:65], v[8:9], v[132:133] op_sel_hi:[1,0]
	v_pk_mul_f32 v[66:67], v[10:11], v[132:133] op_sel_hi:[1,0]
	s_waitcnt lgkmcnt(0)
	v_mfma_f32_32x32x16_bf16 v[4:19], v[20:23], v[12:15], 0
	v_mul_f32_e64 v68, v52, v132
	v_mul_f32_e64 v69, v53, v132
	v_mul_f32_e64 v70, v54, v132
	v_mul_f32_e64 v71, v55, v132
	ds_read2_b64 v[52:55], v77 offset0:12 offset1:14
	v_pk_mul_f32 v[74:75], v[58:59], v[132:133] op_sel_hi:[1,0]
	v_cvt_pk_bf16_f32 v58, v64, v65
	v_lshlrev_b32_e32 v65, 1, v160
	v_pk_mul_f32 v[72:73], v[56:57], v[132:133] op_sel_hi:[1,0]
	s_waitcnt lgkmcnt(0)
	v_mfma_f32_32x32x16_bf16 v[4:19], v[24:27], v[52:55], v[4:19]
	ds_read2_b64 v[52:55], v77 offset0:16 offset1:18
	v_and_b32_e32 v65, 62, v65
	v_cvt_pk_bf16_f32 v56, v60, v61
	v_cvt_pk_bf16_f32 v57, v62, v63
	v_cvt_pk_bf16_f32 v59, v66, v67
	v_cvt_pk_bf16_f32 v60, v68, v69
	v_cvt_pk_bf16_f32 v61, v70, v71
	s_waitcnt lgkmcnt(0)
	v_mfma_f32_32x32x16_bf16 v[4:19], v[32:35], v[52:55], v[4:19]
	v_lshrrev_b32_e32 v52, 3, v160
	v_and_b32_e32 v64, 0xffffffc, v52
	ds_read2_b64 v[52:55], v77 offset0:20 offset1:22
	v_mul_lo_u32 v64, v64, s13
	v_cvt_pk_bf16_f32 v62, v72, v73
	v_cvt_pk_bf16_f32 v63, v74, v75
	v_add3_u32 v64, s2, v64, v65
	s_waitcnt lgkmcnt(0)
	v_mfma_f32_32x32x16_bf16 v[4:19], v[28:31], v[52:55], v[4:19]
	ds_read2_b64 v[52:55], v77 offset0:24 offset1:26
	s_waitcnt lgkmcnt(0)
	v_mfma_f32_32x32x16_bf16 v[4:19], v[36:39], v[52:55], v[4:19]
	ds_read2_b64 v[52:55], v77 offset0:28 offset1:30
	s_waitcnt lgkmcnt(0)
	v_mfma_f32_32x32x16_bf16 v[4:19], v[40:43], v[52:55], v[4:19]
	ds_read2_b64 v[52:55], v77 offset0:32 offset1:34
	s_waitcnt lgkmcnt(0)
	v_mfma_f32_32x32x16_bf16 v[4:19], v[48:51], v[52:55], v[4:19]
	ds_read2_b64 v[52:55], v77 offset0:36 offset1:38
	s_waitcnt lgkmcnt(0)
	v_mfma_f32_32x32x16_bf16 v[4:19], v[44:47], v[52:55], v[4:19]
	ds_read2_b64 v[52:55], v77 offset0:40 offset1:42
	s_waitcnt lgkmcnt(0)
	v_mfma_f32_32x32x16_bf16 v[4:19], v[56:59], v[52:55], v[4:19]
	ds_read2_b64 v[52:55], v77 offset0:44 offset1:46
	s_waitcnt lgkmcnt(0)
	v_mfma_f32_32x32x16_bf16 v[4:19], v[60:63], v[52:55], v[4:19]
	s_nop 11
	v_cvt_pk_bf16_f32 v4, v4, v5
	ds_write_b16 v64, v4
	ds_write_b16_d16_hi v64, v4 offset:144
	v_cvt_pk_bf16_f32 v4, v6, v7
	ds_write_b16 v64, v4 offset:288
	ds_write_b16_d16_hi v64, v4 offset:432
	v_cvt_pk_bf16_f32 v4, v8, v9
	ds_write_b16 v64, v4 offset:1152
	ds_write_b16_d16_hi v64, v4 offset:1296
	v_cvt_pk_bf16_f32 v4, v10, v11
	ds_write_b16 v64, v4 offset:1440
	ds_write_b16_d16_hi v64, v4 offset:1584
	v_cvt_pk_bf16_f32 v4, v12, v13
	ds_write_b16 v64, v4 offset:2304
	ds_write_b16_d16_hi v64, v4 offset:2448
	v_cvt_pk_bf16_f32 v4, v14, v15
	ds_write_b16 v64, v4 offset:2592
	ds_write_b16_d16_hi v64, v4 offset:2736
	v_cvt_pk_bf16_f32 v4, v16, v17
	ds_write_b16 v64, v4 offset:3456
	ds_write_b16_d16_hi v64, v4 offset:3600
	v_cvt_pk_bf16_f32 v4, v18, v19
	ds_write_b16 v64, v4 offset:3744
	ds_write_b16_d16_hi v64, v4 offset:3888
	v_mad_u32_u24 v4, v159, s8, v76
	v_add_u32_e32 v52, 0x9000, v4
	ds_read2_b64 v[4:7], v52 offset0:8 offset1:10
	s_waitcnt lgkmcnt(0)
	v_mfma_f32_32x32x16_bf16 v[4:19], v[20:23], v[4:7], 0
	ds_read2_b64 v[20:23], v52 offset0:12 offset1:14
	s_waitcnt lgkmcnt(0)
	v_mfma_f32_32x32x16_bf16 v[4:19], v[24:27], v[20:23], v[4:19]
	ds_read2_b64 v[20:23], v52 offset0:16 offset1:18
	s_waitcnt lgkmcnt(0)
	v_mfma_f32_32x32x16_bf16 v[4:19], v[32:35], v[20:23], v[4:19]
	ds_read2_b64 v[20:23], v52 offset0:20 offset1:22
	s_waitcnt lgkmcnt(0)
	v_mfma_f32_32x32x16_bf16 v[4:19], v[28:31], v[20:23], v[4:19]
	ds_read2_b64 v[20:23], v52 offset0:24 offset1:26
	s_waitcnt lgkmcnt(0)
	v_mfma_f32_32x32x16_bf16 v[4:19], v[36:39], v[20:23], v[4:19]
	ds_read2_b64 v[20:23], v52 offset0:28 offset1:30
	s_waitcnt lgkmcnt(0)
	v_mfma_f32_32x32x16_bf16 v[4:19], v[40:43], v[20:23], v[4:19]
	ds_read2_b64 v[20:23], v52 offset0:32 offset1:34
	s_waitcnt lgkmcnt(0)
	v_mfma_f32_32x32x16_bf16 v[4:19], v[48:51], v[20:23], v[4:19]
	ds_read2_b64 v[20:23], v52 offset0:36 offset1:38
	s_waitcnt lgkmcnt(0)
	v_mfma_f32_32x32x16_bf16 v[4:19], v[44:47], v[20:23], v[4:19]
	ds_read2_b64 v[20:23], v52 offset0:40 offset1:42
	s_waitcnt lgkmcnt(0)
	v_mfma_f32_32x32x16_bf16 v[4:19], v[56:59], v[20:23], v[4:19]
	ds_read2_b64 v[20:23], v52 offset0:44 offset1:46
	s_waitcnt lgkmcnt(0)
	v_mfma_f32_32x32x16_bf16 v[4:19], v[60:63], v[20:23], v[4:19]
	s_nop 11
	v_cvt_pk_bf16_f32 v4, v4, v5
	ds_write_b16 v64, v4 offset:64
	ds_write_b16_d16_hi v64, v4 offset:208
	v_cvt_pk_bf16_f32 v4, v6, v7
	ds_write_b16 v64, v4 offset:352
	ds_write_b16_d16_hi v64, v4 offset:496
	v_cvt_pk_bf16_f32 v4, v8, v9
	ds_write_b16 v64, v4 offset:1216
	ds_write_b16_d16_hi v64, v4 offset:1360
	v_cvt_pk_bf16_f32 v4, v10, v11
	ds_write_b16 v64, v4 offset:1504
	ds_write_b16_d16_hi v64, v4 offset:1648
	v_cvt_pk_bf16_f32 v4, v12, v13
	ds_write_b16 v64, v4 offset:2368
	ds_write_b16_d16_hi v64, v4 offset:2512
	v_cvt_pk_bf16_f32 v4, v14, v15
	ds_write_b16 v64, v4 offset:2656
	ds_write_b16_d16_hi v64, v4 offset:2800
	v_cvt_pk_bf16_f32 v4, v16, v17
	ds_write_b16 v64, v4 offset:3520
	ds_write_b16_d16_hi v64, v4 offset:3664
	v_cvt_pk_bf16_f32 v4, v18, v19
	ds_write_b16 v64, v4 offset:3808
	ds_write_b16_d16_hi v64, v4 offset:3952
	v_mul_lo_u32 v4, v157, s13
	v_lshlrev_b32_e32 v5, 4, v158
	v_add3_u32 v14, s2, v4, v5
	ds_read_b128 v[6:9], v14
	s_waitcnt vmcnt(15)
	v_lshlrev_b32_e32 v12, 16, v112
	v_and_b32_e32 v13, 0xffff0000, v112
	v_mad_i64_i32 v[4:5], s[40:41], v157, s5, v[148:149]
	s_waitcnt lgkmcnt(0)
	v_lshlrev_b32_e32 v10, 16, v6
	v_and_b32_e32 v11, 0xffff0000, v6
	v_pk_mul_f32 v[10:11], v[12:13], v[10:11]
	v_lshlrev_b32_e32 v12, 16, v113
	v_cvt_pk_bf16_f32 v6, v10, v11
	v_lshlrev_b32_e32 v10, 16, v7
	v_and_b32_e32 v11, 0xffff0000, v7
	v_and_b32_e32 v13, 0xffff0000, v113
	v_pk_mul_f32 v[10:11], v[12:13], v[10:11]
	v_lshlrev_b32_e32 v12, 16, v114
	v_cvt_pk_bf16_f32 v7, v10, v11
	v_lshlrev_b32_e32 v10, 16, v8
	v_and_b32_e32 v11, 0xffff0000, v8
	v_and_b32_e32 v13, 0xffff0000, v114
	v_pk_mul_f32 v[10:11], v[12:13], v[10:11]
	v_lshlrev_b32_e32 v12, 16, v115
	v_cvt_pk_bf16_f32 v8, v10, v11
	v_lshlrev_b32_e32 v10, 16, v9
	v_and_b32_e32 v11, 0xffff0000, v9
	v_and_b32_e32 v13, 0xffff0000, v115
	v_lshl_add_u64 v[4:5], v[4:5], 0, v[152:153]
	v_pk_mul_f32 v[10:11], v[12:13], v[10:11]
	s_waitcnt vmcnt(14)
	v_lshlrev_b32_e32 v12, 16, v104
	v_cvt_pk_bf16_f32 v9, v10, v11
	v_add_co_u32_e32 v10, vcc, s7, v4
	v_and_b32_e32 v13, 0xffff0000, v104
	s_nop 0
	v_addc_co_u32_e32 v11, vcc, 0, v5, vcc
	global_store_dwordx4 v[10:11], v[6:9], off sc1
	ds_read_b128 v[6:9], v14 offset:1152
	s_mov_b32 s40, 0x1e000
	v_mov_b32_e32 v157, v2
	s_or_b32 s24, s24, 0x60
	s_waitcnt lgkmcnt(0)
	v_lshlrev_b32_e32 v10, 16, v6
	v_and_b32_e32 v11, 0xffff0000, v6
	v_pk_mul_f32 v[10:11], v[12:13], v[10:11]
	v_lshlrev_b32_e32 v12, 16, v105
	v_cvt_pk_bf16_f32 v6, v10, v11
	v_lshlrev_b32_e32 v10, 16, v7
	v_and_b32_e32 v11, 0xffff0000, v7
	v_and_b32_e32 v13, 0xffff0000, v105
	v_pk_mul_f32 v[10:11], v[12:13], v[10:11]
	v_lshlrev_b32_e32 v12, 16, v106
	v_cvt_pk_bf16_f32 v7, v10, v11
	v_lshlrev_b32_e32 v10, 16, v8
	v_and_b32_e32 v11, 0xffff0000, v8
	v_and_b32_e32 v13, 0xffff0000, v106
	v_pk_mul_f32 v[10:11], v[12:13], v[10:11]
	v_lshlrev_b32_e32 v12, 16, v107
	v_cvt_pk_bf16_f32 v8, v10, v11
	v_lshlrev_b32_e32 v10, 16, v9
	v_and_b32_e32 v11, 0xffff0000, v9
	v_and_b32_e32 v13, 0xffff0000, v107
	v_pk_mul_f32 v[10:11], v[12:13], v[10:11]
	s_waitcnt vmcnt(14)
	v_lshlrev_b32_e32 v12, 16, v100
	v_cvt_pk_bf16_f32 v9, v10, v11
	v_add_co_u32_e32 v10, vcc, s40, v4
	v_and_b32_e32 v13, 0xffff0000, v100
	s_nop 0
	v_addc_co_u32_e32 v11, vcc, 0, v5, vcc
	global_store_dwordx4 v[10:11], v[6:9], off sc1
	ds_read_b128 v[6:9], v14 offset:2304
	s_mov_b32 s40, 0x2a000
	s_waitcnt lgkmcnt(0)
	v_lshlrev_b32_e32 v10, 16, v6
	v_and_b32_e32 v11, 0xffff0000, v6
	v_pk_mul_f32 v[10:11], v[12:13], v[10:11]
	v_lshlrev_b32_e32 v12, 16, v101
	v_cvt_pk_bf16_f32 v6, v10, v11
	v_lshlrev_b32_e32 v10, 16, v7
	v_and_b32_e32 v11, 0xffff0000, v7
	v_and_b32_e32 v13, 0xffff0000, v101
	v_pk_mul_f32 v[10:11], v[12:13], v[10:11]
	v_lshlrev_b32_e32 v12, 16, v102
	v_cvt_pk_bf16_f32 v7, v10, v11
	v_lshlrev_b32_e32 v10, 16, v8
	v_and_b32_e32 v11, 0xffff0000, v8
	v_and_b32_e32 v13, 0xffff0000, v102
	v_pk_mul_f32 v[10:11], v[12:13], v[10:11]
	v_lshlrev_b32_e32 v12, 16, v103
	v_cvt_pk_bf16_f32 v8, v10, v11
	v_lshlrev_b32_e32 v10, 16, v9
	v_and_b32_e32 v11, 0xffff0000, v9
	v_and_b32_e32 v13, 0xffff0000, v103
	v_pk_mul_f32 v[10:11], v[12:13], v[10:11]
	s_waitcnt vmcnt(14)
	v_lshlrev_b32_e32 v12, 16, v88
	v_cvt_pk_bf16_f32 v9, v10, v11
	v_add_co_u32_e32 v10, vcc, s82, v4
	v_and_b32_e32 v13, 0xffff0000, v88
	s_nop 0
	v_addc_co_u32_e32 v11, vcc, 0, v5, vcc
	global_store_dwordx4 v[10:11], v[6:9], off sc1
	ds_read_b128 v[6:9], v14 offset:3456
	v_add_co_u32_e32 v4, vcc, s40, v4
	s_waitcnt lgkmcnt(0)
	v_lshlrev_b32_e32 v10, 16, v6
	v_and_b32_e32 v11, 0xffff0000, v6
	v_pk_mul_f32 v[10:11], v[12:13], v[10:11]
	v_lshlrev_b32_e32 v12, 16, v89
	v_cvt_pk_bf16_f32 v6, v10, v11
	v_lshlrev_b32_e32 v10, 16, v7
	v_and_b32_e32 v11, 0xffff0000, v7
	v_and_b32_e32 v13, 0xffff0000, v89
	v_pk_mul_f32 v[10:11], v[12:13], v[10:11]
	v_lshlrev_b32_e32 v12, 16, v90
	v_cvt_pk_bf16_f32 v7, v10, v11
	v_lshlrev_b32_e32 v10, 16, v8
	v_and_b32_e32 v11, 0xffff0000, v8
	v_and_b32_e32 v13, 0xffff0000, v90
	v_pk_mul_f32 v[10:11], v[12:13], v[10:11]
	v_lshlrev_b32_e32 v12, 16, v91
	v_cvt_pk_bf16_f32 v8, v10, v11
	v_lshlrev_b32_e32 v10, 16, v9
	v_and_b32_e32 v11, 0xffff0000, v9
	v_and_b32_e32 v13, 0xffff0000, v91
	v_pk_mul_f32 v[10:11], v[12:13], v[10:11]
	v_addc_co_u32_e32 v5, vcc, 0, v5, vcc
	v_cvt_pk_bf16_f32 v9, v10, v11
	global_store_dwordx4 v[4:5], v[6:9], off sc1
	s_nop 0
	v_and_b32_e32 v158, 31, v157
	v_ashrrev_i32_e32 v159, 5, v157
	v_or_b32_e32 v4, s24, v158
	v_mad_u64_u32 v[4:5], s[40:41], v4, s16, v[150:151]
	v_lshlrev_b32_e32 v6, 3, v159
	v_add_u32_e32 v5, s94, v5
	v_ashrrev_i32_e32 v7, 31, v6
	v_lshl_add_u64 v[4:5], v[6:7], 1, v[4:5]
	global_load_dwordx4 v[144:147], v[4:5], off
	global_load_dwordx4 v[140:143], v[4:5], off offset:32
	global_load_dwordx4 v[136:139], v[4:5], off offset:64
	global_load_dwordx4 v[132:135], v[4:5], off offset:96
	s_mul_hi_u32 s40, s24, 0x1800
	v_ashrrev_i32_e32 v4, 31, v157
	s_add_i32 s40, s40, s94
	s_mulk_i32 s24, 0x1800
	v_lshrrev_b32_e32 v4, 29, v4
	s_add_u32 s24, s72, s24
	v_add_u32_e32 v6, v157, v4
	s_addc_u32 s41, s73, s40
	v_ashrrev_i32_e32 v152, 3, v6
	v_and_b32_e32 v6, -8, v6
	s_add_u32 s40, s24, s90
	v_sub_u32_e32 v153, v157, v6
	s_addc_u32 s41, s41, s91
	v_lshlrev_b32_e32 v6, 3, v153
	v_mov_b64_e32 v[4:5], s[40:41]
	v_ashrrev_i32_e32 v7, 31, v6
	v_mad_i64_i32 v[4:5], s[40:41], v152, s16, v[4:5]
	v_lshlrev_b64 v[150:151], 1, v[6:7]
	v_lshl_add_u64 v[4:5], v[4:5], 0, v[150:151]
	v_add_co_u32_e32 v6, vcc, s6, v4
	global_load_dwordx4 v[112:115], v[4:5], off offset:2048
	s_nop 0
	v_addc_co_u32_e32 v7, vcc, 0, v5, vcc
	global_load_dwordx4 v[104:107], v[6:7], off offset:2048
	v_add_co_u32_e32 v6, vcc, s7, v4
	s_nop 1
	v_addc_co_u32_e32 v7, vcc, 0, v5, vcc
	v_add_co_u32_e32 v4, vcc, s82, v4
	global_load_dwordx4 v[100:103], v[6:7], off offset:2048
	s_nop 0
	v_addc_co_u32_e32 v5, vcc, 0, v5, vcc
	global_load_dwordx4 v[88:91], v[4:5], off offset:2048
	v_ashrrev_i32_e32 v4, 1, v157
	v_and_b32_e32 v4, -16, v4
	v_mul_u32_u24_e32 v5, 0x90, v158
	v_add3_u32 v160, 0, v4, v5
	ds_read_b128 v[4:7], v160 offset:9216
	s_waitcnt vmcnt(19) lgkmcnt(0)
	v_mfma_f32_32x32x16_bf16 v[36:51], v[4:7], v[128:131], 0
	ds_read_b128 v[4:7], v160 offset:9248
	s_waitcnt vmcnt(18) lgkmcnt(0)
	v_mfma_f32_32x32x16_bf16 v[36:51], v[4:7], v[124:127], v[36:51]
	ds_read_b128 v[4:7], v160 offset:9280
	s_waitcnt vmcnt(17) lgkmcnt(0)
	v_mfma_f32_32x32x16_bf16 v[36:51], v[4:7], v[120:123], v[36:51]
	ds_read_b128 v[4:7], v160 offset:9312
	s_waitcnt vmcnt(16) lgkmcnt(0)
	v_mfma_f32_32x32x16_bf16 v[36:51], v[4:7], v[116:119], v[36:51]
	ds_read_b128 v[4:7], v160 offset:13824
	s_waitcnt lgkmcnt(0)
	v_mfma_f32_32x32x16_bf16 v[52:67], v[4:7], v[128:131], 0
	ds_read_b128 v[4:7], v160 offset:13856
	s_waitcnt lgkmcnt(0)
	v_mfma_f32_32x32x16_bf16 v[52:67], v[4:7], v[124:127], v[52:67]
	ds_read_b128 v[4:7], v160 offset:13888
	s_waitcnt lgkmcnt(0)
	v_mfma_f32_32x32x16_bf16 v[52:67], v[4:7], v[120:123], v[52:67]
	ds_read_b128 v[4:7], v160 offset:13920
	s_waitcnt lgkmcnt(0)
	v_mfma_f32_32x32x16_bf16 v[52:67], v[4:7], v[116:119], v[52:67]
	ds_read_b128 v[4:7], v160 offset:18432
	s_waitcnt lgkmcnt(0)
	v_mfma_f32_32x32x16_bf16 v[20:35], v[4:7], v[128:131], 0
	ds_read_b128 v[4:7], v160 offset:18464
	s_waitcnt lgkmcnt(0)
	v_mfma_f32_32x32x16_bf16 v[20:35], v[4:7], v[124:127], v[20:35]
	ds_read_b128 v[4:7], v160 offset:18496
	s_waitcnt lgkmcnt(0)
	v_mfma_f32_32x32x16_bf16 v[20:35], v[4:7], v[120:123], v[20:35]
	ds_read_b128 v[4:7], v160 offset:18528
	s_waitcnt lgkmcnt(0)
	v_mfma_f32_32x32x16_bf16 v[20:35], v[4:7], v[116:119], v[20:35]
	ds_read_b128 v[4:7], v160 offset:23040
	ds_read_b128 v[68:71], v160 offset:23072
	s_waitcnt lgkmcnt(1)
	v_mfma_f32_32x32x16_bf16 v[4:19], v[4:7], v[128:131], 0
	s_waitcnt lgkmcnt(0)
	v_mfma_f32_32x32x16_bf16 v[4:19], v[68:71], v[124:127], v[4:19]
	ds_read_b128 v[68:71], v160 offset:23104
	s_waitcnt lgkmcnt(0)
	v_mfma_f32_32x32x16_bf16 v[4:19], v[68:71], v[120:123], v[4:19]
	ds_read_b128 v[68:71], v160 offset:23136
	s_waitcnt lgkmcnt(0)
	v_mfma_f32_32x32x16_bf16 v[4:19], v[68:71], v[116:119], v[4:19]
	ds_read_b128 v[68:71], v160 offset:27648
	s_waitcnt lgkmcnt(0)
	v_mfma_f32_32x32x16_bf16 v[68:83], v[68:71], v[128:131], 0
	ds_read_b128 v[128:131], v160 offset:27680
	s_waitcnt lgkmcnt(0)
	v_mfma_f32_32x32x16_bf16 v[68:83], v[128:131], v[124:127], v[68:83]
	ds_read_b128 v[124:127], v160 offset:27712
	s_waitcnt lgkmcnt(0)
	v_mfma_f32_32x32x16_bf16 v[68:83], v[124:127], v[120:123], v[68:83]
	ds_read_b128 v[120:123], v160 offset:27744
	s_waitcnt lgkmcnt(0)
	v_mfma_f32_32x32x16_bf16 v[68:83], v[120:123], v[116:119], v[68:83]
	v_lshlrev_b32_e32 v116, 2, v159
	v_sub_u32_e32 v116, v116, v158
	v_cmp_lt_i32_e32 vcc, 0, v116
	v_max_f32_e32 v36, v36, v36
	s_nop 7
	v_max_f32_e32 v68, v68, v68
	v_cndmask_b32_e32 v117, v237, v239, vcc
	v_cndmask_b32_e32 v118, v239, v237, vcc
	v_max_f32_e32 v117, v117, v117
	v_min_f32_e32 v36, v36, v117
	v_max_f32_e32 v117, v118, v118
	v_cmp_gt_u32_e32 vcc, s83, v116
	v_min_f32_e32 v159, v68, v117
	v_max_f32_e32 v37, v37, v37
	v_cndmask_b32_e32 v68, v237, v239, vcc
	v_cndmask_b32_e32 v117, v239, v237, vcc
	v_max_f32_e32 v68, v68, v68
	v_min_f32_e32 v37, v37, v68
	v_max_f32_e32 v68, v69, v69
	v_max_f32_e32 v69, v117, v117
	v_cmp_lt_i32_e32 vcc, -2, v116
	v_min_f32_e32 v160, v68, v69
	v_max_f32_e32 v38, v38, v38
	v_cndmask_b32_e32 v68, v237, v239, vcc
	v_cndmask_b32_e32 v69, v239, v237, vcc
	v_max_f32_e32 v68, v68, v68
	v_min_f32_e32 v38, v38, v68
	v_max_f32_e32 v68, v70, v70
	v_max_f32_e32 v69, v69, v69
	v_cmp_lt_i32_e32 vcc, -3, v116
	v_min_f32_e32 v161, v68, v69
	v_max_f32_e32 v39, v39, v39
	v_cndmask_b32_e32 v68, v237, v239, vcc
	v_cndmask_b32_e32 v69, v239, v237, vcc
	v_max_f32_e32 v68, v68, v68
	v_min_f32_e32 v39, v39, v68
	v_max_f32_e32 v68, v71, v71
	v_max_f32_e32 v69, v69, v69
	v_cmp_lt_i32_e32 vcc, -8, v116
	v_min_f32_e32 v162, v68, v69
	v_max_f32_e32 v40, v40, v40
	v_cndmask_b32_e32 v68, v237, v239, vcc
	v_cndmask_b32_e32 v69, v239, v237, vcc
	v_max_f32_e32 v68, v68, v68
	v_min_f32_e32 v40, v40, v68
	v_max_f32_e32 v68, v72, v72
	v_max_f32_e32 v69, v69, v69
	v_cmp_lt_i32_e32 vcc, -9, v116
	v_min_f32_e32 v163, v68, v69
	v_max_f32_e32 v41, v41, v41
	v_cndmask_b32_e32 v68, v237, v239, vcc
	v_cndmask_b32_e32 v69, v239, v237, vcc
	v_max_f32_e32 v68, v68, v68
	v_min_f32_e32 v41, v41, v68
	v_max_f32_e32 v68, v73, v73
	v_max_f32_e32 v69, v69, v69
	v_cmp_lt_i32_e32 vcc, -10, v116
	v_min_f32_e32 v164, v68, v69
	v_max_f32_e32 v42, v42, v42
	v_cndmask_b32_e32 v68, v237, v239, vcc
	v_cndmask_b32_e32 v69, v239, v237, vcc
	v_max_f32_e32 v68, v68, v68
	v_min_f32_e32 v42, v42, v68
	v_max_f32_e32 v68, v74, v74
	v_max_f32_e32 v69, v69, v69
	v_cmp_lt_i32_e32 vcc, -11, v116
	v_min_f32_e32 v165, v68, v69
	v_max_f32_e32 v43, v43, v43
	v_cndmask_b32_e32 v68, v237, v239, vcc
	v_cndmask_b32_e32 v69, v239, v237, vcc
	v_max_f32_e32 v68, v68, v68
	v_min_f32_e32 v43, v43, v68
	v_max_f32_e32 v68, v75, v75
	v_max_f32_e32 v69, v69, v69
	v_cmp_lt_i32_e32 vcc, -16, v116
	v_min_f32_e32 v166, v68, v69
	v_max_f32_e32 v44, v44, v44
	v_cndmask_b32_e32 v68, v237, v239, vcc
	v_cndmask_b32_e32 v69, v239, v237, vcc
	v_max_f32_e32 v68, v68, v68
	v_min_f32_e32 v44, v44, v68
	v_max_f32_e32 v68, v76, v76
	v_max_f32_e32 v69, v69, v69
	v_cmp_lt_i32_e32 vcc, s84, v116
	v_min_f32_e32 v167, v68, v69
	v_max_f32_e32 v45, v45, v45
	v_cndmask_b32_e32 v68, v237, v239, vcc
	v_cndmask_b32_e32 v69, v239, v237, vcc
	v_max_f32_e32 v68, v68, v68
	v_min_f32_e32 v45, v45, v68
	v_max_f32_e32 v68, v77, v77
	v_max_f32_e32 v69, v69, v69
	v_cmp_lt_i32_e32 vcc, s85, v116
	v_min_f32_e32 v168, v68, v69
	v_max_f32_e32 v46, v46, v46
	v_cndmask_b32_e32 v68, v237, v239, vcc
	v_cndmask_b32_e32 v69, v239, v237, vcc
	v_max_f32_e32 v68, v68, v68
	v_min_f32_e32 v46, v46, v68
	v_max_f32_e32 v68, v78, v78
	v_max_f32_e32 v69, v69, v69
	v_cmp_lt_i32_e32 vcc, s86, v116
	v_min_f32_e32 v169, v68, v69
	v_max_f32_e32 v47, v47, v47
	v_cndmask_b32_e32 v68, v237, v239, vcc
	v_cndmask_b32_e32 v69, v239, v237, vcc
	v_max_f32_e32 v68, v68, v68
	v_min_f32_e32 v47, v47, v68
	v_max_f32_e32 v68, v79, v79
	v_max_f32_e32 v69, v69, v69
	v_cmp_lt_i32_e32 vcc, s87, v116
	v_min_f32_e32 v170, v68, v69
	v_max_f32_e32 v48, v48, v48
	v_cndmask_b32_e32 v68, v237, v239, vcc
	v_cndmask_b32_e32 v69, v239, v237, vcc
	v_max_f32_e32 v68, v68, v68
	v_min_f32_e32 v48, v48, v68
	v_max_f32_e32 v68, v80, v80
	v_max_f32_e32 v69, v69, v69
	v_cmp_lt_i32_e32 vcc, s19, v116
	v_min_f32_e32 v171, v68, v69
	v_max_f32_e32 v49, v49, v49
	v_cndmask_b32_e32 v68, v237, v239, vcc
	v_cndmask_b32_e32 v69, v239, v237, vcc
	v_max_f32_e32 v68, v68, v68
	v_min_f32_e32 v49, v49, v68
	v_max_f32_e32 v68, v81, v81
	v_max_f32_e32 v69, v69, v69
	v_cmp_lt_i32_e32 vcc, s15, v116
	v_cndmask_b32_e64 v37, v37, v237, s[38:39]
	v_cndmask_b32_e64 v36, v36, v237, s[38:39]
	v_min_f32_e32 v172, v68, v69
	v_cndmask_b32_e32 v68, v237, v239, vcc
	v_cndmask_b32_e64 v74, v65, v237, s[38:39]
	v_cndmask_b32_e64 v65, v48, v237, s[38:39]
	v_cndmask_b32_e64 v48, v44, v237, s[38:39]
	v_cndmask_b32_e64 v39, v39, v237, s[38:39]
	v_cndmask_b32_e64 v38, v38, v237, s[38:39]
	v_max3_f32 v44, v36, s76, v37
	v_cndmask_b32_e32 v69, v239, v237, vcc
	v_max_f32_e32 v50, v50, v50
	v_max_f32_e32 v68, v68, v68
	v_cndmask_b32_e64 v41, v41, v237, s[38:39]
	v_cndmask_b32_e64 v40, v40, v237, s[38:39]
	v_max3_f32 v44, v44, v38, v39
	v_min_f32_e32 v50, v50, v68
	v_max_f32_e32 v68, v82, v82
	v_max_f32_e32 v69, v69, v69
	v_cmp_lt_i32_e32 vcc, s12, v116
	v_cndmask_b32_e64 v43, v43, v237, s[38:39]
	v_cndmask_b32_e64 v42, v42, v237, s[38:39]
	v_max3_f32 v44, v44, v40, v41
	v_min_f32_e32 v173, v68, v69
	v_cndmask_b32_e32 v68, v237, v239, vcc
	v_cndmask_b32_e64 v75, v64, v237, s[38:39]
	v_cndmask_b32_e64 v64, v49, v237, s[38:39]
	v_cndmask_b32_e64 v49, v45, v237, s[38:39]
	v_max3_f32 v44, v44, v42, v43
	v_max_f32_e32 v51, v51, v51
	v_max_f32_e32 v68, v68, v68
	v_cndmask_b32_e64 v47, v47, v237, s[38:39]
	v_cndmask_b32_e64 v46, v46, v237, s[38:39]
	v_max3_f32 v44, v44, v48, v49
	v_min_f32_e32 v51, v51, v68
	v_max3_f32 v44, v44, v46, v47
	v_cndmask_b32_e64 v51, v51, v237, s[38:39]
	v_cndmask_b32_e64 v50, v50, v237, s[38:39]
	v_max3_f32 v44, v44, v65, v64
	v_cndmask_b32_e64 v53, v53, v237, s[38:39]
	v_cndmask_b32_e64 v52, v52, v237, s[38:39]
	v_max3_f32 v44, v44, v50, v51
	v_cndmask_b32_e64 v55, v55, v237, s[38:39]
	v_cndmask_b32_e64 v54, v54, v237, s[38:39]
	v_max3_f32 v44, v44, v52, v53
	v_cndmask_b32_e64 v57, v57, v237, s[38:39]
	v_cndmask_b32_e64 v56, v56, v237, s[38:39]
	v_max3_f32 v44, v44, v54, v55
	v_cndmask_b32_e64 v59, v59, v237, s[38:39]
	v_cndmask_b32_e64 v58, v58, v237, s[38:39]
	v_max3_f32 v44, v44, v56, v57
	v_cndmask_b32_e64 v71, v61, v237, s[38:39]
	v_cndmask_b32_e64 v70, v60, v237, s[38:39]
	v_max3_f32 v44, v44, v58, v59
	v_cndmask_b32_e32 v69, v239, v237, vcc
	v_cndmask_b32_e64 v63, v63, v237, s[38:39]
	v_cndmask_b32_e64 v62, v62, v237, s[38:39]
	v_max3_f32 v44, v44, v70, v71
	v_max_f32_e32 v68, v83, v83
	v_max_f32_e32 v69, v69, v69
	v_max3_f32 v44, v44, v62, v63
	v_min_f32_e32 v174, v68, v69
	v_cndmask_b32_e64 v68, v67, v237, s[38:39]
	v_cndmask_b32_e64 v69, v66, v237, s[38:39]
	v_max3_f32 v44, v44, v75, v74
	v_max3_f32 v44, v44, v69, v68
	v_max3_f32 v44, v44, v20, v21
	v_max3_f32 v44, v44, v22, v23
	v_max3_f32 v44, v44, v24, v25
	v_max3_f32 v44, v44, v26, v27
	v_max3_f32 v44, v44, v28, v29
	v_max3_f32 v44, v44, v30, v31
	v_max3_f32 v44, v44, v32, v33
	v_max3_f32 v44, v44, v34, v35
	v_max3_f32 v44, v44, v4, v5
	v_max3_f32 v44, v44, v6, v7
	v_max3_f32 v44, v44, v8, v9
	v_max3_f32 v44, v44, v10, v11
	v_max3_f32 v44, v44, v12, v13
	v_max3_f32 v44, v44, v14, v15
	v_max3_f32 v44, v44, v16, v17
	v_max3_f32 v44, v44, v18, v19
	v_max3_f32 v44, v44, v159, v160
	v_max3_f32 v44, v44, v161, v162
	v_max3_f32 v44, v44, v163, v164
	v_max3_f32 v44, v44, v165, v166
	v_max3_f32 v44, v44, v167, v168
	v_max3_f32 v44, v44, v169, v170
	v_max3_f32 v44, v44, v171, v172
	v_max3_f32 v44, v44, v173, v174
	ds_bpermute_b32 v45, v155, v44
	s_waitcnt lgkmcnt(0)
	v_max3_f32 v175, v44, v45, v156
	v_sub_f32_e32 v42, v42, v175
	v_exp_f32_e32 v44, v42
	v_sub_f32_e32 v42, v43, v175
	v_exp_f32_e32 v45, v42
	v_sub_f32_e32 v42, v48, v175
	v_exp_f32_e32 v48, v42
	v_sub_f32_e32 v42, v49, v175
	v_exp_f32_e32 v49, v42
	v_sub_f32_e32 v42, v46, v175
	v_exp_f32_e32 v60, v42
	v_sub_f32_e32 v42, v47, v175
	v_exp_f32_e32 v61, v42
	v_sub_f32_e32 v42, v65, v175
	v_exp_f32_e32 v66, v42
	v_sub_f32_e32 v42, v64, v175
	v_exp_f32_e32 v67, v42
	v_sub_f32_e32 v42, v50, v175
	v_exp_f32_e32 v72, v42
	v_sub_f32_e32 v42, v51, v175
	v_exp_f32_e32 v73, v42
	v_sub_f32_e32 v42, v52, v175
	v_sub_f32_e32 v52, v58, v175
	v_exp_f32_e32 v64, v52
	v_sub_f32_e32 v52, v59, v175
	v_exp_f32_e32 v65, v52
	v_sub_f32_e32 v52, v70, v175
	v_exp_f32_e32 v70, v52
	v_sub_f32_e32 v52, v71, v175
	v_exp_f32_e32 v71, v52
	v_sub_f32_e32 v52, v62, v175
	v_exp_f32_e32 v76, v52
	v_sub_f32_e32 v52, v63, v175
	v_exp_f32_e32 v77, v52
	v_sub_f32_e32 v52, v75, v175
	v_sub_f32_e32 v20, v20, v175
	v_exp_f32_e32 v82, v52
	v_sub_f32_e32 v52, v74, v175
	v_exp_f32_e32 v62, v20
	v_sub_f32_e32 v20, v21, v175
	v_exp_f32_e32 v83, v52
	v_sub_f32_e32 v52, v69, v175
	v_exp_f32_e32 v63, v20
	v_sub_f32_e32 v20, v22, v175
	v_exp_f32_e32 v120, v52
	v_sub_f32_e32 v52, v68, v175
	v_exp_f32_e32 v68, v20
	v_sub_f32_e32 v20, v23, v175
	v_exp_f32_e32 v69, v20
	v_sub_f32_e32 v20, v24, v175
	v_exp_f32_e32 v74, v20
	v_sub_f32_e32 v20, v25, v175
	v_exp_f32_e32 v75, v20
	v_sub_f32_e32 v20, v26, v175
	v_exp_f32_e32 v80, v20
	v_sub_f32_e32 v20, v27, v175
	v_exp_f32_e32 v81, v20
	v_sub_f32_e32 v20, v28, v175
	v_exp_f32_e32 v118, v20
	v_sub_f32_e32 v20, v29, v175
	v_exp_f32_e32 v119, v20
	v_sub_f32_e32 v20, v30, v175
	v_exp_f32_e32 v124, v20
	v_sub_f32_e32 v20, v31, v175
	v_exp_f32_e32 v125, v20
	v_sub_f32_e32 v20, v32, v175
	v_exp_f32_e32 v128, v20
	v_sub_f32_e32 v20, v33, v175
	v_exp_f32_e32 v129, v20
	v_sub_f32_e32 v20, v34, v175
	v_exp_f32_e32 v130, v20
	v_sub_f32_e32 v20, v35, v175
	v_exp_f32_e32 v131, v20
	v_sub_f32_e32 v20, v167, v175
	v_exp_f32_e32 v121, v52
	v_exp_f32_e32 v52, v20
	v_sub_f32_e32 v20, v168, v175
	v_sub_f32_e32 v43, v53, v175
	v_exp_f32_e32 v53, v20
	v_sub_f32_e32 v20, v169, v175
	v_sub_f32_e32 v36, v36, v175
	v_sub_f32_e32 v46, v54, v175
	v_exp_f32_e32 v54, v20
	v_sub_f32_e32 v20, v170, v175
	v_exp_f32_e32 v36, v36
	v_sub_f32_e32 v37, v37, v175
	v_sub_f32_e32 v47, v55, v175
	v_exp_f32_e32 v55, v20
	v_sub_f32_e32 v20, v171, v175
	v_exp_f32_e32 v37, v37
	v_sub_f32_e32 v38, v38, v175
	v_sub_f32_e32 v50, v56, v175
	v_exp_f32_e32 v56, v20
	v_sub_f32_e32 v20, v172, v175
	v_exp_f32_e32 v38, v38
	v_sub_f32_e32 v39, v39, v175
	v_sub_f32_e32 v51, v57, v175
	v_exp_f32_e32 v57, v20
	v_sub_f32_e32 v20, v173, v175
	v_exp_f32_e32 v39, v39
	v_sub_f32_e32 v40, v40, v175
	v_exp_f32_e32 v58, v20
	v_sub_f32_e32 v20, v174, v175
	v_exp_f32_e32 v40, v40
	v_sub_f32_e32 v41, v41, v175
	v_exp_f32_e32 v59, v20
	v_add_f32_e32 v20, 0, v36
	v_exp_f32_e32 v41, v41
	v_add_f32_e32 v20, v37, v20
	v_add_f32_e32 v20, v38, v20
	v_add_f32_e32 v20, v39, v20
	v_add_f32_e32 v20, v40, v20
	v_add_f32_e32 v20, v41, v20
	v_add_f32_e32 v20, v44, v20
	v_add_f32_e32 v20, v45, v20
	v_add_f32_e32 v20, v48, v20
	v_add_f32_e32 v20, v49, v20
	v_add_f32_e32 v20, v60, v20
	v_add_f32_e32 v20, v61, v20
	v_exp_f32_e32 v42, v42
	v_add_f32_e32 v20, v66, v20
	v_exp_f32_e32 v43, v43
	v_add_f32_e32 v20, v67, v20
	v_exp_f32_e32 v46, v46
	v_add_f32_e32 v20, v72, v20
	v_exp_f32_e32 v47, v47
	v_add_f32_e32 v20, v73, v20
	v_exp_f32_e32 v50, v50
	v_add_f32_e32 v20, v42, v20
	v_exp_f32_e32 v51, v51
	v_add_f32_e32 v20, v43, v20
	v_add_f32_e32 v20, v46, v20
	v_add_f32_e32 v20, v47, v20
	v_add_f32_e32 v20, v50, v20
	v_add_f32_e32 v20, v51, v20
	v_add_f32_e32 v20, v64, v20
	v_add_f32_e32 v20, v65, v20
	v_add_f32_e32 v20, v70, v20
	v_add_f32_e32 v20, v71, v20
	v_add_f32_e32 v20, v76, v20
	v_add_f32_e32 v20, v77, v20
	v_add_f32_e32 v20, v82, v20
	v_add_f32_e32 v20, v83, v20
	v_add_f32_e32 v20, v120, v20
	v_add_f32_e32 v20, v121, v20
	v_add_f32_e32 v20, v62, v20
	v_add_f32_e32 v20, v63, v20
	v_add_f32_e32 v20, v68, v20
	v_add_f32_e32 v20, v69, v20
	v_add_f32_e32 v20, v74, v20
	v_add_f32_e32 v20, v75, v20
	v_add_f32_e32 v20, v80, v20
	v_add_f32_e32 v20, v81, v20
	v_add_f32_e32 v20, v118, v20
	v_add_f32_e32 v20, v119, v20
	v_add_f32_e32 v20, v124, v20
	v_sub_f32_e32 v4, v4, v175
	v_add_f32_e32 v20, v125, v20
	v_exp_f32_e32 v78, v4
	v_sub_f32_e32 v4, v5, v175
	v_add_f32_e32 v20, v128, v20
	v_exp_f32_e32 v79, v4
	v_sub_f32_e32 v4, v6, v175
	v_add_f32_e32 v20, v129, v20
	v_exp_f32_e32 v116, v4
	v_sub_f32_e32 v4, v7, v175
	v_add_f32_e32 v20, v130, v20
	v_exp_f32_e32 v117, v4
	v_sub_f32_e32 v4, v8, v175
	v_add_f32_e32 v20, v131, v20
	v_exp_f32_e32 v122, v4
	v_sub_f32_e32 v4, v9, v175
	v_add_f32_e32 v20, v78, v20
	v_exp_f32_e32 v123, v4
	v_sub_f32_e32 v4, v10, v175
	v_add_f32_e32 v20, v79, v20
	v_exp_f32_e32 v126, v4
	v_sub_f32_e32 v4, v11, v175
	v_add_f32_e32 v20, v116, v20
	v_exp_f32_e32 v127, v4
	v_sub_f32_e32 v4, v12, v175
	v_add_f32_e32 v20, v117, v20
	v_exp_f32_e32 v12, v4
	v_sub_f32_e32 v4, v13, v175
	v_add_f32_e32 v20, v122, v20
	v_exp_f32_e32 v13, v4
	v_sub_f32_e32 v4, v14, v175
	v_add_f32_e32 v20, v123, v20
	v_exp_f32_e32 v14, v4
	v_sub_f32_e32 v4, v15, v175
	v_add_f32_e32 v20, v126, v20
	v_exp_f32_e32 v15, v4
	v_sub_f32_e32 v4, v16, v175
	v_add_f32_e32 v20, v127, v20
	v_exp_f32_e32 v16, v4
	v_sub_f32_e32 v4, v17, v175
	v_add_f32_e32 v20, v12, v20
	v_exp_f32_e32 v17, v4
	v_sub_f32_e32 v4, v18, v175
	v_add_f32_e32 v20, v13, v20
	v_exp_f32_e32 v18, v4
	v_sub_f32_e32 v4, v19, v175
	v_add_f32_e32 v20, v14, v20
	v_exp_f32_e32 v19, v4
	v_sub_f32_e32 v4, v159, v175
	v_add_f32_e32 v20, v15, v20
	v_exp_f32_e32 v4, v4
	v_sub_f32_e32 v5, v160, v175
	v_add_f32_e32 v20, v16, v20
	v_exp_f32_e32 v5, v5
	v_sub_f32_e32 v6, v161, v175
	v_add_f32_e32 v20, v17, v20
	v_exp_f32_e32 v6, v6
	v_sub_f32_e32 v7, v162, v175
	v_add_f32_e32 v20, v18, v20
	v_exp_f32_e32 v7, v7
	v_sub_f32_e32 v8, v163, v175
	v_add_f32_e32 v20, v19, v20
	v_exp_f32_e32 v8, v8
	v_sub_f32_e32 v9, v164, v175
	v_add_f32_e32 v20, v4, v20
	v_exp_f32_e32 v9, v9
	v_sub_f32_e32 v10, v165, v175
	v_add_f32_e32 v20, v5, v20
	v_exp_f32_e32 v10, v10
	v_sub_f32_e32 v11, v166, v175
	v_add_f32_e32 v20, v6, v20
	v_exp_f32_e32 v11, v11
	v_add_f32_e32 v20, v7, v20
	v_add_f32_e32 v20, v8, v20
	v_add_f32_e32 v20, v9, v20
	v_add_f32_e32 v20, v10, v20
	v_add_f32_e32 v20, v11, v20
	v_add_f32_e32 v20, v52, v20
	v_add_f32_e32 v20, v53, v20
	v_add_f32_e32 v20, v54, v20
	v_add_f32_e32 v20, v55, v20
	v_add_f32_e32 v20, v56, v20
	v_add_f32_e32 v20, v57, v20
	v_add_f32_e32 v20, v58, v20
	v_add_f32_e32 v20, v59, v20
	ds_bpermute_b32 v21, v155, v20
	v_fma_f32 v22, v154, s18, -v175
	v_exp_f32_e32 v22, v22
	s_waitcnt lgkmcnt(0)
	v_add_f32_e32 v20, v20, v21
	v_add_f32_e32 v20, v22, v20
	v_div_scale_f32 v21, s[40:41], v20, v20, 1.0
	v_rcp_f32_e32 v22, v21
	s_nop 0
	v_fma_f32 v23, -v21, v22, 1.0
	v_fmac_f32_e32 v22, v23, v22
	v_div_scale_f32 v23, vcc, 1.0, v20, 1.0
	v_mul_f32_e32 v24, v23, v22
	v_fma_f32 v25, -v21, v24, v23
	v_fmac_f32_e32 v24, v25, v22
	v_fma_f32 v21, -v21, v24, v23
	v_div_fmas_f32 v21, v21, v22, v24
	v_div_fixup_f32 v160, v21, v20, 1.0
	v_pk_mul_f32 v[20:21], v[36:37], v[160:161] op_sel_hi:[1,0]
	v_pk_mul_f32 v[22:23], v[38:39], v[160:161] op_sel_hi:[1,0]
	v_pk_mul_f32 v[24:25], v[40:41], v[160:161] op_sel_hi:[1,0]
	v_pk_mul_f32 v[26:27], v[44:45], v[160:161] op_sel_hi:[1,0]
	v_pk_mul_f32 v[28:29], v[48:49], v[160:161] op_sel_hi:[1,0]
	v_pk_mul_f32 v[30:31], v[60:61], v[160:161] op_sel_hi:[1,0]
	v_pk_mul_f32 v[34:35], v[72:73], v[160:161] op_sel_hi:[1,0]
	v_pk_mul_f32 v[32:33], v[66:67], v[160:161] op_sel_hi:[1,0]
	v_cvt_pk_bf16_f32 v20, v20, v21
	v_cvt_pk_bf16_f32 v21, v22, v23
	v_cvt_pk_bf16_f32 v22, v24, v25
	v_cvt_pk_bf16_f32 v23, v26, v27
	v_cvt_pk_bf16_f32 v24, v28, v29
	v_cvt_pk_bf16_f32 v25, v30, v31
	v_cvt_pk_bf16_f32 v27, v34, v35
	v_pk_mul_f32 v[28:29], v[42:43], v[160:161] op_sel_hi:[1,0]
	v_pk_mul_f32 v[30:31], v[46:47], v[160:161] op_sel_hi:[1,0]
	v_pk_mul_f32 v[34:35], v[50:51], v[160:161] op_sel_hi:[1,0]
	v_pk_mul_f32 v[36:37], v[64:65], v[160:161] op_sel_hi:[1,0]
	v_pk_mul_f32 v[38:39], v[70:71], v[160:161] op_sel_hi:[1,0]
	v_pk_mul_f32 v[40:41], v[76:77], v[160:161] op_sel_hi:[1,0]
	v_pk_mul_f32 v[44:45], v[120:121], v[160:161] op_sel_hi:[1,0]
	v_cvt_pk_bf16_f32 v26, v32, v33
	v_pk_mul_f32 v[42:43], v[82:83], v[160:161] op_sel_hi:[1,0]
	v_cvt_pk_bf16_f32 v32, v28, v29
	v_cvt_pk_bf16_f32 v33, v30, v31
	v_cvt_pk_bf16_f32 v34, v34, v35
	v_cvt_pk_bf16_f32 v35, v36, v37
	v_cvt_pk_bf16_f32 v28, v38, v39
	v_cvt_pk_bf16_f32 v29, v40, v41
	v_cvt_pk_bf16_f32 v31, v44, v45
	v_pk_mul_f32 v[36:37], v[62:63], v[160:161] op_sel_hi:[1,0]
	v_pk_mul_f32 v[38:39], v[68:69], v[160:161] op_sel_hi:[1,0]
	v_pk_mul_f32 v[40:41], v[74:75], v[160:161] op_sel_hi:[1,0]
	v_pk_mul_f32 v[44:45], v[118:119], v[160:161] op_sel_hi:[1,0]
	v_cvt_pk_bf16_f32 v30, v42, v43
	v_pk_mul_f32 v[42:43], v[80:81], v[160:161] op_sel_hi:[1,0]
	v_pk_mul_f32 v[48:49], v[128:129], v[160:161] op_sel_hi:[1,0]
	v_cvt_pk_bf16_f32 v36, v36, v37
	v_cvt_pk_bf16_f32 v37, v38, v39
	v_cvt_pk_bf16_f32 v38, v40, v41
	v_cvt_pk_bf16_f32 v40, v44, v45
	v_pk_mul_f32 v[44:45], v[78:79], v[160:161] op_sel_hi:[1,0]
	v_pk_mul_f32 v[12:13], v[12:13], v[160:161] op_sel_hi:[1,0]
	v_cvt_pk_bf16_f32 v39, v42, v43
	v_cvt_pk_bf16_f32 v42, v48, v49
	v_cvt_pk_bf16_f32 v48, v44, v45
	v_cvt_pk_bf16_f32 v44, v12, v13
	v_ashrrev_i32_e32 v12, 2, v157
	v_and_b32_e32 v12, -8, v12
	v_mul_u32_u24_e32 v13, 0x208, v158
	v_add3_u32 v76, 0, v12, v13
	v_pk_mul_f32 v[14:15], v[14:15], v[160:161] op_sel_hi:[1,0]
	v_add_u32_e32 v77, 0x9000, v76
	v_cvt_pk_bf16_f32 v45, v14, v15
	ds_read2_b64 v[12:15], v77 offset0:16 offset1:18
	v_pk_mul_f32 v[46:47], v[124:125], v[160:161] op_sel_hi:[1,0]
	v_pk_mul_f32 v[50:51], v[130:131], v[160:161] op_sel_hi:[1,0]
	v_cvt_pk_bf16_f32 v41, v46, v47
	v_cvt_pk_bf16_f32 v43, v50, v51
	v_pk_mul_f32 v[46:47], v[116:117], v[160:161] op_sel_hi:[1,0]
	v_pk_mul_f32 v[50:51], v[122:123], v[160:161] op_sel_hi:[1,0]
	v_pk_mul_f32 v[60:61], v[126:127], v[160:161] op_sel_hi:[1,0]
	v_pk_mul_f32 v[16:17], v[16:17], v[160:161] op_sel_hi:[1,0]
	v_pk_mul_f32 v[18:19], v[18:19], v[160:161] op_sel_hi:[1,0]
	v_cvt_pk_bf16_f32 v49, v46, v47
	v_cvt_pk_bf16_f32 v50, v50, v51
	v_cvt_pk_bf16_f32 v51, v60, v61
	v_cvt_pk_bf16_f32 v46, v16, v17
	v_cvt_pk_bf16_f32 v47, v18, v19
	v_pk_mul_f32 v[60:61], v[4:5], v[160:161] op_sel_hi:[1,0]
	v_pk_mul_f32 v[62:63], v[6:7], v[160:161] op_sel_hi:[1,0]
	v_pk_mul_f32 v[64:65], v[8:9], v[160:161] op_sel_hi:[1,0]
	v_pk_mul_f32 v[66:67], v[10:11], v[160:161] op_sel_hi:[1,0]
	s_waitcnt lgkmcnt(0)
	v_mfma_f32_32x32x16_bf16 v[4:19], v[20:23], v[12:15], 0
	v_mul_f32_e64 v68, v52, v160
	v_mul_f32_e64 v69, v53, v160
	v_mul_f32_e64 v70, v54, v160
	v_mul_f32_e64 v71, v55, v160
	ds_read2_b64 v[52:55], v77 offset0:20 offset1:22
	v_pk_mul_f32 v[74:75], v[58:59], v[160:161] op_sel_hi:[1,0]
	v_cvt_pk_bf16_f32 v58, v64, v65
	v_lshlrev_b32_e32 v65, 1, v157
	v_pk_mul_f32 v[72:73], v[56:57], v[160:161] op_sel_hi:[1,0]
	s_waitcnt lgkmcnt(0)
	v_mfma_f32_32x32x16_bf16 v[4:19], v[24:27], v[52:55], v[4:19]
	ds_read2_b64 v[52:55], v77 offset0:24 offset1:26
	v_and_b32_e32 v65, 62, v65
	v_cvt_pk_bf16_f32 v56, v60, v61
	v_cvt_pk_bf16_f32 v57, v62, v63
	v_cvt_pk_bf16_f32 v59, v66, v67
	v_cvt_pk_bf16_f32 v60, v68, v69
	v_cvt_pk_bf16_f32 v61, v70, v71
	s_waitcnt lgkmcnt(0)
	v_mfma_f32_32x32x16_bf16 v[4:19], v[32:35], v[52:55], v[4:19]
	v_lshrrev_b32_e32 v52, 3, v157
	v_and_b32_e32 v64, 0xffffffc, v52
	ds_read2_b64 v[52:55], v77 offset0:28 offset1:30
	v_mul_lo_u32 v64, v64, s13
	v_cvt_pk_bf16_f32 v62, v72, v73
	v_cvt_pk_bf16_f32 v63, v74, v75
	v_add3_u32 v64, s2, v64, v65
	s_waitcnt lgkmcnt(0)
	v_mfma_f32_32x32x16_bf16 v[4:19], v[28:31], v[52:55], v[4:19]
	ds_read2_b64 v[52:55], v77 offset0:32 offset1:34
	s_waitcnt lgkmcnt(0)
	v_mfma_f32_32x32x16_bf16 v[4:19], v[36:39], v[52:55], v[4:19]
	ds_read2_b64 v[52:55], v77 offset0:36 offset1:38
	s_waitcnt lgkmcnt(0)
	v_mfma_f32_32x32x16_bf16 v[4:19], v[40:43], v[52:55], v[4:19]
	ds_read2_b64 v[52:55], v77 offset0:40 offset1:42
	s_waitcnt lgkmcnt(0)
	v_mfma_f32_32x32x16_bf16 v[4:19], v[48:51], v[52:55], v[4:19]
	ds_read2_b64 v[52:55], v77 offset0:44 offset1:46
	s_waitcnt lgkmcnt(0)
	v_mfma_f32_32x32x16_bf16 v[4:19], v[44:47], v[52:55], v[4:19]
	ds_read2_b64 v[52:55], v77 offset0:48 offset1:50
	s_waitcnt lgkmcnt(0)
	v_mfma_f32_32x32x16_bf16 v[4:19], v[56:59], v[52:55], v[4:19]
	ds_read2_b64 v[52:55], v77 offset0:52 offset1:54
	s_waitcnt lgkmcnt(0)
	v_mfma_f32_32x32x16_bf16 v[4:19], v[60:63], v[52:55], v[4:19]
	s_nop 11
	v_cvt_pk_bf16_f32 v4, v4, v5
	ds_write_b16 v64, v4
	ds_write_b16_d16_hi v64, v4 offset:144
	v_cvt_pk_bf16_f32 v4, v6, v7
	ds_write_b16 v64, v4 offset:288
	ds_write_b16_d16_hi v64, v4 offset:432
	v_cvt_pk_bf16_f32 v4, v8, v9
	ds_write_b16 v64, v4 offset:1152
	ds_write_b16_d16_hi v64, v4 offset:1296
	v_cvt_pk_bf16_f32 v4, v10, v11
	ds_write_b16 v64, v4 offset:1440
	ds_write_b16_d16_hi v64, v4 offset:1584
	v_cvt_pk_bf16_f32 v4, v12, v13
	ds_write_b16 v64, v4 offset:2304
	ds_write_b16_d16_hi v64, v4 offset:2448
	v_cvt_pk_bf16_f32 v4, v14, v15
	ds_write_b16 v64, v4 offset:2592
	ds_write_b16_d16_hi v64, v4 offset:2736
	v_cvt_pk_bf16_f32 v4, v16, v17
	ds_write_b16 v64, v4 offset:3456
	ds_write_b16_d16_hi v64, v4 offset:3600
	v_cvt_pk_bf16_f32 v4, v18, v19
	ds_write_b16 v64, v4 offset:3744
	ds_write_b16_d16_hi v64, v4 offset:3888
	v_add_u32_e32 v52, 0xd000, v76
	ds_read2_b64 v[4:7], v52 offset0:48 offset1:50
	s_waitcnt lgkmcnt(0)
	v_mfma_f32_32x32x16_bf16 v[4:19], v[20:23], v[4:7], 0
	ds_read2_b64 v[20:23], v52 offset0:52 offset1:54
	s_waitcnt lgkmcnt(0)
	v_mfma_f32_32x32x16_bf16 v[4:19], v[24:27], v[20:23], v[4:19]
	ds_read2_b64 v[20:23], v52 offset0:56 offset1:58
	s_waitcnt lgkmcnt(0)
	v_mfma_f32_32x32x16_bf16 v[4:19], v[32:35], v[20:23], v[4:19]
	ds_read2_b64 v[20:23], v52 offset0:60 offset1:62
	s_waitcnt lgkmcnt(0)
	v_mfma_f32_32x32x16_bf16 v[4:19], v[28:31], v[20:23], v[4:19]
	ds_read2_b64 v[20:23], v52 offset0:64 offset1:66
	s_waitcnt lgkmcnt(0)
	v_mfma_f32_32x32x16_bf16 v[4:19], v[36:39], v[20:23], v[4:19]
	ds_read2_b64 v[20:23], v52 offset0:68 offset1:70
	s_waitcnt lgkmcnt(0)
	v_mfma_f32_32x32x16_bf16 v[4:19], v[40:43], v[20:23], v[4:19]
	ds_read2_b64 v[20:23], v52 offset0:72 offset1:74
	s_waitcnt lgkmcnt(0)
	v_mfma_f32_32x32x16_bf16 v[4:19], v[48:51], v[20:23], v[4:19]
	ds_read2_b64 v[20:23], v52 offset0:76 offset1:78
	s_waitcnt lgkmcnt(0)
	v_mfma_f32_32x32x16_bf16 v[4:19], v[44:47], v[20:23], v[4:19]
	ds_read2_b64 v[20:23], v52 offset0:80 offset1:82
	s_waitcnt lgkmcnt(0)
	v_mfma_f32_32x32x16_bf16 v[4:19], v[56:59], v[20:23], v[4:19]
	ds_read2_b64 v[20:23], v52 offset0:84 offset1:86
	s_waitcnt lgkmcnt(0)
	v_mfma_f32_32x32x16_bf16 v[4:19], v[60:63], v[20:23], v[4:19]
	s_nop 11
	v_cvt_pk_bf16_f32 v4, v4, v5
	ds_write_b16 v64, v4 offset:64
	ds_write_b16_d16_hi v64, v4 offset:208
	v_cvt_pk_bf16_f32 v4, v6, v7
	ds_write_b16 v64, v4 offset:352
	ds_write_b16_d16_hi v64, v4 offset:496
	v_cvt_pk_bf16_f32 v4, v8, v9
	ds_write_b16 v64, v4 offset:1216
	ds_write_b16_d16_hi v64, v4 offset:1360
	v_cvt_pk_bf16_f32 v4, v10, v11
	ds_write_b16 v64, v4 offset:1504
	ds_write_b16_d16_hi v64, v4 offset:1648
	v_cvt_pk_bf16_f32 v4, v12, v13
	ds_write_b16 v64, v4 offset:2368
	ds_write_b16_d16_hi v64, v4 offset:2512
	v_cvt_pk_bf16_f32 v4, v14, v15
	ds_write_b16 v64, v4 offset:2656
	ds_write_b16_d16_hi v64, v4 offset:2800
	v_cvt_pk_bf16_f32 v4, v16, v17
	ds_write_b16 v64, v4 offset:3520
	ds_write_b16_d16_hi v64, v4 offset:3664
	v_cvt_pk_bf16_f32 v4, v18, v19
	ds_write_b16 v64, v4 offset:3808
	ds_write_b16_d16_hi v64, v4 offset:3952
	v_mul_lo_u32 v4, v152, s13
	v_lshlrev_b32_e32 v5, 4, v153
	v_add3_u32 v14, s2, v4, v5
	ds_read_b128 v[6:9], v14
	s_waitcnt vmcnt(15)
	v_lshlrev_b32_e32 v12, 16, v108
	v_and_b32_e32 v13, 0xffff0000, v108
	v_mad_i64_i32 v[4:5], s[40:41], v152, s5, v[148:149]
	s_waitcnt lgkmcnt(0)
	v_lshlrev_b32_e32 v10, 16, v6
	v_and_b32_e32 v11, 0xffff0000, v6
	v_pk_mul_f32 v[10:11], v[12:13], v[10:11]
	v_lshlrev_b32_e32 v12, 16, v109
	v_cvt_pk_bf16_f32 v6, v10, v11
	v_lshlrev_b32_e32 v10, 16, v7
	v_and_b32_e32 v11, 0xffff0000, v7
	v_and_b32_e32 v13, 0xffff0000, v109
	v_pk_mul_f32 v[10:11], v[12:13], v[10:11]
	v_lshlrev_b32_e32 v12, 16, v110
	v_cvt_pk_bf16_f32 v7, v10, v11
	v_lshlrev_b32_e32 v10, 16, v8
	v_and_b32_e32 v11, 0xffff0000, v8
	v_and_b32_e32 v13, 0xffff0000, v110
	v_pk_mul_f32 v[10:11], v[12:13], v[10:11]
	v_lshlrev_b32_e32 v12, 16, v111
	v_cvt_pk_bf16_f32 v8, v10, v11
	v_lshlrev_b32_e32 v10, 16, v9
	v_and_b32_e32 v11, 0xffff0000, v9
	v_and_b32_e32 v13, 0xffff0000, v111
	v_lshl_add_u64 v[4:5], v[4:5], 0, v[150:151]
	v_pk_mul_f32 v[10:11], v[12:13], v[10:11]
	s_mov_b32 s24, 0x30000
	v_cvt_pk_bf16_f32 v9, v10, v11
	v_add_co_u32_e32 v10, vcc, s24, v4
	s_waitcnt vmcnt(14)
	v_lshlrev_b32_e32 v12, 16, v96
	v_addc_co_u32_e32 v11, vcc, 0, v5, vcc
	global_store_dwordx4 v[10:11], v[6:9], off sc1
	ds_read_b128 v[6:9], v14 offset:1152
	v_and_b32_e32 v13, 0xffff0000, v96
	s_mov_b32 s24, 0x36000
	s_waitcnt lgkmcnt(0)
	v_lshlrev_b32_e32 v10, 16, v6
	v_and_b32_e32 v11, 0xffff0000, v6
	v_pk_mul_f32 v[10:11], v[12:13], v[10:11]
	v_lshlrev_b32_e32 v12, 16, v97
	v_cvt_pk_bf16_f32 v6, v10, v11
	v_lshlrev_b32_e32 v10, 16, v7
	v_and_b32_e32 v11, 0xffff0000, v7
	v_and_b32_e32 v13, 0xffff0000, v97
	v_pk_mul_f32 v[10:11], v[12:13], v[10:11]
	v_lshlrev_b32_e32 v12, 16, v98
	v_cvt_pk_bf16_f32 v7, v10, v11
	v_lshlrev_b32_e32 v10, 16, v8
	v_and_b32_e32 v11, 0xffff0000, v8
	v_and_b32_e32 v13, 0xffff0000, v98
	v_pk_mul_f32 v[10:11], v[12:13], v[10:11]
	v_lshlrev_b32_e32 v12, 16, v99
	v_cvt_pk_bf16_f32 v8, v10, v11
	v_lshlrev_b32_e32 v10, 16, v9
	v_and_b32_e32 v11, 0xffff0000, v9
	v_and_b32_e32 v13, 0xffff0000, v99
	v_pk_mul_f32 v[10:11], v[12:13], v[10:11]
	s_waitcnt vmcnt(14)
	v_lshlrev_b32_e32 v12, 16, v92
	v_cvt_pk_bf16_f32 v9, v10, v11
	v_add_co_u32_e32 v10, vcc, s24, v4
	v_and_b32_e32 v13, 0xffff0000, v92
	s_nop 0
	v_addc_co_u32_e32 v11, vcc, 0, v5, vcc
	global_store_dwordx4 v[10:11], v[6:9], off sc1
	ds_read_b128 v[6:9], v14 offset:2304
	s_mov_b32 s24, 0x3c000
	s_waitcnt lgkmcnt(0)
	v_lshlrev_b32_e32 v10, 16, v6
	v_and_b32_e32 v11, 0xffff0000, v6
	v_pk_mul_f32 v[10:11], v[12:13], v[10:11]
	v_lshlrev_b32_e32 v12, 16, v93
	v_cvt_pk_bf16_f32 v6, v10, v11
	v_lshlrev_b32_e32 v10, 16, v7
	v_and_b32_e32 v11, 0xffff0000, v7
	v_and_b32_e32 v13, 0xffff0000, v93
	v_pk_mul_f32 v[10:11], v[12:13], v[10:11]
	v_lshlrev_b32_e32 v12, 16, v94
	v_cvt_pk_bf16_f32 v7, v10, v11
	v_lshlrev_b32_e32 v10, 16, v8
	v_and_b32_e32 v11, 0xffff0000, v8
	v_and_b32_e32 v13, 0xffff0000, v94
	v_pk_mul_f32 v[10:11], v[12:13], v[10:11]
	v_lshlrev_b32_e32 v12, 16, v95
	v_cvt_pk_bf16_f32 v8, v10, v11
	v_lshlrev_b32_e32 v10, 16, v9
	v_and_b32_e32 v11, 0xffff0000, v9
	v_and_b32_e32 v13, 0xffff0000, v95
	v_pk_mul_f32 v[10:11], v[12:13], v[10:11]
	s_waitcnt vmcnt(14)
	v_lshlrev_b32_e32 v12, 16, v84
	v_cvt_pk_bf16_f32 v9, v10, v11
	v_add_co_u32_e32 v10, vcc, s24, v4
	v_and_b32_e32 v13, 0xffff0000, v84
	s_nop 0
	v_addc_co_u32_e32 v11, vcc, 0, v5, vcc
	global_store_dwordx4 v[10:11], v[6:9], off sc1
	ds_read_b128 v[6:9], v14 offset:3456
	s_mov_b32 s24, 0x42000
	v_add_co_u32_e32 v4, vcc, s24, v4
	s_waitcnt lgkmcnt(0)
	v_lshlrev_b32_e32 v10, 16, v6
	v_and_b32_e32 v11, 0xffff0000, v6
	v_pk_mul_f32 v[10:11], v[12:13], v[10:11]
	v_lshlrev_b32_e32 v12, 16, v85
	v_cvt_pk_bf16_f32 v6, v10, v11
	v_lshlrev_b32_e32 v10, 16, v7
	v_and_b32_e32 v11, 0xffff0000, v7
	v_and_b32_e32 v13, 0xffff0000, v85
	v_pk_mul_f32 v[10:11], v[12:13], v[10:11]
	v_lshlrev_b32_e32 v12, 16, v86
	v_cvt_pk_bf16_f32 v7, v10, v11
	v_lshlrev_b32_e32 v10, 16, v8
	v_and_b32_e32 v11, 0xffff0000, v8
	v_and_b32_e32 v13, 0xffff0000, v86
	v_pk_mul_f32 v[10:11], v[12:13], v[10:11]
	v_lshlrev_b32_e32 v12, 16, v87
	v_cvt_pk_bf16_f32 v8, v10, v11
	v_lshlrev_b32_e32 v10, 16, v9
	v_and_b32_e32 v11, 0xffff0000, v9
	v_and_b32_e32 v13, 0xffff0000, v87
	v_pk_mul_f32 v[10:11], v[12:13], v[10:11]
	v_addc_co_u32_e32 v5, vcc, 0, v5, vcc
	v_cvt_pk_bf16_f32 v9, v10, v11
	global_store_dwordx4 v[4:5], v[6:9], off sc1
	s_nop 0
	v_and_b32_e32 v116, 31, v2
	v_ashrrev_i32_e32 v4, 1, v2
	v_and_b32_e32 v4, -16, v4
	v_mul_u32_u24_e32 v5, 0x90, v116
	v_add3_u32 v92, 0, v4, v5
	ds_read_b128 v[4:7], v92 offset:13824
	s_waitcnt vmcnt(11) lgkmcnt(0)
	v_mfma_f32_32x32x16_bf16 v[52:67], v[4:7], v[144:147], 0
	ds_read_b128 v[4:7], v92 offset:13856
	s_waitcnt vmcnt(10) lgkmcnt(0)
	v_mfma_f32_32x32x16_bf16 v[52:67], v[4:7], v[140:143], v[52:67]
	ds_read_b128 v[4:7], v92 offset:13888
	s_waitcnt vmcnt(9) lgkmcnt(0)
	v_mfma_f32_32x32x16_bf16 v[52:67], v[4:7], v[136:139], v[52:67]
	ds_read_b128 v[4:7], v92 offset:13920
	s_waitcnt vmcnt(8) lgkmcnt(0)
	v_mfma_f32_32x32x16_bf16 v[52:67], v[4:7], v[132:135], v[52:67]
	ds_read_b128 v[4:7], v92 offset:18432
	s_waitcnt lgkmcnt(0)
	v_mfma_f32_32x32x16_bf16 v[36:51], v[4:7], v[144:147], 0
	ds_read_b128 v[4:7], v92 offset:18464
	s_waitcnt lgkmcnt(0)
	v_mfma_f32_32x32x16_bf16 v[36:51], v[4:7], v[140:143], v[36:51]
	ds_read_b128 v[4:7], v92 offset:18496
	s_waitcnt lgkmcnt(0)
	v_mfma_f32_32x32x16_bf16 v[36:51], v[4:7], v[136:139], v[36:51]
	ds_read_b128 v[4:7], v92 offset:18528
	s_waitcnt lgkmcnt(0)
	v_mfma_f32_32x32x16_bf16 v[36:51], v[4:7], v[132:135], v[36:51]
	ds_read_b128 v[4:7], v92 offset:23040
	s_waitcnt lgkmcnt(0)
	v_mfma_f32_32x32x16_bf16 v[20:35], v[4:7], v[144:147], 0
	ds_read_b128 v[4:7], v92 offset:23072
	s_waitcnt lgkmcnt(0)
	v_mfma_f32_32x32x16_bf16 v[20:35], v[4:7], v[140:143], v[20:35]
	ds_read_b128 v[4:7], v92 offset:23104
	s_waitcnt lgkmcnt(0)
	v_mfma_f32_32x32x16_bf16 v[20:35], v[4:7], v[136:139], v[20:35]
	ds_read_b128 v[4:7], v92 offset:23136
	s_waitcnt lgkmcnt(0)
	v_mfma_f32_32x32x16_bf16 v[20:35], v[4:7], v[132:135], v[20:35]
	ds_read_b128 v[4:7], v92 offset:27648
	ds_read_b128 v[68:71], v92 offset:27680
	s_waitcnt lgkmcnt(1)
	v_mfma_f32_32x32x16_bf16 v[4:19], v[4:7], v[144:147], 0
	s_waitcnt lgkmcnt(0)
	v_mfma_f32_32x32x16_bf16 v[4:19], v[68:71], v[140:143], v[4:19]
	ds_read_b128 v[68:71], v92 offset:27712
	s_waitcnt lgkmcnt(0)
	v_mfma_f32_32x32x16_bf16 v[4:19], v[68:71], v[136:139], v[4:19]
	ds_read_b128 v[68:71], v92 offset:27744
	s_waitcnt lgkmcnt(0)
	v_mfma_f32_32x32x16_bf16 v[4:19], v[68:71], v[132:135], v[4:19]
	ds_read_b128 v[68:71], v92 offset:32256
	ds_read_b128 v[84:87], v92 offset:32288
	s_waitcnt lgkmcnt(1)
	v_mfma_f32_32x32x16_bf16 v[68:83], v[68:71], v[144:147], 0
	s_waitcnt lgkmcnt(0)
	v_mfma_f32_32x32x16_bf16 v[68:83], v[84:87], v[140:143], v[68:83]
	ds_read_b128 v[84:87], v92 offset:32320
	s_waitcnt lgkmcnt(0)
	v_mfma_f32_32x32x16_bf16 v[68:83], v[84:87], v[136:139], v[68:83]
	ds_read_b128 v[84:87], v92 offset:32352
	s_waitcnt lgkmcnt(0)
	v_mfma_f32_32x32x16_bf16 v[68:83], v[84:87], v[132:135], v[68:83]
	v_ashrrev_i32_e32 v84, 3, v2
	v_and_b32_e32 v117, -4, v84
	v_sub_u32_e32 v84, v117, v116
	v_cmp_lt_i32_e32 vcc, 0, v84
	v_max_f32_e32 v52, v52, v52
	v_cmp_gt_u32_e64 s[40:41], s83, v84
	v_cndmask_b32_e32 v85, v237, v239, vcc
	v_max_f32_e32 v85, v85, v85
	v_min_f32_e32 v52, v52, v85
	v_cndmask_b32_e64 v85, v237, v239, s[40:41]
	v_max_f32_e32 v53, v53, v53
	v_max_f32_e32 v85, v85, v85
	v_cmp_lt_i32_e64 s[42:43], -2, v84
	v_min_f32_e32 v53, v53, v85
	v_max_f32_e32 v54, v54, v54
	v_cndmask_b32_e64 v85, v237, v239, s[42:43]
	v_max_f32_e32 v85, v85, v85
	v_cmp_lt_i32_e64 s[44:45], -3, v84
	v_min_f32_e32 v54, v54, v85
	v_max_f32_e32 v55, v55, v55
	v_cndmask_b32_e64 v85, v237, v239, s[44:45]
	v_max_f32_e32 v85, v85, v85
	v_cmp_lt_i32_e64 s[46:47], -8, v84
	v_min_f32_e32 v55, v55, v85
	v_max_f32_e32 v56, v56, v56
	v_cndmask_b32_e64 v85, v237, v239, s[46:47]
	v_max_f32_e32 v85, v85, v85
	v_cmp_lt_i32_e64 s[48:49], -9, v84
	v_min_f32_e32 v56, v56, v85
	v_max_f32_e32 v57, v57, v57
	v_cndmask_b32_e64 v85, v237, v239, s[48:49]
	v_max_f32_e32 v85, v85, v85
	v_cmp_lt_i32_e64 s[50:51], -10, v84
	v_min_f32_e32 v57, v57, v85
	v_max_f32_e32 v58, v58, v58
	v_cndmask_b32_e64 v85, v237, v239, s[50:51]
	v_max_f32_e32 v85, v85, v85
	v_cmp_lt_i32_e64 s[52:53], -11, v84
	v_min_f32_e32 v58, v58, v85
	v_max_f32_e32 v59, v59, v59
	v_cndmask_b32_e64 v85, v237, v239, s[52:53]
	v_max_f32_e32 v85, v85, v85
	v_min_f32_e32 v59, v59, v85
	v_cndmask_b32_e64 v93, v58, v237, s[38:39]
	v_cndmask_b32_e32 v58, v239, v237, vcc
	v_cndmask_b32_e64 v92, v59, v237, s[38:39]
	v_max_f32_e32 v59, v68, v68
	v_max_f32_e32 v58, v58, v58
	v_min_f32_e32 v68, v59, v58
	v_cndmask_b32_e64 v58, v239, v237, s[40:41]
	v_max_f32_e32 v59, v69, v69
	v_max_f32_e32 v58, v58, v58
	v_min_f32_e32 v69, v59, v58
	v_cndmask_b32_e64 v58, v239, v237, s[42:43]
	v_max_f32_e32 v59, v70, v70
	v_max_f32_e32 v58, v58, v58
	v_min_f32_e32 v118, v59, v58
	v_cndmask_b32_e64 v58, v239, v237, s[44:45]
	v_max_f32_e32 v59, v71, v71
	v_max_f32_e32 v58, v58, v58
	v_min_f32_e32 v119, v59, v58
	v_cndmask_b32_e64 v58, v239, v237, s[46:47]
	v_max_f32_e32 v59, v72, v72
	v_max_f32_e32 v58, v58, v58
	v_min_f32_e32 v120, v59, v58
	v_cndmask_b32_e64 v58, v239, v237, s[48:49]
	v_max_f32_e32 v59, v73, v73
	v_max_f32_e32 v58, v58, v58
	v_min_f32_e32 v121, v59, v58
	v_cndmask_b32_e64 v58, v239, v237, s[50:51]
	v_max_f32_e32 v59, v74, v74
	v_max_f32_e32 v58, v58, v58
	v_min_f32_e32 v122, v59, v58
	v_cndmask_b32_e64 v58, v239, v237, s[52:53]
	v_cmp_lt_i32_e64 s[54:55], -16, v84
	v_max_f32_e32 v59, v75, v75
	v_max_f32_e32 v58, v58, v58
	v_min_f32_e32 v123, v59, v58
	v_cndmask_b32_e64 v58, v239, v237, s[54:55]
	v_cmp_lt_i32_e64 s[56:57], s84, v84
	v_max_f32_e32 v59, v76, v76
	v_max_f32_e32 v58, v58, v58
	v_min_f32_e32 v124, v59, v58
	v_cndmask_b32_e64 v58, v239, v237, s[56:57]
	v_cmp_lt_i32_e64 s[58:59], s85, v84
	v_max_f32_e32 v59, v77, v77
	v_max_f32_e32 v58, v58, v58
	v_min_f32_e32 v125, v59, v58
	v_cndmask_b32_e64 v58, v239, v237, s[58:59]
	v_cmp_lt_i32_e64 s[60:61], s86, v84
	v_max_f32_e32 v59, v78, v78
	v_max_f32_e32 v58, v58, v58
	v_min_f32_e32 v126, v59, v58
	v_cndmask_b32_e64 v58, v239, v237, s[60:61]
	v_cndmask_b32_e64 v85, v237, v239, s[54:55]
	v_cmp_lt_i32_e64 s[62:63], s87, v84
	v_max_f32_e32 v59, v79, v79
	v_max_f32_e32 v58, v58, v58
	v_max_f32_e32 v60, v60, v60
	v_max_f32_e32 v85, v85, v85
	v_min_f32_e32 v127, v59, v58
	v_cndmask_b32_e64 v58, v239, v237, s[62:63]
	v_min_f32_e32 v60, v60, v85
	v_cndmask_b32_e64 v85, v237, v239, s[56:57]
	v_cmp_lt_i32_e64 s[64:65], s19, v84
	v_max_f32_e32 v59, v80, v80
	v_max_f32_e32 v58, v58, v58
	v_max_f32_e32 v61, v61, v61
	v_max_f32_e32 v85, v85, v85
	v_min_f32_e32 v128, v59, v58
	v_cndmask_b32_e64 v58, v239, v237, s[64:65]
	v_min_f32_e32 v61, v61, v85
	v_cndmask_b32_e64 v85, v237, v239, s[58:59]
	v_cmp_lt_i32_e64 s[66:67], s15, v84
	v_max_f32_e32 v59, v81, v81
	v_max_f32_e32 v58, v58, v58
	v_max_f32_e32 v62, v62, v62
	v_max_f32_e32 v85, v85, v85
	v_min_f32_e32 v129, v59, v58
	v_cndmask_b32_e64 v58, v239, v237, s[66:67]
	v_min_f32_e32 v62, v62, v85
	v_cndmask_b32_e64 v85, v237, v239, s[60:61]
	v_cmp_lt_i32_e64 s[68:69], s12, v84
	v_max_f32_e32 v59, v82, v82
	v_max_f32_e32 v58, v58, v58
	v_max_f32_e32 v63, v63, v63
	v_max_f32_e32 v85, v85, v85
	v_min_f32_e32 v130, v59, v58
	v_cndmask_b32_e64 v58, v239, v237, s[68:69]
	v_min_f32_e32 v63, v63, v85
	v_cndmask_b32_e64 v85, v237, v239, s[62:63]
	v_cndmask_b32_e64 v53, v53, v237, s[38:39]
	v_cndmask_b32_e64 v52, v52, v237, s[38:39]
	v_max_f32_e32 v59, v83, v83
	v_max_f32_e32 v58, v58, v58
	v_max_f32_e32 v64, v64, v64
	v_max_f32_e32 v85, v85, v85
	v_cndmask_b32_e64 v55, v55, v237, s[38:39]
	v_cndmask_b32_e64 v54, v54, v237, s[38:39]
	v_min_f32_e32 v131, v59, v58
	v_max3_f32 v58, v52, s76, v53
	v_min_f32_e32 v64, v64, v85
	v_cndmask_b32_e64 v85, v237, v239, s[64:65]
	v_cndmask_b32_e64 v57, v57, v237, s[38:39]
	v_cndmask_b32_e64 v56, v56, v237, s[38:39]
	v_max3_f32 v58, v58, v54, v55
	v_max_f32_e32 v65, v65, v65
	v_max_f32_e32 v85, v85, v85
	v_max3_f32 v58, v58, v56, v57
	v_min_f32_e32 v65, v65, v85
	v_cndmask_b32_e64 v85, v237, v239, s[66:67]
	v_cndmask_b32_e64 v84, v237, v239, s[68:69]
	v_cndmask_b32_e64 v61, v61, v237, s[38:39]
	v_cndmask_b32_e64 v60, v60, v237, s[38:39]
	v_max3_f32 v58, v58, v93, v92
	v_max_f32_e32 v66, v66, v66
	v_max_f32_e32 v85, v85, v85
	v_max_f32_e32 v67, v67, v67
	v_max_f32_e32 v84, v84, v84
	v_cndmask_b32_e64 v86, v63, v237, s[38:39]
	v_cndmask_b32_e64 v87, v62, v237, s[38:39]
	v_max3_f32 v58, v58, v60, v61
	v_min_f32_e32 v66, v66, v85
	v_min_f32_e32 v67, v67, v84
	v_cndmask_b32_e64 v65, v65, v237, s[38:39]
	v_cndmask_b32_e64 v64, v64, v237, s[38:39]
	v_max3_f32 v58, v58, v87, v86
	v_cndmask_b32_e64 v84, v67, v237, s[38:39]
	v_cndmask_b32_e64 v85, v66, v237, s[38:39]
	v_max3_f32 v58, v58, v64, v65
	v_max3_f32 v58, v58, v85, v84
	v_max3_f32 v58, v58, v36, v37
	v_max3_f32 v58, v58, v38, v39
	v_max3_f32 v58, v58, v40, v41
	v_max3_f32 v58, v58, v42, v43
	v_max3_f32 v58, v58, v44, v45
	v_max3_f32 v58, v58, v46, v47
	v_max3_f32 v58, v58, v48, v49
	v_max3_f32 v58, v58, v50, v51
	v_max3_f32 v58, v58, v20, v21
	v_max3_f32 v58, v58, v22, v23
	v_max3_f32 v58, v58, v24, v25
	v_max3_f32 v58, v58, v26, v27
	v_max3_f32 v58, v58, v28, v29
	v_max3_f32 v58, v58, v30, v31
	v_max3_f32 v58, v58, v32, v33
	v_max3_f32 v58, v58, v34, v35
	v_max3_f32 v58, v58, v4, v5
	v_max3_f32 v58, v58, v6, v7
	v_max3_f32 v58, v58, v8, v9
	v_max3_f32 v58, v58, v10, v11
	v_max3_f32 v58, v58, v12, v13
	v_max3_f32 v58, v58, v14, v15
	v_max3_f32 v58, v58, v16, v17
	v_max3_f32 v58, v58, v18, v19
	v_max3_f32 v58, v58, v68, v69
	v_max3_f32 v58, v58, v118, v119
	v_max3_f32 v58, v58, v120, v121
	v_max3_f32 v58, v58, v122, v123
	v_max3_f32 v58, v58, v124, v125
	v_max3_f32 v58, v58, v126, v127
	v_max3_f32 v58, v58, v128, v129
	v_max3_f32 v58, v58, v130, v131
	ds_bpermute_b32 v59, v155, v58
	s_waitcnt lgkmcnt(0)
	v_max3_f32 v132, v58, v59, v156
	v_sub_f32_e32 v52, v52, v132
	v_exp_f32_e32 v58, v52
	v_sub_f32_e32 v52, v53, v132
	v_exp_f32_e32 v59, v52
	v_sub_f32_e32 v52, v54, v132
	v_exp_f32_e32 v62, v52
	v_sub_f32_e32 v52, v55, v132
	v_exp_f32_e32 v63, v52
	v_sub_f32_e32 v52, v56, v132
	v_exp_f32_e32 v66, v52
	v_sub_f32_e32 v52, v57, v132
	v_exp_f32_e32 v67, v52
	v_sub_f32_e32 v52, v93, v132
	v_exp_f32_e32 v70, v52
	v_sub_f32_e32 v52, v92, v132
	v_exp_f32_e32 v71, v52
	v_sub_f32_e32 v52, v60, v132
	v_exp_f32_e32 v72, v52
	v_sub_f32_e32 v52, v61, v132
	v_exp_f32_e32 v73, v52
	v_sub_f32_e32 v52, v87, v132
	v_sub_f32_e32 v42, v42, v132
	v_exp_f32_e32 v74, v52
	v_sub_f32_e32 v52, v86, v132
	v_exp_f32_e32 v76, v42
	v_sub_f32_e32 v42, v43, v132
	v_exp_f32_e32 v75, v52
	v_sub_f32_e32 v52, v64, v132
	v_exp_f32_e32 v77, v42
	v_sub_f32_e32 v42, v44, v132
	v_exp_f32_e32 v78, v52
	v_sub_f32_e32 v52, v65, v132
	v_exp_f32_e32 v80, v42
	v_sub_f32_e32 v42, v45, v132
	v_exp_f32_e32 v79, v52
	v_sub_f32_e32 v52, v85, v132
	v_exp_f32_e32 v81, v42
	v_sub_f32_e32 v42, v46, v132
	v_exp_f32_e32 v82, v52
	v_sub_f32_e32 v52, v84, v132
	v_exp_f32_e32 v84, v42
	v_sub_f32_e32 v42, v47, v132
	v_exp_f32_e32 v85, v42
	v_sub_f32_e32 v42, v48, v132
	v_exp_f32_e32 v86, v42
	v_sub_f32_e32 v42, v49, v132
	v_exp_f32_e32 v87, v42
	v_sub_f32_e32 v42, v50, v132
	v_exp_f32_e32 v96, v42
	v_sub_f32_e32 v42, v51, v132
	v_sub_f32_e32 v20, v20, v132
	v_exp_f32_e32 v97, v42
	v_exp_f32_e32 v42, v20
	v_sub_f32_e32 v20, v21, v132
	v_exp_f32_e32 v43, v20
	v_sub_f32_e32 v20, v22, v132
	v_exp_f32_e32 v44, v20
	v_sub_f32_e32 v20, v23, v132
	v_exp_f32_e32 v45, v20
	v_sub_f32_e32 v20, v24, v132
	v_exp_f32_e32 v46, v20
	v_sub_f32_e32 v20, v25, v132
	v_exp_f32_e32 v47, v20
	v_sub_f32_e32 v20, v26, v132
	v_exp_f32_e32 v50, v20
	v_sub_f32_e32 v20, v27, v132
	v_exp_f32_e32 v51, v20
	v_sub_f32_e32 v20, v28, v132
	v_exp_f32_e32 v94, v20
	v_sub_f32_e32 v20, v29, v132
	v_exp_f32_e32 v95, v20
	v_sub_f32_e32 v20, v30, v132
	v_exp_f32_e32 v98, v20
	v_sub_f32_e32 v20, v31, v132
	v_sub_f32_e32 v4, v4, v132
	v_exp_f32_e32 v99, v20
	v_sub_f32_e32 v20, v32, v132
	v_exp_f32_e32 v48, v4
	v_sub_f32_e32 v4, v5, v132
	v_exp_f32_e32 v108, v20
	v_sub_f32_e32 v20, v33, v132
	v_exp_f32_e32 v49, v4
	v_sub_f32_e32 v4, v6, v132
	v_exp_f32_e32 v109, v20
	v_sub_f32_e32 v20, v34, v132
	v_exp_f32_e32 v92, v4
	v_sub_f32_e32 v4, v7, v132
	v_exp_f32_e32 v110, v20
	v_sub_f32_e32 v20, v35, v132
	v_exp_f32_e32 v93, v4
	v_sub_f32_e32 v4, v8, v132
	v_exp_f32_e32 v111, v20
	v_exp_f32_e32 v8, v4
	v_sub_f32_e32 v4, v9, v132
	v_sub_f32_e32 v20, v120, v132
	v_exp_f32_e32 v83, v52
	v_exp_f32_e32 v9, v4
	v_sub_f32_e32 v4, v10, v132
	v_exp_f32_e32 v52, v20
	v_sub_f32_e32 v20, v121, v132
	v_exp_f32_e32 v10, v4
	v_sub_f32_e32 v4, v11, v132
	v_exp_f32_e32 v53, v20
	v_sub_f32_e32 v20, v122, v132
	v_exp_f32_e32 v11, v4
	v_sub_f32_e32 v4, v12, v132
	v_exp_f32_e32 v54, v20
	v_sub_f32_e32 v20, v123, v132
	v_exp_f32_e32 v12, v4
	v_sub_f32_e32 v4, v13, v132
	v_exp_f32_e32 v55, v20
	v_sub_f32_e32 v20, v124, v132
	v_exp_f32_e32 v13, v4
	v_sub_f32_e32 v4, v14, v132
	v_exp_f32_e32 v56, v20
	v_sub_f32_e32 v20, v125, v132
	v_exp_f32_e32 v14, v4
	v_sub_f32_e32 v4, v15, v132
	v_exp_f32_e32 v57, v20
	v_sub_f32_e32 v20, v126, v132
	v_exp_f32_e32 v15, v4
	v_sub_f32_e32 v4, v16, v132
	v_exp_f32_e32 v60, v20
	v_sub_f32_e32 v20, v127, v132
	v_exp_f32_e32 v16, v4
	v_sub_f32_e32 v4, v17, v132
	v_exp_f32_e32 v61, v20
	v_sub_f32_e32 v20, v128, v132
	v_exp_f32_e32 v17, v4
	v_sub_f32_e32 v4, v18, v132
	v_exp_f32_e32 v64, v20
	v_sub_f32_e32 v20, v129, v132
	v_exp_f32_e32 v18, v4
	v_sub_f32_e32 v4, v19, v132
	v_exp_f32_e32 v65, v20
	v_sub_f32_e32 v20, v130, v132
	v_exp_f32_e32 v19, v4
	v_sub_f32_e32 v4, v68, v132
	v_exp_f32_e32 v68, v20
	v_sub_f32_e32 v20, v131, v132
	v_sub_f32_e32 v5, v69, v132
	v_exp_f32_e32 v69, v20
	v_add_f32_e32 v20, 0, v58
	v_add_f32_e32 v20, v59, v20
	v_add_f32_e32 v20, v62, v20
	v_add_f32_e32 v20, v63, v20
	v_add_f32_e32 v20, v66, v20
	v_add_f32_e32 v20, v67, v20
	v_add_f32_e32 v20, v70, v20
	v_add_f32_e32 v20, v71, v20
	v_add_f32_e32 v20, v72, v20
	v_add_f32_e32 v20, v73, v20
	v_add_f32_e32 v20, v74, v20
	v_sub_f32_e32 v36, v36, v132
	v_add_f32_e32 v20, v75, v20
	v_exp_f32_e32 v36, v36
	v_sub_f32_e32 v37, v37, v132
	v_add_f32_e32 v20, v78, v20
	v_exp_f32_e32 v37, v37
	v_sub_f32_e32 v38, v38, v132
	v_add_f32_e32 v20, v79, v20
	v_exp_f32_e32 v38, v38
	v_sub_f32_e32 v39, v39, v132
	v_add_f32_e32 v20, v82, v20
	v_exp_f32_e32 v39, v39
	v_sub_f32_e32 v40, v40, v132
	v_add_f32_e32 v20, v83, v20
	v_exp_f32_e32 v40, v40
	v_sub_f32_e32 v41, v41, v132
	v_add_f32_e32 v20, v36, v20
	v_exp_f32_e32 v41, v41
	v_add_f32_e32 v20, v37, v20
	v_add_f32_e32 v20, v38, v20
	v_add_f32_e32 v20, v39, v20
	v_add_f32_e32 v20, v40, v20
	v_add_f32_e32 v20, v41, v20
	v_add_f32_e32 v20, v76, v20
	v_add_f32_e32 v20, v77, v20
	v_add_f32_e32 v20, v80, v20
	v_add_f32_e32 v20, v81, v20
	v_add_f32_e32 v20, v84, v20
	v_add_f32_e32 v20, v85, v20
	v_add_f32_e32 v20, v86, v20
	v_add_f32_e32 v20, v87, v20
	v_add_f32_e32 v20, v96, v20
	v_add_f32_e32 v20, v97, v20
	v_add_f32_e32 v20, v42, v20
	v_add_f32_e32 v20, v43, v20
	v_add_f32_e32 v20, v44, v20
	v_add_f32_e32 v20, v45, v20
	v_add_f32_e32 v20, v46, v20
	v_add_f32_e32 v20, v47, v20
	v_add_f32_e32 v20, v50, v20
	v_add_f32_e32 v20, v51, v20
	v_add_f32_e32 v20, v94, v20
	v_add_f32_e32 v20, v95, v20
	v_add_f32_e32 v20, v98, v20
	v_add_f32_e32 v20, v99, v20
	v_add_f32_e32 v20, v108, v20
	v_add_f32_e32 v20, v109, v20
	v_add_f32_e32 v20, v110, v20
	v_add_f32_e32 v20, v111, v20
	v_add_f32_e32 v20, v48, v20
	v_add_f32_e32 v20, v49, v20
	v_add_f32_e32 v20, v92, v20
	v_add_f32_e32 v20, v93, v20
	v_add_f32_e32 v20, v8, v20
	v_add_f32_e32 v20, v9, v20
	v_add_f32_e32 v20, v10, v20
	v_add_f32_e32 v20, v11, v20
	v_add_f32_e32 v20, v12, v20
	v_add_f32_e32 v20, v13, v20
	v_add_f32_e32 v20, v14, v20
	v_add_f32_e32 v20, v15, v20
	v_exp_f32_e32 v4, v4
	v_add_f32_e32 v20, v16, v20
	v_exp_f32_e32 v5, v5
	v_sub_f32_e32 v6, v118, v132
	v_add_f32_e32 v20, v17, v20
	v_exp_f32_e32 v6, v6
	v_sub_f32_e32 v7, v119, v132
	v_add_f32_e32 v20, v18, v20
	v_exp_f32_e32 v7, v7
	v_add_f32_e32 v20, v19, v20
	v_add_f32_e32 v20, v4, v20
	v_add_f32_e32 v20, v5, v20
	v_add_f32_e32 v20, v6, v20
	v_add_f32_e32 v20, v7, v20
	v_add_f32_e32 v20, v52, v20
	v_add_f32_e32 v20, v53, v20
	v_add_f32_e32 v20, v54, v20
	v_add_f32_e32 v20, v55, v20
	v_add_f32_e32 v20, v56, v20
	v_add_f32_e32 v20, v57, v20
	v_add_f32_e32 v20, v60, v20
	v_add_f32_e32 v20, v61, v20
	v_add_f32_e32 v20, v64, v20
	v_add_f32_e32 v20, v65, v20
	v_add_f32_e32 v20, v68, v20
	v_add_f32_e32 v20, v69, v20
	ds_bpermute_b32 v21, v155, v20
	v_fma_f32 v22, v154, s18, -v132
	v_exp_f32_e32 v22, v22
	s_waitcnt lgkmcnt(0)
	v_add_f32_e32 v20, v20, v21
	v_add_f32_e32 v20, v22, v20
	v_div_scale_f32 v21, s[38:39], v20, v20, 1.0
	v_rcp_f32_e32 v22, v21
	s_nop 0
	v_fma_f32 v23, -v21, v22, 1.0
	v_fmac_f32_e32 v22, v23, v22
	v_div_scale_f32 v23, vcc, 1.0, v20, 1.0
	v_mul_f32_e32 v24, v23, v22
	v_fma_f32 v25, -v21, v24, v23
	v_fmac_f32_e32 v24, v25, v22
	v_fma_f32 v21, -v21, v24, v23
	v_div_fmas_f32 v21, v21, v22, v24
	v_div_fixup_f32 v118, v21, v20, 1.0
	v_pk_mul_f32 v[20:21], v[58:59], v[118:119] op_sel_hi:[1,0]
	v_pk_mul_f32 v[22:23], v[62:63], v[118:119] op_sel_hi:[1,0]
	v_pk_mul_f32 v[24:25], v[66:67], v[118:119] op_sel_hi:[1,0]
	v_pk_mul_f32 v[26:27], v[70:71], v[118:119] op_sel_hi:[1,0]
	v_pk_mul_f32 v[28:29], v[72:73], v[118:119] op_sel_hi:[1,0]
	v_pk_mul_f32 v[30:31], v[74:75], v[118:119] op_sel_hi:[1,0]
	v_pk_mul_f32 v[34:35], v[82:83], v[118:119] op_sel_hi:[1,0]
	v_pk_mul_f32 v[32:33], v[78:79], v[118:119] op_sel_hi:[1,0]
	v_cvt_pk_bf16_f32 v20, v20, v21
	v_cvt_pk_bf16_f32 v21, v22, v23
	v_cvt_pk_bf16_f32 v22, v24, v25
	v_cvt_pk_bf16_f32 v23, v26, v27
	v_cvt_pk_bf16_f32 v24, v28, v29
	v_cvt_pk_bf16_f32 v25, v30, v31
	v_cvt_pk_bf16_f32 v27, v34, v35
	v_pk_mul_f32 v[28:29], v[36:37], v[118:119] op_sel_hi:[1,0]
	v_pk_mul_f32 v[30:31], v[38:39], v[118:119] op_sel_hi:[1,0]
	v_pk_mul_f32 v[34:35], v[40:41], v[118:119] op_sel_hi:[1,0]
	v_pk_mul_f32 v[36:37], v[76:77], v[118:119] op_sel_hi:[1,0]
	v_pk_mul_f32 v[38:39], v[80:81], v[118:119] op_sel_hi:[1,0]
	v_cvt_pk_bf16_f32 v26, v32, v33
	v_cvt_pk_bf16_f32 v32, v28, v29
	v_cvt_pk_bf16_f32 v34, v34, v35
	v_cvt_pk_bf16_f32 v35, v36, v37
	v_cvt_pk_bf16_f32 v28, v38, v39
	v_pk_mul_f32 v[36:37], v[42:43], v[118:119] op_sel_hi:[1,0]
	v_pk_mul_f32 v[38:39], v[44:45], v[118:119] op_sel_hi:[1,0]
	v_pk_mul_f32 v[42:43], v[50:51], v[118:119] op_sel_hi:[1,0]
	v_pk_mul_f32 v[50:51], v[108:109], v[118:119] op_sel_hi:[1,0]
	v_pk_mul_f32 v[8:9], v[8:9], v[118:119] op_sel_hi:[1,0]
	v_cvt_pk_bf16_f32 v36, v36, v37
	v_cvt_pk_bf16_f32 v37, v38, v39
	v_cvt_pk_bf16_f32 v39, v42, v43
	v_cvt_pk_bf16_f32 v42, v50, v51
	v_cvt_pk_bf16_f32 v50, v8, v9
	v_ashrrev_i32_e32 v8, 2, v2
	v_and_b32_e32 v8, -8, v8
	v_mul_u32_u24_e32 v9, 0x208, v116
	v_add3_u32 v76, 0, v8, v9
	v_pk_mul_f32 v[10:11], v[10:11], v[118:119] op_sel_hi:[1,0]
	v_add_u32_e32 v77, 0x9000, v76
	v_cvt_pk_bf16_f32 v51, v10, v11
	ds_read2_b64 v[8:11], v77 offset0:24 offset1:26
	v_pk_mul_f32 v[40:41], v[84:85], v[118:119] op_sel_hi:[1,0]
	v_pk_mul_f32 v[58:59], v[86:87], v[118:119] op_sel_hi:[1,0]
	v_cvt_pk_bf16_f32 v29, v40, v41
	v_pk_mul_f32 v[40:41], v[46:47], v[118:119] op_sel_hi:[1,0]
	v_pk_mul_f32 v[44:45], v[94:95], v[118:119] op_sel_hi:[1,0]
	v_pk_mul_f32 v[46:47], v[98:99], v[118:119] op_sel_hi:[1,0]
	v_pk_mul_f32 v[62:63], v[96:97], v[118:119] op_sel_hi:[1,0]
	v_cvt_pk_bf16_f32 v33, v30, v31
	v_cvt_pk_bf16_f32 v30, v58, v59
	v_pk_mul_f32 v[58:59], v[110:111], v[118:119] op_sel_hi:[1,0]
	v_cvt_pk_bf16_f32 v38, v40, v41
	v_cvt_pk_bf16_f32 v40, v44, v45
	v_cvt_pk_bf16_f32 v41, v46, v47
	v_pk_mul_f32 v[44:45], v[48:49], v[118:119] op_sel_hi:[1,0]
	v_pk_mul_f32 v[46:47], v[92:93], v[118:119] op_sel_hi:[1,0]
	v_pk_mul_f32 v[12:13], v[12:13], v[118:119] op_sel_hi:[1,0]
	v_pk_mul_f32 v[14:15], v[14:15], v[118:119] op_sel_hi:[1,0]
	v_pk_mul_f32 v[16:17], v[16:17], v[118:119] op_sel_hi:[1,0]
	v_pk_mul_f32 v[18:19], v[18:19], v[118:119] op_sel_hi:[1,0]
	v_cvt_pk_bf16_f32 v31, v62, v63
	v_cvt_pk_bf16_f32 v43, v58, v59
	v_cvt_pk_bf16_f32 v48, v44, v45
	v_cvt_pk_bf16_f32 v49, v46, v47
	v_cvt_pk_bf16_f32 v44, v12, v13
	v_cvt_pk_bf16_f32 v45, v14, v15
	v_cvt_pk_bf16_f32 v46, v16, v17
	v_cvt_pk_bf16_f32 v47, v18, v19
	v_pk_mul_f32 v[58:59], v[4:5], v[118:119] op_sel_hi:[1,0]
	v_pk_mul_f32 v[62:63], v[6:7], v[118:119] op_sel_hi:[1,0]
	s_waitcnt lgkmcnt(0)
	v_mfma_f32_32x32x16_bf16 v[4:19], v[20:23], v[8:11], 0
	v_mul_f32_e64 v66, v52, v118
	v_mul_f32_e64 v67, v53, v118
	v_mul_f32_e64 v70, v54, v118
	v_mul_f32_e64 v71, v55, v118
	ds_read2_b64 v[52:55], v77 offset0:28 offset1:30
	v_pk_mul_f32 v[72:73], v[56:57], v[118:119] op_sel_hi:[1,0]
	v_pk_mul_f32 v[64:65], v[64:65], v[118:119] op_sel_hi:[1,0]
	v_pk_mul_f32 v[74:75], v[60:61], v[118:119] op_sel_hi:[1,0]
	v_pk_mul_f32 v[68:69], v[68:69], v[118:119] op_sel_hi:[1,0]
	s_waitcnt lgkmcnt(0)
	v_mfma_f32_32x32x16_bf16 v[4:19], v[24:27], v[52:55], v[4:19]
	v_cvt_pk_bf16_f32 v52, v58, v59
	ds_read2_b64 v[56:59], v77 offset0:32 offset1:34
	v_cvt_pk_bf16_f32 v53, v62, v63
	v_cvt_pk_bf16_f32 v62, v64, v65
	v_lshlrev_b32_e32 v65, 1, v2
	v_mul_lo_u32 v64, v117, s13
	v_and_b32_e32 v65, 62, v65
	s_waitcnt lgkmcnt(0)
	v_mfma_f32_32x32x16_bf16 v[4:19], v[32:35], v[56:59], v[4:19]
	ds_read2_b64 v[56:59], v77 offset0:36 offset1:38
	v_cvt_pk_bf16_f32 v54, v66, v67
	v_cvt_pk_bf16_f32 v55, v70, v71
	v_cvt_pk_bf16_f32 v60, v72, v73
	v_cvt_pk_bf16_f32 v61, v74, v75
	v_cvt_pk_bf16_f32 v63, v68, v69
	v_add3_u32 v64, s2, v64, v65
	s_waitcnt lgkmcnt(0)
	v_mfma_f32_32x32x16_bf16 v[4:19], v[28:31], v[56:59], v[4:19]
	ds_read2_b64 v[56:59], v77 offset0:40 offset1:42
	s_waitcnt lgkmcnt(0)
	v_mfma_f32_32x32x16_bf16 v[4:19], v[36:39], v[56:59], v[4:19]
	ds_read2_b64 v[56:59], v77 offset0:44 offset1:46
	s_waitcnt lgkmcnt(0)
	v_mfma_f32_32x32x16_bf16 v[4:19], v[40:43], v[56:59], v[4:19]
	ds_read2_b64 v[56:59], v77 offset0:48 offset1:50
	s_waitcnt lgkmcnt(0)
	v_mfma_f32_32x32x16_bf16 v[4:19], v[48:51], v[56:59], v[4:19]
	ds_read2_b64 v[56:59], v77 offset0:52 offset1:54
	s_waitcnt lgkmcnt(0)
	v_mfma_f32_32x32x16_bf16 v[4:19], v[44:47], v[56:59], v[4:19]
	ds_read2_b64 v[56:59], v77 offset0:56 offset1:58
	s_waitcnt lgkmcnt(0)
	v_mfma_f32_32x32x16_bf16 v[4:19], v[52:55], v[56:59], v[4:19]
	ds_read2_b64 v[56:59], v77 offset0:60 offset1:62
	s_waitcnt lgkmcnt(0)
	v_mfma_f32_32x32x16_bf16 v[4:19], v[60:63], v[56:59], v[4:19]
	s_nop 11
	v_cvt_pk_bf16_f32 v4, v4, v5
	ds_write_b16 v64, v4
	ds_write_b16_d16_hi v64, v4 offset:144
	v_cvt_pk_bf16_f32 v4, v6, v7
	ds_write_b16 v64, v4 offset:288
	ds_write_b16_d16_hi v64, v4 offset:432
	v_cvt_pk_bf16_f32 v4, v8, v9
	ds_write_b16 v64, v4 offset:1152
	ds_write_b16_d16_hi v64, v4 offset:1296
	v_cvt_pk_bf16_f32 v4, v10, v11
	ds_write_b16 v64, v4 offset:1440
	ds_write_b16_d16_hi v64, v4 offset:1584
	v_cvt_pk_bf16_f32 v4, v12, v13
	ds_write_b16 v64, v4 offset:2304
	ds_write_b16_d16_hi v64, v4 offset:2448
	v_cvt_pk_bf16_f32 v4, v14, v15
	ds_write_b16 v64, v4 offset:2592
	ds_write_b16_d16_hi v64, v4 offset:2736
	v_cvt_pk_bf16_f32 v4, v16, v17
	ds_write_b16 v64, v4 offset:3456
	ds_write_b16_d16_hi v64, v4 offset:3600
	v_cvt_pk_bf16_f32 v4, v18, v19
	ds_write_b16 v64, v4 offset:3744
	ds_write_b16_d16_hi v64, v4 offset:3888
	v_add_u32_e32 v56, 0xd000, v76
	ds_read2_b64 v[4:7], v56 offset0:56 offset1:58
	s_waitcnt lgkmcnt(0)
	v_mfma_f32_32x32x16_bf16 v[4:19], v[20:23], v[4:7], 0
	ds_read2_b64 v[20:23], v56 offset0:60 offset1:62
	s_waitcnt lgkmcnt(0)
	v_mfma_f32_32x32x16_bf16 v[4:19], v[24:27], v[20:23], v[4:19]
	ds_read2_b64 v[20:23], v56 offset0:64 offset1:66
	s_waitcnt lgkmcnt(0)
	v_mfma_f32_32x32x16_bf16 v[4:19], v[32:35], v[20:23], v[4:19]
	ds_read2_b64 v[20:23], v56 offset0:68 offset1:70
	s_waitcnt lgkmcnt(0)
	v_mfma_f32_32x32x16_bf16 v[4:19], v[28:31], v[20:23], v[4:19]
	ds_read2_b64 v[20:23], v56 offset0:72 offset1:74
	s_waitcnt lgkmcnt(0)
	v_mfma_f32_32x32x16_bf16 v[4:19], v[36:39], v[20:23], v[4:19]
	ds_read2_b64 v[20:23], v56 offset0:76 offset1:78
	s_waitcnt lgkmcnt(0)
	v_mfma_f32_32x32x16_bf16 v[4:19], v[40:43], v[20:23], v[4:19]
	ds_read2_b64 v[20:23], v56 offset0:80 offset1:82
	s_waitcnt lgkmcnt(0)
	v_mfma_f32_32x32x16_bf16 v[4:19], v[48:51], v[20:23], v[4:19]
	ds_read2_b64 v[20:23], v56 offset0:84 offset1:86
	s_waitcnt lgkmcnt(0)
	v_mfma_f32_32x32x16_bf16 v[4:19], v[44:47], v[20:23], v[4:19]
	ds_read2_b64 v[20:23], v56 offset0:88 offset1:90
	s_waitcnt lgkmcnt(0)
	v_mfma_f32_32x32x16_bf16 v[4:19], v[52:55], v[20:23], v[4:19]
	ds_read2_b64 v[20:23], v56 offset0:92 offset1:94
	s_waitcnt lgkmcnt(0)
	v_mfma_f32_32x32x16_bf16 v[4:19], v[60:63], v[20:23], v[4:19]
	s_nop 11
	v_cvt_pk_bf16_f32 v4, v4, v5
	ds_write_b16 v64, v4 offset:64
	ds_write_b16_d16_hi v64, v4 offset:208
	v_cvt_pk_bf16_f32 v4, v6, v7
	ds_write_b16 v64, v4 offset:352
	ds_write_b16_d16_hi v64, v4 offset:496
	v_cvt_pk_bf16_f32 v4, v8, v9
	ds_write_b16 v64, v4 offset:1216
	ds_write_b16_d16_hi v64, v4 offset:1360
	v_cvt_pk_bf16_f32 v4, v10, v11
	ds_write_b16 v64, v4 offset:1504
	ds_write_b16_d16_hi v64, v4 offset:1648
	v_cvt_pk_bf16_f32 v4, v12, v13
	ds_write_b16 v64, v4 offset:2368
	ds_write_b16_d16_hi v64, v4 offset:2512
	v_cvt_pk_bf16_f32 v4, v14, v15
	ds_write_b16 v64, v4 offset:2656
	ds_write_b16_d16_hi v64, v4 offset:2800
	v_cvt_pk_bf16_f32 v4, v16, v17
	ds_write_b16 v64, v4 offset:3520
	ds_write_b16_d16_hi v64, v4 offset:3664
	v_cvt_pk_bf16_f32 v4, v18, v19
	ds_write_b16 v64, v4 offset:3808
	ds_write_b16_d16_hi v64, v4 offset:3952
	v_ashrrev_i32_e32 v4, 31, v2
	v_lshrrev_b32_e32 v4, 29, v4
	v_add_u32_e32 v4, v2, v4
	v_ashrrev_i32_e32 v5, 3, v4
	v_and_b32_e32 v4, -8, v4
	v_sub_u32_e32 v2, v2, v4
	v_mul_lo_u32 v6, v5, s13
	v_lshlrev_b32_e32 v4, 4, v2
	v_add3_u32 v14, s2, v6, v4
	v_lshlrev_b32_e32 v6, 3, v2
	v_mad_i64_i32 v[4:5], s[38:39], v5, s5, v[148:149]
	v_ashrrev_i32_e32 v7, 31, v6
	v_lshl_add_u64 v[4:5], v[6:7], 1, v[4:5]
	ds_read_b128 v[6:9], v14
	s_waitcnt vmcnt(7)
	v_lshlrev_b32_e32 v12, 16, v112
	v_and_b32_e32 v13, 0xffff0000, v112
	s_mov_b32 s24, 0x48000
	s_add_i32 s14, s14, s10
	s_waitcnt lgkmcnt(0)
	v_lshlrev_b32_e32 v10, 16, v6
	v_and_b32_e32 v11, 0xffff0000, v6
	v_pk_mul_f32 v[10:11], v[12:13], v[10:11]
	v_lshlrev_b32_e32 v12, 16, v113
	v_cvt_pk_bf16_f32 v6, v10, v11
	v_lshlrev_b32_e32 v10, 16, v7
	v_and_b32_e32 v11, 0xffff0000, v7
	v_and_b32_e32 v13, 0xffff0000, v113
	v_pk_mul_f32 v[10:11], v[12:13], v[10:11]
	v_lshlrev_b32_e32 v12, 16, v114
	v_cvt_pk_bf16_f32 v7, v10, v11
	v_lshlrev_b32_e32 v10, 16, v8
	v_and_b32_e32 v11, 0xffff0000, v8
	v_and_b32_e32 v13, 0xffff0000, v114
	v_pk_mul_f32 v[10:11], v[12:13], v[10:11]
	v_lshlrev_b32_e32 v12, 16, v115
	v_cvt_pk_bf16_f32 v8, v10, v11
	v_lshlrev_b32_e32 v10, 16, v9
	v_and_b32_e32 v11, 0xffff0000, v9
	v_and_b32_e32 v13, 0xffff0000, v115
	v_pk_mul_f32 v[10:11], v[12:13], v[10:11]
	s_waitcnt vmcnt(6)
	v_lshlrev_b32_e32 v12, 16, v104
	v_cvt_pk_bf16_f32 v9, v10, v11
	v_add_co_u32_e32 v10, vcc, s24, v4
	v_and_b32_e32 v13, 0xffff0000, v104
	s_nop 0
	v_addc_co_u32_e32 v11, vcc, 0, v5, vcc
	global_store_dwordx4 v[10:11], v[6:9], off sc1
	ds_read_b128 v[6:9], v14 offset:1152
	s_mov_b32 s24, 0x4e000
	s_cmpk_gt_i32 s14, 0xff
	s_waitcnt lgkmcnt(0)
	v_lshlrev_b32_e32 v10, 16, v6
	v_and_b32_e32 v11, 0xffff0000, v6
	v_pk_mul_f32 v[10:11], v[12:13], v[10:11]
	v_lshlrev_b32_e32 v12, 16, v105
	v_cvt_pk_bf16_f32 v6, v10, v11
	v_lshlrev_b32_e32 v10, 16, v7
	v_and_b32_e32 v11, 0xffff0000, v7
	v_and_b32_e32 v13, 0xffff0000, v105
	v_pk_mul_f32 v[10:11], v[12:13], v[10:11]
	v_lshlrev_b32_e32 v12, 16, v106
	v_cvt_pk_bf16_f32 v7, v10, v11
	v_lshlrev_b32_e32 v10, 16, v8
	v_and_b32_e32 v11, 0xffff0000, v8
	v_and_b32_e32 v13, 0xffff0000, v106
	v_pk_mul_f32 v[10:11], v[12:13], v[10:11]
	v_lshlrev_b32_e32 v12, 16, v107
	v_cvt_pk_bf16_f32 v8, v10, v11
	v_lshlrev_b32_e32 v10, 16, v9
	v_and_b32_e32 v11, 0xffff0000, v9
	v_and_b32_e32 v13, 0xffff0000, v107
	v_pk_mul_f32 v[10:11], v[12:13], v[10:11]
	s_waitcnt vmcnt(6)
	v_lshlrev_b32_e32 v12, 16, v100
	v_cvt_pk_bf16_f32 v9, v10, v11
	v_add_co_u32_e32 v10, vcc, s24, v4
	v_and_b32_e32 v13, 0xffff0000, v100
	s_nop 0
	v_addc_co_u32_e32 v11, vcc, 0, v5, vcc
	global_store_dwordx4 v[10:11], v[6:9], off sc1
	ds_read_b128 v[6:9], v14 offset:2304
	s_mov_b32 s24, 0x54000
	s_waitcnt lgkmcnt(0)
	v_lshlrev_b32_e32 v10, 16, v6
	v_and_b32_e32 v11, 0xffff0000, v6
	v_pk_mul_f32 v[10:11], v[12:13], v[10:11]
	v_lshlrev_b32_e32 v12, 16, v101
	v_cvt_pk_bf16_f32 v6, v10, v11
	v_lshlrev_b32_e32 v10, 16, v7
	v_and_b32_e32 v11, 0xffff0000, v7
	v_and_b32_e32 v13, 0xffff0000, v101
	v_pk_mul_f32 v[10:11], v[12:13], v[10:11]
	v_lshlrev_b32_e32 v12, 16, v102
	v_cvt_pk_bf16_f32 v7, v10, v11
	v_lshlrev_b32_e32 v10, 16, v8
	v_and_b32_e32 v11, 0xffff0000, v8
	v_and_b32_e32 v13, 0xffff0000, v102
	v_pk_mul_f32 v[10:11], v[12:13], v[10:11]
	v_lshlrev_b32_e32 v12, 16, v103
	v_cvt_pk_bf16_f32 v8, v10, v11
	v_lshlrev_b32_e32 v10, 16, v9
	v_and_b32_e32 v11, 0xffff0000, v9
	v_and_b32_e32 v13, 0xffff0000, v103
	v_pk_mul_f32 v[10:11], v[12:13], v[10:11]
	s_waitcnt vmcnt(6)
	v_lshlrev_b32_e32 v12, 16, v88
	v_cvt_pk_bf16_f32 v9, v10, v11
	v_add_co_u32_e32 v10, vcc, s24, v4
	v_and_b32_e32 v13, 0xffff0000, v88
	s_nop 0
	v_addc_co_u32_e32 v11, vcc, 0, v5, vcc
	global_store_dwordx4 v[10:11], v[6:9], off sc1
	ds_read_b128 v[6:9], v14 offset:3456
	v_add_co_u32_e32 v4, vcc, 0x5a000, v4
	s_waitcnt lgkmcnt(0)
	v_lshlrev_b32_e32 v10, 16, v6
	v_and_b32_e32 v11, 0xffff0000, v6
	v_pk_mul_f32 v[10:11], v[12:13], v[10:11]
	v_lshlrev_b32_e32 v12, 16, v89
	v_cvt_pk_bf16_f32 v6, v10, v11
	v_lshlrev_b32_e32 v10, 16, v7
	v_and_b32_e32 v11, 0xffff0000, v7
	v_and_b32_e32 v13, 0xffff0000, v89
	v_pk_mul_f32 v[10:11], v[12:13], v[10:11]
	v_lshlrev_b32_e32 v12, 16, v90
	v_cvt_pk_bf16_f32 v7, v10, v11
	v_lshlrev_b32_e32 v10, 16, v8
	v_and_b32_e32 v11, 0xffff0000, v8
	v_and_b32_e32 v13, 0xffff0000, v90
	v_pk_mul_f32 v[10:11], v[12:13], v[10:11]
	v_lshlrev_b32_e32 v12, 16, v91
	v_cvt_pk_bf16_f32 v8, v10, v11
	v_lshlrev_b32_e32 v10, 16, v9
	v_and_b32_e32 v11, 0xffff0000, v9
	v_and_b32_e32 v13, 0xffff0000, v91
	v_pk_mul_f32 v[10:11], v[12:13], v[10:11]
	v_addc_co_u32_e32 v5, vcc, 0, v5, vcc
	v_cvt_pk_bf16_f32 v9, v10, v11
	global_store_dwordx4 v[4:5], v[6:9], off sc1
	s_barrier
	s_cbranch_scc1 .LBB0_543

.LBB0_631:
	s_ashr_i32 s1, s80, 4
	s_add_i32 s20, s1, 0x4000
	s_and_b32 s0, s80, 15
	s_ashr_i32 s21, s20, 31
	s_mul_i32 s14, s20, 0x1800
	s_mul_hi_i32 s4, s20, 0x1800
	s_add_u32 s14, s72, s14
	s_addc_u32 s4, s73, s4
	s_lshl_b32 s22, s0, 7
	s_add_u32 s22, s14, s22
	s_addc_u32 s23, s4, 0
	s_lshl_b64 s[28:29], s[20:21], 8
	s_add_u32 s4, s34, s28
	s_addc_u32 s14, s35, s29
	s_lshl_b32 s21, s80, 3
	s_and_b32 s21, s21, 64
	s_lshl_b32 s24, s21, 1
	s_add_u32 s30, s4, s24
	s_addc_u32 s31, s14, 0
	s_add_u32 s4, s78, s28
	s_addc_u32 s14, s79, s29
	s_add_u32 s28, s4, s24
	s_waitcnt vmcnt(24) lgkmcnt(2)
	v_lshl_add_u64 v[6:7], s[30:31], 0, v[104:105]
	s_addc_u32 s29, s14, 0
	v_lshl_add_u64 v[4:5], s[22:23], 0, v[104:105]
	global_load_dwordx2 v[6:7], v[6:7], off
	s_nop 0
	global_load_dwordx2 v[106:107], v2, s[28:29]
	global_load_dwordx2 v[112:113], v[4:5], off
	s_or_b32 s28, s0, s74
	s_ashr_i32 s29, s28, 31
	s_lshl_b64 s[28:29], s[28:29], 2
	s_add_u32 s28, s2, s28
	s_addc_u32 s29, s3, s29
	global_load_dword v120, v3, s[28:29]
	v_lshl_or_b32 v4, s1, 7, v197
	v_ashrrev_i32_e32 v5, 31, v4
	v_lshlrev_b64 v[110:111], 9, v[4:5]
	v_lshl_or_b32 v110, s21, 2, v110
	v_lshl_add_u64 v[4:5], v[100:101], 0, v[110:111]
	s_waitcnt vmcnt(3)
	v_lshlrev_b32_e32 v121, 16, v6
	v_and_b32_e32 v123, 0xffff0000, v6
	v_lshlrev_b32_e32 v122, 16, v7
	v_and_b32_e32 v124, 0xffff0000, v7
	v_add_co_u32_e32 v6, vcc, s17, v4
	global_load_dwordx4 v[126:129], v[4:5], off nt
	global_load_dwordx4 v[130:133], v[4:5], off offset:2048 nt
	v_addc_co_u32_e32 v7, vcc, 0, v5, vcc
	v_add_co_u32_e32 v108, vcc, s91, v4
	s_movk_i32 s1, 0x6000
	s_nop 0
	v_addc_co_u32_e32 v109, vcc, 0, v5, vcc
	v_add_co_u32_e32 v8, vcc, s50, v4
	global_load_dwordx4 v[134:137], v[108:109], off nt
	global_load_dwordx4 v[138:141], v[108:109], off offset:2048 nt
	v_addc_co_u32_e32 v9, vcc, 0, v5, vcc
	s_waitcnt lgkmcnt(1)
	v_add_co_u32_e32 v10, vcc, s90, v4
	s_waitcnt vmcnt(4)
	v_mul_f32_e32 v120, 0x3fb8aa3b, v120
	s_waitcnt lgkmcnt(0)
	v_addc_co_u32_e32 v11, vcc, 0, v5, vcc
	global_load_dwordx4 v[142:145], v[6:7], off offset:2048 nt
	global_load_dwordx4 v[146:149], v[8:9], off offset:2048 nt
	global_load_dwordx4 v[150:153], v[10:11], off offset:-4096 nt
	global_load_dwordx4 v[96:99], v[10:11], off nt
	v_add_co_u32_e32 v6, vcc, s96, v4
	s_nop 1
	v_addc_co_u32_e32 v7, vcc, 0, v5, vcc
	v_add_co_u32_e32 v8, vcc, s1, v4
	s_nop 1
	v_addc_co_u32_e32 v9, vcc, 0, v5, vcc
	global_load_dwordx4 v[92:95], v[10:11], off offset:2048 nt
	global_load_dwordx4 v[88:91], v[8:9], off offset:-4096 nt
	global_load_dwordx4 v[80:83], v[8:9], off nt
	global_load_dwordx4 v[76:79], v[8:9], off offset:2048 nt
	v_add_co_u32_e32 v8, vcc, s51, v4
	s_nop 1
	v_addc_co_u32_e32 v9, vcc, 0, v5, vcc
	v_add_co_u32_e32 v10, vcc, s92, v4
	s_nop 1
	v_addc_co_u32_e32 v11, vcc, 0, v5, vcc
	global_load_dwordx4 v[84:87], v[6:7], off offset:2048 nt
	global_load_dwordx4 v[68:71], v[8:9], off offset:2048 nt
	global_load_dwordx4 v[72:75], v[10:11], off offset:-4096 nt
	global_load_dwordx4 v[64:67], v[10:11], off nt
	v_add_co_u32_e32 v6, vcc, s56, v4
	s_nop 1
	v_addc_co_u32_e32 v7, vcc, 0, v5, vcc
	v_add_co_u32_e32 v8, vcc, s93, v4
	s_nop 1
	v_addc_co_u32_e32 v9, vcc, 0, v5, vcc
	global_load_dwordx4 v[60:63], v[10:11], off offset:2048 nt
	global_load_dwordx4 v[56:59], v[8:9], off offset:-4096 nt
	global_load_dwordx4 v[48:51], v[8:9], off nt
	global_load_dwordx4 v[44:47], v[8:9], off offset:2048 nt
	v_add_co_u32_e32 v8, vcc, s57, v4
	s_nop 1
	v_addc_co_u32_e32 v9, vcc, 0, v5, vcc
	v_add_co_u32_e32 v10, vcc, s6, v4
	s_nop 1
	v_addc_co_u32_e32 v11, vcc, 0, v5, vcc
	global_load_dwordx4 v[52:55], v[6:7], off offset:2048 nt
	global_load_dwordx4 v[36:39], v[8:9], off offset:2048 nt
	global_load_dwordx4 v[40:43], v[10:11], off offset:-4096 nt
	global_load_dwordx4 v[32:35], v[10:11], off nt
	v_add_co_u32_e32 v6, vcc, s58, v4
	s_nop 1
	v_addc_co_u32_e32 v7, vcc, 0, v5, vcc
	v_add_co_u32_e32 v8, vcc, s95, v4
	s_nop 1
	v_addc_co_u32_e32 v9, vcc, 0, v5, vcc
	v_add_co_u32_e32 v4, vcc, s52, v4
	global_load_dwordx4 v[28:31], v[10:11], off offset:2048 nt
	global_load_dwordx4 v[24:27], v[8:9], off offset:-4096 nt
	global_load_dwordx4 v[16:19], v[8:9], off nt
	global_load_dwordx4 v[12:15], v[8:9], off offset:2048 nt
	v_addc_co_u32_e32 v5, vcc, 0, v5, vcc
	global_load_dwordx4 v[20:23], v[6:7], off offset:2048 nt
	global_load_dwordx4 v[8:11], v[4:5], off nt
	global_load_dwordx4 v[154:157], v[108:109], off offset:-4096 nt
	s_nop 0
	global_load_dwordx4 v[4:7], v[4:5], off offset:2048 nt
	v_and_b32_e32 v108, 0xffff0000, v112
	v_lshlrev_b32_e32 v109, 16, v113
	v_lshlrev_b32_e32 v112, 16, v112
	v_and_b32_e32 v113, 0xffff0000, v113
	s_waitcnt vmcnt(31)
	v_mov_b32_e32 v158, v127
	v_mov_b32_e32 v127, v129
	v_mov_b32_e32 v159, v128
	v_pk_mul_f32 v[126:127], v[126:127], v[112:113]
	s_movk_i32 s33, 0x6000
	v_pk_fma_f32 v[126:127], v[158:159], v[108:109], v[126:127]
	s_nop 0
	v_add_f32_e32 v125, v126, v127
	s_waitcnt vmcnt(30)
	v_mov_b32_e32 v126, v131
	v_mov_b32_e32 v131, v133
	v_mov_b32_e32 v127, v132
	v_pk_mul_f32 v[128:129], v[130:131], v[112:113]
	ds_bpermute_b32 v158, v114, v125
	v_pk_fma_f32 v[126:127], v[126:127], v[108:109], v[128:129]
	s_waitcnt lgkmcnt(0)
	v_add_f32_e32 v125, v125, v158
	v_add_f32_e32 v126, v126, v127
	ds_bpermute_b32 v127, v114, v126
	ds_bpermute_b32 v128, v115, v125
	s_waitcnt lgkmcnt(1)
	v_add_f32_e32 v126, v126, v127
	ds_bpermute_b32 v127, v115, v126
	s_waitcnt lgkmcnt(1)
	v_add_f32_e32 v125, v125, v128
	ds_bpermute_b32 v128, v116, v125
	s_waitcnt lgkmcnt(1)
	v_add_f32_e32 v126, v126, v127
	ds_bpermute_b32 v127, v116, v126
	s_waitcnt lgkmcnt(1)
	v_add_f32_e32 v125, v125, v128
	ds_bpermute_b32 v130, v117, v125
	s_waitcnt lgkmcnt(1)
	v_add_f32_e32 v131, v126, v127
	s_waitcnt vmcnt(1)
	v_mov_b32_e32 v126, v155
	v_mov_b32_e32 v155, v157
	v_mov_b32_e32 v127, v156
	v_pk_mul_f32 v[128:129], v[154:155], v[112:113]
	ds_bpermute_b32 v132, v117, v131
	v_pk_fma_f32 v[126:127], v[126:127], v[108:109], v[128:129]
	s_waitcnt lgkmcnt(1)
	v_add_f32_e32 v130, v125, v130
	v_add_f32_e32 v133, v126, v127
	v_mov_b32_e32 v126, v143
	v_mov_b32_e32 v143, v145
	v_mov_b32_e32 v127, v144
	v_pk_mul_f32 v[128:129], v[142:143], v[112:113]
	ds_bpermute_b32 v154, v114, v133
	v_pk_fma_f32 v[126:127], v[126:127], v[108:109], v[128:129]
	v_mov_b32_e32 v129, v136
	v_add_f32_e32 v127, v126, v127
	ds_bpermute_b32 v128, v114, v127
	s_waitcnt lgkmcnt(2)
	v_add_f32_e32 v126, v131, v132
	s_waitcnt lgkmcnt(1)
	v_add_f32_e32 v125, v133, v154
	ds_bpermute_b32 v131, v115, v125
	s_waitcnt lgkmcnt(1)
	v_add_f32_e32 v127, v127, v128
	v_mov_b32_e32 v128, v135
	v_mov_b32_e32 v135, v137
	v_pk_mul_f32 v[132:133], v[134:135], v[112:113]
	ds_bpermute_b32 v142, v115, v127
	v_pk_fma_f32 v[128:129], v[128:129], v[108:109], v[132:133]
	s_waitcnt lgkmcnt(1)
	v_add_f32_e32 v125, v125, v131
	v_add_f32_e32 v128, v128, v129
	ds_bpermute_b32 v129, v114, v128
	s_waitcnt lgkmcnt(1)
	v_add_f32_e32 v127, v127, v142
	ds_bpermute_b32 v132, v116, v127
	ds_bpermute_b32 v131, v116, v125
	s_waitcnt lgkmcnt(2)
	v_add_f32_e32 v128, v128, v129
	ds_bpermute_b32 v129, v115, v128
	s_waitcnt lgkmcnt(2)
	v_add_f32_e32 v127, v127, v132
	s_waitcnt lgkmcnt(1)
	v_add_f32_e32 v125, v125, v131
	ds_bpermute_b32 v131, v117, v125
	ds_bpermute_b32 v134, v117, v127
	s_waitcnt lgkmcnt(2)
	v_add_f32_e32 v135, v128, v129
	v_mov_b32_e32 v128, v139
	v_mov_b32_e32 v139, v141
	v_mov_b32_e32 v129, v140
	v_pk_mul_f32 v[132:133], v[138:139], v[112:113]
	ds_bpermute_b32 v136, v116, v135
	v_pk_fma_f32 v[128:129], v[128:129], v[108:109], v[132:133]
	v_mov_b32_e32 v133, v152
	v_add_f32_e32 v129, v128, v129
	ds_bpermute_b32 v132, v114, v129
	s_waitcnt lgkmcnt(3)
	v_add_f32_e32 v128, v125, v131
	s_waitcnt lgkmcnt(2)
	v_add_f32_e32 v125, v127, v134
	s_waitcnt lgkmcnt(1)
	v_add_f32_e32 v127, v135, v136
	ds_bpermute_b32 v131, v117, v127
	s_waitcnt lgkmcnt(1)
	v_add_f32_e32 v129, v129, v132
	v_mov_b32_e32 v132, v151
	v_mov_b32_e32 v151, v153
	v_pk_mul_f32 v[134:135], v[150:151], v[112:113]
	ds_bpermute_b32 v136, v115, v129
	v_pk_fma_f32 v[132:133], v[132:133], v[108:109], v[134:135]
	s_waitcnt lgkmcnt(0)
	v_add_f32_e32 v129, v129, v136
	v_add_f32_e32 v137, v132, v133
	v_mov_b32_e32 v132, v147
	v_mov_b32_e32 v147, v149
	v_mov_b32_e32 v133, v148
	v_pk_mul_f32 v[134:135], v[146:147], v[112:113]
	ds_bpermute_b32 v138, v114, v137
	v_pk_fma_f32 v[132:133], v[132:133], v[108:109], v[134:135]
	ds_bpermute_b32 v134, v116, v129
	v_add_f32_e32 v132, v132, v133
	ds_bpermute_b32 v133, v114, v132
	s_waitcnt lgkmcnt(2)
	v_add_f32_e32 v135, v137, v138
	ds_bpermute_b32 v136, v115, v135
	s_waitcnt lgkmcnt(2)
	v_add_f32_e32 v134, v129, v134
	v_add_f32_e32 v129, v127, v131
	s_waitcnt lgkmcnt(1)
	v_add_f32_e32 v132, v132, v133
	ds_bpermute_b32 v133, v115, v132
	s_waitcnt lgkmcnt(1)
	v_add_f32_e32 v135, v135, v136
	ds_bpermute_b32 v136, v116, v135
	ds_bpermute_b32 v137, v117, v134
	s_waitcnt lgkmcnt(2)
	v_add_f32_e32 v132, v132, v133
	ds_bpermute_b32 v133, v116, v132
	s_waitcnt lgkmcnt(2)
	v_add_f32_e32 v131, v135, v136
	s_waitcnt lgkmcnt(1)
	v_add_f32_e32 v127, v134, v137
	ds_bpermute_b32 v134, v117, v131
	s_waitcnt lgkmcnt(1)
	v_add_f32_e32 v135, v132, v133
	v_mov_b32_e32 v132, v97
	v_mov_b32_e32 v97, v99
	v_mov_b32_e32 v133, v98
	v_pk_mul_f32 v[96:97], v[96:97], v[112:113]
	ds_bpermute_b32 v136, v117, v135
	v_pk_fma_f32 v[96:97], v[132:133], v[108:109], v[96:97]
	s_nop 0
	v_add_f32_e32 v98, v96, v97
	v_mov_b32_e32 v96, v93
	v_mov_b32_e32 v93, v95
	v_mov_b32_e32 v97, v94
	v_pk_mul_f32 v[92:93], v[92:93], v[112:113]
	ds_bpermute_b32 v99, v114, v98
	v_pk_fma_f32 v[92:93], v[96:97], v[108:109], v[92:93]
	s_waitcnt lgkmcnt(0)
	v_add_f32_e32 v96, v98, v99
	v_add_f32_e32 v94, v92, v93
	ds_bpermute_b32 v95, v114, v94
	ds_bpermute_b32 v97, v115, v96
	v_add_f32_e32 v93, v131, v134
	v_add_f32_e32 v92, v135, v136
	s_waitcnt lgkmcnt(1)
	v_add_f32_e32 v98, v94, v95
	v_mov_b32_e32 v94, v89
	v_mov_b32_e32 v89, v91
	v_mov_b32_e32 v95, v90
	v_pk_mul_f32 v[88:89], v[88:89], v[112:113]
	s_waitcnt lgkmcnt(0)
	v_add_f32_e32 v90, v96, v97
	v_pk_fma_f32 v[88:89], v[94:95], v[108:109], v[88:89]
	ds_bpermute_b32 v91, v116, v90
	v_add_f32_e32 v88, v88, v89
	ds_bpermute_b32 v89, v114, v88
	ds_bpermute_b32 v99, v115, v98
	s_waitcnt lgkmcnt(2)
	v_add_f32_e32 v90, v90, v91
	ds_bpermute_b32 v91, v117, v90
	s_waitcnt lgkmcnt(2)
	v_add_f32_e32 v88, v88, v89
	ds_bpermute_b32 v89, v115, v88
	s_waitcnt lgkmcnt(2)
	v_add_f32_e32 v94, v98, v99
	ds_bpermute_b32 v95, v116, v94
	s_waitcnt lgkmcnt(1)
	v_add_f32_e32 v96, v88, v89
	v_mov_b32_e32 v88, v85
	v_mov_b32_e32 v85, v87
	v_mov_b32_e32 v89, v86
	v_pk_mul_f32 v[84:85], v[84:85], v[112:113]
	ds_bpermute_b32 v97, v116, v96
	v_pk_fma_f32 v[84:85], v[88:89], v[108:109], v[84:85]
	s_waitcnt lgkmcnt(1)
	v_add_f32_e32 v94, v94, v95
	v_add_f32_e32 v86, v84, v85
	ds_bpermute_b32 v87, v114, v86
	v_add_f32_e32 v85, v90, v91
	s_waitcnt lgkmcnt(1)
	v_add_f32_e32 v88, v96, v97
	ds_bpermute_b32 v95, v117, v94
	ds_bpermute_b32 v89, v117, v88
	s_waitcnt lgkmcnt(2)
	v_add_f32_e32 v90, v86, v87
	v_mov_b32_e32 v86, v81
	v_mov_b32_e32 v81, v83
	ds_bpermute_b32 v91, v115, v90
	v_mov_b32_e32 v87, v82
	v_pk_mul_f32 v[80:81], v[80:81], v[112:113]
	s_waitcnt lgkmcnt(2)
	v_add_f32_e32 v84, v94, v95
	v_pk_fma_f32 v[80:81], v[86:87], v[108:109], v[80:81]
	s_nop 0
	v_add_f32_e32 v82, v80, v81
	v_mov_b32_e32 v80, v77
	v_mov_b32_e32 v77, v79
	v_mov_b32_e32 v81, v78
	v_pk_mul_f32 v[76:77], v[76:77], v[112:113]
	s_waitcnt lgkmcnt(0)
	v_add_f32_e32 v78, v90, v91
	v_pk_fma_f32 v[76:77], v[80:81], v[108:109], v[76:77]
	ds_bpermute_b32 v79, v116, v78
	v_add_f32_e32 v76, v76, v77
	ds_bpermute_b32 v77, v114, v76
	ds_bpermute_b32 v83, v114, v82
	s_waitcnt lgkmcnt(2)
	v_add_f32_e32 v78, v78, v79
	ds_bpermute_b32 v79, v117, v78
	s_waitcnt lgkmcnt(2)
	v_add_f32_e32 v76, v76, v77
	ds_bpermute_b32 v77, v115, v76
	s_waitcnt lgkmcnt(2)
	v_add_f32_e32 v80, v82, v83
	ds_bpermute_b32 v81, v115, v80
	s_waitcnt lgkmcnt(1)
	v_add_f32_e32 v82, v76, v77
	v_add_f32_e32 v76, v78, v79
	v_mov_b32_e32 v78, v73
	v_mov_b32_e32 v73, v75
	v_mov_b32_e32 v79, v74
	v_pk_mul_f32 v[72:73], v[72:73], v[112:113]
	ds_bpermute_b32 v83, v116, v82
	v_pk_fma_f32 v[72:73], v[78:79], v[108:109], v[72:73]
	s_waitcnt lgkmcnt(1)
	v_add_f32_e32 v80, v80, v81
	v_add_f32_e32 v74, v72, v73
	v_mov_b32_e32 v72, v69
	v_mov_b32_e32 v69, v71
	v_mov_b32_e32 v73, v70
	v_pk_mul_f32 v[68:69], v[68:69], v[112:113]
	ds_bpermute_b32 v75, v114, v74
	v_pk_fma_f32 v[68:69], v[72:73], v[108:109], v[68:69]
	s_waitcnt lgkmcnt(1)
	v_add_f32_e32 v82, v82, v83
	v_add_f32_e32 v70, v68, v69
	ds_bpermute_b32 v71, v114, v70
	s_waitcnt lgkmcnt(1)
	v_add_f32_e32 v72, v74, v75
	ds_bpermute_b32 v73, v115, v72
	ds_bpermute_b32 v83, v117, v82
	ds_bpermute_b32 v81, v116, v80
	s_waitcnt lgkmcnt(3)
	v_add_f32_e32 v74, v70, v71
	v_mov_b32_e32 v70, v65
	v_mov_b32_e32 v65, v67
	v_mov_b32_e32 v71, v66
	v_pk_mul_f32 v[64:65], v[64:65], v[112:113]
	s_waitcnt lgkmcnt(2)
	v_add_f32_e32 v66, v72, v73
	v_pk_fma_f32 v[64:65], v[70:71], v[108:109], v[64:65]
	ds_bpermute_b32 v67, v116, v66
	v_add_f32_e32 v64, v64, v65
	ds_bpermute_b32 v65, v114, v64
	ds_bpermute_b32 v75, v115, v74
	s_waitcnt lgkmcnt(4)
	v_add_f32_e32 v68, v82, v83
	s_waitcnt lgkmcnt(2)
	v_add_f32_e32 v66, v66, v67
	ds_bpermute_b32 v67, v117, v66
	s_waitcnt lgkmcnt(2)
	v_add_f32_e32 v64, v64, v65
	ds_bpermute_b32 v65, v115, v64
	s_waitcnt lgkmcnt(2)
	v_add_f32_e32 v70, v74, v75
	ds_bpermute_b32 v71, v116, v70
	s_waitcnt lgkmcnt(2)
	v_add_f32_e32 v66, v66, v67
	v_add_f32_e32 v80, v80, v81
	s_waitcnt lgkmcnt(1)
	v_add_f32_e32 v72, v64, v65
	v_mov_b32_e32 v64, v61
	v_mov_b32_e32 v61, v63
	v_mov_b32_e32 v65, v62
	v_pk_mul_f32 v[60:61], v[60:61], v[112:113]
	ds_bpermute_b32 v81, v117, v80
	v_pk_fma_f32 v[60:61], v[64:65], v[108:109], v[60:61]
	ds_bpermute_b32 v73, v116, v72
	v_add_f32_e32 v60, v60, v61
	ds_bpermute_b32 v61, v114, v60
	s_waitcnt lgkmcnt(3)
	v_add_f32_e32 v70, v70, v71
	ds_bpermute_b32 v71, v117, v70
	v_add_f32_e32 v77, v88, v89
	s_waitcnt lgkmcnt(3)
	v_add_f32_e32 v69, v80, v81
	s_waitcnt lgkmcnt(1)
	v_add_f32_e32 v65, v60, v61
	v_mov_b32_e32 v60, v57
	v_mov_b32_e32 v57, v59
	v_mov_b32_e32 v61, v58
	v_pk_mul_f32 v[56:57], v[56:57], v[112:113]
	ds_bpermute_b32 v67, v115, v65
	v_pk_fma_f32 v[56:57], v[60:61], v[108:109], v[56:57]
	v_add_f32_e32 v62, v72, v73
	v_add_f32_e32 v58, v56, v57
	v_mov_b32_e32 v56, v53
	v_mov_b32_e32 v53, v55
	v_mov_b32_e32 v57, v54
	v_pk_mul_f32 v[52:53], v[52:53], v[112:113]
	ds_bpermute_b32 v59, v114, v58
	v_pk_fma_f32 v[52:53], v[56:57], v[108:109], v[52:53]
	s_waitcnt lgkmcnt(1)
	v_add_f32_e32 v54, v65, v67
	v_add_f32_e32 v52, v52, v53
	ds_bpermute_b32 v53, v114, v52
	s_waitcnt lgkmcnt(1)
	v_add_f32_e32 v56, v58, v59
	ds_bpermute_b32 v55, v116, v54
	ds_bpermute_b32 v57, v115, v56
	ds_bpermute_b32 v63, v117, v62
	s_waitcnt lgkmcnt(3)
	v_add_f32_e32 v52, v52, v53
	ds_bpermute_b32 v53, v115, v52
	s_waitcnt lgkmcnt(3)
	v_add_f32_e32 v54, v54, v55
	s_waitcnt lgkmcnt(2)
	v_add_f32_e32 v56, v56, v57
	ds_bpermute_b32 v55, v117, v54
	ds_bpermute_b32 v57, v116, v56
	s_waitcnt lgkmcnt(2)
	v_add_f32_e32 v52, v52, v53
	ds_bpermute_b32 v53, v116, v52
	v_add_f32_e32 v64, v70, v71
	s_waitcnt lgkmcnt(2)
	v_add_f32_e32 v58, v54, v55
	s_waitcnt lgkmcnt(1)
	v_add_f32_e32 v54, v56, v57
	ds_bpermute_b32 v55, v117, v54
	s_waitcnt lgkmcnt(1)
	v_add_f32_e32 v56, v52, v53
	v_mov_b32_e32 v52, v49
	v_mov_b32_e32 v49, v51
	v_mov_b32_e32 v53, v50
	v_pk_mul_f32 v[48:49], v[48:49], v[112:113]
	s_waitcnt lgkmcnt(0)
	v_add_f32_e32 v61, v54, v55
	v_pk_fma_f32 v[48:49], v[52:53], v[108:109], v[48:49]
	ds_bpermute_b32 v57, v117, v56
	v_add_f32_e32 v50, v48, v49
	v_mov_b32_e32 v48, v45
	v_mov_b32_e32 v45, v47
	v_mov_b32_e32 v49, v46
	v_pk_mul_f32 v[44:45], v[44:45], v[112:113]
	ds_bpermute_b32 v51, v114, v50
	v_pk_fma_f32 v[44:45], v[48:49], v[108:109], v[44:45]
	s_waitcnt lgkmcnt(1)
	v_add_f32_e32 v57, v56, v57
	v_add_f32_e32 v44, v44, v45
	ds_bpermute_b32 v45, v114, v44
	s_waitcnt lgkmcnt(1)
	v_add_f32_e32 v46, v50, v51
	ds_bpermute_b32 v47, v115, v46
	v_add_f32_e32 v62, v62, v63
	s_waitcnt lgkmcnt(1)
	v_add_f32_e32 v48, v44, v45
	v_mov_b32_e32 v44, v41
	v_mov_b32_e32 v41, v43
	v_mov_b32_e32 v45, v42
	v_pk_mul_f32 v[40:41], v[40:41], v[112:113]
	s_waitcnt lgkmcnt(0)
	v_add_f32_e32 v42, v46, v47
	v_pk_fma_f32 v[40:41], v[44:45], v[108:109], v[40:41]
	ds_bpermute_b32 v49, v115, v48
	v_add_f32_e32 v40, v40, v41
	ds_bpermute_b32 v41, v114, v40
	ds_bpermute_b32 v43, v116, v42
	s_waitcnt lgkmcnt(2)
	v_add_f32_e32 v44, v48, v49
	ds_bpermute_b32 v45, v116, v44
	s_waitcnt lgkmcnt(2)
	v_add_f32_e32 v40, v40, v41
	ds_bpermute_b32 v41, v115, v40
	v_lshl_add_u64 v[48:49], v[102:103], 0, v[110:111]
	s_waitcnt lgkmcnt(2)
	v_add_f32_e32 v42, v42, v43
	s_waitcnt lgkmcnt(1)
	v_add_f32_e32 v44, v44, v45
	ds_bpermute_b32 v43, v117, v42
	s_waitcnt lgkmcnt(1)
	v_add_f32_e32 v46, v40, v41
	v_mov_b32_e32 v40, v37
	v_mov_b32_e32 v37, v39
	v_mov_b32_e32 v41, v38
	v_pk_mul_f32 v[36:37], v[36:37], v[112:113]
	ds_bpermute_b32 v45, v117, v44
	v_pk_fma_f32 v[36:37], v[40:41], v[108:109], v[36:37]
	ds_bpermute_b32 v47, v116, v46
	v_add_f32_e32 v36, v36, v37
	ds_bpermute_b32 v37, v114, v36
	s_waitcnt lgkmcnt(3)
	v_add_f32_e32 v60, v42, v43
	s_waitcnt lgkmcnt(2)
	v_add_f32_e32 v56, v44, v45
	s_waitcnt lgkmcnt(1)
	v_add_f32_e32 v38, v46, v47
	global_load_dwordx4 v[78:81], v[48:49], off nt
	global_load_dwordx4 v[86:89], v[48:49], off offset:2048 nt
	s_waitcnt lgkmcnt(0)
	v_add_f32_e32 v40, v36, v37
	v_mov_b32_e32 v36, v33
	v_mov_b32_e32 v33, v35
	v_mov_b32_e32 v37, v34
	v_pk_mul_f32 v[32:33], v[32:33], v[112:113]
	ds_bpermute_b32 v41, v115, v40
	v_pk_fma_f32 v[32:33], v[36:37], v[108:109], v[32:33]
	ds_bpermute_b32 v39, v117, v38
	v_add_f32_e32 v34, v32, v33
	v_mov_b32_e32 v32, v29
	v_mov_b32_e32 v29, v31
	v_mov_b32_e32 v33, v30
	v_pk_mul_f32 v[28:29], v[28:29], v[112:113]
	ds_bpermute_b32 v35, v114, v34
	v_pk_fma_f32 v[28:29], v[32:33], v[108:109], v[28:29]
	s_waitcnt lgkmcnt(2)
	v_add_f32_e32 v30, v40, v41
	v_add_f32_e32 v28, v28, v29
	ds_bpermute_b32 v29, v114, v28
	s_waitcnt lgkmcnt(1)
	v_add_f32_e32 v32, v34, v35
	ds_bpermute_b32 v33, v115, v32
	ds_bpermute_b32 v31, v116, v30
	v_add_f32_e32 v63, v38, v39
	s_waitcnt lgkmcnt(2)
	v_add_f32_e32 v28, v28, v29
	ds_bpermute_b32 v29, v115, v28
	s_waitcnt lgkmcnt(2)
	v_add_f32_e32 v32, v32, v33
	ds_bpermute_b32 v33, v116, v32
	s_waitcnt lgkmcnt(2)
	v_add_f32_e32 v30, v30, v31
	ds_bpermute_b32 v31, v117, v30
	s_waitcnt lgkmcnt(2)
	v_add_f32_e32 v34, v28, v29
	v_mov_b32_e32 v28, v25
	v_mov_b32_e32 v25, v27
	v_mov_b32_e32 v29, v26
	v_pk_mul_f32 v[24:25], v[24:25], v[112:113]
	s_waitcnt lgkmcnt(1)
	v_add_f32_e32 v26, v32, v33
	v_pk_fma_f32 v[24:25], v[28:29], v[108:109], v[24:25]
	ds_bpermute_b32 v27, v117, v26
	v_add_f32_e32 v24, v24, v25
	ds_bpermute_b32 v25, v114, v24
	ds_bpermute_b32 v35, v116, v34
	s_waitcnt lgkmcnt(3)
	v_add_f32_e32 v59, v30, v31
	s_waitcnt lgkmcnt(2)
	v_add_f32_e32 v54, v26, v27
	s_waitcnt lgkmcnt(1)
	v_add_f32_e32 v24, v24, v25
	ds_bpermute_b32 v25, v115, v24
	s_waitcnt lgkmcnt(1)
	v_add_f32_e32 v28, v34, v35
	ds_bpermute_b32 v29, v117, v28
	s_waitcnt lgkmcnt(1)
	v_add_f32_e32 v26, v24, v25
	v_mov_b32_e32 v24, v21
	v_mov_b32_e32 v21, v23
	v_mov_b32_e32 v25, v22
	v_pk_mul_f32 v[20:21], v[20:21], v[112:113]
	ds_bpermute_b32 v27, v116, v26
	v_pk_fma_f32 v[20:21], v[24:25], v[108:109], v[20:21]
	s_waitcnt lgkmcnt(1)
	v_add_f32_e32 v52, v28, v29
	v_add_f32_e32 v22, v20, v21
	v_mov_b32_e32 v20, v17
	v_mov_b32_e32 v17, v19
	v_mov_b32_e32 v21, v18
	v_pk_mul_f32 v[16:17], v[16:17], v[112:113]
	ds_bpermute_b32 v23, v114, v22
	v_pk_fma_f32 v[16:17], v[20:21], v[108:109], v[16:17]
	s_waitcnt lgkmcnt(1)
	v_add_f32_e32 v53, v26, v27
	v_add_f32_e32 v16, v16, v17
	ds_bpermute_b32 v17, v114, v16
	s_waitcnt lgkmcnt(1)
	v_add_f32_e32 v18, v22, v23
	ds_bpermute_b32 v19, v115, v18
	ds_bpermute_b32 v55, v117, v53
	s_waitcnt lgkmcnt(2)
	v_add_f32_e32 v20, v16, v17
	v_mov_b32_e32 v16, v13
	v_mov_b32_e32 v13, v15
	v_mov_b32_e32 v17, v14
	v_pk_mul_f32 v[12:13], v[12:13], v[112:113]
	ds_bpermute_b32 v21, v115, v20
	v_pk_fma_f32 v[12:13], v[16:17], v[108:109], v[12:13]
	s_waitcnt lgkmcnt(2)
	v_add_f32_e32 v14, v18, v19
	v_add_f32_e32 v12, v12, v13
	ds_bpermute_b32 v13, v114, v12
	ds_bpermute_b32 v15, v116, v14
	s_waitcnt lgkmcnt(2)
	v_add_f32_e32 v16, v20, v21
	ds_bpermute_b32 v17, v116, v16
	v_add_f32_e32 v73, v53, v55
	s_waitcnt lgkmcnt(2)
	v_add_f32_e32 v12, v12, v13
	ds_bpermute_b32 v13, v115, v12
	s_waitcnt lgkmcnt(2)
	v_add_f32_e32 v65, v14, v15
	s_waitcnt lgkmcnt(1)
	v_add_f32_e32 v74, v16, v17
	ds_bpermute_b32 v75, v117, v74
	ds_bpermute_b32 v67, v117, v65
	s_waitcnt lgkmcnt(2)
	v_add_f32_e32 v82, v12, v13
	v_add_co_u32_e32 v12, vcc, s17, v48
	ds_bpermute_b32 v83, v116, v82
	s_nop 0
	v_addc_co_u32_e32 v13, vcc, 0, v49, vcc
	v_add_co_u32_e32 v14, vcc, s91, v48
	s_waitcnt lgkmcnt(0)
	v_add_f32_e32 v53, v82, v83
	v_addc_co_u32_e32 v15, vcc, 0, v49, vcc
	v_add_co_u32_e32 v16, vcc, s50, v48
	global_load_dwordx4 v[94:97], v[14:15], off offset:-4096 nt
	global_load_dwordx4 v[132:135], v[14:15], off nt
	v_addc_co_u32_e32 v17, vcc, 0, v49, vcc
	v_add_co_u32_e32 v18, vcc, s90, v48
	ds_bpermute_b32 v55, v117, v53
	s_nop 0
	v_addc_co_u32_e32 v19, vcc, 0, v49, vcc
	global_load_dwordx4 v[136:139], v[14:15], off offset:2048 nt
	global_load_dwordx4 v[140:143], v[18:19], off offset:-4096 nt
	global_load_dwordx4 v[144:147], v[12:13], off offset:2048 nt
	global_load_dwordx4 v[44:47], v[16:17], off offset:2048 nt
	global_load_dwordx4 v[40:43], v[18:19], off nt
	global_load_dwordx4 v[32:35], v[18:19], off offset:2048 nt
	v_add_co_u32_e32 v12, vcc, s96, v48
	v_add_f32_e32 v72, v65, v67
	s_nop 0
	v_addc_co_u32_e32 v13, vcc, 0, v49, vcc
	v_add_co_u32_e32 v14, vcc, s1, v48
	s_nop 1
	v_addc_co_u32_e32 v15, vcc, 0, v49, vcc
	v_add_co_u32_e32 v70, vcc, s51, v48
	global_load_dwordx4 v[36:39], v[14:15], off offset:-4096 nt
	global_load_dwordx4 v[24:27], v[14:15], off nt
	v_addc_co_u32_e32 v71, vcc, 0, v49, vcc
	v_add_co_u32_e32 v50, vcc, s92, v48
	s_nop 1
	v_addc_co_u32_e32 v51, vcc, 0, v49, vcc
	global_load_dwordx4 v[20:23], v[14:15], off offset:2048 nt
	global_load_dwordx4 v[16:19], v[50:51], off offset:-4096 nt
	global_load_dwordx4 v[28:31], v[12:13], off offset:2048 nt
	s_nop 0
	global_load_dwordx4 v[12:15], v[70:71], off offset:2048 nt
	v_add_f32_e32 v70, v74, v75
	v_mov_b32_e32 v74, v9
	v_mov_b32_e32 v9, v11
	v_mov_b32_e32 v75, v10
	v_pk_mul_f32 v[8:9], v[8:9], v[112:113]
	s_waitcnt lgkmcnt(0)
	v_add_f32_e32 v71, v53, v55
	v_pk_fma_f32 v[8:9], v[74:75], v[108:109], v[8:9]
	s_nop 0
	v_add_f32_e32 v10, v8, v9
	s_waitcnt vmcnt(16)
	v_mov_b32_e32 v8, v5
	v_mov_b32_e32 v9, v6
	v_mov_b32_e32 v5, v7
	v_mul_f32_e32 v6, v108, v123
	v_mul_f32_e32 v7, v113, v124
	v_pk_mul_f32 v[4:5], v[4:5], v[112:113]
	v_fmac_f32_e32 v6, v112, v121
	v_fmac_f32_e32 v7, v109, v122
	v_pk_fma_f32 v[4:5], v[8:9], v[108:109], v[4:5]
	v_add_f32_e32 v6, v6, v7
	v_add_f32_e32 v4, v4, v5
	ds_bpermute_b32 v7, v114, v6
	ds_bpermute_b32 v5, v114, v4
	ds_bpermute_b32 v11, v114, v10
	s_waitcnt lgkmcnt(2)
	v_add_f32_e32 v6, v6, v7
	s_waitcnt lgkmcnt(1)
	v_add_f32_e32 v4, v4, v5
	ds_bpermute_b32 v7, v115, v6
	ds_bpermute_b32 v5, v115, v4
	s_waitcnt lgkmcnt(2)
	v_add_f32_e32 v8, v10, v11
	ds_bpermute_b32 v9, v115, v8
	s_waitcnt lgkmcnt(2)
	v_add_f32_e32 v6, v6, v7
	s_waitcnt lgkmcnt(1)
	v_add_f32_e32 v4, v4, v5
	ds_bpermute_b32 v7, v116, v6
	ds_bpermute_b32 v5, v116, v4
	s_waitcnt lgkmcnt(2)
	v_add_f32_e32 v8, v8, v9
	ds_bpermute_b32 v9, v116, v8
	s_waitcnt lgkmcnt(2)
	v_add_f32_e32 v6, v6, v7
	s_waitcnt lgkmcnt(1)
	v_add_f32_e32 v4, v4, v5
	ds_bpermute_b32 v7, v117, v6
	ds_bpermute_b32 v5, v117, v4
	s_waitcnt lgkmcnt(2)
	v_add_f32_e32 v8, v8, v9
	ds_bpermute_b32 v9, v117, v8
	s_waitcnt lgkmcnt(2)
	v_add_f32_e32 v53, v6, v7
	s_waitcnt lgkmcnt(1)
	v_add_f32_e32 v65, v4, v5
	v_cndmask_b32_e64 v4, v130, v237, s[38:39]
	v_max_f32_e32 v5, v53, v120
	v_max3_f32 v5, v5, v4, v126
	v_max3_f32 v5, v5, v128, v125
	v_max3_f32 v5, v5, v129, v127
	v_max3_f32 v5, v5, v93, v92
	v_max3_f32 v5, v5, v85, v84
	v_max3_f32 v5, v5, v77, v76
	v_max3_f32 v5, v5, v69, v68
	v_max3_f32 v5, v5, v66, v64
	v_max3_f32 v5, v5, v62, v58
	v_max3_f32 v5, v5, v61, v57
	v_max3_f32 v5, v5, v60, v56
	v_max3_f32 v5, v5, v63, v59
	v_max3_f32 v5, v5, v54, v52
	v_max3_f32 v5, v5, v73, v72
	s_waitcnt lgkmcnt(0)
	v_add_f32_e32 v67, v8, v9
	v_max3_f32 v5, v5, v70, v71
	v_max3_f32 v5, v5, v67, v65
	ds_bpermute_b32 v6, v118, v5
	s_waitcnt lgkmcnt(0)
	v_max_f32_e32 v6, v6, v6
	v_max_f32_e32 v5, v5, v6
	ds_bpermute_b32 v6, v119, v5
	s_waitcnt lgkmcnt(0)
	v_max_f32_e32 v6, v6, v6
	v_max_f32_e32 v55, v5, v6
	v_sub_f32_e32 v4, v4, v55
	v_exp_f32_e32 v4, v4
	v_sub_f32_e32 v8, v126, v55
	v_exp_f32_e32 v8, v8
	v_add_f32_e32 v9, 0, v4
	s_waitcnt vmcnt(15)
	v_pk_fma_f32 v[6:7], v[78:79], v[4:5], 0 op_sel_hi:[1,0,0]
	v_pk_fma_f32 v[4:5], v[80:81], v[4:5], 0 op_sel_hi:[1,0,0]
	v_add_f32_e32 v9, v8, v9
	s_waitcnt vmcnt(14)
	v_pk_fma_f32 v[4:5], v[88:89], v[8:9], v[4:5] op_sel_hi:[1,0,1]
	v_pk_fma_f32 v[6:7], v[86:87], v[8:9], v[6:7] op_sel_hi:[1,0,1]
	v_sub_f32_e32 v8, v128, v55
	v_exp_f32_e32 v8, v8
	s_nop 0
	v_add_f32_e32 v9, v8, v9
	s_waitcnt vmcnt(13)
	v_pk_fma_f32 v[6:7], v[94:95], v[8:9], v[6:7] op_sel_hi:[1,0,1]
	v_pk_fma_f32 v[4:5], v[96:97], v[8:9], v[4:5] op_sel_hi:[1,0,1]
	v_sub_f32_e32 v8, v125, v55
	v_exp_f32_e32 v8, v8
	s_nop 0
	v_add_f32_e32 v9, v8, v9
	s_waitcnt vmcnt(9)
	v_pk_fma_f32 v[4:5], v[146:147], v[8:9], v[4:5] op_sel_hi:[1,0,1]
	v_pk_fma_f32 v[6:7], v[144:145], v[8:9], v[6:7] op_sel_hi:[1,0,1]
	v_sub_f32_e32 v8, v129, v55
	v_exp_f32_e32 v8, v8
	s_nop 0
	v_add_f32_e32 v9, v8, v9
	v_pk_fma_f32 v[6:7], v[132:133], v[8:9], v[6:7] op_sel_hi:[1,0,1]
	v_pk_fma_f32 v[4:5], v[134:135], v[8:9], v[4:5] op_sel_hi:[1,0,1]
	v_sub_f32_e32 v8, v127, v55
	v_exp_f32_e32 v8, v8
	s_nop 0
	v_add_f32_e32 v9, v8, v9
	v_pk_fma_f32 v[4:5], v[138:139], v[8:9], v[4:5] op_sel_hi:[1,0,1]
	v_pk_fma_f32 v[6:7], v[136:137], v[8:9], v[6:7] op_sel_hi:[1,0,1]
	v_sub_f32_e32 v8, v93, v55
	v_exp_f32_e32 v8, v8
	s_nop 0
	v_add_f32_e32 v9, v8, v9
	v_pk_fma_f32 v[6:7], v[140:141], v[8:9], v[6:7] op_sel_hi:[1,0,1]
	v_pk_fma_f32 v[4:5], v[142:143], v[8:9], v[4:5] op_sel_hi:[1,0,1]
	v_sub_f32_e32 v8, v92, v55
	v_exp_f32_e32 v8, v8
	s_nop 0
	v_add_f32_e32 v9, v8, v9
	s_waitcnt vmcnt(8)
	v_pk_fma_f32 v[4:5], v[46:47], v[8:9], v[4:5] op_sel_hi:[1,0,1]
	v_pk_fma_f32 v[6:7], v[44:45], v[8:9], v[6:7] op_sel_hi:[1,0,1]
	v_sub_f32_e32 v8, v85, v55
	v_exp_f32_e32 v8, v8
	s_nop 0
	v_add_f32_e32 v9, v8, v9
	s_waitcnt vmcnt(7)
	v_pk_fma_f32 v[6:7], v[40:41], v[8:9], v[6:7] op_sel_hi:[1,0,1]
	v_pk_fma_f32 v[4:5], v[42:43], v[8:9], v[4:5] op_sel_hi:[1,0,1]
	v_sub_f32_e32 v8, v84, v55
	v_exp_f32_e32 v8, v8
	s_nop 0
	v_add_f32_e32 v9, v8, v9
	s_waitcnt vmcnt(6)
	v_pk_fma_f32 v[4:5], v[34:35], v[8:9], v[4:5] op_sel_hi:[1,0,1]
	v_pk_fma_f32 v[6:7], v[32:33], v[8:9], v[6:7] op_sel_hi:[1,0,1]
	v_sub_f32_e32 v8, v77, v55
	v_exp_f32_e32 v8, v8
	s_nop 0
	v_add_f32_e32 v9, v8, v9
	s_waitcnt vmcnt(5)
	v_pk_fma_f32 v[6:7], v[36:37], v[8:9], v[6:7] op_sel_hi:[1,0,1]
	v_pk_fma_f32 v[4:5], v[38:39], v[8:9], v[4:5] op_sel_hi:[1,0,1]
	v_sub_f32_e32 v8, v76, v55
	v_exp_f32_e32 v8, v8
	s_nop 0
	v_add_f32_e32 v9, v8, v9
	s_waitcnt vmcnt(1)
	v_pk_fma_f32 v[4:5], v[30:31], v[8:9], v[4:5] op_sel_hi:[1,0,1]
	v_pk_fma_f32 v[6:7], v[28:29], v[8:9], v[6:7] op_sel_hi:[1,0,1]
	v_sub_f32_e32 v8, v69, v55
	v_exp_f32_e32 v8, v8
	s_nop 0
	v_add_f32_e32 v9, v8, v9
	v_pk_fma_f32 v[6:7], v[24:25], v[8:9], v[6:7] op_sel_hi:[1,0,1]
	v_pk_fma_f32 v[4:5], v[26:27], v[8:9], v[4:5] op_sel_hi:[1,0,1]
	v_sub_f32_e32 v8, v68, v55
	v_exp_f32_e32 v8, v8
	s_nop 0
	v_add_f32_e32 v9, v8, v9
	v_pk_fma_f32 v[4:5], v[22:23], v[8:9], v[4:5] op_sel_hi:[1,0,1]
	v_pk_fma_f32 v[6:7], v[20:21], v[8:9], v[6:7] op_sel_hi:[1,0,1]
	v_sub_f32_e32 v8, v66, v55
	v_exp_f32_e32 v8, v8
	s_nop 0
	v_add_f32_e32 v9, v8, v9
	v_pk_fma_f32 v[6:7], v[16:17], v[8:9], v[6:7] op_sel_hi:[1,0,1]
	v_pk_fma_f32 v[4:5], v[18:19], v[8:9], v[4:5] op_sel_hi:[1,0,1]
	v_sub_f32_e32 v8, v64, v55
	v_exp_f32_e32 v8, v8
	s_nop 0
	v_add_f32_e32 v64, v8, v9
	s_waitcnt vmcnt(0)
	v_pk_fma_f32 v[68:69], v[14:15], v[8:9], v[4:5] op_sel_hi:[1,0,1]
	v_pk_fma_f32 v[90:91], v[12:13], v[8:9], v[6:7] op_sel_hi:[1,0,1]
	v_add_co_u32_e32 v4, vcc, s56, v48
	s_nop 1
	v_addc_co_u32_e32 v5, vcc, 0, v49, vcc
	v_add_co_u32_e32 v6, vcc, s93, v48
	s_nop 1
	v_addc_co_u32_e32 v7, vcc, 0, v49, vcc
	global_load_dwordx4 v[28:31], v[50:51], off offset:2048 nt
	global_load_dwordx4 v[32:35], v[6:7], off offset:-4096 nt
	global_load_dwordx4 v[36:39], v[6:7], off nt
	global_load_dwordx4 v[40:43], v[6:7], off offset:2048 nt
	v_add_co_u32_e32 v6, vcc, s57, v48
	s_nop 1
	v_addc_co_u32_e32 v7, vcc, 0, v49, vcc
	v_add_co_u32_e32 v8, vcc, s6, v48
	s_nop 1
	v_addc_co_u32_e32 v9, vcc, 0, v49, vcc
	global_load_dwordx4 v[44:47], v[4:5], off offset:2048 nt
	global_load_dwordx4 v[74:77], v[6:7], off offset:2048 nt
	global_load_dwordx4 v[78:81], v[8:9], off offset:-4096 nt
	global_load_dwordx4 v[82:85], v[8:9], off nt
	v_add_co_u32_e32 v4, vcc, s58, v48
	s_nop 1
	v_addc_co_u32_e32 v5, vcc, 0, v49, vcc
	v_add_co_u32_e32 v6, vcc, s95, v48
	s_nop 1
	v_addc_co_u32_e32 v7, vcc, 0, v49, vcc
	global_load_dwordx4 v[86:89], v[8:9], off offset:2048 nt
	global_load_dwordx4 v[24:27], v[6:7], off offset:-4096 nt
	global_load_dwordx4 v[16:19], v[6:7], off nt
	global_load_dwordx4 v[12:15], v[6:7], off offset:2048 nt
	v_add_co_u32_e32 v6, vcc, s52, v48
	s_nop 1
	v_addc_co_u32_e32 v7, vcc, 0, v49, vcc
	global_load_dwordx4 v[20:23], v[4:5], off offset:2048 nt
	global_load_dwordx4 v[8:11], v[6:7], off nt
	s_nop 0
	global_load_dwordx4 v[48:51], v[50:51], off nt
	s_nop 0
	global_load_dwordx4 v[4:7], v[6:7], off offset:2048 nt
	v_sub_f32_e32 v62, v62, v55
	v_exp_f32_e32 v62, v62
	v_sub_f32_e32 v58, v58, v55
	v_exp_f32_e32 v58, v58
	s_waitcnt vmcnt(1)
	v_pk_fma_f32 v[48:49], v[48:49], v[62:63], v[90:91] op_sel_hi:[1,0,1]
	v_add_f32_e32 v64, v62, v64
	v_pk_fma_f32 v[28:29], v[28:29], v[58:59], v[48:49] op_sel_hi:[1,0,1]
	v_sub_f32_e32 v48, v61, v55
	v_exp_f32_e32 v48, v48
	v_pk_fma_f32 v[50:51], v[50:51], v[62:63], v[68:69] op_sel_hi:[1,0,1]
	v_add_f32_e32 v62, v58, v64
	v_pk_fma_f32 v[30:31], v[30:31], v[58:59], v[50:51] op_sel_hi:[1,0,1]
	v_add_f32_e32 v49, v48, v62
	v_pk_fma_f32 v[28:29], v[32:33], v[48:49], v[28:29] op_sel_hi:[1,0,1]
	v_sub_f32_e32 v32, v57, v55
	v_exp_f32_e32 v32, v32
	v_pk_fma_f32 v[30:31], v[34:35], v[48:49], v[30:31] op_sel_hi:[1,0,1]
	v_add_f32_e32 v33, v32, v49
	v_pk_fma_f32 v[30:31], v[46:47], v[32:33], v[30:31] op_sel_hi:[1,0,1]
	v_pk_fma_f32 v[28:29], v[44:45], v[32:33], v[28:29] op_sel_hi:[1,0,1]
	v_sub_f32_e32 v32, v60, v55
	v_exp_f32_e32 v32, v32
	s_nop 0
	v_add_f32_e32 v33, v32, v33
	v_pk_fma_f32 v[28:29], v[36:37], v[32:33], v[28:29] op_sel_hi:[1,0,1]
	v_pk_fma_f32 v[30:31], v[38:39], v[32:33], v[30:31] op_sel_hi:[1,0,1]
	v_sub_f32_e32 v32, v56, v55
	v_exp_f32_e32 v32, v32
	s_nop 0
	v_add_f32_e32 v33, v32, v33
	v_pk_fma_f32 v[30:31], v[42:43], v[32:33], v[30:31] op_sel_hi:[1,0,1]
	v_pk_fma_f32 v[28:29], v[40:41], v[32:33], v[28:29] op_sel_hi:[1,0,1]
	v_sub_f32_e32 v32, v63, v55
	v_exp_f32_e32 v32, v32
	s_nop 0
	v_add_f32_e32 v33, v32, v33
	v_pk_fma_f32 v[28:29], v[78:79], v[32:33], v[28:29] op_sel_hi:[1,0,1]
	v_pk_fma_f32 v[30:31], v[80:81], v[32:33], v[30:31] op_sel_hi:[1,0,1]
	v_sub_f32_e32 v32, v59, v55
	v_exp_f32_e32 v32, v32
	s_nop 0
	v_add_f32_e32 v33, v32, v33
	v_pk_fma_f32 v[30:31], v[76:77], v[32:33], v[30:31] op_sel_hi:[1,0,1]
	v_pk_fma_f32 v[28:29], v[74:75], v[32:33], v[28:29] op_sel_hi:[1,0,1]
	v_sub_f32_e32 v32, v54, v55
	v_exp_f32_e32 v32, v32
	s_nop 0
	v_add_f32_e32 v33, v32, v33
	v_pk_fma_f32 v[28:29], v[82:83], v[32:33], v[28:29] op_sel_hi:[1,0,1]
	v_pk_fma_f32 v[30:31], v[84:85], v[32:33], v[30:31] op_sel_hi:[1,0,1]
	v_sub_f32_e32 v32, v52, v55
	v_exp_f32_e32 v32, v32
	s_nop 0
	v_add_f32_e32 v33, v32, v33
	v_pk_fma_f32 v[30:31], v[88:89], v[32:33], v[30:31] op_sel_hi:[1,0,1]
	v_pk_fma_f32 v[28:29], v[86:87], v[32:33], v[28:29] op_sel_hi:[1,0,1]
	v_sub_f32_e32 v32, v73, v55
	v_exp_f32_e32 v32, v32
	s_nop 0
	v_add_f32_e32 v33, v32, v33
	v_pk_fma_f32 v[24:25], v[24:25], v[32:33], v[28:29] op_sel_hi:[1,0,1]
	v_sub_f32_e32 v28, v72, v55
	v_exp_f32_e32 v28, v28
	v_pk_fma_f32 v[26:27], v[26:27], v[32:33], v[30:31] op_sel_hi:[1,0,1]
	v_add_f32_e32 v29, v28, v33
	v_pk_fma_f32 v[20:21], v[20:21], v[28:29], v[24:25] op_sel_hi:[1,0,1]
	v_sub_f32_e32 v24, v70, v55
	v_exp_f32_e32 v24, v24
	v_pk_fma_f32 v[22:23], v[22:23], v[28:29], v[26:27] op_sel_hi:[1,0,1]
	v_add_f32_e32 v25, v24, v29
	v_pk_fma_f32 v[16:17], v[16:17], v[24:25], v[20:21] op_sel_hi:[1,0,1]
	v_sub_f32_e32 v20, v71, v55
	v_exp_f32_e32 v20, v20
	v_pk_fma_f32 v[18:19], v[18:19], v[24:25], v[22:23] op_sel_hi:[1,0,1]
	v_add_f32_e32 v21, v20, v25
	v_pk_fma_f32 v[12:13], v[12:13], v[20:21], v[16:17] op_sel_hi:[1,0,1]
	v_sub_f32_e32 v16, v67, v55
	v_exp_f32_e32 v16, v16
	v_pk_fma_f32 v[14:15], v[14:15], v[20:21], v[18:19] op_sel_hi:[1,0,1]
	v_add_f32_e32 v17, v16, v21
	v_pk_fma_f32 v[8:9], v[8:9], v[16:17], v[12:13] op_sel_hi:[1,0,1]
	v_sub_f32_e32 v12, v65, v55
	v_exp_f32_e32 v12, v12
	v_pk_fma_f32 v[10:11], v[10:11], v[16:17], v[14:15] op_sel_hi:[1,0,1]
	v_add_f32_e32 v13, v12, v17
	s_waitcnt vmcnt(0)
	v_pk_fma_f32 v[10:11], v[6:7], v[12:13], v[10:11] op_sel_hi:[1,0,1]
	v_pk_fma_f32 v[4:5], v[4:5], v[12:13], v[8:9] op_sel_hi:[1,0,1]
	ds_bpermute_b32 v12, v118, v13
	ds_bpermute_b32 v6, v118, v4
	ds_bpermute_b32 v7, v118, v5
	ds_bpermute_b32 v8, v118, v10
	ds_bpermute_b32 v9, v118, v11
	s_waitcnt lgkmcnt(4)
	v_add_f32_e32 v12, v13, v12
	ds_bpermute_b32 v13, v119, v12
	s_waitcnt lgkmcnt(3)
	v_pk_add_f32 v[4:5], v[4:5], v[6:7]
	ds_bpermute_b32 v6, v119, v4
	s_waitcnt lgkmcnt(2)
	v_pk_add_f32 v[8:9], v[10:11], v[8:9]
	ds_bpermute_b32 v7, v119, v5
	ds_bpermute_b32 v10, v119, v8
	ds_bpermute_b32 v11, v119, v9
	s_and_saveexec_b64 s[30:31], s[38:39]
	s_cbranch_execz .LBB0_630
	global_load_dwordx2 v[14:15], v2, s[22:23] offset:2048
	s_waitcnt lgkmcnt(2)
	v_pk_add_f32 v[4:5], v[4:5], v[6:7]
	s_waitcnt lgkmcnt(0)
	v_pk_add_f32 v[6:7], v[8:9], v[10:11]
	v_sub_f32_e32 v8, v53, v55
	v_sub_f32_e32 v9, v120, v55
	v_exp_f32_e32 v8, v8
	v_exp_f32_e32 v9, v9
	v_add_f32_e32 v12, v12, v13
	v_lshlrev_b32_e32 v18, 16, v107
	v_and_b32_e32 v19, 0xffff0000, v107
	v_add_f32_e32 v10, v8, v12
	v_pk_fma_f32 v[6:7], v[8:9], v[18:19], v[6:7] op_sel_hi:[0,1,1]
	v_add_f32_e32 v9, v9, v10
	s_mul_hi_i32 s1, s20, 0xc00
	s_mul_i32 s4, s20, 0xc00
	v_div_scale_f32 v10, s[20:21], v9, v9, 1.0
	v_rcp_f32_e32 v11, v10
	v_lshlrev_b32_e32 v16, 16, v106
	v_and_b32_e32 v17, 0xffff0000, v106
	v_pk_fma_f32 v[4:5], v[8:9], v[16:17], v[4:5] op_sel_hi:[0,1,1]
	v_fma_f32 v12, -v10, v11, 1.0
	v_div_scale_f32 v8, vcc, 1.0, v9, 1.0
	v_fmac_f32_e32 v11, v12, v11
	v_mul_f32_e32 v12, v8, v11
	v_fma_f32 v13, -v10, v12, v8
	v_fmac_f32_e32 v12, v13, v11
	v_fma_f32 v8, -v10, v12, v8
	s_lshl_b32 s0, s0, 6
	v_div_fmas_f32 v8, v8, v11, v12
	s_add_u32 s4, s81, s4
	v_div_fixup_f32 v8, v8, v9, 1.0
	s_addc_u32 s1, s9, s1
	s_lshl_b32 s0, s0, 1
	v_mul_f32_e32 v4, v8, v4
	v_mul_f32_e32 v5, v8, v5
	v_mul_f32_e32 v6, v8, v6
	v_mul_f32_e32 v7, v8, v7
	s_add_u32 s0, s4, s0
	s_addc_u32 s1, s1, 0
	s_waitcnt vmcnt(0)
	v_lshlrev_b32_e32 v8, 16, v14
	v_and_b32_e32 v9, 0xffff0000, v14
	v_lshlrev_b32_e32 v10, 16, v15
	v_and_b32_e32 v11, 0xffff0000, v15
	v_mul_f32_e32 v4, v4, v8
	v_mul_f32_e32 v5, v5, v9
	v_mul_f32_e32 v6, v6, v10
	v_mul_f32_e32 v7, v7, v11
	v_cvt_pk_bf16_f32 v4, v4, v5
	v_cvt_pk_bf16_f32 v5, v6, v7
	global_store_dwordx2 v2, v[4:5], s[0:1] sc1
	s_branch .LBB0_630

.LBB0_655:
	s_add_i32 s24, s28, s68
	s_cmp_eq_u32 s24, 0
	s_cselect_b64 s[38:39], -1, 0
	s_and_saveexec_b64 s[70:71], s[40:41]
	s_cbranch_execz .LBB0_658
	s_and_b64 s[56:57], s[48:49], s[38:39]
	s_waitcnt vmcnt(16)
	ds_write_b128 v181, v[108:111]
	s_and_b64 exec, exec, s[56:57]
	s_cbranch_execz .LBB0_658
	v_readlane_b32 s20, v253, 11
	v_readlane_b32 s21, v253, 12
	s_load_dwordx2 s[56:57], s[20:21], 0xc8
	s_lshl_b32 s24, s14, 2
	v_lshlrev_b32_e32 v2, 2, v126
	v_lshlrev_b32_e32 v4, 16, v108
	v_and_b32_e32 v5, 0xffff0000, v108
	s_waitcnt lgkmcnt(0)
	v_lshl_add_u64 v[6:7], s[56:57], 0, v[144:145]
	v_lshl_add_u64 v[6:7], v[6:7], 0, s[24:25]
	v_lshl_add_u64 v[8:9], v[6:7], 0, v[2:3]
	v_lshl_add_u64 v[10:11], v[8:9], 0, s[2:3]
	v_add_co_u32_e32 v8, vcc, 0x4884000, v8
	v_lshlrev_b32_e32 v6, 16, v109
	v_and_b32_e32 v7, 0xffff0000, v109
	v_addc_co_u32_e32 v9, vcc, 0, v9, vcc
	global_store_dwordx4 v[8:9], v[4:7], off sc1
	s_nop 1
	v_lshlrev_b32_e32 v4, 16, v110
	v_and_b32_e32 v5, 0xffff0000, v110
	v_lshlrev_b32_e32 v6, 16, v111
	v_and_b32_e32 v7, 0xffff0000, v111
	global_store_dwordx4 v[10:11], v[4:7], off offset:16 sc1
.LBB0_658:
	s_or_b64 exec, exec, s[70:71]
	s_and_saveexec_b64 s[70:71], s[42:43]
	s_cbranch_execz .LBB0_661
	s_and_b64 s[56:57], s[50:51], s[38:39]
	s_waitcnt vmcnt(16)
	ds_write_b128 v177, v[112:115]
	s_and_b64 exec, exec, s[56:57]
	s_cbranch_execz .LBB0_661
	v_readlane_b32 s20, v253, 11
	v_readlane_b32 s21, v253, 12
	s_load_dwordx2 s[56:57], s[20:21], 0xc8
	s_lshl_b32 s24, s14, 2
	v_lshlrev_b32_e32 v2, 2, v126
	v_lshlrev_b32_e32 v4, 16, v112
	v_and_b32_e32 v5, 0xffff0000, v112
	s_waitcnt lgkmcnt(0)
	v_lshl_add_u64 v[6:7], s[56:57], 0, v[146:147]
	v_lshl_add_u64 v[6:7], v[6:7], 0, s[24:25]
	v_lshl_add_u64 v[8:9], v[6:7], 0, v[2:3]
	v_lshl_add_u64 v[10:11], v[8:9], 0, s[2:3]
	v_add_co_u32_e32 v8, vcc, 0x4884000, v8
	v_lshlrev_b32_e32 v6, 16, v113
	v_and_b32_e32 v7, 0xffff0000, v113
	v_addc_co_u32_e32 v9, vcc, 0, v9, vcc
	global_store_dwordx4 v[8:9], v[4:7], off sc1
	s_nop 1
	v_lshlrev_b32_e32 v4, 16, v114
	v_and_b32_e32 v5, 0xffff0000, v114
	v_lshlrev_b32_e32 v6, 16, v115
	v_and_b32_e32 v7, 0xffff0000, v115
	global_store_dwordx4 v[10:11], v[4:7], off offset:16 sc1
.LBB0_661:
	s_or_b64 exec, exec, s[70:71]
	s_and_saveexec_b64 s[70:71], s[44:45]
	s_cbranch_execz .LBB0_664
	s_and_b64 s[38:39], s[52:53], s[38:39]
	s_waitcnt vmcnt(16)
	ds_write_b128 v178, v[116:119]
	s_and_b64 exec, exec, s[38:39]
	s_cbranch_execz .LBB0_664
	v_readlane_b32 s20, v253, 11
	v_readlane_b32 s21, v253, 12
	s_load_dwordx2 s[38:39], s[20:21], 0xc8
	s_lshl_b32 s24, s14, 2
	v_lshlrev_b32_e32 v2, 2, v126
	v_lshlrev_b32_e32 v4, 16, v116
	v_and_b32_e32 v5, 0xffff0000, v116
	s_waitcnt lgkmcnt(0)
	v_lshl_add_u64 v[6:7], s[38:39], 0, v[148:149]
	v_lshl_add_u64 v[6:7], v[6:7], 0, s[24:25]
	v_lshl_add_u64 v[8:9], v[6:7], 0, v[2:3]
	v_lshl_add_u64 v[10:11], v[8:9], 0, s[2:3]
	v_add_co_u32_e32 v8, vcc, 0x4884000, v8
	v_lshlrev_b32_e32 v6, 16, v117
	v_and_b32_e32 v7, 0xffff0000, v117
	v_addc_co_u32_e32 v9, vcc, 0, v9, vcc
	global_store_dwordx4 v[8:9], v[4:7], off sc1
	s_nop 1
	v_lshlrev_b32_e32 v4, 16, v118
	v_and_b32_e32 v5, 0xffff0000, v118
	v_lshlrev_b32_e32 v6, 16, v119
	v_and_b32_e32 v7, 0xffff0000, v119
	global_store_dwordx4 v[10:11], v[4:7], off offset:16 sc1

.LBB0_676:
	v_writelane_b32 v254, s4, 37
	s_nop 0
	v_readlane_b32 s2, v254, 26
	v_readlane_b32 s3, v254, 27
	s_lshl_b64 s[20:21], s[2:3], 17
	s_add_u32 s0, s36, 0xfb00000
	s_addc_u32 s4, s37, 0
	s_and_b64 vcc, exec, s[66:67]
	s_cbranch_vccz .LBB0_680
	s_add_u32 s14, s0, s20
	s_addc_u32 s24, s4, s21
	s_lshl_b32 s9, s9, 3
	s_or_b32 s28, s9, s58
	s_ashr_i32 s29, s28, 31
	s_lshl_b64 s[28:29], s[28:29], 9
	s_add_u32 s28, s14, s28
	s_addc_u32 s29, s24, s29
	v_lshlrev_b32_e32 v2, 3, v122
	global_store_dwordx2 v2, v[4:5], s[28:29] sc1
	s_waitcnt vmcnt(0)
	v_cmp_eq_u32_e32 vcc, 0, v122
	s_and_saveexec_b64 s[40:41], vcc
	s_cbranch_execz .LBB0_679
	v_readlane_b32 s2, v254, 26
	s_lshl_b32 s14, s2, 8
	s_add_i32 s9, s9, s14
	s_or_b32 s28, s9, s58
	s_ashr_i32 s29, s28, 31
	s_lshl_b64 s[28:29], s[28:29], 8
	buffer_wbl2 sc1
	s_waitcnt vmcnt(0)
	s_waitcnt vmcnt(0)
	s_add_u32 s28, s36, s28
	s_addc_u32 s29, s37, s29
	v_mov_b32_e32 v2, 0x180000
	v_readlane_b32 s3, v254, 27
	global_store_dword v2, v245, s[28:29] sc1

.LBB0_758:
	s_ashr_i32 s40, s43, 7
	s_lshl_b32 s24, s40, 8
	s_add_i32 s44, s24, s95
	s_ashr_i32 s45, s44, 31
	s_lshl_b64 s[44:45], s[44:45], 10
	s_add_u32 s41, s92, s44
	s_addc_u32 s47, s9, s45
	s_and_b32 s24, s42, 0x180
	s_lshl_b32 s24, s24, 1
	s_add_u32 s46, s41, s24
	s_addc_u32 s47, s47, 0
	v_mov_b32_e32 v211, v204
	s_add_u32 s41, s56, s44
	s_addc_u32 s45, s57, s45
	v_ashrrev_i32_e32 v62, 5, v211
	v_and_b32_e32 v69, -8, v62
	s_add_u32 s44, s41, s24
	v_and_b32_e32 v68, 0xff, v211
	v_lshlrev_b32_e32 v4, 3, v69
	s_addc_u32 s45, s45, 0
	v_lshlrev_b32_e32 v2, 10, v68
	v_ashrrev_i32_e32 v5, 31, v4
	v_or_b32_e32 v70, 1, v69
	v_lshl_add_u64 v[60:61], s[46:47], 0, v[2:3]
	v_lshl_add_u64 v[64:65], s[44:45], 0, v[2:3]
	v_lshlrev_b64 v[8:9], 1, v[4:5]
	v_lshlrev_b32_e32 v16, 3, v70
	v_or_b32_e32 v71, 2, v69
	v_or_b32_e32 v73, 4, v69
	v_lshl_add_u64 v[28:29], v[60:61], 0, v[8:9]
	v_lshl_add_u64 v[8:9], v[64:65], 0, v[8:9]
	v_ashrrev_i32_e32 v17, 31, v16
	v_lshlrev_b32_e32 v24, 3, v71
	v_or_b32_e32 v72, 3, v69
	v_lshlrev_b32_e32 v36, 3, v73
	global_load_dwordx4 v[4:7], v[28:29], off
	s_nop 0
	global_load_dwordx4 v[8:11], v[8:9], off
	s_nop 0
	global_load_dwordx4 v[12:15], v[28:29], off offset:16
	v_lshl_add_u64 v[16:17], v[16:17], 1, v[64:65]
	v_ashrrev_i32_e32 v25, 31, v24
	v_lshlrev_b32_e32 v32, 3, v72
	v_ashrrev_i32_e32 v37, 31, v36
	global_load_dwordx4 v[16:19], v[16:17], off
	s_nop 0
	global_load_dwordx4 v[20:23], v[28:29], off offset:32
	v_lshl_add_u64 v[24:25], v[24:25], 1, v[64:65]
	v_ashrrev_i32_e32 v33, 31, v32
	v_lshlrev_b64 v[40:41], 1, v[36:37]
	v_or_b32_e32 v74, 5, v69
	v_or_b32_e32 v75, 6, v69
	v_or_b32_e32 v76, 7, v62
	global_load_dwordx4 v[24:27], v[24:25], off
	s_nop 0
	global_load_dwordx4 v[28:31], v[28:29], off offset:48
	v_lshl_add_u64 v[32:33], v[32:33], 1, v[64:65]
	v_lshl_add_u64 v[52:53], v[60:61], 0, v[40:41]
	v_lshlrev_b32_e32 v48, 3, v74
	v_lshlrev_b32_e32 v56, 3, v75
	v_lshlrev_b32_e32 v62, 3, v76
	global_load_dwordx4 v[32:35], v[32:33], off
	v_lshl_add_u64 v[40:41], v[64:65], 0, v[40:41]
	global_load_dwordx4 v[36:39], v[52:53], off
	v_ashrrev_i32_e32 v49, 31, v48
	v_ashrrev_i32_e32 v57, 31, v56
	v_ashrrev_i32_e32 v63, 31, v62
	global_load_dwordx4 v[40:43], v[40:41], off
	v_lshl_add_u64 v[48:49], v[48:49], 1, v[64:65]
	global_load_dwordx4 v[44:47], v[52:53], off offset:16
	v_lshl_add_u64 v[56:57], v[56:57], 1, v[64:65]
	v_lshlrev_b64 v[66:67], 1, v[62:63]
	global_load_dwordx4 v[48:51], v[48:49], off
	v_lshl_add_u64 v[60:61], v[60:61], 0, v[66:67]
	global_load_dwordx4 v[56:59], v[56:57], off
	v_lshl_add_u64 v[64:65], v[64:65], 0, v[66:67]
	global_load_dwordx4 v[52:55], v[52:53], off offset:32
	v_mad_u32_u24 v77, v68, s31, 0
	global_load_dwordx4 v[60:63], v[60:61], off
	v_lshl_add_u32 v2, v68, 1, s11
	global_load_dwordx4 v[64:67], v[64:65], off
	v_lshl_add_u32 v78, v69, 4, v77
	v_mad_u64_u32 v[68:69], s[44:45], v69, s77, v[2:3]
	v_lshl_add_u32 v69, v70, 4, v77
	s_ashr_i32 s41, s40, 31
	s_lshl_b64 s[40:41], s[40:41], 13
	v_and_b32_e32 v213, 31, v211
	v_bfe_u32 v210, v211, 4, 2
	s_waitcnt vmcnt(15)
	ds_write_b128 v78, v[4:7]
	s_waitcnt vmcnt(14)
	ds_write_b16 v68, v8
	ds_write_b16_d16_hi v68, v8 offset:520
	ds_write_b16 v68, v9 offset:1040
	ds_write_b16_d16_hi v68, v9 offset:1560
	ds_write_b16 v68, v10 offset:2080
	ds_write_b16_d16_hi v68, v10 offset:2600
	ds_write_b16 v68, v11 offset:3120
	ds_write_b16_d16_hi v68, v11 offset:3640
	s_waitcnt vmcnt(13)
	ds_write_b128 v69, v[12:15]
	s_waitcnt vmcnt(12)
	ds_write_b16 v68, v16 offset:4160
	ds_write_b16_d16_hi v68, v16 offset:4680
	ds_write_b16 v68, v17 offset:5200
	ds_write_b16_d16_hi v68, v17 offset:5720
	ds_write_b16 v68, v18 offset:6240
	ds_write_b16_d16_hi v68, v18 offset:6760
	ds_write_b16 v68, v19 offset:7280
	ds_write_b16_d16_hi v68, v19 offset:7800
	v_lshl_add_u32 v4, v71, 4, v77
	s_waitcnt vmcnt(11)
	ds_write_b128 v4, v[20:23]
	s_waitcnt vmcnt(10)
	ds_write_b16 v68, v24 offset:8320
	ds_write_b16_d16_hi v68, v24 offset:8840
	ds_write_b16 v68, v25 offset:9360
	ds_write_b16_d16_hi v68, v25 offset:9880
	ds_write_b16 v68, v26 offset:10400
	ds_write_b16_d16_hi v68, v26 offset:10920
	ds_write_b16 v68, v27 offset:11440
	ds_write_b16_d16_hi v68, v27 offset:11960
	v_lshl_add_u32 v4, v72, 4, v77
	s_waitcnt vmcnt(9)
	ds_write_b128 v4, v[28:31]
	s_waitcnt vmcnt(8)
	ds_write_b16 v68, v32 offset:12480
	ds_write_b16_d16_hi v68, v32 offset:13000
	ds_write_b16 v68, v33 offset:13520
	ds_write_b16_d16_hi v68, v33 offset:14040
	ds_write_b16 v68, v34 offset:14560
	ds_write_b16_d16_hi v68, v34 offset:15080
	ds_write_b16 v68, v35 offset:15600
	ds_write_b16_d16_hi v68, v35 offset:16120
	v_lshl_add_u32 v4, v73, 4, v77
	s_waitcnt vmcnt(7)
	ds_write_b128 v4, v[36:39]
	s_waitcnt vmcnt(6)
	ds_write_b16 v68, v40 offset:16640
	ds_write_b16_d16_hi v68, v40 offset:17160
	ds_write_b16 v68, v41 offset:17680
	ds_write_b16_d16_hi v68, v41 offset:18200
	ds_write_b16 v68, v42 offset:18720
	ds_write_b16_d16_hi v68, v42 offset:19240
	ds_write_b16 v68, v43 offset:19760
	ds_write_b16_d16_hi v68, v43 offset:20280
	v_lshl_add_u32 v4, v74, 4, v77
	s_waitcnt vmcnt(5)
	ds_write_b128 v4, v[44:47]
	s_waitcnt vmcnt(4)
	ds_write_b16 v68, v48 offset:20800
	ds_write_b16_d16_hi v68, v48 offset:21320
	ds_write_b16 v68, v49 offset:21840
	ds_write_b16_d16_hi v68, v49 offset:22360
	ds_write_b16 v68, v50 offset:22880
	ds_write_b16_d16_hi v68, v50 offset:23400
	ds_write_b16 v68, v51 offset:23920
	ds_write_b16_d16_hi v68, v51 offset:24440
	v_lshl_add_u32 v4, v75, 4, v77
	s_waitcnt vmcnt(2)
	ds_write_b128 v4, v[52:55]
	ds_write_b16 v68, v56 offset:24960
	ds_write_b16_d16_hi v68, v56 offset:25480
	ds_write_b16 v68, v57 offset:26000
	ds_write_b16_d16_hi v68, v57 offset:26520
	ds_write_b16 v68, v58 offset:27040
	ds_write_b16_d16_hi v68, v58 offset:27560
	ds_write_b16 v68, v59 offset:28080
	ds_write_b16_d16_hi v68, v59 offset:28600
	v_lshl_add_u32 v4, v76, 4, v77
	s_waitcnt vmcnt(1)
	ds_write_b128 v4, v[60:63]
	v_mad_u64_u32 v[4:5], s[44:45], v76, s77, v[2:3]
	s_and_b32 s44, s14, 0x1f00
	s_add_u32 s44, s44, s89
	s_addc_u32 s45, 0, s60
	s_add_u32 s40, s44, s40
	s_waitcnt vmcnt(0)
	ds_write_b16 v4, v64
	ds_write_b16_d16_hi v4, v64 offset:520
	ds_write_b16 v4, v65 offset:1040
	ds_write_b16_d16_hi v4, v65 offset:1560
	ds_write_b16 v4, v66 offset:2080
	ds_write_b16_d16_hi v4, v66 offset:2600
	ds_write_b16 v4, v67 offset:3120
	ds_write_b16_d16_hi v4, v67 offset:3640
	v_or_b32_e32 v2, s40, v213
	v_mov_b64_e32 v[4:5], s[54:55]
	s_addc_u32 s41, s45, s41
	v_mad_u64_u32 v[4:5], s[44:45], v2, s16, v[4:5]
	v_lshrrev_b32_e32 v2, 2, v211
	v_mad_i32_i24 v5, s41, v238, v5
	v_and_b32_e32 v215, 8, v2
	v_lshl_add_u64 v[4:5], v[4:5], 0, s[24:25]
	v_lshlrev_b32_e32 v6, 1, v215
	v_mov_b32_e32 v7, v3
	v_lshl_add_u64 v[4:5], v[4:5], 0, v[6:7]
	v_add_co_u32_e32 v6, vcc, s17, v4
	s_waitcnt lgkmcnt(0)
	s_nop 0
	v_addc_co_u32_e32 v7, vcc, 0, v5, vcc
	s_barrier
	global_load_dwordx4 v[116:119], v[6:7], off
	v_lshl_add_u64 v[8:9], v[4:5], 0, s[64:65]
	global_load_dwordx4 v[188:191], v[8:9], off offset:32
	global_load_dwordx4 v[184:187], v[8:9], off offset:64
	global_load_dwordx4 v[180:183], v[8:9], off offset:96
	global_load_dwordx4 v[176:179], v[8:9], off offset:128
	global_load_dwordx4 v[168:171], v[8:9], off offset:160
	global_load_dwordx4 v[164:167], v[8:9], off offset:192
	s_mul_i32 s44, s41, 0x1800
	s_mul_hi_u32 s45, s40, 0x1800
	s_add_i32 s45, s45, s44
	s_mul_i32 s44, s40, 0x1800
	v_lshrrev_b32_e32 v2, 1, v211
	s_add_u32 s44, s54, s44
	v_and_b32_e32 v2, 16, v2
	v_mul_u32_u24_e32 v4, 0x110, v213
	s_addc_u32 s45, s55, s45
	v_add3_u32 v198, 0, v2, v4
	s_add_u32 s44, s44, s24
	v_mul_u32_u24_e32 v2, 0xc00, v210
	s_addc_u32 s45, s45, 0
	v_lshlrev_b32_e32 v2, 1, v2
	global_load_dwordx4 v[172:175], v[8:9], off offset:224
	v_lshl_add_u64 v[8:9], s[44:45], 0, v[2:3]
	v_lshlrev_b32_e32 v2, 4, v211
	v_and_b32_e32 v2, 0xf0, v2
	v_lshl_add_u64 v[8:9], v[8:9], 0, v[2:3]
	v_add_co_u32_e32 v10, vcc, s17, v8
	ds_read_b128 v[4:7], v198
	s_nop 0
	v_addc_co_u32_e32 v11, vcc, 0, v9, vcc
	v_add_co_u32_e32 v12, vcc, s20, v8
	s_nop 1
	v_addc_co_u32_e32 v13, vcc, 0, v9, vcc
	global_load_dwordx4 v[160:163], v[10:11], off offset:1024
	global_load_dwordx4 v[156:159], v[12:13], off offset:1024
	v_add_co_u32_e32 v10, vcc, s30, v8
	s_nop 1
	v_addc_co_u32_e32 v11, vcc, 0, v9, vcc
	v_add_co_u32_e32 v12, vcc, s63, v8
	s_nop 1
	v_addc_co_u32_e32 v13, vcc, 0, v9, vcc
	global_load_dwordx4 v[152:155], v[10:11], off offset:1024
	global_load_dwordx4 v[148:151], v[12:13], off offset:1024
	v_add_co_u32_e32 v10, vcc, s34, v8
	s_nop 1
	v_addc_co_u32_e32 v11, vcc, 0, v9, vcc
	v_add_co_u32_e32 v12, vcc, s35, v8
	s_nop 1
	v_addc_co_u32_e32 v13, vcc, 0, v9, vcc
	global_load_dwordx4 v[144:147], v[10:11], off offset:1024
	global_load_dwordx4 v[140:143], v[12:13], off offset:1024
	v_add_co_u32_e32 v10, vcc, s96, v8
	s_nop 1
	v_addc_co_u32_e32 v11, vcc, 0, v9, vcc
	v_add_co_u32_e32 v8, vcc, s0, v8
	s_nop 1
	v_addc_co_u32_e32 v9, vcc, 0, v9, vcc
	global_load_dwordx4 v[136:139], v[10:11], off offset:1024
	global_load_dwordx4 v[132:135], v[8:9], off offset:1024
	ds_read_b128 v[20:23], v198 offset:32
	s_waitcnt vmcnt(15) lgkmcnt(1)
	v_mfma_f32_32x32x16_bf16 v[4:19], v[4:7], v[116:119], 0
	s_waitcnt vmcnt(14) lgkmcnt(0)
	v_mfma_f32_32x32x16_bf16 v[4:19], v[20:23], v[188:191], v[4:19]
	ds_read_b128 v[20:23], v198 offset:64
	s_waitcnt vmcnt(13) lgkmcnt(0)
	v_mfma_f32_32x32x16_bf16 v[4:19], v[20:23], v[184:187], v[4:19]
	ds_read_b128 v[20:23], v198 offset:96
	s_waitcnt vmcnt(12) lgkmcnt(0)
	v_mfma_f32_32x32x16_bf16 v[4:19], v[20:23], v[180:183], v[4:19]
	ds_read_b128 v[20:23], v198 offset:128
	s_waitcnt vmcnt(11) lgkmcnt(0)
	v_mfma_f32_32x32x16_bf16 v[4:19], v[20:23], v[176:179], v[4:19]
	ds_read_b128 v[20:23], v198 offset:160
	s_waitcnt vmcnt(10) lgkmcnt(0)
	v_mfma_f32_32x32x16_bf16 v[4:19], v[20:23], v[168:171], v[4:19]
	ds_read_b128 v[20:23], v198 offset:192
	s_waitcnt vmcnt(9) lgkmcnt(0)
	v_mfma_f32_32x32x16_bf16 v[4:19], v[20:23], v[164:167], v[4:19]
	ds_read_b128 v[20:23], v198 offset:224
	s_waitcnt vmcnt(8) lgkmcnt(0)
	v_mfma_f32_32x32x16_bf16 v[4:19], v[20:23], v[172:175], v[4:19]
	ds_read_b128 v[20:23], v198 offset:8704
	ds_read_b128 v[36:39], v198 offset:8736
	s_waitcnt lgkmcnt(1)
	v_mfma_f32_32x32x16_bf16 v[20:35], v[20:23], v[116:119], 0
	s_waitcnt lgkmcnt(0)
	v_mfma_f32_32x32x16_bf16 v[20:35], v[36:39], v[188:191], v[20:35]
	ds_read_b128 v[36:39], v198 offset:8768
	s_waitcnt lgkmcnt(0)
	v_mfma_f32_32x32x16_bf16 v[20:35], v[36:39], v[184:187], v[20:35]
	ds_read_b128 v[36:39], v198 offset:8800
	s_waitcnt lgkmcnt(0)
	v_mfma_f32_32x32x16_bf16 v[20:35], v[36:39], v[180:183], v[20:35]
	ds_read_b128 v[36:39], v198 offset:8832
	s_waitcnt lgkmcnt(0)
	v_mfma_f32_32x32x16_bf16 v[20:35], v[36:39], v[176:179], v[20:35]
	ds_read_b128 v[36:39], v198 offset:8864
	s_waitcnt lgkmcnt(0)
	v_mfma_f32_32x32x16_bf16 v[20:35], v[36:39], v[168:171], v[20:35]
	ds_read_b128 v[36:39], v198 offset:8896
	s_waitcnt lgkmcnt(0)
	v_mfma_f32_32x32x16_bf16 v[20:35], v[36:39], v[164:167], v[20:35]
	ds_read_b128 v[36:39], v198 offset:8928
	s_waitcnt lgkmcnt(0)
	v_mfma_f32_32x32x16_bf16 v[20:35], v[36:39], v[172:175], v[20:35]
	ds_read_b128 v[36:39], v198 offset:17408
	ds_read_b128 v[52:55], v198 offset:17440
	v_or_b32_e32 v214, 64, v213
	s_waitcnt lgkmcnt(1)
	v_mfma_f32_32x32x16_bf16 v[36:51], v[36:39], v[116:119], 0
	s_waitcnt lgkmcnt(0)
	v_mfma_f32_32x32x16_bf16 v[36:51], v[52:55], v[188:191], v[36:51]
	ds_read_b128 v[52:55], v198 offset:17472
	s_waitcnt lgkmcnt(0)
	v_mfma_f32_32x32x16_bf16 v[36:51], v[52:55], v[184:187], v[36:51]
	ds_read_b128 v[52:55], v198 offset:17504
	s_waitcnt lgkmcnt(0)
	v_mfma_f32_32x32x16_bf16 v[36:51], v[52:55], v[180:183], v[36:51]
	ds_read_b128 v[52:55], v198 offset:17536
	s_waitcnt lgkmcnt(0)
	v_mfma_f32_32x32x16_bf16 v[36:51], v[52:55], v[176:179], v[36:51]
	ds_read_b128 v[52:55], v198 offset:17568
	s_waitcnt lgkmcnt(0)
	v_mfma_f32_32x32x16_bf16 v[36:51], v[52:55], v[168:171], v[36:51]
	ds_read_b128 v[52:55], v198 offset:17600
	s_waitcnt lgkmcnt(0)
	v_mfma_f32_32x32x16_bf16 v[36:51], v[52:55], v[164:167], v[36:51]
	ds_read_b128 v[52:55], v198 offset:17632
	s_waitcnt lgkmcnt(0)
	v_mfma_f32_32x32x16_bf16 v[36:51], v[52:55], v[172:175], v[36:51]
	ds_read_b128 v[52:55], v198 offset:26112
	ds_read_b128 v[68:71], v198 offset:26144
	v_or_b32_e32 v212, 0x60, v213
	s_waitcnt lgkmcnt(1)
	v_mfma_f32_32x32x16_bf16 v[52:67], v[52:55], v[116:119], 0
	s_waitcnt lgkmcnt(0)
	v_mfma_f32_32x32x16_bf16 v[52:67], v[68:71], v[188:191], v[52:67]
	ds_read_b128 v[68:71], v198 offset:26176
	s_waitcnt lgkmcnt(0)
	v_mfma_f32_32x32x16_bf16 v[52:67], v[68:71], v[184:187], v[52:67]
	ds_read_b128 v[68:71], v198 offset:26208
	s_waitcnt lgkmcnt(0)
	v_mfma_f32_32x32x16_bf16 v[52:67], v[68:71], v[180:183], v[52:67]
	ds_read_b128 v[68:71], v198 offset:26240
	s_waitcnt lgkmcnt(0)
	v_mfma_f32_32x32x16_bf16 v[52:67], v[68:71], v[176:179], v[52:67]
	ds_read_b128 v[68:71], v198 offset:26272
	s_waitcnt lgkmcnt(0)
	v_mfma_f32_32x32x16_bf16 v[52:67], v[68:71], v[168:171], v[52:67]
	ds_read_b128 v[68:71], v198 offset:26304
	s_waitcnt lgkmcnt(0)
	v_mfma_f32_32x32x16_bf16 v[52:67], v[68:71], v[164:167], v[52:67]
	ds_read_b128 v[68:71], v198 offset:26336
	s_waitcnt lgkmcnt(0)
	v_mfma_f32_32x32x16_bf16 v[52:67], v[68:71], v[172:175], v[52:67]
	ds_read_b128 v[68:71], v198 offset:34816
	ds_read_b128 v[84:87], v198 offset:34848
	s_waitcnt lgkmcnt(1)
	v_mfma_f32_32x32x16_bf16 v[68:83], v[68:71], v[116:119], 0
	s_waitcnt lgkmcnt(0)
	v_mfma_f32_32x32x16_bf16 v[68:83], v[84:87], v[188:191], v[68:83]
	ds_read_b128 v[84:87], v198 offset:34880
	s_waitcnt lgkmcnt(0)
	v_mfma_f32_32x32x16_bf16 v[68:83], v[84:87], v[184:187], v[68:83]
	ds_read_b128 v[84:87], v198 offset:34912
	s_waitcnt lgkmcnt(0)
	v_mfma_f32_32x32x16_bf16 v[68:83], v[84:87], v[180:183], v[68:83]
	ds_read_b128 v[84:87], v198 offset:34944
	s_waitcnt lgkmcnt(0)
	v_mfma_f32_32x32x16_bf16 v[68:83], v[84:87], v[176:179], v[68:83]
	ds_read_b128 v[84:87], v198 offset:34976
	s_waitcnt lgkmcnt(0)
	v_mfma_f32_32x32x16_bf16 v[68:83], v[84:87], v[168:171], v[68:83]
	ds_read_b128 v[84:87], v198 offset:35008
	s_waitcnt lgkmcnt(0)
	v_mfma_f32_32x32x16_bf16 v[68:83], v[84:87], v[164:167], v[68:83]
	ds_read_b128 v[84:87], v198 offset:35040
	s_waitcnt lgkmcnt(0)
	v_mfma_f32_32x32x16_bf16 v[68:83], v[84:87], v[172:175], v[68:83]
	ds_read_b128 v[84:87], v198 offset:43520
	ds_read_b128 v[100:103], v198 offset:43552
	s_waitcnt lgkmcnt(1)
	v_mfma_f32_32x32x16_bf16 v[84:99], v[84:87], v[116:119], 0
	s_waitcnt lgkmcnt(0)
	v_mfma_f32_32x32x16_bf16 v[84:99], v[100:103], v[188:191], v[84:99]
	ds_read_b128 v[100:103], v198 offset:43584
	s_waitcnt lgkmcnt(0)
	v_mfma_f32_32x32x16_bf16 v[84:99], v[100:103], v[184:187], v[84:99]
	ds_read_b128 v[100:103], v198 offset:43616
	s_waitcnt lgkmcnt(0)
	v_mfma_f32_32x32x16_bf16 v[84:99], v[100:103], v[180:183], v[84:99]
	ds_read_b128 v[100:103], v198 offset:43648
	s_waitcnt lgkmcnt(0)
	v_mfma_f32_32x32x16_bf16 v[84:99], v[100:103], v[176:179], v[84:99]
	ds_read_b128 v[100:103], v198 offset:43680
	s_waitcnt lgkmcnt(0)
	v_mfma_f32_32x32x16_bf16 v[84:99], v[100:103], v[168:171], v[84:99]
	ds_read_b128 v[100:103], v198 offset:43712
	s_waitcnt lgkmcnt(0)
	v_mfma_f32_32x32x16_bf16 v[84:99], v[100:103], v[164:167], v[84:99]
	ds_read_b128 v[100:103], v198 offset:43744
	s_waitcnt lgkmcnt(0)
	v_mfma_f32_32x32x16_bf16 v[84:99], v[100:103], v[172:175], v[84:99]
	ds_read_b128 v[100:103], v198 offset:52224
	ds_read_b128 v[120:123], v198 offset:52256
	s_waitcnt lgkmcnt(1)
	v_mfma_f32_32x32x16_bf16 v[100:115], v[100:103], v[116:119], 0
	s_waitcnt lgkmcnt(0)
	v_mfma_f32_32x32x16_bf16 v[100:115], v[120:123], v[188:191], v[100:115]
	ds_read_b128 v[120:123], v198 offset:52288
	s_waitcnt lgkmcnt(0)
	v_mfma_f32_32x32x16_bf16 v[100:115], v[120:123], v[184:187], v[100:115]
	ds_read_b128 v[120:123], v198 offset:52320
	s_waitcnt lgkmcnt(0)
	v_mfma_f32_32x32x16_bf16 v[100:115], v[120:123], v[180:183], v[100:115]
	ds_read_b128 v[120:123], v198 offset:52352
	s_waitcnt lgkmcnt(0)
	v_mfma_f32_32x32x16_bf16 v[100:115], v[120:123], v[176:179], v[100:115]
	ds_read_b128 v[120:123], v198 offset:52384
	s_waitcnt lgkmcnt(0)
	v_mfma_f32_32x32x16_bf16 v[100:115], v[120:123], v[168:171], v[100:115]
	ds_read_b128 v[120:123], v198 offset:52416
	s_waitcnt lgkmcnt(0)
	v_mfma_f32_32x32x16_bf16 v[100:115], v[120:123], v[164:167], v[100:115]
	ds_read_b128 v[120:123], v198 offset:52448
	s_waitcnt lgkmcnt(0)
	v_mfma_f32_32x32x16_bf16 v[100:115], v[120:123], v[172:175], v[100:115]
	ds_read_b128 v[120:123], v198 offset:60928
	ds_read_b128 v[200:203], v198 offset:60960
	s_waitcnt lgkmcnt(1)
	v_mfma_f32_32x32x16_bf16 v[116:131], v[120:123], v[116:119], 0
	s_waitcnt lgkmcnt(0)
	v_mfma_f32_32x32x16_bf16 v[116:131], v[200:203], v[188:191], v[116:131]
	ds_read_b128 v[188:191], v198 offset:60992
	s_waitcnt lgkmcnt(0)
	v_mfma_f32_32x32x16_bf16 v[116:131], v[188:191], v[184:187], v[116:131]
	ds_read_b128 v[184:187], v198 offset:61024
	s_waitcnt lgkmcnt(0)
	v_mfma_f32_32x32x16_bf16 v[116:131], v[184:187], v[180:183], v[116:131]
	ds_read_b128 v[180:183], v198 offset:61056
	s_waitcnt lgkmcnt(0)
	v_mfma_f32_32x32x16_bf16 v[116:131], v[180:183], v[176:179], v[116:131]
	ds_read_b128 v[176:179], v198 offset:61088
	s_waitcnt lgkmcnt(0)
	v_mfma_f32_32x32x16_bf16 v[116:131], v[176:179], v[168:171], v[116:131]
	ds_read_b128 v[168:171], v198 offset:61120
	s_waitcnt lgkmcnt(0)
	v_mfma_f32_32x32x16_bf16 v[116:131], v[168:171], v[164:167], v[116:131]
	ds_read_b128 v[164:167], v198 offset:61152
	s_waitcnt lgkmcnt(0)
	v_mfma_f32_32x32x16_bf16 v[116:131], v[164:167], v[172:175], v[116:131]
	v_max3_f32 v164, v4, s76, v5
	v_max3_f32 v164, v164, v6, v7
	v_max3_f32 v164, v164, v8, v9
	v_max3_f32 v164, v164, v10, v11
	v_max3_f32 v164, v164, v12, v13
	v_max3_f32 v164, v164, v14, v15
	v_max3_f32 v164, v164, v16, v17
	v_max3_f32 v164, v164, v18, v19
	v_max3_f32 v164, v164, v20, v21
	v_max3_f32 v164, v164, v22, v23
	v_max3_f32 v164, v164, v24, v25
	v_max3_f32 v164, v164, v26, v27
	v_max3_f32 v164, v164, v28, v29
	v_max3_f32 v164, v164, v30, v31
	v_max3_f32 v164, v164, v32, v33
	v_max3_f32 v164, v164, v34, v35
	v_max3_f32 v164, v164, v36, v37
	v_max3_f32 v164, v164, v38, v39
	v_max3_f32 v164, v164, v40, v41
	v_max3_f32 v164, v164, v42, v43
	v_max3_f32 v164, v164, v44, v45
	v_max3_f32 v164, v164, v46, v47
	v_max3_f32 v164, v164, v48, v49
	v_max3_f32 v164, v164, v50, v51
	v_max3_f32 v164, v164, v52, v53
	v_max3_f32 v164, v164, v54, v55
	v_max3_f32 v164, v164, v56, v57
	v_max3_f32 v164, v164, v58, v59
	v_max3_f32 v164, v164, v60, v61
	v_max3_f32 v164, v164, v62, v63
	v_max3_f32 v164, v164, v64, v65
	v_max3_f32 v164, v164, v66, v67
	v_max3_f32 v164, v164, v68, v69
	v_max3_f32 v164, v164, v70, v71
	v_max3_f32 v164, v164, v72, v73
	v_max3_f32 v164, v164, v74, v75
	v_max3_f32 v164, v164, v76, v77
	v_max3_f32 v164, v164, v78, v79
	v_max3_f32 v164, v164, v80, v81
	v_max3_f32 v164, v164, v82, v83
	v_max3_f32 v164, v164, v84, v85
	v_max3_f32 v164, v164, v86, v87
	v_max3_f32 v164, v164, v88, v89
	v_max3_f32 v164, v164, v90, v91
	v_max3_f32 v164, v164, v92, v93
	v_max3_f32 v164, v164, v94, v95
	v_max3_f32 v164, v164, v96, v97
	v_max3_f32 v164, v164, v98, v99
	v_max3_f32 v164, v164, v100, v101
	v_max3_f32 v164, v164, v102, v103
	v_max3_f32 v164, v164, v104, v105
	v_max3_f32 v164, v164, v106, v107
	v_max3_f32 v164, v164, v108, v109
	v_max3_f32 v164, v164, v110, v111
	v_max3_f32 v164, v164, v112, v113
	v_max3_f32 v164, v164, v114, v115
	v_max3_f32 v164, v164, v116, v117
	v_max3_f32 v164, v164, v118, v119
	v_max3_f32 v164, v164, v120, v121
	v_max3_f32 v164, v164, v122, v123
	v_max3_f32 v164, v164, v124, v125
	v_max3_f32 v164, v164, v126, v127
	v_max3_f32 v164, v164, v128, v129
	v_max3_f32 v164, v164, v130, v131
	ds_bpermute_b32 v165, v197, v164
	s_waitcnt lgkmcnt(0)
	s_barrier
	v_max_f32_e32 v165, v165, v165
	v_max_f32_e32 v216, v164, v165
	v_sub_f32_e32 v10, v10, v216
	v_exp_f32_e32 v164, v10
	v_sub_f32_e32 v10, v11, v216
	v_exp_f32_e32 v165, v10
	v_sub_f32_e32 v10, v12, v216
	v_exp_f32_e32 v166, v10
	v_sub_f32_e32 v10, v13, v216
	v_exp_f32_e32 v167, v10
	v_sub_f32_e32 v10, v14, v216
	v_exp_f32_e32 v168, v10
	v_sub_f32_e32 v10, v15, v216
	v_exp_f32_e32 v169, v10
	v_sub_f32_e32 v10, v16, v216
	v_exp_f32_e32 v170, v10
	v_sub_f32_e32 v10, v17, v216
	v_sub_f32_e32 v16, v26, v216
	v_exp_f32_e32 v171, v10
	v_sub_f32_e32 v10, v18, v216
	v_exp_f32_e32 v18, v16
	v_sub_f32_e32 v16, v27, v216
	v_exp_f32_e32 v172, v10
	v_sub_f32_e32 v10, v19, v216
	v_exp_f32_e32 v19, v16
	v_sub_f32_e32 v16, v28, v216
	v_exp_f32_e32 v28, v16
	v_sub_f32_e32 v16, v29, v216
	v_exp_f32_e32 v29, v16
	v_sub_f32_e32 v16, v30, v216
	v_exp_f32_e32 v30, v16
	v_sub_f32_e32 v16, v31, v216
	v_exp_f32_e32 v31, v16
	v_sub_f32_e32 v16, v32, v216
	v_exp_f32_e32 v32, v16
	v_sub_f32_e32 v16, v33, v216
	v_exp_f32_e32 v33, v16
	v_sub_f32_e32 v16, v34, v216
	v_exp_f32_e32 v173, v10
	v_sub_f32_e32 v10, v20, v216
	v_exp_f32_e32 v34, v16
	v_sub_f32_e32 v16, v35, v216
	v_sub_f32_e32 v20, v38, v216
	v_exp_f32_e32 v35, v16
	v_sub_f32_e32 v16, v36, v216
	v_exp_f32_e32 v36, v20
	v_sub_f32_e32 v20, v39, v216
	v_sub_f32_e32 v17, v37, v216
	v_exp_f32_e32 v37, v20
	v_sub_f32_e32 v20, v40, v216
	v_exp_f32_e32 v38, v20
	v_sub_f32_e32 v20, v41, v216
	v_exp_f32_e32 v39, v20
	v_sub_f32_e32 v20, v42, v216
	v_exp_f32_e32 v40, v20
	v_sub_f32_e32 v20, v43, v216
	v_exp_f32_e32 v41, v20
	v_sub_f32_e32 v20, v44, v216
	v_exp_f32_e32 v42, v20
	v_sub_f32_e32 v20, v45, v216
	v_exp_f32_e32 v43, v20
	v_sub_f32_e32 v20, v46, v216
	v_exp_f32_e32 v174, v20
	v_sub_f32_e32 v20, v47, v216
	v_exp_f32_e32 v175, v20
	v_sub_f32_e32 v20, v48, v216
	v_exp_f32_e32 v176, v20
	v_sub_f32_e32 v20, v49, v216
	v_exp_f32_e32 v177, v20
	v_sub_f32_e32 v20, v50, v216
	v_exp_f32_e32 v178, v20
	v_sub_f32_e32 v20, v51, v216
	v_exp_f32_e32 v179, v20
	v_sub_f32_e32 v20, v52, v216
	v_exp_f32_e32 v44, v20
	v_sub_f32_e32 v20, v53, v216
	v_exp_f32_e32 v45, v20
	v_sub_f32_e32 v20, v54, v216
	v_exp_f32_e32 v46, v20
	v_sub_f32_e32 v20, v55, v216
	v_exp_f32_e32 v47, v20
	v_sub_f32_e32 v20, v56, v216
	v_exp_f32_e32 v48, v20
	v_sub_f32_e32 v20, v57, v216
	v_exp_f32_e32 v49, v20
	v_sub_f32_e32 v20, v58, v216
	v_exp_f32_e32 v50, v20
	v_sub_f32_e32 v20, v59, v216
	v_exp_f32_e32 v51, v20
	v_sub_f32_e32 v20, v60, v216
	v_exp_f32_e32 v56, v20
	v_sub_f32_e32 v20, v61, v216
	v_exp_f32_e32 v57, v20
	v_sub_f32_e32 v20, v62, v216
	v_exp_f32_e32 v60, v20
	v_sub_f32_e32 v20, v63, v216
	v_exp_f32_e32 v61, v20
	v_sub_f32_e32 v20, v64, v216
	v_exp_f32_e32 v180, v20
	v_sub_f32_e32 v20, v65, v216
	v_exp_f32_e32 v181, v20
	v_sub_f32_e32 v20, v66, v216
	v_exp_f32_e32 v182, v20
	v_sub_f32_e32 v20, v67, v216
	v_exp_f32_e32 v183, v20
	v_sub_f32_e32 v20, v68, v216
	v_exp_f32_e32 v52, v20
	v_sub_f32_e32 v20, v69, v216
	v_exp_f32_e32 v53, v20
	v_sub_f32_e32 v20, v70, v216
	v_exp_f32_e32 v54, v20
	v_sub_f32_e32 v20, v71, v216
	v_exp_f32_e32 v55, v20
	v_sub_f32_e32 v20, v72, v216
	v_exp_f32_e32 v58, v20
	v_sub_f32_e32 v20, v73, v216
	v_exp_f32_e32 v59, v20
	v_sub_f32_e32 v20, v74, v216
	v_exp_f32_e32 v64, v20
	v_sub_f32_e32 v20, v75, v216
	v_exp_f32_e32 v65, v20
	v_sub_f32_e32 v20, v76, v216
	v_exp_f32_e32 v68, v20
	v_sub_f32_e32 v20, v77, v216
	v_exp_f32_e32 v69, v20
	v_sub_f32_e32 v20, v78, v216
	v_exp_f32_e32 v72, v20
	v_sub_f32_e32 v20, v79, v216
	v_exp_f32_e32 v73, v20
	v_sub_f32_e32 v20, v80, v216
	v_exp_f32_e32 v186, v20
	v_sub_f32_e32 v20, v81, v216
	v_exp_f32_e32 v187, v20
	v_sub_f32_e32 v20, v82, v216
	v_exp_f32_e32 v190, v20
	v_sub_f32_e32 v20, v83, v216
	v_exp_f32_e32 v191, v20
	v_sub_f32_e32 v20, v84, v216
	v_exp_f32_e32 v62, v20
	v_sub_f32_e32 v20, v85, v216
	v_exp_f32_e32 v63, v20
	v_sub_f32_e32 v20, v86, v216
	v_exp_f32_e32 v66, v20
	v_sub_f32_e32 v20, v87, v216
	v_exp_f32_e32 v67, v20
	v_sub_f32_e32 v20, v88, v216
	v_exp_f32_e32 v70, v20
	v_sub_f32_e32 v20, v89, v216
	v_exp_f32_e32 v71, v20
	v_sub_f32_e32 v20, v90, v216
	v_exp_f32_e32 v184, v20
	v_sub_f32_e32 v20, v91, v216
	v_exp_f32_e32 v185, v20
	v_sub_f32_e32 v20, v92, v216
	v_exp_f32_e32 v188, v20
	v_sub_f32_e32 v20, v93, v216
	v_exp_f32_e32 v189, v20
	v_sub_f32_e32 v20, v94, v216
	v_exp_f32_e32 v198, v20
	v_sub_f32_e32 v20, v95, v216
	v_exp_f32_e32 v199, v20
	v_sub_f32_e32 v20, v96, v216
	v_exp_f32_e32 v200, v20
	v_sub_f32_e32 v20, v97, v216
	v_exp_f32_e32 v201, v20
	v_sub_f32_e32 v20, v98, v216
	v_exp_f32_e32 v202, v20
	v_sub_f32_e32 v20, v99, v216
	v_exp_f32_e32 v203, v20
	v_sub_f32_e32 v20, v100, v216
	v_exp_f32_e32 v74, v20
	v_sub_f32_e32 v20, v101, v216
	v_exp_f32_e32 v75, v20
	v_sub_f32_e32 v20, v102, v216
	v_exp_f32_e32 v92, v20
	v_sub_f32_e32 v20, v103, v216
	v_exp_f32_e32 v93, v20
	v_sub_f32_e32 v20, v104, v216
	v_exp_f32_e32 v94, v20
	v_sub_f32_e32 v20, v105, v216
	v_exp_f32_e32 v95, v20
	v_sub_f32_e32 v20, v106, v216
	v_exp_f32_e32 v96, v20
	v_sub_f32_e32 v20, v107, v216
	v_exp_f32_e32 v97, v20
	v_sub_f32_e32 v20, v108, v216
	v_exp_f32_e32 v98, v20
	v_sub_f32_e32 v20, v109, v216
	v_exp_f32_e32 v99, v20
	v_sub_f32_e32 v20, v110, v216
	v_exp_f32_e32 v100, v20
	v_sub_f32_e32 v20, v111, v216
	v_exp_f32_e32 v101, v20
	v_sub_f32_e32 v20, v112, v216
	v_exp_f32_e32 v102, v20
	v_sub_f32_e32 v20, v113, v216
	v_exp_f32_e32 v103, v20
	v_sub_f32_e32 v20, v114, v216
	v_exp_f32_e32 v104, v20
	v_sub_f32_e32 v20, v115, v216
	v_exp_f32_e32 v105, v20
	v_sub_f32_e32 v20, v116, v216
	v_exp_f32_e32 v76, v20
	v_sub_f32_e32 v20, v117, v216
	v_exp_f32_e32 v77, v20
	v_sub_f32_e32 v20, v118, v216
	v_exp_f32_e32 v80, v20
	v_sub_f32_e32 v20, v119, v216
	v_exp_f32_e32 v81, v20
	v_sub_f32_e32 v20, v120, v216
	v_exp_f32_e32 v84, v20
	v_sub_f32_e32 v20, v121, v216
	v_exp_f32_e32 v85, v20
	v_sub_f32_e32 v20, v122, v216
	v_exp_f32_e32 v88, v20
	v_sub_f32_e32 v20, v123, v216
	v_exp_f32_e32 v89, v20
	v_sub_f32_e32 v20, v124, v216
	v_exp_f32_e32 v78, v20
	v_sub_f32_e32 v20, v125, v216
	v_exp_f32_e32 v79, v20
	v_sub_f32_e32 v20, v126, v216
	v_sub_f32_e32 v4, v4, v216
	v_exp_f32_e32 v82, v20
	v_sub_f32_e32 v20, v127, v216
	v_sub_f32_e32 v5, v5, v216
	v_exp_f32_e32 v4, v4
	v_exp_f32_e32 v83, v20
	v_sub_f32_e32 v20, v128, v216
	v_sub_f32_e32 v6, v6, v216
	v_exp_f32_e32 v5, v5
	v_exp_f32_e32 v86, v20
	v_sub_f32_e32 v20, v129, v216
	v_exp_f32_e32 v6, v6
	v_sub_f32_e32 v7, v7, v216
	v_exp_f32_e32 v87, v20
	v_sub_f32_e32 v20, v130, v216
	v_exp_f32_e32 v7, v7
	v_sub_f32_e32 v8, v8, v216
	v_exp_f32_e32 v90, v20
	v_sub_f32_e32 v20, v131, v216
	v_exp_f32_e32 v8, v8
	v_sub_f32_e32 v9, v9, v216
	v_exp_f32_e32 v91, v20
	v_add_f32_e32 v20, 0, v4
	v_exp_f32_e32 v9, v9
	v_add_f32_e32 v20, v5, v20
	v_add_f32_e32 v20, v6, v20
	v_add_f32_e32 v20, v7, v20
	v_add_f32_e32 v20, v8, v20
	v_add_f32_e32 v20, v9, v20
	v_add_f32_e32 v20, v164, v20
	v_add_f32_e32 v20, v165, v20
	v_add_f32_e32 v20, v166, v20
	v_add_f32_e32 v20, v167, v20
	v_add_f32_e32 v20, v168, v20
	v_add_f32_e32 v20, v169, v20
	v_exp_f32_e32 v10, v10
	v_sub_f32_e32 v11, v21, v216
	v_add_f32_e32 v20, v170, v20
	v_exp_f32_e32 v11, v11
	v_sub_f32_e32 v12, v22, v216
	v_add_f32_e32 v20, v171, v20
	v_exp_f32_e32 v12, v12
	v_sub_f32_e32 v13, v23, v216
	v_add_f32_e32 v20, v172, v20
	v_exp_f32_e32 v13, v13
	v_sub_f32_e32 v14, v24, v216
	v_add_f32_e32 v20, v173, v20
	v_exp_f32_e32 v14, v14
	v_sub_f32_e32 v15, v25, v216
	v_add_f32_e32 v20, v10, v20
	v_exp_f32_e32 v15, v15
	v_add_f32_e32 v20, v11, v20
	v_add_f32_e32 v20, v12, v20
	v_add_f32_e32 v20, v13, v20
	v_add_f32_e32 v20, v14, v20
	v_add_f32_e32 v20, v15, v20
	v_add_f32_e32 v20, v18, v20
	v_add_f32_e32 v20, v19, v20
	v_add_f32_e32 v20, v28, v20
	v_add_f32_e32 v20, v29, v20
	v_add_f32_e32 v20, v30, v20
	v_add_f32_e32 v20, v31, v20
	v_exp_f32_e32 v16, v16
	v_add_f32_e32 v20, v32, v20
	v_exp_f32_e32 v17, v17
	v_add_f32_e32 v20, v33, v20
	v_add_f32_e32 v20, v34, v20
	v_add_f32_e32 v20, v35, v20
	v_add_f32_e32 v20, v16, v20
	v_add_f32_e32 v20, v17, v20
	v_add_f32_e32 v20, v36, v20
	v_add_f32_e32 v20, v37, v20
	v_add_f32_e32 v20, v38, v20
	v_add_f32_e32 v20, v39, v20
	v_add_f32_e32 v20, v40, v20
	v_add_f32_e32 v20, v41, v20
	v_add_f32_e32 v20, v42, v20
	v_add_f32_e32 v20, v43, v20
	v_add_f32_e32 v20, v174, v20
	v_add_f32_e32 v20, v175, v20
	v_add_f32_e32 v20, v176, v20
	v_add_f32_e32 v20, v177, v20
	v_add_f32_e32 v20, v178, v20
	v_add_f32_e32 v20, v179, v20
	v_add_f32_e32 v20, v44, v20
	v_add_f32_e32 v20, v45, v20
	v_add_f32_e32 v20, v46, v20
	v_add_f32_e32 v20, v47, v20
	v_add_f32_e32 v20, v48, v20
	v_add_f32_e32 v20, v49, v20
	v_add_f32_e32 v20, v50, v20
	v_add_f32_e32 v20, v51, v20
	v_add_f32_e32 v20, v56, v20
	v_add_f32_e32 v20, v57, v20
	v_add_f32_e32 v20, v60, v20
	v_add_f32_e32 v20, v61, v20
	v_add_f32_e32 v20, v180, v20
	v_add_f32_e32 v20, v181, v20
	v_add_f32_e32 v20, v182, v20
	v_add_f32_e32 v20, v183, v20
	v_add_f32_e32 v20, v52, v20
	v_add_f32_e32 v20, v53, v20
	v_add_f32_e32 v20, v54, v20
	v_add_f32_e32 v20, v55, v20
	v_add_f32_e32 v20, v58, v20
	v_add_f32_e32 v20, v59, v20
	v_add_f32_e32 v20, v64, v20
	v_add_f32_e32 v20, v65, v20
	v_add_f32_e32 v20, v68, v20
	v_add_f32_e32 v20, v69, v20
	v_add_f32_e32 v20, v72, v20
	v_add_f32_e32 v20, v73, v20
	v_add_f32_e32 v20, v186, v20
	v_add_f32_e32 v20, v187, v20
	v_add_f32_e32 v20, v190, v20
	v_add_f32_e32 v20, v191, v20
	v_add_f32_e32 v20, v62, v20
	v_add_f32_e32 v20, v63, v20
	v_add_f32_e32 v20, v66, v20
	v_add_f32_e32 v20, v67, v20
	v_add_f32_e32 v20, v70, v20
	v_add_f32_e32 v20, v71, v20
	v_add_f32_e32 v20, v184, v20
	v_add_f32_e32 v20, v185, v20
	v_add_f32_e32 v20, v188, v20
	v_add_f32_e32 v20, v189, v20
	v_add_f32_e32 v20, v198, v20
	v_add_f32_e32 v20, v199, v20
	v_add_f32_e32 v20, v200, v20
	v_add_f32_e32 v20, v201, v20
	v_add_f32_e32 v20, v202, v20
	v_add_f32_e32 v20, v203, v20
	v_add_f32_e32 v20, v74, v20
	v_add_f32_e32 v20, v75, v20
	v_add_f32_e32 v20, v92, v20
	v_add_f32_e32 v20, v93, v20
	v_add_f32_e32 v20, v94, v20
	v_add_f32_e32 v20, v95, v20
	v_add_f32_e32 v20, v96, v20
	v_add_f32_e32 v20, v97, v20
	v_add_f32_e32 v20, v98, v20
	v_add_f32_e32 v20, v99, v20
	v_add_f32_e32 v20, v100, v20
	v_add_f32_e32 v20, v101, v20
	v_add_f32_e32 v20, v102, v20
	v_add_f32_e32 v20, v103, v20
	v_add_f32_e32 v20, v104, v20
	v_add_f32_e32 v20, v105, v20
	v_add_f32_e32 v20, v76, v20
	v_add_f32_e32 v20, v77, v20
	v_add_f32_e32 v20, v80, v20
	v_add_f32_e32 v20, v81, v20
	v_add_f32_e32 v20, v84, v20
	v_add_f32_e32 v20, v85, v20
	v_add_f32_e32 v20, v88, v20
	v_add_f32_e32 v20, v89, v20
	v_add_f32_e32 v20, v78, v20
	v_add_f32_e32 v20, v79, v20
	v_add_f32_e32 v20, v82, v20
	v_add_f32_e32 v20, v83, v20
	v_add_f32_e32 v20, v86, v20
	v_add_f32_e32 v20, v87, v20
	v_add_f32_e32 v20, v90, v20
	v_add_f32_e32 v20, v91, v20
	ds_bpermute_b32 v21, v197, v20
	s_waitcnt lgkmcnt(0)
	v_add_f32_e32 v20, v20, v21
	v_div_scale_f32 v21, s[44:45], v20, v20, 1.0
	v_rcp_f32_e32 v22, v21
	s_nop 0
	v_fma_f32 v23, -v21, v22, 1.0
	v_fmac_f32_e32 v22, v23, v22
	v_div_scale_f32 v23, vcc, 1.0, v20, 1.0
	v_mul_f32_e32 v24, v23, v22
	v_fma_f32 v25, -v21, v24, v23
	v_fmac_f32_e32 v24, v25, v22
	v_fma_f32 v21, -v21, v24, v23
	v_div_fmas_f32 v21, v21, v22, v24
	v_div_fixup_f32 v106, v21, v20, 1.0
	v_pk_mul_f32 v[6:7], v[6:7], v[106:107] op_sel_hi:[1,0]
	v_pk_mul_f32 v[4:5], v[4:5], v[106:107] op_sel_hi:[1,0]
	v_pk_mul_f32 v[8:9], v[8:9], v[106:107] op_sel_hi:[1,0]
	v_cvt_pk_bf16_f32 v21, v6, v7
	v_pk_mul_f32 v[6:7], v[12:13], v[106:107] op_sel_hi:[1,0]
	v_pk_mul_f32 v[24:25], v[164:165], v[106:107] op_sel_hi:[1,0]
	v_pk_mul_f32 v[108:109], v[168:169], v[106:107] op_sel_hi:[1,0]
	v_cvt_pk_bf16_f32 v20, v4, v5
	v_cvt_pk_bf16_f32 v22, v8, v9
	v_pk_mul_f32 v[4:5], v[10:11], v[106:107] op_sel_hi:[1,0]
	v_pk_mul_f32 v[8:9], v[14:15], v[106:107] op_sel_hi:[1,0]
	v_pk_mul_f32 v[10:11], v[18:19], v[106:107] op_sel_hi:[1,0]
	v_pk_mul_f32 v[18:19], v[32:33], v[106:107] op_sel_hi:[1,0]
	v_cvt_pk_bf16_f32 v33, v6, v7
	v_pk_mul_f32 v[6:7], v[36:37], v[106:107] op_sel_hi:[1,0]
	v_cvt_pk_bf16_f32 v23, v24, v25
	v_cvt_pk_bf16_f32 v25, v108, v109
	v_pk_mul_f32 v[108:109], v[34:35], v[106:107] op_sel_hi:[1,0]
	v_cvt_pk_bf16_f32 v32, v4, v5
	v_cvt_pk_bf16_f32 v34, v8, v9
	v_pk_mul_f32 v[4:5], v[16:17], v[106:107] op_sel_hi:[1,0]
	v_pk_mul_f32 v[8:9], v[38:39], v[106:107] op_sel_hi:[1,0]
	v_cvt_pk_bf16_f32 v37, v6, v7
	v_pk_mul_f32 v[6:7], v[46:47], v[106:107] op_sel_hi:[1,0]
	v_cvt_pk_bf16_f32 v35, v10, v11
	v_pk_mul_f32 v[10:11], v[40:41], v[106:107] op_sel_hi:[1,0]
	v_cvt_pk_bf16_f32 v36, v4, v5
	v_cvt_pk_bf16_f32 v38, v8, v9
	v_pk_mul_f32 v[4:5], v[44:45], v[106:107] op_sel_hi:[1,0]
	v_pk_mul_f32 v[8:9], v[48:49], v[106:107] op_sel_hi:[1,0]
	v_cvt_pk_bf16_f32 v49, v6, v7
	v_pk_mul_f32 v[6:7], v[54:55], v[106:107] op_sel_hi:[1,0]
	v_pk_mul_f32 v[12:13], v[28:29], v[106:107] op_sel_hi:[1,0]
	v_cvt_pk_bf16_f32 v39, v10, v11
	v_pk_mul_f32 v[10:11], v[50:51], v[106:107] op_sel_hi:[1,0]
	v_cvt_pk_bf16_f32 v48, v4, v5
	v_pk_mul_f32 v[4:5], v[52:53], v[106:107] op_sel_hi:[1,0]
	v_cvt_pk_bf16_f32 v53, v6, v7
	v_pk_mul_f32 v[6:7], v[66:67], v[106:107] op_sel_hi:[1,0]
	v_cvt_pk_bf16_f32 v28, v12, v13
	v_pk_mul_f32 v[12:13], v[42:43], v[106:107] op_sel_hi:[1,0]
	v_cvt_pk_bf16_f32 v51, v10, v11
	v_pk_mul_f32 v[10:11], v[64:65], v[106:107] op_sel_hi:[1,0]
	v_cvt_pk_bf16_f32 v52, v4, v5
	v_pk_mul_f32 v[4:5], v[62:63], v[106:107] op_sel_hi:[1,0]
	v_cvt_pk_bf16_f32 v65, v6, v7
	v_pk_mul_f32 v[6:7], v[92:93], v[106:107] op_sel_hi:[1,0]
	v_add_u32_e32 v92, s11, v215
	v_pk_mul_f32 v[14:15], v[30:31], v[106:107] op_sel_hi:[1,0]
	v_cvt_pk_bf16_f32 v40, v12, v13
	v_pk_mul_f32 v[12:13], v[56:57], v[106:107] op_sel_hi:[1,0]
	v_cvt_pk_bf16_f32 v64, v4, v5
	v_pk_mul_f32 v[4:5], v[74:75], v[106:107] op_sel_hi:[1,0]
	v_mad_u32_u24 v93, v213, s8, v92
	v_cvt_pk_bf16_f32 v29, v14, v15
	v_cvt_pk_bf16_f32 v30, v18, v19
	v_pk_mul_f32 v[14:15], v[174:175], v[106:107] op_sel_hi:[1,0]
	v_pk_mul_f32 v[16:17], v[176:177], v[106:107] op_sel_hi:[1,0]
	v_pk_mul_f32 v[18:19], v[178:179], v[106:107] op_sel_hi:[1,0]
	v_cvt_pk_bf16_f32 v44, v12, v13
	v_pk_mul_f32 v[12:13], v[68:69], v[106:107] op_sel_hi:[1,0]
	v_cvt_pk_bf16_f32 v68, v4, v5
	v_cvt_pk_bf16_f32 v69, v6, v7
	ds_read2_b64 v[4:7], v93 offset1:2
	v_cvt_pk_bf16_f32 v41, v14, v15
	v_cvt_pk_bf16_f32 v42, v16, v17
	v_cvt_pk_bf16_f32 v43, v18, v19
	v_pk_mul_f32 v[14:15], v[60:61], v[106:107] op_sel_hi:[1,0]
	v_pk_mul_f32 v[16:17], v[180:181], v[106:107] op_sel_hi:[1,0]
	v_pk_mul_f32 v[18:19], v[182:183], v[106:107] op_sel_hi:[1,0]
	v_cvt_pk_bf16_f32 v50, v8, v9
	v_cvt_pk_bf16_f32 v45, v14, v15
	v_cvt_pk_bf16_f32 v46, v16, v17
	v_cvt_pk_bf16_f32 v47, v18, v19
	v_pk_mul_f32 v[8:9], v[58:59], v[106:107] op_sel_hi:[1,0]
	v_pk_mul_f32 v[14:15], v[72:73], v[106:107] op_sel_hi:[1,0]
	v_pk_mul_f32 v[16:17], v[186:187], v[106:107] op_sel_hi:[1,0]
	v_pk_mul_f32 v[18:19], v[190:191], v[106:107] op_sel_hi:[1,0]
	v_cvt_pk_bf16_f32 v54, v8, v9
	v_cvt_pk_bf16_f32 v55, v10, v11
	v_cvt_pk_bf16_f32 v56, v12, v13
	v_cvt_pk_bf16_f32 v57, v14, v15
	v_cvt_pk_bf16_f32 v58, v16, v17
	v_cvt_pk_bf16_f32 v59, v18, v19
	v_pk_mul_f32 v[8:9], v[70:71], v[106:107] op_sel_hi:[1,0]
	v_pk_mul_f32 v[10:11], v[184:185], v[106:107] op_sel_hi:[1,0]
	v_pk_mul_f32 v[12:13], v[188:189], v[106:107] op_sel_hi:[1,0]
	v_pk_mul_f32 v[14:15], v[198:199], v[106:107] op_sel_hi:[1,0]
	v_pk_mul_f32 v[16:17], v[200:201], v[106:107] op_sel_hi:[1,0]
	v_pk_mul_f32 v[18:19], v[202:203], v[106:107] op_sel_hi:[1,0]
	v_cvt_pk_bf16_f32 v66, v8, v9
	v_cvt_pk_bf16_f32 v67, v10, v11
	v_cvt_pk_bf16_f32 v60, v12, v13
	v_cvt_pk_bf16_f32 v61, v14, v15
	v_cvt_pk_bf16_f32 v62, v16, v17
	v_cvt_pk_bf16_f32 v63, v18, v19
	v_pk_mul_f32 v[8:9], v[94:95], v[106:107] op_sel_hi:[1,0]
	v_pk_mul_f32 v[10:11], v[96:97], v[106:107] op_sel_hi:[1,0]
	v_pk_mul_f32 v[12:13], v[98:99], v[106:107] op_sel_hi:[1,0]
	v_pk_mul_f32 v[14:15], v[100:101], v[106:107] op_sel_hi:[1,0]
	v_pk_mul_f32 v[16:17], v[102:103], v[106:107] op_sel_hi:[1,0]
	v_pk_mul_f32 v[18:19], v[104:105], v[106:107] op_sel_hi:[1,0]
	v_cvt_pk_bf16_f32 v70, v8, v9
	v_cvt_pk_bf16_f32 v71, v10, v11
	v_cvt_pk_bf16_f32 v72, v12, v13
	v_cvt_pk_bf16_f32 v73, v14, v15
	v_cvt_pk_bf16_f32 v74, v16, v17
	v_cvt_pk_bf16_f32 v75, v18, v19
	s_waitcnt lgkmcnt(0)
	v_mfma_f32_32x32x16_bf16 v[4:19], v[20:23], v[4:7], 0
	v_mul_f32_e64 v26, v166, v106
	v_mul_f32_e64 v27, v167, v106
	v_mul_f32_e64 v110, v170, v106
	v_mul_f32_e64 v111, v171, v106
	v_mul_f32_e64 v112, v172, v106
	v_mul_f32_e64 v113, v173, v106
	v_cvt_pk_bf16_f32 v24, v26, v27
	v_cvt_pk_bf16_f32 v26, v110, v111
	v_cvt_pk_bf16_f32 v27, v112, v113
	v_pk_mul_f32 v[94:95], v[80:81], v[106:107] op_sel_hi:[1,0]
	v_pk_mul_f32 v[96:97], v[78:79], v[106:107] op_sel_hi:[1,0]
	ds_read2_b64 v[78:81], v93 offset0:4 offset1:6
	s_waitcnt lgkmcnt(0)
	v_mfma_f32_32x32x16_bf16 v[4:19], v[24:27], v[78:81], v[4:19]
	v_mul_f32_e64 v84, v84, v106
	v_mul_f32_e64 v85, v85, v106
	v_mul_f32_e64 v98, v86, v106
	v_mul_f32_e64 v99, v87, v106
	v_cvt_pk_bf16_f32 v78, v84, v85
	ds_read2_b64 v[84:87], v93 offset0:8 offset1:10
	v_pk_mul_f32 v[88:89], v[88:89], v[106:107] op_sel_hi:[1,0]
	v_cvt_pk_bf16_f32 v31, v108, v109
	v_cvt_pk_bf16_f32 v79, v88, v89
	s_waitcnt lgkmcnt(0)
	v_mfma_f32_32x32x16_bf16 v[4:19], v[32:35], v[84:87], v[4:19]
	ds_read2_b64 v[86:89], v93 offset0:12 offset1:14
	v_lshrrev_b32_e32 v84, 3, v211
	v_and_b32_e32 v84, 4, v84
	v_lshlrev_b32_e32 v85, 1, v211
	v_mul_f32_e64 v76, v76, v106
	v_mul_f32_e64 v77, v77, v106
	v_pk_mul_f32 v[82:83], v[82:83], v[106:107] op_sel_hi:[1,0]
	v_pk_mul_f32 v[90:91], v[90:91], v[106:107] op_sel_hi:[1,0]
	v_mul_u32_u24_e32 v84, 0x110, v84
	v_and_b32_e32 v85, 62, v85
	v_cvt_pk_bf16_f32 v76, v76, v77
	v_cvt_pk_bf16_f32 v77, v94, v95
	v_cvt_pk_bf16_f32 v80, v96, v97
	v_cvt_pk_bf16_f32 v81, v82, v83
	v_cvt_pk_bf16_f32 v82, v98, v99
	v_cvt_pk_bf16_f32 v83, v90, v91
	v_add3_u32 v84, s61, v84, v85
	s_waitcnt lgkmcnt(0)
	v_mfma_f32_32x32x16_bf16 v[4:19], v[28:31], v[86:89], v[4:19]
	ds_read2_b64 v[86:89], v93 offset0:16 offset1:18
	s_waitcnt lgkmcnt(0)
	v_mfma_f32_32x32x16_bf16 v[4:19], v[36:39], v[86:89], v[4:19]
	ds_read2_b64 v[86:89], v93 offset0:20 offset1:22
	s_waitcnt lgkmcnt(0)
	v_mfma_f32_32x32x16_bf16 v[4:19], v[40:43], v[86:89], v[4:19]
	ds_read2_b64 v[86:89], v93 offset0:24 offset1:26
	s_waitcnt lgkmcnt(0)
	v_mfma_f32_32x32x16_bf16 v[4:19], v[48:51], v[86:89], v[4:19]
	ds_read2_b64 v[86:89], v93 offset0:28 offset1:30
	s_waitcnt lgkmcnt(0)
	v_mfma_f32_32x32x16_bf16 v[4:19], v[44:47], v[86:89], v[4:19]
	ds_read2_b64 v[86:89], v93 offset0:32 offset1:34
	s_waitcnt lgkmcnt(0)
	v_mfma_f32_32x32x16_bf16 v[4:19], v[52:55], v[86:89], v[4:19]
	ds_read2_b64 v[86:89], v93 offset0:36 offset1:38
	s_waitcnt lgkmcnt(0)
	v_mfma_f32_32x32x16_bf16 v[4:19], v[56:59], v[86:89], v[4:19]
	ds_read2_b64 v[86:89], v93 offset0:40 offset1:42
	s_waitcnt lgkmcnt(0)
	v_mfma_f32_32x32x16_bf16 v[4:19], v[64:67], v[86:89], v[4:19]
	ds_read2_b64 v[86:89], v93 offset0:44 offset1:46
	s_waitcnt lgkmcnt(0)
	v_mfma_f32_32x32x16_bf16 v[4:19], v[60:63], v[86:89], v[4:19]
	ds_read2_b64 v[86:89], v93 offset0:48 offset1:50
	s_waitcnt lgkmcnt(0)
	v_mfma_f32_32x32x16_bf16 v[4:19], v[68:71], v[86:89], v[4:19]
	ds_read2_b64 v[86:89], v93 offset0:52 offset1:54
	s_waitcnt lgkmcnt(0)
	v_mfma_f32_32x32x16_bf16 v[4:19], v[72:75], v[86:89], v[4:19]
	ds_read2_b64 v[86:89], v93 offset0:56 offset1:58
	s_waitcnt lgkmcnt(0)
	v_mfma_f32_32x32x16_bf16 v[4:19], v[76:79], v[86:89], v[4:19]
	ds_read2_b64 v[86:89], v93 offset0:60 offset1:62
	s_waitcnt lgkmcnt(0)
	v_mfma_f32_32x32x16_bf16 v[4:19], v[80:83], v[86:89], v[4:19]
	s_nop 11
	v_cvt_pk_bf16_f32 v4, v4, v5
	ds_write_b16 v84, v4
	ds_write_b16_d16_hi v84, v4 offset:272
	v_cvt_pk_bf16_f32 v4, v6, v7
	ds_write_b16 v84, v4 offset:544
	ds_write_b16_d16_hi v84, v4 offset:816
	v_cvt_pk_bf16_f32 v4, v8, v9
	ds_write_b16 v84, v4 offset:2176
	ds_write_b16_d16_hi v84, v4 offset:2448
	v_cvt_pk_bf16_f32 v4, v10, v11
	ds_write_b16 v84, v4 offset:2720
	ds_write_b16_d16_hi v84, v4 offset:2992
	v_cvt_pk_bf16_f32 v4, v12, v13
	ds_write_b16 v84, v4 offset:4352
	ds_write_b16_d16_hi v84, v4 offset:4624
	v_cvt_pk_bf16_f32 v4, v14, v15
	ds_write_b16 v84, v4 offset:4896
	ds_write_b16_d16_hi v84, v4 offset:5168
	v_cvt_pk_bf16_f32 v4, v16, v17
	ds_write_b16 v84, v4 offset:6528
	ds_write_b16_d16_hi v84, v4 offset:6800
	v_cvt_pk_bf16_f32 v4, v18, v19
	ds_write_b16 v84, v4 offset:7072
	ds_write_b16_d16_hi v84, v4 offset:7344
	v_add_u32_e32 v85, 0x4000, v93
	ds_read2_b64 v[4:7], v85 offset0:32 offset1:34
	s_waitcnt lgkmcnt(0)
	v_mfma_f32_32x32x16_bf16 v[4:19], v[20:23], v[4:7], 0
	ds_read2_b64 v[86:89], v85 offset0:36 offset1:38
	s_waitcnt lgkmcnt(0)
	v_mfma_f32_32x32x16_bf16 v[4:19], v[24:27], v[86:89], v[4:19]
	ds_read2_b64 v[86:89], v85 offset0:40 offset1:42
	s_waitcnt lgkmcnt(0)
	v_mfma_f32_32x32x16_bf16 v[4:19], v[32:35], v[86:89], v[4:19]
	ds_read2_b64 v[86:89], v85 offset0:44 offset1:46
	s_waitcnt lgkmcnt(0)
	v_mfma_f32_32x32x16_bf16 v[4:19], v[28:31], v[86:89], v[4:19]
	ds_read2_b64 v[86:89], v85 offset0:48 offset1:50
	s_waitcnt lgkmcnt(0)
	v_mfma_f32_32x32x16_bf16 v[4:19], v[36:39], v[86:89], v[4:19]
	ds_read2_b64 v[86:89], v85 offset0:52 offset1:54
	s_waitcnt lgkmcnt(0)
	v_mfma_f32_32x32x16_bf16 v[4:19], v[40:43], v[86:89], v[4:19]
	ds_read2_b64 v[86:89], v85 offset0:56 offset1:58
	s_waitcnt lgkmcnt(0)
	v_mfma_f32_32x32x16_bf16 v[4:19], v[48:51], v[86:89], v[4:19]
	ds_read2_b64 v[86:89], v85 offset0:60 offset1:62
	s_waitcnt lgkmcnt(0)
	v_mfma_f32_32x32x16_bf16 v[4:19], v[44:47], v[86:89], v[4:19]
	ds_read2_b64 v[86:89], v85 offset0:64 offset1:66
	s_waitcnt lgkmcnt(0)
	v_mfma_f32_32x32x16_bf16 v[4:19], v[52:55], v[86:89], v[4:19]
	ds_read2_b64 v[86:89], v85 offset0:68 offset1:70
	s_waitcnt lgkmcnt(0)
	v_mfma_f32_32x32x16_bf16 v[4:19], v[56:59], v[86:89], v[4:19]
	ds_read2_b64 v[86:89], v85 offset0:72 offset1:74
	s_waitcnt lgkmcnt(0)
	v_mfma_f32_32x32x16_bf16 v[4:19], v[64:67], v[86:89], v[4:19]
	ds_read2_b64 v[86:89], v85 offset0:76 offset1:78
	s_waitcnt lgkmcnt(0)
	v_mfma_f32_32x32x16_bf16 v[4:19], v[60:63], v[86:89], v[4:19]
	ds_read2_b64 v[86:89], v85 offset0:80 offset1:82
	s_waitcnt lgkmcnt(0)
	v_mfma_f32_32x32x16_bf16 v[4:19], v[68:71], v[86:89], v[4:19]
	ds_read2_b64 v[86:89], v85 offset0:84 offset1:86
	s_waitcnt lgkmcnt(0)
	v_mfma_f32_32x32x16_bf16 v[4:19], v[72:75], v[86:89], v[4:19]
	ds_read2_b64 v[86:89], v85 offset0:88 offset1:90
	s_waitcnt lgkmcnt(0)
	v_mfma_f32_32x32x16_bf16 v[4:19], v[76:79], v[86:89], v[4:19]
	ds_read2_b64 v[86:89], v85 offset0:92 offset1:94
	s_waitcnt lgkmcnt(0)
	v_mfma_f32_32x32x16_bf16 v[4:19], v[80:83], v[86:89], v[4:19]
	s_nop 11
	v_cvt_pk_bf16_f32 v4, v4, v5
	ds_write_b16 v84, v4 offset:64
	ds_write_b16_d16_hi v84, v4 offset:336
	v_cvt_pk_bf16_f32 v4, v6, v7
	ds_write_b16 v84, v4 offset:608
	ds_write_b16_d16_hi v84, v4 offset:880
	v_cvt_pk_bf16_f32 v4, v8, v9
	ds_write_b16 v84, v4 offset:2240
	ds_write_b16_d16_hi v84, v4 offset:2512
	v_cvt_pk_bf16_f32 v4, v10, v11
	ds_write_b16 v84, v4 offset:2784
	ds_write_b16_d16_hi v84, v4 offset:3056
	v_cvt_pk_bf16_f32 v4, v12, v13
	ds_write_b16 v84, v4 offset:4416
	ds_write_b16_d16_hi v84, v4 offset:4688
	v_cvt_pk_bf16_f32 v4, v14, v15
	ds_write_b16 v84, v4 offset:4960
	ds_write_b16_d16_hi v84, v4 offset:5232
	v_cvt_pk_bf16_f32 v4, v16, v17
	ds_write_b16 v84, v4 offset:6592
	ds_write_b16_d16_hi v84, v4 offset:6864
	v_cvt_pk_bf16_f32 v4, v18, v19
	ds_write_b16 v84, v4 offset:7136
	ds_write_b16_d16_hi v84, v4 offset:7408
	v_mad_u32_u24 v85, v214, s8, v92
	ds_read2_b64 v[4:7], v85 offset1:2
	s_waitcnt lgkmcnt(0)
	v_mfma_f32_32x32x16_bf16 v[4:19], v[20:23], v[4:7], 0
	ds_read2_b64 v[86:89], v85 offset0:4 offset1:6
	s_waitcnt lgkmcnt(0)
	v_mfma_f32_32x32x16_bf16 v[4:19], v[24:27], v[86:89], v[4:19]
	ds_read2_b64 v[86:89], v85 offset0:8 offset1:10
	s_waitcnt lgkmcnt(0)
	v_mfma_f32_32x32x16_bf16 v[4:19], v[32:35], v[86:89], v[4:19]
	ds_read2_b64 v[86:89], v85 offset0:12 offset1:14
	s_waitcnt lgkmcnt(0)
	v_mfma_f32_32x32x16_bf16 v[4:19], v[28:31], v[86:89], v[4:19]
	ds_read2_b64 v[86:89], v85 offset0:16 offset1:18
	s_waitcnt lgkmcnt(0)
	v_mfma_f32_32x32x16_bf16 v[4:19], v[36:39], v[86:89], v[4:19]
	ds_read2_b64 v[86:89], v85 offset0:20 offset1:22
	s_waitcnt lgkmcnt(0)
	v_mfma_f32_32x32x16_bf16 v[4:19], v[40:43], v[86:89], v[4:19]
	ds_read2_b64 v[86:89], v85 offset0:24 offset1:26
	s_waitcnt lgkmcnt(0)
	v_mfma_f32_32x32x16_bf16 v[4:19], v[48:51], v[86:89], v[4:19]
	ds_read2_b64 v[86:89], v85 offset0:28 offset1:30
	s_waitcnt lgkmcnt(0)
	v_mfma_f32_32x32x16_bf16 v[4:19], v[44:47], v[86:89], v[4:19]
	ds_read2_b64 v[86:89], v85 offset0:32 offset1:34
	s_waitcnt lgkmcnt(0)
	v_mfma_f32_32x32x16_bf16 v[4:19], v[52:55], v[86:89], v[4:19]
	ds_read2_b64 v[86:89], v85 offset0:36 offset1:38
	s_waitcnt lgkmcnt(0)
	v_mfma_f32_32x32x16_bf16 v[4:19], v[56:59], v[86:89], v[4:19]
	ds_read2_b64 v[86:89], v85 offset0:40 offset1:42
	s_waitcnt lgkmcnt(0)
	v_mfma_f32_32x32x16_bf16 v[4:19], v[64:67], v[86:89], v[4:19]
	ds_read2_b64 v[86:89], v85 offset0:44 offset1:46
	s_waitcnt lgkmcnt(0)
	v_mfma_f32_32x32x16_bf16 v[4:19], v[60:63], v[86:89], v[4:19]
	ds_read2_b64 v[86:89], v85 offset0:48 offset1:50
	s_waitcnt lgkmcnt(0)
	v_mfma_f32_32x32x16_bf16 v[4:19], v[68:71], v[86:89], v[4:19]
	ds_read2_b64 v[86:89], v85 offset0:52 offset1:54
	s_waitcnt lgkmcnt(0)
	v_mfma_f32_32x32x16_bf16 v[4:19], v[72:75], v[86:89], v[4:19]
	ds_read2_b64 v[86:89], v85 offset0:56 offset1:58
	s_waitcnt lgkmcnt(0)
	v_mfma_f32_32x32x16_bf16 v[4:19], v[76:79], v[86:89], v[4:19]
	ds_read2_b64 v[86:89], v85 offset0:60 offset1:62
	s_waitcnt lgkmcnt(0)
	v_mfma_f32_32x32x16_bf16 v[4:19], v[80:83], v[86:89], v[4:19]
	s_nop 11
	v_cvt_pk_bf16_f32 v4, v4, v5
	ds_write_b16 v84, v4 offset:128
	ds_write_b16_d16_hi v84, v4 offset:400
	v_cvt_pk_bf16_f32 v4, v6, v7
	ds_write_b16 v84, v4 offset:672
	ds_write_b16_d16_hi v84, v4 offset:944
	v_cvt_pk_bf16_f32 v4, v8, v9
	ds_write_b16 v84, v4 offset:2304
	ds_write_b16_d16_hi v84, v4 offset:2576
	v_cvt_pk_bf16_f32 v4, v10, v11
	ds_write_b16 v84, v4 offset:2848
	ds_write_b16_d16_hi v84, v4 offset:3120
	v_cvt_pk_bf16_f32 v4, v12, v13
	ds_write_b16 v84, v4 offset:4480
	ds_write_b16_d16_hi v84, v4 offset:4752
	v_cvt_pk_bf16_f32 v4, v14, v15
	ds_write_b16 v84, v4 offset:5024
	ds_write_b16_d16_hi v84, v4 offset:5296
	v_cvt_pk_bf16_f32 v4, v16, v17
	ds_write_b16 v84, v4 offset:6656
	ds_write_b16_d16_hi v84, v4 offset:6928
	v_cvt_pk_bf16_f32 v4, v18, v19
	ds_write_b16 v84, v4 offset:7200
	ds_write_b16_d16_hi v84, v4 offset:7472
	v_mad_u32_u24 v85, v212, s8, v92
	ds_read2_b64 v[4:7], v85 offset1:2
	s_waitcnt lgkmcnt(0)
	v_mfma_f32_32x32x16_bf16 v[4:19], v[20:23], v[4:7], 0
	ds_read2_b64 v[20:23], v85 offset0:4 offset1:6
	s_waitcnt lgkmcnt(0)
	v_mfma_f32_32x32x16_bf16 v[4:19], v[24:27], v[20:23], v[4:19]
	ds_read2_b64 v[20:23], v85 offset0:8 offset1:10
	s_waitcnt lgkmcnt(0)
	v_mfma_f32_32x32x16_bf16 v[4:19], v[32:35], v[20:23], v[4:19]
	ds_read2_b64 v[20:23], v85 offset0:12 offset1:14
	s_waitcnt lgkmcnt(0)
	v_mfma_f32_32x32x16_bf16 v[4:19], v[28:31], v[20:23], v[4:19]
	ds_read2_b64 v[20:23], v85 offset0:16 offset1:18
	s_waitcnt lgkmcnt(0)
	v_mfma_f32_32x32x16_bf16 v[4:19], v[36:39], v[20:23], v[4:19]
	ds_read2_b64 v[20:23], v85 offset0:20 offset1:22
	s_waitcnt lgkmcnt(0)
	v_mfma_f32_32x32x16_bf16 v[4:19], v[40:43], v[20:23], v[4:19]
	ds_read2_b64 v[20:23], v85 offset0:24 offset1:26
	s_waitcnt lgkmcnt(0)
	v_mfma_f32_32x32x16_bf16 v[4:19], v[48:51], v[20:23], v[4:19]
	ds_read2_b64 v[20:23], v85 offset0:28 offset1:30
	s_waitcnt lgkmcnt(0)
	v_mfma_f32_32x32x16_bf16 v[4:19], v[44:47], v[20:23], v[4:19]
	ds_read2_b64 v[20:23], v85 offset0:32 offset1:34
	s_waitcnt lgkmcnt(0)
	v_mfma_f32_32x32x16_bf16 v[4:19], v[52:55], v[20:23], v[4:19]
	ds_read2_b64 v[20:23], v85 offset0:36 offset1:38
	s_waitcnt lgkmcnt(0)
	v_mfma_f32_32x32x16_bf16 v[4:19], v[56:59], v[20:23], v[4:19]
	ds_read2_b64 v[20:23], v85 offset0:40 offset1:42
	s_waitcnt lgkmcnt(0)
	v_mfma_f32_32x32x16_bf16 v[4:19], v[64:67], v[20:23], v[4:19]
	ds_read2_b64 v[20:23], v85 offset0:44 offset1:46
	s_waitcnt lgkmcnt(0)
	v_mfma_f32_32x32x16_bf16 v[4:19], v[60:63], v[20:23], v[4:19]
	ds_read2_b64 v[20:23], v85 offset0:48 offset1:50
	s_waitcnt lgkmcnt(0)
	v_mfma_f32_32x32x16_bf16 v[4:19], v[68:71], v[20:23], v[4:19]
	ds_read2_b64 v[20:23], v85 offset0:52 offset1:54
	s_waitcnt lgkmcnt(0)
	v_mfma_f32_32x32x16_bf16 v[4:19], v[72:75], v[20:23], v[4:19]
	ds_read2_b64 v[20:23], v85 offset0:56 offset1:58
	s_waitcnt lgkmcnt(0)
	v_mfma_f32_32x32x16_bf16 v[4:19], v[76:79], v[20:23], v[4:19]
	ds_read2_b64 v[20:23], v85 offset0:60 offset1:62
	s_waitcnt lgkmcnt(0)
	v_mfma_f32_32x32x16_bf16 v[4:19], v[80:83], v[20:23], v[4:19]
	s_nop 11
	v_cvt_pk_bf16_f32 v4, v4, v5
	ds_write_b16 v84, v4 offset:192
	ds_write_b16_d16_hi v84, v4 offset:464
	v_cvt_pk_bf16_f32 v4, v6, v7
	ds_write_b16 v84, v4 offset:736
	ds_write_b16_d16_hi v84, v4 offset:1008
	v_cvt_pk_bf16_f32 v4, v8, v9
	ds_write_b16 v84, v4 offset:2368
	ds_write_b16_d16_hi v84, v4 offset:2640
	v_cvt_pk_bf16_f32 v4, v10, v11
	ds_write_b16 v84, v4 offset:2912
	ds_write_b16_d16_hi v84, v4 offset:3184
	v_cvt_pk_bf16_f32 v4, v12, v13
	ds_write_b16 v84, v4 offset:4544
	ds_write_b16_d16_hi v84, v4 offset:4816
	v_cvt_pk_bf16_f32 v4, v14, v15
	ds_write_b16 v84, v4 offset:5088
	ds_write_b16_d16_hi v84, v4 offset:5360
	v_cvt_pk_bf16_f32 v4, v16, v17
	ds_write_b16 v84, v4 offset:6720
	ds_write_b16_d16_hi v84, v4 offset:6992
	v_cvt_pk_bf16_f32 v4, v18, v19
	ds_write_b16 v84, v4 offset:7264
	ds_write_b16_d16_hi v84, v4 offset:7536
	v_mul_u32_u24_e32 v4, 0x110, v210
	v_add3_u32 v6, s61, v4, v2
	ds_read_b128 v[8:11], v6
	s_mulk_i32 s41, 0xc00
	s_mul_hi_u32 s44, s40, 0xc00
	s_waitcnt vmcnt(7)
	v_lshlrev_b32_e32 v14, 16, v160
	v_and_b32_e32 v15, 0xffff0000, v160
	s_waitcnt lgkmcnt(0)
	v_lshlrev_b32_e32 v12, 16, v8
	v_and_b32_e32 v13, 0xffff0000, v8
	s_add_i32 s44, s44, s41
	s_mulk_i32 s40, 0xc00
	v_pk_mul_f32 v[12:13], v[14:15], v[12:13]
	s_add_u32 s40, s36, s40
	v_cvt_pk_bf16_f32 v8, v12, v13
	v_lshlrev_b32_e32 v12, 16, v9
	v_and_b32_e32 v13, 0xffff0000, v9
	v_lshlrev_b32_e32 v14, 16, v161
	v_and_b32_e32 v15, 0xffff0000, v161
	s_addc_u32 s41, s37, s44
	v_pk_mul_f32 v[12:13], v[14:15], v[12:13]
	s_add_u32 s40, s40, s24
	v_mul_u32_u24_e32 v4, 0x600, v210
	v_cvt_pk_bf16_f32 v9, v12, v13
	v_lshlrev_b32_e32 v12, 16, v10
	v_and_b32_e32 v13, 0xffff0000, v10
	v_lshlrev_b32_e32 v14, 16, v162
	v_and_b32_e32 v15, 0xffff0000, v162
	s_addc_u32 s41, s41, 0
	v_lshlrev_b32_e32 v4, 1, v4
	v_mov_b32_e32 v5, v3
	v_pk_mul_f32 v[12:13], v[14:15], v[12:13]
	v_lshl_add_u64 v[4:5], s[40:41], 0, v[4:5]
	v_cvt_pk_bf16_f32 v10, v12, v13
	v_lshlrev_b32_e32 v12, 16, v11
	v_and_b32_e32 v13, 0xffff0000, v11
	v_lshlrev_b32_e32 v14, 16, v163
	v_and_b32_e32 v15, 0xffff0000, v163
	v_lshl_add_u64 v[4:5], v[4:5], 0, v[2:3]
	v_pk_mul_f32 v[12:13], v[14:15], v[12:13]
	s_waitcnt vmcnt(6)
	v_lshlrev_b32_e32 v14, 16, v156
	v_cvt_pk_bf16_f32 v11, v12, v13
	v_add_co_u32_e32 v12, vcc, s21, v4
	v_and_b32_e32 v15, 0xffff0000, v156
	s_nop 0
	v_addc_co_u32_e32 v13, vcc, 0, v5, vcc
	global_store_dwordx4 v[12:13], v[8:11], off offset:2048 sc1
	ds_read_b128 v[8:11], v6 offset:1088
	s_add_i32 s43, s43, s10
	s_add_i32 s42, s42, s93
	s_add_i32 s14, s14, s29
	s_cmpk_lt_i32 s43, 0x100
	s_waitcnt lgkmcnt(0)
	v_lshlrev_b32_e32 v12, 16, v8
	v_and_b32_e32 v13, 0xffff0000, v8
	v_pk_mul_f32 v[12:13], v[14:15], v[12:13]
	v_lshlrev_b32_e32 v14, 16, v157
	v_cvt_pk_bf16_f32 v8, v12, v13
	v_lshlrev_b32_e32 v12, 16, v9
	v_and_b32_e32 v13, 0xffff0000, v9
	v_and_b32_e32 v15, 0xffff0000, v157
	v_pk_mul_f32 v[12:13], v[14:15], v[12:13]
	v_lshlrev_b32_e32 v14, 16, v158
	v_cvt_pk_bf16_f32 v9, v12, v13
	v_lshlrev_b32_e32 v12, 16, v10
	v_and_b32_e32 v13, 0xffff0000, v10
	v_and_b32_e32 v15, 0xffff0000, v158
	v_pk_mul_f32 v[12:13], v[14:15], v[12:13]
	v_lshlrev_b32_e32 v14, 16, v159
	v_cvt_pk_bf16_f32 v10, v12, v13
	v_lshlrev_b32_e32 v12, 16, v11
	v_and_b32_e32 v13, 0xffff0000, v11
	v_and_b32_e32 v15, 0xffff0000, v159
	v_pk_mul_f32 v[12:13], v[14:15], v[12:13]
	s_waitcnt vmcnt(6)
	v_lshlrev_b32_e32 v14, 16, v152
	v_cvt_pk_bf16_f32 v11, v12, v13
	v_add_co_u32_e32 v12, vcc, s2, v4
	v_and_b32_e32 v15, 0xffff0000, v152
	s_nop 0
	v_addc_co_u32_e32 v13, vcc, 0, v5, vcc
	global_store_dwordx4 v[12:13], v[8:11], off offset:2048 sc1
	ds_read_b128 v[8:11], v6 offset:2176
	s_waitcnt lgkmcnt(0)
	v_lshlrev_b32_e32 v12, 16, v8
	v_and_b32_e32 v13, 0xffff0000, v8
	v_pk_mul_f32 v[12:13], v[14:15], v[12:13]
	v_lshlrev_b32_e32 v14, 16, v153
	v_cvt_pk_bf16_f32 v8, v12, v13
	v_lshlrev_b32_e32 v12, 16, v9
	v_and_b32_e32 v13, 0xffff0000, v9
	v_and_b32_e32 v15, 0xffff0000, v153
	v_pk_mul_f32 v[12:13], v[14:15], v[12:13]
	v_lshlrev_b32_e32 v14, 16, v154
	v_cvt_pk_bf16_f32 v9, v12, v13
	v_lshlrev_b32_e32 v12, 16, v10
	v_and_b32_e32 v13, 0xffff0000, v10
	v_and_b32_e32 v15, 0xffff0000, v154
	v_pk_mul_f32 v[12:13], v[14:15], v[12:13]
	v_lshlrev_b32_e32 v14, 16, v155
	v_cvt_pk_bf16_f32 v10, v12, v13
	v_lshlrev_b32_e32 v12, 16, v11
	v_and_b32_e32 v13, 0xffff0000, v11
	v_and_b32_e32 v15, 0xffff0000, v155
	v_pk_mul_f32 v[12:13], v[14:15], v[12:13]
	s_waitcnt vmcnt(6)
	v_lshlrev_b32_e32 v14, 16, v148
	v_cvt_pk_bf16_f32 v11, v12, v13
	v_add_co_u32_e32 v12, vcc, s3, v4
	v_and_b32_e32 v15, 0xffff0000, v148
	s_nop 0
	v_addc_co_u32_e32 v13, vcc, 0, v5, vcc
	global_store_dwordx4 v[12:13], v[8:11], off offset:2048 sc1
	ds_read_b128 v[8:11], v6 offset:3264
	s_waitcnt lgkmcnt(0)
	v_lshlrev_b32_e32 v12, 16, v8
	v_and_b32_e32 v13, 0xffff0000, v8
	v_pk_mul_f32 v[12:13], v[14:15], v[12:13]
	v_lshlrev_b32_e32 v14, 16, v149
	v_cvt_pk_bf16_f32 v8, v12, v13
	v_lshlrev_b32_e32 v12, 16, v9
	v_and_b32_e32 v13, 0xffff0000, v9
	v_and_b32_e32 v15, 0xffff0000, v149
	v_pk_mul_f32 v[12:13], v[14:15], v[12:13]
	v_lshlrev_b32_e32 v14, 16, v150
	v_cvt_pk_bf16_f32 v9, v12, v13
	v_lshlrev_b32_e32 v12, 16, v10
	v_and_b32_e32 v13, 0xffff0000, v10
	v_and_b32_e32 v15, 0xffff0000, v150
	v_pk_mul_f32 v[12:13], v[14:15], v[12:13]
	v_lshlrev_b32_e32 v14, 16, v151
	v_cvt_pk_bf16_f32 v10, v12, v13
	v_lshlrev_b32_e32 v12, 16, v11
	v_and_b32_e32 v13, 0xffff0000, v11
	v_and_b32_e32 v15, 0xffff0000, v151
	v_pk_mul_f32 v[12:13], v[14:15], v[12:13]
	s_waitcnt vmcnt(6)
	v_lshlrev_b32_e32 v14, 16, v144
	v_cvt_pk_bf16_f32 v11, v12, v13
	v_add_co_u32_e32 v12, vcc, s94, v4
	v_and_b32_e32 v15, 0xffff0000, v144
	s_nop 0
	v_addc_co_u32_e32 v13, vcc, 0, v5, vcc
	global_store_dwordx4 v[12:13], v[8:11], off offset:2048 sc1
	ds_read_b128 v[8:11], v6 offset:4352
	s_waitcnt lgkmcnt(0)
	v_lshlrev_b32_e32 v12, 16, v8
	v_and_b32_e32 v13, 0xffff0000, v8
	v_pk_mul_f32 v[12:13], v[14:15], v[12:13]
	v_lshlrev_b32_e32 v14, 16, v145
	v_cvt_pk_bf16_f32 v8, v12, v13
	v_lshlrev_b32_e32 v12, 16, v9
	v_and_b32_e32 v13, 0xffff0000, v9
	v_and_b32_e32 v15, 0xffff0000, v145
	v_pk_mul_f32 v[12:13], v[14:15], v[12:13]
	v_lshlrev_b32_e32 v14, 16, v146
	v_cvt_pk_bf16_f32 v9, v12, v13
	v_lshlrev_b32_e32 v12, 16, v10
	v_and_b32_e32 v13, 0xffff0000, v10
	v_and_b32_e32 v15, 0xffff0000, v146
	v_pk_mul_f32 v[12:13], v[14:15], v[12:13]
	v_lshlrev_b32_e32 v14, 16, v147
	v_cvt_pk_bf16_f32 v10, v12, v13
	v_lshlrev_b32_e32 v12, 16, v11
	v_and_b32_e32 v13, 0xffff0000, v11
	v_and_b32_e32 v15, 0xffff0000, v147
	v_pk_mul_f32 v[12:13], v[14:15], v[12:13]
	s_waitcnt vmcnt(6)
	v_lshlrev_b32_e32 v14, 16, v140
	v_cvt_pk_bf16_f32 v11, v12, v13
	v_add_co_u32_e32 v12, vcc, s97, v4
	v_and_b32_e32 v15, 0xffff0000, v140
	s_nop 0
	v_addc_co_u32_e32 v13, vcc, 0, v5, vcc
	global_store_dwordx4 v[12:13], v[8:11], off offset:2048 sc1
	ds_read_b128 v[8:11], v6 offset:5440
	s_waitcnt lgkmcnt(0)
	v_lshlrev_b32_e32 v12, 16, v8
	v_and_b32_e32 v13, 0xffff0000, v8
	v_pk_mul_f32 v[12:13], v[14:15], v[12:13]
	v_lshlrev_b32_e32 v14, 16, v141
	v_cvt_pk_bf16_f32 v8, v12, v13
	v_lshlrev_b32_e32 v12, 16, v9
	v_and_b32_e32 v13, 0xffff0000, v9
	v_and_b32_e32 v15, 0xffff0000, v141
	v_pk_mul_f32 v[12:13], v[14:15], v[12:13]
	v_lshlrev_b32_e32 v14, 16, v142
	v_cvt_pk_bf16_f32 v9, v12, v13
	v_lshlrev_b32_e32 v12, 16, v10
	v_and_b32_e32 v13, 0xffff0000, v10
	v_and_b32_e32 v15, 0xffff0000, v142
	v_pk_mul_f32 v[12:13], v[14:15], v[12:13]
	v_lshlrev_b32_e32 v14, 16, v143
	v_cvt_pk_bf16_f32 v10, v12, v13
	v_lshlrev_b32_e32 v12, 16, v11
	v_and_b32_e32 v13, 0xffff0000, v11
	v_and_b32_e32 v15, 0xffff0000, v143
	v_pk_mul_f32 v[12:13], v[14:15], v[12:13]
	s_waitcnt vmcnt(6)
	v_lshlrev_b32_e32 v14, 16, v136
	v_cvt_pk_bf16_f32 v11, v12, v13
	v_add_co_u32_e32 v12, vcc, s4, v4
	v_and_b32_e32 v15, 0xffff0000, v136
	s_nop 0
	v_addc_co_u32_e32 v13, vcc, 0, v5, vcc
	global_store_dwordx4 v[12:13], v[8:11], off offset:2048 sc1
	ds_read_b128 v[8:11], v6 offset:6528
	s_waitcnt lgkmcnt(0)
	v_lshlrev_b32_e32 v12, 16, v8
	v_and_b32_e32 v13, 0xffff0000, v8
	v_pk_mul_f32 v[12:13], v[14:15], v[12:13]
	v_lshlrev_b32_e32 v14, 16, v137
	v_cvt_pk_bf16_f32 v8, v12, v13
	v_lshlrev_b32_e32 v12, 16, v9
	v_and_b32_e32 v13, 0xffff0000, v9
	v_and_b32_e32 v15, 0xffff0000, v137
	v_pk_mul_f32 v[12:13], v[14:15], v[12:13]
	v_lshlrev_b32_e32 v14, 16, v138
	v_cvt_pk_bf16_f32 v9, v12, v13
	v_lshlrev_b32_e32 v12, 16, v10
	v_and_b32_e32 v13, 0xffff0000, v10
	v_and_b32_e32 v15, 0xffff0000, v138
	v_pk_mul_f32 v[12:13], v[14:15], v[12:13]
	v_lshlrev_b32_e32 v14, 16, v139
	v_cvt_pk_bf16_f32 v10, v12, v13
	v_lshlrev_b32_e32 v12, 16, v11
	v_and_b32_e32 v13, 0xffff0000, v11
	v_and_b32_e32 v15, 0xffff0000, v139
	v_pk_mul_f32 v[12:13], v[14:15], v[12:13]
	s_nop 0
	v_cvt_pk_bf16_f32 v11, v12, v13
	v_add_co_u32_e32 v12, vcc, s22, v4
	s_nop 1
	v_addc_co_u32_e32 v13, vcc, 0, v5, vcc
	global_store_dwordx4 v[12:13], v[8:11], off offset:2048 sc1
	ds_read_b128 v[6:9], v6 offset:7616
	s_waitcnt vmcnt(7)
	v_lshlrev_b32_e32 v12, 16, v132
	v_and_b32_e32 v13, 0xffff0000, v132
	v_add_co_u32_e32 v4, vcc, 0xc615000, v4
	s_waitcnt lgkmcnt(0)
	v_lshlrev_b32_e32 v10, 16, v6
	v_and_b32_e32 v11, 0xffff0000, v6
	v_pk_mul_f32 v[10:11], v[12:13], v[10:11]
	v_lshlrev_b32_e32 v12, 16, v133
	v_cvt_pk_bf16_f32 v6, v10, v11
	v_lshlrev_b32_e32 v10, 16, v7
	v_and_b32_e32 v11, 0xffff0000, v7
	v_and_b32_e32 v13, 0xffff0000, v133
	v_pk_mul_f32 v[10:11], v[12:13], v[10:11]
	v_lshlrev_b32_e32 v12, 16, v134
	v_cvt_pk_bf16_f32 v7, v10, v11
	v_lshlrev_b32_e32 v10, 16, v8
	v_and_b32_e32 v11, 0xffff0000, v8
	v_and_b32_e32 v13, 0xffff0000, v134
	v_pk_mul_f32 v[10:11], v[12:13], v[10:11]
	v_lshlrev_b32_e32 v12, 16, v135
	v_cvt_pk_bf16_f32 v8, v10, v11
	v_lshlrev_b32_e32 v10, 16, v9
	v_and_b32_e32 v11, 0xffff0000, v9
	v_and_b32_e32 v13, 0xffff0000, v135
	v_pk_mul_f32 v[10:11], v[12:13], v[10:11]
	v_addc_co_u32_e32 v5, vcc, 0, v5, vcc
	v_cvt_pk_bf16_f32 v9, v10, v11
	global_store_dwordx4 v[4:5], v[6:9], off offset:2048 sc1
	s_barrier
	s_cbranch_scc1 .LBB0_758
	s_branch .LBB0_681

.LBB0_780:
	s_mul_i32 s2, s62, 0x1200
	v_readlane_b32 s0, v254, 31
	s_add_i32 s2, s2, 0
	s_lshl_b32 s0, s0, 6
	v_lshrrev_b32_e32 v20, 3, v25
	s_add_i32 s0, s2, s0
	v_and_b32_e32 v20, 4, v20
	v_lshlrev_b32_e32 v21, 1, v24
	v_mul_u32_u24_e32 v20, 0x90, v20
	v_and_b32_e32 v21, 62, v21
	s_add_i32 s0, s0, 0x11ac0
	v_add3_u32 v72, s0, v20, v21
	v_cndmask_b32_e64 v21, v31, 1.0, s[38:39]
	v_cndmask_b32_e64 v20, v87, 0, s[38:39]
	s_waitcnt lgkmcnt(0)
	v_fmac_f32_e32 v20, v21, v23
	v_lshlrev_b32_e32 v22, 3, v70
	v_cmp_lt_u32_e32 vcc, 31, v24
	v_cndmask_b32_e64 v25, v92, v89, s[38:39]
	v_cndmask_b32_e64 v24, v90, v88, s[38:39]
	v_cndmask_b32_e64 v31, v96, v93, s[38:39]
	v_cndmask_b32_e64 v70, v94, v91, s[38:39]
	v_cndmask_b32_e64 v87, v99, v97, s[38:39]
	v_cndmask_b32_e64 v88, v98, v95, s[38:39]
	v_pk_fma_f32 v[50:51], v[50:51], v[20:21], v[54:55] op_sel_hi:[1,0,1]
	v_pk_fma_f32 v[54:55], v[64:65], v[20:21], v[56:57] op_sel_hi:[1,0,1]
	v_fmac_f32_e32 v24, v25, v23
	v_fmac_f32_e32 v70, v31, v23
	v_fmac_f32_e32 v88, v87, v23
	v_cvt_pk_bf16_f32 v23, v50, v51
	v_pk_fma_f32 v[44:45], v[44:45], v[24:25], v[48:49] op_sel_hi:[1,0,1]
	ds_write_b16 v72, v23
	ds_write_b16_d16_hi v72, v23 offset:144
	v_cvt_pk_bf16_f32 v23, v54, v55
	v_pk_fma_f32 v[24:25], v[60:61], v[24:25], v[52:53] op_sel_hi:[1,0,1]
	ds_write_b16 v72, v23 offset:288
	ds_write_b16_d16_hi v72, v23 offset:432
	v_cvt_pk_bf16_f32 v23, v44, v45
	v_pk_fma_f32 v[38:39], v[38:39], v[70:71], v[42:43] op_sel_hi:[1,0,1]
	ds_write_b16 v72, v23 offset:1152
	ds_write_b16_d16_hi v72, v23 offset:1296
	v_cvt_pk_bf16_f32 v23, v24, v25
	s_cmp_eq_u32 s62, 3
	v_pk_fma_f32 v[42:43], v[58:59], v[70:71], v[46:47] op_sel_hi:[1,0,1]
	ds_write_b16 v72, v23 offset:1440
	ds_write_b16_d16_hi v72, v23 offset:1584
	v_cvt_pk_bf16_f32 v23, v38, v39
	s_cselect_b64 s[2:3], -1, 0
	v_pk_fma_f32 v[34:35], v[34:35], v[88:89], v[36:37] op_sel_hi:[1,0,1]
	v_pk_fma_f32 v[20:21], v[62:63], v[88:89], v[40:41] op_sel_hi:[1,0,1]
	ds_write_b16 v72, v23 offset:2304
	ds_write_b16_d16_hi v72, v23 offset:2448
	v_cvt_pk_bf16_f32 v23, v42, v43
	s_and_b64 s[2:3], s[2:3], vcc
	ds_write_b16 v72, v23 offset:2592
	ds_write_b16_d16_hi v72, v23 offset:2736
	v_cvt_pk_bf16_f32 v23, v34, v35
	v_cvt_pk_bf16_f32 v20, v20, v21
	ds_write_b16 v72, v23 offset:3456
	ds_write_b16_d16_hi v72, v23 offset:3600
	ds_write_b16 v72, v20 offset:3744
	ds_write_b16_d16_hi v72, v20 offset:3888
	s_waitcnt lgkmcnt(0)
	s_barrier
	s_and_saveexec_b64 s[30:31], s[2:3]
	ds_write_b32 v69, v21
	s_or_b64 exec, exec, s[30:31]
	v_mul_lo_u32 v20, v30, s13
	s_add_i32 s0, 0, 0x11ac0
	v_add_u32_e32 v34, s0, v20
	v_add_u32_e32 v70, v34, v2
	s_add_u32 s28, s36, s24
	ds_read_b128 v[34:37], v70
	s_addc_u32 s29, s37, 0
	v_lshlrev_b32_e32 v30, 1, v22
	v_mov_b32_e32 v31, v3
	v_readlane_b32 s30, v253, 9
	v_lshl_add_u64 v[20:21], s[28:29], 0, v[30:31]
	s_mov_b64 s[28:29], 0xc600000
	v_readlane_b32 s31, v253, 10
	v_lshl_add_u64 v[24:25], v[20:21], 0, s[28:29]
	s_waitcnt vmcnt(19)
	v_lshlrev_b32_e32 v38, 16, v16
	v_lshl_add_u64 v[22:23], v[28:29], 0, s[30:31]
	v_mad_u64_u32 v[20:21], s[28:29], v22, s5, v[24:25]
	v_mad_i32_i24 v21, v23, s5, v21
	s_waitcnt lgkmcnt(0)
	v_lshlrev_b32_e32 v22, 16, v34
	v_and_b32_e32 v23, 0xffff0000, v34
	v_and_b32_e32 v39, 0xffff0000, v16
	v_pk_mul_f32 v[22:23], v[38:39], v[22:23]
	v_lshlrev_b32_e32 v34, 16, v17
	v_cvt_pk_bf16_f32 v16, v22, v23
	v_lshlrev_b32_e32 v22, 16, v35
	v_and_b32_e32 v23, 0xffff0000, v35
	v_and_b32_e32 v35, 0xffff0000, v17
	v_pk_mul_f32 v[22:23], v[34:35], v[22:23]
	v_lshlrev_b32_e32 v34, 16, v18
	v_cvt_pk_bf16_f32 v17, v22, v23
	v_lshlrev_b32_e32 v22, 16, v36
	v_and_b32_e32 v23, 0xffff0000, v36
	v_and_b32_e32 v35, 0xffff0000, v18
	v_pk_mul_f32 v[22:23], v[34:35], v[22:23]
	v_lshlrev_b32_e32 v34, 16, v19
	v_cvt_pk_bf16_f32 v18, v22, v23
	v_lshlrev_b32_e32 v22, 16, v37
	v_and_b32_e32 v23, 0xffff0000, v37
	v_and_b32_e32 v35, 0xffff0000, v19
	v_pk_mul_f32 v[22:23], v[34:35], v[22:23]
	s_waitcnt vmcnt(18)
	v_lshlrev_b32_e32 v34, 16, v8
	v_cvt_pk_bf16_f32 v19, v22, v23
	global_store_dwordx4 v[20:21], v[16:19], off sc1
	ds_read_b128 v[16:19], v70 offset:9216
	v_and_b32_e32 v35, 0xffff0000, v8
	s_mov_b32 s0, 0x30000
	s_or_b32 s28, s30, 0x100
	s_mov_b32 s29, s25
	s_waitcnt lgkmcnt(0)
	v_lshlrev_b32_e32 v22, 16, v16
	v_and_b32_e32 v23, 0xffff0000, v16
	v_pk_mul_f32 v[22:23], v[34:35], v[22:23]
	v_lshlrev_b32_e32 v16, 16, v17
	v_cvt_pk_bf16_f32 v8, v22, v23
	v_and_b32_e32 v17, 0xffff0000, v17
	v_lshlrev_b32_e32 v22, 16, v9
	v_and_b32_e32 v23, 0xffff0000, v9
	v_pk_mul_f32 v[16:17], v[22:23], v[16:17]
	v_lshlrev_b32_e32 v22, 16, v10
	v_cvt_pk_bf16_f32 v9, v16, v17
	v_lshlrev_b32_e32 v16, 16, v18
	v_and_b32_e32 v17, 0xffff0000, v18
	v_and_b32_e32 v23, 0xffff0000, v10
	v_pk_mul_f32 v[16:17], v[22:23], v[16:17]
	v_lshlrev_b32_e32 v18, 16, v11
	v_cvt_pk_bf16_f32 v10, v16, v17
	v_lshlrev_b32_e32 v16, 16, v19
	v_and_b32_e32 v17, 0xffff0000, v19
	v_and_b32_e32 v19, 0xffff0000, v11
	v_pk_mul_f32 v[16:17], v[18:19], v[16:17]
	v_lshl_add_u64 v[34:35], v[28:29], 0, s[28:29]
	v_cvt_pk_bf16_f32 v11, v16, v17
	v_add_co_u32_e32 v16, vcc, s0, v20
	s_mov_b32 s0, 0x10000
	s_nop 0
	v_addc_co_u32_e32 v17, vcc, 0, v21, vcc
	global_store_dwordx4 v[16:17], v[8:11], off sc1
	s_nop 1
	v_add_co_u32_e32 v8, vcc, s0, v26
	s_nop 1
	v_addc_co_u32_e32 v9, vcc, 0, v27, vcc
	global_load_dword v110, v[8:9], off nt
	global_load_dword v109, v[8:9], off offset:256 nt
	global_load_dword v107, v[8:9], off offset:512 nt
	global_load_dword v105, v[8:9], off offset:768 nt
	global_load_dword v103, v[8:9], off offset:1024 nt
	global_load_dword v101, v[8:9], off offset:1280 nt
	global_load_dword v99, v[8:9], off offset:1536 nt
	global_load_dword v97, v[8:9], off offset:1792 nt
	global_load_dword v95, v[8:9], off offset:2048 nt
	global_load_dword v93, v[8:9], off offset:2304 nt
	global_load_dword v92, v[8:9], off offset:2560 nt
	global_load_dword v91, v[8:9], off offset:2816 nt
	global_load_dword v90, v[8:9], off offset:3072 nt
	global_load_dword v89, v[8:9], off offset:3328 nt
	global_load_dword v88, v[8:9], off offset:3584 nt
	global_load_dword v87, v[8:9], off offset:3840 nt
	v_mov_b64_e32 v[8:9], s[54:55]
	v_mad_u64_u32 v[8:9], s[28:29], v34, s16, v[8:9]
	v_mad_i32_i24 v9, v35, s16, v9
	v_lshl_add_u64 v[8:9], v[8:9], 0, s[24:25]
	v_lshl_add_u64 v[8:9], v[8:9], 0, v[30:31]
	global_load_dwordx4 v[16:19], v[8:9], off offset:2048
	v_add_co_u32_e32 v8, vcc, s14, v8
	s_nop 1
	v_addc_co_u32_e32 v9, vcc, 0, v9, vcc
	global_load_dwordx4 v[8:11], v[8:9], off offset:2048
	s_waitcnt vmcnt(37)
	v_lshlrev_b32_e32 v2, 16, v86
	v_exp_f32_e32 v52, v2
	s_waitcnt vmcnt(36)
	v_lshlrev_b32_e32 v2, 16, v85
	v_exp_f32_e32 v2, v2
	s_waitcnt vmcnt(35)
	v_lshlrev_b32_e32 v20, 16, v84
	s_waitcnt vmcnt(29)
	v_lshlrev_b32_e32 v36, 16, v78
	v_exp_f32_e32 v20, v20
	v_lshlrev_b32_e32 v21, 16, v83
	v_exp_f32_e32 v40, v36
	s_waitcnt vmcnt(28)
	v_lshlrev_b32_e32 v36, 16, v77
	v_and_b32_e32 v56, 0xffff0000, v86
	v_exp_f32_e32 v21, v21
	v_exp_f32_e32 v37, v36
	s_waitcnt vmcnt(27)
	v_lshlrev_b32_e32 v36, 16, v76
	v_and_b32_e32 v57, 0xffff0000, v85
	v_lshlrev_b32_e32 v22, 16, v82
	v_exp_f32_e32 v60, v36
	s_waitcnt vmcnt(26)
	v_lshlrev_b32_e32 v36, 16, v75
	v_fmac_f32_e32 v56, 0, v52
	v_and_b32_e32 v58, 0xffff0000, v84
	v_exp_f32_e32 v46, v22
	v_lshlrev_b32_e32 v22, 16, v81
	v_exp_f32_e32 v61, v36
	s_waitcnt vmcnt(25)
	v_lshlrev_b32_e32 v36, 16, v74
	v_fmac_f32_e32 v57, v2, v56
	v_and_b32_e32 v59, 0xffff0000, v83
	v_exp_f32_e32 v22, v22
	v_lshlrev_b32_e32 v23, 16, v80
	v_exp_f32_e32 v36, v36
	s_waitcnt vmcnt(24)
	v_lshlrev_b32_e32 v39, 16, v73
	v_fmac_f32_e32 v58, v20, v57
	v_exp_f32_e32 v23, v23
	v_lshlrev_b32_e32 v31, 16, v79
	v_exp_f32_e32 v64, v39
	s_waitcnt vmcnt(23)
	v_lshlrev_b32_e32 v41, 16, v67
	v_mul_f32_e32 v53, v52, v2
	v_fmac_f32_e32 v59, v21, v58
	v_and_b32_e32 v50, 0xffff0000, v82
	v_exp_f32_e32 v31, v31
	v_exp_f32_e32 v65, v41
	s_waitcnt vmcnt(22)
	v_lshlrev_b32_e32 v41, 16, v66
	v_and_b32_e32 v43, 0xffff0000, v66
	v_mul_f32_e32 v66, v20, v53
	ds_bpermute_b32 v20, v197, v59
	v_and_b32_e32 v51, 0xffff0000, v81
	v_and_b32_e32 v44, 0xffff0000, v78
	v_and_b32_e32 v38, 0xffff0000, v74
	v_and_b32_e32 v39, 0xffff0000, v73
	v_exp_f32_e32 v73, v41
	v_fmac_f32_e32 v50, 0, v46
	v_and_b32_e32 v54, 0xffff0000, v80
	v_and_b32_e32 v45, 0xffff0000, v77
	v_and_b32_e32 v42, 0xffff0000, v67
	v_mul_f32_e32 v67, v21, v66
	v_fmac_f32_e32 v51, v22, v50
	v_mul_f32_e32 v47, v46, v22
	v_fmac_f32_e32 v44, 0, v40
	v_fmac_f32_e32 v38, 0, v36
	v_and_b32_e32 v55, 0xffff0000, v79
	v_fmac_f32_e32 v54, v23, v51
	v_mul_f32_e32 v62, v23, v47
	v_fmac_f32_e32 v45, v37, v44
	v_mul_f32_e32 v41, v40, v37
	v_fmac_f32_e32 v39, v64, v38
	v_mul_f32_e32 v37, v36, v64
	ds_bpermute_b32 v2, v197, v67
	v_fmac_f32_e32 v55, v31, v54
	v_mul_f32_e32 v63, v31, v62
	v_fmac_f32_e32 v42, v65, v39
	v_mul_f32_e32 v64, v65, v37
	v_fmac_f32_e32 v43, v73, v42
	v_mul_f32_e32 v65, v73, v64
	s_waitcnt lgkmcnt(1)
	v_cndmask_b32_e64 v31, v20, v59, s[38:39]
	v_cndmask_b32_e64 v73, v59, v20, s[38:39]
	ds_bpermute_b32 v20, v197, v63
	ds_bpermute_b32 v23, v197, v55
	v_and_b32_e32 v48, 0xffff0000, v76
	v_and_b32_e32 v49, 0xffff0000, v75
	v_fmac_f32_e32 v48, v60, v45
	v_mul_f32_e32 v60, v60, v41
	s_waitcnt lgkmcnt(2)
	v_cndmask_b32_e64 v21, v2, v67, s[38:39]
	v_fmac_f32_e32 v49, v61, v48
	v_mul_f32_e32 v61, v61, v60
	v_cndmask_b32_e64 v22, v67, v2, s[38:39]
	v_fmac_f32_e32 v31, 0, v21
	v_mul_f32_e32 v74, v67, v2
	v_fmac_f32_e32 v73, v22, v31
	s_waitcnt lgkmcnt(1)
	v_cndmask_b32_e64 v21, v20, v63, s[38:39]
	s_waitcnt lgkmcnt(0)
	v_cndmask_b32_e64 v75, v23, v55, s[38:39]
	v_cndmask_b32_e64 v76, v55, v23, s[38:39]
	ds_bpermute_b32 v22, v197, v61
	ds_bpermute_b32 v23, v197, v49
	v_cndmask_b32_e64 v20, v63, v20, s[38:39]
	v_mul_f32_e32 v77, v74, v21
	v_fmac_f32_e32 v75, v21, v73
	v_mul_f32_e32 v78, v20, v77
	v_fmac_f32_e32 v76, v20, v75
	ds_bpermute_b32 v21, v197, v65
	ds_bpermute_b32 v20, v197, v43
	s_waitcnt lgkmcnt(3)
	v_cndmask_b32_e64 v82, v22, v61, s[38:39]
	s_waitcnt lgkmcnt(2)
	v_cndmask_b32_e64 v79, v23, v49, s[38:39]
	v_cndmask_b32_e64 v22, v61, v22, s[38:39]
	v_cndmask_b32_e64 v80, v49, v23, s[38:39]
	v_mul_f32_e32 v81, v78, v82
	v_fmac_f32_e32 v79, v82, v76
	v_mul_f32_e32 v82, v22, v81
	v_fmac_f32_e32 v80, v22, v79
	s_waitcnt lgkmcnt(1)
	v_cndmask_b32_e64 v22, v21, v65, s[38:39]
	s_waitcnt lgkmcnt(0)
	v_cndmask_b32_e64 v83, v20, v43, s[38:39]
	v_mul_f32_e32 v84, v82, v22
	v_fmac_f32_e32 v83, v22, v80
	s_and_saveexec_b64 s[30:31], s[38:39]
	v_mul_f32_e32 v23, v83, v21
	v_mul_f32_e32 v22, v84, v21
	v_add_f32_e32 v23, v23, v20
	ds_write_b64 v71, v[22:23]
	s_or_b64 exec, exec, s[30:31]
	s_waitcnt lgkmcnt(0)
	s_barrier
	ds_read_b32 v23, v69
	v_cndmask_b32_e64 v20, 0, 1, s[22:23]
	v_cmp_ne_u32_e64 s[40:41], 1, v20
	s_andn2_b64 vcc, exec, s[22:23]
	s_cbranch_vccnz .LBB0_791
	s_add_i32 s0, s62, -1
	s_cmp_lt_u32 s0, 7
	s_mov_b32 s0, 0
	s_cbranch_scc1 .LBB0_788
	v_readlane_b32 s9, v254, 35
	s_add_i32 s9, s9, 0
	s_add_i32 s9, s9, 0x111c0
	s_and_b32 s0, s62, 0x7ffffff8
	v_lshl_add_u32 v85, v68, 3, s9
	s_mov_b32 s9, 0

.LBB0_791:
	v_cndmask_b32_e64 v21, v2, 1.0, s[38:39]
	v_cndmask_b32_e64 v2, v31, 0, s[38:39]
	s_waitcnt lgkmcnt(0)
	v_fmac_f32_e32 v2, v21, v23
	v_cndmask_b32_e64 v31, v77, v74, s[38:39]
	v_cndmask_b32_e64 v20, v75, v73, s[38:39]
	v_pk_fma_f32 v[52:53], v[52:53], v[2:3], v[56:57] op_sel_hi:[1,0,1]
	v_pk_fma_f32 v[56:57], v[66:67], v[2:3], v[58:59] op_sel_hi:[1,0,1]
	v_fmac_f32_e32 v20, v31, v23
	v_cvt_pk_bf16_f32 v2, v52, v53
	v_cndmask_b32_e64 v73, v81, v78, s[38:39]
	v_cndmask_b32_e64 v22, v79, v76, s[38:39]
	v_pk_fma_f32 v[46:47], v[46:47], v[20:21], v[50:51] op_sel_hi:[1,0,1]
	ds_write_b16 v72, v2
	ds_write_b16_d16_hi v72, v2 offset:144
	v_cvt_pk_bf16_f32 v2, v56, v57
	v_pk_fma_f32 v[50:51], v[62:63], v[20:21], v[54:55] op_sel_hi:[1,0,1]
	v_fmac_f32_e32 v22, v73, v23
	ds_write_b16 v72, v2 offset:288
	ds_write_b16_d16_hi v72, v2 offset:432
	v_cvt_pk_bf16_f32 v2, v46, v47
	v_cndmask_b32_e64 v75, v84, v82, s[38:39]
	v_cndmask_b32_e64 v74, v83, v80, s[38:39]
	v_pk_fma_f32 v[40:41], v[40:41], v[22:23], v[44:45] op_sel_hi:[1,0,1]
	ds_write_b16 v72, v2 offset:1152
	ds_write_b16_d16_hi v72, v2 offset:1296
	v_cvt_pk_bf16_f32 v2, v50, v51
	v_pk_fma_f32 v[44:45], v[60:61], v[22:23], v[48:49] op_sel_hi:[1,0,1]
	v_fmac_f32_e32 v74, v75, v23
	ds_write_b16 v72, v2 offset:1440
	ds_write_b16_d16_hi v72, v2 offset:1584
	v_cvt_pk_bf16_f32 v2, v40, v41
	v_pk_fma_f32 v[22:23], v[36:37], v[74:75], v[38:39] op_sel_hi:[1,0,1]
	ds_write_b16 v72, v2 offset:2304
	ds_write_b16_d16_hi v72, v2 offset:2448
	v_cvt_pk_bf16_f32 v2, v44, v45
	v_pk_fma_f32 v[20:21], v[64:65], v[74:75], v[42:43] op_sel_hi:[1,0,1]
	ds_write_b16 v72, v2 offset:2592
	ds_write_b16_d16_hi v72, v2 offset:2736
	v_cvt_pk_bf16_f32 v2, v22, v23
	ds_write_b16 v72, v2 offset:3456
	ds_write_b16_d16_hi v72, v2 offset:3600
	v_cvt_pk_bf16_f32 v2, v20, v21
	ds_write_b16 v72, v2 offset:3744
	ds_write_b16_d16_hi v72, v2 offset:3888
	s_waitcnt lgkmcnt(0)
	s_barrier
	s_and_saveexec_b64 s[22:23], s[2:3]
	ds_write_b32 v69, v21
	s_or_b64 exec, exec, s[22:23]
	ds_read_b128 v[36:39], v70
	v_mad_u64_u32 v[20:21], s[22:23], v32, s5, v[24:25]
	v_mad_i32_i24 v21, v33, s5, v21
	s_waitcnt vmcnt(21)
	v_lshlrev_b32_e32 v32, 16, v12
	s_waitcnt lgkmcnt(0)
	v_lshlrev_b32_e32 v22, 16, v36
	v_and_b32_e32 v23, 0xffff0000, v36
	v_and_b32_e32 v33, 0xffff0000, v12
	v_pk_mul_f32 v[22:23], v[32:33], v[22:23]
	v_lshlrev_b32_e32 v32, 16, v13
	v_cvt_pk_bf16_f32 v12, v22, v23
	v_lshlrev_b32_e32 v22, 16, v37
	v_and_b32_e32 v23, 0xffff0000, v37
	v_and_b32_e32 v33, 0xffff0000, v13
	v_pk_mul_f32 v[22:23], v[32:33], v[22:23]
	v_lshlrev_b32_e32 v32, 16, v14
	v_cvt_pk_bf16_f32 v13, v22, v23
	v_lshlrev_b32_e32 v22, 16, v38
	v_and_b32_e32 v23, 0xffff0000, v38
	v_and_b32_e32 v33, 0xffff0000, v14
	v_pk_mul_f32 v[22:23], v[32:33], v[22:23]
	v_lshlrev_b32_e32 v32, 16, v15
	v_cvt_pk_bf16_f32 v14, v22, v23
	v_lshlrev_b32_e32 v22, 16, v39
	v_and_b32_e32 v23, 0xffff0000, v39
	v_and_b32_e32 v33, 0xffff0000, v15
	v_pk_mul_f32 v[22:23], v[32:33], v[22:23]
	s_waitcnt vmcnt(20)
	v_lshlrev_b32_e32 v32, 16, v4
	v_cvt_pk_bf16_f32 v15, v22, v23
	global_store_dwordx4 v[20:21], v[12:15], off sc1
	ds_read_b128 v[12:15], v70 offset:9216
	v_and_b32_e32 v33, 0xffff0000, v4
	s_mov_b32 s0, 0x30000
	v_readlane_b32 s22, v253, 9
	v_readlane_b32 s23, v253, 10
	s_waitcnt lgkmcnt(0)
	v_lshlrev_b32_e32 v22, 16, v12
	v_and_b32_e32 v23, 0xffff0000, v12
	v_pk_mul_f32 v[22:23], v[32:33], v[22:23]
	v_lshlrev_b32_e32 v12, 16, v13
	v_cvt_pk_bf16_f32 v4, v22, v23
	v_and_b32_e32 v13, 0xffff0000, v13
	v_lshlrev_b32_e32 v22, 16, v5
	v_and_b32_e32 v23, 0xffff0000, v5
	v_pk_mul_f32 v[12:13], v[22:23], v[12:13]
	v_lshlrev_b32_e32 v22, 16, v6
	v_cvt_pk_bf16_f32 v5, v12, v13
	v_lshlrev_b32_e32 v12, 16, v14
	v_and_b32_e32 v13, 0xffff0000, v14
	v_and_b32_e32 v23, 0xffff0000, v6
	v_pk_mul_f32 v[12:13], v[22:23], v[12:13]
	v_lshlrev_b32_e32 v14, 16, v7
	v_cvt_pk_bf16_f32 v6, v12, v13
	v_lshlrev_b32_e32 v12, 16, v15
	v_and_b32_e32 v13, 0xffff0000, v15
	v_and_b32_e32 v15, 0xffff0000, v7
	v_pk_mul_f32 v[12:13], v[14:15], v[12:13]
	s_or_b32 s22, s22, 0x180
	v_cvt_pk_bf16_f32 v7, v12, v13
	v_add_co_u32_e32 v12, vcc, s0, v20
	s_mov_b32 s23, s25
	s_nop 0
	v_addc_co_u32_e32 v13, vcc, 0, v21, vcc
	global_store_dwordx4 v[12:13], v[4:7], off sc1
	v_lshl_add_u64 v[32:33], v[28:29], 0, s[22:23]
	v_mov_b32_e32 v31, v3
	v_add_co_u32_e32 v4, vcc, s7, v26
	s_nop 1
	v_addc_co_u32_e32 v5, vcc, 0, v27, vcc
	global_load_dword v108, v[4:5], off nt
	global_load_dword v106, v[4:5], off offset:256 nt
	global_load_dword v104, v[4:5], off offset:512 nt
	global_load_dword v102, v[4:5], off offset:768 nt
	global_load_dword v100, v[4:5], off offset:1024 nt
	global_load_dword v98, v[4:5], off offset:1280 nt
	global_load_dword v96, v[4:5], off offset:1536 nt
	global_load_dword v94, v[4:5], off offset:1792 nt
	global_load_dword v86, v[4:5], off offset:2048 nt
	global_load_dword v84, v[4:5], off offset:2304 nt
	global_load_dword v82, v[4:5], off offset:2560 nt
	global_load_dword v80, v[4:5], off offset:2816 nt
	global_load_dword v78, v[4:5], off offset:3072 nt
	global_load_dword v76, v[4:5], off offset:3328 nt
	global_load_dword v74, v[4:5], off offset:3584 nt
	global_load_dword v2, v[4:5], off offset:3840 nt
	v_mov_b64_e32 v[4:5], s[54:55]
	v_mad_u64_u32 v[4:5], s[22:23], v32, s16, v[4:5]
	v_mad_i32_i24 v5, v33, s16, v5
	v_lshl_add_u64 v[4:5], v[4:5], 0, s[24:25]
	v_lshl_add_u64 v[4:5], v[4:5], 0, v[30:31]
	global_load_dwordx4 v[12:15], v[4:5], off offset:2048
	v_add_co_u32_e32 v4, vcc, s14, v4
	s_nop 1
	v_addc_co_u32_e32 v5, vcc, 0, v5, vcc
	global_load_dwordx4 v[4:7], v[4:5], off offset:2048
	s_waitcnt vmcnt(37)
	v_lshlrev_b32_e32 v20, 16, v110
	v_exp_f32_e32 v52, v20
	s_waitcnt vmcnt(36)
	v_lshlrev_b32_e32 v20, 16, v109
	s_waitcnt vmcnt(30)
	v_lshlrev_b32_e32 v36, 16, v97
	v_exp_f32_e32 v20, v20
	v_lshlrev_b32_e32 v21, 16, v107
	v_exp_f32_e32 v37, v36
	s_waitcnt vmcnt(29)
	v_lshlrev_b32_e32 v36, 16, v95
	v_exp_f32_e32 v21, v21
	v_lshlrev_b32_e32 v22, 16, v105
	v_exp_f32_e32 v40, v36
	s_waitcnt vmcnt(28)
	v_lshlrev_b32_e32 v36, 16, v93
	v_and_b32_e32 v56, 0xffff0000, v110
	v_exp_f32_e32 v22, v22
	v_lshlrev_b32_e32 v23, 16, v103
	v_exp_f32_e32 v41, v36
	s_waitcnt vmcnt(27)
	v_lshlrev_b32_e32 v36, 16, v92
	v_and_b32_e32 v57, 0xffff0000, v109
	v_exp_f32_e32 v46, v23
	v_lshlrev_b32_e32 v23, 16, v101
	v_exp_f32_e32 v60, v36
	s_waitcnt vmcnt(26)
	v_lshlrev_b32_e32 v36, 16, v91
	v_fmac_f32_e32 v56, 0, v52
	v_and_b32_e32 v58, 0xffff0000, v107
	v_exp_f32_e32 v23, v23
	v_lshlrev_b32_e32 v31, 16, v99
	v_exp_f32_e32 v61, v36
	s_waitcnt vmcnt(25)
	v_lshlrev_b32_e32 v36, 16, v90
	v_fmac_f32_e32 v57, v20, v56
	v_and_b32_e32 v59, 0xffff0000, v105
	v_exp_f32_e32 v31, v31
	v_exp_f32_e32 v36, v36
	s_waitcnt vmcnt(24)
	v_lshlrev_b32_e32 v39, 16, v89
	v_fmac_f32_e32 v58, v21, v57
	v_and_b32_e32 v50, 0xffff0000, v103
	v_exp_f32_e32 v64, v39
	s_waitcnt vmcnt(23)
	v_lshlrev_b32_e32 v42, 16, v88
	v_fmac_f32_e32 v59, v22, v58
	v_and_b32_e32 v51, 0xffff0000, v101
	v_exp_f32_e32 v65, v42
	s_waitcnt vmcnt(22)
	v_lshlrev_b32_e32 v43, 16, v87
	v_mul_f32_e32 v53, v52, v20
	v_fmac_f32_e32 v50, 0, v46
	ds_bpermute_b32 v20, v197, v59
	v_and_b32_e32 v54, 0xffff0000, v99
	v_and_b32_e32 v38, 0xffff0000, v90
	v_exp_f32_e32 v73, v43
	v_mul_f32_e32 v66, v21, v53
	v_fmac_f32_e32 v51, v23, v50
	v_mul_f32_e32 v47, v46, v23
	v_and_b32_e32 v55, 0xffff0000, v97
	v_and_b32_e32 v39, 0xffff0000, v89
	v_mul_f32_e32 v67, v22, v66
	v_fmac_f32_e32 v54, v31, v51
	v_mul_f32_e32 v62, v31, v47
	v_fmac_f32_e32 v38, 0, v36
	v_and_b32_e32 v42, 0xffff0000, v88
	v_fmac_f32_e32 v55, v37, v54
	v_mul_f32_e32 v63, v37, v62
	v_fmac_f32_e32 v39, v64, v38
	v_mul_f32_e32 v37, v36, v64
	ds_bpermute_b32 v31, v197, v67
	v_and_b32_e32 v43, 0xffff0000, v87
	v_fmac_f32_e32 v42, v65, v39
	v_mul_f32_e32 v64, v65, v37
	v_and_b32_e32 v44, 0xffff0000, v95
	v_fmac_f32_e32 v43, v73, v42
	v_mul_f32_e32 v65, v73, v64
	s_waitcnt lgkmcnt(1)
	v_cndmask_b32_e64 v73, v20, v59, s[38:39]
	v_cndmask_b32_e64 v75, v59, v20, s[38:39]
	ds_bpermute_b32 v20, v197, v63
	ds_bpermute_b32 v23, v197, v55
	v_and_b32_e32 v45, 0xffff0000, v93
	v_fmac_f32_e32 v44, 0, v40
	v_and_b32_e32 v48, 0xffff0000, v92
	v_fmac_f32_e32 v45, v41, v44
	v_mul_f32_e32 v41, v40, v41
	v_and_b32_e32 v49, 0xffff0000, v91
	v_fmac_f32_e32 v48, v60, v45
	v_mul_f32_e32 v60, v60, v41
	s_waitcnt lgkmcnt(2)
	v_cndmask_b32_e64 v21, v31, v67, s[38:39]
	v_fmac_f32_e32 v49, v61, v48
	v_mul_f32_e32 v61, v61, v60
	v_cndmask_b32_e64 v22, v67, v31, s[38:39]
	v_fmac_f32_e32 v73, 0, v21
	v_mul_f32_e32 v77, v67, v31
	v_fmac_f32_e32 v75, v22, v73
	s_waitcnt lgkmcnt(1)
	v_cndmask_b32_e64 v21, v20, v63, s[38:39]
	s_waitcnt lgkmcnt(0)
	v_cndmask_b32_e64 v79, v23, v55, s[38:39]
	v_cndmask_b32_e64 v81, v55, v23, s[38:39]
	ds_bpermute_b32 v22, v197, v61
	ds_bpermute_b32 v23, v197, v49
	v_cndmask_b32_e64 v20, v63, v20, s[38:39]
	v_mul_f32_e32 v83, v77, v21
	v_fmac_f32_e32 v79, v21, v75
	v_mul_f32_e32 v85, v20, v83
	v_fmac_f32_e32 v81, v20, v79
	ds_bpermute_b32 v21, v197, v65
	ds_bpermute_b32 v20, v197, v43
	s_waitcnt lgkmcnt(3)
	v_cndmask_b32_e64 v90, v22, v61, s[38:39]
	s_waitcnt lgkmcnt(2)
	v_cndmask_b32_e64 v87, v23, v49, s[38:39]
	v_cndmask_b32_e64 v22, v61, v22, s[38:39]
	v_cndmask_b32_e64 v88, v49, v23, s[38:39]
	v_mul_f32_e32 v89, v85, v90
	v_fmac_f32_e32 v87, v90, v81
	v_mul_f32_e32 v90, v22, v89
	v_fmac_f32_e32 v88, v22, v87
	s_waitcnt lgkmcnt(1)
	v_cndmask_b32_e64 v22, v21, v65, s[38:39]
	s_waitcnt lgkmcnt(0)
	v_cndmask_b32_e64 v91, v20, v43, s[38:39]
	v_mul_f32_e32 v92, v90, v22
	v_fmac_f32_e32 v91, v22, v88
	s_and_saveexec_b64 s[22:23], s[38:39]
	v_mul_f32_e32 v23, v91, v21
	v_mul_f32_e32 v22, v92, v21
	v_add_f32_e32 v23, v23, v20
	ds_write_b64 v71, v[22:23]
	s_or_b64 exec, exec, s[22:23]
	s_waitcnt lgkmcnt(0)
	s_barrier
	ds_read_b32 v23, v69
	s_and_b64 vcc, exec, s[40:41]
	s_cbranch_vccnz .LBB0_802
	s_add_i32 s0, s62, -1
	s_cmp_lt_u32 s0, 7
	s_mov_b32 s0, 0
	s_cbranch_scc1 .LBB0_799
	v_readlane_b32 s9, v254, 35
	s_add_i32 s9, s9, 0
	s_add_i32 s9, s9, 0x111c0
	s_and_b32 s0, s62, 0x7ffffff8
	v_lshl_add_u32 v93, v68, 3, s9
	s_mov_b32 s9, 0

.LBB0_802:
	v_cndmask_b32_e64 v21, v31, 1.0, s[38:39]
	v_cndmask_b32_e64 v20, v73, 0, s[38:39]
	s_waitcnt lgkmcnt(0)
	v_fmac_f32_e32 v20, v21, v23
	v_cndmask_b32_e64 v31, v83, v77, s[38:39]
	v_cndmask_b32_e64 v22, v79, v75, s[38:39]
	v_pk_fma_f32 v[52:53], v[52:53], v[20:21], v[56:57] op_sel_hi:[1,0,1]
	v_pk_fma_f32 v[56:57], v[66:67], v[20:21], v[58:59] op_sel_hi:[1,0,1]
	v_fmac_f32_e32 v22, v31, v23
	v_cvt_pk_bf16_f32 v31, v52, v53
	v_cndmask_b32_e64 v73, v89, v85, s[38:39]
	v_cndmask_b32_e64 v110, v87, v81, s[38:39]
	v_pk_fma_f32 v[46:47], v[46:47], v[22:23], v[50:51] op_sel_hi:[1,0,1]
	ds_write_b16 v72, v31
	ds_write_b16_d16_hi v72, v31 offset:144
	v_cvt_pk_bf16_f32 v31, v56, v57
	v_cndmask_b32_e64 v75, v92, v90, s[38:39]
	v_cndmask_b32_e64 v88, v91, v88, s[38:39]
	v_pk_fma_f32 v[50:51], v[62:63], v[22:23], v[54:55] op_sel_hi:[1,0,1]
	v_fmac_f32_e32 v110, v73, v23
	ds_write_b16 v72, v31 offset:288
	ds_write_b16_d16_hi v72, v31 offset:432
	v_cvt_pk_bf16_f32 v31, v46, v47
	v_pk_fma_f32 v[40:41], v[40:41], v[110:111], v[44:45] op_sel_hi:[1,0,1]
	v_fmac_f32_e32 v88, v75, v23
	ds_write_b16 v72, v31 offset:1152
	ds_write_b16_d16_hi v72, v31 offset:1296
	v_cvt_pk_bf16_f32 v31, v50, v51
	v_pk_fma_f32 v[44:45], v[60:61], v[110:111], v[48:49] op_sel_hi:[1,0,1]
	v_pk_fma_f32 v[22:23], v[36:37], v[88:89], v[38:39] op_sel_hi:[1,0,1]
	v_pk_fma_f32 v[20:21], v[64:65], v[88:89], v[42:43] op_sel_hi:[1,0,1]
	ds_write_b16 v72, v31 offset:1440
	ds_write_b16_d16_hi v72, v31 offset:1584
	v_cvt_pk_bf16_f32 v31, v40, v41
	ds_write_b16 v72, v31 offset:2304
	ds_write_b16_d16_hi v72, v31 offset:2448
	v_cvt_pk_bf16_f32 v31, v44, v45
	v_cvt_pk_bf16_f32 v22, v22, v23
	v_cvt_pk_bf16_f32 v20, v20, v21
	ds_write_b16 v72, v31 offset:2592
	ds_write_b16_d16_hi v72, v31 offset:2736
	ds_write_b16 v72, v22 offset:3456
	ds_write_b16_d16_hi v72, v22 offset:3600
	ds_write_b16 v72, v20 offset:3744
	ds_write_b16_d16_hi v72, v20 offset:3888
	s_waitcnt lgkmcnt(0)
	s_barrier
	s_and_saveexec_b64 s[22:23], s[2:3]
	ds_write_b32 v69, v21
	s_or_b64 exec, exec, s[22:23]
	v_mad_u64_u32 v[20:21], s[22:23], v34, s5, v[24:25]
	v_mad_i32_i24 v21, v35, s5, v21
	ds_read_b128 v[34:37], v70
	s_waitcnt vmcnt(21)
	v_lshlrev_b32_e32 v38, 16, v16
	v_and_b32_e32 v39, 0xffff0000, v16
	s_mov_b32 s0, 0x30000
	v_readlane_b32 s22, v253, 9
	s_waitcnt lgkmcnt(0)
	v_lshlrev_b32_e32 v22, 16, v34
	v_and_b32_e32 v23, 0xffff0000, v34
	v_pk_mul_f32 v[22:23], v[38:39], v[22:23]
	v_lshlrev_b32_e32 v34, 16, v17
	v_cvt_pk_bf16_f32 v16, v22, v23
	v_lshlrev_b32_e32 v22, 16, v35
	v_and_b32_e32 v23, 0xffff0000, v35
	v_and_b32_e32 v35, 0xffff0000, v17
	v_pk_mul_f32 v[22:23], v[34:35], v[22:23]
	v_lshlrev_b32_e32 v34, 16, v18
	v_cvt_pk_bf16_f32 v17, v22, v23
	v_lshlrev_b32_e32 v22, 16, v36
	v_and_b32_e32 v23, 0xffff0000, v36
	v_and_b32_e32 v35, 0xffff0000, v18
	v_pk_mul_f32 v[22:23], v[34:35], v[22:23]
	v_lshlrev_b32_e32 v34, 16, v19
	v_cvt_pk_bf16_f32 v18, v22, v23
	v_lshlrev_b32_e32 v22, 16, v37
	v_and_b32_e32 v23, 0xffff0000, v37
	v_and_b32_e32 v35, 0xffff0000, v19
	v_pk_mul_f32 v[22:23], v[34:35], v[22:23]
	s_waitcnt vmcnt(20)
	v_lshlrev_b32_e32 v34, 16, v8
	v_cvt_pk_bf16_f32 v19, v22, v23
	global_store_dwordx4 v[20:21], v[16:19], off sc1
	ds_read_b128 v[16:19], v70 offset:9216
	v_and_b32_e32 v35, 0xffff0000, v8
	v_readlane_b32 s23, v253, 10
	s_bitset1_b32 s22, 9
	s_mov_b32 s23, s25
	s_waitcnt lgkmcnt(0)
	v_lshlrev_b32_e32 v22, 16, v16
	v_and_b32_e32 v23, 0xffff0000, v16
	v_pk_mul_f32 v[22:23], v[34:35], v[22:23]
	v_lshlrev_b32_e32 v16, 16, v17
	v_cvt_pk_bf16_f32 v8, v22, v23
	v_and_b32_e32 v17, 0xffff0000, v17
	v_lshlrev_b32_e32 v22, 16, v9
	v_and_b32_e32 v23, 0xffff0000, v9
	v_pk_mul_f32 v[16:17], v[22:23], v[16:17]
	v_lshlrev_b32_e32 v22, 16, v10
	v_cvt_pk_bf16_f32 v9, v16, v17
	v_lshlrev_b32_e32 v16, 16, v18
	v_and_b32_e32 v17, 0xffff0000, v18
	v_and_b32_e32 v23, 0xffff0000, v10
	v_pk_mul_f32 v[16:17], v[22:23], v[16:17]
	v_lshlrev_b32_e32 v18, 16, v11
	v_cvt_pk_bf16_f32 v10, v16, v17
	v_lshlrev_b32_e32 v16, 16, v19
	v_and_b32_e32 v17, 0xffff0000, v19
	v_and_b32_e32 v19, 0xffff0000, v11
	v_pk_mul_f32 v[16:17], v[18:19], v[16:17]
	v_lshl_add_u64 v[34:35], v[28:29], 0, s[22:23]
	v_cvt_pk_bf16_f32 v11, v16, v17
	v_add_co_u32_e32 v16, vcc, s0, v20
	s_mov_b32 s0, 0x20000
	s_nop 0
	v_addc_co_u32_e32 v17, vcc, 0, v21, vcc
	global_store_dwordx4 v[16:17], v[8:11], off sc1
	v_mov_b32_e32 v31, v3
	s_nop 0
	v_add_co_u32_e32 v8, vcc, s0, v26
	s_nop 1
	v_addc_co_u32_e32 v9, vcc, 0, v27, vcc
	global_load_dword v103, v[8:9], off nt
	global_load_dword v101, v[8:9], off offset:256 nt
	global_load_dword v99, v[8:9], off offset:512 nt
	global_load_dword v97, v[8:9], off offset:768 nt
	global_load_dword v95, v[8:9], off offset:1024 nt
	global_load_dword v92, v[8:9], off offset:1280 nt
	global_load_dword v90, v[8:9], off offset:1536 nt
	global_load_dword v88, v[8:9], off offset:1792 nt
	global_load_dword v87, v[8:9], off offset:2048 nt
	global_load_dword v85, v[8:9], off offset:2304 nt
	global_load_dword v83, v[8:9], off offset:2560 nt
	global_load_dword v81, v[8:9], off offset:2816 nt
	global_load_dword v79, v[8:9], off offset:3072 nt
	global_load_dword v77, v[8:9], off offset:3328 nt
	global_load_dword v75, v[8:9], off offset:3584 nt
	global_load_dword v73, v[8:9], off offset:3840 nt
	v_mov_b64_e32 v[8:9], s[54:55]
	v_mad_u64_u32 v[8:9], s[22:23], v34, s16, v[8:9]
	v_mad_i32_i24 v9, v35, s16, v9
	v_lshl_add_u64 v[8:9], v[8:9], 0, s[24:25]
	v_lshl_add_u64 v[8:9], v[8:9], 0, v[30:31]
	global_load_dwordx4 v[16:19], v[8:9], off offset:2048
	v_add_co_u32_e32 v8, vcc, s14, v8
	s_nop 1
	v_addc_co_u32_e32 v9, vcc, 0, v9, vcc
	global_load_dwordx4 v[8:11], v[8:9], off offset:2048
	s_waitcnt vmcnt(37)
	v_lshlrev_b32_e32 v20, 16, v108
	v_exp_f32_e32 v52, v20
	s_waitcnt vmcnt(36)
	v_lshlrev_b32_e32 v20, 16, v106
	s_waitcnt vmcnt(30)
	v_lshlrev_b32_e32 v36, 16, v94
	v_exp_f32_e32 v20, v20
	v_lshlrev_b32_e32 v21, 16, v104
	v_exp_f32_e32 v37, v36
	s_waitcnt vmcnt(29)
	v_lshlrev_b32_e32 v36, 16, v86
	v_exp_f32_e32 v21, v21
	v_lshlrev_b32_e32 v22, 16, v102
	v_exp_f32_e32 v40, v36
	s_waitcnt vmcnt(28)
	v_lshlrev_b32_e32 v36, 16, v84
	v_and_b32_e32 v56, 0xffff0000, v108
	v_exp_f32_e32 v22, v22
	v_lshlrev_b32_e32 v23, 16, v100
	v_exp_f32_e32 v41, v36
	s_waitcnt vmcnt(27)
	v_lshlrev_b32_e32 v36, 16, v82
	v_and_b32_e32 v57, 0xffff0000, v106
	v_exp_f32_e32 v46, v23
	v_lshlrev_b32_e32 v23, 16, v98
	v_exp_f32_e32 v60, v36
	s_waitcnt vmcnt(26)
	v_lshlrev_b32_e32 v36, 16, v80
	v_fmac_f32_e32 v56, 0, v52
	v_and_b32_e32 v58, 0xffff0000, v104
	v_exp_f32_e32 v23, v23
	v_lshlrev_b32_e32 v31, 16, v96
	v_exp_f32_e32 v61, v36
	s_waitcnt vmcnt(25)
	v_lshlrev_b32_e32 v36, 16, v78
	v_fmac_f32_e32 v57, v20, v56
	v_and_b32_e32 v59, 0xffff0000, v102
	v_exp_f32_e32 v31, v31
	v_exp_f32_e32 v36, v36
	s_waitcnt vmcnt(24)
	v_lshlrev_b32_e32 v39, 16, v76
	v_fmac_f32_e32 v58, v21, v57
	v_and_b32_e32 v50, 0xffff0000, v100
	v_exp_f32_e32 v64, v39
	s_waitcnt vmcnt(23)
	v_lshlrev_b32_e32 v42, 16, v74
	v_fmac_f32_e32 v59, v22, v58
	v_and_b32_e32 v51, 0xffff0000, v98
	v_exp_f32_e32 v65, v42
	s_waitcnt vmcnt(22)
	v_lshlrev_b32_e32 v43, 16, v2
	v_mul_f32_e32 v53, v52, v20
	v_fmac_f32_e32 v50, 0, v46
	ds_bpermute_b32 v20, v197, v59
	v_and_b32_e32 v54, 0xffff0000, v96
	v_and_b32_e32 v38, 0xffff0000, v78
	v_and_b32_e32 v42, 0xffff0000, v74
	v_exp_f32_e32 v74, v43
	v_mul_f32_e32 v66, v21, v53
	v_fmac_f32_e32 v51, v23, v50
	v_mul_f32_e32 v47, v46, v23
	v_and_b32_e32 v55, 0xffff0000, v94
	v_and_b32_e32 v39, 0xffff0000, v76
	v_mul_f32_e32 v67, v22, v66
	v_fmac_f32_e32 v54, v31, v51
	v_mul_f32_e32 v62, v31, v47
	v_fmac_f32_e32 v38, 0, v36
	v_and_b32_e32 v43, 0xffff0000, v2
	v_fmac_f32_e32 v55, v37, v54
	v_mul_f32_e32 v63, v37, v62
	v_fmac_f32_e32 v39, v64, v38
	v_mul_f32_e32 v37, v36, v64
	ds_bpermute_b32 v2, v197, v67
	v_fmac_f32_e32 v42, v65, v39
	v_mul_f32_e32 v64, v65, v37
	v_and_b32_e32 v44, 0xffff0000, v86
	v_fmac_f32_e32 v43, v74, v42
	v_mul_f32_e32 v65, v74, v64
	s_waitcnt lgkmcnt(1)
	v_cndmask_b32_e64 v31, v20, v59, s[38:39]
	v_cndmask_b32_e64 v74, v59, v20, s[38:39]
	ds_bpermute_b32 v20, v197, v63
	ds_bpermute_b32 v23, v197, v55
	v_and_b32_e32 v45, 0xffff0000, v84
	v_fmac_f32_e32 v44, 0, v40
	v_and_b32_e32 v48, 0xffff0000, v82
	v_fmac_f32_e32 v45, v41, v44
	v_mul_f32_e32 v41, v40, v41
	v_and_b32_e32 v49, 0xffff0000, v80
	v_fmac_f32_e32 v48, v60, v45
	v_mul_f32_e32 v60, v60, v41
	s_waitcnt lgkmcnt(2)
	v_cndmask_b32_e64 v21, v2, v67, s[38:39]
	v_fmac_f32_e32 v49, v61, v48
	v_mul_f32_e32 v61, v61, v60
	v_cndmask_b32_e64 v22, v67, v2, s[38:39]
	v_fmac_f32_e32 v31, 0, v21
	v_mul_f32_e32 v76, v67, v2
	v_fmac_f32_e32 v74, v22, v31
	s_waitcnt lgkmcnt(1)
	v_cndmask_b32_e64 v21, v20, v63, s[38:39]
	s_waitcnt lgkmcnt(0)
	v_cndmask_b32_e64 v78, v23, v55, s[38:39]
	v_cndmask_b32_e64 v80, v55, v23, s[38:39]
	ds_bpermute_b32 v22, v197, v61
	ds_bpermute_b32 v23, v197, v49
	v_cndmask_b32_e64 v20, v63, v20, s[38:39]
	v_mul_f32_e32 v82, v76, v21
	v_fmac_f32_e32 v78, v21, v74
	v_mul_f32_e32 v84, v20, v82
	v_fmac_f32_e32 v80, v20, v78
	ds_bpermute_b32 v21, v197, v65
	ds_bpermute_b32 v20, v197, v43
	s_waitcnt lgkmcnt(3)
	v_cndmask_b32_e64 v93, v22, v61, s[38:39]
	s_waitcnt lgkmcnt(2)
	v_cndmask_b32_e64 v86, v23, v49, s[38:39]
	v_cndmask_b32_e64 v22, v61, v22, s[38:39]
	v_cndmask_b32_e64 v89, v49, v23, s[38:39]
	v_mul_f32_e32 v91, v84, v93
	v_fmac_f32_e32 v86, v93, v80
	v_mul_f32_e32 v93, v22, v91
	v_fmac_f32_e32 v89, v22, v86
	s_waitcnt lgkmcnt(1)
	v_cndmask_b32_e64 v22, v21, v65, s[38:39]
	s_waitcnt lgkmcnt(0)
	v_cndmask_b32_e64 v94, v20, v43, s[38:39]
	v_mul_f32_e32 v96, v93, v22
	v_fmac_f32_e32 v94, v22, v89
	s_and_saveexec_b64 s[22:23], s[38:39]
	v_mul_f32_e32 v23, v94, v21
	v_mul_f32_e32 v22, v96, v21
	v_add_f32_e32 v23, v23, v20
	ds_write_b64 v71, v[22:23]
	s_or_b64 exec, exec, s[22:23]
	s_waitcnt lgkmcnt(0)
	s_barrier
	ds_read_b32 v23, v69
	s_and_b64 vcc, exec, s[40:41]
	s_cbranch_vccnz .LBB0_813
	s_add_i32 s0, s62, -1
	s_cmp_lt_u32 s0, 7
	s_mov_b32 s0, 0
	s_cbranch_scc1 .LBB0_810
	v_readlane_b32 s9, v254, 35
	s_add_i32 s9, s9, 0
	s_add_i32 s9, s9, 0x111c0
	s_and_b32 s0, s62, 0x7ffffff8
	v_lshl_add_u32 v98, v68, 3, s9
	s_mov_b32 s9, 0

.LBB0_813:
	v_cndmask_b32_e64 v21, v2, 1.0, s[38:39]
	v_cndmask_b32_e64 v2, v31, 0, s[38:39]
	s_waitcnt lgkmcnt(0)
	v_fmac_f32_e32 v2, v21, v23
	v_cndmask_b32_e64 v31, v82, v76, s[38:39]
	v_cndmask_b32_e64 v20, v78, v74, s[38:39]
	v_pk_fma_f32 v[52:53], v[52:53], v[2:3], v[56:57] op_sel_hi:[1,0,1]
	v_pk_fma_f32 v[56:57], v[66:67], v[2:3], v[58:59] op_sel_hi:[1,0,1]
	v_fmac_f32_e32 v20, v31, v23
	v_cvt_pk_bf16_f32 v2, v52, v53
	v_cndmask_b32_e64 v76, v91, v84, s[38:39]
	v_cndmask_b32_e64 v22, v86, v80, s[38:39]
	v_pk_fma_f32 v[46:47], v[46:47], v[20:21], v[50:51] op_sel_hi:[1,0,1]
	ds_write_b16 v72, v2
	ds_write_b16_d16_hi v72, v2 offset:144
	v_cvt_pk_bf16_f32 v2, v56, v57
	v_pk_fma_f32 v[50:51], v[62:63], v[20:21], v[54:55] op_sel_hi:[1,0,1]
	v_fmac_f32_e32 v22, v76, v23
	ds_write_b16 v72, v2 offset:288
	ds_write_b16_d16_hi v72, v2 offset:432
	v_cvt_pk_bf16_f32 v2, v46, v47
	v_cndmask_b32_e64 v78, v96, v93, s[38:39]
	v_cndmask_b32_e64 v74, v94, v89, s[38:39]
	v_pk_fma_f32 v[40:41], v[40:41], v[22:23], v[44:45] op_sel_hi:[1,0,1]
	ds_write_b16 v72, v2 offset:1152
	ds_write_b16_d16_hi v72, v2 offset:1296
	v_cvt_pk_bf16_f32 v2, v50, v51
	v_pk_fma_f32 v[44:45], v[60:61], v[22:23], v[48:49] op_sel_hi:[1,0,1]
	v_fmac_f32_e32 v74, v78, v23
	ds_write_b16 v72, v2 offset:1440
	ds_write_b16_d16_hi v72, v2 offset:1584
	v_cvt_pk_bf16_f32 v2, v40, v41
	s_waitcnt vmcnt(3)
	v_pk_fma_f32 v[22:23], v[36:37], v[74:75], v[38:39] op_sel_hi:[1,0,1]
	ds_write_b16 v72, v2 offset:2304
	ds_write_b16_d16_hi v72, v2 offset:2448
	v_cvt_pk_bf16_f32 v2, v44, v45
	v_pk_fma_f32 v[20:21], v[64:65], v[74:75], v[42:43] op_sel_hi:[1,0,1]
	ds_write_b16 v72, v2 offset:2592
	ds_write_b16_d16_hi v72, v2 offset:2736
	v_cvt_pk_bf16_f32 v2, v22, v23
	ds_write_b16 v72, v2 offset:3456
	ds_write_b16_d16_hi v72, v2 offset:3600
	v_cvt_pk_bf16_f32 v2, v20, v21
	ds_write_b16 v72, v2 offset:3744
	ds_write_b16_d16_hi v72, v2 offset:3888
	s_waitcnt lgkmcnt(0)
	s_barrier
	s_and_saveexec_b64 s[22:23], s[2:3]
	ds_write_b32 v69, v21
	s_or_b64 exec, exec, s[22:23]
	ds_read_b128 v[36:39], v70
	v_mad_u64_u32 v[20:21], s[22:23], v32, s5, v[24:25]
	v_mad_i32_i24 v21, v33, s5, v21
	v_lshlrev_b32_e32 v32, 16, v12
	s_waitcnt lgkmcnt(0)
	v_lshlrev_b32_e32 v22, 16, v36
	v_and_b32_e32 v23, 0xffff0000, v36
	v_and_b32_e32 v33, 0xffff0000, v12
	v_pk_mul_f32 v[22:23], v[32:33], v[22:23]
	v_lshlrev_b32_e32 v32, 16, v13
	v_cvt_pk_bf16_f32 v12, v22, v23
	v_lshlrev_b32_e32 v22, 16, v37
	v_and_b32_e32 v23, 0xffff0000, v37
	v_and_b32_e32 v33, 0xffff0000, v13
	v_pk_mul_f32 v[22:23], v[32:33], v[22:23]
	v_lshlrev_b32_e32 v32, 16, v14
	v_cvt_pk_bf16_f32 v13, v22, v23
	v_lshlrev_b32_e32 v22, 16, v38
	v_and_b32_e32 v23, 0xffff0000, v38
	v_and_b32_e32 v33, 0xffff0000, v14
	v_pk_mul_f32 v[22:23], v[32:33], v[22:23]
	v_lshlrev_b32_e32 v32, 16, v15
	v_cvt_pk_bf16_f32 v14, v22, v23
	v_lshlrev_b32_e32 v22, 16, v39
	v_and_b32_e32 v23, 0xffff0000, v39
	v_and_b32_e32 v33, 0xffff0000, v15
	v_pk_mul_f32 v[22:23], v[32:33], v[22:23]
	v_lshlrev_b32_e32 v32, 16, v4
	v_cvt_pk_bf16_f32 v15, v22, v23
	global_store_dwordx4 v[20:21], v[12:15], off sc1
	ds_read_b128 v[12:15], v70 offset:9216
	v_and_b32_e32 v33, 0xffff0000, v4
	s_mov_b32 s0, 0x30000
	v_readlane_b32 s22, v253, 9
	v_readlane_b32 s23, v253, 10
	s_waitcnt lgkmcnt(0)
	v_lshlrev_b32_e32 v22, 16, v12
	v_and_b32_e32 v23, 0xffff0000, v12
	v_pk_mul_f32 v[22:23], v[32:33], v[22:23]
	v_lshlrev_b32_e32 v12, 16, v13
	v_cvt_pk_bf16_f32 v4, v22, v23
	v_and_b32_e32 v13, 0xffff0000, v13
	v_lshlrev_b32_e32 v22, 16, v5
	v_and_b32_e32 v23, 0xffff0000, v5
	v_pk_mul_f32 v[12:13], v[22:23], v[12:13]
	v_lshlrev_b32_e32 v22, 16, v6
	v_cvt_pk_bf16_f32 v5, v12, v13
	v_lshlrev_b32_e32 v12, 16, v14
	v_and_b32_e32 v13, 0xffff0000, v14
	v_and_b32_e32 v23, 0xffff0000, v6
	v_pk_mul_f32 v[12:13], v[22:23], v[12:13]
	v_lshlrev_b32_e32 v14, 16, v7
	v_cvt_pk_bf16_f32 v6, v12, v13
	v_lshlrev_b32_e32 v12, 16, v15
	v_and_b32_e32 v13, 0xffff0000, v15
	v_and_b32_e32 v15, 0xffff0000, v7
	v_pk_mul_f32 v[12:13], v[14:15], v[12:13]
	s_or_b32 s22, s22, 0x280
	v_cvt_pk_bf16_f32 v7, v12, v13
	v_add_co_u32_e32 v12, vcc, s0, v20
	s_mov_b32 s0, 0x28000
	s_nop 0
	v_addc_co_u32_e32 v13, vcc, 0, v21, vcc
	global_store_dwordx4 v[12:13], v[4:7], off sc1
	s_mov_b32 s23, s25
	v_lshl_add_u64 v[32:33], v[28:29], 0, s[22:23]
	v_add_co_u32_e32 v4, vcc, s0, v26
	v_mov_b32_e32 v31, v3
	s_nop 0
	v_addc_co_u32_e32 v5, vcc, 0, v27, vcc
	global_load_dword v102, v[4:5], off nt
	global_load_dword v100, v[4:5], off offset:256 nt
	global_load_dword v98, v[4:5], off offset:512 nt
	global_load_dword v96, v[4:5], off offset:768 nt
	global_load_dword v94, v[4:5], off offset:1024 nt
	global_load_dword v93, v[4:5], off offset:1280 nt
	global_load_dword v91, v[4:5], off offset:1536 nt
	global_load_dword v89, v[4:5], off offset:1792 nt
	global_load_dword v86, v[4:5], off offset:2048 nt
	global_load_dword v84, v[4:5], off offset:2304 nt
	global_load_dword v82, v[4:5], off offset:2560 nt
	global_load_dword v80, v[4:5], off offset:2816 nt
	global_load_dword v78, v[4:5], off offset:3072 nt
	global_load_dword v76, v[4:5], off offset:3328 nt
	global_load_dword v74, v[4:5], off offset:3584 nt
	global_load_dword v2, v[4:5], off offset:3840 nt
	v_mov_b64_e32 v[4:5], s[54:55]
	v_mad_u64_u32 v[4:5], s[22:23], v32, s16, v[4:5]
	v_mad_i32_i24 v5, v33, s16, v5
	v_lshl_add_u64 v[4:5], v[4:5], 0, s[24:25]
	v_lshl_add_u64 v[4:5], v[4:5], 0, v[30:31]
	global_load_dwordx4 v[12:15], v[4:5], off offset:2048
	v_add_co_u32_e32 v4, vcc, s14, v4
	s_nop 1
	v_addc_co_u32_e32 v5, vcc, 0, v5, vcc
	global_load_dwordx4 v[4:7], v[4:5], off offset:2048
	v_lshlrev_b32_e32 v20, 16, v103
	v_exp_f32_e32 v52, v20
	v_lshlrev_b32_e32 v20, 16, v101
	v_lshlrev_b32_e32 v36, 16, v88
	v_exp_f32_e32 v20, v20
	v_lshlrev_b32_e32 v21, 16, v99
	v_exp_f32_e32 v37, v36
	v_lshlrev_b32_e32 v36, 16, v87
	v_exp_f32_e32 v21, v21
	v_lshlrev_b32_e32 v22, 16, v97
	v_exp_f32_e32 v40, v36
	v_lshlrev_b32_e32 v36, 16, v85
	v_and_b32_e32 v56, 0xffff0000, v103
	v_exp_f32_e32 v22, v22
	v_lshlrev_b32_e32 v23, 16, v95
	v_exp_f32_e32 v41, v36
	v_lshlrev_b32_e32 v36, 16, v83
	v_and_b32_e32 v57, 0xffff0000, v101
	v_exp_f32_e32 v46, v23
	v_lshlrev_b32_e32 v23, 16, v92
	v_exp_f32_e32 v60, v36
	v_lshlrev_b32_e32 v36, 16, v81
	v_fmac_f32_e32 v56, 0, v52
	v_and_b32_e32 v58, 0xffff0000, v99
	v_exp_f32_e32 v23, v23
	v_lshlrev_b32_e32 v31, 16, v90
	v_exp_f32_e32 v61, v36
	v_lshlrev_b32_e32 v36, 16, v79
	v_fmac_f32_e32 v57, v20, v56
	v_and_b32_e32 v59, 0xffff0000, v97
	v_exp_f32_e32 v31, v31
	v_exp_f32_e32 v36, v36
	v_lshlrev_b32_e32 v39, 16, v77
	v_fmac_f32_e32 v58, v21, v57
	v_and_b32_e32 v50, 0xffff0000, v95
	v_exp_f32_e32 v64, v39
	v_lshlrev_b32_e32 v42, 16, v75
	v_fmac_f32_e32 v59, v22, v58
	v_and_b32_e32 v51, 0xffff0000, v92
	v_exp_f32_e32 v65, v42
	s_waitcnt vmcnt(22)
	v_lshlrev_b32_e32 v43, 16, v73
	v_mul_f32_e32 v53, v52, v20
	v_fmac_f32_e32 v50, 0, v46
	ds_bpermute_b32 v20, v197, v59
	v_and_b32_e32 v54, 0xffff0000, v90
	v_and_b32_e32 v38, 0xffff0000, v79
	v_and_b32_e32 v42, 0xffff0000, v75
	v_exp_f32_e32 v75, v43
	v_mul_f32_e32 v66, v21, v53
	v_fmac_f32_e32 v51, v23, v50
	v_mul_f32_e32 v47, v46, v23
	v_and_b32_e32 v55, 0xffff0000, v88
	v_and_b32_e32 v39, 0xffff0000, v77
	v_mul_f32_e32 v67, v22, v66
	v_fmac_f32_e32 v54, v31, v51
	v_mul_f32_e32 v62, v31, v47
	v_fmac_f32_e32 v38, 0, v36
	v_fmac_f32_e32 v55, v37, v54
	v_mul_f32_e32 v63, v37, v62
	v_fmac_f32_e32 v39, v64, v38
	v_mul_f32_e32 v37, v36, v64
	ds_bpermute_b32 v31, v197, v67
	v_and_b32_e32 v43, 0xffff0000, v73
	v_fmac_f32_e32 v42, v65, v39
	v_mul_f32_e32 v64, v65, v37
	v_and_b32_e32 v44, 0xffff0000, v87
	v_fmac_f32_e32 v43, v75, v42
	v_mul_f32_e32 v65, v75, v64
	s_waitcnt lgkmcnt(1)
	v_cndmask_b32_e64 v73, v20, v59, s[38:39]
	v_cndmask_b32_e64 v75, v59, v20, s[38:39]
	ds_bpermute_b32 v20, v197, v63
	ds_bpermute_b32 v23, v197, v55
	v_and_b32_e32 v45, 0xffff0000, v85
	v_fmac_f32_e32 v44, 0, v40
	v_and_b32_e32 v48, 0xffff0000, v83
	v_fmac_f32_e32 v45, v41, v44
	v_mul_f32_e32 v41, v40, v41
	v_and_b32_e32 v49, 0xffff0000, v81
	v_fmac_f32_e32 v48, v60, v45
	v_mul_f32_e32 v60, v60, v41
	s_waitcnt lgkmcnt(2)
	v_cndmask_b32_e64 v21, v31, v67, s[38:39]
	v_fmac_f32_e32 v49, v61, v48
	v_mul_f32_e32 v61, v61, v60
	v_cndmask_b32_e64 v22, v67, v31, s[38:39]
	v_fmac_f32_e32 v73, 0, v21
	v_mul_f32_e32 v77, v67, v31
	v_fmac_f32_e32 v75, v22, v73
	s_waitcnt lgkmcnt(1)
	v_cndmask_b32_e64 v21, v20, v63, s[38:39]
	s_waitcnt lgkmcnt(0)
	v_cndmask_b32_e64 v79, v23, v55, s[38:39]
	v_cndmask_b32_e64 v81, v55, v23, s[38:39]
	ds_bpermute_b32 v22, v197, v61
	ds_bpermute_b32 v23, v197, v49
	v_cndmask_b32_e64 v20, v63, v20, s[38:39]
	v_mul_f32_e32 v83, v77, v21
	v_fmac_f32_e32 v79, v21, v75
	v_mul_f32_e32 v85, v20, v83
	v_fmac_f32_e32 v81, v20, v79
	ds_bpermute_b32 v21, v197, v65
	ds_bpermute_b32 v20, v197, v43
	s_waitcnt lgkmcnt(3)
	v_cndmask_b32_e64 v92, v22, v61, s[38:39]
	s_waitcnt lgkmcnt(2)
	v_cndmask_b32_e64 v87, v23, v49, s[38:39]
	v_cndmask_b32_e64 v22, v61, v22, s[38:39]
	v_cndmask_b32_e64 v88, v49, v23, s[38:39]
	v_mul_f32_e32 v90, v85, v92
	v_fmac_f32_e32 v87, v92, v81
	v_mul_f32_e32 v92, v22, v90
	v_fmac_f32_e32 v88, v22, v87
	s_waitcnt lgkmcnt(1)
	v_cndmask_b32_e64 v22, v21, v65, s[38:39]
	s_waitcnt lgkmcnt(0)
	v_cndmask_b32_e64 v95, v20, v43, s[38:39]
	v_mul_f32_e32 v97, v92, v22
	v_fmac_f32_e32 v95, v22, v88
	s_and_saveexec_b64 s[22:23], s[38:39]
	v_mul_f32_e32 v23, v95, v21
	v_mul_f32_e32 v22, v97, v21
	v_add_f32_e32 v23, v23, v20
	ds_write_b64 v71, v[22:23]
	s_or_b64 exec, exec, s[22:23]
	s_waitcnt lgkmcnt(0)
	s_barrier
	ds_read_b32 v23, v69
	s_and_b64 vcc, exec, s[40:41]
	s_cbranch_vccnz .LBB0_824
	s_add_i32 s0, s62, -1
	s_cmp_lt_u32 s0, 7
	s_mov_b32 s0, 0
	s_cbranch_scc1 .LBB0_821
	v_readlane_b32 s9, v254, 35
	s_add_i32 s9, s9, 0
	s_add_i32 s9, s9, 0x111c0
	s_and_b32 s0, s62, 0x7ffffff8
	v_lshl_add_u32 v99, v68, 3, s9
	s_mov_b32 s9, 0

.LBB0_824:
	v_cndmask_b32_e64 v21, v31, 1.0, s[38:39]
	v_cndmask_b32_e64 v20, v73, 0, s[38:39]
	s_waitcnt lgkmcnt(0)
	v_fmac_f32_e32 v20, v21, v23
	v_cndmask_b32_e64 v31, v83, v77, s[38:39]
	v_cndmask_b32_e64 v22, v79, v75, s[38:39]
	v_pk_fma_f32 v[52:53], v[52:53], v[20:21], v[56:57] op_sel_hi:[1,0,1]
	v_pk_fma_f32 v[56:57], v[66:67], v[20:21], v[58:59] op_sel_hi:[1,0,1]
	v_fmac_f32_e32 v22, v31, v23
	v_cvt_pk_bf16_f32 v31, v52, v53
	v_cndmask_b32_e64 v73, v90, v85, s[38:39]
	v_cndmask_b32_e64 v90, v87, v81, s[38:39]
	v_pk_fma_f32 v[46:47], v[46:47], v[22:23], v[50:51] op_sel_hi:[1,0,1]
	ds_write_b16 v72, v31
	ds_write_b16_d16_hi v72, v31 offset:144
	v_cvt_pk_bf16_f32 v31, v56, v57
	v_cndmask_b32_e64 v75, v97, v92, s[38:39]
	v_cndmask_b32_e64 v88, v95, v88, s[38:39]
	v_pk_fma_f32 v[50:51], v[62:63], v[22:23], v[54:55] op_sel_hi:[1,0,1]
	v_fmac_f32_e32 v90, v73, v23
	ds_write_b16 v72, v31 offset:288
	ds_write_b16_d16_hi v72, v31 offset:432
	v_cvt_pk_bf16_f32 v31, v46, v47
	s_waitcnt vmcnt(11)
	v_pk_fma_f32 v[40:41], v[40:41], v[90:91], v[44:45] op_sel_hi:[1,0,1]
	v_fmac_f32_e32 v88, v75, v23
	ds_write_b16 v72, v31 offset:1152
	ds_write_b16_d16_hi v72, v31 offset:1296
	v_cvt_pk_bf16_f32 v31, v50, v51
	v_pk_fma_f32 v[44:45], v[60:61], v[90:91], v[48:49] op_sel_hi:[1,0,1]
	s_waitcnt vmcnt(10)
	v_pk_fma_f32 v[22:23], v[36:37], v[88:89], v[38:39] op_sel_hi:[1,0,1]
	v_pk_fma_f32 v[20:21], v[64:65], v[88:89], v[42:43] op_sel_hi:[1,0,1]
	ds_write_b16 v72, v31 offset:1440
	ds_write_b16_d16_hi v72, v31 offset:1584
	v_cvt_pk_bf16_f32 v31, v40, v41
	ds_write_b16 v72, v31 offset:2304
	ds_write_b16_d16_hi v72, v31 offset:2448
	v_cvt_pk_bf16_f32 v31, v44, v45
	v_cvt_pk_bf16_f32 v22, v22, v23
	v_cvt_pk_bf16_f32 v20, v20, v21
	ds_write_b16 v72, v31 offset:2592
	ds_write_b16_d16_hi v72, v31 offset:2736
	ds_write_b16 v72, v22 offset:3456
	ds_write_b16_d16_hi v72, v22 offset:3600
	ds_write_b16 v72, v20 offset:3744
	ds_write_b16_d16_hi v72, v20 offset:3888
	s_waitcnt lgkmcnt(0)
	s_barrier
	s_and_saveexec_b64 s[22:23], s[2:3]
	ds_write_b32 v69, v21
	s_or_b64 exec, exec, s[22:23]
	v_mad_u64_u32 v[20:21], s[22:23], v34, s5, v[24:25]
	v_mad_i32_i24 v21, v35, s5, v21
	ds_read_b128 v[34:37], v70
	v_lshlrev_b32_e32 v38, 16, v16
	v_and_b32_e32 v39, 0xffff0000, v16
	s_mov_b32 s0, 0x30000
	v_readlane_b32 s22, v253, 9
	s_waitcnt lgkmcnt(0)
	v_lshlrev_b32_e32 v22, 16, v34
	v_and_b32_e32 v23, 0xffff0000, v34
	v_pk_mul_f32 v[22:23], v[38:39], v[22:23]
	v_lshlrev_b32_e32 v34, 16, v17
	v_cvt_pk_bf16_f32 v16, v22, v23
	v_lshlrev_b32_e32 v22, 16, v35
	v_and_b32_e32 v23, 0xffff0000, v35
	v_and_b32_e32 v35, 0xffff0000, v17
	v_pk_mul_f32 v[22:23], v[34:35], v[22:23]
	v_lshlrev_b32_e32 v34, 16, v18
	v_cvt_pk_bf16_f32 v17, v22, v23
	v_lshlrev_b32_e32 v22, 16, v36
	v_and_b32_e32 v23, 0xffff0000, v36
	v_and_b32_e32 v35, 0xffff0000, v18
	v_pk_mul_f32 v[22:23], v[34:35], v[22:23]
	v_lshlrev_b32_e32 v34, 16, v19
	v_cvt_pk_bf16_f32 v18, v22, v23
	v_lshlrev_b32_e32 v22, 16, v37
	v_and_b32_e32 v23, 0xffff0000, v37
	v_and_b32_e32 v35, 0xffff0000, v19
	v_pk_mul_f32 v[22:23], v[34:35], v[22:23]
	v_lshlrev_b32_e32 v34, 16, v8
	v_cvt_pk_bf16_f32 v19, v22, v23
	global_store_dwordx4 v[20:21], v[16:19], off sc1
	ds_read_b128 v[16:19], v70 offset:9216
	v_and_b32_e32 v35, 0xffff0000, v8
	v_readlane_b32 s23, v253, 10
	s_or_b32 s22, s22, 0x300
	s_mov_b32 s23, s25
	s_waitcnt lgkmcnt(0)
	v_lshlrev_b32_e32 v22, 16, v16
	v_and_b32_e32 v23, 0xffff0000, v16
	v_pk_mul_f32 v[22:23], v[34:35], v[22:23]
	v_lshlrev_b32_e32 v16, 16, v17
	v_cvt_pk_bf16_f32 v8, v22, v23
	v_and_b32_e32 v17, 0xffff0000, v17
	v_lshlrev_b32_e32 v22, 16, v9
	v_and_b32_e32 v23, 0xffff0000, v9
	v_pk_mul_f32 v[16:17], v[22:23], v[16:17]
	v_lshlrev_b32_e32 v22, 16, v10
	v_cvt_pk_bf16_f32 v9, v16, v17
	v_lshlrev_b32_e32 v16, 16, v18
	v_and_b32_e32 v17, 0xffff0000, v18
	v_and_b32_e32 v23, 0xffff0000, v10
	v_pk_mul_f32 v[16:17], v[22:23], v[16:17]
	v_lshlrev_b32_e32 v18, 16, v11
	v_cvt_pk_bf16_f32 v10, v16, v17
	v_lshlrev_b32_e32 v16, 16, v19
	v_and_b32_e32 v17, 0xffff0000, v19
	v_and_b32_e32 v19, 0xffff0000, v11
	v_pk_mul_f32 v[16:17], v[18:19], v[16:17]
	v_lshl_add_u64 v[34:35], v[28:29], 0, s[22:23]
	v_cvt_pk_bf16_f32 v11, v16, v17
	v_add_co_u32_e32 v16, vcc, s0, v20
	v_mov_b32_e32 v31, v3
	s_nop 0
	v_addc_co_u32_e32 v17, vcc, 0, v21, vcc
	global_store_dwordx4 v[16:17], v[8:11], off sc1
	s_nop 1
	v_add_co_u32_e32 v8, vcc, s0, v26
	s_nop 1
	v_addc_co_u32_e32 v9, vcc, 0, v27, vcc
	global_load_dword v103, v[8:9], off nt
	global_load_dword v101, v[8:9], off offset:256 nt
	global_load_dword v99, v[8:9], off offset:512 nt
	global_load_dword v97, v[8:9], off offset:768 nt
	global_load_dword v95, v[8:9], off offset:1024 nt
	global_load_dword v92, v[8:9], off offset:1280 nt
	global_load_dword v90, v[8:9], off offset:1536 nt
	global_load_dword v88, v[8:9], off offset:1792 nt
	global_load_dword v87, v[8:9], off offset:2048 nt
	global_load_dword v85, v[8:9], off offset:2304 nt
	global_load_dword v83, v[8:9], off offset:2560 nt
	global_load_dword v81, v[8:9], off offset:2816 nt
	global_load_dword v79, v[8:9], off offset:3072 nt
	global_load_dword v77, v[8:9], off offset:3328 nt
	global_load_dword v75, v[8:9], off offset:3584 nt
	global_load_dword v73, v[8:9], off offset:3840 nt
	v_mov_b64_e32 v[8:9], s[54:55]
	v_mad_u64_u32 v[8:9], s[22:23], v34, s16, v[8:9]
	v_mad_i32_i24 v9, v35, s16, v9
	v_lshl_add_u64 v[8:9], v[8:9], 0, s[24:25]
	v_lshl_add_u64 v[8:9], v[8:9], 0, v[30:31]
	global_load_dwordx4 v[16:19], v[8:9], off offset:2048
	v_add_co_u32_e32 v8, vcc, s14, v8
	s_nop 1
	v_addc_co_u32_e32 v9, vcc, 0, v9, vcc
	global_load_dwordx4 v[8:11], v[8:9], off offset:2048
	v_lshlrev_b32_e32 v20, 16, v102
	v_exp_f32_e32 v52, v20
	v_lshlrev_b32_e32 v20, 16, v100
	v_lshlrev_b32_e32 v36, 16, v89
	v_exp_f32_e32 v20, v20
	v_lshlrev_b32_e32 v21, 16, v98
	v_exp_f32_e32 v37, v36
	s_waitcnt vmcnt(29)
	v_lshlrev_b32_e32 v36, 16, v86
	v_exp_f32_e32 v21, v21
	v_lshlrev_b32_e32 v22, 16, v96
	v_exp_f32_e32 v40, v36
	s_waitcnt vmcnt(28)
	v_lshlrev_b32_e32 v36, 16, v84
	v_and_b32_e32 v56, 0xffff0000, v102
	v_exp_f32_e32 v22, v22
	v_lshlrev_b32_e32 v23, 16, v94
	v_exp_f32_e32 v41, v36
	s_waitcnt vmcnt(27)
	v_lshlrev_b32_e32 v36, 16, v82
	v_and_b32_e32 v57, 0xffff0000, v100
	v_exp_f32_e32 v46, v23
	v_lshlrev_b32_e32 v23, 16, v93
	v_exp_f32_e32 v60, v36
	s_waitcnt vmcnt(26)
	v_lshlrev_b32_e32 v36, 16, v80
	v_fmac_f32_e32 v56, 0, v52
	v_and_b32_e32 v58, 0xffff0000, v98
	v_exp_f32_e32 v23, v23
	v_lshlrev_b32_e32 v31, 16, v91
	v_exp_f32_e32 v61, v36
	s_waitcnt vmcnt(25)
	v_lshlrev_b32_e32 v36, 16, v78
	v_fmac_f32_e32 v57, v20, v56
	v_and_b32_e32 v59, 0xffff0000, v96
	v_exp_f32_e32 v31, v31
	v_exp_f32_e32 v36, v36
	s_waitcnt vmcnt(24)
	v_lshlrev_b32_e32 v39, 16, v76
	v_fmac_f32_e32 v58, v21, v57
	v_and_b32_e32 v50, 0xffff0000, v94
	v_exp_f32_e32 v64, v39
	s_waitcnt vmcnt(23)
	v_lshlrev_b32_e32 v42, 16, v74
	v_fmac_f32_e32 v59, v22, v58
	v_and_b32_e32 v51, 0xffff0000, v93
	v_exp_f32_e32 v65, v42
	s_waitcnt vmcnt(22)
	v_lshlrev_b32_e32 v43, 16, v2
	v_mul_f32_e32 v53, v52, v20
	v_fmac_f32_e32 v50, 0, v46
	ds_bpermute_b32 v20, v197, v59
	v_and_b32_e32 v54, 0xffff0000, v91
	v_and_b32_e32 v38, 0xffff0000, v78
	v_and_b32_e32 v42, 0xffff0000, v74
	v_exp_f32_e32 v74, v43
	v_mul_f32_e32 v66, v21, v53
	v_fmac_f32_e32 v51, v23, v50
	v_mul_f32_e32 v47, v46, v23
	v_and_b32_e32 v55, 0xffff0000, v89
	v_and_b32_e32 v39, 0xffff0000, v76
	v_mul_f32_e32 v67, v22, v66
	v_fmac_f32_e32 v54, v31, v51
	v_mul_f32_e32 v62, v31, v47
	v_fmac_f32_e32 v38, 0, v36
	v_and_b32_e32 v43, 0xffff0000, v2
	v_fmac_f32_e32 v55, v37, v54
	v_mul_f32_e32 v63, v37, v62
	v_fmac_f32_e32 v39, v64, v38
	v_mul_f32_e32 v37, v36, v64
	ds_bpermute_b32 v2, v197, v67
	v_fmac_f32_e32 v42, v65, v39
	v_mul_f32_e32 v64, v65, v37
	v_and_b32_e32 v44, 0xffff0000, v86
	v_fmac_f32_e32 v43, v74, v42
	v_mul_f32_e32 v65, v74, v64
	s_waitcnt lgkmcnt(1)
	v_cndmask_b32_e64 v31, v20, v59, s[38:39]
	v_cndmask_b32_e64 v74, v59, v20, s[38:39]
	ds_bpermute_b32 v20, v197, v63
	ds_bpermute_b32 v23, v197, v55
	v_and_b32_e32 v45, 0xffff0000, v84
	v_fmac_f32_e32 v44, 0, v40
	v_and_b32_e32 v48, 0xffff0000, v82
	v_fmac_f32_e32 v45, v41, v44
	v_mul_f32_e32 v41, v40, v41
	v_and_b32_e32 v49, 0xffff0000, v80
	v_fmac_f32_e32 v48, v60, v45
	v_mul_f32_e32 v60, v60, v41
	s_waitcnt lgkmcnt(2)
	v_cndmask_b32_e64 v21, v2, v67, s[38:39]
	v_fmac_f32_e32 v49, v61, v48
	v_mul_f32_e32 v61, v61, v60
	v_cndmask_b32_e64 v22, v67, v2, s[38:39]
	v_fmac_f32_e32 v31, 0, v21
	v_mul_f32_e32 v76, v67, v2
	v_fmac_f32_e32 v74, v22, v31
	s_waitcnt lgkmcnt(1)
	v_cndmask_b32_e64 v21, v20, v63, s[38:39]
	s_waitcnt lgkmcnt(0)
	v_cndmask_b32_e64 v78, v23, v55, s[38:39]
	v_cndmask_b32_e64 v80, v55, v23, s[38:39]
	ds_bpermute_b32 v22, v197, v61
	ds_bpermute_b32 v23, v197, v49
	v_cndmask_b32_e64 v20, v63, v20, s[38:39]
	v_mul_f32_e32 v82, v76, v21
	v_fmac_f32_e32 v78, v21, v74
	v_mul_f32_e32 v84, v20, v82
	v_fmac_f32_e32 v80, v20, v78
	ds_bpermute_b32 v21, v197, v65
	ds_bpermute_b32 v20, v197, v43
	s_waitcnt lgkmcnt(3)
	v_cndmask_b32_e64 v93, v22, v61, s[38:39]
	s_waitcnt lgkmcnt(2)
	v_cndmask_b32_e64 v86, v23, v49, s[38:39]
	v_cndmask_b32_e64 v22, v61, v22, s[38:39]
	v_cndmask_b32_e64 v89, v49, v23, s[38:39]
	v_mul_f32_e32 v91, v84, v93
	v_fmac_f32_e32 v86, v93, v80
	v_mul_f32_e32 v93, v22, v91
	v_fmac_f32_e32 v89, v22, v86
	s_waitcnt lgkmcnt(1)
	v_cndmask_b32_e64 v22, v21, v65, s[38:39]
	s_waitcnt lgkmcnt(0)
	v_cndmask_b32_e64 v94, v20, v43, s[38:39]
	v_mul_f32_e32 v96, v93, v22
	v_fmac_f32_e32 v94, v22, v89
	s_and_saveexec_b64 s[22:23], s[38:39]
	v_mul_f32_e32 v23, v94, v21
	v_mul_f32_e32 v22, v96, v21
	v_add_f32_e32 v23, v23, v20
	ds_write_b64 v71, v[22:23]
	s_or_b64 exec, exec, s[22:23]
	s_waitcnt lgkmcnt(0)
	s_barrier
	ds_read_b32 v23, v69
	s_and_b64 vcc, exec, s[40:41]
	s_cbranch_vccnz .LBB0_835
	s_add_i32 s0, s62, -1
	s_cmp_lt_u32 s0, 7
	s_mov_b32 s0, 0
	s_cbranch_scc1 .LBB0_832
	v_readlane_b32 s9, v254, 35
	s_add_i32 s9, s9, 0
	s_add_i32 s9, s9, 0x111c0
	s_and_b32 s0, s62, 0x7ffffff8
	v_lshl_add_u32 v98, v68, 3, s9
	s_mov_b32 s9, 0

.LBB0_835:
	v_cndmask_b32_e64 v21, v2, 1.0, s[38:39]
	v_cndmask_b32_e64 v2, v31, 0, s[38:39]
	s_waitcnt lgkmcnt(0)
	v_fmac_f32_e32 v2, v21, v23
	v_cndmask_b32_e64 v31, v82, v76, s[38:39]
	v_cndmask_b32_e64 v20, v78, v74, s[38:39]
	v_pk_fma_f32 v[52:53], v[52:53], v[2:3], v[56:57] op_sel_hi:[1,0,1]
	v_pk_fma_f32 v[56:57], v[66:67], v[2:3], v[58:59] op_sel_hi:[1,0,1]
	v_fmac_f32_e32 v20, v31, v23
	v_cvt_pk_bf16_f32 v2, v52, v53
	v_cndmask_b32_e64 v76, v91, v84, s[38:39]
	v_cndmask_b32_e64 v22, v86, v80, s[38:39]
	v_pk_fma_f32 v[46:47], v[46:47], v[20:21], v[50:51] op_sel_hi:[1,0,1]
	ds_write_b16 v72, v2
	ds_write_b16_d16_hi v72, v2 offset:144
	v_cvt_pk_bf16_f32 v2, v56, v57
	v_pk_fma_f32 v[50:51], v[62:63], v[20:21], v[54:55] op_sel_hi:[1,0,1]
	v_fmac_f32_e32 v22, v76, v23
	ds_write_b16 v72, v2 offset:288
	ds_write_b16_d16_hi v72, v2 offset:432
	v_cvt_pk_bf16_f32 v2, v46, v47
	v_cndmask_b32_e64 v78, v96, v93, s[38:39]
	v_cndmask_b32_e64 v74, v94, v89, s[38:39]
	v_pk_fma_f32 v[40:41], v[40:41], v[22:23], v[44:45] op_sel_hi:[1,0,1]
	ds_write_b16 v72, v2 offset:1152
	ds_write_b16_d16_hi v72, v2 offset:1296
	v_cvt_pk_bf16_f32 v2, v50, v51
	v_pk_fma_f32 v[44:45], v[60:61], v[22:23], v[48:49] op_sel_hi:[1,0,1]
	v_fmac_f32_e32 v74, v78, v23
	ds_write_b16 v72, v2 offset:1440
	ds_write_b16_d16_hi v72, v2 offset:1584
	v_cvt_pk_bf16_f32 v2, v40, v41
	s_waitcnt vmcnt(3)
	v_pk_fma_f32 v[22:23], v[36:37], v[74:75], v[38:39] op_sel_hi:[1,0,1]
	ds_write_b16 v72, v2 offset:2304
	ds_write_b16_d16_hi v72, v2 offset:2448
	v_cvt_pk_bf16_f32 v2, v44, v45
	v_pk_fma_f32 v[20:21], v[64:65], v[74:75], v[42:43] op_sel_hi:[1,0,1]
	ds_write_b16 v72, v2 offset:2592
	ds_write_b16_d16_hi v72, v2 offset:2736
	v_cvt_pk_bf16_f32 v2, v22, v23
	ds_write_b16 v72, v2 offset:3456
	ds_write_b16_d16_hi v72, v2 offset:3600
	v_cvt_pk_bf16_f32 v2, v20, v21
	ds_write_b16 v72, v2 offset:3744
	ds_write_b16_d16_hi v72, v2 offset:3888
	s_waitcnt lgkmcnt(0)
	s_barrier
	s_and_saveexec_b64 s[22:23], s[2:3]
	ds_write_b32 v69, v21
	s_or_b64 exec, exec, s[22:23]
	ds_read_b128 v[36:39], v70
	v_mad_u64_u32 v[20:21], s[22:23], v32, s5, v[24:25]
	v_mad_i32_i24 v21, v33, s5, v21
	v_lshlrev_b32_e32 v32, 16, v12
	s_waitcnt lgkmcnt(0)
	v_lshlrev_b32_e32 v22, 16, v36
	v_and_b32_e32 v23, 0xffff0000, v36
	v_and_b32_e32 v33, 0xffff0000, v12
	v_pk_mul_f32 v[22:23], v[32:33], v[22:23]
	v_lshlrev_b32_e32 v32, 16, v13
	v_cvt_pk_bf16_f32 v12, v22, v23
	v_lshlrev_b32_e32 v22, 16, v37
	v_and_b32_e32 v23, 0xffff0000, v37
	v_and_b32_e32 v33, 0xffff0000, v13
	v_pk_mul_f32 v[22:23], v[32:33], v[22:23]
	v_lshlrev_b32_e32 v32, 16, v14
	v_cvt_pk_bf16_f32 v13, v22, v23
	v_lshlrev_b32_e32 v22, 16, v38
	v_and_b32_e32 v23, 0xffff0000, v38
	v_and_b32_e32 v33, 0xffff0000, v14
	v_pk_mul_f32 v[22:23], v[32:33], v[22:23]
	v_lshlrev_b32_e32 v32, 16, v15
	v_cvt_pk_bf16_f32 v14, v22, v23
	v_lshlrev_b32_e32 v22, 16, v39
	v_and_b32_e32 v23, 0xffff0000, v39
	v_and_b32_e32 v33, 0xffff0000, v15
	v_pk_mul_f32 v[22:23], v[32:33], v[22:23]
	v_lshlrev_b32_e32 v32, 16, v4
	v_cvt_pk_bf16_f32 v15, v22, v23
	global_store_dwordx4 v[20:21], v[12:15], off sc1
	ds_read_b128 v[12:15], v70 offset:9216
	v_and_b32_e32 v33, 0xffff0000, v4
	s_mov_b32 s0, 0x30000
	v_readlane_b32 s22, v253, 9
	v_readlane_b32 s23, v253, 10
	s_waitcnt lgkmcnt(0)
	v_lshlrev_b32_e32 v22, 16, v12
	v_and_b32_e32 v23, 0xffff0000, v12
	v_pk_mul_f32 v[22:23], v[32:33], v[22:23]
	v_lshlrev_b32_e32 v12, 16, v13
	v_cvt_pk_bf16_f32 v4, v22, v23
	v_and_b32_e32 v13, 0xffff0000, v13
	v_lshlrev_b32_e32 v22, 16, v5
	v_and_b32_e32 v23, 0xffff0000, v5
	v_pk_mul_f32 v[12:13], v[22:23], v[12:13]
	v_lshlrev_b32_e32 v22, 16, v6
	v_cvt_pk_bf16_f32 v5, v12, v13
	v_lshlrev_b32_e32 v12, 16, v14
	v_and_b32_e32 v13, 0xffff0000, v14
	v_and_b32_e32 v23, 0xffff0000, v6
	v_pk_mul_f32 v[12:13], v[22:23], v[12:13]
	v_lshlrev_b32_e32 v14, 16, v7
	v_cvt_pk_bf16_f32 v6, v12, v13
	v_lshlrev_b32_e32 v12, 16, v15
	v_and_b32_e32 v13, 0xffff0000, v15
	v_and_b32_e32 v15, 0xffff0000, v7
	v_pk_mul_f32 v[12:13], v[14:15], v[12:13]
	s_or_b32 s22, s22, 0x380
	v_cvt_pk_bf16_f32 v7, v12, v13
	v_add_co_u32_e32 v12, vcc, s0, v20
	s_mov_b32 s0, 0x38000
	s_nop 0
	v_addc_co_u32_e32 v13, vcc, 0, v21, vcc
	global_store_dwordx4 v[12:13], v[4:7], off sc1
	s_mov_b32 s23, s25
	v_mov_b32_e32 v31, v3
	v_add_co_u32_e32 v4, vcc, s0, v26
	s_nop 1
	v_addc_co_u32_e32 v5, vcc, 0, v27, vcc
	global_load_dword v91, v[4:5], off nt
	global_load_dword v89, v[4:5], off offset:256 nt
	global_load_dword v86, v[4:5], off offset:512 nt
	global_load_dword v84, v[4:5], off offset:768 nt
	global_load_dword v82, v[4:5], off offset:1024 nt
	global_load_dword v80, v[4:5], off offset:1280 nt
	global_load_dword v78, v[4:5], off offset:1536 nt
	global_load_dword v76, v[4:5], off offset:1792 nt
	global_load_dword v74, v[4:5], off offset:2048 nt
	global_load_dword v67, v[4:5], off offset:2304 nt
	global_load_dword v66, v[4:5], off offset:2560 nt
	global_load_dword v65, v[4:5], off offset:2816 nt
	global_load_dword v64, v[4:5], off offset:3072 nt
	global_load_dword v63, v[4:5], off offset:3328 nt
	global_load_dword v62, v[4:5], off offset:3584 nt
	global_load_dword v2, v[4:5], off offset:3840 nt
	v_lshl_add_u64 v[26:27], v[28:29], 0, s[22:23]
	v_mov_b64_e32 v[4:5], s[54:55]
	v_mad_u64_u32 v[4:5], s[22:23], v26, s16, v[4:5]
	v_mad_i32_i24 v5, v27, s16, v5
	v_lshl_add_u64 v[4:5], v[4:5], 0, s[24:25]
	v_lshl_add_u64 v[4:5], v[4:5], 0, v[30:31]
	global_load_dwordx4 v[12:15], v[4:5], off offset:2048
	v_add_co_u32_e32 v4, vcc, s14, v4
	s_nop 1
	v_addc_co_u32_e32 v5, vcc, 0, v5, vcc
	global_load_dwordx4 v[4:7], v[4:5], off offset:2048
	v_lshlrev_b32_e32 v20, 16, v103
	v_lshlrev_b32_e32 v28, 16, v90
	v_exp_f32_e32 v46, v20
	v_lshlrev_b32_e32 v20, 16, v101
	v_exp_f32_e32 v29, v28
	v_lshlrev_b32_e32 v28, 16, v88
	v_exp_f32_e32 v20, v20
	v_lshlrev_b32_e32 v21, 16, v99
	v_exp_f32_e32 v33, v28
	v_lshlrev_b32_e32 v28, 16, v87
	v_exp_f32_e32 v21, v21
	v_lshlrev_b32_e32 v22, 16, v97
	v_lshlrev_b32_e32 v23, 16, v95
	v_exp_f32_e32 v32, v28
	v_lshlrev_b32_e32 v28, 16, v85
	v_and_b32_e32 v50, 0xffff0000, v103
	v_exp_f32_e32 v22, v22
	v_exp_f32_e32 v40, v23
	v_lshlrev_b32_e32 v23, 16, v92
	v_exp_f32_e32 v54, v28
	v_lshlrev_b32_e32 v28, 16, v83
	v_and_b32_e32 v51, 0xffff0000, v101
	v_exp_f32_e32 v23, v23
	v_exp_f32_e32 v55, v28
	v_lshlrev_b32_e32 v28, 16, v81
	v_fmac_f32_e32 v50, 0, v46
	v_and_b32_e32 v52, 0xffff0000, v99
	v_exp_f32_e32 v58, v28
	v_lshlrev_b32_e32 v28, 16, v79
	v_fmac_f32_e32 v51, v20, v50
	v_and_b32_e32 v53, 0xffff0000, v97
	v_and_b32_e32 v44, 0xffff0000, v95
	v_exp_f32_e32 v28, v28
	v_lshlrev_b32_e32 v31, 16, v77
	v_fmac_f32_e32 v52, v21, v51
	v_and_b32_e32 v45, 0xffff0000, v92
	v_exp_f32_e32 v59, v31
	v_lshlrev_b32_e32 v36, 16, v75
	v_fmac_f32_e32 v53, v22, v52
	v_fmac_f32_e32 v44, 0, v40
	v_and_b32_e32 v48, 0xffff0000, v90
	v_and_b32_e32 v38, 0xffff0000, v87
	v_and_b32_e32 v31, 0xffff0000, v77
	v_exp_f32_e32 v77, v36
	s_waitcnt vmcnt(22)
	v_lshlrev_b32_e32 v37, 16, v73
	v_mul_f32_e32 v47, v46, v20
	v_fmac_f32_e32 v45, v23, v44
	v_mul_f32_e32 v41, v40, v23
	ds_bpermute_b32 v20, v197, v53
	v_and_b32_e32 v49, 0xffff0000, v88
	v_and_b32_e32 v39, 0xffff0000, v85
	v_and_b32_e32 v30, 0xffff0000, v79
	v_and_b32_e32 v36, 0xffff0000, v75
	v_exp_f32_e32 v75, v37
	v_mul_f32_e32 v60, v21, v47
	v_fmac_f32_e32 v48, v29, v45
	v_mul_f32_e32 v56, v29, v41
	v_fmac_f32_e32 v38, 0, v32
	v_and_b32_e32 v42, 0xffff0000, v83
	v_mul_f32_e32 v61, v22, v60
	v_fmac_f32_e32 v49, v33, v48
	v_mul_f32_e32 v57, v33, v56
	v_fmac_f32_e32 v39, v54, v38
	v_mul_f32_e32 v33, v32, v54
	v_fmac_f32_e32 v30, 0, v28
	v_and_b32_e32 v43, 0xffff0000, v81
	v_and_b32_e32 v37, 0xffff0000, v73
	v_fmac_f32_e32 v42, v55, v39
	v_mul_f32_e32 v54, v55, v33
	v_fmac_f32_e32 v31, v59, v30
	v_mul_f32_e32 v29, v28, v59
	ds_bpermute_b32 v73, v197, v61
	v_fmac_f32_e32 v43, v58, v42
	v_mul_f32_e32 v55, v58, v54
	v_fmac_f32_e32 v36, v77, v31
	v_mul_f32_e32 v58, v77, v29
	v_fmac_f32_e32 v37, v75, v36
	v_mul_f32_e32 v59, v75, v58
	s_waitcnt lgkmcnt(1)
	v_cndmask_b32_e64 v75, v20, v53, s[38:39]
	v_cndmask_b32_e64 v77, v53, v20, s[38:39]
	ds_bpermute_b32 v20, v197, v57
	ds_bpermute_b32 v23, v197, v49
	s_waitcnt lgkmcnt(2)
	v_cndmask_b32_e64 v21, v73, v61, s[38:39]
	v_cndmask_b32_e64 v22, v61, v73, s[38:39]
	v_fmac_f32_e32 v75, 0, v21
	v_mul_f32_e32 v79, v61, v73
	v_fmac_f32_e32 v77, v22, v75
	s_waitcnt lgkmcnt(1)
	v_cndmask_b32_e64 v21, v20, v57, s[38:39]
	s_waitcnt lgkmcnt(0)
	v_cndmask_b32_e64 v81, v23, v49, s[38:39]
	v_cndmask_b32_e64 v83, v49, v23, s[38:39]
	ds_bpermute_b32 v22, v197, v55
	ds_bpermute_b32 v23, v197, v43
	v_cndmask_b32_e64 v20, v57, v20, s[38:39]
	v_mul_f32_e32 v85, v79, v21
	v_fmac_f32_e32 v81, v21, v77
	v_mul_f32_e32 v87, v20, v85
	v_fmac_f32_e32 v83, v20, v81
	ds_bpermute_b32 v21, v197, v59
	ds_bpermute_b32 v20, v197, v37
	s_waitcnt lgkmcnt(3)
	v_cndmask_b32_e64 v93, v22, v55, s[38:39]
	s_waitcnt lgkmcnt(2)
	v_cndmask_b32_e64 v88, v23, v43, s[38:39]
	v_cndmask_b32_e64 v22, v55, v22, s[38:39]
	v_cndmask_b32_e64 v90, v43, v23, s[38:39]
	v_mul_f32_e32 v92, v87, v93
	v_fmac_f32_e32 v88, v93, v83
	v_mul_f32_e32 v93, v22, v92
	v_fmac_f32_e32 v90, v22, v88
	s_waitcnt lgkmcnt(1)
	v_cndmask_b32_e64 v22, v21, v59, s[38:39]
	s_waitcnt lgkmcnt(0)
	v_cndmask_b32_e64 v94, v20, v37, s[38:39]
	v_mul_f32_e32 v95, v93, v22
	v_fmac_f32_e32 v94, v22, v90
	s_and_saveexec_b64 s[22:23], s[38:39]
	v_mul_f32_e32 v23, v94, v21
	v_mul_f32_e32 v22, v95, v21
	v_add_f32_e32 v23, v23, v20
	ds_write_b64 v71, v[22:23]
	s_or_b64 exec, exec, s[22:23]
	s_waitcnt lgkmcnt(0)
	s_barrier
	ds_read_b32 v23, v69
	s_and_b64 vcc, exec, s[40:41]
	s_cbranch_vccnz .LBB0_846
	s_add_i32 s0, s62, -1
	s_cmp_lt_u32 s0, 7
	s_mov_b32 s0, 0
	s_cbranch_scc1 .LBB0_843
	v_readlane_b32 s9, v254, 35
	s_add_i32 s9, s9, 0
	s_add_i32 s9, s9, 0x111c0
	s_and_b32 s0, s62, 0x7ffffff8
	v_lshl_add_u32 v96, v68, 3, s9
	s_mov_b32 s9, 0

.LBB0_846:
	v_cndmask_b32_e64 v21, v73, 1.0, s[38:39]
	v_cndmask_b32_e64 v20, v75, 0, s[38:39]
	v_cndmask_b32_e64 v73, v85, v79, s[38:39]
	v_cndmask_b32_e64 v22, v81, v77, s[38:39]
	v_cndmask_b32_e64 v77, v95, v93, s[38:39]
	v_cndmask_b32_e64 v90, v94, v90, s[38:39]
	s_waitcnt lgkmcnt(0)
	v_fmac_f32_e32 v20, v21, v23
	v_cndmask_b32_e64 v75, v92, v87, s[38:39]
	v_cndmask_b32_e64 v88, v88, v83, s[38:39]
	v_pk_fma_f32 v[46:47], v[46:47], v[20:21], v[50:51] op_sel_hi:[1,0,1]
	v_fmac_f32_e32 v22, v73, v23
	v_fmac_f32_e32 v90, v77, v23
	v_pk_fma_f32 v[50:51], v[60:61], v[20:21], v[52:53] op_sel_hi:[1,0,1]
	v_pk_fma_f32 v[40:41], v[40:41], v[22:23], v[44:45] op_sel_hi:[1,0,1]
	v_pk_fma_f32 v[44:45], v[56:57], v[22:23], v[48:49] op_sel_hi:[1,0,1]
	v_fmac_f32_e32 v88, v75, v23
	s_waitcnt vmcnt(17)
	v_pk_fma_f32 v[22:23], v[28:29], v[90:91], v[30:31] op_sel_hi:[1,0,1]
	v_cvt_pk_bf16_f32 v28, v46, v47
	ds_write_b16 v72, v28
	ds_write_b16_d16_hi v72, v28 offset:144
	v_cvt_pk_bf16_f32 v28, v50, v51
	ds_write_b16 v72, v28 offset:288
	ds_write_b16_d16_hi v72, v28 offset:432
	v_cvt_pk_bf16_f32 v28, v40, v41
	s_waitcnt vmcnt(16)
	v_pk_fma_f32 v[32:33], v[32:33], v[88:89], v[38:39] op_sel_hi:[1,0,1]
	ds_write_b16 v72, v28 offset:1152
	ds_write_b16_d16_hi v72, v28 offset:1296
	v_cvt_pk_bf16_f32 v28, v44, v45
	v_pk_fma_f32 v[38:39], v[54:55], v[88:89], v[42:43] op_sel_hi:[1,0,1]
	v_pk_fma_f32 v[20:21], v[58:59], v[90:91], v[36:37] op_sel_hi:[1,0,1]
	ds_write_b16 v72, v28 offset:1440
	ds_write_b16_d16_hi v72, v28 offset:1584
	v_cvt_pk_bf16_f32 v28, v32, v33
	ds_write_b16 v72, v28 offset:2304
	ds_write_b16_d16_hi v72, v28 offset:2448
	v_cvt_pk_bf16_f32 v28, v38, v39
	v_cvt_pk_bf16_f32 v22, v22, v23
	v_cvt_pk_bf16_f32 v20, v20, v21
	ds_write_b16 v72, v28 offset:2592
	ds_write_b16_d16_hi v72, v28 offset:2736
	ds_write_b16 v72, v22 offset:3456
	ds_write_b16_d16_hi v72, v22 offset:3600
	ds_write_b16 v72, v20 offset:3744
	ds_write_b16_d16_hi v72, v20 offset:3888
	s_waitcnt lgkmcnt(0)
	s_barrier
	s_and_saveexec_b64 s[22:23], s[2:3]
	ds_write_b32 v69, v21
	s_or_b64 exec, exec, s[22:23]
	ds_read_b128 v[28:31], v70
	v_lshlrev_b32_e32 v32, 16, v16
	v_and_b32_e32 v33, 0xffff0000, v16
	v_mad_u64_u32 v[20:21], s[22:23], v34, s5, v[24:25]
	s_waitcnt lgkmcnt(0)
	v_lshlrev_b32_e32 v22, 16, v28
	v_and_b32_e32 v23, 0xffff0000, v28
	v_pk_mul_f32 v[22:23], v[32:33], v[22:23]
	v_lshlrev_b32_e32 v28, 16, v17
	v_cvt_pk_bf16_f32 v16, v22, v23
	v_lshlrev_b32_e32 v22, 16, v29
	v_and_b32_e32 v23, 0xffff0000, v29
	v_and_b32_e32 v29, 0xffff0000, v17
	v_pk_mul_f32 v[22:23], v[28:29], v[22:23]
	v_lshlrev_b32_e32 v28, 16, v18
	v_cvt_pk_bf16_f32 v17, v22, v23
	v_lshlrev_b32_e32 v22, 16, v30
	v_and_b32_e32 v23, 0xffff0000, v30
	v_and_b32_e32 v29, 0xffff0000, v18
	v_pk_mul_f32 v[22:23], v[28:29], v[22:23]
	v_lshlrev_b32_e32 v28, 16, v19
	v_cvt_pk_bf16_f32 v18, v22, v23
	v_lshlrev_b32_e32 v22, 16, v31
	v_and_b32_e32 v23, 0xffff0000, v31
	v_and_b32_e32 v29, 0xffff0000, v19
	v_pk_mul_f32 v[22:23], v[28:29], v[22:23]
	v_mad_i32_i24 v21, v35, s5, v21
	v_cvt_pk_bf16_f32 v19, v22, v23
	global_store_dwordx4 v[20:21], v[16:19], off sc1
	ds_read_b128 v[16:19], v70 offset:9216
	v_lshlrev_b32_e32 v28, 16, v8
	v_and_b32_e32 v29, 0xffff0000, v8
	s_mov_b32 s0, 0x30000
	s_waitcnt lgkmcnt(0)
	v_lshlrev_b32_e32 v22, 16, v16
	v_and_b32_e32 v23, 0xffff0000, v16
	v_pk_mul_f32 v[22:23], v[28:29], v[22:23]
	v_lshlrev_b32_e32 v16, 16, v17
	v_cvt_pk_bf16_f32 v8, v22, v23
	v_and_b32_e32 v17, 0xffff0000, v17
	v_lshlrev_b32_e32 v22, 16, v9
	v_and_b32_e32 v23, 0xffff0000, v9
	v_pk_mul_f32 v[16:17], v[22:23], v[16:17]
	v_lshlrev_b32_e32 v22, 16, v10
	v_cvt_pk_bf16_f32 v9, v16, v17
	v_lshlrev_b32_e32 v16, 16, v18
	v_and_b32_e32 v17, 0xffff0000, v18
	v_and_b32_e32 v23, 0xffff0000, v10
	v_pk_mul_f32 v[16:17], v[22:23], v[16:17]
	v_lshlrev_b32_e32 v18, 16, v11
	v_cvt_pk_bf16_f32 v10, v16, v17
	v_lshlrev_b32_e32 v16, 16, v19
	v_and_b32_e32 v17, 0xffff0000, v19
	v_and_b32_e32 v19, 0xffff0000, v11
	v_pk_mul_f32 v[16:17], v[18:19], v[16:17]
	s_nop 0
	v_cvt_pk_bf16_f32 v11, v16, v17
	v_add_co_u32_e32 v16, vcc, s0, v20
	s_nop 1
	v_addc_co_u32_e32 v17, vcc, 0, v21, vcc
	global_store_dwordx4 v[16:17], v[8:11], off sc1
	s_nop 1
	v_lshlrev_b32_e32 v8, 16, v91
	s_waitcnt vmcnt(13)
	v_lshlrev_b32_e32 v16, 16, v78
	v_exp_f32_e32 v36, v8
	v_lshlrev_b32_e32 v8, 16, v89
	v_exp_f32_e32 v17, v16
	s_waitcnt vmcnt(12)
	v_lshlrev_b32_e32 v16, 16, v76
	v_exp_f32_e32 v8, v8
	v_lshlrev_b32_e32 v9, 16, v86
	v_exp_f32_e32 v21, v16
	s_waitcnt vmcnt(11)
	v_lshlrev_b32_e32 v16, 16, v74
	v_exp_f32_e32 v9, v9
	v_lshlrev_b32_e32 v10, 16, v84
	v_lshlrev_b32_e32 v11, 16, v82
	v_exp_f32_e32 v20, v16
	s_waitcnt vmcnt(10)
	v_lshlrev_b32_e32 v16, 16, v67
	v_and_b32_e32 v40, 0xffff0000, v91
	v_exp_f32_e32 v10, v10
	v_exp_f32_e32 v30, v11
	v_lshlrev_b32_e32 v11, 16, v80
	v_exp_f32_e32 v44, v16
	s_waitcnt vmcnt(9)
	v_lshlrev_b32_e32 v16, 16, v66
	v_and_b32_e32 v41, 0xffff0000, v89
	v_exp_f32_e32 v11, v11
	v_exp_f32_e32 v45, v16
	s_waitcnt vmcnt(8)
	v_lshlrev_b32_e32 v16, 16, v65
	v_fmac_f32_e32 v40, 0, v36
	v_and_b32_e32 v42, 0xffff0000, v86
	v_exp_f32_e32 v48, v16
	s_waitcnt vmcnt(7)
	v_lshlrev_b32_e32 v16, 16, v64
	v_fmac_f32_e32 v41, v8, v40
	v_and_b32_e32 v43, 0xffff0000, v84
	v_and_b32_e32 v34, 0xffff0000, v82
	v_exp_f32_e32 v16, v16
	s_waitcnt vmcnt(6)
	v_lshlrev_b32_e32 v19, 16, v63
	v_fmac_f32_e32 v42, v9, v41
	v_and_b32_e32 v35, 0xffff0000, v80
	v_exp_f32_e32 v49, v19
	s_waitcnt vmcnt(5)
	v_lshlrev_b32_e32 v22, 16, v62
	v_fmac_f32_e32 v43, v10, v42
	v_fmac_f32_e32 v34, 0, v30
	v_and_b32_e32 v38, 0xffff0000, v78
	v_and_b32_e32 v28, 0xffff0000, v74
	v_exp_f32_e32 v52, v22
	s_waitcnt vmcnt(4)
	v_lshlrev_b32_e32 v23, 16, v2
	v_mul_f32_e32 v37, v36, v8
	v_fmac_f32_e32 v35, v11, v34
	v_mul_f32_e32 v31, v30, v11
	ds_bpermute_b32 v8, v197, v43
	v_and_b32_e32 v39, 0xffff0000, v76
	v_and_b32_e32 v29, 0xffff0000, v67
	v_and_b32_e32 v18, 0xffff0000, v64
	v_exp_f32_e32 v53, v23
	v_mul_f32_e32 v50, v9, v37
	v_fmac_f32_e32 v38, v17, v35
	v_mul_f32_e32 v46, v17, v31
	v_fmac_f32_e32 v28, 0, v20
	v_and_b32_e32 v32, 0xffff0000, v66
	v_and_b32_e32 v19, 0xffff0000, v63
	v_mul_f32_e32 v51, v10, v50
	v_fmac_f32_e32 v39, v21, v38
	v_mul_f32_e32 v47, v21, v46
	v_fmac_f32_e32 v29, v44, v28
	v_mul_f32_e32 v21, v20, v44
	v_fmac_f32_e32 v18, 0, v16
	v_and_b32_e32 v33, 0xffff0000, v65
	v_and_b32_e32 v22, 0xffff0000, v62
	v_and_b32_e32 v23, 0xffff0000, v2
	v_fmac_f32_e32 v32, v45, v29
	v_mul_f32_e32 v44, v45, v21
	v_fmac_f32_e32 v19, v49, v18
	v_mul_f32_e32 v17, v16, v49
	ds_bpermute_b32 v2, v197, v51
	v_fmac_f32_e32 v33, v48, v32
	v_mul_f32_e32 v45, v48, v44
	v_fmac_f32_e32 v22, v52, v19
	v_mul_f32_e32 v48, v52, v17
	v_fmac_f32_e32 v23, v53, v22
	v_mul_f32_e32 v49, v53, v48
	s_waitcnt lgkmcnt(1)
	v_cndmask_b32_e64 v52, v8, v43, s[38:39]
	v_cndmask_b32_e64 v53, v43, v8, s[38:39]
	ds_bpermute_b32 v8, v197, v47
	ds_bpermute_b32 v11, v197, v39
	s_waitcnt lgkmcnt(2)
	v_cndmask_b32_e64 v9, v2, v51, s[38:39]
	v_cndmask_b32_e64 v10, v51, v2, s[38:39]
	v_fmac_f32_e32 v52, 0, v9
	v_mul_f32_e32 v54, v51, v2
	v_fmac_f32_e32 v53, v10, v52
	s_waitcnt lgkmcnt(1)
	v_cndmask_b32_e64 v9, v8, v47, s[38:39]
	s_waitcnt lgkmcnt(0)
	v_cndmask_b32_e64 v55, v11, v39, s[38:39]
	v_cndmask_b32_e64 v56, v39, v11, s[38:39]
	ds_bpermute_b32 v10, v197, v45
	ds_bpermute_b32 v11, v197, v33
	v_cndmask_b32_e64 v8, v47, v8, s[38:39]
	v_mul_f32_e32 v57, v54, v9
	v_fmac_f32_e32 v55, v9, v53
	v_mul_f32_e32 v58, v8, v57
	v_fmac_f32_e32 v56, v8, v55
	ds_bpermute_b32 v9, v197, v49
	ds_bpermute_b32 v8, v197, v23
	s_waitcnt lgkmcnt(3)
	v_cndmask_b32_e64 v62, v10, v45, s[38:39]
	s_waitcnt lgkmcnt(2)
	v_cndmask_b32_e64 v59, v11, v33, s[38:39]
	v_cndmask_b32_e64 v10, v45, v10, s[38:39]
	v_cndmask_b32_e64 v60, v33, v11, s[38:39]
	v_mul_f32_e32 v61, v58, v62
	v_fmac_f32_e32 v59, v62, v56
	v_mul_f32_e32 v62, v10, v61
	v_fmac_f32_e32 v60, v10, v59
	s_waitcnt lgkmcnt(1)
	v_cndmask_b32_e64 v10, v9, v49, s[38:39]
	s_waitcnt lgkmcnt(0)
	v_cndmask_b32_e64 v63, v8, v23, s[38:39]
	v_mul_f32_e32 v64, v62, v10
	v_fmac_f32_e32 v63, v10, v60
	s_and_saveexec_b64 s[22:23], s[38:39]
	v_mul_f32_e32 v11, v63, v9
	v_mul_f32_e32 v10, v64, v9
	v_add_f32_e32 v11, v11, v8
	ds_write_b64 v71, v[10:11]
	s_or_b64 exec, exec, s[22:23]
	s_waitcnt lgkmcnt(0)
	s_barrier
	ds_read_b32 v11, v69
	s_and_b64 vcc, exec, s[40:41]
	s_cbranch_vccnz .LBB0_857
	s_add_i32 s0, s62, -1
	s_cmp_lt_u32 s0, 7
	s_mov_b32 s0, 0
	s_cbranch_scc1 .LBB0_854
	v_readlane_b32 s9, v254, 35
	s_add_i32 s9, s9, 0
	s_add_i32 s9, s9, 0x111c0
	s_and_b32 s0, s62, 0x7ffffff8
	v_lshl_add_u32 v65, v68, 3, s9
	s_mov_b32 s9, 0

.LBB0_860:
	s_or_b64 exec, exec, s[22:23]
	ds_read_b128 v[16:19], v70
	s_waitcnt vmcnt(3)
	v_lshlrev_b32_e32 v20, 16, v12
	v_and_b32_e32 v21, 0xffff0000, v12
	v_lshlrev_b32_e32 v12, 16, v13
	v_and_b32_e32 v13, 0xffff0000, v13
	s_waitcnt lgkmcnt(0)
	v_lshlrev_b32_e32 v10, 16, v16
	v_and_b32_e32 v11, 0xffff0000, v16
	v_lshlrev_b32_e32 v16, 16, v17
	v_and_b32_e32 v17, 0xffff0000, v17
	v_pk_mul_f32 v[10:11], v[20:21], v[10:11]
	v_pk_mul_f32 v[12:13], v[12:13], v[16:17]
	v_cvt_pk_bf16_f32 v10, v10, v11
	v_cvt_pk_bf16_f32 v11, v12, v13
	v_lshlrev_b32_e32 v12, 16, v18
	v_and_b32_e32 v13, 0xffff0000, v18
	v_lshlrev_b32_e32 v16, 16, v14
	v_and_b32_e32 v17, 0xffff0000, v14
	v_pk_mul_f32 v[12:13], v[16:17], v[12:13]
	v_lshlrev_b32_e32 v16, 16, v19
	v_and_b32_e32 v17, 0xffff0000, v19
	v_lshlrev_b32_e32 v14, 16, v15
	v_and_b32_e32 v15, 0xffff0000, v15
	v_mad_u64_u32 v[8:9], s[0:1], v26, s5, v[24:25]
	v_pk_mul_f32 v[14:15], v[14:15], v[16:17]
	v_mad_i32_i24 v9, v27, s5, v9
	v_cvt_pk_bf16_f32 v12, v12, v13
	v_cvt_pk_bf16_f32 v13, v14, v15
	global_store_dwordx4 v[8:9], v[10:13], off sc1
	ds_read_b128 v[10:13], v70 offset:9216
	s_waitcnt vmcnt(3)
	v_lshlrev_b32_e32 v16, 16, v4
	v_and_b32_e32 v17, 0xffff0000, v4
	s_mov_b32 s0, 0x30000
	s_bitcmp1_b32 s75, 0
	s_waitcnt lgkmcnt(0)
	v_lshlrev_b32_e32 v14, 16, v10
	v_and_b32_e32 v15, 0xffff0000, v10
	v_pk_mul_f32 v[14:15], v[16:17], v[14:15]
	v_lshlrev_b32_e32 v10, 16, v11
	v_cvt_pk_bf16_f32 v4, v14, v15
	v_and_b32_e32 v11, 0xffff0000, v11
	v_lshlrev_b32_e32 v14, 16, v5
	v_and_b32_e32 v15, 0xffff0000, v5
	v_pk_mul_f32 v[10:11], v[14:15], v[10:11]
	v_lshlrev_b32_e32 v14, 16, v6
	v_cvt_pk_bf16_f32 v5, v10, v11
	v_lshlrev_b32_e32 v10, 16, v12
	v_and_b32_e32 v11, 0xffff0000, v12
	v_and_b32_e32 v15, 0xffff0000, v6
	v_pk_mul_f32 v[10:11], v[14:15], v[10:11]
	v_add_co_u32_e32 v8, vcc, s0, v8
	s_cselect_b64 s[0:1], -1, 0
	s_cmpk_lt_i32 s75, 0x80
	v_cvt_pk_bf16_f32 v6, v10, v11
	v_lshlrev_b32_e32 v10, 16, v13
	v_and_b32_e32 v11, 0xffff0000, v13
	v_lshlrev_b32_e32 v12, 16, v7
	v_and_b32_e32 v13, 0xffff0000, v7
	s_cselect_b64 s[2:3], -1, 0
	v_pk_mul_f32 v[10:11], v[12:13], v[10:11]
	v_addc_co_u32_e32 v9, vcc, 0, v9, vcc
	s_and_b64 s[0:1], s[2:3], s[0:1]
	v_cvt_pk_bf16_f32 v7, v10, v11
	s_and_b64 vcc, exec, s[0:1]
	s_movk_i32 s96, 0x5000
	global_store_dwordx4 v[8:9], v[4:7], off sc1
	s_barrier
	s_cbranch_vccz .LBB0_868
	s_ashr_i32 s1, s75, 3
	s_lshl_b32 s22, s1, 6
	s_bfe_u32 s0, s75, 0x20001
	s_or_b32 s2, s34, s22
	v_and_b32_e32 v107, 31, v204
	v_readlane_b32 s4, v255, 10
	v_or_b32_e32 v104, s2, v107
	s_cmp_lt_i32 s4, 2
	v_bfe_u32 v110, v204, 5, 1
	v_mov_b32_e32 v117, 0
	s_cselect_b64 s[2:3], -1, 0
	s_cmp_gt_i32 s4, 1
	v_ashrrev_i32_e32 v105, 31, v104
	v_mov_b32_e32 v127, 0
	v_mov_b32_e32 v129, 0
	v_mov_b32_e32 v130, 0
	v_mov_b32_e32 v131, 0
	v_mov_b32_e32 v132, 0
	v_mov_b32_e32 v133, 0
	v_mov_b32_e32 v134, 0
	v_mov_b32_e32 v136, 0
	v_mov_b32_e32 v138, 0
	v_mov_b32_e32 v139, 0
	v_mov_b32_e32 v140, 0
	v_mov_b32_e32 v141, 0
	v_mov_b32_e32 v142, 0
	v_mov_b32_e32 v143, 0
	v_mov_b32_e32 v144, 0
	s_cbranch_scc1 .LBB0_863
	v_readlane_b32 s20, v254, 53
	s_add_i32 s4, s20, s22
	s_or_b32 s4, s34, s4
	v_or_b32_e32 v4, s4, v107
	v_ashrrev_i32_e32 v5, 31, v4
	v_readlane_b32 s40, v254, 46
	v_lshlrev_b64 v[4:5], 2, v[4:5]
	v_readlane_b32 s42, v254, 48
	v_readlane_b32 s43, v254, 49
	v_readlane_b32 s4, v254, 41
	v_readlane_b32 s21, v254, 54
	v_lshl_add_u64 v[6:7], s[42:43], 0, v[4:5]
	global_load_dword v60, v[6:7], off
	s_add_i32 s20, s4, s1
	s_lshl_b32 s1, s0, 5
	s_ashr_i32 s21, s20, 31
	v_lshl_or_b32 v88, v110, 2, s1
	s_lshl_b64 s[20:21], s[20:21], 6
	v_mov_b32_e32 v8, 0x4800
	v_mad_u32_u24 v14, v88, s16, v8
	v_or_b32_e32 v8, s20, v107
	v_mov_b32_e32 v19, s21
	v_readlane_b32 s20, v254, 44
	v_mov_b32_e32 v7, v3
	v_mul_u32_u24_e32 v6, 0x1800, v88
	v_readlane_b32 s21, v254, 45
	v_lshlrev_b64 v[12:13], 1, v[104:105]
	v_lshl_add_u64 v[6:7], s[54:55], 0, v[6:7]
	v_or_b32_e32 v18, s34, v8
	v_lshl_add_u64 v[24:25], s[20:21], 0, v[4:5]
	v_readlane_b32 s20, v254, 42
	v_lshrrev_b32_e32 v2, 1, v204
	v_readlane_b32 s28, v253, 11
	v_lshl_add_u64 v[16:17], v[6:7], 0, v[12:13]
	v_lshlrev_b64 v[6:7], 7, v[18:19]
	v_readlane_b32 s21, v254, 43
	v_readlane_b32 s41, v254, 47
	v_readlane_b32 s29, v253, 12
	v_and_b32_e32 v2, 16, v2
	v_lshl_add_u64 v[6:7], s[20:21], 0, v[6:7]
	v_readlane_b32 s1, v255, 8
	s_load_dwordx2 s[28:29], s[28:29], 0x20
	v_lshl_add_u64 v[4:5], s[40:41], 0, v[4:5]
	global_load_dword v137, v[24:25], off
	global_load_dword v135, v[4:5], off
	v_lshl_add_u64 v[24:25], v[6:7], 0, v[2:3]
	v_or_b32_e32 v2, s1, v88
	s_mov_b32 s1, 0x20000
	v_mov_b32_e32 v23, v3
	v_add_co_u32_e32 v26, vcc, s1, v24
	v_or_b32_e32 v22, 8, v2
	v_mov_b32_e32 v9, v3
	v_mov_b32_e32 v11, v3
	v_or_b32_e32 v8, 1, v2
	v_or_b32_e32 v10, 2, v2
	v_addc_co_u32_e32 v27, vcc, 0, v25, vcc
	v_lshlrev_b64 v[32:33], 12, v[22:23]
	s_mov_b32 s1, 0xbfb8aa3b
	global_load_dwordx4 v[4:7], v[24:25], off
	global_load_dwordx4 v[52:55], v[24:25], off offset:32
	global_load_dwordx4 v[48:51], v[24:25], off offset:64
	global_load_dwordx4 v[44:47], v[24:25], off offset:96
	v_lshlrev_b64 v[24:25], 12, v[8:9]
	v_lshlrev_b64 v[30:31], 12, v[10:11]
	global_load_dwordx4 v[8:11], v[26:27], off
	global_load_dwordx4 v[56:59], v[26:27], off offset:32
	global_load_dwordx4 v[40:43], v[26:27], off offset:64
	global_load_dwordx4 v[36:39], v[26:27], off offset:96
	v_mov_b32_e32 v21, v3
	v_or_b32_e32 v20, 3, v2
	s_waitcnt lgkmcnt(0)
	v_lshl_add_u64 v[18:19], v[104:105], 2, s[28:29]
	v_lshlrev_b64 v[20:21], 12, v[20:21]
	v_lshl_add_u64 v[34:35], v[18:19], 0, v[20:21]
	v_lshlrev_b64 v[28:29], 12, v[2:3]
	v_mov_b32_e32 v63, v3
	v_or_b32_e32 v66, 10, v2
	v_mov_b32_e32 v67, v3
	v_or_b32_e32 v70, 11, v2
	v_mov_b32_e32 v71, v3
	v_lshl_add_u64 v[28:29], v[18:19], 0, v[28:29]
	v_lshlrev_b64 v[66:67], 12, v[66:67]
	v_lshlrev_b64 v[70:71], 12, v[70:71]
	v_lshl_add_u64 v[30:31], v[18:19], 0, v[30:31]
	v_lshl_add_u64 v[32:33], v[18:19], 0, v[32:33]
	v_lshl_add_u64 v[66:67], v[18:19], 0, v[66:67]
	v_lshl_add_u64 v[70:71], v[18:19], 0, v[70:71]
	v_or_b32_e32 v74, 24, v2
	v_or_b32_e32 v78, 25, v2
	v_or_b32_e32 v82, 26, v2
	v_mov_b32_e32 v75, v3
	v_mov_b32_e32 v79, v3
	v_mov_b32_e32 v83, v3
	v_mov_b32_e32 v15, v3
	v_mad_u32_u24 v64, v88, s16, v244
	v_mov_b32_e32 v65, v3
	v_mov_b32_e32 v69, v3
	v_mov_b32_e32 v73, v3
	s_waitcnt vmcnt(10)
	v_mul_f32_e32 v22, 0xbfb8aa3b, v60
	v_fma_f32 v23, v60, s1, -v22
	v_rndne_f32_e32 v26, v22
	v_fmac_f32_e32 v23, 0xb2a5705f, v60
	v_sub_f32_e32 v22, v22, v26
	v_add_f32_e32 v22, v22, v23
	v_cvt_i32_f32_e32 v61, v26
	v_exp_f32_e32 v22, v22
	s_mov_b32 s1, 0x42ce8ed0
	v_cmp_nlt_f32_e32 vcc, s1, v60
	s_mov_b32 s1, 0xc2b17218
	v_ldexp_f32 v20, v22, v61
	v_cndmask_b32_e32 v20, 0, v20, vcc
	v_cmp_ngt_f32_e32 vcc, s1, v60
	v_lshl_add_u64 v[26:27], v[18:19], 0, v[24:25]
	s_mov_b32 s1, 0x3f2aaaab
	v_cndmask_b32_e32 v90, v243, v20, vcc
	v_add_f32_e32 v22, 1.0, v90
	v_add_f32_e32 v23, -1.0, v22
	v_frexp_mant_f32_e32 v24, v22
	v_cvt_f64_f32_e32 v[20:21], v22
	v_sub_f32_e32 v25, v23, v22
	v_frexp_exp_i32_f64_e32 v20, v[20:21]
	v_cmp_gt_f32_e32 vcc, s1, v24
	v_sub_f32_e32 v23, v90, v23
	v_add_f32_e32 v21, 1.0, v25
	v_subbrev_co_u32_e32 v91, vcc, 0, v20, vcc
	v_add_f32_e32 v20, v23, v21
	v_sub_u32_e32 v21, 0, v91
	v_ldexp_f32 v22, v22, v21
	v_add_f32_e32 v23, -1.0, v22
	v_add_f32_e32 v24, 1.0, v22
	v_ldexp_f32 v20, v20, v21
	v_add_f32_e32 v21, 1.0, v23
	v_add_f32_e32 v25, -1.0, v24
	v_sub_f32_e32 v21, v22, v21
	v_sub_f32_e32 v22, v22, v25
	v_add_f32_e32 v25, v20, v21
	v_add_f32_e32 v20, v20, v22
	v_add_f32_e32 v60, v24, v20
	v_rcp_f32_e32 v92, v60
	v_add_f32_e32 v21, v23, v25
	v_sub_f32_e32 v22, v24, v60
	v_add_f32_e32 v61, v20, v22
	v_mul_f32_e32 v93, v21, v92
	v_mul_f32_e32 v24, v60, v93
	v_fma_f32 v22, v93, v60, -v24
	v_fmac_f32_e32 v22, v93, v61
	v_sub_f32_e32 v23, v23, v21
	v_add_f32_e32 v20, v24, v22
	v_add_f32_e32 v62, v25, v23
	v_sub_f32_e32 v25, v21, v20
	v_mov_b32_e32 v23, v20
	v_pk_add_f32 v[20:21], v[20:21], v[24:25] neg_lo:[0,1] neg_hi:[0,1]
	v_lshlrev_b64 v[74:75], 12, v[74:75]
	v_pk_add_f32 v[20:21], v[20:21], v[22:23] neg_lo:[0,1] neg_hi:[0,1]
	v_mov_b32_e32 v77, v3
	v_add_f32_e32 v21, v62, v21
	v_add_f32_e32 v21, v20, v21
	v_add_f32_e32 v23, v25, v21
	v_sub_f32_e32 v22, v25, v23
	v_or_b32_e32 v62, 9, v2
	v_mov_b32_e32 v25, 0xf000
	v_lshlrev_b64 v[62:63], 12, v[62:63]
	v_mad_u32_u24 v68, v88, s16, v25
	v_mov_b32_e32 v25, 0x10800
	v_lshl_add_u64 v[62:63], v[18:19], 0, v[62:63]
	global_load_dword v125, v[28:29], off
	global_load_dword v123, v[26:27], off
	global_load_dword v121, v[30:31], off
	global_load_dword v119, v[34:35], off
	global_load_dword v116, v[32:33], off
	global_load_dword v114, v[62:63], off
	global_load_dword v112, v[66:67], off
	global_load_dword v111, v[70:71], off
	v_mad_u32_u24 v26, v88, s16, v25
	v_mov_b32_e32 v25, 0x19800
	v_mad_u32_u24 v34, v88, s16, v25
	v_mov_b32_e32 v25, 0x1b000
	v_mad_u32_u24 v66, v88, s16, v25
	v_mov_b32_e32 v25, 0x1c800
	v_mul_f32_e32 v94, v92, v23
	v_mad_u32_u24 v72, v88, s16, v25
	v_mov_b32_e32 v25, 0x24000
	v_mul_f32_e32 v20, v60, v94
	v_or_b32_e32 v28, 16, v2
	v_or_b32_e32 v32, 17, v2
	v_or_b32_e32 v62, 18, v2
	v_or_b32_e32 v70, 19, v2
	v_mad_u32_u24 v76, v88, s16, v25
	v_mov_b32_e32 v25, 0x25800
	v_or_b32_e32 v2, 27, v2
	v_fma_f32 v24, v94, v60, -v20
	v_mov_b32_e32 v29, v3
	v_mov_b32_e32 v33, v3
	v_mov_b32_e32 v63, v3
	v_mov_b32_e32 v71, v3
	v_mad_u32_u24 v80, v88, s16, v25
	v_mov_b32_e32 v25, 0x27000
	v_lshlrev_b64 v[86:87], 12, v[2:3]
	v_mov_b32_e32 v2, 0x28800
	v_fmac_f32_e32 v24, v94, v61
	v_mad_u32_u24 v60, v88, s16, v242
	v_mov_b32_e32 v61, v3
	v_mov_b32_e32 v27, v3
	v_lshlrev_b64 v[28:29], 12, v[28:29]
	v_mad_u32_u24 v30, v88, s16, v241
	v_mov_b32_e32 v31, v3
	v_lshlrev_b64 v[32:33], 12, v[32:33]
	v_mov_b32_e32 v35, v3
	v_lshlrev_b64 v[62:63], 12, v[62:63]
	v_mov_b32_e32 v67, v3
	v_lshlrev_b64 v[70:71], 12, v[70:71]
	v_lshlrev_b64 v[78:79], 12, v[78:79]
	v_mov_b32_e32 v81, v3
	v_lshlrev_b64 v[82:83], 12, v[82:83]
	v_mad_u32_u24 v84, v88, s16, v25
	v_mov_b32_e32 v85, v3
	v_mad_u32_u24 v2, v88, s16, v2
	v_lshl_add_u64 v[14:15], s[54:55], 0, v[14:15]
	v_lshl_add_u64 v[60:61], s[54:55], 0, v[60:61]
	v_lshl_add_u64 v[64:65], s[54:55], 0, v[64:65]
	v_lshl_add_u64 v[68:69], s[54:55], 0, v[68:69]
	v_lshl_add_u64 v[26:27], s[54:55], 0, v[26:27]
	v_lshl_add_u64 v[28:29], v[18:19], 0, v[28:29]
	v_lshl_add_u64 v[30:31], s[54:55], 0, v[30:31]
	v_lshl_add_u64 v[32:33], v[18:19], 0, v[32:33]
	v_lshl_add_u64 v[34:35], s[54:55], 0, v[34:35]
	v_lshl_add_u64 v[62:63], v[18:19], 0, v[62:63]
	v_lshl_add_u64 v[66:67], s[54:55], 0, v[66:67]
	v_lshl_add_u64 v[70:71], v[18:19], 0, v[70:71]
	v_lshl_add_u64 v[72:73], s[54:55], 0, v[72:73]
	v_lshl_add_u64 v[74:75], v[18:19], 0, v[74:75]
	v_lshl_add_u64 v[76:77], s[54:55], 0, v[76:77]
	v_lshl_add_u64 v[78:79], v[18:19], 0, v[78:79]
	v_lshl_add_u64 v[80:81], s[54:55], 0, v[80:81]
	v_lshl_add_u64 v[82:83], v[18:19], 0, v[82:83]
	v_lshl_add_u64 v[84:85], s[54:55], 0, v[84:85]
	v_lshl_add_u64 v[18:19], v[18:19], 0, v[86:87]
	v_lshl_add_u64 v[86:87], s[54:55], 0, v[2:3]
	s_mov_b32 s4, 0x6000000
	v_lshl_add_u64 v[14:15], v[14:15], 0, v[12:13]
	v_lshl_add_u64 v[60:61], v[60:61], 0, v[12:13]
	v_lshl_add_u64 v[64:65], v[64:65], 0, v[12:13]
	v_lshl_add_u64 v[68:69], v[68:69], 0, v[12:13]
	v_lshl_add_u64 v[26:27], v[26:27], 0, v[12:13]
	v_lshl_add_u64 v[30:31], v[30:31], 0, v[12:13]
	v_lshl_add_u64 v[34:35], v[34:35], 0, v[12:13]
	v_lshl_add_u64 v[66:67], v[66:67], 0, v[12:13]
	v_lshl_add_u64 v[72:73], v[72:73], 0, v[12:13]
	v_lshl_add_u64 v[76:77], v[76:77], 0, v[12:13]
	v_lshl_add_u64 v[80:81], v[80:81], 0, v[12:13]
	v_lshl_add_u64 v[84:85], v[84:85], 0, v[12:13]
	v_lshl_add_u64 v[12:13], v[86:87], 0, v[12:13]
	v_add_co_u32_e32 v86, vcc, s4, v16
	s_mov_b32 s1, 0x6002000
	s_nop 0
	v_addc_co_u32_e32 v87, vcc, 0, v17, vcc
	v_add_co_u32_e32 v88, vcc, s1, v16
	s_mov_b32 s1, 0x6003000
	s_nop 0
	v_addc_co_u32_e32 v89, vcc, 0, v17, vcc
	v_add_co_u32_e32 v16, vcc, s1, v16
	v_add_f32_e32 v95, v21, v22
	s_nop 0
	v_addc_co_u32_e32 v17, vcc, 0, v17, vcc
	v_add_co_u32_e32 v14, vcc, s4, v14
	v_add_f32_e32 v22, v20, v24
	s_nop 0
	v_addc_co_u32_e32 v15, vcc, 0, v15, vcc
	v_add_co_u32_e32 v60, vcc, s4, v60
	v_sub_f32_e32 v21, v23, v22
	s_nop 0
	v_addc_co_u32_e32 v61, vcc, 0, v61, vcc
	v_add_co_u32_e32 v64, vcc, s4, v64
	v_mov_b32_e32 v25, v22
	s_nop 0
	v_addc_co_u32_e32 v65, vcc, 0, v65, vcc
	v_add_co_u32_e32 v68, vcc, s4, v68
	s_mov_b32 s1, 0x3f317218
	s_nop 0
	v_addc_co_u32_e32 v69, vcc, 0, v69, vcc
	v_add_co_u32_e32 v26, vcc, s4, v26
	s_nop 1
	v_addc_co_u32_e32 v27, vcc, 0, v27, vcc
	global_load_ushort v2, v[86:87], off offset:2048
	s_nop 0
	global_load_ushort v86, v[88:89], off
	global_load_ushort v87, v[16:17], off offset:2048
	s_nop 0
	global_load_ushort v88, v[14:15], off offset:2048
	global_load_ushort v89, v[60:61], off offset:2048
	global_load_ushort v96, v[64:65], off offset:2048
	s_nop 0
	global_load_ushort v68, v[68:69], off offset:2048
	s_nop 0
	global_load_ushort v69, v[26:27], off offset:2048
	v_add_co_u32_e32 v14, vcc, s4, v30
	s_waitcnt vmcnt(7)
	v_lshlrev_b32_e32 v144, 16, v2
	v_addc_co_u32_e32 v15, vcc, 0, v31, vcc
	v_add_co_u32_e32 v16, vcc, s4, v34
	s_waitcnt vmcnt(6)
	v_lshlrev_b32_e32 v143, 16, v86
	v_addc_co_u32_e32 v17, vcc, 0, v35, vcc
	v_add_co_u32_e32 v26, vcc, s4, v66
	s_waitcnt vmcnt(4)
	v_lshlrev_b32_e32 v141, 16, v88
	v_addc_co_u32_e32 v27, vcc, 0, v67, vcc
	v_add_co_u32_e32 v30, vcc, s4, v72
	v_lshlrev_b32_e32 v142, 16, v87
	s_nop 0
	v_addc_co_u32_e32 v31, vcc, 0, v73, vcc
	v_add_co_u32_e32 v34, vcc, s4, v76
	s_waitcnt vmcnt(2)
	v_lshlrev_b32_e32 v139, 16, v96
	v_addc_co_u32_e32 v35, vcc, 0, v77, vcc
	v_add_co_u32_e32 v60, vcc, s4, v80
	v_lshlrev_b32_e32 v140, 16, v89
	s_nop 0
	v_addc_co_u32_e32 v61, vcc, 0, v81, vcc
	v_add_co_u32_e32 v64, vcc, s4, v84
	s_waitcnt vmcnt(0)
	v_lshlrev_b32_e32 v136, 16, v69
	v_addc_co_u32_e32 v65, vcc, 0, v85, vcc
	v_add_co_u32_e32 v12, vcc, s4, v12
	v_lshlrev_b32_e32 v138, 16, v68
	s_nop 0
	v_addc_co_u32_e32 v13, vcc, 0, v13, vcc
	global_load_ushort v66, v[14:15], off offset:2048
	global_load_ushort v67, v[16:17], off offset:2048
	s_nop 0
	global_load_ushort v26, v[26:27], off offset:2048
	s_nop 0
	global_load_ushort v27, v[30:31], off offset:2048
	s_nop 0
	global_load_ushort v30, v[34:35], off offset:2048
	global_load_ushort v31, v[60:61], off offset:2048
	s_nop 0
	global_load_ushort v34, v[64:65], off offset:2048
	global_load_ushort v35, v[12:13], off offset:2048
	global_load_dword v128, v[28:29], off
	global_load_dword v126, v[32:33], off
	global_load_dword v124, v[62:63], off
	global_load_dword v122, v[70:71], off
	global_load_dword v120, v[74:75], off
	global_load_dword v118, v[78:79], off
	global_load_dword v115, v[82:83], off
	global_load_dword v113, v[18:19], off
	v_pk_add_f32 v[12:13], v[22:23], v[20:21] neg_lo:[0,1] neg_hi:[0,1]
	s_waitcnt vmcnt(15)
	v_lshlrev_b32_e32 v134, 16, v66
	v_pk_add_f32 v[12:13], v[12:13], v[24:25] neg_lo:[0,1] neg_hi:[0,1]
	s_waitcnt vmcnt(14)
	v_lshlrev_b32_e32 v133, 16, v67
	v_add_f32_e32 v13, v95, v13
	v_add_f32_e32 v12, v12, v13
	v_add_f32_e32 v13, v93, v94
	v_add_f32_e32 v12, v21, v12
	v_sub_f32_e32 v14, v13, v93
	v_mul_f32_e32 v12, v92, v12
	v_sub_f32_e32 v14, v94, v14
	v_add_f32_e32 v14, v14, v12
	v_add_f32_e32 v16, v13, v14
	v_mul_f32_e32 v17, v16, v16
	v_fmamk_f32 v12, v17, 0x3e9b6dac, v233
	v_fmaak_f32 v197, v17, v12, 0x3f2aaada
	v_cvt_f32_i32_e32 v12, v91
	v_sub_f32_e32 v13, v16, v13
	v_sub_f32_e32 v13, v14, v13
	v_ldexp_f32 v18, v13, 1
	v_mul_f32_e32 v13, v16, v17
	v_ldexp_f32 v15, v16, 1
	v_pk_mul_f32 v[16:17], v[12:13], v[196:197]
	s_waitcnt vmcnt(12)
	v_lshlrev_b32_e32 v131, 16, v27
	v_fma_f32 v14, v12, s1, -v16
	v_fmac_f32_e32 v14, 0xb102e308, v12
	v_pk_add_f32 v[12:13], v[16:17], v[14:15]
	s_mov_b32 s1, 0x7f800000
	v_sub_f32_e32 v15, v13, v15
	v_sub_f32_e32 v15, v17, v15
	v_add_f32_e32 v19, v18, v15
	v_mov_b32_e32 v18, v16
	v_pk_add_f32 v[16:17], v[12:13], v[16:17] neg_lo:[0,1] neg_hi:[0,1]
	v_pk_add_f32 v[20:21], v[12:13], v[18:19]
	v_mov_b32_e32 v15, v12
	v_mov_b32_e32 v17, v21
	v_pk_add_f32 v[22:23], v[14:15], v[16:17] neg_lo:[0,1] neg_hi:[0,1]
	v_pk_add_f32 v[14:15], v[14:15], v[16:17]
	v_mov_b32_e32 v18, v19
	v_pk_add_f32 v[16:17], v[14:15], v[12:13] op_sel:[1,0] op_sel_hi:[0,1] neg_lo:[0,1] neg_hi:[0,1]
	v_pk_add_f32 v[24:25], v[20:21], v[16:17] op_sel_hi:[1,0] neg_lo:[0,1] neg_hi:[0,1]
	v_mov_b32_e32 v20, v21
	v_mov_b32_e32 v21, v15
	v_pk_mov_b32 v[16:17], v[12:13], v[16:17] op_sel:[1,0]
	v_mov_b32_e32 v19, v12
	v_pk_add_f32 v[16:17], v[20:21], v[16:17] neg_lo:[0,1] neg_hi:[0,1]
	v_mov_b32_e32 v24, v22
	v_pk_add_f32 v[12:13], v[18:19], v[16:17] neg_lo:[0,1] neg_hi:[0,1]
	v_mov_b32_e32 v23, v15
	v_pk_add_f32 v[16:17], v[24:25], v[12:13]
	v_cmp_neq_f32_e32 vcc, s1, v90
	v_pk_add_f32 v[18:19], v[16:17], v[16:17] op_sel:[0,1] op_sel_hi:[1,0]
	s_mov_b32 s1, 0x33800000
	v_pk_add_f32 v[14:15], v[14:15], v[18:19] op_sel:[1,0] op_sel_hi:[0,1]
	v_mov_b32_e32 v17, v14
	v_pk_add_f32 v[20:21], v[16:17], v[22:23] neg_lo:[0,1] neg_hi:[0,1]
	v_mov_b32_e32 v13, v18
	v_sub_f32_e32 v15, v16, v20
	v_pk_add_f32 v[12:13], v[12:13], v[20:21] neg_lo:[0,1] neg_hi:[0,1]
	v_sub_f32_e32 v15, v22, v15
	v_add_f32_e32 v12, v12, v15
	v_add_f32_e32 v12, v12, v13
	v_add_f32_e32 v12, v14, v12
	v_cndmask_b32_e32 v12, v243, v12, vcc
	v_cmp_lt_f32_e64 vcc, |v90|, s1
	v_lshlrev_b32_e32 v132, 16, v26
	s_waitcnt vmcnt(10)
	v_lshlrev_b32_e32 v129, 16, v31
	v_cndmask_b32_e32 v12, v12, v90, vcc
	v_mul_f32_e32 v106, 0xc138aa3b, v12
	v_lshlrev_b32_e32 v130, 16, v30
	s_waitcnt vmcnt(8)
	v_lshlrev_b32_e32 v117, 16, v35
	v_lshlrev_b32_e32 v127, 16, v34
.LBB0_863:
	s_movk_i32 s1, 0x100
	v_cmp_gt_i32_e32 vcc, s1, v204
	s_and_saveexec_b64 s[20:21], vcc
	s_cbranch_execz .LBB0_865
	v_readlane_b32 s34, v253, 11
	v_readlane_b32 s35, v253, 12
	s_load_dwordx2 s[28:29], s[34:35], 0x28
	v_ashrrev_i32_e32 v145, 3, v204
	v_lshl_add_u32 v14, s0, 5, v145
	v_readlane_b32 s1, v255, 8
	s_ashr_i32 s23, s22, 31
	s_waitcnt lgkmcnt(0)
	v_mov_b64_e32 v[12:13], s[28:29]
	v_add_u32_e32 v148, s1, v14
	v_and_b32_e32 v16, 7, v204
	v_mad_i64_i32 v[12:13], s[28:29], v148, s50, v[12:13]
	s_lshl_b64 s[30:31], s[22:23], 2
	v_add_u32_e32 v17, 0x4000, v14
	v_mov_b64_e32 v[14:15], s[54:55]
	v_lshl_add_u64 v[12:13], v[12:13], 0, s[30:31]
	v_lshlrev_b32_e32 v2, 5, v16
	v_mad_i64_i32 v[14:15], s[28:29], v17, s16, v[14:15]
	v_readlane_b32 s1, v254, 50
	v_lshl_add_u64 v[12:13], v[12:13], 0, v[2:3]
	v_lshl_add_u64 v[14:15], s[22:23], 1, v[14:15]
	v_lshlrev_b32_e32 v108, 4, v16
	v_mov_b32_e32 v109, v3
	s_add_u32 s22, s1, s30
	v_readlane_b32 s1, v254, 52
	v_lshl_add_u64 v[14:15], v[14:15], 0, v[108:109]
	v_add_co_u32_e32 v16, vcc, s91, v12
	s_mov_b64 s[28:29], 0x2000
	s_addc_u32 s23, s1, s31
	global_load_dwordx4 v[96:99], v[14:15], off
	global_load_dwordx4 v[32:35], v[12:13], off offset:16
	global_load_dwordx4 v[80:83], v[12:13], off
	v_lshl_add_u64 v[14:15], v[12:13], 0, s[88:89]
	v_addc_co_u32_e32 v17, vcc, 0, v13, vcc
	v_lshl_add_u64 v[12:13], v[12:13], 0, s[28:29]
	v_lshl_add_u64 v[24:25], s[22:23], 0, v[2:3]
	v_readlane_b32 s1, v254, 55
	global_load_dwordx4 v[28:31], v[16:17], off offset:-4096
	global_load_dwordx4 v[20:23], v[14:15], off offset:16
	s_nop 0
	global_load_dwordx4 v[16:19], v[16:17], off
	s_nop 0
	global_load_dwordx4 v[12:15], v[12:13], off offset:16
	s_nop 0
	global_load_dwordx4 v[72:75], v2, s[22:23] offset:16
	global_load_dwordx4 v[92:95], v2, s[22:23]
	s_add_u32 s22, s1, s30
	v_readlane_b32 s1, v254, 56
	v_add_co_u32_e32 v60, vcc, s91, v24
	s_addc_u32 s23, s1, s31
	v_lshl_add_u64 v[26:27], v[24:25], 0, s[88:89]
	v_addc_co_u32_e32 v61, vcc, 0, v25, vcc
	global_load_dwordx4 v[100:103], v2, s[22:23]
	global_load_dwordx4 v[88:91], v2, s[22:23] offset:16
	global_load_dwordx4 v[84:87], v[60:61], off offset:-4096
	global_load_dwordx4 v[76:79], v[26:27], off offset:16
	v_lshl_add_u64 v[26:27], v[24:25], 0, s[28:29]
	global_load_dwordx4 v[68:71], v[60:61], off
	global_load_dwordx4 v[64:67], v[26:27], off offset:16
	v_add_co_u32_e32 v26, vcc, s50, v24
	s_mov_b64 s[22:23], 0x3000
	s_nop 0
	v_addc_co_u32_e32 v27, vcc, 0, v25, vcc
	v_lshl_add_u64 v[24:25], v[24:25], 0, s[22:23]
	global_load_dwordx4 v[60:63], v[26:27], off
	s_load_dwordx2 s[22:23], s[34:35], 0xc8
	global_load_dwordx4 v[24:27], v[24:25], off offset:16
	s_mov_b32 s1, 0x49d1000
	s_waitcnt lgkmcnt(0)
	v_mov_b64_e32 v[146:147], s[22:23]
	v_mad_i64_i32 v[146:147], s[22:23], v148, s50, v[146:147]
	v_lshl_add_u64 v[146:147], v[146:147], 0, s[30:31]
	v_lshl_add_u64 v[146:147], v[146:147], 0, v[2:3]
	v_add_co_u32_e32 v152, vcc, s1, v146
	s_mov_b32 s1, 0x49d2000
	s_mov_b64 s[22:23], 0x49d0000
	v_add_co_u32_e64 v154, s[38:39], s1, v146
	v_lshl_add_u64 v[150:151], v[146:147], 0, s[22:23]
	v_addc_co_u32_e32 v153, vcc, 0, v147, vcc
	v_addc_co_u32_e64 v155, vcc, 0, v147, s[38:39]
	s_movk_i32 s1, 0x70
	s_waitcnt vmcnt(16)
	v_lshlrev_b32_e32 v146, 16, v96
	v_and_b32_e32 v147, 0xffff0000, v96
	v_lshlrev_b32_e32 v148, 16, v97
	v_and_b32_e32 v149, 0xffff0000, v97
	v_lshlrev_b32_e32 v96, 16, v98
	v_and_b32_e32 v97, 0xffff0000, v98
	v_lshlrev_b32_e32 v98, 16, v99
	v_and_b32_e32 v99, 0xffff0000, v99
	global_store_dwordx4 v[154:155], v[146:149], off sc1
	global_store_dwordx4 v[154:155], v[96:99], off offset:16 sc1
	s_waitcnt vmcnt(14)
	global_store_dwordx4 v[150:151], v[20:23], off offset:16 sc1
	s_waitcnt vmcnt(13)
	global_store_dwordx4 v[152:153], v[12:15], off offset:16 sc1
	global_store_dwordx4 v[152:153], v[28:31], off offset:-4096 sc1
	global_store_dwordx4 v[152:153], v[16:19], off sc1
	s_waitcnt vmcnt(13)
	v_pk_fma_f32 v[80:81], v[80:81], v[92:93], v[100:101]
	s_waitcnt vmcnt(12)
	v_pk_fma_f32 v[32:33], v[32:33], v[72:73], v[88:89]
	v_pk_fma_f32 v[82:83], v[82:83], v[94:95], v[102:103]
	v_pk_fma_f32 v[34:35], v[34:35], v[74:75], v[90:91]
	s_waitcnt vmcnt(11)
	v_pk_fma_f32 v[28:29], v[28:29], v[84:85], v[80:81]
	s_waitcnt vmcnt(10)
	v_pk_fma_f32 v[20:21], v[20:21], v[76:77], v[32:33]
	v_pk_fma_f32 v[30:31], v[30:31], v[86:87], v[82:83]
	v_pk_fma_f32 v[22:23], v[22:23], v[78:79], v[34:35]
	s_waitcnt vmcnt(9)
	v_pk_fma_f32 v[16:17], v[16:17], v[68:69], v[28:29]
	s_waitcnt vmcnt(8)
	v_pk_fma_f32 v[20:21], v[12:13], v[64:65], v[20:21]
	v_pk_fma_f32 v[18:19], v[18:19], v[70:71], v[30:31]
	v_pk_fma_f32 v[22:23], v[14:15], v[66:67], v[22:23]
	s_waitcnt vmcnt(7)
	v_pk_fma_f32 v[12:13], v[60:61], v[146:147], v[16:17]
	s_waitcnt vmcnt(6)
	v_pk_fma_f32 v[16:17], v[24:25], v[96:97], v[20:21]
	v_mul_lo_u32 v24, v145, s13
	v_pk_fma_f32 v[14:15], v[62:63], v[148:149], v[18:19]
	v_pk_fma_f32 v[18:19], v[26:27], v[98:99], v[22:23]
	v_add_u32_e32 v24, 0, v24
	v_cvt_pk_bf16_f32 v20, v12, v13
	v_cvt_pk_bf16_f32 v21, v14, v15
	v_cvt_pk_bf16_f32 v22, v16, v17
	v_cvt_pk_bf16_f32 v23, v18, v19
	v_add_u32_e32 v25, v24, v108
	ds_write_b128 v25, v[20:23] offset:18880
	v_mul_lo_u32 v20, v145, s1
	v_add3_u32 v2, v24, v20, v2
	ds_write_b128 v2, v[12:15] offset:37312
	ds_write_b128 v2, v[16:19] offset:37328

.LBB0_883:
	s_lshl_b64 s[38:39], s[24:25], 11
	s_add_u32 s38, s1, s38
	s_addc_u32 s39, s4, s39
	s_lshl_b32 s2, s28, 7
	v_lshrrev_b32_e32 v2, 1, v47
	v_and_or_b32 v12, v2, 24, s2
	v_ashrrev_i32_e32 v13, 31, v12
	v_lshlrev_b64 v[50:51], 1, v[12:13]
	v_lshl_add_u64 v[28:29], s[38:39], 0, v[50:51]
	v_lshlrev_b32_e32 v2, 11, v47
	v_lshl_add_u64 v[50:51], s[36:37], 0, v[50:51]
	s_mov_b64 s[38:39], 0x5620000
	v_and_b32_e32 v2, 0x7800, v2
	v_lshl_add_u64 v[98:99], v[50:51], 0, s[38:39]
	v_and_b32_e32 v118, 63, v47
	v_lshl_add_u64 v[82:83], v[98:99], 0, v[2:3]
	s_mov_b32 s0, 0x10000
	v_lshl_add_u64 v[24:25], v[28:29], 0, v[2:3]
	v_or_b32_e32 v66, 0x8000, v2
	v_mov_b32_e32 v67, v3
	v_add_co_u32_e32 v94, vcc, s0, v82
	v_lshl_or_b32 v2, v118, 11, v241
	v_lshl_add_u64 v[40:41], v[28:29], 0, v[66:67]
	v_lshl_add_u64 v[78:79], v[98:99], 0, v[66:67]
	v_addc_co_u32_e32 v95, vcc, 0, v83, vcc
	v_lshl_add_u64 v[110:111], v[98:99], 0, v[2:3]
	global_load_dwordx4 v[12:15], v[24:25], off
	global_load_dwordx4 v[16:19], v[24:25], off offset:64
	global_load_dwordx4 v[20:23], v[24:25], off offset:128
	s_nop 0
	global_load_dwordx4 v[24:27], v[24:25], off offset:192
	s_nop 0
	global_load_dwordx4 v[28:31], v[40:41], off
	global_load_dwordx4 v[32:35], v[40:41], off offset:64
	global_load_dwordx4 v[36:39], v[40:41], off offset:128
	s_nop 0
	global_load_dwordx4 v[40:43], v[40:41], off offset:192
	s_nop 0
	global_load_dwordx4 v[50:53], v[82:83], off
	global_load_dwordx4 v[54:57], v[82:83], off offset:64
	global_load_dwordx4 v[58:61], v[82:83], off offset:128
	global_load_dwordx4 v[62:65], v[82:83], off offset:192
	global_load_dwordx4 v[66:69], v[78:79], off
	global_load_dwordx4 v[70:73], v[78:79], off offset:64
	global_load_dwordx4 v[74:77], v[78:79], off offset:128
	s_nop 0
	global_load_dwordx4 v[78:81], v[78:79], off offset:192
	s_nop 0
	global_load_dwordx4 v[82:85], v[94:95], off
	global_load_dwordx4 v[86:89], v[94:95], off offset:64
	global_load_dwordx4 v[90:93], v[94:95], off offset:128
	s_nop 0
	global_load_dwordx4 v[94:97], v[94:95], off offset:192
	s_nop 0
	global_load_dwordx4 v[98:101], v[110:111], off
	global_load_dwordx4 v[102:105], v[110:111], off offset:64
	global_load_dwordx4 v[106:109], v[110:111], off offset:128
	s_nop 0
	global_load_dwordx4 v[110:113], v[110:111], off offset:192
	s_waitcnt vmcnt(15)
	v_mfma_f32_16x16x32_bf16 v[114:117], v[12:15], v[50:53], 0
	s_lshl_b32 s2, s28, 13
	v_lshlrev_b32_e32 v2, 4, v118
	s_add_i32 s2, s2, 0
	v_mfma_f32_16x16x32_bf16 v[50:53], v[28:31], v[50:53], 0
	s_waitcnt vmcnt(14)
	v_mfma_f32_16x16x32_bf16 v[114:117], v[16:19], v[54:57], v[114:117]
	v_mfma_f32_16x16x32_bf16 v[50:53], v[32:35], v[54:57], v[50:53]
	s_waitcnt vmcnt(13)
	v_mfma_f32_16x16x32_bf16 v[114:117], v[20:23], v[58:61], v[114:117]
	v_mfma_f32_16x16x32_bf16 v[50:53], v[36:39], v[58:61], v[50:53]
	s_waitcnt vmcnt(12)
	v_mfma_f32_16x16x32_bf16 v[114:117], v[24:27], v[62:65], v[114:117]
	v_mfma_f32_16x16x32_bf16 v[50:53], v[40:43], v[62:65], v[50:53]
	s_waitcnt vmcnt(11)
	v_mfma_f32_16x16x32_bf16 v[54:57], v[12:15], v[66:69], 0
	s_waitcnt vmcnt(7)
	v_mfma_f32_16x16x32_bf16 v[62:65], v[12:15], v[82:85], 0
	s_waitcnt vmcnt(3)
	v_mfma_f32_16x16x32_bf16 v[12:15], v[12:15], v[98:101], 0
	v_mfma_f32_16x16x32_bf16 v[58:61], v[28:31], v[66:69], 0
	v_mfma_f32_16x16x32_bf16 v[66:69], v[28:31], v[82:85], 0
	v_mfma_f32_16x16x32_bf16 v[54:57], v[16:19], v[70:73], v[54:57]
	v_mfma_f32_16x16x32_bf16 v[62:65], v[16:19], v[86:89], v[62:65]
	s_waitcnt vmcnt(2)
	v_mfma_f32_16x16x32_bf16 v[12:15], v[16:19], v[102:105], v[12:15]
	v_mfma_f32_16x16x32_bf16 v[16:19], v[28:31], v[98:101], 0
	v_mfma_f32_16x16x32_bf16 v[66:69], v[32:35], v[86:89], v[66:69]
	v_mfma_f32_16x16x32_bf16 v[58:61], v[32:35], v[70:73], v[58:61]
	v_mfma_f32_16x16x32_bf16 v[62:65], v[20:23], v[90:93], v[62:65]
	v_mfma_f32_16x16x32_bf16 v[16:19], v[32:35], v[102:105], v[16:19]
	v_mfma_f32_16x16x32_bf16 v[54:57], v[20:23], v[74:77], v[54:57]
	v_mfma_f32_16x16x32_bf16 v[66:69], v[36:39], v[90:93], v[66:69]
	v_mfma_f32_16x16x32_bf16 v[58:61], v[36:39], v[74:77], v[58:61]
	s_waitcnt vmcnt(1)
	v_mfma_f32_16x16x32_bf16 v[12:15], v[20:23], v[106:109], v[12:15]
	v_add_u32_e32 v20, s2, v2
	ds_write_b128 v20, v[114:117]
	s_lshl_b32 s2, s28, 10
	v_mfma_f32_16x16x32_bf16 v[62:65], v[24:27], v[94:97], v[62:65]
	s_add_i32 s2, s2, 0
	v_add_u32_e32 v2, s2, v2
	s_cmp_lt_i32 s22, 3
	v_mfma_f32_16x16x32_bf16 v[16:19], v[36:39], v[106:109], v[16:19]
	v_mfma_f32_16x16x32_bf16 v[54:57], v[24:27], v[78:81], v[54:57]
	v_mfma_f32_16x16x32_bf16 v[66:69], v[40:43], v[94:97], v[66:69]
	v_mfma_f32_16x16x32_bf16 v[58:61], v[40:43], v[78:81], v[58:61]
	ds_write_b128 v20, v[50:53] offset:1024
	s_nop 4
	ds_write_b128 v20, v[54:57] offset:2048
	s_nop 0
	ds_write_b128 v20, v[58:61] offset:3072
	s_waitcnt vmcnt(0)
	v_mfma_f32_16x16x32_bf16 v[12:15], v[24:27], v[110:113], v[12:15]
	ds_write_b128 v20, v[62:65] offset:4096
	ds_write_b128 v20, v[66:69] offset:5120
	s_nop 5
	ds_write_b128 v20, v[12:15] offset:6144
	v_mfma_f32_16x16x32_bf16 v[12:15], v[40:43], v[110:113], v[16:19]
	s_nop 7
	ds_write_b128 v20, v[12:15] offset:7168
	s_waitcnt lgkmcnt(0)
	s_barrier
	ds_read_b128 v[36:39], v2
	ds_read_b128 v[40:43], v2 offset:8192
	ds_read_b128 v[32:35], v2 offset:16384
	ds_read_b128 v[28:31], v2 offset:24576
	ds_read_b128 v[24:27], v2 offset:32768
	ds_read_b128 v[20:23], v2 offset:40960
	ds_read_b128 v[16:19], v2 offset:49152
	ds_read_b128 v[12:15], v2 offset:57344
	s_waitcnt lgkmcnt(6)
	v_pk_add_f32 v[38:39], v[38:39], v[42:43]
	v_pk_add_f32 v[36:37], v[36:37], v[40:41]
	s_waitcnt lgkmcnt(5)
	v_pk_add_f32 v[34:35], v[38:39], v[34:35]
	v_pk_add_f32 v[32:33], v[36:37], v[32:33]
	s_waitcnt lgkmcnt(4)
	v_pk_add_f32 v[30:31], v[34:35], v[30:31]
	v_pk_add_f32 v[28:29], v[32:33], v[28:29]
	v_fmamk_f32 v2, v49, 0x3a800000, v1
	s_waitcnt lgkmcnt(3)
	v_pk_add_f32 v[26:27], v[30:31], v[26:27]
	v_pk_add_f32 v[24:25], v[28:29], v[24:25]
	v_rsq_f32_e32 v2, v2
	s_waitcnt lgkmcnt(2)
	v_pk_add_f32 v[22:23], v[26:27], v[22:23]
	v_pk_add_f32 v[20:21], v[24:25], v[20:21]
	s_waitcnt lgkmcnt(1)
	v_pk_add_f32 v[18:19], v[22:23], v[18:19]
	v_pk_add_f32 v[16:17], v[20:21], v[16:17]
	s_waitcnt lgkmcnt(0)
	v_pk_add_f32 v[14:15], v[18:19], v[14:15]
	v_pk_add_f32 v[12:13], v[16:17], v[12:13]
	v_pk_mul_f32 v[18:19], v[2:3], v[14:15] op_sel_hi:[0,1]
	v_pk_mul_f32 v[16:17], v[2:3], v[12:13] op_sel_hi:[0,1]
	v_add_u32_e32 v2, 0xffffc000, v44
	s_barrier
	s_cbranch_scc1 .LBB0_889
	s_cmp_gt_i32 s22, 3
	s_cbranch_scc0 .LBB0_890
	s_cmp_gt_i32 s22, 4
	s_mov_b64 s[38:39], -1
	s_cbranch_scc0 .LBB0_887
	v_lshl_or_b32 v12, v2, 7, v240
	v_ashrrev_i32_e32 v13, 31, v12
	v_lshlrev_b64 v[12:13], 9, v[12:13]
	v_lshl_add_u64 v[12:13], s[64:65], 0, v[12:13]
	v_mov_b32_e32 v49, v3
	v_lshl_add_u64 v[12:13], v[48:49], 2, v[12:13]
	v_add_co_u32_e32 v12, vcc, 0x54cc000, v12
	s_mov_b64 s[38:39], 0
	s_nop 0
	v_addc_co_u32_e32 v13, vcc, 0, v13, vcc
	global_store_dwordx4 v[12:13], v[16:19], off offset:3584 sc1

.LBB0_896:
	s_and_b64 vcc, exec, s[38:39]
	s_cbranch_vccz .LBB0_901
	v_cmp_lt_i32_e32 vcc, v234, v235
	v_bfe_u32 v20, v47, 4, 1
	s_cmp_lg_u32 s22, 1
	v_cndmask_b32_e32 v12, v231, v234, vcc
	v_lshlrev_b32_e32 v15, 2, v12
	ds_bpermute_b32 v12, v15, v16
	ds_bpermute_b32 v13, v15, v17
	ds_bpermute_b32 v14, v15, v18
	ds_bpermute_b32 v15, v15, v19
	v_cmp_eq_u32_e32 vcc, 0, v20
	s_mov_b64 s[38:39], -1
	s_waitcnt lgkmcnt(2)
	v_pk_mul_f32 v[8:9], v[8:9], v[12:13]
	s_waitcnt lgkmcnt(0)
	v_pk_mul_f32 v[10:11], v[10:11], v[14:15]
	s_nop 0
	v_xor_b32_e32 v12, 0x80000000, v10
	v_xor_b32_e32 v13, 0x80000000, v11
	v_xor_b32_e32 v14, 0x80000000, v8
	v_xor_b32_e32 v15, 0x80000000, v9
	v_cndmask_b32_e32 v9, v9, v15, vcc
	v_cndmask_b32_e32 v8, v8, v14, vcc
	v_cndmask_b32_e32 v11, v11, v13, vcc
	v_cndmask_b32_e32 v10, v10, v12, vcc
	v_pk_fma_f32 v[14:15], v[6:7], v[18:19], v[10:11]
	v_pk_fma_f32 v[12:13], v[4:5], v[16:17], v[8:9]
	s_cbranch_scc0 .LBB0_899
	v_lshl_or_b32 v4, v2, 7, v240
	s_addk_i32 s23, 0xf400
	v_ashrrev_i32_e32 v5, 31, v4
	s_ashr_i32 s28, s23, 6
	s_ashr_i32 s29, s28, 31
	v_lshlrev_b64 v[4:5], 9, v[4:5]
	v_lshl_add_u64 v[4:5], s[64:65], 0, v[4:5]
	s_lshl_b64 s[28:29], s[28:29], 8
	v_lshl_add_u64 v[4:5], v[4:5], 0, s[28:29]
	v_lshlrev_b32_e32 v2, 7, v20
	v_lshl_add_u64 v[4:5], v[4:5], 0, v[2:3]
	v_and_b32_e32 v2, 0x70, v46
	v_lshl_add_u64 v[4:5], v[4:5], 0, v[2:3]
	v_add_co_u32_e32 v4, vcc, 0x4cd0000, v4
	s_mov_b64 s[38:39], 0
	s_nop 0
	v_addc_co_u32_e32 v5, vcc, 0, v5, vcc
	global_store_dwordx4 v[4:5], v[12:15], off sc1

.LBB0_908:
	v_cvt_pk_bf16_f32 v7, v14, v15
	v_cvt_pk_bf16_f32 v6, v12, v13
	global_store_dwordx2 v[4:5], v[6:7], off sc1

.LBB0_923:
	v_mov_b32_e32 v191, v186
	v_mov_b32_e32 v190, v187
	s_cmp_gt_i32 s62, 3
	s_mov_b64 s[70:71], -1
	s_mov_b32 s61, 0x1f000
	s_mov_b32 s63, 0x25000
	s_mov_b32 s75, s94
	s_cbranch_scc0 .LBB0_969
	s_cmp_gt_u32 s62, 7
	s_cbranch_scc0 .LBB0_966
	s_cmp_gt_u32 s62, 9
	s_cbranch_scc0 .LBB0_963
	s_cmp_gt_u32 s62, 11
	s_cbranch_scc0 .LBB0_960
	s_lshl_b32 s0, s68, 8
	s_add_i32 s0, s0, s90
	v_add_u32_e32 v180, s0, v191
	v_readlane_b32 s0, v253, 9
	v_ashrrev_i32_e32 v181, 31, v180
	v_lshlrev_b32_e32 v2, 8, v180
	v_add_lshl_u32 v178, v190, s0, 2
	v_ashrrev_i32_e32 v179, 31, v178
	v_lshl_add_u64 v[132:133], v[180:181], 2, s[30:31]
	v_lshlrev_b32_e32 v201, 6, v180
	v_lshl_add_u64 v[182:183], v[178:179], 2, s[50:51]
	v_and_b32_e32 v2, 0x1fff00, v2
	global_load_dword v156, v[132:133], off
	global_load_dword v204, v[132:133], off offset:64
	global_load_dword v203, v[132:133], off offset:128
	global_load_dword v202, v[132:133], off offset:192
	global_load_dword v200, v[132:133], off offset:512
	global_load_dword v199, v[132:133], off offset:576
	global_load_dword v198, v[132:133], off offset:640
	global_load_dword v197, v[132:133], off offset:704
	v_lshl_add_u64 v[132:133], v[182:183], 0, v[2:3]
	v_add_u32_e32 v2, 0x400, v201
	v_and_b32_e32 v2, 0x7ffc0, v2
	v_lshlrev_b32_e32 v2, 2, v2
	global_load_dwordx4 v[160:163], v[132:133], off
	global_load_dwordx4 v[206:209], v[132:133], off offset:128
	v_lshl_add_u64 v[132:133], v[182:183], 0, v[2:3]
	v_add_u32_e32 v2, 0x800, v201
	v_and_b32_e32 v2, 0x7ffc0, v2
	v_lshlrev_b32_e32 v2, 2, v2
	global_load_dwordx4 v[148:151], v[132:133], off
	global_load_dwordx4 v[152:155], v[132:133], off offset:128
	v_lshl_add_u64 v[132:133], v[182:183], 0, v[2:3]
	v_add_u32_e32 v2, 0xc00, v201
	v_and_b32_e32 v2, 0x7ffc0, v2
	v_lshlrev_b32_e32 v2, 2, v2
	v_lshl_add_u64 v[136:137], v[182:183], 0, v[2:3]
	global_load_dwordx4 v[140:143], v[132:133], off
	global_load_dwordx4 v[144:147], v[132:133], off offset:128
	s_nop 0
	global_load_dwordx4 v[132:135], v[136:137], off
	s_nop 0
	global_load_dwordx4 v[136:139], v[136:137], off offset:128
	v_lshl_add_u32 v176, v190, 3, s91
	v_ashrrev_i32_e32 v177, 31, v176
	v_and_b32_e32 v2, 0x1fff, v180
	s_movk_i32 s0, 0x1f7f
	v_cmp_lt_u32_e32 vcc, s0, v2
	s_waitcnt vmcnt(0)
	v_fmamk_f32 v156, v156, 0x3a800000, v1
	v_rsq_f32_e32 v184, v156
	s_nop 0
	v_pk_mul_f32 v[214:215], v[124:125], v[184:185] op_sel_hi:[1,0]
	v_pk_mul_f32 v[216:217], v[126:127], v[184:185] op_sel_hi:[1,0]
	v_pk_mul_f32 v[210:211], v[128:129], v[184:185] op_sel_hi:[1,0]
	v_pk_mul_f32 v[212:213], v[130:131], v[184:185] op_sel_hi:[1,0]
	v_ashrrev_i32_e32 v185, 6, v180
	v_and_b32_e32 v205, 0xffffff80, v185
	v_pk_mul_f32 v[156:157], v[216:217], v[208:209]
	v_pk_mul_f32 v[218:219], v[214:215], v[206:207]
	v_pk_fma_f32 v[158:159], v[212:213], v[162:163], v[156:157] neg_lo:[0,0,1] neg_hi:[0,0,1]
	v_pk_fma_f32 v[156:157], v[210:211], v[160:161], v[218:219] neg_lo:[0,0,1] neg_hi:[0,0,1]
	v_pk_mul_f32 v[206:207], v[210:211], v[206:207]
	v_lshlrev_b64 v[210:211], 8, v[180:181]
	v_pk_mul_f32 v[208:209], v[212:213], v[208:209]
	v_lshl_add_u64 v[210:211], s[46:47], 0, v[210:211]
	v_pk_fma_f32 v[162:163], v[216:217], v[162:163], v[208:209]
	v_pk_fma_f32 v[160:161], v[214:215], v[160:161], v[206:207]
	v_lshl_add_u64 v[210:211], v[176:177], 1, v[210:211]
	v_cvt_pk_bf16_f32 v206, v156, v157
	v_cvt_pk_bf16_f32 v207, v158, v159
	v_cvt_pk_bf16_f32 v208, v160, v161
	v_cvt_pk_bf16_f32 v209, v162, v163
	global_store_dwordx4 v[210:211], v[206:209], off sc1
	s_and_saveexec_b64 s[70:71], vcc
	s_cbranch_execz .LBB0_929
	s_movk_i32 s0, 0xe080
	v_add3_u32 v206, v2, v205, s0
	v_ashrrev_i32_e32 v207, 31, v206
	v_lshlrev_b64 v[206:207], 9, v[206:207]
	v_lshl_add_u64 v[206:207], s[54:55], 0, v[206:207]
	v_lshl_add_u64 v[206:207], v[178:179], 2, v[206:207]
	global_store_dwordx4 v[206:207], v[156:159], off sc1
	global_store_dwordx4 v[206:207], v[160:163], off offset:128 sc1
.LBB0_929:
	s_or_b64 exec, exec, s[70:71]
	v_mov_b32_e32 v185, v184
	v_lshlrev_b64 v[210:211], 7, v[180:181]
	v_mov_b32_e32 v160, v184
	v_mov_b32_e32 v161, v184
	v_pk_mul_f32 v[158:159], v[122:123], v[160:161]
	v_pk_mul_f32 v[156:157], v[120:121], v[184:185]
	v_pk_mul_f32 v[162:163], v[118:119], v[160:161]
	v_pk_mul_f32 v[160:161], v[116:117], v[184:185]
	v_lshl_add_u64 v[184:185], v[210:211], 1, s[48:49]
	v_lshl_add_u64 v[184:185], v[176:177], 1, v[184:185]
	v_cvt_pk_bf16_f32 v206, v156, v157
	v_cvt_pk_bf16_f32 v207, v158, v159
	v_cvt_pk_bf16_f32 v208, v160, v161
	v_cvt_pk_bf16_f32 v209, v162, v163
	global_store_dwordx4 v[184:185], v[206:209], off sc1
	s_and_saveexec_b64 s[70:71], vcc
	s_cbranch_execz .LBB0_931
	s_movk_i32 s0, 0xe080
	v_add3_u32 v184, v2, v205, s0
	v_ashrrev_i32_e32 v185, 31, v184
	v_lshlrev_b64 v[184:185], 9, v[184:185]
	v_lshl_add_u64 v[184:185], s[56:57], 0, v[184:185]
	v_lshl_add_u64 v[184:185], v[176:177], 2, v[184:185]
	global_store_dwordx4 v[184:185], v[156:159], off sc1
	global_store_dwordx4 v[184:185], v[160:163], off offset:16 sc1
.LBB0_931:
	s_or_b64 exec, exec, s[70:71]
	v_fmamk_f32 v2, v204, 0x3a800000, v1
	v_rsq_f32_e32 v160, v2
	v_add_u32_e32 v162, 16, v180
	v_ashrrev_i32_e32 v163, 31, v162
	v_and_b32_e32 v2, 0x1fff, v162
	v_pk_mul_f32 v[208:209], v[108:109], v[160:161] op_sel_hi:[1,0]
	v_pk_mul_f32 v[184:185], v[112:113], v[160:161] op_sel_hi:[1,0]
	v_pk_mul_f32 v[156:157], v[208:209], v[152:153]
	v_pk_mul_f32 v[204:205], v[114:115], v[160:161] op_sel_hi:[1,0]
	v_pk_mul_f32 v[206:207], v[110:111], v[160:161] op_sel_hi:[1,0]
	v_pk_fma_f32 v[156:157], v[184:185], v[148:149], v[156:157] neg_lo:[0,0,1] neg_hi:[0,0,1]
	v_pk_mul_f32 v[152:153], v[184:185], v[152:153]
	v_lshlrev_b64 v[184:185], 8, v[162:163]
	v_pk_mul_f32 v[158:159], v[206:207], v[154:155]
	v_pk_mul_f32 v[154:155], v[204:205], v[154:155]
	v_lshl_add_u64 v[184:185], s[46:47], 0, v[184:185]
	s_movk_i32 s0, 0x1f7f
	v_pk_fma_f32 v[158:159], v[204:205], v[150:151], v[158:159] neg_lo:[0,0,1] neg_hi:[0,0,1]
	v_pk_fma_f32 v[150:151], v[206:207], v[150:151], v[154:155]
	v_pk_fma_f32 v[148:149], v[208:209], v[148:149], v[152:153]
	v_lshl_add_u64 v[184:185], v[176:177], 1, v[184:185]
	v_cmp_lt_u32_e32 vcc, s0, v2
	v_ashrrev_i32_e32 v181, 6, v162
	v_cvt_pk_bf16_f32 v152, v156, v157
	v_cvt_pk_bf16_f32 v153, v158, v159
	v_cvt_pk_bf16_f32 v154, v148, v149
	v_cvt_pk_bf16_f32 v155, v150, v151
	global_store_dwordx4 v[184:185], v[152:155], off sc1
	s_and_saveexec_b64 s[70:71], vcc
	s_cbranch_execz .LBB0_933
	v_and_b32_e32 v152, 0xffffff80, v181
	s_movk_i32 s0, 0xe080
	v_add3_u32 v152, v2, v152, s0
	v_ashrrev_i32_e32 v153, 31, v152
	v_lshlrev_b64 v[152:153], 9, v[152:153]
	v_lshl_add_u64 v[152:153], s[54:55], 0, v[152:153]
	v_lshl_add_u64 v[152:153], v[178:179], 2, v[152:153]
	global_store_dwordx4 v[152:153], v[156:159], off sc1
	global_store_dwordx4 v[152:153], v[148:151], off offset:128 sc1
.LBB0_933:
	s_or_b64 exec, exec, s[70:71]
	v_mov_b32_e32 v161, v160
	v_lshlrev_b64 v[162:163], 7, v[162:163]
	v_mov_b32_e32 v152, v160
	v_mov_b32_e32 v153, v160
	v_pk_mul_f32 v[150:151], v[106:107], v[152:153]
	v_pk_mul_f32 v[148:149], v[104:105], v[160:161]
	v_pk_mul_f32 v[154:155], v[102:103], v[152:153]
	v_pk_mul_f32 v[152:153], v[100:101], v[160:161]
	v_lshl_add_u64 v[160:161], v[162:163], 1, s[48:49]
	v_lshl_add_u64 v[160:161], v[176:177], 1, v[160:161]
	v_cvt_pk_bf16_f32 v156, v148, v149
	v_cvt_pk_bf16_f32 v157, v150, v151
	v_cvt_pk_bf16_f32 v158, v152, v153
	v_cvt_pk_bf16_f32 v159, v154, v155
	global_store_dwordx4 v[160:161], v[156:159], off sc1
	s_and_saveexec_b64 s[70:71], vcc
	s_cbranch_execz .LBB0_935
	v_and_b32_e32 v156, 0xffffff80, v181
	s_movk_i32 s0, 0xe080
	v_add3_u32 v156, v2, v156, s0
	v_ashrrev_i32_e32 v157, 31, v156
	v_lshlrev_b64 v[156:157], 9, v[156:157]
	v_lshl_add_u64 v[156:157], s[56:57], 0, v[156:157]
	v_lshl_add_u64 v[156:157], v[176:177], 2, v[156:157]
	global_store_dwordx4 v[156:157], v[148:151], off sc1
	global_store_dwordx4 v[156:157], v[152:155], off offset:16 sc1
.LBB0_935:
	s_or_b64 exec, exec, s[70:71]
	v_fmamk_f32 v2, v203, 0x3a800000, v1
	v_rsq_f32_e32 v152, v2
	v_add_u32_e32 v154, 32, v180
	v_ashrrev_i32_e32 v155, 31, v154
	v_and_b32_e32 v2, 0x1fff, v154
	v_pk_mul_f32 v[162:163], v[92:93], v[152:153] op_sel_hi:[1,0]
	v_pk_mul_f32 v[156:157], v[96:97], v[152:153] op_sel_hi:[1,0]
	v_pk_mul_f32 v[148:149], v[162:163], v[144:145]
	v_pk_mul_f32 v[144:145], v[156:157], v[144:145]
	v_pk_fma_f32 v[148:149], v[156:157], v[140:141], v[148:149] neg_lo:[0,0,1] neg_hi:[0,0,1]
	v_lshlrev_b64 v[156:157], 8, v[154:155]
	v_pk_mul_f32 v[158:159], v[98:99], v[152:153] op_sel_hi:[1,0]
	v_pk_mul_f32 v[160:161], v[94:95], v[152:153] op_sel_hi:[1,0]
	v_lshl_add_u64 v[156:157], s[46:47], 0, v[156:157]
	v_pk_mul_f32 v[150:151], v[160:161], v[146:147]
	v_pk_mul_f32 v[146:147], v[158:159], v[146:147]
	v_lshl_add_u64 v[156:157], v[176:177], 1, v[156:157]
	s_movk_i32 s0, 0x1f7f
	v_pk_fma_f32 v[150:151], v[158:159], v[142:143], v[150:151] neg_lo:[0,0,1] neg_hi:[0,0,1]
	v_pk_fma_f32 v[142:143], v[160:161], v[142:143], v[146:147]
	v_pk_fma_f32 v[140:141], v[162:163], v[140:141], v[144:145]
	v_cvt_pk_bf16_f32 v144, v148, v149
	v_cvt_pk_bf16_f32 v145, v150, v151
	v_cmp_lt_u32_e32 vcc, s0, v2
	v_cvt_pk_bf16_f32 v146, v140, v141
	v_cvt_pk_bf16_f32 v147, v142, v143
	global_store_dwordx4 v[156:157], v[144:147], off sc1
	v_ashrrev_i32_e32 v156, 6, v154
	s_and_saveexec_b64 s[70:71], vcc
	s_cbranch_execz .LBB0_937
	v_and_b32_e32 v144, 0xffffff80, v156
	s_movk_i32 s0, 0xe080
	v_add3_u32 v144, v2, v144, s0
	v_ashrrev_i32_e32 v145, 31, v144
	v_lshlrev_b64 v[144:145], 9, v[144:145]
	v_lshl_add_u64 v[144:145], s[54:55], 0, v[144:145]
	v_lshl_add_u64 v[144:145], v[178:179], 2, v[144:145]
	global_store_dwordx4 v[144:145], v[148:151], off sc1
	global_store_dwordx4 v[144:145], v[140:143], off offset:128 sc1
.LBB0_937:
	s_or_b64 exec, exec, s[70:71]
	v_mov_b32_e32 v153, v152
	v_lshlrev_b64 v[154:155], 7, v[154:155]
	v_mov_b32_e32 v144, v152
	v_mov_b32_e32 v145, v152
	v_pk_mul_f32 v[142:143], v[90:91], v[144:145]
	v_pk_mul_f32 v[140:141], v[88:89], v[152:153]
	v_pk_mul_f32 v[146:147], v[86:87], v[144:145]
	v_pk_mul_f32 v[144:145], v[84:85], v[152:153]
	v_lshl_add_u64 v[152:153], v[154:155], 1, s[48:49]
	v_lshl_add_u64 v[152:153], v[176:177], 1, v[152:153]
	v_cvt_pk_bf16_f32 v148, v140, v141
	v_cvt_pk_bf16_f32 v149, v142, v143
	v_cvt_pk_bf16_f32 v150, v144, v145
	v_cvt_pk_bf16_f32 v151, v146, v147
	global_store_dwordx4 v[152:153], v[148:151], off sc1
	s_and_saveexec_b64 s[70:71], vcc
	s_cbranch_execz .LBB0_939
	v_and_b32_e32 v148, 0xffffff80, v156
	s_movk_i32 s0, 0xe080
	v_add3_u32 v148, v2, v148, s0
	v_ashrrev_i32_e32 v149, 31, v148
	v_lshlrev_b64 v[148:149], 9, v[148:149]
	v_lshl_add_u64 v[148:149], s[56:57], 0, v[148:149]
	v_lshl_add_u64 v[148:149], v[176:177], 2, v[148:149]
	global_store_dwordx4 v[148:149], v[140:143], off sc1
	global_store_dwordx4 v[148:149], v[144:147], off offset:16 sc1
.LBB0_939:
	s_or_b64 exec, exec, s[70:71]
	v_fmamk_f32 v2, v202, 0x3a800000, v1
	v_rsq_f32_e32 v144, v2
	v_add_u32_e32 v146, 48, v180
	v_ashrrev_i32_e32 v147, 31, v146
	v_and_b32_e32 v2, 0x1fff, v146
	v_pk_mul_f32 v[154:155], v[76:77], v[144:145] op_sel_hi:[1,0]
	v_pk_mul_f32 v[148:149], v[80:81], v[144:145] op_sel_hi:[1,0]
	v_pk_mul_f32 v[140:141], v[154:155], v[136:137]
	v_pk_mul_f32 v[136:137], v[148:149], v[136:137]
	v_pk_fma_f32 v[140:141], v[148:149], v[132:133], v[140:141] neg_lo:[0,0,1] neg_hi:[0,0,1]
	v_lshlrev_b64 v[148:149], 8, v[146:147]
	v_pk_mul_f32 v[150:151], v[82:83], v[144:145] op_sel_hi:[1,0]
	v_pk_mul_f32 v[152:153], v[78:79], v[144:145] op_sel_hi:[1,0]
	v_lshl_add_u64 v[148:149], s[46:47], 0, v[148:149]
	v_pk_mul_f32 v[142:143], v[152:153], v[138:139]
	v_pk_mul_f32 v[138:139], v[150:151], v[138:139]
	v_lshl_add_u64 v[148:149], v[176:177], 1, v[148:149]
	s_movk_i32 s0, 0x1f7f
	v_pk_fma_f32 v[142:143], v[150:151], v[134:135], v[142:143] neg_lo:[0,0,1] neg_hi:[0,0,1]
	v_pk_fma_f32 v[134:135], v[152:153], v[134:135], v[138:139]
	v_pk_fma_f32 v[132:133], v[154:155], v[132:133], v[136:137]
	v_cvt_pk_bf16_f32 v136, v140, v141
	v_cvt_pk_bf16_f32 v137, v142, v143
	v_cmp_lt_u32_e32 vcc, s0, v2
	v_cvt_pk_bf16_f32 v138, v132, v133
	v_cvt_pk_bf16_f32 v139, v134, v135
	global_store_dwordx4 v[148:149], v[136:139], off sc1
	v_ashrrev_i32_e32 v148, 6, v146
	s_and_saveexec_b64 s[70:71], vcc
	s_cbranch_execz .LBB0_941
	v_and_b32_e32 v136, 0xffffff80, v148
	s_movk_i32 s0, 0xe080
	v_add3_u32 v136, v2, v136, s0
	v_ashrrev_i32_e32 v137, 31, v136
	v_lshlrev_b64 v[136:137], 9, v[136:137]
	v_lshl_add_u64 v[136:137], s[54:55], 0, v[136:137]
	v_lshl_add_u64 v[136:137], v[178:179], 2, v[136:137]
	global_store_dwordx4 v[136:137], v[140:143], off sc1
	global_store_dwordx4 v[136:137], v[132:135], off offset:128 sc1
.LBB0_941:
	s_or_b64 exec, exec, s[70:71]
	v_mov_b32_e32 v145, v144
	v_lshlrev_b64 v[146:147], 7, v[146:147]
	v_mov_b32_e32 v136, v144
	v_mov_b32_e32 v137, v144
	v_pk_mul_f32 v[134:135], v[74:75], v[136:137]
	v_pk_mul_f32 v[132:133], v[72:73], v[144:145]
	v_pk_mul_f32 v[138:139], v[70:71], v[136:137]
	v_pk_mul_f32 v[136:137], v[68:69], v[144:145]
	v_lshl_add_u64 v[144:145], v[146:147], 1, s[48:49]
	v_lshl_add_u64 v[144:145], v[176:177], 1, v[144:145]
	v_cvt_pk_bf16_f32 v140, v132, v133
	v_cvt_pk_bf16_f32 v141, v134, v135
	v_cvt_pk_bf16_f32 v142, v136, v137
	v_cvt_pk_bf16_f32 v143, v138, v139
	global_store_dwordx4 v[144:145], v[140:143], off sc1
	s_and_saveexec_b64 s[70:71], vcc
	s_cbranch_execz .LBB0_943
	v_and_b32_e32 v140, 0xffffff80, v148
	s_movk_i32 s0, 0xe080
	v_add3_u32 v140, v2, v140, s0
	v_ashrrev_i32_e32 v141, 31, v140
	v_lshlrev_b64 v[140:141], 9, v[140:141]
	v_lshl_add_u64 v[140:141], s[56:57], 0, v[140:141]
	v_lshl_add_u64 v[140:141], v[176:177], 2, v[140:141]
	global_store_dwordx4 v[140:141], v[132:135], off sc1
	global_store_dwordx4 v[140:141], v[136:139], off offset:16 sc1
.LBB0_943:
	s_or_b64 exec, exec, s[70:71]
	v_add_u32_e32 v2, 0x2000, v201
	v_and_b32_e32 v2, 0x7ffc0, v2
	v_lshlrev_b32_e32 v2, 2, v2
	v_lshl_add_u64 v[132:133], v[182:183], 0, v[2:3]
	v_add_u32_e32 v2, 0x2400, v201
	v_and_b32_e32 v2, 0x7ffc0, v2
	v_lshlrev_b32_e32 v2, 2, v2
	global_load_dwordx4 v[160:163], v[132:133], off
	global_load_dwordx4 v[202:205], v[132:133], off offset:128
	v_lshl_add_u64 v[132:133], v[182:183], 0, v[2:3]
	v_add_u32_e32 v2, 0x2800, v201
	v_and_b32_e32 v2, 0x7ffc0, v2
	v_lshlrev_b32_e32 v2, 2, v2
	global_load_dwordx4 v[148:151], v[132:133], off
	global_load_dwordx4 v[152:155], v[132:133], off offset:128
	v_lshl_add_u64 v[132:133], v[182:183], 0, v[2:3]
	v_add_u32_e32 v2, 0x2c00, v201
	v_and_b32_e32 v2, 0x7ffc0, v2
	v_lshlrev_b32_e32 v2, 2, v2
	v_lshl_add_u64 v[136:137], v[182:183], 0, v[2:3]
	global_load_dwordx4 v[140:143], v[132:133], off
	global_load_dwordx4 v[144:147], v[132:133], off offset:128
	s_nop 0
	global_load_dwordx4 v[132:135], v[136:137], off
	s_nop 0
	global_load_dwordx4 v[136:139], v[136:137], off offset:128
	v_fmamk_f32 v156, v200, 0x3a800000, v1
	v_rsq_f32_e32 v182, v156
	v_add_u32_e32 v184, 0x80, v180
	v_ashrrev_i32_e32 v185, 31, v184
	v_and_b32_e32 v2, 0x1fff, v184
	v_pk_mul_f32 v[206:207], v[66:67], v[182:183] op_sel_hi:[1,0]
	v_pk_mul_f32 v[210:211], v[62:63], v[182:183] op_sel_hi:[1,0]
	v_pk_mul_f32 v[208:209], v[60:61], v[182:183] op_sel_hi:[1,0]
	v_pk_mul_f32 v[200:201], v[64:65], v[182:183] op_sel_hi:[1,0]
	s_movk_i32 s0, 0x1f7f
	v_cmp_lt_u32_e32 vcc, s0, v2
	v_ashrrev_i32_e32 v181, 6, v184
	s_waitcnt vmcnt(6)
	v_pk_mul_f32 v[156:157], v[210:211], v[204:205]
	v_pk_mul_f32 v[204:205], v[206:207], v[204:205]
	v_pk_mul_f32 v[212:213], v[208:209], v[202:203]
	v_pk_fma_f32 v[158:159], v[206:207], v[162:163], v[156:157] neg_lo:[0,0,1] neg_hi:[0,0,1]
	v_pk_fma_f32 v[162:163], v[210:211], v[162:163], v[204:205]
	v_lshlrev_b64 v[204:205], 8, v[184:185]
	v_pk_fma_f32 v[156:157], v[200:201], v[160:161], v[212:213] neg_lo:[0,0,1] neg_hi:[0,0,1]
	v_pk_mul_f32 v[200:201], v[200:201], v[202:203]
	v_lshl_add_u64 v[204:205], s[46:47], 0, v[204:205]
	v_pk_fma_f32 v[160:161], v[208:209], v[160:161], v[200:201]
	v_lshl_add_u64 v[204:205], v[176:177], 1, v[204:205]
	v_cvt_pk_bf16_f32 v200, v156, v157
	v_cvt_pk_bf16_f32 v201, v158, v159
	v_cvt_pk_bf16_f32 v202, v160, v161
	v_cvt_pk_bf16_f32 v203, v162, v163
	global_store_dwordx4 v[204:205], v[200:203], off sc1
	s_and_saveexec_b64 s[70:71], vcc
	s_cbranch_execz .LBB0_945
	v_and_b32_e32 v183, 0xffffff80, v181
	s_movk_i32 s0, 0xe080
	v_add3_u32 v200, v2, v183, s0
	v_ashrrev_i32_e32 v201, 31, v200
	v_lshlrev_b64 v[200:201], 9, v[200:201]
	v_lshl_add_u64 v[200:201], s[54:55], 0, v[200:201]
	v_lshl_add_u64 v[200:201], v[178:179], 2, v[200:201]
	global_store_dwordx4 v[200:201], v[156:159], off sc1
	global_store_dwordx4 v[200:201], v[160:163], off offset:128 sc1
.LBB0_945:
	s_or_b64 exec, exec, s[70:71]
	v_lshlrev_b64 v[200:201], 7, v[184:185]
	v_mov_b32_e32 v183, v182
	v_mov_b32_e32 v160, v182
	v_mov_b32_e32 v161, v182
	v_lshl_add_u64 v[200:201], v[200:201], 1, s[48:49]
	v_pk_mul_f32 v[158:159], v[58:59], v[160:161]
	v_pk_mul_f32 v[156:157], v[56:57], v[182:183]
	v_pk_mul_f32 v[162:163], v[54:55], v[160:161]
	v_pk_mul_f32 v[160:161], v[52:53], v[182:183]
	v_lshl_add_u64 v[200:201], v[176:177], 1, v[200:201]
	v_cvt_pk_bf16_f32 v182, v156, v157
	v_cvt_pk_bf16_f32 v183, v158, v159
	v_cvt_pk_bf16_f32 v184, v160, v161
	v_cvt_pk_bf16_f32 v185, v162, v163
	global_store_dwordx4 v[200:201], v[182:185], off sc1
	s_and_saveexec_b64 s[70:71], vcc
	s_cbranch_execz .LBB0_947
	v_and_b32_e32 v181, 0xffffff80, v181
	s_movk_i32 s0, 0xe080
	v_add3_u32 v182, v2, v181, s0
	v_ashrrev_i32_e32 v183, 31, v182
	v_lshlrev_b64 v[182:183], 9, v[182:183]
	v_lshl_add_u64 v[182:183], s[56:57], 0, v[182:183]
	v_lshl_add_u64 v[182:183], v[176:177], 2, v[182:183]
	global_store_dwordx4 v[182:183], v[156:159], off sc1
	global_store_dwordx4 v[182:183], v[160:163], off offset:16 sc1
.LBB0_947:
	s_or_b64 exec, exec, s[70:71]
	v_fmamk_f32 v2, v199, 0x3a800000, v1
	v_rsq_f32_e32 v160, v2
	v_add_u32_e32 v162, 0x90, v180
	v_ashrrev_i32_e32 v163, 31, v162
	v_and_b32_e32 v2, 0x1fff, v162
	v_pk_mul_f32 v[202:203], v[44:45], v[160:161] op_sel_hi:[1,0]
	v_pk_mul_f32 v[182:183], v[48:49], v[160:161] op_sel_hi:[1,0]
	s_waitcnt vmcnt(6)
	v_pk_mul_f32 v[156:157], v[202:203], v[152:153]
	v_pk_mul_f32 v[184:185], v[50:51], v[160:161] op_sel_hi:[1,0]
	v_pk_mul_f32 v[200:201], v[46:47], v[160:161] op_sel_hi:[1,0]
	v_pk_fma_f32 v[156:157], v[182:183], v[148:149], v[156:157] neg_lo:[0,0,1] neg_hi:[0,0,1]
	v_pk_mul_f32 v[152:153], v[182:183], v[152:153]
	v_lshlrev_b64 v[182:183], 8, v[162:163]
	v_pk_mul_f32 v[158:159], v[200:201], v[154:155]
	v_pk_mul_f32 v[154:155], v[184:185], v[154:155]
	v_lshl_add_u64 v[182:183], s[46:47], 0, v[182:183]
	s_movk_i32 s0, 0x1f7f
	v_pk_fma_f32 v[158:159], v[184:185], v[150:151], v[158:159] neg_lo:[0,0,1] neg_hi:[0,0,1]
	v_pk_fma_f32 v[150:151], v[200:201], v[150:151], v[154:155]
	v_pk_fma_f32 v[148:149], v[202:203], v[148:149], v[152:153]
	v_lshl_add_u64 v[182:183], v[176:177], 1, v[182:183]
	v_cmp_lt_u32_e32 vcc, s0, v2
	v_ashrrev_i32_e32 v181, 6, v162
	v_cvt_pk_bf16_f32 v152, v156, v157
	v_cvt_pk_bf16_f32 v153, v158, v159
	v_cvt_pk_bf16_f32 v154, v148, v149
	v_cvt_pk_bf16_f32 v155, v150, v151
	global_store_dwordx4 v[182:183], v[152:155], off sc1
	s_and_saveexec_b64 s[70:71], vcc
	s_cbranch_execz .LBB0_949
	v_and_b32_e32 v152, 0xffffff80, v181
	s_movk_i32 s0, 0xe080
	v_add3_u32 v152, v2, v152, s0
	v_ashrrev_i32_e32 v153, 31, v152
	v_lshlrev_b64 v[152:153], 9, v[152:153]
	v_lshl_add_u64 v[152:153], s[54:55], 0, v[152:153]
	v_lshl_add_u64 v[152:153], v[178:179], 2, v[152:153]
	global_store_dwordx4 v[152:153], v[156:159], off sc1
	global_store_dwordx4 v[152:153], v[148:151], off offset:128 sc1
.LBB0_949:
	s_or_b64 exec, exec, s[70:71]
	v_mov_b32_e32 v161, v160
	v_lshlrev_b64 v[162:163], 7, v[162:163]
	v_mov_b32_e32 v152, v160
	v_mov_b32_e32 v153, v160
	v_pk_mul_f32 v[150:151], v[42:43], v[152:153]
	v_pk_mul_f32 v[148:149], v[40:41], v[160:161]
	v_pk_mul_f32 v[154:155], v[38:39], v[152:153]
	v_pk_mul_f32 v[152:153], v[36:37], v[160:161]
	v_lshl_add_u64 v[160:161], v[162:163], 1, s[48:49]
	v_lshl_add_u64 v[160:161], v[176:177], 1, v[160:161]
	v_cvt_pk_bf16_f32 v156, v148, v149
	v_cvt_pk_bf16_f32 v157, v150, v151
	v_cvt_pk_bf16_f32 v158, v152, v153
	v_cvt_pk_bf16_f32 v159, v154, v155
	global_store_dwordx4 v[160:161], v[156:159], off sc1
	s_and_saveexec_b64 s[70:71], vcc
	s_cbranch_execz .LBB0_951
	v_and_b32_e32 v156, 0xffffff80, v181
	s_movk_i32 s0, 0xe080
	v_add3_u32 v156, v2, v156, s0
	v_ashrrev_i32_e32 v157, 31, v156
	v_lshlrev_b64 v[156:157], 9, v[156:157]
	v_lshl_add_u64 v[156:157], s[56:57], 0, v[156:157]
	v_lshl_add_u64 v[156:157], v[176:177], 2, v[156:157]
	global_store_dwordx4 v[156:157], v[148:151], off sc1
	global_store_dwordx4 v[156:157], v[152:155], off offset:16 sc1
.LBB0_951:
	s_or_b64 exec, exec, s[70:71]
	v_fmamk_f32 v2, v198, 0x3a800000, v1
	v_rsq_f32_e32 v152, v2
	v_add_u32_e32 v154, 0xa0, v180
	v_ashrrev_i32_e32 v155, 31, v154
	v_and_b32_e32 v2, 0x1fff, v154
	v_pk_mul_f32 v[162:163], v[28:29], v[152:153] op_sel_hi:[1,0]
	v_pk_mul_f32 v[156:157], v[32:33], v[152:153] op_sel_hi:[1,0]
	s_waitcnt vmcnt(6)
	v_pk_mul_f32 v[148:149], v[162:163], v[144:145]
	v_pk_mul_f32 v[144:145], v[156:157], v[144:145]
	v_pk_fma_f32 v[148:149], v[156:157], v[140:141], v[148:149] neg_lo:[0,0,1] neg_hi:[0,0,1]
	v_lshlrev_b64 v[156:157], 8, v[154:155]
	v_pk_mul_f32 v[158:159], v[34:35], v[152:153] op_sel_hi:[1,0]
	v_pk_mul_f32 v[160:161], v[30:31], v[152:153] op_sel_hi:[1,0]
	v_lshl_add_u64 v[156:157], s[46:47], 0, v[156:157]
	v_pk_mul_f32 v[150:151], v[160:161], v[146:147]
	v_pk_mul_f32 v[146:147], v[158:159], v[146:147]
	v_lshl_add_u64 v[156:157], v[176:177], 1, v[156:157]
	s_movk_i32 s0, 0x1f7f
	v_pk_fma_f32 v[150:151], v[158:159], v[142:143], v[150:151] neg_lo:[0,0,1] neg_hi:[0,0,1]
	v_pk_fma_f32 v[142:143], v[160:161], v[142:143], v[146:147]
	v_pk_fma_f32 v[140:141], v[162:163], v[140:141], v[144:145]
	v_cvt_pk_bf16_f32 v144, v148, v149
	v_cvt_pk_bf16_f32 v145, v150, v151
	v_cmp_lt_u32_e32 vcc, s0, v2
	v_cvt_pk_bf16_f32 v146, v140, v141
	v_cvt_pk_bf16_f32 v147, v142, v143
	global_store_dwordx4 v[156:157], v[144:147], off sc1
	v_ashrrev_i32_e32 v156, 6, v154
	s_and_saveexec_b64 s[70:71], vcc
	s_cbranch_execz .LBB0_953
	v_and_b32_e32 v144, 0xffffff80, v156
	s_movk_i32 s0, 0xe080
	v_add3_u32 v144, v2, v144, s0
	v_ashrrev_i32_e32 v145, 31, v144
	v_lshlrev_b64 v[144:145], 9, v[144:145]
	v_lshl_add_u64 v[144:145], s[54:55], 0, v[144:145]
	v_lshl_add_u64 v[144:145], v[178:179], 2, v[144:145]
	global_store_dwordx4 v[144:145], v[148:151], off sc1
	global_store_dwordx4 v[144:145], v[140:143], off offset:128 sc1
.LBB0_953:
	s_or_b64 exec, exec, s[70:71]
	v_mov_b32_e32 v153, v152
	v_lshlrev_b64 v[154:155], 7, v[154:155]
	v_mov_b32_e32 v144, v152
	v_mov_b32_e32 v145, v152
	v_pk_mul_f32 v[142:143], v[26:27], v[144:145]
	v_pk_mul_f32 v[140:141], v[24:25], v[152:153]
	v_pk_mul_f32 v[146:147], v[22:23], v[144:145]
	v_pk_mul_f32 v[144:145], v[20:21], v[152:153]
	v_lshl_add_u64 v[152:153], v[154:155], 1, s[48:49]
	v_lshl_add_u64 v[152:153], v[176:177], 1, v[152:153]
	v_cvt_pk_bf16_f32 v148, v140, v141
	v_cvt_pk_bf16_f32 v149, v142, v143
	v_cvt_pk_bf16_f32 v150, v144, v145
	v_cvt_pk_bf16_f32 v151, v146, v147
	global_store_dwordx4 v[152:153], v[148:151], off sc1
	s_and_saveexec_b64 s[70:71], vcc
	s_cbranch_execz .LBB0_955
	v_and_b32_e32 v148, 0xffffff80, v156
	s_movk_i32 s0, 0xe080
	v_add3_u32 v148, v2, v148, s0
	v_ashrrev_i32_e32 v149, 31, v148
	v_lshlrev_b64 v[148:149], 9, v[148:149]
	v_lshl_add_u64 v[148:149], s[56:57], 0, v[148:149]
	v_lshl_add_u64 v[148:149], v[176:177], 2, v[148:149]
	global_store_dwordx4 v[148:149], v[140:143], off sc1
	global_store_dwordx4 v[148:149], v[144:147], off offset:16 sc1
.LBB0_955:
	s_or_b64 exec, exec, s[70:71]
	v_fmamk_f32 v2, v197, 0x3a800000, v1
	v_rsq_f32_e32 v144, v2
	v_add_u32_e32 v146, 0xb0, v180
	v_ashrrev_i32_e32 v147, 31, v146
	v_and_b32_e32 v2, 0x1fff, v146
	v_pk_mul_f32 v[154:155], v[12:13], v[144:145] op_sel_hi:[1,0]
	v_pk_mul_f32 v[148:149], v[16:17], v[144:145] op_sel_hi:[1,0]
	s_waitcnt vmcnt(6)
	v_pk_mul_f32 v[140:141], v[154:155], v[136:137]
	v_pk_mul_f32 v[136:137], v[148:149], v[136:137]
	v_pk_fma_f32 v[140:141], v[148:149], v[132:133], v[140:141] neg_lo:[0,0,1] neg_hi:[0,0,1]
	v_lshlrev_b64 v[148:149], 8, v[146:147]
	v_pk_mul_f32 v[150:151], v[18:19], v[144:145] op_sel_hi:[1,0]
	v_pk_mul_f32 v[152:153], v[14:15], v[144:145] op_sel_hi:[1,0]
	v_lshl_add_u64 v[148:149], s[46:47], 0, v[148:149]
	v_pk_mul_f32 v[142:143], v[152:153], v[138:139]
	v_pk_mul_f32 v[138:139], v[150:151], v[138:139]
	v_lshl_add_u64 v[148:149], v[176:177], 1, v[148:149]
	s_movk_i32 s0, 0x1f7f
	v_pk_fma_f32 v[142:143], v[150:151], v[134:135], v[142:143] neg_lo:[0,0,1] neg_hi:[0,0,1]
	v_pk_fma_f32 v[134:135], v[152:153], v[134:135], v[138:139]
	v_pk_fma_f32 v[132:133], v[154:155], v[132:133], v[136:137]
	v_cvt_pk_bf16_f32 v136, v140, v141
	v_cvt_pk_bf16_f32 v137, v142, v143
	v_cmp_lt_u32_e32 vcc, s0, v2
	v_cvt_pk_bf16_f32 v138, v132, v133
	v_cvt_pk_bf16_f32 v139, v134, v135
	global_store_dwordx4 v[148:149], v[136:139], off sc1
	v_ashrrev_i32_e32 v148, 6, v146
	s_and_saveexec_b64 s[70:71], vcc
	s_cbranch_execz .LBB0_957
	v_and_b32_e32 v136, 0xffffff80, v148
	s_movk_i32 s0, 0xe080
	v_add3_u32 v136, v2, v136, s0
	v_ashrrev_i32_e32 v137, 31, v136
	v_lshlrev_b64 v[136:137], 9, v[136:137]
	v_lshl_add_u64 v[136:137], s[54:55], 0, v[136:137]
	v_lshl_add_u64 v[136:137], v[178:179], 2, v[136:137]
	global_store_dwordx4 v[136:137], v[140:143], off sc1
	global_store_dwordx4 v[136:137], v[132:135], off offset:128 sc1
.LBB0_957:
	s_or_b64 exec, exec, s[70:71]
	v_mov_b32_e32 v145, v144
	v_lshlrev_b64 v[146:147], 7, v[146:147]
	v_mov_b32_e32 v136, v144
	v_mov_b32_e32 v137, v144
	v_pk_mul_f32 v[134:135], v[10:11], v[136:137]
	v_pk_mul_f32 v[132:133], v[8:9], v[144:145]
	v_pk_mul_f32 v[138:139], v[6:7], v[136:137]
	v_pk_mul_f32 v[136:137], v[4:5], v[144:145]
	v_lshl_add_u64 v[144:145], v[146:147], 1, s[48:49]
	v_lshl_add_u64 v[144:145], v[176:177], 1, v[144:145]
	v_cvt_pk_bf16_f32 v140, v132, v133
	v_cvt_pk_bf16_f32 v141, v134, v135
	v_cvt_pk_bf16_f32 v142, v136, v137
	v_cvt_pk_bf16_f32 v143, v138, v139
	global_store_dwordx4 v[144:145], v[140:143], off sc1
	s_and_saveexec_b64 s[70:71], vcc
	s_cbranch_execz .LBB0_959
	v_and_b32_e32 v140, 0xffffff80, v148
	s_movk_i32 s0, 0xe080
	v_add3_u32 v140, v2, v140, s0
	v_ashrrev_i32_e32 v141, 31, v140
	v_lshlrev_b64 v[140:141], 9, v[140:141]
	v_lshl_add_u64 v[140:141], s[56:57], 0, v[140:141]
	v_lshl_add_u64 v[140:141], v[176:177], 2, v[140:141]
	global_store_dwordx4 v[140:141], v[132:135], off sc1
	global_store_dwordx4 v[140:141], v[136:139], off offset:16 sc1

.LBB0_960:
	s_and_b64 vcc, exec, s[70:71]
	s_cbranch_vccz .LBB0_962
	s_lshl_b32 s0, s68, 8
	s_add_i32 s0, s0, s90
	v_add_u32_e32 v138, s0, v191
	v_ashrrev_i32_e32 v139, 31, v138
	v_lshl_add_u64 v[132:133], v[138:139], 2, s[30:31]
	global_load_dword v2, v[132:133], off
	global_load_dword v155, v[132:133], off offset:64
	global_load_dword v153, v[132:133], off offset:128
	global_load_dword v151, v[132:133], off offset:192
	global_load_dword v149, v[132:133], off offset:512
	global_load_dword v147, v[132:133], off offset:576
	global_load_dword v145, v[132:133], off offset:640
	global_load_dword v143, v[132:133], off offset:704
	s_mov_b32 s70, 0xbfb8aa3b
	v_lshl_add_u32 v140, v190, 3, s91
	v_add_u32_e32 v154, 16, v138
	v_add_u32_e32 v152, 32, v138
	v_add_u32_e32 v150, 48, v138
	v_add_u32_e32 v148, 0x80, v138
	v_add_u32_e32 v146, 0x90, v138
	v_add_u32_e32 v144, 0xa0, v138
	v_add_u32_e32 v142, 0xb0, v138
	v_ashrrev_i32_e32 v141, 31, v140
	s_lshl_b32 s24, s62, 9
	s_waitcnt vmcnt(0)
	v_fmamk_f32 v2, v2, 0x3a800000, v1
	v_rsq_f32_e32 v2, v2
	s_nop 0
	v_pk_mul_f32 v[132:133], v[128:129], v[2:3] op_sel_hi:[1,0]
	v_pk_mul_f32 v[134:135], v[130:131], v[2:3] op_sel_hi:[1,0]
	v_pk_mul_f32 v[136:137], v[124:125], v[2:3] op_sel_hi:[1,0]
	v_pk_mul_f32 v[158:159], v[134:135], s[70:71] op_sel_hi:[1,0]
	v_pk_mul_f32 v[160:161], v[132:133], s[70:71] op_sel_hi:[1,0]
	v_pk_mul_f32 v[176:177], v[136:137], s[70:71] op_sel_hi:[1,0]
	v_pk_mul_f32 v[156:157], v[126:127], v[2:3] op_sel_hi:[1,0]
	v_exp_f32_e32 v160, v160
	v_exp_f32_e32 v176, v176
	v_exp_f32_e32 v161, v161
	v_exp_f32_e32 v177, v177
	v_exp_f32_e32 v158, v158
	v_exp_f32_e32 v159, v159
	v_pk_mul_f32 v[162:163], v[156:157], s[70:71] op_sel_hi:[1,0]
	v_pk_add_f32 v[160:161], v[160:161], 1.0 op_sel_hi:[1,0]
	v_exp_f32_e32 v162, v162
	v_exp_f32_e32 v163, v163
	v_pk_add_f32 v[158:159], v[158:159], 1.0 op_sel_hi:[1,0]
	v_pk_add_f32 v[176:177], v[176:177], 1.0 op_sel_hi:[1,0]
	v_rcp_f32_e32 v160, v160
	v_rcp_f32_e32 v176, v176
	v_rcp_f32_e32 v161, v161
	v_rcp_f32_e32 v177, v177
	v_rcp_f32_e32 v158, v158
	v_rcp_f32_e32 v159, v159
	v_pk_add_f32 v[162:163], v[162:163], 1.0 op_sel_hi:[1,0]
	v_pk_mul_f32 v[132:133], v[132:133], v[160:161]
	v_rcp_f32_e32 v162, v162
	v_rcp_f32_e32 v163, v163
	v_pk_mul_f32 v[134:135], v[134:135], v[158:159]
	v_pk_mul_f32 v[136:137], v[136:137], v[176:177]
	v_cvt_pk_bf16_f32 v132, v132, v133
	v_cvt_pk_bf16_f32 v133, v134, v135
	v_pk_mul_f32 v[156:157], v[156:157], v[162:163]
	v_cvt_pk_bf16_f32 v134, v136, v137
	v_mov_b64_e32 v[136:137], s[20:21]
	v_mad_i64_i32 v[138:139], s[2:3], v138, s16, v[136:137]
	v_cvt_pk_bf16_f32 v135, v156, v157
	v_lshl_add_u64 v[156:157], v[138:139], 0, s[24:25]
	v_lshlrev_b64 v[138:139], 1, v[140:141]
	v_lshl_add_u64 v[140:141], v[156:157], 0, v[138:139]
	global_store_dwordx4 v[140:141], v[132:135], off sc1
	v_pk_mul_f32 v[156:157], v[116:117], v[2:3] op_sel_hi:[1,0]
	v_pk_mul_f32 v[158:159], v[118:119], v[2:3] op_sel_hi:[1,0]
	v_pk_mul_f32 v[132:133], v[120:121], v[2:3] op_sel_hi:[1,0]
	v_pk_mul_f32 v[134:135], v[122:123], v[2:3] op_sel_hi:[1,0]
	v_pk_mul_f32 v[162:163], v[132:133], s[70:71] op_sel_hi:[1,0]
	v_pk_mul_f32 v[160:161], v[134:135], s[70:71] op_sel_hi:[1,0]
	v_pk_mul_f32 v[176:177], v[158:159], s[70:71] op_sel_hi:[1,0]
	v_pk_mul_f32 v[178:179], v[156:157], s[70:71] op_sel_hi:[1,0]
	v_exp_f32_e32 v162, v162
	v_exp_f32_e32 v163, v163
	v_exp_f32_e32 v160, v160
	v_exp_f32_e32 v161, v161
	v_exp_f32_e32 v178, v178
	v_exp_f32_e32 v179, v179
	v_exp_f32_e32 v176, v176
	v_exp_f32_e32 v177, v177
	v_pk_add_f32 v[160:161], v[160:161], 1.0 op_sel_hi:[1,0]
	v_pk_add_f32 v[162:163], v[162:163], 1.0 op_sel_hi:[1,0]
	v_pk_add_f32 v[178:179], v[178:179], 1.0 op_sel_hi:[1,0]
	v_pk_add_f32 v[176:177], v[176:177], 1.0 op_sel_hi:[1,0]
	v_rcp_f32_e32 v162, v162
	v_rcp_f32_e32 v163, v163
	v_rcp_f32_e32 v160, v160
	v_rcp_f32_e32 v161, v161
	v_rcp_f32_e32 v178, v178
	v_rcp_f32_e32 v179, v179
	v_rcp_f32_e32 v176, v176
	v_rcp_f32_e32 v177, v177
	v_fmamk_f32 v2, v155, 0x3a800000, v1
	v_rsq_f32_e32 v2, v2
	v_pk_mul_f32 v[134:135], v[134:135], v[160:161]
	v_pk_mul_f32 v[132:133], v[132:133], v[162:163]
	v_pk_mul_f32 v[158:159], v[158:159], v[176:177]
	v_pk_mul_f32 v[156:157], v[156:157], v[178:179]
	v_cvt_pk_bf16_f32 v132, v132, v133
	v_cvt_pk_bf16_f32 v133, v134, v135
	s_nop 0
	v_cvt_pk_bf16_f32 v134, v156, v157
	v_cvt_pk_bf16_f32 v135, v158, v159
	global_store_dwordx4 v[140:141], v[132:135], off offset:256 sc1
	v_pk_mul_f32 v[140:141], v[108:109], v[2:3] op_sel_hi:[1,0]
	v_pk_mul_f32 v[156:157], v[110:111], v[2:3] op_sel_hi:[1,0]
	v_pk_mul_f32 v[132:133], v[112:113], v[2:3] op_sel_hi:[1,0]
	v_pk_mul_f32 v[134:135], v[114:115], v[2:3] op_sel_hi:[1,0]
	v_pk_mul_f32 v[160:161], v[132:133], s[70:71] op_sel_hi:[1,0]
	v_pk_mul_f32 v[158:159], v[134:135], s[70:71] op_sel_hi:[1,0]
	v_pk_mul_f32 v[176:177], v[140:141], s[70:71] op_sel_hi:[1,0]
	v_exp_f32_e32 v160, v160
	v_exp_f32_e32 v176, v176
	v_exp_f32_e32 v161, v161
	v_exp_f32_e32 v177, v177
	v_exp_f32_e32 v158, v158
	v_exp_f32_e32 v159, v159
	v_pk_mul_f32 v[162:163], v[156:157], s[70:71] op_sel_hi:[1,0]
	v_pk_add_f32 v[160:161], v[160:161], 1.0 op_sel_hi:[1,0]
	v_exp_f32_e32 v162, v162
	v_exp_f32_e32 v163, v163
	v_pk_add_f32 v[158:159], v[158:159], 1.0 op_sel_hi:[1,0]
	v_pk_add_f32 v[176:177], v[176:177], 1.0 op_sel_hi:[1,0]
	v_rcp_f32_e32 v160, v160
	v_rcp_f32_e32 v176, v176
	v_rcp_f32_e32 v161, v161
	v_rcp_f32_e32 v177, v177
	v_rcp_f32_e32 v158, v158
	v_rcp_f32_e32 v159, v159
	v_pk_add_f32 v[162:163], v[162:163], 1.0 op_sel_hi:[1,0]
	v_pk_mul_f32 v[132:133], v[132:133], v[160:161]
	v_rcp_f32_e32 v162, v162
	v_rcp_f32_e32 v163, v163
	v_pk_mul_f32 v[134:135], v[134:135], v[158:159]
	v_pk_mul_f32 v[140:141], v[140:141], v[176:177]
	v_cvt_pk_bf16_f32 v132, v132, v133
	v_cvt_pk_bf16_f32 v133, v134, v135
	v_pk_mul_f32 v[156:157], v[156:157], v[162:163]
	v_cvt_pk_bf16_f32 v134, v140, v141
	v_mad_i64_i32 v[140:141], s[2:3], v154, s16, v[136:137]
	v_lshl_add_u64 v[140:141], v[140:141], 0, s[24:25]
	v_cvt_pk_bf16_f32 v135, v156, v157
	v_lshl_add_u64 v[140:141], v[140:141], 0, v[138:139]
	global_store_dwordx4 v[140:141], v[132:135], off sc1
	v_pk_mul_f32 v[154:155], v[100:101], v[2:3] op_sel_hi:[1,0]
	v_pk_mul_f32 v[156:157], v[102:103], v[2:3] op_sel_hi:[1,0]
	v_pk_mul_f32 v[132:133], v[104:105], v[2:3] op_sel_hi:[1,0]
	v_pk_mul_f32 v[134:135], v[106:107], v[2:3] op_sel_hi:[1,0]
	v_pk_mul_f32 v[160:161], v[132:133], s[70:71] op_sel_hi:[1,0]
	v_pk_mul_f32 v[158:159], v[134:135], s[70:71] op_sel_hi:[1,0]
	v_pk_mul_f32 v[162:163], v[156:157], s[70:71] op_sel_hi:[1,0]
	v_pk_mul_f32 v[176:177], v[154:155], s[70:71] op_sel_hi:[1,0]
	v_exp_f32_e32 v160, v160
	v_exp_f32_e32 v161, v161
	v_exp_f32_e32 v158, v158
	v_exp_f32_e32 v159, v159
	v_exp_f32_e32 v176, v176
	v_exp_f32_e32 v177, v177
	v_exp_f32_e32 v162, v162
	v_exp_f32_e32 v163, v163
	v_pk_add_f32 v[158:159], v[158:159], 1.0 op_sel_hi:[1,0]
	v_pk_add_f32 v[160:161], v[160:161], 1.0 op_sel_hi:[1,0]
	v_pk_add_f32 v[176:177], v[176:177], 1.0 op_sel_hi:[1,0]
	v_pk_add_f32 v[162:163], v[162:163], 1.0 op_sel_hi:[1,0]
	v_rcp_f32_e32 v160, v160
	v_rcp_f32_e32 v161, v161
	v_rcp_f32_e32 v158, v158
	v_rcp_f32_e32 v159, v159
	v_rcp_f32_e32 v176, v176
	v_rcp_f32_e32 v177, v177
	v_rcp_f32_e32 v162, v162
	v_rcp_f32_e32 v163, v163
	v_fmamk_f32 v2, v153, 0x3a800000, v1
	v_rsq_f32_e32 v2, v2
	v_pk_mul_f32 v[134:135], v[134:135], v[158:159]
	v_pk_mul_f32 v[132:133], v[132:133], v[160:161]
	v_pk_mul_f32 v[156:157], v[156:157], v[162:163]
	v_pk_mul_f32 v[154:155], v[154:155], v[176:177]
	v_cvt_pk_bf16_f32 v132, v132, v133
	v_cvt_pk_bf16_f32 v133, v134, v135
	s_nop 0
	v_cvt_pk_bf16_f32 v134, v154, v155
	v_cvt_pk_bf16_f32 v135, v156, v157
	global_store_dwordx4 v[140:141], v[132:135], off offset:256 sc1
	v_pk_mul_f32 v[140:141], v[92:93], v[2:3] op_sel_hi:[1,0]
	v_pk_mul_f32 v[154:155], v[94:95], v[2:3] op_sel_hi:[1,0]
	v_pk_mul_f32 v[132:133], v[96:97], v[2:3] op_sel_hi:[1,0]
	v_pk_mul_f32 v[134:135], v[98:99], v[2:3] op_sel_hi:[1,0]
	v_pk_mul_f32 v[158:159], v[132:133], s[70:71] op_sel_hi:[1,0]
	v_pk_mul_f32 v[156:157], v[134:135], s[70:71] op_sel_hi:[1,0]
	v_pk_mul_f32 v[162:163], v[140:141], s[70:71] op_sel_hi:[1,0]
	v_exp_f32_e32 v158, v158
	v_exp_f32_e32 v162, v162
	v_exp_f32_e32 v159, v159
	v_exp_f32_e32 v163, v163
	v_exp_f32_e32 v156, v156
	v_exp_f32_e32 v157, v157
	v_pk_mul_f32 v[160:161], v[154:155], s[70:71] op_sel_hi:[1,0]
	v_pk_add_f32 v[158:159], v[158:159], 1.0 op_sel_hi:[1,0]
	v_exp_f32_e32 v160, v160
	v_exp_f32_e32 v161, v161
	v_pk_add_f32 v[156:157], v[156:157], 1.0 op_sel_hi:[1,0]
	v_pk_add_f32 v[162:163], v[162:163], 1.0 op_sel_hi:[1,0]
	v_rcp_f32_e32 v158, v158
	v_rcp_f32_e32 v162, v162
	v_rcp_f32_e32 v159, v159
	v_rcp_f32_e32 v163, v163
	v_rcp_f32_e32 v156, v156
	v_rcp_f32_e32 v157, v157
	v_pk_add_f32 v[160:161], v[160:161], 1.0 op_sel_hi:[1,0]
	v_pk_mul_f32 v[132:133], v[132:133], v[158:159]
	v_rcp_f32_e32 v160, v160
	v_rcp_f32_e32 v161, v161
	v_pk_mul_f32 v[134:135], v[134:135], v[156:157]
	v_pk_mul_f32 v[140:141], v[140:141], v[162:163]
	v_cvt_pk_bf16_f32 v132, v132, v133
	v_cvt_pk_bf16_f32 v133, v134, v135
	v_pk_mul_f32 v[154:155], v[154:155], v[160:161]
	v_cvt_pk_bf16_f32 v134, v140, v141
	v_mad_i64_i32 v[140:141], s[2:3], v152, s16, v[136:137]
	v_lshl_add_u64 v[140:141], v[140:141], 0, s[24:25]
	v_cvt_pk_bf16_f32 v135, v154, v155
	v_lshl_add_u64 v[140:141], v[140:141], 0, v[138:139]
	global_store_dwordx4 v[140:141], v[132:135], off sc1
	v_pk_mul_f32 v[152:153], v[84:85], v[2:3] op_sel_hi:[1,0]
	v_pk_mul_f32 v[154:155], v[86:87], v[2:3] op_sel_hi:[1,0]
	v_pk_mul_f32 v[132:133], v[88:89], v[2:3] op_sel_hi:[1,0]
	v_pk_mul_f32 v[134:135], v[90:91], v[2:3] op_sel_hi:[1,0]
	v_pk_mul_f32 v[158:159], v[132:133], s[70:71] op_sel_hi:[1,0]
	v_pk_mul_f32 v[156:157], v[134:135], s[70:71] op_sel_hi:[1,0]
	v_pk_mul_f32 v[160:161], v[154:155], s[70:71] op_sel_hi:[1,0]
	v_pk_mul_f32 v[162:163], v[152:153], s[70:71] op_sel_hi:[1,0]
	v_exp_f32_e32 v158, v158
	v_exp_f32_e32 v159, v159
	v_exp_f32_e32 v156, v156
	v_exp_f32_e32 v157, v157
	v_exp_f32_e32 v162, v162
	v_exp_f32_e32 v163, v163
	v_exp_f32_e32 v160, v160
	v_exp_f32_e32 v161, v161
	v_pk_add_f32 v[156:157], v[156:157], 1.0 op_sel_hi:[1,0]
	v_pk_add_f32 v[158:159], v[158:159], 1.0 op_sel_hi:[1,0]
	v_pk_add_f32 v[162:163], v[162:163], 1.0 op_sel_hi:[1,0]
	v_pk_add_f32 v[160:161], v[160:161], 1.0 op_sel_hi:[1,0]
	v_rcp_f32_e32 v158, v158
	v_rcp_f32_e32 v159, v159
	v_rcp_f32_e32 v156, v156
	v_rcp_f32_e32 v157, v157
	v_rcp_f32_e32 v162, v162
	v_rcp_f32_e32 v163, v163
	v_rcp_f32_e32 v160, v160
	v_rcp_f32_e32 v161, v161
	v_fmamk_f32 v2, v151, 0x3a800000, v1
	v_rsq_f32_e32 v2, v2
	v_pk_mul_f32 v[134:135], v[134:135], v[156:157]
	v_pk_mul_f32 v[132:133], v[132:133], v[158:159]
	v_pk_mul_f32 v[154:155], v[154:155], v[160:161]
	v_pk_mul_f32 v[152:153], v[152:153], v[162:163]
	v_cvt_pk_bf16_f32 v132, v132, v133
	v_cvt_pk_bf16_f32 v133, v134, v135
	s_nop 0
	v_cvt_pk_bf16_f32 v134, v152, v153
	v_cvt_pk_bf16_f32 v135, v154, v155
	global_store_dwordx4 v[140:141], v[132:135], off offset:256 sc1
	v_pk_mul_f32 v[140:141], v[76:77], v[2:3] op_sel_hi:[1,0]
	v_pk_mul_f32 v[152:153], v[78:79], v[2:3] op_sel_hi:[1,0]
	v_pk_mul_f32 v[132:133], v[80:81], v[2:3] op_sel_hi:[1,0]
	v_pk_mul_f32 v[134:135], v[82:83], v[2:3] op_sel_hi:[1,0]
	v_pk_mul_f32 v[156:157], v[132:133], s[70:71] op_sel_hi:[1,0]
	v_pk_mul_f32 v[154:155], v[134:135], s[70:71] op_sel_hi:[1,0]
	v_pk_mul_f32 v[160:161], v[140:141], s[70:71] op_sel_hi:[1,0]
	v_exp_f32_e32 v156, v156
	v_exp_f32_e32 v160, v160
	v_exp_f32_e32 v157, v157
	v_exp_f32_e32 v161, v161
	v_exp_f32_e32 v154, v154
	v_exp_f32_e32 v155, v155
	v_pk_mul_f32 v[158:159], v[152:153], s[70:71] op_sel_hi:[1,0]
	v_pk_add_f32 v[156:157], v[156:157], 1.0 op_sel_hi:[1,0]
	v_exp_f32_e32 v158, v158
	v_exp_f32_e32 v159, v159
	v_pk_add_f32 v[154:155], v[154:155], 1.0 op_sel_hi:[1,0]
	v_pk_add_f32 v[160:161], v[160:161], 1.0 op_sel_hi:[1,0]
	v_rcp_f32_e32 v156, v156
	v_rcp_f32_e32 v160, v160
	v_rcp_f32_e32 v157, v157
	v_rcp_f32_e32 v161, v161
	v_rcp_f32_e32 v154, v154
	v_rcp_f32_e32 v155, v155
	v_pk_add_f32 v[158:159], v[158:159], 1.0 op_sel_hi:[1,0]
	v_pk_mul_f32 v[132:133], v[132:133], v[156:157]
	v_rcp_f32_e32 v158, v158
	v_rcp_f32_e32 v159, v159
	v_pk_mul_f32 v[134:135], v[134:135], v[154:155]
	v_pk_mul_f32 v[140:141], v[140:141], v[160:161]
	v_cvt_pk_bf16_f32 v132, v132, v133
	v_cvt_pk_bf16_f32 v133, v134, v135
	v_pk_mul_f32 v[152:153], v[152:153], v[158:159]
	v_cvt_pk_bf16_f32 v134, v140, v141
	v_mad_i64_i32 v[140:141], s[2:3], v150, s16, v[136:137]
	v_lshl_add_u64 v[140:141], v[140:141], 0, s[24:25]
	v_cvt_pk_bf16_f32 v135, v152, v153
	v_lshl_add_u64 v[140:141], v[140:141], 0, v[138:139]
	global_store_dwordx4 v[140:141], v[132:135], off sc1
	v_pk_mul_f32 v[150:151], v[68:69], v[2:3] op_sel_hi:[1,0]
	v_pk_mul_f32 v[152:153], v[70:71], v[2:3] op_sel_hi:[1,0]
	v_pk_mul_f32 v[132:133], v[72:73], v[2:3] op_sel_hi:[1,0]
	v_pk_mul_f32 v[134:135], v[74:75], v[2:3] op_sel_hi:[1,0]
	v_pk_mul_f32 v[156:157], v[132:133], s[70:71] op_sel_hi:[1,0]
	v_pk_mul_f32 v[154:155], v[134:135], s[70:71] op_sel_hi:[1,0]
	v_pk_mul_f32 v[158:159], v[152:153], s[70:71] op_sel_hi:[1,0]
	v_pk_mul_f32 v[160:161], v[150:151], s[70:71] op_sel_hi:[1,0]
	v_exp_f32_e32 v156, v156
	v_exp_f32_e32 v157, v157
	v_exp_f32_e32 v154, v154
	v_exp_f32_e32 v155, v155
	v_exp_f32_e32 v160, v160
	v_exp_f32_e32 v161, v161
	v_exp_f32_e32 v158, v158
	v_exp_f32_e32 v159, v159
	v_pk_add_f32 v[154:155], v[154:155], 1.0 op_sel_hi:[1,0]
	v_pk_add_f32 v[156:157], v[156:157], 1.0 op_sel_hi:[1,0]
	v_pk_add_f32 v[160:161], v[160:161], 1.0 op_sel_hi:[1,0]
	v_pk_add_f32 v[158:159], v[158:159], 1.0 op_sel_hi:[1,0]
	v_rcp_f32_e32 v156, v156
	v_rcp_f32_e32 v157, v157
	v_rcp_f32_e32 v154, v154
	v_rcp_f32_e32 v155, v155
	v_rcp_f32_e32 v160, v160
	v_rcp_f32_e32 v161, v161
	v_rcp_f32_e32 v158, v158
	v_rcp_f32_e32 v159, v159
	v_fmamk_f32 v2, v149, 0x3a800000, v1
	v_rsq_f32_e32 v2, v2
	v_pk_mul_f32 v[134:135], v[134:135], v[154:155]
	v_pk_mul_f32 v[132:133], v[132:133], v[156:157]
	v_pk_mul_f32 v[152:153], v[152:153], v[158:159]
	v_pk_mul_f32 v[150:151], v[150:151], v[160:161]
	v_cvt_pk_bf16_f32 v132, v132, v133
	v_cvt_pk_bf16_f32 v133, v134, v135
	s_nop 0
	v_cvt_pk_bf16_f32 v134, v150, v151
	v_cvt_pk_bf16_f32 v135, v152, v153
	global_store_dwordx4 v[140:141], v[132:135], off offset:256 sc1
	v_pk_mul_f32 v[140:141], v[60:61], v[2:3] op_sel_hi:[1,0]
	v_pk_mul_f32 v[150:151], v[62:63], v[2:3] op_sel_hi:[1,0]
	v_pk_mul_f32 v[132:133], v[64:65], v[2:3] op_sel_hi:[1,0]
	v_pk_mul_f32 v[134:135], v[66:67], v[2:3] op_sel_hi:[1,0]
	v_pk_mul_f32 v[154:155], s[70:71], v[132:133] op_sel_hi:[0,1]
	v_pk_mul_f32 v[152:153], s[70:71], v[134:135] op_sel_hi:[0,1]
	v_pk_mul_f32 v[158:159], s[70:71], v[140:141] op_sel_hi:[0,1]
	v_exp_f32_e32 v154, v154
	v_exp_f32_e32 v158, v158
	v_exp_f32_e32 v155, v155
	v_exp_f32_e32 v159, v159
	v_exp_f32_e32 v152, v152
	v_exp_f32_e32 v153, v153
	v_pk_mul_f32 v[156:157], s[70:71], v[150:151] op_sel_hi:[0,1]
	v_exp_f32_e32 v156, v156
	v_exp_f32_e32 v157, v157
	v_pk_add_f32 v[152:153], v[152:153], 1.0 op_sel_hi:[1,0]
	v_pk_add_f32 v[154:155], v[154:155], 1.0 op_sel_hi:[1,0]
	v_pk_add_f32 v[158:159], v[158:159], 1.0 op_sel_hi:[1,0]
	v_rcp_f32_e32 v154, v154
	v_rcp_f32_e32 v158, v158
	v_rcp_f32_e32 v155, v155
	v_rcp_f32_e32 v159, v159
	v_rcp_f32_e32 v152, v152
	v_rcp_f32_e32 v153, v153
	v_pk_add_f32 v[156:157], v[156:157], 1.0 op_sel_hi:[1,0]
	v_pk_mul_f32 v[132:133], v[132:133], v[154:155]
	v_rcp_f32_e32 v156, v156
	v_rcp_f32_e32 v157, v157
	v_pk_mul_f32 v[134:135], v[134:135], v[152:153]
	v_pk_mul_f32 v[140:141], v[140:141], v[158:159]
	v_cvt_pk_bf16_f32 v132, v132, v133
	v_cvt_pk_bf16_f32 v133, v134, v135
	v_pk_mul_f32 v[150:151], v[150:151], v[156:157]
	v_cvt_pk_bf16_f32 v134, v140, v141
	v_mad_i64_i32 v[140:141], s[2:3], v148, s16, v[136:137]
	v_lshl_add_u64 v[140:141], v[140:141], 0, s[24:25]
	v_cvt_pk_bf16_f32 v135, v150, v151
	v_lshl_add_u64 v[140:141], v[140:141], 0, v[138:139]
	global_store_dwordx4 v[140:141], v[132:135], off sc1
	v_pk_mul_f32 v[148:149], v[52:53], v[2:3] op_sel_hi:[1,0]
	v_pk_mul_f32 v[150:151], v[54:55], v[2:3] op_sel_hi:[1,0]
	v_pk_mul_f32 v[132:133], v[56:57], v[2:3] op_sel_hi:[1,0]
	v_pk_mul_f32 v[134:135], v[58:59], v[2:3] op_sel_hi:[1,0]
	v_pk_mul_f32 v[154:155], s[70:71], v[132:133] op_sel_hi:[0,1]
	v_pk_mul_f32 v[152:153], s[70:71], v[134:135] op_sel_hi:[0,1]
	v_pk_mul_f32 v[156:157], s[70:71], v[150:151] op_sel_hi:[0,1]
	v_pk_mul_f32 v[158:159], s[70:71], v[148:149] op_sel_hi:[0,1]
	v_exp_f32_e32 v154, v154
	v_exp_f32_e32 v155, v155
	v_exp_f32_e32 v152, v152
	v_exp_f32_e32 v153, v153
	v_exp_f32_e32 v158, v158
	v_exp_f32_e32 v159, v159
	v_exp_f32_e32 v156, v156
	v_exp_f32_e32 v157, v157
	v_pk_add_f32 v[152:153], v[152:153], 1.0 op_sel_hi:[1,0]
	v_pk_add_f32 v[154:155], v[154:155], 1.0 op_sel_hi:[1,0]
	v_pk_add_f32 v[158:159], v[158:159], 1.0 op_sel_hi:[1,0]
	v_pk_add_f32 v[156:157], v[156:157], 1.0 op_sel_hi:[1,0]
	v_rcp_f32_e32 v154, v154
	v_rcp_f32_e32 v155, v155
	v_rcp_f32_e32 v152, v152
	v_rcp_f32_e32 v153, v153
	v_rcp_f32_e32 v158, v158
	v_rcp_f32_e32 v159, v159
	v_rcp_f32_e32 v156, v156
	v_rcp_f32_e32 v157, v157
	v_fmamk_f32 v2, v147, 0x3a800000, v1
	v_rsq_f32_e32 v2, v2
	v_pk_mul_f32 v[134:135], v[134:135], v[152:153]
	v_pk_mul_f32 v[132:133], v[132:133], v[154:155]
	v_pk_mul_f32 v[150:151], v[150:151], v[156:157]
	v_pk_mul_f32 v[148:149], v[148:149], v[158:159]
	v_cvt_pk_bf16_f32 v132, v132, v133
	v_cvt_pk_bf16_f32 v133, v134, v135
	s_nop 0
	v_cvt_pk_bf16_f32 v134, v148, v149
	v_cvt_pk_bf16_f32 v135, v150, v151
	global_store_dwordx4 v[140:141], v[132:135], off offset:256 sc1
	v_pk_mul_f32 v[140:141], v[44:45], v[2:3] op_sel_hi:[1,0]
	v_pk_mul_f32 v[148:149], v[46:47], v[2:3] op_sel_hi:[1,0]
	v_pk_mul_f32 v[132:133], v[48:49], v[2:3] op_sel_hi:[1,0]
	v_pk_mul_f32 v[134:135], v[50:51], v[2:3] op_sel_hi:[1,0]
	v_pk_mul_f32 v[152:153], s[70:71], v[132:133] op_sel_hi:[0,1]
	v_pk_mul_f32 v[150:151], s[70:71], v[134:135] op_sel_hi:[0,1]
	v_pk_mul_f32 v[156:157], s[70:71], v[140:141] op_sel_hi:[0,1]
	v_exp_f32_e32 v152, v152
	v_exp_f32_e32 v156, v156
	v_exp_f32_e32 v153, v153
	v_exp_f32_e32 v157, v157
	v_exp_f32_e32 v150, v150
	v_exp_f32_e32 v151, v151
	v_pk_mul_f32 v[154:155], s[70:71], v[148:149] op_sel_hi:[0,1]
	v_exp_f32_e32 v154, v154
	v_exp_f32_e32 v155, v155
	v_pk_add_f32 v[150:151], v[150:151], 1.0 op_sel_hi:[1,0]
	v_pk_add_f32 v[152:153], v[152:153], 1.0 op_sel_hi:[1,0]
	v_pk_add_f32 v[156:157], v[156:157], 1.0 op_sel_hi:[1,0]
	v_rcp_f32_e32 v152, v152
	v_rcp_f32_e32 v156, v156
	v_rcp_f32_e32 v153, v153
	v_rcp_f32_e32 v157, v157
	v_rcp_f32_e32 v150, v150
	v_rcp_f32_e32 v151, v151
	v_pk_add_f32 v[154:155], v[154:155], 1.0 op_sel_hi:[1,0]
	v_pk_mul_f32 v[132:133], v[132:133], v[152:153]
	v_rcp_f32_e32 v154, v154
	v_rcp_f32_e32 v155, v155
	v_pk_mul_f32 v[134:135], v[134:135], v[150:151]
	v_pk_mul_f32 v[140:141], v[140:141], v[156:157]
	v_cvt_pk_bf16_f32 v132, v132, v133
	v_cvt_pk_bf16_f32 v133, v134, v135
	v_pk_mul_f32 v[148:149], v[148:149], v[154:155]
	v_cvt_pk_bf16_f32 v134, v140, v141
	v_mad_i64_i32 v[140:141], s[2:3], v146, s16, v[136:137]
	v_lshl_add_u64 v[140:141], v[140:141], 0, s[24:25]
	v_cvt_pk_bf16_f32 v135, v148, v149
	v_lshl_add_u64 v[140:141], v[140:141], 0, v[138:139]
	global_store_dwordx4 v[140:141], v[132:135], off sc1
	v_pk_mul_f32 v[146:147], v[36:37], v[2:3] op_sel_hi:[1,0]
	v_pk_mul_f32 v[148:149], v[38:39], v[2:3] op_sel_hi:[1,0]
	v_pk_mul_f32 v[132:133], v[40:41], v[2:3] op_sel_hi:[1,0]
	v_pk_mul_f32 v[134:135], v[42:43], v[2:3] op_sel_hi:[1,0]
	v_pk_mul_f32 v[152:153], s[70:71], v[132:133] op_sel_hi:[0,1]
	v_pk_mul_f32 v[150:151], s[70:71], v[134:135] op_sel_hi:[0,1]
	v_pk_mul_f32 v[154:155], s[70:71], v[148:149] op_sel_hi:[0,1]
	v_pk_mul_f32 v[156:157], s[70:71], v[146:147] op_sel_hi:[0,1]
	v_exp_f32_e32 v152, v152
	v_exp_f32_e32 v153, v153
	v_exp_f32_e32 v150, v150
	v_exp_f32_e32 v151, v151
	v_exp_f32_e32 v156, v156
	v_exp_f32_e32 v157, v157
	v_exp_f32_e32 v154, v154
	v_exp_f32_e32 v155, v155
	v_pk_add_f32 v[150:151], v[150:151], 1.0 op_sel_hi:[1,0]
	v_pk_add_f32 v[152:153], v[152:153], 1.0 op_sel_hi:[1,0]
	v_pk_add_f32 v[156:157], v[156:157], 1.0 op_sel_hi:[1,0]
	v_pk_add_f32 v[154:155], v[154:155], 1.0 op_sel_hi:[1,0]
	v_rcp_f32_e32 v152, v152
	v_rcp_f32_e32 v153, v153
	v_rcp_f32_e32 v150, v150
	v_rcp_f32_e32 v151, v151
	v_rcp_f32_e32 v156, v156
	v_rcp_f32_e32 v157, v157
	v_rcp_f32_e32 v154, v154
	v_rcp_f32_e32 v155, v155
	v_fmamk_f32 v2, v145, 0x3a800000, v1
	v_rsq_f32_e32 v2, v2
	v_pk_mul_f32 v[134:135], v[134:135], v[150:151]
	v_pk_mul_f32 v[132:133], v[132:133], v[152:153]
	v_pk_mul_f32 v[148:149], v[148:149], v[154:155]
	v_pk_mul_f32 v[146:147], v[146:147], v[156:157]
	v_cvt_pk_bf16_f32 v132, v132, v133
	v_cvt_pk_bf16_f32 v133, v134, v135
	s_nop 0
	v_cvt_pk_bf16_f32 v134, v146, v147
	v_cvt_pk_bf16_f32 v135, v148, v149
	global_store_dwordx4 v[140:141], v[132:135], off offset:256 sc1
	v_pk_mul_f32 v[140:141], v[28:29], v[2:3] op_sel_hi:[1,0]
	v_pk_mul_f32 v[146:147], v[30:31], v[2:3] op_sel_hi:[1,0]
	v_pk_mul_f32 v[132:133], v[32:33], v[2:3] op_sel_hi:[1,0]
	v_pk_mul_f32 v[134:135], v[34:35], v[2:3] op_sel_hi:[1,0]
	v_pk_mul_f32 v[150:151], s[70:71], v[132:133] op_sel_hi:[0,1]
	v_pk_mul_f32 v[148:149], s[70:71], v[134:135] op_sel_hi:[0,1]
	v_pk_mul_f32 v[154:155], s[70:71], v[140:141] op_sel_hi:[0,1]
	v_exp_f32_e32 v150, v150
	v_exp_f32_e32 v154, v154
	v_exp_f32_e32 v151, v151
	v_exp_f32_e32 v155, v155
	v_exp_f32_e32 v148, v148
	v_exp_f32_e32 v149, v149
	v_pk_mul_f32 v[152:153], s[70:71], v[146:147] op_sel_hi:[0,1]
	v_exp_f32_e32 v152, v152
	v_exp_f32_e32 v153, v153
	v_pk_add_f32 v[148:149], v[148:149], 1.0 op_sel_hi:[1,0]
	v_pk_add_f32 v[150:151], v[150:151], 1.0 op_sel_hi:[1,0]
	v_pk_add_f32 v[154:155], v[154:155], 1.0 op_sel_hi:[1,0]
	v_rcp_f32_e32 v150, v150
	v_rcp_f32_e32 v154, v154
	v_rcp_f32_e32 v151, v151
	v_rcp_f32_e32 v155, v155
	v_rcp_f32_e32 v148, v148
	v_rcp_f32_e32 v149, v149
	v_pk_add_f32 v[152:153], v[152:153], 1.0 op_sel_hi:[1,0]
	v_pk_mul_f32 v[132:133], v[132:133], v[150:151]
	v_rcp_f32_e32 v152, v152
	v_rcp_f32_e32 v153, v153
	v_pk_mul_f32 v[134:135], v[134:135], v[148:149]
	v_pk_mul_f32 v[140:141], v[140:141], v[154:155]
	v_cvt_pk_bf16_f32 v132, v132, v133
	v_cvt_pk_bf16_f32 v133, v134, v135
	v_pk_mul_f32 v[146:147], v[146:147], v[152:153]
	v_cvt_pk_bf16_f32 v134, v140, v141
	v_mad_i64_i32 v[140:141], s[2:3], v144, s16, v[136:137]
	v_lshl_add_u64 v[140:141], v[140:141], 0, s[24:25]
	v_cvt_pk_bf16_f32 v135, v146, v147
	v_lshl_add_u64 v[140:141], v[140:141], 0, v[138:139]
	global_store_dwordx4 v[140:141], v[132:135], off sc1
	v_pk_mul_f32 v[144:145], v[20:21], v[2:3] op_sel_hi:[1,0]
	v_pk_mul_f32 v[146:147], v[22:23], v[2:3] op_sel_hi:[1,0]
	v_pk_mul_f32 v[132:133], v[24:25], v[2:3] op_sel_hi:[1,0]
	v_pk_mul_f32 v[134:135], v[26:27], v[2:3] op_sel_hi:[1,0]
	v_pk_mul_f32 v[150:151], s[70:71], v[132:133] op_sel_hi:[0,1]
	v_pk_mul_f32 v[148:149], s[70:71], v[134:135] op_sel_hi:[0,1]
	v_pk_mul_f32 v[152:153], s[70:71], v[146:147] op_sel_hi:[0,1]
	v_pk_mul_f32 v[154:155], s[70:71], v[144:145] op_sel_hi:[0,1]
	v_exp_f32_e32 v150, v150
	v_exp_f32_e32 v151, v151
	v_exp_f32_e32 v148, v148
	v_exp_f32_e32 v149, v149
	v_exp_f32_e32 v154, v154
	v_exp_f32_e32 v155, v155
	v_exp_f32_e32 v152, v152
	v_exp_f32_e32 v153, v153
	v_pk_add_f32 v[148:149], v[148:149], 1.0 op_sel_hi:[1,0]
	v_pk_add_f32 v[150:151], v[150:151], 1.0 op_sel_hi:[1,0]
	v_pk_add_f32 v[154:155], v[154:155], 1.0 op_sel_hi:[1,0]
	v_pk_add_f32 v[152:153], v[152:153], 1.0 op_sel_hi:[1,0]
	v_rcp_f32_e32 v150, v150
	v_rcp_f32_e32 v151, v151
	v_rcp_f32_e32 v148, v148
	v_rcp_f32_e32 v149, v149
	v_rcp_f32_e32 v154, v154
	v_rcp_f32_e32 v155, v155
	v_rcp_f32_e32 v152, v152
	v_rcp_f32_e32 v153, v153
	v_fmamk_f32 v2, v143, 0x3a800000, v1
	v_rsq_f32_e32 v2, v2
	v_pk_mul_f32 v[134:135], v[134:135], v[148:149]
	v_pk_mul_f32 v[132:133], v[132:133], v[150:151]
	v_pk_mul_f32 v[146:147], v[146:147], v[152:153]
	v_pk_mul_f32 v[144:145], v[144:145], v[154:155]
	v_cvt_pk_bf16_f32 v132, v132, v133
	v_cvt_pk_bf16_f32 v133, v134, v135
	v_mad_i64_i32 v[136:137], s[2:3], v142, s16, v[136:137]
	v_cvt_pk_bf16_f32 v134, v144, v145
	v_cvt_pk_bf16_f32 v135, v146, v147
	global_store_dwordx4 v[140:141], v[132:135], off offset:256 sc1
	v_pk_mul_f32 v[140:141], v[12:13], v[2:3] op_sel_hi:[1,0]
	v_pk_mul_f32 v[144:145], v[14:15], v[2:3] op_sel_hi:[1,0]
	v_pk_mul_f32 v[132:133], v[16:17], v[2:3] op_sel_hi:[1,0]
	v_pk_mul_f32 v[134:135], v[18:19], v[2:3] op_sel_hi:[1,0]
	v_pk_mul_f32 v[148:149], s[70:71], v[132:133] op_sel_hi:[0,1]
	v_pk_mul_f32 v[146:147], s[70:71], v[134:135] op_sel_hi:[0,1]
	v_pk_mul_f32 v[150:151], s[70:71], v[144:145] op_sel_hi:[0,1]
	v_pk_mul_f32 v[152:153], s[70:71], v[140:141] op_sel_hi:[0,1]
	v_exp_f32_e32 v148, v148
	v_exp_f32_e32 v149, v149
	v_exp_f32_e32 v146, v146
	v_exp_f32_e32 v147, v147
	v_exp_f32_e32 v152, v152
	v_exp_f32_e32 v153, v153
	v_exp_f32_e32 v150, v150
	v_exp_f32_e32 v151, v151
	v_pk_add_f32 v[146:147], v[146:147], 1.0 op_sel_hi:[1,0]
	v_pk_add_f32 v[148:149], v[148:149], 1.0 op_sel_hi:[1,0]
	v_pk_add_f32 v[152:153], v[152:153], 1.0 op_sel_hi:[1,0]
	v_pk_add_f32 v[150:151], v[150:151], 1.0 op_sel_hi:[1,0]
	v_rcp_f32_e32 v148, v148
	v_rcp_f32_e32 v149, v149
	v_rcp_f32_e32 v146, v146
	v_rcp_f32_e32 v147, v147
	v_rcp_f32_e32 v152, v152
	v_rcp_f32_e32 v153, v153
	v_rcp_f32_e32 v150, v150
	v_rcp_f32_e32 v151, v151
	v_pk_mul_f32 v[134:135], v[134:135], v[146:147]
	v_pk_mul_f32 v[132:133], v[132:133], v[148:149]
	v_lshl_add_u64 v[136:137], v[136:137], 0, s[24:25]
	v_pk_mul_f32 v[144:145], v[144:145], v[150:151]
	v_pk_mul_f32 v[140:141], v[140:141], v[152:153]
	v_cvt_pk_bf16_f32 v132, v132, v133
	v_cvt_pk_bf16_f32 v133, v134, v135
	v_lshl_add_u64 v[136:137], v[136:137], 0, v[138:139]
	v_cvt_pk_bf16_f32 v134, v140, v141
	v_cvt_pk_bf16_f32 v135, v144, v145
	global_store_dwordx4 v[136:137], v[132:135], off sc1
	v_pk_mul_f32 v[138:139], v[4:5], v[2:3] op_sel_hi:[1,0]
	v_pk_mul_f32 v[140:141], v[6:7], v[2:3] op_sel_hi:[1,0]
	v_pk_mul_f32 v[132:133], v[8:9], v[2:3] op_sel_hi:[1,0]
	v_pk_mul_f32 v[134:135], v[10:11], v[2:3] op_sel_hi:[1,0]
	v_pk_mul_f32 v[144:145], s[70:71], v[132:133] op_sel_hi:[0,1]
	v_pk_mul_f32 v[142:143], s[70:71], v[134:135] op_sel_hi:[0,1]
	v_pk_mul_f32 v[146:147], s[70:71], v[140:141] op_sel_hi:[0,1]
	v_pk_mul_f32 v[148:149], s[70:71], v[138:139] op_sel_hi:[0,1]
	v_exp_f32_e32 v144, v144
	v_exp_f32_e32 v145, v145
	v_exp_f32_e32 v142, v142
	v_exp_f32_e32 v143, v143
	v_exp_f32_e32 v148, v148
	v_exp_f32_e32 v149, v149
	v_exp_f32_e32 v146, v146
	v_exp_f32_e32 v147, v147
	v_pk_add_f32 v[142:143], v[142:143], 1.0 op_sel_hi:[1,0]
	v_pk_add_f32 v[144:145], v[144:145], 1.0 op_sel_hi:[1,0]
	v_pk_add_f32 v[148:149], v[148:149], 1.0 op_sel_hi:[1,0]
	v_pk_add_f32 v[146:147], v[146:147], 1.0 op_sel_hi:[1,0]
	v_rcp_f32_e32 v144, v144
	v_rcp_f32_e32 v145, v145
	v_rcp_f32_e32 v142, v142
	v_rcp_f32_e32 v143, v143
	v_rcp_f32_e32 v148, v148
	v_rcp_f32_e32 v149, v149
	v_rcp_f32_e32 v146, v146
	v_rcp_f32_e32 v147, v147
	v_pk_mul_f32 v[134:135], v[134:135], v[142:143]
	v_pk_mul_f32 v[132:133], v[132:133], v[144:145]
	v_pk_mul_f32 v[138:139], v[138:139], v[148:149]
	v_pk_mul_f32 v[140:141], v[140:141], v[146:147]
	v_cvt_pk_bf16_f32 v132, v132, v133
	v_cvt_pk_bf16_f32 v133, v134, v135
	v_cvt_pk_bf16_f32 v134, v138, v139
	s_nop 0
	v_cvt_pk_bf16_f32 v135, v140, v141
	global_store_dwordx4 v[136:137], v[132:135], off offset:256 sc1

.LBB0_963:
	s_andn2_b64 vcc, exec, s[70:71]
	s_cbranch_vccnz .LBB0_965
	s_lshl_b32 s0, s68, 8
	s_add_i32 s0, s0, s90
	v_add_u32_e32 v134, s0, v191
	v_ashrrev_i32_e32 v135, 31, v134
	v_lshl_add_u64 v[132:133], v[134:135], 2, s[30:31]
	global_load_dword v135, v[132:133], off
	global_load_dword v156, v[132:133], off offset:64
	global_load_dword v158, v[132:133], off offset:128
	global_load_dword v144, v[132:133], off offset:192
	global_load_dword v142, v[132:133], off offset:512
	global_load_dword v140, v[132:133], off offset:576
	global_load_dword v138, v[132:133], off offset:640
	global_load_dword v136, v[132:133], off offset:704
	v_lshl_add_u32 v150, v190, 3, s91
	v_add_u32_e32 v145, 16, v134
	v_add_u32_e32 v157, 32, v134
	v_add_u32_e32 v143, 48, v134
	v_add_u32_e32 v141, 0x80, v134
	v_add_u32_e32 v139, 0x90, v134
	v_add_u32_e32 v137, 0xa0, v134
	v_add_u32_e32 v2, 0xb0, v134
	v_ashrrev_i32_e32 v151, 31, v150
	s_lshl_b32 s24, s62, 9
	s_waitcnt vmcnt(0)
	v_fmamk_f32 v132, v135, 0x3a800000, v1
	v_rsq_f32_e32 v132, v132
	v_fmamk_f32 v144, v144, 0x3a800000, v1
	v_rsq_f32_e32 v144, v144
	v_mul_f32_e32 v152, 0x3e0293ee, v132
	v_pk_mul_f32 v[132:133], v[130:131], v[152:153] op_sel_hi:[1,0]
	v_pk_mul_f32 v[146:147], v[128:129], v[152:153] op_sel_hi:[1,0]
	v_pk_mul_f32 v[154:155], v[126:127], v[152:153] op_sel_hi:[1,0]
	v_cvt_pk_bf16_f32 v146, v146, v147
	v_cvt_pk_bf16_f32 v147, v132, v133
	v_mov_b64_e32 v[132:133], s[20:21]
	v_pk_mul_f32 v[148:149], v[124:125], v[152:153] op_sel_hi:[1,0]
	v_mad_i64_i32 v[134:135], s[2:3], v134, s16, v[132:133]
	v_cvt_pk_bf16_f32 v148, v148, v149
	v_cvt_pk_bf16_f32 v149, v154, v155
	v_lshl_add_u64 v[154:155], v[134:135], 0, s[24:25]
	v_lshlrev_b64 v[134:135], 1, v[150:151]
	v_lshl_add_u64 v[150:151], v[154:155], 0, v[134:135]
	global_store_dwordx4 v[150:151], v[146:149], off sc1
	v_pk_mul_f32 v[154:155], v[118:119], v[152:153] op_sel_hi:[1,0]
	v_fmamk_f32 v142, v142, 0x3a800000, v1
	v_pk_mul_f32 v[146:147], v[120:121], v[152:153] op_sel_hi:[1,0]
	v_pk_mul_f32 v[148:149], v[122:123], v[152:153] op_sel_hi:[1,0]
	v_cvt_pk_bf16_f32 v146, v146, v147
	v_pk_mul_f32 v[152:153], v[116:117], v[152:153] op_sel_hi:[1,0]
	v_cvt_pk_bf16_f32 v147, v148, v149
	v_rsq_f32_e32 v142, v142
	v_cvt_pk_bf16_f32 v148, v152, v153
	v_cvt_pk_bf16_f32 v149, v154, v155
	global_store_dwordx4 v[150:151], v[146:149], off offset:256 sc1
	v_fmamk_f32 v140, v140, 0x3a800000, v1
	v_rsq_f32_e32 v140, v140
	v_fmamk_f32 v146, v156, 0x3a800000, v1
	v_rsq_f32_e32 v146, v146
	v_fmamk_f32 v138, v138, 0x3a800000, v1
	v_rsq_f32_e32 v138, v138
	v_fmamk_f32 v136, v136, 0x3a800000, v1
	v_mul_f32_e32 v150, 0x3e0293ee, v146
	v_pk_mul_f32 v[148:149], v[114:115], v[150:151] op_sel_hi:[1,0]
	v_pk_mul_f32 v[146:147], v[112:113], v[150:151] op_sel_hi:[1,0]
	v_pk_mul_f32 v[152:153], v[110:111], v[150:151] op_sel_hi:[1,0]
	v_pk_mul_f32 v[154:155], v[108:109], v[150:151] op_sel_hi:[1,0]
	v_cvt_pk_bf16_f32 v146, v146, v147
	v_cvt_pk_bf16_f32 v147, v148, v149
	v_rsq_f32_e32 v136, v136
	v_cvt_pk_bf16_f32 v148, v154, v155
	v_cvt_pk_bf16_f32 v149, v152, v153
	v_mad_i64_i32 v[152:153], s[2:3], v145, s16, v[132:133]
	v_fmamk_f32 v145, v158, 0x3a800000, v1
	v_rsq_f32_e32 v145, v145
	v_lshl_add_u64 v[152:153], v[152:153], 0, s[24:25]
	v_lshl_add_u64 v[152:153], v[152:153], 0, v[134:135]
	global_store_dwordx4 v[152:153], v[146:149], off sc1
	v_pk_mul_f32 v[154:155], v[102:103], v[150:151] op_sel_hi:[1,0]
	s_nop 0
	v_pk_mul_f32 v[148:149], v[106:107], v[150:151] op_sel_hi:[1,0]
	v_pk_mul_f32 v[146:147], v[104:105], v[150:151] op_sel_hi:[1,0]
	v_pk_mul_f32 v[150:151], v[100:101], v[150:151] op_sel_hi:[1,0]
	v_cvt_pk_bf16_f32 v146, v146, v147
	v_cvt_pk_bf16_f32 v147, v148, v149
	s_nop 0
	v_cvt_pk_bf16_f32 v148, v150, v151
	v_cvt_pk_bf16_f32 v149, v154, v155
	v_mul_f32_e32 v150, 0x3e0293ee, v145
	global_store_dwordx4 v[152:153], v[146:149], off offset:256 sc1
	v_pk_mul_f32 v[152:153], v[94:95], v[150:151] op_sel_hi:[1,0]
	v_pk_mul_f32 v[154:155], v[92:93], v[150:151] op_sel_hi:[1,0]
	v_pk_mul_f32 v[148:149], v[98:99], v[150:151] op_sel_hi:[1,0]
	v_pk_mul_f32 v[146:147], v[96:97], v[150:151] op_sel_hi:[1,0]
	s_nop 0
	v_cvt_pk_bf16_f32 v146, v146, v147
	v_cvt_pk_bf16_f32 v147, v148, v149
	v_cvt_pk_bf16_f32 v148, v154, v155
	v_cvt_pk_bf16_f32 v149, v152, v153
	v_mad_i64_i32 v[152:153], s[2:3], v157, s16, v[132:133]
	v_lshl_add_u64 v[152:153], v[152:153], 0, s[24:25]
	v_lshl_add_u64 v[152:153], v[152:153], 0, v[134:135]
	global_store_dwordx4 v[152:153], v[146:149], off sc1
	v_pk_mul_f32 v[154:155], v[86:87], v[150:151] op_sel_hi:[1,0]
	s_nop 0
	v_pk_mul_f32 v[148:149], v[90:91], v[150:151] op_sel_hi:[1,0]
	v_pk_mul_f32 v[146:147], v[88:89], v[150:151] op_sel_hi:[1,0]
	v_pk_mul_f32 v[150:151], v[84:85], v[150:151] op_sel_hi:[1,0]
	v_cvt_pk_bf16_f32 v146, v146, v147
	v_cvt_pk_bf16_f32 v147, v148, v149
	s_nop 0
	v_cvt_pk_bf16_f32 v148, v150, v151
	v_cvt_pk_bf16_f32 v149, v154, v155
	global_store_dwordx4 v[152:153], v[146:149], off offset:256 sc1
	s_nop 1
	v_mul_f32_e32 v148, 0x3e0293ee, v144
	v_pk_mul_f32 v[146:147], v[82:83], v[148:149] op_sel_hi:[1,0]
	v_pk_mul_f32 v[144:145], v[80:81], v[148:149] op_sel_hi:[1,0]
	v_pk_mul_f32 v[150:151], v[78:79], v[148:149] op_sel_hi:[1,0]
	v_pk_mul_f32 v[152:153], v[76:77], v[148:149] op_sel_hi:[1,0]
	v_cvt_pk_bf16_f32 v144, v144, v145
	v_cvt_pk_bf16_f32 v145, v146, v147
	s_nop 0
	v_cvt_pk_bf16_f32 v146, v152, v153
	v_cvt_pk_bf16_f32 v147, v150, v151
	v_mad_i64_i32 v[150:151], s[2:3], v143, s16, v[132:133]
	v_lshl_add_u64 v[150:151], v[150:151], 0, s[24:25]
	v_lshl_add_u64 v[150:151], v[150:151], 0, v[134:135]
	global_store_dwordx4 v[150:151], v[144:147], off sc1
	v_pk_mul_f32 v[152:153], v[70:71], v[148:149] op_sel_hi:[1,0]
	s_nop 0
	v_pk_mul_f32 v[146:147], v[74:75], v[148:149] op_sel_hi:[1,0]
	v_pk_mul_f32 v[144:145], v[72:73], v[148:149] op_sel_hi:[1,0]
	v_pk_mul_f32 v[148:149], v[68:69], v[148:149] op_sel_hi:[1,0]
	v_cvt_pk_bf16_f32 v144, v144, v145
	v_cvt_pk_bf16_f32 v145, v146, v147
	s_nop 0
	v_cvt_pk_bf16_f32 v146, v148, v149
	v_cvt_pk_bf16_f32 v147, v152, v153
	global_store_dwordx4 v[150:151], v[144:147], off offset:256 sc1
	s_nop 1
	v_mul_f32_e32 v146, 0x3e0293ee, v142
	v_pk_mul_f32 v[144:145], v[66:67], v[146:147] op_sel_hi:[1,0]
	v_pk_mul_f32 v[142:143], v[64:65], v[146:147] op_sel_hi:[1,0]
	v_pk_mul_f32 v[148:149], v[62:63], v[146:147] op_sel_hi:[1,0]
	v_pk_mul_f32 v[150:151], v[60:61], v[146:147] op_sel_hi:[1,0]
	v_cvt_pk_bf16_f32 v142, v142, v143
	v_cvt_pk_bf16_f32 v143, v144, v145
	s_nop 0
	v_cvt_pk_bf16_f32 v144, v150, v151
	v_cvt_pk_bf16_f32 v145, v148, v149
	v_mad_i64_i32 v[148:149], s[2:3], v141, s16, v[132:133]
	v_lshl_add_u64 v[148:149], v[148:149], 0, s[24:25]
	v_lshl_add_u64 v[148:149], v[148:149], 0, v[134:135]
	global_store_dwordx4 v[148:149], v[142:145], off sc1
	v_pk_mul_f32 v[150:151], v[54:55], v[146:147] op_sel_hi:[1,0]
	s_nop 0
	v_pk_mul_f32 v[144:145], v[58:59], v[146:147] op_sel_hi:[1,0]
	v_pk_mul_f32 v[142:143], v[56:57], v[146:147] op_sel_hi:[1,0]
	v_pk_mul_f32 v[146:147], v[52:53], v[146:147] op_sel_hi:[1,0]
	v_cvt_pk_bf16_f32 v142, v142, v143
	v_cvt_pk_bf16_f32 v143, v144, v145
	s_nop 0
	v_cvt_pk_bf16_f32 v144, v146, v147
	v_cvt_pk_bf16_f32 v145, v150, v151
	global_store_dwordx4 v[148:149], v[142:145], off offset:256 sc1
	s_nop 1
	v_mul_f32_e32 v144, 0x3e0293ee, v140
	v_pk_mul_f32 v[142:143], v[50:51], v[144:145] op_sel_hi:[1,0]
	v_pk_mul_f32 v[140:141], v[48:49], v[144:145] op_sel_hi:[1,0]
	v_pk_mul_f32 v[146:147], v[46:47], v[144:145] op_sel_hi:[1,0]
	v_pk_mul_f32 v[148:149], v[44:45], v[144:145] op_sel_hi:[1,0]
	v_cvt_pk_bf16_f32 v140, v140, v141
	v_cvt_pk_bf16_f32 v141, v142, v143
	s_nop 0
	v_cvt_pk_bf16_f32 v142, v148, v149
	v_cvt_pk_bf16_f32 v143, v146, v147
	v_mad_i64_i32 v[146:147], s[2:3], v139, s16, v[132:133]
	v_lshl_add_u64 v[146:147], v[146:147], 0, s[24:25]
	v_lshl_add_u64 v[146:147], v[146:147], 0, v[134:135]
	global_store_dwordx4 v[146:147], v[140:143], off sc1
	v_pk_mul_f32 v[148:149], v[38:39], v[144:145] op_sel_hi:[1,0]
	s_nop 0
	v_pk_mul_f32 v[142:143], v[42:43], v[144:145] op_sel_hi:[1,0]
	v_pk_mul_f32 v[140:141], v[40:41], v[144:145] op_sel_hi:[1,0]
	v_pk_mul_f32 v[144:145], v[36:37], v[144:145] op_sel_hi:[1,0]
	v_cvt_pk_bf16_f32 v140, v140, v141
	v_cvt_pk_bf16_f32 v141, v142, v143
	s_nop 0
	v_cvt_pk_bf16_f32 v142, v144, v145
	v_cvt_pk_bf16_f32 v143, v148, v149
	global_store_dwordx4 v[146:147], v[140:143], off offset:256 sc1
	s_nop 1
	v_mul_f32_e32 v142, 0x3e0293ee, v138
	v_pk_mul_f32 v[140:141], v[34:35], v[142:143] op_sel_hi:[1,0]
	v_pk_mul_f32 v[138:139], v[32:33], v[142:143] op_sel_hi:[1,0]
	v_pk_mul_f32 v[144:145], v[30:31], v[142:143] op_sel_hi:[1,0]
	v_pk_mul_f32 v[146:147], v[28:29], v[142:143] op_sel_hi:[1,0]
	v_cvt_pk_bf16_f32 v138, v138, v139
	v_cvt_pk_bf16_f32 v139, v140, v141
	s_nop 0
	v_cvt_pk_bf16_f32 v140, v146, v147
	v_cvt_pk_bf16_f32 v141, v144, v145
	v_mad_i64_i32 v[144:145], s[2:3], v137, s16, v[132:133]
	v_lshl_add_u64 v[144:145], v[144:145], 0, s[24:25]
	v_lshl_add_u64 v[144:145], v[144:145], 0, v[134:135]
	global_store_dwordx4 v[144:145], v[138:141], off sc1
	v_pk_mul_f32 v[146:147], v[22:23], v[142:143] op_sel_hi:[1,0]
	v_mad_i64_i32 v[132:133], s[2:3], v2, s16, v[132:133]
	v_pk_mul_f32 v[140:141], v[26:27], v[142:143] op_sel_hi:[1,0]
	v_pk_mul_f32 v[138:139], v[24:25], v[142:143] op_sel_hi:[1,0]
	v_pk_mul_f32 v[142:143], v[20:21], v[142:143] op_sel_hi:[1,0]
	v_cvt_pk_bf16_f32 v138, v138, v139
	v_cvt_pk_bf16_f32 v139, v140, v141
	v_lshl_add_u64 v[132:133], v[132:133], 0, s[24:25]
	v_cvt_pk_bf16_f32 v140, v142, v143
	v_cvt_pk_bf16_f32 v141, v146, v147
	global_store_dwordx4 v[144:145], v[138:141], off offset:256 sc1
	s_nop 1
	v_mul_f32_e32 v140, 0x3e0293ee, v136
	v_pk_mul_f32 v[138:139], v[18:19], v[140:141] op_sel_hi:[1,0]
	v_pk_mul_f32 v[136:137], v[16:17], v[140:141] op_sel_hi:[1,0]
	v_pk_mul_f32 v[142:143], v[14:15], v[140:141] op_sel_hi:[1,0]
	v_pk_mul_f32 v[144:145], v[12:13], v[140:141] op_sel_hi:[1,0]
	v_cvt_pk_bf16_f32 v136, v136, v137
	v_cvt_pk_bf16_f32 v137, v138, v139
	s_nop 0
	v_cvt_pk_bf16_f32 v138, v144, v145
	v_cvt_pk_bf16_f32 v139, v142, v143
	v_lshl_add_u64 v[142:143], v[132:133], 0, v[134:135]
	v_pk_mul_f32 v[134:135], v[10:11], v[140:141] op_sel_hi:[1,0]
	v_pk_mul_f32 v[132:133], v[8:9], v[140:141] op_sel_hi:[1,0]
	global_store_dwordx4 v[142:143], v[136:139], off sc1
	v_cvt_pk_bf16_f32 v132, v132, v133
	v_cvt_pk_bf16_f32 v133, v134, v135
	s_nop 1
	v_pk_mul_f32 v[136:137], v[6:7], v[140:141] op_sel_hi:[1,0]
	v_pk_mul_f32 v[138:139], v[4:5], v[140:141] op_sel_hi:[1,0]
	s_nop 0
	v_cvt_pk_bf16_f32 v134, v138, v139
	v_cvt_pk_bf16_f32 v135, v136, v137
	global_store_dwordx4 v[142:143], v[132:135], off offset:256 sc1

.LBB0_966:
	s_andn2_b64 vcc, exec, s[70:71]
	s_cbranch_vccnz .LBB0_968
	s_lshl_b32 s0, s68, 8
	s_add_i32 s0, s0, s90
	v_add_u32_e32 v138, s0, v191
	v_ashrrev_i32_e32 v139, 31, v138
	v_lshl_add_u64 v[132:133], v[138:139], 2, s[30:31]
	global_load_dword v2, v[132:133], off
	global_load_dword v155, v[132:133], off offset:64
	global_load_dword v153, v[132:133], off offset:128
	global_load_dword v151, v[132:133], off offset:192
	global_load_dword v149, v[132:133], off offset:512
	global_load_dword v147, v[132:133], off offset:576
	global_load_dword v145, v[132:133], off offset:640
	global_load_dword v143, v[132:133], off offset:704
	s_mov_b32 s70, 0xbfb8aa3b
	v_lshl_add_u32 v140, v190, 3, s91
	v_add_u32_e32 v154, 16, v138
	v_add_u32_e32 v152, 32, v138
	v_add_u32_e32 v150, 48, v138
	v_add_u32_e32 v148, 0x80, v138
	v_add_u32_e32 v146, 0x90, v138
	v_add_u32_e32 v144, 0xa0, v138
	v_add_u32_e32 v142, 0xb0, v138
	v_ashrrev_i32_e32 v141, 31, v140
	s_lshl_b32 s24, s62, 9
	s_waitcnt vmcnt(0)
	v_fmamk_f32 v2, v2, 0x3a800000, v1
	v_rsq_f32_e32 v2, v2
	s_nop 0
	v_pk_mul_f32 v[132:133], v[128:129], v[2:3] op_sel_hi:[1,0]
	v_pk_mul_f32 v[134:135], v[130:131], v[2:3] op_sel_hi:[1,0]
	v_pk_mul_f32 v[136:137], v[124:125], v[2:3] op_sel_hi:[1,0]
	v_pk_mul_f32 v[158:159], v[134:135], s[70:71] op_sel_hi:[1,0]
	v_pk_mul_f32 v[160:161], v[132:133], s[70:71] op_sel_hi:[1,0]
	v_pk_mul_f32 v[176:177], v[136:137], s[70:71] op_sel_hi:[1,0]
	v_pk_mul_f32 v[156:157], v[126:127], v[2:3] op_sel_hi:[1,0]
	v_exp_f32_e32 v160, v160
	v_exp_f32_e32 v176, v176
	v_exp_f32_e32 v161, v161
	v_exp_f32_e32 v177, v177
	v_exp_f32_e32 v158, v158
	v_exp_f32_e32 v159, v159
	v_pk_mul_f32 v[162:163], v[156:157], s[70:71] op_sel_hi:[1,0]
	v_pk_add_f32 v[160:161], v[160:161], 1.0 op_sel_hi:[1,0]
	v_exp_f32_e32 v162, v162
	v_exp_f32_e32 v163, v163
	v_pk_add_f32 v[158:159], v[158:159], 1.0 op_sel_hi:[1,0]
	v_pk_add_f32 v[176:177], v[176:177], 1.0 op_sel_hi:[1,0]
	v_rcp_f32_e32 v160, v160
	v_rcp_f32_e32 v176, v176
	v_rcp_f32_e32 v161, v161
	v_rcp_f32_e32 v177, v177
	v_rcp_f32_e32 v158, v158
	v_rcp_f32_e32 v159, v159
	v_pk_add_f32 v[162:163], v[162:163], 1.0 op_sel_hi:[1,0]
	v_pk_mul_f32 v[132:133], v[132:133], v[160:161]
	v_rcp_f32_e32 v162, v162
	v_rcp_f32_e32 v163, v163
	v_pk_mul_f32 v[134:135], v[134:135], v[158:159]
	v_pk_mul_f32 v[136:137], v[136:137], v[176:177]
	v_cvt_pk_bf16_f32 v132, v132, v133
	v_cvt_pk_bf16_f32 v133, v134, v135
	v_pk_mul_f32 v[156:157], v[156:157], v[162:163]
	v_cvt_pk_bf16_f32 v134, v136, v137
	v_mov_b64_e32 v[136:137], s[20:21]
	v_mad_i64_i32 v[138:139], s[2:3], v138, s16, v[136:137]
	v_cvt_pk_bf16_f32 v135, v156, v157
	v_lshl_add_u64 v[156:157], v[138:139], 0, s[24:25]
	v_lshlrev_b64 v[138:139], 1, v[140:141]
	v_lshl_add_u64 v[140:141], v[156:157], 0, v[138:139]
	global_store_dwordx4 v[140:141], v[132:135], off sc1
	v_pk_mul_f32 v[156:157], v[116:117], v[2:3] op_sel_hi:[1,0]
	v_pk_mul_f32 v[158:159], v[118:119], v[2:3] op_sel_hi:[1,0]
	v_pk_mul_f32 v[132:133], v[120:121], v[2:3] op_sel_hi:[1,0]
	v_pk_mul_f32 v[134:135], v[122:123], v[2:3] op_sel_hi:[1,0]
	v_pk_mul_f32 v[162:163], v[132:133], s[70:71] op_sel_hi:[1,0]
	v_pk_mul_f32 v[160:161], v[134:135], s[70:71] op_sel_hi:[1,0]
	v_pk_mul_f32 v[176:177], v[158:159], s[70:71] op_sel_hi:[1,0]
	v_pk_mul_f32 v[178:179], v[156:157], s[70:71] op_sel_hi:[1,0]
	v_exp_f32_e32 v162, v162
	v_exp_f32_e32 v163, v163
	v_exp_f32_e32 v160, v160
	v_exp_f32_e32 v161, v161
	v_exp_f32_e32 v178, v178
	v_exp_f32_e32 v179, v179
	v_exp_f32_e32 v176, v176
	v_exp_f32_e32 v177, v177
	v_pk_add_f32 v[160:161], v[160:161], 1.0 op_sel_hi:[1,0]
	v_pk_add_f32 v[162:163], v[162:163], 1.0 op_sel_hi:[1,0]
	v_pk_add_f32 v[178:179], v[178:179], 1.0 op_sel_hi:[1,0]
	v_pk_add_f32 v[176:177], v[176:177], 1.0 op_sel_hi:[1,0]
	v_rcp_f32_e32 v162, v162
	v_rcp_f32_e32 v163, v163
	v_rcp_f32_e32 v160, v160
	v_rcp_f32_e32 v161, v161
	v_rcp_f32_e32 v178, v178
	v_rcp_f32_e32 v179, v179
	v_rcp_f32_e32 v176, v176
	v_rcp_f32_e32 v177, v177
	v_fmamk_f32 v2, v155, 0x3a800000, v1
	v_rsq_f32_e32 v2, v2
	v_pk_mul_f32 v[134:135], v[134:135], v[160:161]
	v_pk_mul_f32 v[132:133], v[132:133], v[162:163]
	v_pk_mul_f32 v[158:159], v[158:159], v[176:177]
	v_pk_mul_f32 v[156:157], v[156:157], v[178:179]
	v_cvt_pk_bf16_f32 v132, v132, v133
	v_cvt_pk_bf16_f32 v133, v134, v135
	s_nop 0
	v_cvt_pk_bf16_f32 v134, v156, v157
	v_cvt_pk_bf16_f32 v135, v158, v159
	global_store_dwordx4 v[140:141], v[132:135], off offset:256 sc1
	v_pk_mul_f32 v[140:141], v[108:109], v[2:3] op_sel_hi:[1,0]
	v_pk_mul_f32 v[156:157], v[110:111], v[2:3] op_sel_hi:[1,0]
	v_pk_mul_f32 v[132:133], v[112:113], v[2:3] op_sel_hi:[1,0]
	v_pk_mul_f32 v[134:135], v[114:115], v[2:3] op_sel_hi:[1,0]
	v_pk_mul_f32 v[160:161], v[132:133], s[70:71] op_sel_hi:[1,0]
	v_pk_mul_f32 v[158:159], v[134:135], s[70:71] op_sel_hi:[1,0]
	v_pk_mul_f32 v[176:177], v[140:141], s[70:71] op_sel_hi:[1,0]
	v_exp_f32_e32 v160, v160
	v_exp_f32_e32 v176, v176
	v_exp_f32_e32 v161, v161
	v_exp_f32_e32 v177, v177
	v_exp_f32_e32 v158, v158
	v_exp_f32_e32 v159, v159
	v_pk_mul_f32 v[162:163], v[156:157], s[70:71] op_sel_hi:[1,0]
	v_pk_add_f32 v[160:161], v[160:161], 1.0 op_sel_hi:[1,0]
	v_exp_f32_e32 v162, v162
	v_exp_f32_e32 v163, v163
	v_pk_add_f32 v[158:159], v[158:159], 1.0 op_sel_hi:[1,0]
	v_pk_add_f32 v[176:177], v[176:177], 1.0 op_sel_hi:[1,0]
	v_rcp_f32_e32 v160, v160
	v_rcp_f32_e32 v176, v176
	v_rcp_f32_e32 v161, v161
	v_rcp_f32_e32 v177, v177
	v_rcp_f32_e32 v158, v158
	v_rcp_f32_e32 v159, v159
	v_pk_add_f32 v[162:163], v[162:163], 1.0 op_sel_hi:[1,0]
	v_pk_mul_f32 v[132:133], v[132:133], v[160:161]
	v_rcp_f32_e32 v162, v162
	v_rcp_f32_e32 v163, v163
	v_pk_mul_f32 v[134:135], v[134:135], v[158:159]
	v_pk_mul_f32 v[140:141], v[140:141], v[176:177]
	v_cvt_pk_bf16_f32 v132, v132, v133
	v_cvt_pk_bf16_f32 v133, v134, v135
	v_pk_mul_f32 v[156:157], v[156:157], v[162:163]
	v_cvt_pk_bf16_f32 v134, v140, v141
	v_mad_i64_i32 v[140:141], s[2:3], v154, s16, v[136:137]
	v_lshl_add_u64 v[140:141], v[140:141], 0, s[24:25]
	v_cvt_pk_bf16_f32 v135, v156, v157
	v_lshl_add_u64 v[140:141], v[140:141], 0, v[138:139]
	global_store_dwordx4 v[140:141], v[132:135], off sc1
	v_pk_mul_f32 v[154:155], v[100:101], v[2:3] op_sel_hi:[1,0]
	v_pk_mul_f32 v[156:157], v[102:103], v[2:3] op_sel_hi:[1,0]
	v_pk_mul_f32 v[132:133], v[104:105], v[2:3] op_sel_hi:[1,0]
	v_pk_mul_f32 v[134:135], v[106:107], v[2:3] op_sel_hi:[1,0]
	v_pk_mul_f32 v[160:161], v[132:133], s[70:71] op_sel_hi:[1,0]
	v_pk_mul_f32 v[158:159], v[134:135], s[70:71] op_sel_hi:[1,0]
	v_pk_mul_f32 v[162:163], v[156:157], s[70:71] op_sel_hi:[1,0]
	v_pk_mul_f32 v[176:177], v[154:155], s[70:71] op_sel_hi:[1,0]
	v_exp_f32_e32 v160, v160
	v_exp_f32_e32 v161, v161
	v_exp_f32_e32 v158, v158
	v_exp_f32_e32 v159, v159
	v_exp_f32_e32 v176, v176
	v_exp_f32_e32 v177, v177
	v_exp_f32_e32 v162, v162
	v_exp_f32_e32 v163, v163
	v_pk_add_f32 v[158:159], v[158:159], 1.0 op_sel_hi:[1,0]
	v_pk_add_f32 v[160:161], v[160:161], 1.0 op_sel_hi:[1,0]
	v_pk_add_f32 v[176:177], v[176:177], 1.0 op_sel_hi:[1,0]
	v_pk_add_f32 v[162:163], v[162:163], 1.0 op_sel_hi:[1,0]
	v_rcp_f32_e32 v160, v160
	v_rcp_f32_e32 v161, v161
	v_rcp_f32_e32 v158, v158
	v_rcp_f32_e32 v159, v159
	v_rcp_f32_e32 v176, v176
	v_rcp_f32_e32 v177, v177
	v_rcp_f32_e32 v162, v162
	v_rcp_f32_e32 v163, v163
	v_fmamk_f32 v2, v153, 0x3a800000, v1
	v_rsq_f32_e32 v2, v2
	v_pk_mul_f32 v[134:135], v[134:135], v[158:159]
	v_pk_mul_f32 v[132:133], v[132:133], v[160:161]
	v_pk_mul_f32 v[156:157], v[156:157], v[162:163]
	v_pk_mul_f32 v[154:155], v[154:155], v[176:177]
	v_cvt_pk_bf16_f32 v132, v132, v133
	v_cvt_pk_bf16_f32 v133, v134, v135
	s_nop 0
	v_cvt_pk_bf16_f32 v134, v154, v155
	v_cvt_pk_bf16_f32 v135, v156, v157
	global_store_dwordx4 v[140:141], v[132:135], off offset:256 sc1
	v_pk_mul_f32 v[140:141], v[92:93], v[2:3] op_sel_hi:[1,0]
	v_pk_mul_f32 v[154:155], v[94:95], v[2:3] op_sel_hi:[1,0]
	v_pk_mul_f32 v[132:133], v[96:97], v[2:3] op_sel_hi:[1,0]
	v_pk_mul_f32 v[134:135], v[98:99], v[2:3] op_sel_hi:[1,0]
	v_pk_mul_f32 v[158:159], v[132:133], s[70:71] op_sel_hi:[1,0]
	v_pk_mul_f32 v[156:157], v[134:135], s[70:71] op_sel_hi:[1,0]
	v_pk_mul_f32 v[162:163], v[140:141], s[70:71] op_sel_hi:[1,0]
	v_exp_f32_e32 v158, v158
	v_exp_f32_e32 v162, v162
	v_exp_f32_e32 v159, v159
	v_exp_f32_e32 v163, v163
	v_exp_f32_e32 v156, v156
	v_exp_f32_e32 v157, v157
	v_pk_mul_f32 v[160:161], v[154:155], s[70:71] op_sel_hi:[1,0]
	v_pk_add_f32 v[158:159], v[158:159], 1.0 op_sel_hi:[1,0]
	v_exp_f32_e32 v160, v160
	v_exp_f32_e32 v161, v161
	v_pk_add_f32 v[156:157], v[156:157], 1.0 op_sel_hi:[1,0]
	v_pk_add_f32 v[162:163], v[162:163], 1.0 op_sel_hi:[1,0]
	v_rcp_f32_e32 v158, v158
	v_rcp_f32_e32 v162, v162
	v_rcp_f32_e32 v159, v159
	v_rcp_f32_e32 v163, v163
	v_rcp_f32_e32 v156, v156
	v_rcp_f32_e32 v157, v157
	v_pk_add_f32 v[160:161], v[160:161], 1.0 op_sel_hi:[1,0]
	v_pk_mul_f32 v[132:133], v[132:133], v[158:159]
	v_rcp_f32_e32 v160, v160
	v_rcp_f32_e32 v161, v161
	v_pk_mul_f32 v[134:135], v[134:135], v[156:157]
	v_pk_mul_f32 v[140:141], v[140:141], v[162:163]
	v_cvt_pk_bf16_f32 v132, v132, v133
	v_cvt_pk_bf16_f32 v133, v134, v135
	v_pk_mul_f32 v[154:155], v[154:155], v[160:161]
	v_cvt_pk_bf16_f32 v134, v140, v141
	v_mad_i64_i32 v[140:141], s[2:3], v152, s16, v[136:137]
	v_lshl_add_u64 v[140:141], v[140:141], 0, s[24:25]
	v_cvt_pk_bf16_f32 v135, v154, v155
	v_lshl_add_u64 v[140:141], v[140:141], 0, v[138:139]
	global_store_dwordx4 v[140:141], v[132:135], off sc1
	v_pk_mul_f32 v[152:153], v[84:85], v[2:3] op_sel_hi:[1,0]
	v_pk_mul_f32 v[154:155], v[86:87], v[2:3] op_sel_hi:[1,0]
	v_pk_mul_f32 v[132:133], v[88:89], v[2:3] op_sel_hi:[1,0]
	v_pk_mul_f32 v[134:135], v[90:91], v[2:3] op_sel_hi:[1,0]
	v_pk_mul_f32 v[158:159], v[132:133], s[70:71] op_sel_hi:[1,0]
	v_pk_mul_f32 v[156:157], v[134:135], s[70:71] op_sel_hi:[1,0]
	v_pk_mul_f32 v[160:161], v[154:155], s[70:71] op_sel_hi:[1,0]
	v_pk_mul_f32 v[162:163], v[152:153], s[70:71] op_sel_hi:[1,0]
	v_exp_f32_e32 v158, v158
	v_exp_f32_e32 v159, v159
	v_exp_f32_e32 v156, v156
	v_exp_f32_e32 v157, v157
	v_exp_f32_e32 v162, v162
	v_exp_f32_e32 v163, v163
	v_exp_f32_e32 v160, v160
	v_exp_f32_e32 v161, v161
	v_pk_add_f32 v[156:157], v[156:157], 1.0 op_sel_hi:[1,0]
	v_pk_add_f32 v[158:159], v[158:159], 1.0 op_sel_hi:[1,0]
	v_pk_add_f32 v[162:163], v[162:163], 1.0 op_sel_hi:[1,0]
	v_pk_add_f32 v[160:161], v[160:161], 1.0 op_sel_hi:[1,0]
	v_rcp_f32_e32 v158, v158
	v_rcp_f32_e32 v159, v159
	v_rcp_f32_e32 v156, v156
	v_rcp_f32_e32 v157, v157
	v_rcp_f32_e32 v162, v162
	v_rcp_f32_e32 v163, v163
	v_rcp_f32_e32 v160, v160
	v_rcp_f32_e32 v161, v161
	v_fmamk_f32 v2, v151, 0x3a800000, v1
	v_rsq_f32_e32 v2, v2
	v_pk_mul_f32 v[134:135], v[134:135], v[156:157]
	v_pk_mul_f32 v[132:133], v[132:133], v[158:159]
	v_pk_mul_f32 v[154:155], v[154:155], v[160:161]
	v_pk_mul_f32 v[152:153], v[152:153], v[162:163]
	v_cvt_pk_bf16_f32 v132, v132, v133
	v_cvt_pk_bf16_f32 v133, v134, v135
	s_nop 0
	v_cvt_pk_bf16_f32 v134, v152, v153
	v_cvt_pk_bf16_f32 v135, v154, v155
	global_store_dwordx4 v[140:141], v[132:135], off offset:256 sc1
	v_pk_mul_f32 v[140:141], v[76:77], v[2:3] op_sel_hi:[1,0]
	v_pk_mul_f32 v[152:153], v[78:79], v[2:3] op_sel_hi:[1,0]
	v_pk_mul_f32 v[132:133], v[80:81], v[2:3] op_sel_hi:[1,0]
	v_pk_mul_f32 v[134:135], v[82:83], v[2:3] op_sel_hi:[1,0]
	v_pk_mul_f32 v[156:157], v[132:133], s[70:71] op_sel_hi:[1,0]
	v_pk_mul_f32 v[154:155], v[134:135], s[70:71] op_sel_hi:[1,0]
	v_pk_mul_f32 v[160:161], v[140:141], s[70:71] op_sel_hi:[1,0]
	v_exp_f32_e32 v156, v156
	v_exp_f32_e32 v160, v160
	v_exp_f32_e32 v157, v157
	v_exp_f32_e32 v161, v161
	v_exp_f32_e32 v154, v154
	v_exp_f32_e32 v155, v155
	v_pk_mul_f32 v[158:159], v[152:153], s[70:71] op_sel_hi:[1,0]
	v_pk_add_f32 v[156:157], v[156:157], 1.0 op_sel_hi:[1,0]
	v_exp_f32_e32 v158, v158
	v_exp_f32_e32 v159, v159
	v_pk_add_f32 v[154:155], v[154:155], 1.0 op_sel_hi:[1,0]
	v_pk_add_f32 v[160:161], v[160:161], 1.0 op_sel_hi:[1,0]
	v_rcp_f32_e32 v156, v156
	v_rcp_f32_e32 v160, v160
	v_rcp_f32_e32 v157, v157
	v_rcp_f32_e32 v161, v161
	v_rcp_f32_e32 v154, v154
	v_rcp_f32_e32 v155, v155
	v_pk_add_f32 v[158:159], v[158:159], 1.0 op_sel_hi:[1,0]
	v_pk_mul_f32 v[132:133], v[132:133], v[156:157]
	v_rcp_f32_e32 v158, v158
	v_rcp_f32_e32 v159, v159
	v_pk_mul_f32 v[134:135], v[134:135], v[154:155]
	v_pk_mul_f32 v[140:141], v[140:141], v[160:161]
	v_cvt_pk_bf16_f32 v132, v132, v133
	v_cvt_pk_bf16_f32 v133, v134, v135
	v_pk_mul_f32 v[152:153], v[152:153], v[158:159]
	v_cvt_pk_bf16_f32 v134, v140, v141
	v_mad_i64_i32 v[140:141], s[2:3], v150, s16, v[136:137]
	v_lshl_add_u64 v[140:141], v[140:141], 0, s[24:25]
	v_cvt_pk_bf16_f32 v135, v152, v153
	v_lshl_add_u64 v[140:141], v[140:141], 0, v[138:139]
	global_store_dwordx4 v[140:141], v[132:135], off sc1
	v_pk_mul_f32 v[150:151], v[68:69], v[2:3] op_sel_hi:[1,0]
	v_pk_mul_f32 v[152:153], v[70:71], v[2:3] op_sel_hi:[1,0]
	v_pk_mul_f32 v[132:133], v[72:73], v[2:3] op_sel_hi:[1,0]
	v_pk_mul_f32 v[134:135], v[74:75], v[2:3] op_sel_hi:[1,0]
	v_pk_mul_f32 v[156:157], v[132:133], s[70:71] op_sel_hi:[1,0]
	v_pk_mul_f32 v[154:155], v[134:135], s[70:71] op_sel_hi:[1,0]
	v_pk_mul_f32 v[158:159], v[152:153], s[70:71] op_sel_hi:[1,0]
	v_pk_mul_f32 v[160:161], v[150:151], s[70:71] op_sel_hi:[1,0]
	v_exp_f32_e32 v156, v156
	v_exp_f32_e32 v157, v157
	v_exp_f32_e32 v154, v154
	v_exp_f32_e32 v155, v155
	v_exp_f32_e32 v160, v160
	v_exp_f32_e32 v161, v161
	v_exp_f32_e32 v158, v158
	v_exp_f32_e32 v159, v159
	v_pk_add_f32 v[154:155], v[154:155], 1.0 op_sel_hi:[1,0]
	v_pk_add_f32 v[156:157], v[156:157], 1.0 op_sel_hi:[1,0]
	v_pk_add_f32 v[160:161], v[160:161], 1.0 op_sel_hi:[1,0]
	v_pk_add_f32 v[158:159], v[158:159], 1.0 op_sel_hi:[1,0]
	v_rcp_f32_e32 v156, v156
	v_rcp_f32_e32 v157, v157
	v_rcp_f32_e32 v154, v154
	v_rcp_f32_e32 v155, v155
	v_rcp_f32_e32 v160, v160
	v_rcp_f32_e32 v161, v161
	v_rcp_f32_e32 v158, v158
	v_rcp_f32_e32 v159, v159
	v_fmamk_f32 v2, v149, 0x3a800000, v1
	v_rsq_f32_e32 v2, v2
	v_pk_mul_f32 v[134:135], v[134:135], v[154:155]
	v_pk_mul_f32 v[132:133], v[132:133], v[156:157]
	v_pk_mul_f32 v[152:153], v[152:153], v[158:159]
	v_pk_mul_f32 v[150:151], v[150:151], v[160:161]
	v_cvt_pk_bf16_f32 v132, v132, v133
	v_cvt_pk_bf16_f32 v133, v134, v135
	s_nop 0
	v_cvt_pk_bf16_f32 v134, v150, v151
	v_cvt_pk_bf16_f32 v135, v152, v153
	global_store_dwordx4 v[140:141], v[132:135], off offset:256 sc1
	v_pk_mul_f32 v[140:141], v[60:61], v[2:3] op_sel_hi:[1,0]
	v_pk_mul_f32 v[150:151], v[62:63], v[2:3] op_sel_hi:[1,0]
	v_pk_mul_f32 v[132:133], v[64:65], v[2:3] op_sel_hi:[1,0]
	v_pk_mul_f32 v[134:135], v[66:67], v[2:3] op_sel_hi:[1,0]
	v_pk_mul_f32 v[154:155], s[70:71], v[132:133] op_sel_hi:[0,1]
	v_pk_mul_f32 v[152:153], s[70:71], v[134:135] op_sel_hi:[0,1]
	v_pk_mul_f32 v[158:159], s[70:71], v[140:141] op_sel_hi:[0,1]
	v_exp_f32_e32 v154, v154
	v_exp_f32_e32 v158, v158
	v_exp_f32_e32 v155, v155
	v_exp_f32_e32 v159, v159
	v_exp_f32_e32 v152, v152
	v_exp_f32_e32 v153, v153
	v_pk_mul_f32 v[156:157], s[70:71], v[150:151] op_sel_hi:[0,1]
	v_exp_f32_e32 v156, v156
	v_exp_f32_e32 v157, v157
	v_pk_add_f32 v[152:153], v[152:153], 1.0 op_sel_hi:[1,0]
	v_pk_add_f32 v[154:155], v[154:155], 1.0 op_sel_hi:[1,0]
	v_pk_add_f32 v[158:159], v[158:159], 1.0 op_sel_hi:[1,0]
	v_rcp_f32_e32 v154, v154
	v_rcp_f32_e32 v158, v158
	v_rcp_f32_e32 v155, v155
	v_rcp_f32_e32 v159, v159
	v_rcp_f32_e32 v152, v152
	v_rcp_f32_e32 v153, v153
	v_pk_add_f32 v[156:157], v[156:157], 1.0 op_sel_hi:[1,0]
	v_pk_mul_f32 v[132:133], v[132:133], v[154:155]
	v_rcp_f32_e32 v156, v156
	v_rcp_f32_e32 v157, v157
	v_pk_mul_f32 v[134:135], v[134:135], v[152:153]
	v_pk_mul_f32 v[140:141], v[140:141], v[158:159]
	v_cvt_pk_bf16_f32 v132, v132, v133
	v_cvt_pk_bf16_f32 v133, v134, v135
	v_pk_mul_f32 v[150:151], v[150:151], v[156:157]
	v_cvt_pk_bf16_f32 v134, v140, v141
	v_mad_i64_i32 v[140:141], s[2:3], v148, s16, v[136:137]
	v_lshl_add_u64 v[140:141], v[140:141], 0, s[24:25]
	v_cvt_pk_bf16_f32 v135, v150, v151
	v_lshl_add_u64 v[140:141], v[140:141], 0, v[138:139]
	global_store_dwordx4 v[140:141], v[132:135], off sc1
	v_pk_mul_f32 v[148:149], v[52:53], v[2:3] op_sel_hi:[1,0]
	v_pk_mul_f32 v[150:151], v[54:55], v[2:3] op_sel_hi:[1,0]
	v_pk_mul_f32 v[132:133], v[56:57], v[2:3] op_sel_hi:[1,0]
	v_pk_mul_f32 v[134:135], v[58:59], v[2:3] op_sel_hi:[1,0]
	v_pk_mul_f32 v[154:155], s[70:71], v[132:133] op_sel_hi:[0,1]
	v_pk_mul_f32 v[152:153], s[70:71], v[134:135] op_sel_hi:[0,1]
	v_pk_mul_f32 v[156:157], s[70:71], v[150:151] op_sel_hi:[0,1]
	v_pk_mul_f32 v[158:159], s[70:71], v[148:149] op_sel_hi:[0,1]
	v_exp_f32_e32 v154, v154
	v_exp_f32_e32 v155, v155
	v_exp_f32_e32 v152, v152
	v_exp_f32_e32 v153, v153
	v_exp_f32_e32 v158, v158
	v_exp_f32_e32 v159, v159
	v_exp_f32_e32 v156, v156
	v_exp_f32_e32 v157, v157
	v_pk_add_f32 v[152:153], v[152:153], 1.0 op_sel_hi:[1,0]
	v_pk_add_f32 v[154:155], v[154:155], 1.0 op_sel_hi:[1,0]
	v_pk_add_f32 v[158:159], v[158:159], 1.0 op_sel_hi:[1,0]
	v_pk_add_f32 v[156:157], v[156:157], 1.0 op_sel_hi:[1,0]
	v_rcp_f32_e32 v154, v154
	v_rcp_f32_e32 v155, v155
	v_rcp_f32_e32 v152, v152
	v_rcp_f32_e32 v153, v153
	v_rcp_f32_e32 v158, v158
	v_rcp_f32_e32 v159, v159
	v_rcp_f32_e32 v156, v156
	v_rcp_f32_e32 v157, v157
	v_fmamk_f32 v2, v147, 0x3a800000, v1
	v_rsq_f32_e32 v2, v2
	v_pk_mul_f32 v[134:135], v[134:135], v[152:153]
	v_pk_mul_f32 v[132:133], v[132:133], v[154:155]
	v_pk_mul_f32 v[150:151], v[150:151], v[156:157]
	v_pk_mul_f32 v[148:149], v[148:149], v[158:159]
	v_cvt_pk_bf16_f32 v132, v132, v133
	v_cvt_pk_bf16_f32 v133, v134, v135
	s_nop 0
	v_cvt_pk_bf16_f32 v134, v148, v149
	v_cvt_pk_bf16_f32 v135, v150, v151
	global_store_dwordx4 v[140:141], v[132:135], off offset:256 sc1
	v_pk_mul_f32 v[140:141], v[44:45], v[2:3] op_sel_hi:[1,0]
	v_pk_mul_f32 v[148:149], v[46:47], v[2:3] op_sel_hi:[1,0]
	v_pk_mul_f32 v[132:133], v[48:49], v[2:3] op_sel_hi:[1,0]
	v_pk_mul_f32 v[134:135], v[50:51], v[2:3] op_sel_hi:[1,0]
	v_pk_mul_f32 v[152:153], s[70:71], v[132:133] op_sel_hi:[0,1]
	v_pk_mul_f32 v[150:151], s[70:71], v[134:135] op_sel_hi:[0,1]
	v_pk_mul_f32 v[156:157], s[70:71], v[140:141] op_sel_hi:[0,1]
	v_exp_f32_e32 v152, v152
	v_exp_f32_e32 v156, v156
	v_exp_f32_e32 v153, v153
	v_exp_f32_e32 v157, v157
	v_exp_f32_e32 v150, v150
	v_exp_f32_e32 v151, v151
	v_pk_mul_f32 v[154:155], s[70:71], v[148:149] op_sel_hi:[0,1]
	v_exp_f32_e32 v154, v154
	v_exp_f32_e32 v155, v155
	v_pk_add_f32 v[150:151], v[150:151], 1.0 op_sel_hi:[1,0]
	v_pk_add_f32 v[152:153], v[152:153], 1.0 op_sel_hi:[1,0]
	v_pk_add_f32 v[156:157], v[156:157], 1.0 op_sel_hi:[1,0]
	v_rcp_f32_e32 v152, v152
	v_rcp_f32_e32 v156, v156
	v_rcp_f32_e32 v153, v153
	v_rcp_f32_e32 v157, v157
	v_rcp_f32_e32 v150, v150
	v_rcp_f32_e32 v151, v151
	v_pk_add_f32 v[154:155], v[154:155], 1.0 op_sel_hi:[1,0]
	v_pk_mul_f32 v[132:133], v[132:133], v[152:153]
	v_rcp_f32_e32 v154, v154
	v_rcp_f32_e32 v155, v155
	v_pk_mul_f32 v[134:135], v[134:135], v[150:151]
	v_pk_mul_f32 v[140:141], v[140:141], v[156:157]
	v_cvt_pk_bf16_f32 v132, v132, v133
	v_cvt_pk_bf16_f32 v133, v134, v135
	v_pk_mul_f32 v[148:149], v[148:149], v[154:155]
	v_cvt_pk_bf16_f32 v134, v140, v141
	v_mad_i64_i32 v[140:141], s[2:3], v146, s16, v[136:137]
	v_lshl_add_u64 v[140:141], v[140:141], 0, s[24:25]
	v_cvt_pk_bf16_f32 v135, v148, v149
	v_lshl_add_u64 v[140:141], v[140:141], 0, v[138:139]
	global_store_dwordx4 v[140:141], v[132:135], off sc1
	v_pk_mul_f32 v[146:147], v[36:37], v[2:3] op_sel_hi:[1,0]
	v_pk_mul_f32 v[148:149], v[38:39], v[2:3] op_sel_hi:[1,0]
	v_pk_mul_f32 v[132:133], v[40:41], v[2:3] op_sel_hi:[1,0]
	v_pk_mul_f32 v[134:135], v[42:43], v[2:3] op_sel_hi:[1,0]
	v_pk_mul_f32 v[152:153], s[70:71], v[132:133] op_sel_hi:[0,1]
	v_pk_mul_f32 v[150:151], s[70:71], v[134:135] op_sel_hi:[0,1]
	v_pk_mul_f32 v[154:155], s[70:71], v[148:149] op_sel_hi:[0,1]
	v_pk_mul_f32 v[156:157], s[70:71], v[146:147] op_sel_hi:[0,1]
	v_exp_f32_e32 v152, v152
	v_exp_f32_e32 v153, v153
	v_exp_f32_e32 v150, v150
	v_exp_f32_e32 v151, v151
	v_exp_f32_e32 v156, v156
	v_exp_f32_e32 v157, v157
	v_exp_f32_e32 v154, v154
	v_exp_f32_e32 v155, v155
	v_pk_add_f32 v[150:151], v[150:151], 1.0 op_sel_hi:[1,0]
	v_pk_add_f32 v[152:153], v[152:153], 1.0 op_sel_hi:[1,0]
	v_pk_add_f32 v[156:157], v[156:157], 1.0 op_sel_hi:[1,0]
	v_pk_add_f32 v[154:155], v[154:155], 1.0 op_sel_hi:[1,0]
	v_rcp_f32_e32 v152, v152
	v_rcp_f32_e32 v153, v153
	v_rcp_f32_e32 v150, v150
	v_rcp_f32_e32 v151, v151
	v_rcp_f32_e32 v156, v156
	v_rcp_f32_e32 v157, v157
	v_rcp_f32_e32 v154, v154
	v_rcp_f32_e32 v155, v155
	v_fmamk_f32 v2, v145, 0x3a800000, v1
	v_rsq_f32_e32 v2, v2
	v_pk_mul_f32 v[134:135], v[134:135], v[150:151]
	v_pk_mul_f32 v[132:133], v[132:133], v[152:153]
	v_pk_mul_f32 v[148:149], v[148:149], v[154:155]
	v_pk_mul_f32 v[146:147], v[146:147], v[156:157]
	v_cvt_pk_bf16_f32 v132, v132, v133
	v_cvt_pk_bf16_f32 v133, v134, v135
	s_nop 0
	v_cvt_pk_bf16_f32 v134, v146, v147
	v_cvt_pk_bf16_f32 v135, v148, v149
	global_store_dwordx4 v[140:141], v[132:135], off offset:256 sc1
	v_pk_mul_f32 v[140:141], v[28:29], v[2:3] op_sel_hi:[1,0]
	v_pk_mul_f32 v[146:147], v[30:31], v[2:3] op_sel_hi:[1,0]
	v_pk_mul_f32 v[132:133], v[32:33], v[2:3] op_sel_hi:[1,0]
	v_pk_mul_f32 v[134:135], v[34:35], v[2:3] op_sel_hi:[1,0]
	v_pk_mul_f32 v[150:151], s[70:71], v[132:133] op_sel_hi:[0,1]
	v_pk_mul_f32 v[148:149], s[70:71], v[134:135] op_sel_hi:[0,1]
	v_pk_mul_f32 v[154:155], s[70:71], v[140:141] op_sel_hi:[0,1]
	v_exp_f32_e32 v150, v150
	v_exp_f32_e32 v154, v154
	v_exp_f32_e32 v151, v151
	v_exp_f32_e32 v155, v155
	v_exp_f32_e32 v148, v148
	v_exp_f32_e32 v149, v149
	v_pk_mul_f32 v[152:153], s[70:71], v[146:147] op_sel_hi:[0,1]
	v_exp_f32_e32 v152, v152
	v_exp_f32_e32 v153, v153
	v_pk_add_f32 v[148:149], v[148:149], 1.0 op_sel_hi:[1,0]
	v_pk_add_f32 v[150:151], v[150:151], 1.0 op_sel_hi:[1,0]
	v_pk_add_f32 v[154:155], v[154:155], 1.0 op_sel_hi:[1,0]
	v_rcp_f32_e32 v150, v150
	v_rcp_f32_e32 v154, v154
	v_rcp_f32_e32 v151, v151
	v_rcp_f32_e32 v155, v155
	v_rcp_f32_e32 v148, v148
	v_rcp_f32_e32 v149, v149
	v_pk_add_f32 v[152:153], v[152:153], 1.0 op_sel_hi:[1,0]
	v_pk_mul_f32 v[132:133], v[132:133], v[150:151]
	v_rcp_f32_e32 v152, v152
	v_rcp_f32_e32 v153, v153
	v_pk_mul_f32 v[134:135], v[134:135], v[148:149]
	v_pk_mul_f32 v[140:141], v[140:141], v[154:155]
	v_cvt_pk_bf16_f32 v132, v132, v133
	v_cvt_pk_bf16_f32 v133, v134, v135
	v_pk_mul_f32 v[146:147], v[146:147], v[152:153]
	v_cvt_pk_bf16_f32 v134, v140, v141
	v_mad_i64_i32 v[140:141], s[2:3], v144, s16, v[136:137]
	v_lshl_add_u64 v[140:141], v[140:141], 0, s[24:25]
	v_cvt_pk_bf16_f32 v135, v146, v147
	v_lshl_add_u64 v[140:141], v[140:141], 0, v[138:139]
	global_store_dwordx4 v[140:141], v[132:135], off sc1
	v_pk_mul_f32 v[144:145], v[20:21], v[2:3] op_sel_hi:[1,0]
	v_pk_mul_f32 v[146:147], v[22:23], v[2:3] op_sel_hi:[1,0]
	v_pk_mul_f32 v[132:133], v[24:25], v[2:3] op_sel_hi:[1,0]
	v_pk_mul_f32 v[134:135], v[26:27], v[2:3] op_sel_hi:[1,0]
	v_pk_mul_f32 v[150:151], s[70:71], v[132:133] op_sel_hi:[0,1]
	v_pk_mul_f32 v[148:149], s[70:71], v[134:135] op_sel_hi:[0,1]
	v_pk_mul_f32 v[152:153], s[70:71], v[146:147] op_sel_hi:[0,1]
	v_pk_mul_f32 v[154:155], s[70:71], v[144:145] op_sel_hi:[0,1]
	v_exp_f32_e32 v150, v150
	v_exp_f32_e32 v151, v151
	v_exp_f32_e32 v148, v148
	v_exp_f32_e32 v149, v149
	v_exp_f32_e32 v154, v154
	v_exp_f32_e32 v155, v155
	v_exp_f32_e32 v152, v152
	v_exp_f32_e32 v153, v153
	v_pk_add_f32 v[148:149], v[148:149], 1.0 op_sel_hi:[1,0]
	v_pk_add_f32 v[150:151], v[150:151], 1.0 op_sel_hi:[1,0]
	v_pk_add_f32 v[154:155], v[154:155], 1.0 op_sel_hi:[1,0]
	v_pk_add_f32 v[152:153], v[152:153], 1.0 op_sel_hi:[1,0]
	v_rcp_f32_e32 v150, v150
	v_rcp_f32_e32 v151, v151
	v_rcp_f32_e32 v148, v148
	v_rcp_f32_e32 v149, v149
	v_rcp_f32_e32 v154, v154
	v_rcp_f32_e32 v155, v155
	v_rcp_f32_e32 v152, v152
	v_rcp_f32_e32 v153, v153
	v_fmamk_f32 v2, v143, 0x3a800000, v1
	v_rsq_f32_e32 v2, v2
	v_pk_mul_f32 v[134:135], v[134:135], v[148:149]
	v_pk_mul_f32 v[132:133], v[132:133], v[150:151]
	v_pk_mul_f32 v[146:147], v[146:147], v[152:153]
	v_pk_mul_f32 v[144:145], v[144:145], v[154:155]
	v_cvt_pk_bf16_f32 v132, v132, v133
	v_cvt_pk_bf16_f32 v133, v134, v135
	v_mad_i64_i32 v[136:137], s[2:3], v142, s16, v[136:137]
	v_cvt_pk_bf16_f32 v134, v144, v145
	v_cvt_pk_bf16_f32 v135, v146, v147
	global_store_dwordx4 v[140:141], v[132:135], off offset:256 sc1
	v_pk_mul_f32 v[140:141], v[12:13], v[2:3] op_sel_hi:[1,0]
	v_pk_mul_f32 v[144:145], v[14:15], v[2:3] op_sel_hi:[1,0]
	v_pk_mul_f32 v[132:133], v[16:17], v[2:3] op_sel_hi:[1,0]
	v_pk_mul_f32 v[134:135], v[18:19], v[2:3] op_sel_hi:[1,0]
	v_pk_mul_f32 v[148:149], s[70:71], v[132:133] op_sel_hi:[0,1]
	v_pk_mul_f32 v[146:147], s[70:71], v[134:135] op_sel_hi:[0,1]
	v_pk_mul_f32 v[150:151], s[70:71], v[144:145] op_sel_hi:[0,1]
	v_pk_mul_f32 v[152:153], s[70:71], v[140:141] op_sel_hi:[0,1]
	v_exp_f32_e32 v148, v148
	v_exp_f32_e32 v149, v149
	v_exp_f32_e32 v146, v146
	v_exp_f32_e32 v147, v147
	v_exp_f32_e32 v152, v152
	v_exp_f32_e32 v153, v153
	v_exp_f32_e32 v150, v150
	v_exp_f32_e32 v151, v151
	v_pk_add_f32 v[146:147], v[146:147], 1.0 op_sel_hi:[1,0]
	v_pk_add_f32 v[148:149], v[148:149], 1.0 op_sel_hi:[1,0]
	v_pk_add_f32 v[152:153], v[152:153], 1.0 op_sel_hi:[1,0]
	v_pk_add_f32 v[150:151], v[150:151], 1.0 op_sel_hi:[1,0]
	v_rcp_f32_e32 v148, v148
	v_rcp_f32_e32 v149, v149
	v_rcp_f32_e32 v146, v146
	v_rcp_f32_e32 v147, v147
	v_rcp_f32_e32 v152, v152
	v_rcp_f32_e32 v153, v153
	v_rcp_f32_e32 v150, v150
	v_rcp_f32_e32 v151, v151
	v_pk_mul_f32 v[134:135], v[134:135], v[146:147]
	v_pk_mul_f32 v[132:133], v[132:133], v[148:149]
	v_lshl_add_u64 v[136:137], v[136:137], 0, s[24:25]
	v_pk_mul_f32 v[144:145], v[144:145], v[150:151]
	v_pk_mul_f32 v[140:141], v[140:141], v[152:153]
	v_cvt_pk_bf16_f32 v132, v132, v133
	v_cvt_pk_bf16_f32 v133, v134, v135
	v_lshl_add_u64 v[136:137], v[136:137], 0, v[138:139]
	v_cvt_pk_bf16_f32 v134, v140, v141
	v_cvt_pk_bf16_f32 v135, v144, v145
	global_store_dwordx4 v[136:137], v[132:135], off sc1
	v_pk_mul_f32 v[138:139], v[4:5], v[2:3] op_sel_hi:[1,0]
	v_pk_mul_f32 v[140:141], v[6:7], v[2:3] op_sel_hi:[1,0]
	v_pk_mul_f32 v[132:133], v[8:9], v[2:3] op_sel_hi:[1,0]
	v_pk_mul_f32 v[134:135], v[10:11], v[2:3] op_sel_hi:[1,0]
	v_pk_mul_f32 v[144:145], s[70:71], v[132:133] op_sel_hi:[0,1]
	v_pk_mul_f32 v[142:143], s[70:71], v[134:135] op_sel_hi:[0,1]
	v_pk_mul_f32 v[146:147], s[70:71], v[140:141] op_sel_hi:[0,1]
	v_pk_mul_f32 v[148:149], s[70:71], v[138:139] op_sel_hi:[0,1]
	v_exp_f32_e32 v144, v144
	v_exp_f32_e32 v145, v145
	v_exp_f32_e32 v142, v142
	v_exp_f32_e32 v143, v143
	v_exp_f32_e32 v148, v148
	v_exp_f32_e32 v149, v149
	v_exp_f32_e32 v146, v146
	v_exp_f32_e32 v147, v147
	v_pk_add_f32 v[142:143], v[142:143], 1.0 op_sel_hi:[1,0]
	v_pk_add_f32 v[144:145], v[144:145], 1.0 op_sel_hi:[1,0]
	v_pk_add_f32 v[148:149], v[148:149], 1.0 op_sel_hi:[1,0]
	v_pk_add_f32 v[146:147], v[146:147], 1.0 op_sel_hi:[1,0]
	v_rcp_f32_e32 v144, v144
	v_rcp_f32_e32 v145, v145
	v_rcp_f32_e32 v142, v142
	v_rcp_f32_e32 v143, v143
	v_rcp_f32_e32 v148, v148
	v_rcp_f32_e32 v149, v149
	v_rcp_f32_e32 v146, v146
	v_rcp_f32_e32 v147, v147
	v_pk_mul_f32 v[134:135], v[134:135], v[142:143]
	v_pk_mul_f32 v[132:133], v[132:133], v[144:145]
	v_pk_mul_f32 v[138:139], v[138:139], v[148:149]
	v_pk_mul_f32 v[140:141], v[140:141], v[146:147]
	v_cvt_pk_bf16_f32 v132, v132, v133
	v_cvt_pk_bf16_f32 v133, v134, v135
	v_cvt_pk_bf16_f32 v134, v138, v139
	s_nop 0
	v_cvt_pk_bf16_f32 v135, v140, v141
	global_store_dwordx4 v[136:137], v[132:135], off offset:256 sc1

.LBB0_969:
	s_andn2_b64 vcc, exec, s[70:71]
	s_cbranch_vccnz .LBB0_974
	s_mov_b64 s[70:71], -1
	s_and_b64 vcc, exec, s[34:35]
	v_lshl_add_u32 v156, v190, 3, s91
	s_cbranch_vccz .LBB0_972
	s_lshl_b32 s0, s68, 8
	s_add_i32 s0, s0, s90
	v_add_u32_e32 v134, s0, v191
	v_ashrrev_i32_e32 v135, 31, v134
	v_lshl_add_u64 v[132:133], v[134:135], 2, s[30:31]
	global_load_dword v135, v[132:133], off
	global_load_dword v158, v[132:133], off offset:64
	global_load_dword v160, v[132:133], off offset:128
	global_load_dword v2, v[132:133], off offset:192
	global_load_dword v143, v[132:133], off offset:512
	global_load_dword v141, v[132:133], off offset:576
	global_load_dword v139, v[132:133], off offset:640
	global_load_dword v137, v[132:133], off offset:704
	s_lshl_b32 s2, s62, 8
	v_add_u32_e32 v145, 16, v134
	v_add_u32_e32 v159, 32, v134
	v_add_u32_e32 v144, 48, v134
	v_add_u32_e32 v142, 0x80, v134
	v_add_u32_e32 v140, 0x90, v134
	v_add_u32_e32 v138, 0xa0, v134
	v_add_u32_e32 v136, 0xb0, v134
	s_ashr_i32 s3, s2, 31
	v_ashrrev_i32_e32 v157, 31, v156
	s_waitcnt vmcnt(0)
	v_fmamk_f32 v132, v135, 0x3a800000, v1
	v_rsq_f32_e32 v150, v132
	v_fmamk_f32 v2, v2, 0x3a800000, v1
	v_rsq_f32_e32 v2, v2
	v_pk_mul_f32 v[132:133], v[130:131], v[150:151] op_sel_hi:[1,0]
	v_pk_mul_f32 v[146:147], v[128:129], v[150:151] op_sel_hi:[1,0]
	v_pk_mul_f32 v[152:153], v[126:127], v[150:151] op_sel_hi:[1,0]
	v_cvt_pk_bf16_f32 v146, v146, v147
	v_cvt_pk_bf16_f32 v147, v132, v133
	v_mov_b64_e32 v[132:133], s[20:21]
	v_mad_i64_i32 v[134:135], s[70:71], v134, s16, v[132:133]
	v_pk_mul_f32 v[148:149], v[124:125], v[150:151] op_sel_hi:[1,0]
	s_lshl_b64 s[70:71], s[2:3], 1
	v_cvt_pk_bf16_f32 v148, v148, v149
	v_cvt_pk_bf16_f32 v149, v152, v153
	v_lshl_add_u64 v[152:153], v[134:135], 0, s[70:71]
	v_lshlrev_b64 v[134:135], 1, v[156:157]
	v_lshl_add_u64 v[152:153], v[152:153], 0, v[134:135]
	global_store_dwordx4 v[152:153], v[146:149], off sc1
	v_pk_mul_f32 v[154:155], v[118:119], v[150:151] op_sel_hi:[1,0]
	s_nop 0
	v_pk_mul_f32 v[146:147], v[120:121], v[150:151] op_sel_hi:[1,0]
	v_pk_mul_f32 v[148:149], v[122:123], v[150:151] op_sel_hi:[1,0]
	v_cvt_pk_bf16_f32 v146, v146, v147
	v_pk_mul_f32 v[150:151], v[116:117], v[150:151] op_sel_hi:[1,0]
	v_cvt_pk_bf16_f32 v147, v148, v149
	s_nop 0
	v_cvt_pk_bf16_f32 v148, v150, v151
	v_cvt_pk_bf16_f32 v149, v154, v155
	global_store_dwordx4 v[152:153], v[146:149], off offset:256 sc1
	s_nop 1
	v_fmamk_f32 v146, v158, 0x3a800000, v1
	v_rsq_f32_e32 v150, v146
	s_nop 0
	v_pk_mul_f32 v[148:149], v[114:115], v[150:151] op_sel_hi:[1,0]
	v_pk_mul_f32 v[146:147], v[112:113], v[150:151] op_sel_hi:[1,0]
	v_pk_mul_f32 v[152:153], v[110:111], v[150:151] op_sel_hi:[1,0]
	v_pk_mul_f32 v[154:155], v[108:109], v[150:151] op_sel_hi:[1,0]
	v_cvt_pk_bf16_f32 v146, v146, v147
	v_cvt_pk_bf16_f32 v147, v148, v149
	s_nop 0
	v_cvt_pk_bf16_f32 v148, v154, v155
	v_cvt_pk_bf16_f32 v149, v152, v153
	v_mad_i64_i32 v[152:153], s[2:3], v145, s16, v[132:133]
	v_lshl_add_u64 v[152:153], v[152:153], 0, s[70:71]
	v_lshl_add_u64 v[152:153], v[152:153], 0, v[134:135]
	global_store_dwordx4 v[152:153], v[146:149], off sc1
	v_pk_mul_f32 v[154:155], v[102:103], v[150:151] op_sel_hi:[1,0]
	v_fmamk_f32 v145, v160, 0x3a800000, v1
	v_pk_mul_f32 v[148:149], v[106:107], v[150:151] op_sel_hi:[1,0]
	v_pk_mul_f32 v[146:147], v[104:105], v[150:151] op_sel_hi:[1,0]
	v_pk_mul_f32 v[150:151], v[100:101], v[150:151] op_sel_hi:[1,0]
	v_cvt_pk_bf16_f32 v146, v146, v147
	v_cvt_pk_bf16_f32 v147, v148, v149
	s_nop 0
	v_cvt_pk_bf16_f32 v148, v150, v151
	v_rsq_f32_e32 v150, v145
	v_cvt_pk_bf16_f32 v149, v154, v155
	global_store_dwordx4 v[152:153], v[146:149], off offset:256 sc1
	v_mad_i64_i32 v[144:145], s[2:3], v144, s16, v[132:133]
	s_nop 0
	v_pk_mul_f32 v[148:149], v[98:99], v[150:151] op_sel_hi:[1,0]
	v_pk_mul_f32 v[146:147], v[96:97], v[150:151] op_sel_hi:[1,0]
	v_pk_mul_f32 v[152:153], v[94:95], v[150:151] op_sel_hi:[1,0]
	v_pk_mul_f32 v[154:155], v[92:93], v[150:151] op_sel_hi:[1,0]
	v_cvt_pk_bf16_f32 v146, v146, v147
	v_cvt_pk_bf16_f32 v147, v148, v149
	v_lshl_add_u64 v[144:145], v[144:145], 0, s[70:71]
	v_cvt_pk_bf16_f32 v148, v154, v155
	v_cvt_pk_bf16_f32 v149, v152, v153
	v_mad_i64_i32 v[152:153], s[2:3], v159, s16, v[132:133]
	v_lshl_add_u64 v[152:153], v[152:153], 0, s[70:71]
	v_lshl_add_u64 v[152:153], v[152:153], 0, v[134:135]
	global_store_dwordx4 v[152:153], v[146:149], off sc1
	v_pk_mul_f32 v[154:155], v[86:87], v[150:151] op_sel_hi:[1,0]
	s_nop 0
	v_pk_mul_f32 v[148:149], v[90:91], v[150:151] op_sel_hi:[1,0]
	v_pk_mul_f32 v[146:147], v[88:89], v[150:151] op_sel_hi:[1,0]
	v_pk_mul_f32 v[150:151], v[84:85], v[150:151] op_sel_hi:[1,0]
	v_cvt_pk_bf16_f32 v146, v146, v147
	v_cvt_pk_bf16_f32 v147, v148, v149
	s_nop 0
	v_cvt_pk_bf16_f32 v148, v150, v151
	v_cvt_pk_bf16_f32 v149, v154, v155
	global_store_dwordx4 v[152:153], v[146:149], off offset:256 sc1
	v_pk_mul_f32 v[150:151], v[78:79], v[2:3] op_sel_hi:[1,0]
	v_pk_mul_f32 v[152:153], v[76:77], v[2:3] op_sel_hi:[1,0]
	v_pk_mul_f32 v[148:149], v[82:83], v[2:3] op_sel_hi:[1,0]
	v_pk_mul_f32 v[146:147], v[80:81], v[2:3] op_sel_hi:[1,0]
	s_nop 0
	v_cvt_pk_bf16_f32 v146, v146, v147
	v_cvt_pk_bf16_f32 v147, v148, v149
	v_cvt_pk_bf16_f32 v148, v152, v153
	v_cvt_pk_bf16_f32 v149, v150, v151
	v_lshl_add_u64 v[150:151], v[144:145], 0, v[134:135]
	global_store_dwordx4 v[150:151], v[146:149], off sc1
	v_pk_mul_f32 v[144:145], v[72:73], v[2:3] op_sel_hi:[1,0]
	v_pk_mul_f32 v[152:153], v[68:69], v[2:3] op_sel_hi:[1,0]
	v_pk_mul_f32 v[146:147], v[74:75], v[2:3] op_sel_hi:[1,0]
	v_pk_mul_f32 v[148:149], v[70:71], v[2:3] op_sel_hi:[1,0]
	v_fmamk_f32 v2, v143, 0x3a800000, v1
	v_rsq_f32_e32 v2, v2
	v_cvt_pk_bf16_f32 v144, v144, v145
	v_cvt_pk_bf16_f32 v145, v146, v147
	v_cvt_pk_bf16_f32 v146, v152, v153
	v_cvt_pk_bf16_f32 v147, v148, v149
	v_mad_i64_i32 v[142:143], s[2:3], v142, s16, v[132:133]
	global_store_dwordx4 v[150:151], v[144:147], off offset:256 sc1
	v_pk_mul_f32 v[148:149], v[62:63], v[2:3] op_sel_hi:[1,0]
	v_lshl_add_u64 v[142:143], v[142:143], 0, s[70:71]
	v_pk_mul_f32 v[146:147], v[66:67], v[2:3] op_sel_hi:[1,0]
	v_pk_mul_f32 v[144:145], v[64:65], v[2:3] op_sel_hi:[1,0]
	v_pk_mul_f32 v[150:151], v[60:61], v[2:3] op_sel_hi:[1,0]
	v_cvt_pk_bf16_f32 v144, v144, v145
	v_cvt_pk_bf16_f32 v145, v146, v147
	s_nop 0
	v_cvt_pk_bf16_f32 v146, v150, v151
	v_cvt_pk_bf16_f32 v147, v148, v149
	v_lshl_add_u64 v[148:149], v[142:143], 0, v[134:135]
	global_store_dwordx4 v[148:149], v[144:147], off sc1
	v_pk_mul_f32 v[142:143], v[56:57], v[2:3] op_sel_hi:[1,0]
	v_pk_mul_f32 v[150:151], v[52:53], v[2:3] op_sel_hi:[1,0]
	v_pk_mul_f32 v[144:145], v[58:59], v[2:3] op_sel_hi:[1,0]
	v_pk_mul_f32 v[146:147], v[54:55], v[2:3] op_sel_hi:[1,0]
	v_fmamk_f32 v2, v141, 0x3a800000, v1
	v_rsq_f32_e32 v2, v2
	v_cvt_pk_bf16_f32 v142, v142, v143
	v_cvt_pk_bf16_f32 v143, v144, v145
	v_cvt_pk_bf16_f32 v144, v150, v151
	v_cvt_pk_bf16_f32 v145, v146, v147
	v_mad_i64_i32 v[140:141], s[2:3], v140, s16, v[132:133]
	global_store_dwordx4 v[148:149], v[142:145], off offset:256 sc1
	v_pk_mul_f32 v[146:147], v[46:47], v[2:3] op_sel_hi:[1,0]
	v_lshl_add_u64 v[140:141], v[140:141], 0, s[70:71]
	v_pk_mul_f32 v[144:145], v[50:51], v[2:3] op_sel_hi:[1,0]
	v_pk_mul_f32 v[142:143], v[48:49], v[2:3] op_sel_hi:[1,0]
	v_pk_mul_f32 v[148:149], v[44:45], v[2:3] op_sel_hi:[1,0]
	v_cvt_pk_bf16_f32 v142, v142, v143
	v_cvt_pk_bf16_f32 v143, v144, v145
	s_nop 0
	v_cvt_pk_bf16_f32 v144, v148, v149
	v_cvt_pk_bf16_f32 v145, v146, v147
	v_lshl_add_u64 v[146:147], v[140:141], 0, v[134:135]
	global_store_dwordx4 v[146:147], v[142:145], off sc1
	v_pk_mul_f32 v[140:141], v[40:41], v[2:3] op_sel_hi:[1,0]
	v_pk_mul_f32 v[148:149], v[36:37], v[2:3] op_sel_hi:[1,0]
	v_pk_mul_f32 v[142:143], v[42:43], v[2:3] op_sel_hi:[1,0]
	v_pk_mul_f32 v[144:145], v[38:39], v[2:3] op_sel_hi:[1,0]
	v_fmamk_f32 v2, v139, 0x3a800000, v1
	v_rsq_f32_e32 v2, v2
	v_cvt_pk_bf16_f32 v140, v140, v141
	v_cvt_pk_bf16_f32 v141, v142, v143
	v_cvt_pk_bf16_f32 v142, v148, v149
	v_cvt_pk_bf16_f32 v143, v144, v145
	v_mad_i64_i32 v[138:139], s[2:3], v138, s16, v[132:133]
	global_store_dwordx4 v[146:147], v[140:143], off offset:256 sc1
	v_pk_mul_f32 v[144:145], v[30:31], v[2:3] op_sel_hi:[1,0]
	v_lshl_add_u64 v[138:139], v[138:139], 0, s[70:71]
	v_pk_mul_f32 v[142:143], v[34:35], v[2:3] op_sel_hi:[1,0]
	v_pk_mul_f32 v[140:141], v[32:33], v[2:3] op_sel_hi:[1,0]
	v_pk_mul_f32 v[146:147], v[28:29], v[2:3] op_sel_hi:[1,0]
	v_cvt_pk_bf16_f32 v140, v140, v141
	v_cvt_pk_bf16_f32 v141, v142, v143
	v_mad_i64_i32 v[132:133], s[2:3], v136, s16, v[132:133]
	v_cvt_pk_bf16_f32 v142, v146, v147
	v_cvt_pk_bf16_f32 v143, v144, v145
	v_lshl_add_u64 v[144:145], v[138:139], 0, v[134:135]
	global_store_dwordx4 v[144:145], v[140:143], off sc1
	v_pk_mul_f32 v[138:139], v[24:25], v[2:3] op_sel_hi:[1,0]
	v_pk_mul_f32 v[146:147], v[20:21], v[2:3] op_sel_hi:[1,0]
	v_pk_mul_f32 v[140:141], v[26:27], v[2:3] op_sel_hi:[1,0]
	v_pk_mul_f32 v[142:143], v[22:23], v[2:3] op_sel_hi:[1,0]
	v_fmamk_f32 v2, v137, 0x3a800000, v1
	v_rsq_f32_e32 v2, v2
	v_cvt_pk_bf16_f32 v138, v138, v139
	v_cvt_pk_bf16_f32 v139, v140, v141
	v_cvt_pk_bf16_f32 v140, v146, v147
	v_cvt_pk_bf16_f32 v141, v142, v143
	global_store_dwordx4 v[144:145], v[138:141], off offset:256 sc1
	v_lshl_add_u64 v[132:133], v[132:133], 0, s[70:71]
	v_pk_mul_f32 v[142:143], v[14:15], v[2:3] op_sel_hi:[1,0]
	v_pk_mul_f32 v[140:141], v[18:19], v[2:3] op_sel_hi:[1,0]
	v_pk_mul_f32 v[138:139], v[16:17], v[2:3] op_sel_hi:[1,0]
	v_pk_mul_f32 v[144:145], v[12:13], v[2:3] op_sel_hi:[1,0]
	v_cvt_pk_bf16_f32 v138, v138, v139
	v_cvt_pk_bf16_f32 v139, v140, v141
	v_lshl_add_u64 v[136:137], v[132:133], 0, v[134:135]
	v_cvt_pk_bf16_f32 v140, v144, v145
	v_cvt_pk_bf16_f32 v141, v142, v143
	v_pk_mul_f32 v[134:135], v[10:11], v[2:3] op_sel_hi:[1,0]
	v_pk_mul_f32 v[132:133], v[8:9], v[2:3] op_sel_hi:[1,0]
	global_store_dwordx4 v[136:137], v[138:141], off sc1
	v_cvt_pk_bf16_f32 v132, v132, v133
	v_cvt_pk_bf16_f32 v133, v134, v135
	s_mov_b64 s[70:71], 0
	s_nop 0
	v_pk_mul_f32 v[138:139], v[6:7], v[2:3] op_sel_hi:[1,0]
	v_pk_mul_f32 v[140:141], v[4:5], v[2:3] op_sel_hi:[1,0]
	s_nop 0
	v_cvt_pk_bf16_f32 v134, v140, v141
	v_cvt_pk_bf16_f32 v135, v138, v139
	global_store_dwordx4 v[136:137], v[132:135], off offset:256 sc1
.LBB0_972:
	s_andn2_b64 vcc, exec, s[70:71]
	s_cbranch_vccnz .LBB0_974
	s_lshl_b32 s0, s68, 8
	s_add_i32 s0, s0, s90
	v_add_u32_e32 v158, s0, v191
	v_ashrrev_i32_e32 v159, 31, v158
	v_lshl_add_u64 v[132:133], v[158:159], 2, s[30:31]
	global_load_dword v183, v[132:133], off
	global_load_dword v197, v[132:133], off offset:64
	global_load_dword v182, v[132:133], off offset:128
	global_load_dword v181, v[132:133], off offset:192
	v_readlane_b32 s0, v253, 9
	global_load_dword v177, v[132:133], off offset:512
	global_load_dword v163, v[132:133], off offset:576
	global_load_dword v162, v[132:133], off offset:640
	global_load_dword v159, v[132:133], off offset:704
	v_add_lshl_u32 v132, v190, s0, 2
	v_ashrrev_i32_e32 v133, 31, v132
	v_lshlrev_b32_e32 v2, 8, v158
	v_lshl_add_u64 v[160:161], v[132:133], 2, s[50:51]
	v_and_b32_e32 v2, 0x1fff00, v2
	v_lshl_add_u64 v[132:133], v[160:161], 0, v[2:3]
	global_load_dwordx4 v[198:201], v[132:133], off
	global_load_dwordx4 v[202:205], v[132:133], off offset:128
	v_lshlrev_b32_e32 v157, 6, v158
	v_add_u32_e32 v2, 0x400, v157
	v_and_b32_e32 v2, 0x7ffc0, v2
	v_lshlrev_b32_e32 v2, 2, v2
	v_lshl_add_u64 v[132:133], v[160:161], 0, v[2:3]
	global_load_dwordx4 v[148:151], v[132:133], off
	global_load_dwordx4 v[152:155], v[132:133], off offset:128
	v_add_u32_e32 v2, 0x800, v157
	v_and_b32_e32 v2, 0x7ffc0, v2
	v_lshlrev_b32_e32 v2, 2, v2
	v_lshl_add_u64 v[132:133], v[160:161], 0, v[2:3]
	global_load_dwordx4 v[140:143], v[132:133], off
	global_load_dwordx4 v[144:147], v[132:133], off offset:128
	v_add_u32_e32 v2, 0xc00, v157
	v_and_b32_e32 v2, 0x7ffc0, v2
	v_lshlrev_b32_e32 v2, 2, v2
	v_lshl_add_u64 v[136:137], v[160:161], 0, v[2:3]
	global_load_dwordx4 v[132:135], v[136:137], off
	s_nop 0
	global_load_dwordx4 v[136:139], v[136:137], off offset:128
	v_add_u32_e32 v179, 16, v158
	v_add_u32_e32 v180, 32, v158
	v_add_u32_e32 v178, 48, v158
	v_add_u32_e32 v176, 0x80, v158
	s_waitcnt vmcnt(0)
	v_fmamk_f32 v2, v183, 0x3a800000, v1
	v_rsq_f32_e32 v2, v2
	s_nop 0
	v_mul_f32_e32 v2, 0x3e38aa3b, v2
	v_pk_mul_f32 v[128:129], v[128:129], v[2:3] op_sel_hi:[1,0]
	v_pk_mul_f32 v[130:131], v[130:131], v[2:3] op_sel_hi:[1,0]
	v_pk_mul_f32 v[124:125], v[124:125], v[2:3] op_sel_hi:[1,0]
	v_pk_mul_f32 v[126:127], v[126:127], v[2:3] op_sel_hi:[1,0]
	v_pk_mul_f32 v[120:121], v[120:121], v[2:3] op_sel_hi:[1,0]
	v_pk_mul_f32 v[122:123], v[122:123], v[2:3] op_sel_hi:[1,0]
	v_pk_mul_f32 v[116:117], v[116:117], v[2:3] op_sel_hi:[1,0]
	v_pk_mul_f32 v[118:119], v[118:119], v[2:3] op_sel_hi:[1,0]
	v_fmamk_f32 v2, v197, 0x3a800000, v1
	v_pk_mul_f32 v[184:185], v[126:127], v[204:205]
	v_pk_mul_f32 v[190:191], v[124:125], v[202:203]
	v_rsq_f32_e32 v2, v2
	v_pk_fma_f32 v[184:185], v[130:131], v[200:201], v[184:185] neg_lo:[0,0,1] neg_hi:[0,0,1]
	v_pk_fma_f32 v[190:191], v[128:129], v[198:199], v[190:191] neg_lo:[0,0,1] neg_hi:[0,0,1]
	v_pk_mul_f32 v[130:131], v[130:131], v[204:205]
	v_pk_mul_f32 v[128:129], v[128:129], v[202:203]
	v_pk_fma_f32 v[130:131], v[126:127], v[200:201], v[130:131]
	v_pk_fma_f32 v[126:127], v[124:125], v[198:199], v[128:129]
	v_cvt_pk_bf16_f32 v124, v190, v191
	v_cvt_pk_bf16_f32 v125, v184, v185
	v_pk_mul_f32 v[128:129], v[118:119], v[204:205]
	v_cvt_pk_bf16_f32 v126, v126, v127
	v_cvt_pk_bf16_f32 v127, v130, v131
	v_pk_mul_f32 v[130:131], v[116:117], v[202:203]
	v_pk_fma_f32 v[128:129], v[122:123], v[200:201], v[128:129] neg_lo:[0,0,1] neg_hi:[0,0,1]
	v_pk_fma_f32 v[130:131], v[120:121], v[198:199], v[130:131] neg_lo:[0,0,1] neg_hi:[0,0,1]
	v_pk_mul_f32 v[122:123], v[122:123], v[204:205]
	v_pk_mul_f32 v[120:121], v[120:121], v[202:203]
	v_mul_f32_e32 v2, 0x3e38aa3b, v2
	v_pk_fma_f32 v[122:123], v[118:119], v[200:201], v[122:123]
	v_pk_fma_f32 v[118:119], v[116:117], v[198:199], v[120:121]
	v_pk_mul_f32 v[112:113], v[112:113], v[2:3] op_sel_hi:[1,0]
	v_pk_mul_f32 v[114:115], v[114:115], v[2:3] op_sel_hi:[1,0]
	v_pk_mul_f32 v[108:109], v[108:109], v[2:3] op_sel_hi:[1,0]
	v_pk_mul_f32 v[110:111], v[110:111], v[2:3] op_sel_hi:[1,0]
	v_pk_mul_f32 v[104:105], v[104:105], v[2:3] op_sel_hi:[1,0]
	v_pk_mul_f32 v[106:107], v[106:107], v[2:3] op_sel_hi:[1,0]
	v_pk_mul_f32 v[100:101], v[100:101], v[2:3] op_sel_hi:[1,0]
	v_pk_mul_f32 v[102:103], v[102:103], v[2:3] op_sel_hi:[1,0]
	v_fmamk_f32 v2, v182, 0x3a800000, v1
	v_cvt_pk_bf16_f32 v116, v130, v131
	v_cvt_pk_bf16_f32 v117, v128, v129
	v_cvt_pk_bf16_f32 v118, v118, v119
	v_cvt_pk_bf16_f32 v119, v122, v123
	v_pk_mul_f32 v[120:121], v[110:111], v[154:155]
	v_pk_mul_f32 v[122:123], v[108:109], v[152:153]
	v_rsq_f32_e32 v2, v2
	v_pk_fma_f32 v[120:121], v[114:115], v[150:151], v[120:121] neg_lo:[0,0,1] neg_hi:[0,0,1]
	v_pk_fma_f32 v[122:123], v[112:113], v[148:149], v[122:123] neg_lo:[0,0,1] neg_hi:[0,0,1]
	v_pk_mul_f32 v[114:115], v[114:115], v[154:155]
	v_pk_mul_f32 v[112:113], v[112:113], v[152:153]
	v_pk_fma_f32 v[114:115], v[110:111], v[150:151], v[114:115]
	v_pk_fma_f32 v[110:111], v[108:109], v[148:149], v[112:113]
	v_cvt_pk_bf16_f32 v108, v122, v123
	v_cvt_pk_bf16_f32 v109, v120, v121
	v_pk_mul_f32 v[112:113], v[102:103], v[154:155]
	v_cvt_pk_bf16_f32 v110, v110, v111
	v_cvt_pk_bf16_f32 v111, v114, v115
	v_pk_mul_f32 v[114:115], v[100:101], v[152:153]
	v_pk_fma_f32 v[112:113], v[106:107], v[150:151], v[112:113] neg_lo:[0,0,1] neg_hi:[0,0,1]
	v_pk_fma_f32 v[114:115], v[104:105], v[148:149], v[114:115] neg_lo:[0,0,1] neg_hi:[0,0,1]
	v_pk_mul_f32 v[106:107], v[106:107], v[154:155]
	v_pk_mul_f32 v[104:105], v[104:105], v[152:153]
	v_mul_f32_e32 v2, 0x3e38aa3b, v2
	v_pk_fma_f32 v[106:107], v[102:103], v[150:151], v[106:107]
	v_pk_fma_f32 v[102:103], v[100:101], v[148:149], v[104:105]
	v_pk_mul_f32 v[96:97], v[96:97], v[2:3] op_sel_hi:[1,0]
	v_pk_mul_f32 v[98:99], v[98:99], v[2:3] op_sel_hi:[1,0]
	v_pk_mul_f32 v[92:93], v[92:93], v[2:3] op_sel_hi:[1,0]
	v_pk_mul_f32 v[94:95], v[94:95], v[2:3] op_sel_hi:[1,0]
	v_pk_mul_f32 v[88:89], v[88:89], v[2:3] op_sel_hi:[1,0]
	v_pk_mul_f32 v[90:91], v[90:91], v[2:3] op_sel_hi:[1,0]
	v_pk_mul_f32 v[84:85], v[84:85], v[2:3] op_sel_hi:[1,0]
	v_pk_mul_f32 v[86:87], v[86:87], v[2:3] op_sel_hi:[1,0]
	v_fmamk_f32 v2, v181, 0x3a800000, v1
	v_cvt_pk_bf16_f32 v100, v114, v115
	v_cvt_pk_bf16_f32 v101, v112, v113
	v_cvt_pk_bf16_f32 v102, v102, v103
	v_cvt_pk_bf16_f32 v103, v106, v107
	v_pk_mul_f32 v[104:105], v[94:95], v[146:147]
	v_pk_mul_f32 v[106:107], v[92:93], v[144:145]
	v_rsq_f32_e32 v2, v2
	v_pk_fma_f32 v[104:105], v[98:99], v[142:143], v[104:105] neg_lo:[0,0,1] neg_hi:[0,0,1]
	v_pk_fma_f32 v[106:107], v[96:97], v[140:141], v[106:107] neg_lo:[0,0,1] neg_hi:[0,0,1]
	v_pk_mul_f32 v[98:99], v[98:99], v[146:147]
	v_pk_mul_f32 v[96:97], v[96:97], v[144:145]
	v_pk_fma_f32 v[98:99], v[94:95], v[142:143], v[98:99]
	v_pk_fma_f32 v[94:95], v[92:93], v[140:141], v[96:97]
	v_cvt_pk_bf16_f32 v92, v106, v107
	v_cvt_pk_bf16_f32 v93, v104, v105
	v_pk_mul_f32 v[96:97], v[86:87], v[146:147]
	v_cvt_pk_bf16_f32 v94, v94, v95
	v_cvt_pk_bf16_f32 v95, v98, v99
	v_pk_mul_f32 v[98:99], v[84:85], v[144:145]
	v_pk_fma_f32 v[96:97], v[90:91], v[142:143], v[96:97] neg_lo:[0,0,1] neg_hi:[0,0,1]
	v_pk_fma_f32 v[98:99], v[88:89], v[140:141], v[98:99] neg_lo:[0,0,1] neg_hi:[0,0,1]
	v_pk_mul_f32 v[90:91], v[90:91], v[146:147]
	v_pk_mul_f32 v[88:89], v[88:89], v[144:145]
	v_mul_f32_e32 v2, 0x3e38aa3b, v2
	v_pk_fma_f32 v[86:87], v[86:87], v[142:143], v[90:91]
	v_pk_fma_f32 v[84:85], v[84:85], v[140:141], v[88:89]
	v_pk_mul_f32 v[76:77], v[76:77], v[2:3] op_sel_hi:[1,0]
	v_pk_mul_f32 v[78:79], v[78:79], v[2:3] op_sel_hi:[1,0]
	v_cvt_pk_bf16_f32 v88, v98, v99
	v_cvt_pk_bf16_f32 v89, v96, v97
	v_cvt_pk_bf16_f32 v90, v84, v85
	v_cvt_pk_bf16_f32 v91, v86, v87
	v_pk_mul_f32 v[80:81], v[80:81], v[2:3] op_sel_hi:[1,0]
	v_pk_mul_f32 v[82:83], v[82:83], v[2:3] op_sel_hi:[1,0]
	v_pk_mul_f32 v[84:85], v[78:79], v[138:139]
	v_pk_mul_f32 v[86:87], v[76:77], v[136:137]
	v_pk_fma_f32 v[84:85], v[82:83], v[134:135], v[84:85] neg_lo:[0,0,1] neg_hi:[0,0,1]
	v_pk_fma_f32 v[86:87], v[80:81], v[132:133], v[86:87] neg_lo:[0,0,1] neg_hi:[0,0,1]
	v_pk_mul_f32 v[82:83], v[82:83], v[138:139]
	v_pk_mul_f32 v[80:81], v[80:81], v[136:137]
	v_pk_fma_f32 v[78:79], v[78:79], v[134:135], v[82:83]
	v_pk_fma_f32 v[76:77], v[76:77], v[132:133], v[80:81]
	v_pk_mul_f32 v[68:69], v[68:69], v[2:3] op_sel_hi:[1,0]
	v_pk_mul_f32 v[70:71], v[70:71], v[2:3] op_sel_hi:[1,0]
	v_cvt_pk_bf16_f32 v96, v86, v87
	v_cvt_pk_bf16_f32 v97, v84, v85
	v_cvt_pk_bf16_f32 v98, v76, v77
	v_cvt_pk_bf16_f32 v99, v78, v79
	v_pk_mul_f32 v[72:73], v[72:73], v[2:3] op_sel_hi:[1,0]
	v_pk_mul_f32 v[74:75], v[74:75], v[2:3] op_sel_hi:[1,0]
	v_pk_mul_f32 v[76:77], v[70:71], v[138:139]
	v_pk_mul_f32 v[78:79], v[68:69], v[136:137]
	v_pk_fma_f32 v[76:77], v[74:75], v[134:135], v[76:77] neg_lo:[0,0,1] neg_hi:[0,0,1]
	v_pk_fma_f32 v[78:79], v[72:73], v[132:133], v[78:79] neg_lo:[0,0,1] neg_hi:[0,0,1]
	v_pk_mul_f32 v[74:75], v[74:75], v[138:139]
	v_pk_mul_f32 v[72:73], v[72:73], v[136:137]
	v_pk_fma_f32 v[70:71], v[70:71], v[134:135], v[74:75]
	v_pk_fma_f32 v[68:69], v[68:69], v[132:133], v[72:73]
	v_cvt_pk_bf16_f32 v104, v78, v79
	v_cvt_pk_bf16_f32 v105, v76, v77
	s_nop 0
	v_cvt_pk_bf16_f32 v106, v68, v69
	v_cvt_pk_bf16_f32 v107, v70, v71
	v_add_u32_e32 v2, 0x2000, v157
	v_and_b32_e32 v2, 0x7ffc0, v2
	v_lshlrev_b32_e32 v2, 2, v2
	v_lshl_add_u64 v[68:69], v[160:161], 0, v[2:3]
	v_add_u32_e32 v2, 0x2400, v157
	v_and_b32_e32 v2, 0x7ffc0, v2
	v_lshlrev_b32_e32 v2, 2, v2
	global_load_dwordx4 v[112:115], v[68:69], off
	global_load_dwordx4 v[120:123], v[68:69], off offset:128
	v_lshl_add_u64 v[68:69], v[160:161], 0, v[2:3]
	v_add_u32_e32 v2, 0x2800, v157
	v_and_b32_e32 v2, 0x7ffc0, v2
	v_lshlrev_b32_e32 v2, 2, v2
	global_load_dwordx4 v[128:131], v[68:69], off
	global_load_dwordx4 v[132:135], v[68:69], off offset:128
	v_lshl_add_u64 v[68:69], v[160:161], 0, v[2:3]
	v_add_u32_e32 v2, 0x2c00, v157
	v_and_b32_e32 v2, 0x7ffc0, v2
	v_lshlrev_b32_e32 v2, 2, v2
	v_lshl_add_u64 v[72:73], v[160:161], 0, v[2:3]
	global_load_dwordx4 v[76:79], v[68:69], off
	global_load_dwordx4 v[80:83], v[68:69], off offset:128
	s_nop 0
	global_load_dwordx4 v[68:71], v[72:73], off
	s_nop 0
	global_load_dwordx4 v[72:75], v[72:73], off offset:128
	s_lshl_b32 s2, s62, 8
	v_mov_b64_e32 v[84:85], s[20:21]
	s_ashr_i32 s3, s2, 31
	v_mad_i64_i32 v[86:87], s[62:63], v158, s16, v[84:85]
	v_ashrrev_i32_e32 v157, 31, v156
	s_lshl_b64 s[62:63], s[2:3], 1
	v_lshl_add_u64 v[136:137], v[86:87], 0, s[62:63]
	v_lshlrev_b64 v[86:87], 1, v[156:157]
	v_lshl_add_u64 v[136:137], v[136:137], 0, v[86:87]
	global_store_dwordx4 v[136:137], v[124:127], off sc1
	global_store_dwordx4 v[136:137], v[116:119], off offset:256 sc1
	v_fmamk_f32 v2, v177, 0x3a800000, v1
	v_rsq_f32_e32 v2, v2
	v_mad_i64_i32 v[116:117], s[2:3], v179, s16, v[84:85]
	v_lshl_add_u64 v[116:117], v[116:117], 0, s[62:63]
	v_lshl_add_u64 v[116:117], v[116:117], 0, v[86:87]
	global_store_dwordx4 v[116:117], v[108:111], off sc1
	global_store_dwordx4 v[116:117], v[100:103], off offset:256 sc1
	v_mul_f32_e32 v2, 0x3e38aa3b, v2
	v_pk_mul_f32 v[60:61], v[60:61], v[2:3] op_sel_hi:[1,0]
	v_mad_i64_i32 v[100:101], s[2:3], v180, s16, v[84:85]
	v_lshl_add_u64 v[100:101], v[100:101], 0, s[62:63]
	v_lshl_add_u64 v[100:101], v[100:101], 0, v[86:87]
	global_store_dwordx4 v[100:101], v[92:95], off sc1
	global_store_dwordx4 v[100:101], v[88:91], off offset:256 sc1
	v_pk_mul_f32 v[62:63], v[62:63], v[2:3] op_sel_hi:[1,0]
	v_pk_mul_f32 v[64:65], v[64:65], v[2:3] op_sel_hi:[1,0]
	v_mad_i64_i32 v[88:89], s[2:3], v178, s16, v[84:85]
	v_lshl_add_u64 v[88:89], v[88:89], 0, s[62:63]
	v_lshl_add_u64 v[88:89], v[88:89], 0, v[86:87]
	global_store_dwordx4 v[88:89], v[96:99], off sc1
	global_store_dwordx4 v[88:89], v[104:107], off offset:256 sc1
	v_pk_mul_f32 v[66:67], v[66:67], v[2:3] op_sel_hi:[1,0]
	s_waitcnt vmcnt(14)
	v_pk_mul_f32 v[88:89], v[62:63], v[122:123]
	v_pk_mul_f32 v[90:91], v[60:61], v[120:121]
	v_pk_fma_f32 v[88:89], v[66:67], v[114:115], v[88:89] neg_lo:[0,0,1] neg_hi:[0,0,1]
	v_pk_fma_f32 v[90:91], v[64:65], v[112:113], v[90:91] neg_lo:[0,0,1] neg_hi:[0,0,1]
	v_pk_mul_f32 v[66:67], v[66:67], v[122:123]
	v_pk_mul_f32 v[64:65], v[64:65], v[120:121]
	v_pk_fma_f32 v[66:67], v[62:63], v[114:115], v[66:67]
	v_pk_fma_f32 v[62:63], v[60:61], v[112:113], v[64:65]
	v_mad_i64_i32 v[64:65], s[2:3], v176, s16, v[84:85]
	v_pk_mul_f32 v[56:57], v[56:57], v[2:3] op_sel_hi:[1,0]
	v_pk_mul_f32 v[58:59], v[58:59], v[2:3] op_sel_hi:[1,0]
	v_pk_mul_f32 v[52:53], v[52:53], v[2:3] op_sel_hi:[1,0]
	v_pk_mul_f32 v[54:55], v[54:55], v[2:3] op_sel_hi:[1,0]
	v_fmamk_f32 v2, v163, 0x3a800000, v1
	v_lshl_add_u64 v[64:65], v[64:65], 0, s[62:63]
	v_rsq_f32_e32 v2, v2
	v_cvt_pk_bf16_f32 v60, v90, v91
	v_cvt_pk_bf16_f32 v61, v88, v89
	v_cvt_pk_bf16_f32 v62, v62, v63
	v_cvt_pk_bf16_f32 v63, v66, v67
	v_lshl_add_u64 v[64:65], v[64:65], 0, v[86:87]
	global_store_dwordx4 v[64:65], v[60:63], off sc1
	v_mul_f32_e32 v2, 0x3e38aa3b, v2
	v_pk_mul_f32 v[44:45], v[44:45], v[2:3] op_sel_hi:[1,0]
	v_pk_mul_f32 v[60:61], v[54:55], v[122:123]
	v_pk_mul_f32 v[62:63], v[52:53], v[120:121]
	v_pk_fma_f32 v[60:61], v[58:59], v[114:115], v[60:61] neg_lo:[0,0,1] neg_hi:[0,0,1]
	v_pk_fma_f32 v[62:63], v[56:57], v[112:113], v[62:63] neg_lo:[0,0,1] neg_hi:[0,0,1]
	v_pk_mul_f32 v[58:59], v[58:59], v[122:123]
	v_pk_mul_f32 v[56:57], v[56:57], v[120:121]
	v_pk_fma_f32 v[58:59], v[54:55], v[114:115], v[58:59]
	v_pk_fma_f32 v[54:55], v[52:53], v[112:113], v[56:57]
	v_cvt_pk_bf16_f32 v52, v62, v63
	v_cvt_pk_bf16_f32 v53, v60, v61
	v_pk_mul_f32 v[46:47], v[46:47], v[2:3] op_sel_hi:[1,0]
	v_cvt_pk_bf16_f32 v54, v54, v55
	v_cvt_pk_bf16_f32 v55, v58, v59
	global_store_dwordx4 v[64:65], v[52:55], off offset:256 sc1
	v_pk_mul_f32 v[48:49], v[48:49], v[2:3] op_sel_hi:[1,0]
	v_pk_mul_f32 v[50:51], v[50:51], v[2:3] op_sel_hi:[1,0]
	s_waitcnt vmcnt(14)
	v_pk_mul_f32 v[52:53], v[46:47], v[134:135]
	v_pk_mul_f32 v[54:55], v[44:45], v[132:133]
	v_add_u32_e32 v56, 0x90, v158
	v_pk_fma_f32 v[52:53], v[50:51], v[130:131], v[52:53] neg_lo:[0,0,1] neg_hi:[0,0,1]
	v_pk_fma_f32 v[54:55], v[48:49], v[128:129], v[54:55] neg_lo:[0,0,1] neg_hi:[0,0,1]
	v_pk_mul_f32 v[50:51], v[50:51], v[134:135]
	v_pk_mul_f32 v[48:49], v[48:49], v[132:133]
	v_pk_fma_f32 v[50:51], v[46:47], v[130:131], v[50:51]
	v_pk_fma_f32 v[46:47], v[44:45], v[128:129], v[48:49]
	v_mad_i64_i32 v[48:49], s[2:3], v56, s16, v[84:85]
	v_pk_mul_f32 v[40:41], v[40:41], v[2:3] op_sel_hi:[1,0]
	v_pk_mul_f32 v[42:43], v[42:43], v[2:3] op_sel_hi:[1,0]
	v_pk_mul_f32 v[36:37], v[36:37], v[2:3] op_sel_hi:[1,0]
	v_pk_mul_f32 v[38:39], v[38:39], v[2:3] op_sel_hi:[1,0]
	v_fmamk_f32 v2, v162, 0x3a800000, v1
	v_lshl_add_u64 v[48:49], v[48:49], 0, s[62:63]
	v_rsq_f32_e32 v2, v2
	v_cvt_pk_bf16_f32 v44, v54, v55
	v_cvt_pk_bf16_f32 v45, v52, v53
	v_cvt_pk_bf16_f32 v46, v46, v47
	v_cvt_pk_bf16_f32 v47, v50, v51
	v_lshl_add_u64 v[48:49], v[48:49], 0, v[86:87]
	global_store_dwordx4 v[48:49], v[44:47], off sc1
	v_mul_f32_e32 v2, 0x3e38aa3b, v2
	v_pk_mul_f32 v[28:29], v[28:29], v[2:3] op_sel_hi:[1,0]
	v_pk_mul_f32 v[44:45], v[38:39], v[134:135]
	v_pk_mul_f32 v[46:47], v[36:37], v[132:133]
	v_pk_fma_f32 v[44:45], v[42:43], v[130:131], v[44:45] neg_lo:[0,0,1] neg_hi:[0,0,1]
	v_pk_fma_f32 v[46:47], v[40:41], v[128:129], v[46:47] neg_lo:[0,0,1] neg_hi:[0,0,1]
	v_pk_mul_f32 v[42:43], v[42:43], v[134:135]
	v_pk_mul_f32 v[40:41], v[40:41], v[132:133]
	v_pk_fma_f32 v[42:43], v[38:39], v[130:131], v[42:43]
	v_pk_fma_f32 v[38:39], v[36:37], v[128:129], v[40:41]
	v_cvt_pk_bf16_f32 v36, v46, v47
	v_cvt_pk_bf16_f32 v37, v44, v45
	v_pk_mul_f32 v[30:31], v[30:31], v[2:3] op_sel_hi:[1,0]
	v_cvt_pk_bf16_f32 v38, v38, v39
	v_cvt_pk_bf16_f32 v39, v42, v43
	global_store_dwordx4 v[48:49], v[36:39], off offset:256 sc1
	v_pk_mul_f32 v[32:33], v[32:33], v[2:3] op_sel_hi:[1,0]
	v_pk_mul_f32 v[34:35], v[34:35], v[2:3] op_sel_hi:[1,0]
	s_waitcnt vmcnt(14)
	v_pk_mul_f32 v[36:37], v[30:31], v[82:83]
	v_pk_mul_f32 v[38:39], v[28:29], v[80:81]
	v_add_u32_e32 v40, 0xa0, v158
	v_pk_fma_f32 v[36:37], v[34:35], v[78:79], v[36:37] neg_lo:[0,0,1] neg_hi:[0,0,1]
	v_pk_fma_f32 v[38:39], v[32:33], v[76:77], v[38:39] neg_lo:[0,0,1] neg_hi:[0,0,1]
	v_pk_mul_f32 v[34:35], v[34:35], v[82:83]
	v_pk_mul_f32 v[32:33], v[32:33], v[80:81]
	v_pk_fma_f32 v[34:35], v[30:31], v[78:79], v[34:35]
	v_pk_fma_f32 v[30:31], v[28:29], v[76:77], v[32:33]
	v_mad_i64_i32 v[32:33], s[2:3], v40, s16, v[84:85]
	v_pk_mul_f32 v[24:25], v[24:25], v[2:3] op_sel_hi:[1,0]
	v_pk_mul_f32 v[26:27], v[26:27], v[2:3] op_sel_hi:[1,0]
	v_pk_mul_f32 v[20:21], v[20:21], v[2:3] op_sel_hi:[1,0]
	v_pk_mul_f32 v[22:23], v[22:23], v[2:3] op_sel_hi:[1,0]
	v_fmamk_f32 v2, v159, 0x3a800000, v1
	v_lshl_add_u64 v[32:33], v[32:33], 0, s[62:63]
	v_rsq_f32_e32 v2, v2
	v_cvt_pk_bf16_f32 v28, v38, v39
	v_cvt_pk_bf16_f32 v29, v36, v37
	v_cvt_pk_bf16_f32 v30, v30, v31
	v_cvt_pk_bf16_f32 v31, v34, v35
	v_lshl_add_u64 v[32:33], v[32:33], 0, v[86:87]
	global_store_dwordx4 v[32:33], v[28:31], off sc1
	v_mul_f32_e32 v2, 0x3e38aa3b, v2
	v_pk_mul_f32 v[12:13], v[12:13], v[2:3] op_sel_hi:[1,0]
	v_pk_mul_f32 v[28:29], v[22:23], v[82:83]
	v_pk_mul_f32 v[30:31], v[20:21], v[80:81]
	v_pk_fma_f32 v[28:29], v[26:27], v[78:79], v[28:29] neg_lo:[0,0,1] neg_hi:[0,0,1]
	v_pk_fma_f32 v[30:31], v[24:25], v[76:77], v[30:31] neg_lo:[0,0,1] neg_hi:[0,0,1]
	v_pk_mul_f32 v[26:27], v[26:27], v[82:83]
	v_pk_mul_f32 v[24:25], v[24:25], v[80:81]
	v_pk_fma_f32 v[26:27], v[22:23], v[78:79], v[26:27]
	v_pk_fma_f32 v[22:23], v[20:21], v[76:77], v[24:25]
	v_cvt_pk_bf16_f32 v20, v30, v31
	v_cvt_pk_bf16_f32 v21, v28, v29
	v_pk_mul_f32 v[14:15], v[14:15], v[2:3] op_sel_hi:[1,0]
	v_cvt_pk_bf16_f32 v22, v22, v23
	v_cvt_pk_bf16_f32 v23, v26, v27
	global_store_dwordx4 v[32:33], v[20:23], off offset:256 sc1
	v_pk_mul_f32 v[16:17], v[16:17], v[2:3] op_sel_hi:[1,0]
	v_pk_mul_f32 v[18:19], v[18:19], v[2:3] op_sel_hi:[1,0]
	s_waitcnt vmcnt(14)
	v_pk_mul_f32 v[20:21], v[14:15], v[74:75]
	v_pk_mul_f32 v[22:23], v[12:13], v[72:73]
	v_add_u32_e32 v24, 0xb0, v158
	v_pk_fma_f32 v[20:21], v[18:19], v[70:71], v[20:21] neg_lo:[0,0,1] neg_hi:[0,0,1]
	v_pk_fma_f32 v[22:23], v[16:17], v[68:69], v[22:23] neg_lo:[0,0,1] neg_hi:[0,0,1]
	v_pk_mul_f32 v[18:19], v[18:19], v[74:75]
	v_pk_mul_f32 v[16:17], v[16:17], v[72:73]
	v_pk_fma_f32 v[18:19], v[14:15], v[70:71], v[18:19]
	v_pk_fma_f32 v[14:15], v[12:13], v[68:69], v[16:17]
	v_mad_i64_i32 v[16:17], s[2:3], v24, s16, v[84:85]
	v_lshl_add_u64 v[16:17], v[16:17], 0, s[62:63]
	v_cvt_pk_bf16_f32 v12, v22, v23
	v_cvt_pk_bf16_f32 v13, v20, v21
	v_cvt_pk_bf16_f32 v14, v14, v15
	v_cvt_pk_bf16_f32 v15, v18, v19
	v_lshl_add_u64 v[16:17], v[16:17], 0, v[86:87]
	v_pk_mul_f32 v[4:5], v[4:5], v[2:3] op_sel_hi:[1,0]
	v_pk_mul_f32 v[6:7], v[6:7], v[2:3] op_sel_hi:[1,0]
	global_store_dwordx4 v[16:17], v[12:15], off sc1
	v_pk_mul_f32 v[8:9], v[8:9], v[2:3] op_sel_hi:[1,0]
	v_pk_mul_f32 v[10:11], v[10:11], v[2:3] op_sel_hi:[1,0]
	v_pk_mul_f32 v[12:13], v[6:7], v[74:75]
	v_pk_mul_f32 v[14:15], v[4:5], v[72:73]
	v_pk_fma_f32 v[12:13], v[10:11], v[70:71], v[12:13] neg_lo:[0,0,1] neg_hi:[0,0,1]
	v_pk_fma_f32 v[14:15], v[8:9], v[68:69], v[14:15] neg_lo:[0,0,1] neg_hi:[0,0,1]
	v_pk_mul_f32 v[10:11], v[10:11], v[74:75]
	v_pk_mul_f32 v[8:9], v[8:9], v[72:73]
	s_mov_b32 s63, 0x25000
	v_pk_fma_f32 v[10:11], v[6:7], v[70:71], v[10:11]
	v_pk_fma_f32 v[6:7], v[4:5], v[68:69], v[8:9]
	v_cvt_pk_bf16_f32 v4, v14, v15
	v_cvt_pk_bf16_f32 v5, v12, v13
	s_nop 0
	v_cvt_pk_bf16_f32 v6, v6, v7
	v_cvt_pk_bf16_f32 v7, v10, v11
	global_store_dwordx4 v[16:17], v[4:7], off offset:256 sc1

.LBB0_991:
	s_lshl_b64 s[2:3], s[24:25], 11
	s_add_u32 s2, s1, s2
	s_addc_u32 s3, s4, s3
	s_lshl_b32 s0, s22, 7
	v_lshrrev_b32_e32 v2, 1, v49
	v_and_or_b32 v12, v2, 24, s0
	v_ashrrev_i32_e32 v13, 31, v12
	v_lshlrev_b64 v[50:51], 1, v[12:13]
	v_lshl_add_u64 v[28:29], s[2:3], 0, v[50:51]
	v_lshlrev_b32_e32 v2, 11, v49
	v_lshl_add_u64 v[50:51], s[36:37], 0, v[50:51]
	s_mov_b64 s[2:3], 0x5600000
	v_and_b32_e32 v2, 0x7800, v2
	v_lshl_add_u64 v[98:99], v[50:51], 0, s[2:3]
	v_and_b32_e32 v118, 63, v49
	v_lshl_add_u64 v[82:83], v[98:99], 0, v[2:3]
	s_mov_b32 s0, 0x10000
	v_lshl_add_u64 v[24:25], v[28:29], 0, v[2:3]
	v_or_b32_e32 v66, 0x8000, v2
	v_mov_b32_e32 v67, v3
	v_add_co_u32_e32 v94, vcc, s0, v82
	v_lshl_or_b32 v2, v118, 11, v241
	v_lshl_add_u64 v[40:41], v[28:29], 0, v[66:67]
	v_lshl_add_u64 v[78:79], v[98:99], 0, v[66:67]
	v_addc_co_u32_e32 v95, vcc, 0, v83, vcc
	v_lshl_add_u64 v[110:111], v[98:99], 0, v[2:3]
	global_load_dwordx4 v[12:15], v[24:25], off
	global_load_dwordx4 v[16:19], v[24:25], off offset:64
	global_load_dwordx4 v[20:23], v[24:25], off offset:128
	s_nop 0
	global_load_dwordx4 v[24:27], v[24:25], off offset:192
	s_nop 0
	global_load_dwordx4 v[28:31], v[40:41], off
	global_load_dwordx4 v[32:35], v[40:41], off offset:64
	global_load_dwordx4 v[36:39], v[40:41], off offset:128
	s_nop 0
	global_load_dwordx4 v[40:43], v[40:41], off offset:192
	s_nop 0
	global_load_dwordx4 v[50:53], v[82:83], off
	global_load_dwordx4 v[54:57], v[82:83], off offset:64
	global_load_dwordx4 v[58:61], v[82:83], off offset:128
	global_load_dwordx4 v[62:65], v[82:83], off offset:192
	global_load_dwordx4 v[66:69], v[78:79], off
	global_load_dwordx4 v[70:73], v[78:79], off offset:64
	global_load_dwordx4 v[74:77], v[78:79], off offset:128
	s_nop 0
	global_load_dwordx4 v[78:81], v[78:79], off offset:192
	s_nop 0
	global_load_dwordx4 v[82:85], v[94:95], off
	global_load_dwordx4 v[86:89], v[94:95], off offset:64
	global_load_dwordx4 v[90:93], v[94:95], off offset:128
	s_nop 0
	global_load_dwordx4 v[94:97], v[94:95], off offset:192
	s_nop 0
	global_load_dwordx4 v[98:101], v[110:111], off
	global_load_dwordx4 v[102:105], v[110:111], off offset:64
	global_load_dwordx4 v[106:109], v[110:111], off offset:128
	s_nop 0
	global_load_dwordx4 v[110:113], v[110:111], off offset:192
	s_waitcnt vmcnt(0)
	v_mfma_f32_16x16x32_bf16 v[114:117], v[12:15], v[50:53], 0
	s_lshl_b32 s0, s22, 13
	v_lshlrev_b32_e32 v2, 4, v118
	s_add_i32 s0, s0, 0
	v_mfma_f32_16x16x32_bf16 v[50:53], v[28:31], v[50:53], 0
	v_mfma_f32_16x16x32_bf16 v[114:117], v[16:19], v[54:57], v[114:117]
	v_mfma_f32_16x16x32_bf16 v[50:53], v[32:35], v[54:57], v[50:53]
	v_mfma_f32_16x16x32_bf16 v[114:117], v[20:23], v[58:61], v[114:117]
	v_mfma_f32_16x16x32_bf16 v[50:53], v[36:39], v[58:61], v[50:53]
	v_mfma_f32_16x16x32_bf16 v[114:117], v[24:27], v[62:65], v[114:117]
	v_mfma_f32_16x16x32_bf16 v[50:53], v[40:43], v[62:65], v[50:53]
	v_mfma_f32_16x16x32_bf16 v[54:57], v[12:15], v[66:69], 0
	v_mfma_f32_16x16x32_bf16 v[62:65], v[12:15], v[82:85], 0
	v_mfma_f32_16x16x32_bf16 v[12:15], v[12:15], v[98:101], 0
	v_mfma_f32_16x16x32_bf16 v[58:61], v[28:31], v[66:69], 0
	v_mfma_f32_16x16x32_bf16 v[66:69], v[28:31], v[82:85], 0
	v_mfma_f32_16x16x32_bf16 v[54:57], v[16:19], v[70:73], v[54:57]
	v_mfma_f32_16x16x32_bf16 v[62:65], v[16:19], v[86:89], v[62:65]
	v_mfma_f32_16x16x32_bf16 v[12:15], v[16:19], v[102:105], v[12:15]
	v_mfma_f32_16x16x32_bf16 v[16:19], v[28:31], v[98:101], 0
	v_mfma_f32_16x16x32_bf16 v[66:69], v[32:35], v[86:89], v[66:69]
	v_mfma_f32_16x16x32_bf16 v[58:61], v[32:35], v[70:73], v[58:61]
	v_mfma_f32_16x16x32_bf16 v[62:65], v[20:23], v[90:93], v[62:65]
	v_mfma_f32_16x16x32_bf16 v[16:19], v[32:35], v[102:105], v[16:19]
	v_mfma_f32_16x16x32_bf16 v[54:57], v[20:23], v[74:77], v[54:57]
	v_mfma_f32_16x16x32_bf16 v[66:69], v[36:39], v[90:93], v[66:69]
	v_mfma_f32_16x16x32_bf16 v[58:61], v[36:39], v[74:77], v[58:61]
	v_mfma_f32_16x16x32_bf16 v[12:15], v[20:23], v[106:109], v[12:15]
	v_add_u32_e32 v20, s0, v2
	ds_write_b128 v20, v[114:117]
	s_lshl_b32 s0, s22, 10
	v_mfma_f32_16x16x32_bf16 v[62:65], v[24:27], v[94:97], v[62:65]
	s_add_i32 s0, s0, 0
	v_add_u32_e32 v2, s0, v2
	s_cmp_lt_i32 s14, 3
	v_mfma_f32_16x16x32_bf16 v[16:19], v[36:39], v[106:109], v[16:19]
	v_mfma_f32_16x16x32_bf16 v[54:57], v[24:27], v[78:81], v[54:57]
	v_mfma_f32_16x16x32_bf16 v[66:69], v[40:43], v[94:97], v[66:69]
	v_mfma_f32_16x16x32_bf16 v[58:61], v[40:43], v[78:81], v[58:61]
	ds_write_b128 v20, v[50:53] offset:1024
	s_nop 4
	ds_write_b128 v20, v[54:57] offset:2048
	s_nop 0
	ds_write_b128 v20, v[58:61] offset:3072
	v_mfma_f32_16x16x32_bf16 v[12:15], v[24:27], v[110:113], v[12:15]
	ds_write_b128 v20, v[62:65] offset:4096
	ds_write_b128 v20, v[66:69] offset:5120
	s_nop 5
	ds_write_b128 v20, v[12:15] offset:6144
	v_mfma_f32_16x16x32_bf16 v[12:15], v[40:43], v[110:113], v[16:19]
	s_nop 7
	ds_write_b128 v20, v[12:15] offset:7168
	s_waitcnt lgkmcnt(0)
	s_barrier
	ds_read_b128 v[36:39], v2
	ds_read_b128 v[40:43], v2 offset:8192
	ds_read_b128 v[32:35], v2 offset:16384
	ds_read_b128 v[28:31], v2 offset:24576
	ds_read_b128 v[24:27], v2 offset:32768
	ds_read_b128 v[20:23], v2 offset:40960
	ds_read_b128 v[16:19], v2 offset:49152
	ds_read_b128 v[12:15], v2 offset:57344
	s_waitcnt lgkmcnt(6)
	v_pk_add_f32 v[38:39], v[38:39], v[42:43]
	v_pk_add_f32 v[36:37], v[36:37], v[40:41]
	s_waitcnt lgkmcnt(5)
	v_pk_add_f32 v[34:35], v[38:39], v[34:35]
	v_pk_add_f32 v[32:33], v[36:37], v[32:33]
	s_waitcnt lgkmcnt(4)
	v_pk_add_f32 v[30:31], v[34:35], v[30:31]
	v_pk_add_f32 v[28:29], v[32:33], v[28:29]
	v_fmamk_f32 v2, v47, 0x3a800000, v1
	s_waitcnt lgkmcnt(3)
	v_pk_add_f32 v[26:27], v[30:31], v[26:27]
	v_pk_add_f32 v[24:25], v[28:29], v[24:25]
	v_rsq_f32_e32 v2, v2
	s_waitcnt lgkmcnt(2)
	v_pk_add_f32 v[22:23], v[26:27], v[22:23]
	v_pk_add_f32 v[20:21], v[24:25], v[20:21]
	s_waitcnt lgkmcnt(1)
	v_pk_add_f32 v[18:19], v[22:23], v[18:19]
	v_pk_add_f32 v[16:17], v[20:21], v[16:17]
	s_waitcnt lgkmcnt(0)
	v_pk_add_f32 v[14:15], v[18:19], v[14:15]
	v_pk_add_f32 v[12:13], v[16:17], v[12:13]
	v_pk_mul_f32 v[18:19], v[2:3], v[14:15] op_sel_hi:[0,1]
	v_pk_mul_f32 v[16:17], v[2:3], v[12:13] op_sel_hi:[0,1]
	v_add_u32_e32 v2, 0xffffc000, v44
	s_barrier
	s_cbranch_scc1 .LBB0_999
	s_cmp_gt_i32 s14, 3
	s_cbranch_scc0 .LBB0_1000
	s_cmp_gt_i32 s14, 4
	s_mov_b64 s[34:35], -1
	s_cbranch_scc0 .LBB0_997
	s_cmp_eq_u32 s14, 5
	s_cbranch_scc0 .LBB0_996
	v_lshl_or_b32 v12, v2, 7, v240
	v_ashrrev_i32_e32 v13, 31, v12
	v_lshlrev_b64 v[12:13], 9, v[12:13]
	v_lshl_add_u64 v[12:13], s[64:65], 0, v[12:13]
	v_mov_b32_e32 v47, v3
	v_lshl_add_u64 v[12:13], v[46:47], 2, v[12:13]
	v_add_co_u32_e32 v12, vcc, 0x54cc000, v12
	s_nop 1
	v_addc_co_u32_e32 v13, vcc, 0, v13, vcc
	global_store_dwordx4 v[12:13], v[16:19], off offset:3584 sc1

.LBB0_1006:
	s_and_b64 vcc, exec, s[34:35]
	s_cbranch_vccz .LBB0_1011
	v_cmp_lt_i32_e32 vcc, v234, v235
	v_bfe_u32 v20, v49, 4, 1
	s_cmp_lg_u32 s14, 1
	v_cndmask_b32_e32 v12, v231, v234, vcc
	v_lshlrev_b32_e32 v15, 2, v12
	ds_bpermute_b32 v12, v15, v16
	ds_bpermute_b32 v13, v15, v17
	ds_bpermute_b32 v14, v15, v18
	ds_bpermute_b32 v15, v15, v19
	v_cmp_eq_u32_e32 vcc, 0, v20
	s_mov_b64 s[34:35], -1
	s_waitcnt lgkmcnt(2)
	v_pk_mul_f32 v[8:9], v[8:9], v[12:13]
	s_waitcnt lgkmcnt(0)
	v_pk_mul_f32 v[10:11], v[10:11], v[14:15]
	s_nop 0
	v_xor_b32_e32 v12, 0x80000000, v10
	v_xor_b32_e32 v13, 0x80000000, v11
	v_xor_b32_e32 v14, 0x80000000, v8
	v_xor_b32_e32 v15, 0x80000000, v9
	v_cndmask_b32_e32 v9, v9, v15, vcc
	v_cndmask_b32_e32 v8, v8, v14, vcc
	v_cndmask_b32_e32 v11, v11, v13, vcc
	v_cndmask_b32_e32 v10, v10, v12, vcc
	v_pk_fma_f32 v[14:15], v[6:7], v[18:19], v[10:11]
	v_pk_fma_f32 v[12:13], v[4:5], v[16:17], v[8:9]
	s_cbranch_scc0 .LBB0_1009
	v_lshl_or_b32 v4, v2, 7, v240
	s_add_i32 s0, s24, 0xfffff400
	v_ashrrev_i32_e32 v5, 31, v4
	s_ashr_i32 s2, s0, 6
	s_ashr_i32 s3, s2, 31
	v_lshlrev_b64 v[4:5], 9, v[4:5]
	v_lshl_add_u64 v[4:5], s[64:65], 0, v[4:5]
	s_lshl_b64 s[2:3], s[2:3], 8
	v_lshl_add_u64 v[4:5], v[4:5], 0, s[2:3]
	v_lshlrev_b32_e32 v2, 7, v20
	v_lshl_add_u64 v[4:5], v[4:5], 0, v[2:3]
	v_lshlrev_b32_e32 v2, 1, v46
	v_and_b32_e32 v2, 0x70, v2
	v_lshl_add_u64 v[4:5], v[4:5], 0, v[2:3]
	v_add_co_u32_e32 v4, vcc, 0x4cd0000, v4
	s_mov_b64 s[34:35], 0
	s_nop 0
	v_addc_co_u32_e32 v5, vcc, 0, v5, vcc
	global_store_dwordx4 v[4:5], v[12:15], off sc1

.LBB0_1034:
	s_lshl_b32 s0, s23, 11
	s_add_u32 s2, s28, s0
	s_addc_u32 s3, s29, 0
	s_ashr_i32 s35, s34, 31
	s_lshl_b64 s[28:29], s[34:35], 11
	s_add_u32 s28, s1, s28
	s_addc_u32 s29, s4, s29
	s_lshl_b32 s0, s22, 7
	v_lshrrev_b32_e32 v2, 1, v48
	v_and_or_b32 v12, v2, 24, s0
	v_ashrrev_i32_e32 v13, 31, v12
	v_lshlrev_b64 v[50:51], 1, v[12:13]
	v_lshlrev_b32_e32 v2, 11, v48
	v_and_b32_e32 v2, 0x7800, v2
	v_lshl_add_u64 v[98:99], s[2:3], 0, v[50:51]
	v_and_b32_e32 v49, 63, v48
	v_lshl_add_u64 v[28:29], s[28:29], 0, v[50:51]
	v_lshl_add_u64 v[82:83], v[98:99], 0, v[2:3]
	s_mov_b32 s0, 0x10000
	v_lshl_add_u64 v[24:25], v[28:29], 0, v[2:3]
	v_or_b32_e32 v66, 0x8000, v2
	v_mov_b32_e32 v67, v3
	v_add_co_u32_e32 v94, vcc, s0, v82
	v_lshl_or_b32 v2, v49, 11, v241
	v_lshl_add_u64 v[40:41], v[28:29], 0, v[66:67]
	v_lshl_add_u64 v[78:79], v[98:99], 0, v[66:67]
	v_addc_co_u32_e32 v95, vcc, 0, v83, vcc
	v_lshl_add_u64 v[110:111], v[98:99], 0, v[2:3]
	global_load_dwordx4 v[12:15], v[24:25], off
	global_load_dwordx4 v[16:19], v[24:25], off offset:64
	global_load_dwordx4 v[20:23], v[24:25], off offset:128
	s_nop 0
	global_load_dwordx4 v[24:27], v[24:25], off offset:192
	s_nop 0
	global_load_dwordx4 v[28:31], v[40:41], off
	global_load_dwordx4 v[32:35], v[40:41], off offset:64
	global_load_dwordx4 v[36:39], v[40:41], off offset:128
	s_nop 0
	global_load_dwordx4 v[40:43], v[40:41], off offset:192
	s_nop 0
	global_load_dwordx4 v[50:53], v[82:83], off
	global_load_dwordx4 v[54:57], v[82:83], off offset:64
	global_load_dwordx4 v[58:61], v[82:83], off offset:128
	global_load_dwordx4 v[62:65], v[82:83], off offset:192
	global_load_dwordx4 v[66:69], v[78:79], off
	global_load_dwordx4 v[70:73], v[78:79], off offset:64
	global_load_dwordx4 v[74:77], v[78:79], off offset:128
	s_nop 0
	global_load_dwordx4 v[78:81], v[78:79], off offset:192
	s_nop 0
	global_load_dwordx4 v[82:85], v[94:95], off
	global_load_dwordx4 v[86:89], v[94:95], off offset:64
	global_load_dwordx4 v[90:93], v[94:95], off offset:128
	s_nop 0
	global_load_dwordx4 v[94:97], v[94:95], off offset:192
	s_nop 0
	global_load_dwordx4 v[98:101], v[110:111], off
	global_load_dwordx4 v[102:105], v[110:111], off offset:64
	global_load_dwordx4 v[106:109], v[110:111], off offset:128
	s_nop 0
	global_load_dwordx4 v[110:113], v[110:111], off offset:192
	s_waitcnt vmcnt(0)
	v_mfma_f32_16x16x32_bf16 v[114:117], v[12:15], v[50:53], 0
	s_lshl_b32 s0, s22, 13
	v_lshlrev_b32_e32 v2, 4, v49
	s_add_i32 s0, s0, 0
	v_mfma_f32_16x16x32_bf16 v[50:53], v[28:31], v[50:53], 0
	v_mfma_f32_16x16x32_bf16 v[114:117], v[16:19], v[54:57], v[114:117]
	v_mfma_f32_16x16x32_bf16 v[50:53], v[32:35], v[54:57], v[50:53]
	v_mfma_f32_16x16x32_bf16 v[114:117], v[20:23], v[58:61], v[114:117]
	v_mfma_f32_16x16x32_bf16 v[50:53], v[36:39], v[58:61], v[50:53]
	v_mfma_f32_16x16x32_bf16 v[114:117], v[24:27], v[62:65], v[114:117]
	v_mfma_f32_16x16x32_bf16 v[50:53], v[40:43], v[62:65], v[50:53]
	v_mfma_f32_16x16x32_bf16 v[54:57], v[12:15], v[66:69], 0
	v_mfma_f32_16x16x32_bf16 v[62:65], v[12:15], v[82:85], 0
	v_mfma_f32_16x16x32_bf16 v[12:15], v[12:15], v[98:101], 0
	v_mfma_f32_16x16x32_bf16 v[58:61], v[28:31], v[66:69], 0
	v_mfma_f32_16x16x32_bf16 v[66:69], v[28:31], v[82:85], 0
	v_mfma_f32_16x16x32_bf16 v[54:57], v[16:19], v[70:73], v[54:57]
	v_mfma_f32_16x16x32_bf16 v[62:65], v[16:19], v[86:89], v[62:65]
	v_mfma_f32_16x16x32_bf16 v[12:15], v[16:19], v[102:105], v[12:15]
	v_mfma_f32_16x16x32_bf16 v[16:19], v[28:31], v[98:101], 0
	v_mfma_f32_16x16x32_bf16 v[66:69], v[32:35], v[86:89], v[66:69]
	v_mfma_f32_16x16x32_bf16 v[58:61], v[32:35], v[70:73], v[58:61]
	v_mfma_f32_16x16x32_bf16 v[62:65], v[20:23], v[90:93], v[62:65]
	v_mfma_f32_16x16x32_bf16 v[16:19], v[32:35], v[102:105], v[16:19]
	v_mfma_f32_16x16x32_bf16 v[54:57], v[20:23], v[74:77], v[54:57]
	v_mfma_f32_16x16x32_bf16 v[66:69], v[36:39], v[90:93], v[66:69]
	v_mfma_f32_16x16x32_bf16 v[58:61], v[36:39], v[74:77], v[58:61]
	v_mfma_f32_16x16x32_bf16 v[12:15], v[20:23], v[106:109], v[12:15]
	v_add_u32_e32 v20, s0, v2
	ds_write_b128 v20, v[114:117]
	s_lshl_b32 s0, s22, 10
	v_mfma_f32_16x16x32_bf16 v[62:65], v[24:27], v[94:97], v[62:65]
	s_add_i32 s0, s0, 0
	v_add_u32_e32 v2, s0, v2
	s_cmp_lt_i32 s46, 3
	v_mfma_f32_16x16x32_bf16 v[16:19], v[36:39], v[106:109], v[16:19]
	v_mfma_f32_16x16x32_bf16 v[54:57], v[24:27], v[78:81], v[54:57]
	v_mfma_f32_16x16x32_bf16 v[66:69], v[40:43], v[94:97], v[66:69]
	v_mfma_f32_16x16x32_bf16 v[58:61], v[40:43], v[78:81], v[58:61]
	ds_write_b128 v20, v[50:53] offset:1024
	s_nop 4
	ds_write_b128 v20, v[54:57] offset:2048
	s_nop 0
	ds_write_b128 v20, v[58:61] offset:3072
	v_mfma_f32_16x16x32_bf16 v[12:15], v[24:27], v[110:113], v[12:15]
	ds_write_b128 v20, v[62:65] offset:4096
	ds_write_b128 v20, v[66:69] offset:5120
	s_nop 5
	ds_write_b128 v20, v[12:15] offset:6144
	v_mfma_f32_16x16x32_bf16 v[12:15], v[40:43], v[110:113], v[16:19]
	s_nop 7
	ds_write_b128 v20, v[12:15] offset:7168
	s_waitcnt lgkmcnt(0)
	s_barrier
	ds_read_b128 v[36:39], v2
	ds_read_b128 v[40:43], v2 offset:8192
	ds_read_b128 v[32:35], v2 offset:16384
	ds_read_b128 v[28:31], v2 offset:24576
	ds_read_b128 v[24:27], v2 offset:32768
	ds_read_b128 v[20:23], v2 offset:40960
	ds_read_b128 v[16:19], v2 offset:49152
	ds_read_b128 v[12:15], v2 offset:57344
	s_waitcnt lgkmcnt(6)
	v_pk_add_f32 v[38:39], v[38:39], v[42:43]
	v_pk_add_f32 v[36:37], v[36:37], v[40:41]
	s_waitcnt lgkmcnt(5)
	v_pk_add_f32 v[34:35], v[38:39], v[34:35]
	v_pk_add_f32 v[32:33], v[36:37], v[32:33]
	s_waitcnt lgkmcnt(4)
	v_pk_add_f32 v[30:31], v[34:35], v[30:31]
	v_pk_add_f32 v[28:29], v[32:33], v[28:29]
	v_fmamk_f32 v2, v47, 0x3a800000, v1
	s_waitcnt lgkmcnt(3)
	v_pk_add_f32 v[26:27], v[30:31], v[26:27]
	v_pk_add_f32 v[24:25], v[28:29], v[24:25]
	v_rsq_f32_e32 v2, v2
	s_waitcnt lgkmcnt(2)
	v_pk_add_f32 v[22:23], v[26:27], v[22:23]
	v_pk_add_f32 v[20:21], v[24:25], v[20:21]
	s_waitcnt lgkmcnt(1)
	v_pk_add_f32 v[18:19], v[22:23], v[18:19]
	v_pk_add_f32 v[16:17], v[20:21], v[16:17]
	s_waitcnt lgkmcnt(0)
	v_pk_add_f32 v[14:15], v[18:19], v[14:15]
	v_pk_add_f32 v[12:13], v[16:17], v[12:13]
	v_pk_mul_f32 v[18:19], v[2:3], v[14:15] op_sel_hi:[0,1]
	v_pk_mul_f32 v[16:17], v[2:3], v[12:13] op_sel_hi:[0,1]
	v_add_u32_e32 v2, 0xffffc000, v44
	s_barrier
	s_cbranch_scc1 .LBB0_1042
	s_cmp_gt_i32 s46, 3
	s_cbranch_scc0 .LBB0_1043
	s_cmp_gt_i32 s46, 4
	s_mov_b64 s[30:31], -1
	s_cbranch_scc0 .LBB0_1040
	s_cmp_eq_u32 s46, 5
	s_cbranch_scc0 .LBB0_1039
	v_lshl_or_b32 v12, v2, 7, v240
	v_ashrrev_i32_e32 v13, 31, v12
	v_lshlrev_b64 v[12:13], 9, v[12:13]
	v_lshl_add_u64 v[12:13], s[64:65], 0, v[12:13]
	v_ashrrev_i32_e32 v47, 31, v46
	v_lshl_add_u64 v[12:13], v[46:47], 2, v[12:13]
	v_add_co_u32_e32 v12, vcc, 0x54cc000, v12
	s_nop 1
	v_addc_co_u32_e32 v13, vcc, 0, v13, vcc
	global_store_dwordx4 v[12:13], v[16:19], off offset:3584 sc1

.LBB0_1049:
	s_and_b64 vcc, exec, s[30:31]
	s_cbranch_vccz .LBB0_1054
	v_cmp_lt_i32_e32 vcc, v234, v235
	v_bfe_u32 v20, v48, 4, 1
	s_cmp_lg_u32 s46, 1
	v_cndmask_b32_e32 v12, v231, v234, vcc
	v_lshlrev_b32_e32 v15, 2, v12
	ds_bpermute_b32 v12, v15, v16
	ds_bpermute_b32 v13, v15, v17
	ds_bpermute_b32 v14, v15, v18
	ds_bpermute_b32 v15, v15, v19
	v_cmp_eq_u32_e32 vcc, 0, v20
	s_mov_b64 s[30:31], -1
	s_waitcnt lgkmcnt(2)
	v_pk_mul_f32 v[8:9], v[8:9], v[12:13]
	s_waitcnt lgkmcnt(0)
	v_pk_mul_f32 v[10:11], v[10:11], v[14:15]
	s_nop 0
	v_xor_b32_e32 v12, 0x80000000, v10
	v_xor_b32_e32 v13, 0x80000000, v11
	v_xor_b32_e32 v14, 0x80000000, v8
	v_xor_b32_e32 v15, 0x80000000, v9
	v_cndmask_b32_e32 v9, v9, v15, vcc
	v_cndmask_b32_e32 v8, v8, v14, vcc
	v_cndmask_b32_e32 v11, v11, v13, vcc
	v_cndmask_b32_e32 v10, v10, v12, vcc
	v_pk_fma_f32 v[14:15], v[6:7], v[18:19], v[10:11]
	v_pk_fma_f32 v[12:13], v[4:5], v[16:17], v[8:9]
	s_cbranch_scc0 .LBB0_1052
	v_lshl_or_b32 v4, v2, 7, v240
	s_addk_i32 s9, 0xf400
	v_ashrrev_i32_e32 v5, 31, v4
	s_ashr_i32 s2, s9, 6
	s_ashr_i32 s3, s2, 31
	v_lshlrev_b64 v[4:5], 9, v[4:5]
	v_lshl_add_u64 v[4:5], s[64:65], 0, v[4:5]
	s_lshl_b64 s[2:3], s[2:3], 8
	v_lshl_add_u64 v[4:5], v[4:5], 0, s[2:3]
	v_lshlrev_b32_e32 v2, 7, v20
	v_lshl_add_u64 v[4:5], v[4:5], 0, v[2:3]
	v_lshlrev_b32_e32 v2, 1, v46
	v_and_b32_e32 v2, 0x70, v2
	v_lshl_add_u64 v[4:5], v[4:5], 0, v[2:3]
	v_add_co_u32_e32 v4, vcc, 0x4cd0000, v4
	s_mov_b64 s[30:31], 0
	s_nop 0
	v_addc_co_u32_e32 v5, vcc, 0, v5, vcc
	global_store_dwordx4 v[4:5], v[12:15], off sc1

.LBB0_1079:
	s_mul_i32 s35, s35, s45
	v_add_u32_e32 v107, 4, v74
	s_sub_i32 s36, s44, s35
	ds_read2st64_b32 v[38:39], v74 offset1:1
	ds_read2st64_b32 v[112:113], v107 offset0:4 offset1:5
	v_lshl_add_u32 v134, s36, 8, v72
	s_movk_i32 s38, 0xffc0
	v_cmp_gt_i32_e32 vcc, s28, v134
	v_and_or_b32 v37, v134, s38, v73
	v_add_u32_e32 v128, 8, v74
	v_cndmask_b32_e32 v37, v134, v37, vcc
	v_add_u32_e32 v129, 12, v74
	v_add_u32_e32 v130, 16, v74
	v_add_u32_e32 v131, 20, v74
	v_add_u32_e32 v132, 24, v74
	v_add_u32_e32 v133, 28, v74
	v_add_u32_e32 v37, s29, v37
	s_waitcnt lgkmcnt(0)
	v_cvt_pk_bf16_f32 v108, v38, v112
	ds_read2st64_b32 v[114:115], v128 offset0:8 offset1:9
	ds_read2st64_b32 v[116:117], v129 offset0:12 offset1:13
	ds_read2st64_b32 v[118:119], v130 offset0:16 offset1:17
	ds_read2st64_b32 v[120:121], v131 offset0:20 offset1:21
	ds_read2st64_b32 v[122:123], v132 offset0:24 offset1:25
	ds_read2st64_b32 v[124:125], v133 offset0:28 offset1:29
	v_ashrrev_i32_e32 v38, 31, v37
	v_mul_lo_u32 v38, s30, v38
	v_mul_lo_u32 v112, s31, v37
	v_mad_u64_u32 v[126:127], s[36:37], s30, v37, 0
	s_ashr_i32 s35, s34, 31
	v_add3_u32 v127, v127, v38, v112
	v_lshl_add_u64 v[126:127], v[126:127], 1, s[22:23]
	s_lshl_b64 s[34:35], s[34:35], 1
	v_lshl_add_u64 v[126:127], v[126:127], 0, s[34:35]
	v_mov_b32_e32 v37, v3
	s_waitcnt lgkmcnt(4)
	v_cvt_pk_bf16_f32 v109, v114, v116
	s_waitcnt lgkmcnt(2)
	v_cvt_pk_bf16_f32 v110, v118, v120
	s_waitcnt lgkmcnt(0)
	v_cvt_pk_bf16_f32 v111, v122, v124
	v_lshl_add_u64 v[126:127], v[126:127], 0, v[36:37]
	v_add_u32_e32 v38, 64, v134
	global_store_dwordx4 v[126:127], v[108:111], off sc1
	v_cmp_gt_i32_e32 vcc, s28, v38
	s_add_i32 s75, s75, s14
	v_cvt_pk_bf16_f32 v108, v39, v113
	v_and_or_b32 v39, v38, s38, v73
	v_cndmask_b32_e32 v38, v38, v39, vcc
	v_add_u32_e32 v38, s29, v38
	v_ashrrev_i32_e32 v39, 31, v38
	v_mul_lo_u32 v112, s30, v39
	v_mul_lo_u32 v113, s31, v38
	v_mad_u64_u32 v[38:39], s[36:37], s30, v38, 0
	v_add3_u32 v39, v39, v112, v113
	v_lshl_add_u64 v[38:39], v[38:39], 1, s[22:23]
	v_lshl_add_u64 v[38:39], v[38:39], 0, s[34:35]
	v_cvt_pk_bf16_f32 v109, v115, v117
	v_cvt_pk_bf16_f32 v110, v119, v121
	v_cvt_pk_bf16_f32 v111, v123, v125
	v_lshl_add_u64 v[38:39], v[38:39], 0, v[36:37]
	global_store_dwordx4 v[38:39], v[108:111], off sc1
	ds_read2st64_b32 v[38:39], v74 offset0:2 offset1:3
	ds_read2st64_b32 v[112:113], v107 offset0:6 offset1:7
	ds_read2st64_b32 v[114:115], v128 offset0:10 offset1:11
	ds_read2st64_b32 v[116:117], v129 offset0:14 offset1:15
	ds_read2st64_b32 v[118:119], v130 offset0:18 offset1:19
	ds_read2st64_b32 v[120:121], v131 offset0:22 offset1:23
	ds_read2st64_b32 v[122:123], v132 offset0:26 offset1:27
	ds_read2st64_b32 v[124:125], v133 offset0:30 offset1:31
	s_add_i32 s4, s4, s9
	s_waitcnt lgkmcnt(6)
	v_cvt_pk_bf16_f32 v108, v38, v112
	v_add_u32_e32 v38, 0x80, v134
	v_cmp_gt_i32_e32 vcc, s28, v38
	v_and_or_b32 v107, v38, s38, v73
	s_waitcnt lgkmcnt(4)
	v_cvt_pk_bf16_f32 v109, v114, v116
	v_cndmask_b32_e32 v38, v38, v107, vcc
	v_add_u32_e32 v38, s29, v38
	v_ashrrev_i32_e32 v107, 31, v38
	v_mul_lo_u32 v107, s30, v107
	v_mul_lo_u32 v112, s31, v38
	v_mad_u64_u32 v[126:127], s[36:37], s30, v38, 0
	v_add3_u32 v127, v127, v107, v112
	v_lshl_add_u64 v[126:127], v[126:127], 1, s[22:23]
	v_lshl_add_u64 v[126:127], v[126:127], 0, s[34:35]
	s_waitcnt lgkmcnt(2)
	v_cvt_pk_bf16_f32 v110, v118, v120
	s_waitcnt lgkmcnt(0)
	v_cvt_pk_bf16_f32 v111, v122, v124
	v_lshl_add_u64 v[126:127], v[126:127], 0, v[36:37]
	v_add_u32_e32 v38, 0xc0, v134
	global_store_dwordx4 v[126:127], v[108:111], off sc1
	v_cmp_gt_i32_e32 vcc, s28, v38
	s_add_i32 s24, s24, s9
	v_cvt_pk_bf16_f32 v108, v39, v113
	v_and_or_b32 v39, v38, s38, v73
	v_cndmask_b32_e32 v38, v38, v39, vcc
	v_add_u32_e32 v38, s29, v38
	v_ashrrev_i32_e32 v39, 31, v38
	v_mul_lo_u32 v107, s30, v39
	v_mul_lo_u32 v112, s31, v38
	v_mad_u64_u32 v[38:39], s[28:29], s30, v38, 0
	v_add3_u32 v39, v39, v107, v112
	v_lshl_add_u64 v[38:39], v[38:39], 1, s[22:23]
	v_lshl_add_u64 v[38:39], v[38:39], 0, s[34:35]
	v_cvt_pk_bf16_f32 v109, v115, v117
	v_cvt_pk_bf16_f32 v110, v119, v121
	v_cvt_pk_bf16_f32 v111, v123, v125
	v_lshl_add_u64 v[38:39], v[38:39], 0, v[36:37]
	s_cmpk_gt_i32 s0, 0x17f
	global_store_dwordx4 v[38:39], v[108:111], off sc1
	s_barrier
	s_cbranch_scc1 .LBB0_1177

.LBB0_1244:
	s_add_i32 s26, s26, s71
	v_add_u32_e32 v37, 4, v71
	ds_read2st64_b32 v[108:109], v71 offset1:1
	ds_read2st64_b32 v[110:111], v37 offset0:4 offset1:5
	s_mul_i32 s30, s30, s29
	s_sub_i32 s4, s21, s30
	v_add_u32_e32 v105, 8, v71
	v_add_u32_e32 v106, 12, v71
	ds_read2st64_b32 v[112:113], v105 offset0:8 offset1:9
	ds_read2st64_b32 v[114:115], v106 offset0:12 offset1:13
	ds_read2st64_b32 v[116:117], v71 offset0:2 offset1:3
	ds_read2st64_b32 v[118:119], v37 offset0:6 offset1:7
	s_waitcnt lgkmcnt(4)
	v_cvt_pk_bf16_f32 v104, v108, v110
	ds_read2st64_b32 v[120:121], v105 offset0:10 offset1:11
	ds_read2st64_b32 v[122:123], v106 offset0:14 offset1:15
	v_add_u32_e32 v37, 16, v71
	v_add_u32_e32 v106, 20, v71
	v_add_u32_e32 v107, 24, v71
	v_add_u32_e32 v108, 28, v71
	v_lshl_add_u32 v110, s4, 8, v69
	ds_read2st64_b32 v[124:125], v37 offset0:16 offset1:17
	ds_read2st64_b32 v[126:127], v106 offset0:20 offset1:21
	ds_read2st64_b32 v[128:129], v107 offset0:24 offset1:25
	ds_read2st64_b32 v[130:131], v108 offset0:28 offset1:29
	ds_read2st64_b32 v[132:133], v37 offset0:18 offset1:19
	ds_read2st64_b32 v[134:135], v106 offset0:22 offset1:23
	v_and_or_b32 v37, v110, s3, v70
	v_cmp_gt_i32_e32 vcc, s27, v110
	ds_read2st64_b32 v[136:137], v107 offset0:26 offset1:27
	ds_read2st64_b32 v[138:139], v108 offset0:30 offset1:31
	v_cndmask_b32_e32 v37, v110, v37, vcc
	v_add_u32_e32 v37, s28, v37
	v_ashrrev_i32_e32 v108, 31, v37
	s_waitcnt lgkmcnt(12)
	v_cvt_pk_bf16_f32 v105, v112, v114
	v_mul_lo_u32 v108, s16, v108
	v_mul_lo_u32 v112, s17, v37
	v_mad_u64_u32 v[140:141], s[4:5], s16, v37, 0
	s_ashr_i32 s21, s20, 31
	v_add3_u32 v141, v141, v108, v112
	v_lshl_add_u64 v[140:141], v[140:141], 1, s[18:19]
	s_lshl_b64 s[4:5], s[20:21], 1
	v_lshl_add_u64 v[140:141], v[140:141], 0, s[4:5]
	v_mov_b32_e32 v37, v35
	s_waitcnt lgkmcnt(6)
	v_cvt_pk_bf16_f32 v106, v124, v126
	s_waitcnt lgkmcnt(4)
	v_cvt_pk_bf16_f32 v107, v128, v130
	v_lshl_add_u64 v[140:141], v[140:141], 0, v[36:37]
	v_add_u32_e32 v108, 64, v110
	global_store_dwordx4 v[140:141], v[104:107], off sc1
	v_cmp_gt_i32_e32 vcc, s27, v108
	s_add_i32 s2, s2, s71
	v_cvt_pk_bf16_f32 v104, v109, v111
	v_and_or_b32 v109, v108, s3, v70
	v_cndmask_b32_e32 v108, v108, v109, vcc
	v_add_u32_e32 v108, s28, v108
	v_ashrrev_i32_e32 v109, 31, v108
	v_mul_lo_u32 v111, s16, v109
	v_mul_lo_u32 v112, s17, v108
	v_mad_u64_u32 v[108:109], s[20:21], s16, v108, 0
	v_add3_u32 v109, v109, v111, v112
	v_lshl_add_u64 v[108:109], v[108:109], 1, s[18:19]
	v_lshl_add_u64 v[108:109], v[108:109], 0, s[4:5]
	v_cvt_pk_bf16_f32 v105, v113, v115
	v_cvt_pk_bf16_f32 v106, v125, v127
	v_cvt_pk_bf16_f32 v107, v129, v131
	v_lshl_add_u64 v[108:109], v[108:109], 0, v[36:37]
	global_store_dwordx4 v[108:109], v[104:107], off sc1
	v_add_u32_e32 v108, 0x80, v110
	v_and_or_b32 v109, v108, s3, v70
	v_cmp_gt_i32_e32 vcc, s27, v108
	v_cvt_pk_bf16_f32 v104, v116, v118
	v_cvt_pk_bf16_f32 v105, v120, v122
	v_cndmask_b32_e32 v108, v108, v109, vcc
	v_add_u32_e32 v108, s28, v108
	v_ashrrev_i32_e32 v109, 31, v108
	v_mul_lo_u32 v111, s16, v109
	v_mul_lo_u32 v112, s17, v108
	v_mad_u64_u32 v[108:109], s[20:21], s16, v108, 0
	v_add3_u32 v109, v109, v111, v112
	v_lshl_add_u64 v[108:109], v[108:109], 1, s[18:19]
	v_lshl_add_u64 v[108:109], v[108:109], 0, s[4:5]
	s_waitcnt lgkmcnt(2)
	v_cvt_pk_bf16_f32 v106, v132, v134
	s_waitcnt lgkmcnt(0)
	v_cvt_pk_bf16_f32 v107, v136, v138
	v_lshl_add_u64 v[108:109], v[108:109], 0, v[36:37]
	global_store_dwordx4 v[108:109], v[104:107], off sc1
	v_add_u32_e32 v108, 0xc0, v110
	v_and_or_b32 v109, v108, s3, v70
	v_cmp_gt_i32_e32 vcc, s27, v108
	v_cvt_pk_bf16_f32 v104, v117, v119
	v_cvt_pk_bf16_f32 v105, v121, v123
	v_cndmask_b32_e32 v108, v108, v109, vcc
	v_add_u32_e32 v108, s28, v108
	v_ashrrev_i32_e32 v109, 31, v108
	v_mul_lo_u32 v110, s16, v109
	v_mul_lo_u32 v111, s17, v108
	v_mad_u64_u32 v[108:109], s[16:17], s16, v108, 0
	v_add3_u32 v109, v109, v110, v111
	v_lshl_add_u64 v[108:109], v[108:109], 1, s[18:19]
	v_lshl_add_u64 v[108:109], v[108:109], 0, s[4:5]
	v_cvt_pk_bf16_f32 v106, v133, v135
	v_cvt_pk_bf16_f32 v107, v137, v139
	v_lshl_add_u64 v[108:109], v[108:109], 0, v[36:37]
	s_cmpk_lt_i32 s26, 0x310
	global_store_dwordx4 v[108:109], v[104:107], off sc1
	s_barrier
	s_cbranch_scc0 .LBB0_1342

.LBB0_1438:
	s_cmp_eq_u64 s[48:49], 0
	v_lshlrev_b32_e32 v86, 3, v82
	s_cbranch_scc1 .LBB0_1442
	v_mul_f32_e32 v87, v7, v7
	v_mul_f32_e32 v88, v9, v9
	v_fmac_f32_e32 v87, v6, v6
	v_fmac_f32_e32 v88, v8, v8
	v_add_f32_e32 v87, v87, v88
	v_mul_f32_e32 v88, v3, v3
	v_mul_f32_e32 v89, v5, v5
	v_fmac_f32_e32 v88, v2, v2
	v_fmac_f32_e32 v89, v4, v4
	v_add_f32_e32 v88, v88, v89
	v_add_f32_e32 v87, v87, v88
	v_mul_f32_e32 v88, v15, v15
	v_mul_f32_e32 v89, v17, v17
	v_fmac_f32_e32 v88, v14, v14
	v_fmac_f32_e32 v89, v16, v16
	v_add_f32_e32 v88, v88, v89
	v_add_f32_e32 v87, v87, v88
	v_mul_f32_e32 v88, v11, v11
	v_mul_f32_e32 v89, v13, v13
	v_fmac_f32_e32 v88, v10, v10
	v_fmac_f32_e32 v89, v12, v12
	v_add_f32_e32 v88, v88, v89
	v_add_f32_e32 v87, v87, v88
	v_and_b32_e32 v88, 64, v83
	v_add_u32_e32 v88, 64, v88
	v_xor_b32_e32 v89, 1, v83
	v_cmp_lt_i32_e32 vcc, v89, v88
	v_cvt_pk_bf16_f32 v2, v2, v3
	v_cvt_pk_bf16_f32 v3, v4, v5
	v_cndmask_b32_e32 v89, v83, v89, vcc
	v_lshlrev_b32_e32 v89, 2, v89
	ds_bpermute_b32 v89, v89, v87
	global_store_dwordx2 v86, v[2:3], s[48:49] offset:512 sc1
	v_cvt_pk_bf16_f32 v2, v14, v15
	v_cvt_pk_bf16_f32 v3, v16, v17
	v_cvt_pk_bf16_f32 v6, v6, v7
	s_waitcnt lgkmcnt(0)
	v_add_f32_e32 v87, v87, v89
	v_xor_b32_e32 v89, 2, v83
	v_cmp_lt_i32_e32 vcc, v89, v88
	v_cvt_pk_bf16_f32 v7, v8, v9
	global_store_dwordx2 v86, v[2:3], s[48:49] offset:1024 sc1
	v_cndmask_b32_e32 v89, v83, v89, vcc
	v_lshlrev_b32_e32 v89, 2, v89
	ds_bpermute_b32 v89, v89, v87
	v_cvt_pk_bf16_f32 v2, v10, v11
	v_cvt_pk_bf16_f32 v3, v12, v13
	global_store_dwordx2 v86, v[6:7], s[48:49] sc1
	global_store_dwordx2 v86, v[2:3], s[48:49] offset:1536 sc1
	s_waitcnt lgkmcnt(0)
	v_add_f32_e32 v87, v87, v89
	v_xor_b32_e32 v89, 4, v83
	v_cmp_lt_i32_e32 vcc, v89, v88
	s_nop 1
	v_cndmask_b32_e32 v89, v83, v89, vcc
	v_lshlrev_b32_e32 v89, 2, v89
	ds_bpermute_b32 v89, v89, v87
	s_waitcnt lgkmcnt(0)
	v_add_f32_e32 v87, v87, v89
	v_xor_b32_e32 v89, 8, v83
	v_cmp_lt_i32_e32 vcc, v89, v88
	s_nop 1
	v_cndmask_b32_e32 v89, v83, v89, vcc
	v_lshlrev_b32_e32 v89, 2, v89
	ds_bpermute_b32 v89, v89, v87
	s_waitcnt lgkmcnt(0)
	v_add_f32_e32 v87, v87, v89
	v_xor_b32_e32 v89, 16, v83
	v_cmp_lt_i32_e32 vcc, v89, v88
	s_nop 1
	v_cndmask_b32_e32 v89, v83, v89, vcc
	v_lshlrev_b32_e32 v89, 2, v89
	ds_bpermute_b32 v89, v89, v87
	s_waitcnt lgkmcnt(0)
	v_add_f32_e32 v87, v87, v89
	v_xor_b32_e32 v89, 32, v83
	v_cmp_lt_i32_e32 vcc, v89, v88
	s_nop 1
	v_cndmask_b32_e32 v88, v83, v89, vcc
	v_lshlrev_b32_e32 v88, 2, v88
	ds_bpermute_b32 v88, v88, v87
	s_and_saveexec_b64 s[6:7], s[4:5]
	s_cbranch_execz .LBB0_1441
	s_lshl_b64 s[12:13], s[46:47], 2
	s_add_u32 s12, s72, s12
	s_addc_u32 s13, s75, s13
	s_waitcnt lgkmcnt(0)
	v_add_f32_e32 v2, v87, v88
	global_store_dword v85, v2, s[12:13]

.LBB0_1442:
	s_cmp_eq_u64 s[50:51], 0
	s_cbranch_scc1 .LBB0_1446
	v_mul_f32_e32 v2, v23, v23
	v_mul_f32_e32 v3, v25, v25
	v_fmac_f32_e32 v2, v22, v22
	v_fmac_f32_e32 v3, v24, v24
	v_add_f32_e32 v2, v2, v3
	v_mul_f32_e32 v3, v19, v19
	v_mul_f32_e32 v4, v21, v21
	v_fmac_f32_e32 v3, v18, v18
	v_fmac_f32_e32 v4, v20, v20
	v_add_f32_e32 v3, v3, v4
	v_add_f32_e32 v2, v2, v3
	s_waitcnt vmcnt(0)
	v_mul_f32_e32 v3, v31, v31
	v_mul_f32_e32 v4, v33, v33
	v_fmac_f32_e32 v3, v30, v30
	v_fmac_f32_e32 v4, v32, v32
	v_add_f32_e32 v3, v3, v4
	v_add_f32_e32 v2, v2, v3
	v_mul_f32_e32 v3, v27, v27
	v_mul_f32_e32 v4, v29, v29
	v_fmac_f32_e32 v3, v26, v26
	v_fmac_f32_e32 v4, v28, v28
	v_add_f32_e32 v3, v3, v4
	v_add_f32_e32 v2, v2, v3
	v_and_b32_e32 v3, 64, v83
	v_add_u32_e32 v3, 64, v3
	v_xor_b32_e32 v4, 1, v83
	v_cmp_lt_i32_e32 vcc, v4, v3
	v_cvt_pk_bf16_f32 v5, v24, v25
	s_nop 0
	v_cndmask_b32_e32 v4, v83, v4, vcc
	v_lshlrev_b32_e32 v4, 2, v4
	ds_bpermute_b32 v4, v4, v2
	s_waitcnt lgkmcnt(0)
	v_add_f32_e32 v2, v2, v4
	v_xor_b32_e32 v4, 2, v83
	v_cmp_lt_i32_e32 vcc, v4, v3
	s_nop 1
	v_cndmask_b32_e32 v4, v83, v4, vcc
	v_lshlrev_b32_e32 v4, 2, v4
	ds_bpermute_b32 v4, v4, v2
	s_waitcnt lgkmcnt(0)
	v_add_f32_e32 v2, v2, v4
	v_xor_b32_e32 v4, 4, v83
	v_cmp_lt_i32_e32 vcc, v4, v3
	s_nop 1
	v_cndmask_b32_e32 v4, v83, v4, vcc
	v_lshlrev_b32_e32 v4, 2, v4
	ds_bpermute_b32 v4, v4, v2
	s_waitcnt lgkmcnt(0)
	v_add_f32_e32 v2, v2, v4
	v_xor_b32_e32 v4, 8, v83
	v_cmp_lt_i32_e32 vcc, v4, v3
	s_nop 1
	v_cndmask_b32_e32 v4, v83, v4, vcc
	v_lshlrev_b32_e32 v4, 2, v4
	ds_bpermute_b32 v4, v4, v2
	s_waitcnt lgkmcnt(0)
	v_add_f32_e32 v2, v2, v4
	v_xor_b32_e32 v4, 16, v83
	v_cmp_lt_i32_e32 vcc, v4, v3
	s_nop 1
	v_cndmask_b32_e32 v4, v83, v4, vcc
	v_lshlrev_b32_e32 v4, 2, v4
	ds_bpermute_b32 v4, v4, v2
	s_waitcnt lgkmcnt(0)
	v_add_f32_e32 v2, v2, v4
	v_xor_b32_e32 v4, 32, v83
	v_cmp_lt_i32_e32 vcc, v4, v3
	s_nop 1
	v_cndmask_b32_e32 v3, v83, v4, vcc
	v_lshlrev_b32_e32 v3, 2, v3
	ds_bpermute_b32 v3, v3, v2
	v_cvt_pk_bf16_f32 v4, v22, v23
	global_store_dwordx2 v86, v[4:5], s[50:51] sc1
	v_cvt_pk_bf16_f32 v4, v18, v19
	v_cvt_pk_bf16_f32 v5, v20, v21
	global_store_dwordx2 v86, v[4:5], s[50:51] offset:512 sc1
	v_cvt_pk_bf16_f32 v4, v30, v31
	v_cvt_pk_bf16_f32 v5, v32, v33
	global_store_dwordx2 v86, v[4:5], s[50:51] offset:1024 sc1
	v_cvt_pk_bf16_f32 v4, v26, v27
	v_cvt_pk_bf16_f32 v5, v28, v29
	global_store_dwordx2 v86, v[4:5], s[50:51] offset:1536 sc1
	s_and_saveexec_b64 s[6:7], s[4:5]
	s_cbranch_execz .LBB0_1445
	s_waitcnt lgkmcnt(0)
	v_add_f32_e32 v2, v2, v3
	global_store_dword v85, v2, s[54:55]

.LBB0_1446:
	s_cmp_eq_u64 s[56:57], 0
	s_cbranch_scc1 .LBB0_1450
	s_waitcnt vmcnt(0)
	v_mul_f32_e32 v2, v39, v39
	s_waitcnt lgkmcnt(0)
	v_mul_f32_e32 v3, v41, v41
	v_fmac_f32_e32 v2, v38, v38
	v_fmac_f32_e32 v3, v40, v40
	v_add_f32_e32 v2, v2, v3
	v_mul_f32_e32 v3, v35, v35
	v_mul_f32_e32 v4, v37, v37
	v_fmac_f32_e32 v3, v34, v34
	v_fmac_f32_e32 v4, v36, v36
	v_add_f32_e32 v3, v3, v4
	v_add_f32_e32 v2, v2, v3
	v_mul_f32_e32 v3, v47, v47
	v_mul_f32_e32 v4, v49, v49
	v_fmac_f32_e32 v3, v46, v46
	v_fmac_f32_e32 v4, v48, v48
	v_add_f32_e32 v3, v3, v4
	v_add_f32_e32 v2, v2, v3
	v_mul_f32_e32 v3, v43, v43
	v_mul_f32_e32 v4, v45, v45
	v_fmac_f32_e32 v3, v42, v42
	v_fmac_f32_e32 v4, v44, v44
	v_add_f32_e32 v3, v3, v4
	v_add_f32_e32 v2, v2, v3
	v_and_b32_e32 v3, 64, v83
	v_add_u32_e32 v3, 64, v3
	v_xor_b32_e32 v4, 1, v83
	v_cmp_lt_i32_e32 vcc, v4, v3
	v_cvt_pk_bf16_f32 v5, v40, v41
	s_nop 0
	v_cndmask_b32_e32 v4, v83, v4, vcc
	v_lshlrev_b32_e32 v4, 2, v4
	ds_bpermute_b32 v4, v4, v2
	s_waitcnt lgkmcnt(0)
	v_add_f32_e32 v2, v2, v4
	v_xor_b32_e32 v4, 2, v83
	v_cmp_lt_i32_e32 vcc, v4, v3
	s_nop 1
	v_cndmask_b32_e32 v4, v83, v4, vcc
	v_lshlrev_b32_e32 v4, 2, v4
	ds_bpermute_b32 v4, v4, v2
	s_waitcnt lgkmcnt(0)
	v_add_f32_e32 v2, v2, v4
	v_xor_b32_e32 v4, 4, v83
	v_cmp_lt_i32_e32 vcc, v4, v3
	s_nop 1
	v_cndmask_b32_e32 v4, v83, v4, vcc
	v_lshlrev_b32_e32 v4, 2, v4
	ds_bpermute_b32 v4, v4, v2
	s_waitcnt lgkmcnt(0)
	v_add_f32_e32 v2, v2, v4
	v_xor_b32_e32 v4, 8, v83
	v_cmp_lt_i32_e32 vcc, v4, v3
	s_nop 1
	v_cndmask_b32_e32 v4, v83, v4, vcc
	v_lshlrev_b32_e32 v4, 2, v4
	ds_bpermute_b32 v4, v4, v2
	s_waitcnt lgkmcnt(0)
	v_add_f32_e32 v2, v2, v4
	v_xor_b32_e32 v4, 16, v83
	v_cmp_lt_i32_e32 vcc, v4, v3
	s_nop 1
	v_cndmask_b32_e32 v4, v83, v4, vcc
	v_lshlrev_b32_e32 v4, 2, v4
	ds_bpermute_b32 v4, v4, v2
	s_waitcnt lgkmcnt(0)
	v_add_f32_e32 v2, v2, v4
	v_xor_b32_e32 v4, 32, v83
	v_cmp_lt_i32_e32 vcc, v4, v3
	s_nop 1
	v_cndmask_b32_e32 v3, v83, v4, vcc
	v_lshlrev_b32_e32 v3, 2, v3
	ds_bpermute_b32 v3, v3, v2
	v_cvt_pk_bf16_f32 v4, v38, v39
	global_store_dwordx2 v86, v[4:5], s[56:57] sc1
	v_cvt_pk_bf16_f32 v4, v34, v35
	v_cvt_pk_bf16_f32 v5, v36, v37
	global_store_dwordx2 v86, v[4:5], s[56:57] offset:512 sc1
	v_cvt_pk_bf16_f32 v4, v46, v47
	v_cvt_pk_bf16_f32 v5, v48, v49
	global_store_dwordx2 v86, v[4:5], s[56:57] offset:1024 sc1
	v_cvt_pk_bf16_f32 v4, v42, v43
	v_cvt_pk_bf16_f32 v5, v44, v45
	global_store_dwordx2 v86, v[4:5], s[56:57] offset:1536 sc1
	s_and_saveexec_b64 s[6:7], s[4:5]
	s_cbranch_execz .LBB0_1449
	s_waitcnt lgkmcnt(0)
	v_add_f32_e32 v2, v2, v3
	global_store_dword v85, v2, s[58:59]

.LBB0_1450:
	s_cmp_eq_u64 s[60:61], 0
	s_cbranch_scc1 .LBB0_1454
	s_waitcnt vmcnt(0)
	v_mul_f32_e32 v2, v55, v55
	s_waitcnt lgkmcnt(0)
	v_mul_f32_e32 v3, v57, v57
	v_fmac_f32_e32 v2, v54, v54
	v_fmac_f32_e32 v3, v56, v56
	v_add_f32_e32 v2, v2, v3
	v_mul_f32_e32 v3, v51, v51
	v_mul_f32_e32 v4, v53, v53
	v_fmac_f32_e32 v3, v50, v50
	v_fmac_f32_e32 v4, v52, v52
	v_add_f32_e32 v3, v3, v4
	v_add_f32_e32 v2, v2, v3
	v_mul_f32_e32 v3, v63, v63
	v_mul_f32_e32 v4, v65, v65
	v_fmac_f32_e32 v3, v62, v62
	v_fmac_f32_e32 v4, v64, v64
	v_add_f32_e32 v3, v3, v4
	v_add_f32_e32 v2, v2, v3
	v_mul_f32_e32 v3, v59, v59
	v_mul_f32_e32 v4, v61, v61
	v_fmac_f32_e32 v3, v58, v58
	v_fmac_f32_e32 v4, v60, v60
	v_add_f32_e32 v3, v3, v4
	v_add_f32_e32 v2, v2, v3
	v_and_b32_e32 v3, 64, v83
	v_add_u32_e32 v3, 64, v3
	v_xor_b32_e32 v4, 1, v83
	v_cmp_lt_i32_e32 vcc, v4, v3
	v_cvt_pk_bf16_f32 v5, v56, v57
	s_nop 0
	v_cndmask_b32_e32 v4, v83, v4, vcc
	v_lshlrev_b32_e32 v4, 2, v4
	ds_bpermute_b32 v4, v4, v2
	s_waitcnt lgkmcnt(0)
	v_add_f32_e32 v2, v2, v4
	v_xor_b32_e32 v4, 2, v83
	v_cmp_lt_i32_e32 vcc, v4, v3
	s_nop 1
	v_cndmask_b32_e32 v4, v83, v4, vcc
	v_lshlrev_b32_e32 v4, 2, v4
	ds_bpermute_b32 v4, v4, v2
	s_waitcnt lgkmcnt(0)
	v_add_f32_e32 v2, v2, v4
	v_xor_b32_e32 v4, 4, v83
	v_cmp_lt_i32_e32 vcc, v4, v3
	s_nop 1
	v_cndmask_b32_e32 v4, v83, v4, vcc
	v_lshlrev_b32_e32 v4, 2, v4
	ds_bpermute_b32 v4, v4, v2
	s_waitcnt lgkmcnt(0)
	v_add_f32_e32 v2, v2, v4
	v_xor_b32_e32 v4, 8, v83
	v_cmp_lt_i32_e32 vcc, v4, v3
	s_nop 1
	v_cndmask_b32_e32 v4, v83, v4, vcc
	v_lshlrev_b32_e32 v4, 2, v4
	ds_bpermute_b32 v4, v4, v2
	s_waitcnt lgkmcnt(0)
	v_add_f32_e32 v2, v2, v4
	v_xor_b32_e32 v4, 16, v83
	v_cmp_lt_i32_e32 vcc, v4, v3
	s_nop 1
	v_cndmask_b32_e32 v4, v83, v4, vcc
	v_lshlrev_b32_e32 v4, 2, v4
	ds_bpermute_b32 v4, v4, v2
	s_waitcnt lgkmcnt(0)
	v_add_f32_e32 v2, v2, v4
	v_xor_b32_e32 v4, 32, v83
	v_cmp_lt_i32_e32 vcc, v4, v3
	s_nop 1
	v_cndmask_b32_e32 v3, v83, v4, vcc
	v_lshlrev_b32_e32 v3, 2, v3
	ds_bpermute_b32 v3, v3, v2
	v_cvt_pk_bf16_f32 v4, v54, v55
	global_store_dwordx2 v86, v[4:5], s[60:61] sc1
	v_cvt_pk_bf16_f32 v4, v50, v51
	v_cvt_pk_bf16_f32 v5, v52, v53
	global_store_dwordx2 v86, v[4:5], s[60:61] offset:512 sc1
	v_cvt_pk_bf16_f32 v4, v62, v63
	v_cvt_pk_bf16_f32 v5, v64, v65
	global_store_dwordx2 v86, v[4:5], s[60:61] offset:1024 sc1
	v_cvt_pk_bf16_f32 v4, v58, v59
	v_cvt_pk_bf16_f32 v5, v60, v61
	global_store_dwordx2 v86, v[4:5], s[60:61] offset:1536 sc1
	s_and_saveexec_b64 s[6:7], s[4:5]
	s_cbranch_execz .LBB0_1453
	s_waitcnt lgkmcnt(0)
	v_add_f32_e32 v2, v2, v3
	global_store_dword v85, v2, s[62:63]

.LBB0_1454:
	s_cmp_eq_u64 s[64:65], 0
	s_cbranch_scc1 .LBB0_1345
	s_waitcnt vmcnt(0)
	v_mul_f32_e32 v2, v71, v71
	s_waitcnt lgkmcnt(0)
	v_mul_f32_e32 v3, v73, v73
	v_fmac_f32_e32 v2, v70, v70
	v_fmac_f32_e32 v3, v72, v72
	v_add_f32_e32 v2, v2, v3
	v_mul_f32_e32 v3, v67, v67
	v_mul_f32_e32 v4, v69, v69
	v_fmac_f32_e32 v3, v66, v66
	v_fmac_f32_e32 v4, v68, v68
	v_add_f32_e32 v3, v3, v4
	v_add_f32_e32 v2, v2, v3
	v_mul_f32_e32 v3, v79, v79
	v_mul_f32_e32 v4, v81, v81
	v_fmac_f32_e32 v3, v78, v78
	v_fmac_f32_e32 v4, v80, v80
	v_add_f32_e32 v3, v3, v4
	v_add_f32_e32 v2, v2, v3
	v_mul_f32_e32 v3, v75, v75
	v_mul_f32_e32 v4, v77, v77
	v_fmac_f32_e32 v3, v74, v74
	v_fmac_f32_e32 v4, v76, v76
	v_add_f32_e32 v3, v3, v4
	v_add_f32_e32 v2, v2, v3
	v_and_b32_e32 v3, 64, v83
	v_add_u32_e32 v3, 64, v3
	v_xor_b32_e32 v4, 1, v83
	v_cmp_lt_i32_e32 vcc, v4, v3
	v_cvt_pk_bf16_f32 v5, v72, v73
	s_nop 0
	v_cndmask_b32_e32 v4, v83, v4, vcc
	v_lshlrev_b32_e32 v4, 2, v4
	ds_bpermute_b32 v4, v4, v2
	s_waitcnt lgkmcnt(0)
	v_add_f32_e32 v2, v2, v4
	v_xor_b32_e32 v4, 2, v83
	v_cmp_lt_i32_e32 vcc, v4, v3
	s_nop 1
	v_cndmask_b32_e32 v4, v83, v4, vcc
	v_lshlrev_b32_e32 v4, 2, v4
	ds_bpermute_b32 v4, v4, v2
	s_waitcnt lgkmcnt(0)
	v_add_f32_e32 v2, v2, v4
	v_xor_b32_e32 v4, 4, v83
	v_cmp_lt_i32_e32 vcc, v4, v3
	s_nop 1
	v_cndmask_b32_e32 v4, v83, v4, vcc
	v_lshlrev_b32_e32 v4, 2, v4
	ds_bpermute_b32 v4, v4, v2
	s_waitcnt lgkmcnt(0)
	v_add_f32_e32 v2, v2, v4
	v_xor_b32_e32 v4, 8, v83
	v_cmp_lt_i32_e32 vcc, v4, v3
	s_nop 1
	v_cndmask_b32_e32 v4, v83, v4, vcc
	v_lshlrev_b32_e32 v4, 2, v4
	ds_bpermute_b32 v4, v4, v2
	s_waitcnt lgkmcnt(0)
	v_add_f32_e32 v2, v2, v4
	v_xor_b32_e32 v4, 16, v83
	v_cmp_lt_i32_e32 vcc, v4, v3
	s_nop 1
	v_cndmask_b32_e32 v4, v83, v4, vcc
	v_lshlrev_b32_e32 v4, 2, v4
	ds_bpermute_b32 v4, v4, v2
	s_waitcnt lgkmcnt(0)
	v_add_f32_e32 v2, v2, v4
	v_xor_b32_e32 v4, 32, v83
	v_cmp_lt_i32_e32 vcc, v4, v3
	s_nop 1
	v_cndmask_b32_e32 v3, v83, v4, vcc
	v_lshlrev_b32_e32 v3, 2, v3
	ds_bpermute_b32 v3, v3, v2
	v_cvt_pk_bf16_f32 v4, v70, v71
	global_store_dwordx2 v86, v[4:5], s[64:65] sc1
	v_cvt_pk_bf16_f32 v4, v66, v67
	v_cvt_pk_bf16_f32 v5, v68, v69
	global_store_dwordx2 v86, v[4:5], s[64:65] offset:512 sc1
	v_cvt_pk_bf16_f32 v4, v78, v79
	v_cvt_pk_bf16_f32 v5, v80, v81
	global_store_dwordx2 v86, v[4:5], s[64:65] offset:1024 sc1
	v_cvt_pk_bf16_f32 v4, v74, v75
	v_cvt_pk_bf16_f32 v5, v76, v77
	global_store_dwordx2 v86, v[4:5], s[64:65] offset:1536 sc1
	s_and_saveexec_b64 s[6:7], s[4:5]
	s_cbranch_execz .LBB0_1344
	s_waitcnt lgkmcnt(0)
	v_add_f32_e32 v2, v2, v3
	global_store_dword v85, v2, s[66:67]
	s_branch .LBB0_1344
